# act sub-phase inputs (expert scale pairs, token scales, row sums, tile counter) requested in the u-phase's last step
# baseline (speedup 1.0000x reference)
; #define LAS __attribute__((address_space(3)))
; __device__ __forceinline__ void peer_u_item(int p, int j, const LAS unsigned short* EL  , const unsigned char* __restrict__ XQ, const unsigned char* __restrict__ U8, LAS int* ACC  , int lane, int wave) {
;     ...
;     for (int it = 0; it < 8; ++it) {
;         const int t = j * 64 + it * 8 + wave;
;         unsigned E[8];
;         { const LAS v4u* ep = (const LAS v4u*)(EL + (it * 8 + wave) * 128 + 16 * gidx); const v4u e0 = ep[0], e1 = ep[1];
;           E[0] = e0.x; E[1] = e0.y; E[2] = e0.z; E[3] = e0.w; E[4] = e1.x; E[5] = e1.y; E[6] = e1.z; E[7] = e1.w; }
;         uint4 uu[16];
; #pragma unroll
;         for (int i = 0; i < 16; ++i) uu[i] = *(const uint4*)(U8 + (size_t)(PE_ID(E, i) * 128u + toff));
;         const uint4 xh = *(const uint4*)(XQ + (size_t)t * 512 + coff), xl = *(const uint4*)(XQ + 8 * MiB + (size_t)t * 512 + coff);
;         int d[16];
; #pragma unroll
;         for (int i = 0; i < 16; ++i) {
;             int sh = __builtin_amdgcn_sdot8((int)uu[i].x, (int)xh.x, 0, false); sh = __builtin_amdgcn_sdot8((int)uu[i].y, (int)xh.y, sh, false);
;             sh = __builtin_amdgcn_sdot8((int)uu[i].z, (int)xh.z, sh, false); sh = __builtin_amdgcn_sdot8((int)uu[i].w, (int)xh.w, sh, false);
;             int sl = __builtin_amdgcn_sdot8((int)uu[i].x, (int)xl.x, 0, false); sl = __builtin_amdgcn_sdot8((int)uu[i].y, (int)xl.y, sl, false);
;             sl = __builtin_amdgcn_sdot8((int)uu[i].z, (int)xl.z, sl, false); sl = __builtin_amdgcn_sdot8((int)uu[i].w, (int)xl.w, sl, false);
;             d[i] = (sh << 4) + sl;
;         }
;         int r0, r1; treduce16i<4, 2, 1>(d, lane, r0, r1);
;         { typedef int i2v __attribute__((ext_vector_type(2))); LAS i2v* ap = (LAS i2v*)(ACC + (it * 8 + wave) * 128 + 2 * lane);
;           i2v a2; if (p == 0) { a2.x = r0; a2.y = r1; } else { a2 = *ap; a2.x += r0; a2.y += r1; } *ap = a2; }
.Lpu_trip:
	s_lshl_b32 s32, s44, 11
	v_add_u32_e32 v39, s32, v59
	ds_read_b128 v[210:213], v39
	ds_read_b128 v[214:217], v39 offset:16
	s_lshl_b32 s32, s42, 12
	v_add_u32_e32 v61, s32, v60
	ds_read_b64 v[62:63], v61
	s_lshl_b32 s46, s44, 3
	s_add_i32 s46, s46, s40
	s_lshl_b32 s46, s46, 9
	s_lshl_b32 s32, s45, 7
	s_add_i32 s46, s46, s32
	v_add_u32_e32 v57, s46, v56
	global_load_dwordx4 v[194:197], v57, s[34:35]
	global_load_dwordx4 v[198:201], v57, s[36:37]
	s_lshl_b32 s32, s45, 21
	v_add_u32_e32 v58, s32, v56
	s_waitcnt lgkmcnt(0)
	s_waitcnt vmcnt(17)
	v_dot8_i32_i4 v34, v122, v186, 0
	v_dot8_i32_i4 v35, v122, v190, 0
	v_dot8_i32_i4 v34, v123, v187, v34
	v_dot8_i32_i4 v35, v123, v191, v35
	v_dot8_i32_i4 v34, v124, v188, v34
	v_dot8_i32_i4 v35, v124, v192, v35
	v_dot8_i32_i4 v34, v125, v189, v34
	v_dot8_i32_i4 v35, v125, v193, v35
	v_and_b32_e32 v38, 0xffff, v210
	v_lshl_add_u32 v38, v38, 7, v58
	global_load_dwordx4 v[122:125], v38, s[96:97]
	s_nop 0
	v_lshl_add_u32 v18, v34, 4, v35
	s_waitcnt vmcnt(17)
	v_dot8_i32_i4 v36, v126, v186, 0
	v_dot8_i32_i4 v37, v126, v190, 0
	v_dot8_i32_i4 v36, v127, v187, v36
	v_dot8_i32_i4 v37, v127, v191, v37
	v_dot8_i32_i4 v36, v128, v188, v36
	v_dot8_i32_i4 v37, v128, v192, v37
	v_dot8_i32_i4 v36, v129, v189, v36
	v_dot8_i32_i4 v37, v129, v193, v37
	v_lshrrev_b32_e32 v38, 16, v210
	v_lshl_add_u32 v38, v38, 7, v58
	global_load_dwordx4 v[126:129], v38, s[96:97]
	s_nop 0
	v_lshl_add_u32 v19, v36, 4, v37
	s_waitcnt vmcnt(17)
	v_dot8_i32_i4 v34, v130, v186, 0
	v_dot8_i32_i4 v35, v130, v190, 0
	v_dot8_i32_i4 v34, v131, v187, v34
	v_dot8_i32_i4 v35, v131, v191, v35
	v_dot8_i32_i4 v34, v132, v188, v34
	v_dot8_i32_i4 v35, v132, v192, v35
	v_dot8_i32_i4 v34, v133, v189, v34
	v_dot8_i32_i4 v35, v133, v193, v35
	v_and_b32_e32 v38, 0xffff, v211
	v_lshl_add_u32 v38, v38, 7, v58
	global_load_dwordx4 v[130:133], v38, s[96:97]
	s_nop 0
	v_lshl_add_u32 v20, v34, 4, v35
	s_waitcnt vmcnt(17)
	v_dot8_i32_i4 v36, v134, v186, 0
	v_dot8_i32_i4 v37, v134, v190, 0
	v_dot8_i32_i4 v36, v135, v187, v36
	v_dot8_i32_i4 v37, v135, v191, v37
	v_dot8_i32_i4 v36, v136, v188, v36
	v_dot8_i32_i4 v37, v136, v192, v37
	v_dot8_i32_i4 v36, v137, v189, v36
	v_dot8_i32_i4 v37, v137, v193, v37
	v_lshrrev_b32_e32 v38, 16, v211
	v_lshl_add_u32 v38, v38, 7, v58
	global_load_dwordx4 v[134:137], v38, s[96:97]
	s_nop 0
	v_lshl_add_u32 v21, v36, 4, v37
	s_waitcnt vmcnt(17)
	v_dot8_i32_i4 v34, v138, v186, 0
	v_dot8_i32_i4 v35, v138, v190, 0
	v_dot8_i32_i4 v34, v139, v187, v34
	v_dot8_i32_i4 v35, v139, v191, v35
	v_dot8_i32_i4 v34, v140, v188, v34
	v_dot8_i32_i4 v35, v140, v192, v35
	v_dot8_i32_i4 v34, v141, v189, v34
	v_dot8_i32_i4 v35, v141, v193, v35
	v_and_b32_e32 v38, 0xffff, v212
	v_lshl_add_u32 v38, v38, 7, v58
	global_load_dwordx4 v[138:141], v38, s[96:97]
	s_nop 0
	v_lshl_add_u32 v22, v34, 4, v35
	s_waitcnt vmcnt(17)
	v_dot8_i32_i4 v36, v142, v186, 0
	v_dot8_i32_i4 v37, v142, v190, 0
	v_dot8_i32_i4 v36, v143, v187, v36
	v_dot8_i32_i4 v37, v143, v191, v37
	v_dot8_i32_i4 v36, v144, v188, v36
	v_dot8_i32_i4 v37, v144, v192, v37
	v_dot8_i32_i4 v36, v145, v189, v36
	v_dot8_i32_i4 v37, v145, v193, v37
	v_lshrrev_b32_e32 v38, 16, v212
	v_lshl_add_u32 v38, v38, 7, v58
	global_load_dwordx4 v[142:145], v38, s[96:97]
	s_nop 0
	v_lshl_add_u32 v23, v36, 4, v37
	s_waitcnt vmcnt(17)
	v_dot8_i32_i4 v34, v146, v186, 0
	v_dot8_i32_i4 v35, v146, v190, 0
	v_dot8_i32_i4 v34, v147, v187, v34
	v_dot8_i32_i4 v35, v147, v191, v35
	v_dot8_i32_i4 v34, v148, v188, v34
	v_dot8_i32_i4 v35, v148, v192, v35
	v_dot8_i32_i4 v34, v149, v189, v34
	v_dot8_i32_i4 v35, v149, v193, v35
	v_and_b32_e32 v38, 0xffff, v213
	v_lshl_add_u32 v38, v38, 7, v58
	global_load_dwordx4 v[146:149], v38, s[96:97]
	s_nop 0
	v_lshl_add_u32 v24, v34, 4, v35
	s_waitcnt vmcnt(17)
	v_dot8_i32_i4 v36, v150, v186, 0
	v_dot8_i32_i4 v37, v150, v190, 0
	v_dot8_i32_i4 v36, v151, v187, v36
	v_dot8_i32_i4 v37, v151, v191, v37
	v_dot8_i32_i4 v36, v152, v188, v36
	v_dot8_i32_i4 v37, v152, v192, v37
	v_dot8_i32_i4 v36, v153, v189, v36
	v_dot8_i32_i4 v37, v153, v193, v37
	v_lshrrev_b32_e32 v38, 16, v213
	v_lshl_add_u32 v38, v38, 7, v58
	global_load_dwordx4 v[150:153], v38, s[96:97]
	s_nop 0
	v_lshl_add_u32 v25, v36, 4, v37
	s_waitcnt vmcnt(17)
	v_dot8_i32_i4 v34, v154, v186, 0
	v_dot8_i32_i4 v35, v154, v190, 0
	v_dot8_i32_i4 v34, v155, v187, v34
	v_dot8_i32_i4 v35, v155, v191, v35
	v_dot8_i32_i4 v34, v156, v188, v34
	v_dot8_i32_i4 v35, v156, v192, v35
	v_dot8_i32_i4 v34, v157, v189, v34
	v_dot8_i32_i4 v35, v157, v193, v35
	v_and_b32_e32 v38, 0xffff, v214
	v_lshl_add_u32 v38, v38, 7, v58
	global_load_dwordx4 v[154:157], v38, s[96:97]
	s_nop 0
	v_lshl_add_u32 v26, v34, 4, v35
	s_waitcnt vmcnt(17)
	v_dot8_i32_i4 v36, v158, v186, 0
	v_dot8_i32_i4 v37, v158, v190, 0
	v_dot8_i32_i4 v36, v159, v187, v36
	v_dot8_i32_i4 v37, v159, v191, v37
	v_dot8_i32_i4 v36, v160, v188, v36
	v_dot8_i32_i4 v37, v160, v192, v37
	v_dot8_i32_i4 v36, v161, v189, v36
	v_dot8_i32_i4 v37, v161, v193, v37
	v_lshrrev_b32_e32 v38, 16, v214
	v_lshl_add_u32 v38, v38, 7, v58
	global_load_dwordx4 v[158:161], v38, s[96:97]
	s_nop 0
	v_lshl_add_u32 v27, v36, 4, v37
	s_waitcnt vmcnt(17)
	v_dot8_i32_i4 v34, v162, v186, 0
	v_dot8_i32_i4 v35, v162, v190, 0
	v_dot8_i32_i4 v34, v163, v187, v34
	v_dot8_i32_i4 v35, v163, v191, v35
	v_dot8_i32_i4 v34, v164, v188, v34
	v_dot8_i32_i4 v35, v164, v192, v35
	v_dot8_i32_i4 v34, v165, v189, v34
	v_dot8_i32_i4 v35, v165, v193, v35
	v_and_b32_e32 v38, 0xffff, v215
	v_lshl_add_u32 v38, v38, 7, v58
	global_load_dwordx4 v[162:165], v38, s[96:97]
	s_nop 0
	v_lshl_add_u32 v28, v34, 4, v35
	s_waitcnt vmcnt(17)
; #define LAS __attribute__((address_space(3)))
; __device__ __forceinline__ void peer_u_item(int p, int j, const LAS unsigned short* EL  , const unsigned char* __restrict__ XQ, const unsigned char* __restrict__ U8, LAS int* ACC  , int lane, int wave) {
;     ...
;     for (int it = 0; it < 8; ++it) {
;         const int t = j * 64 + it * 8 + wave;
;         unsigned E[8];
;         { const LAS v4u* ep = (const LAS v4u*)(EL + (it * 8 + wave) * 128 + 16 * gidx); const v4u e0 = ep[0], e1 = ep[1];
;           E[0] = e0.x; E[1] = e0.y; E[2] = e0.z; E[3] = e0.w; E[4] = e1.x; E[5] = e1.y; E[6] = e1.z; E[7] = e1.w; }
;         uint4 uu[16];
; #pragma unroll
;         for (int i = 0; i < 16; ++i) uu[i] = *(const uint4*)(U8 + (size_t)(PE_ID(E, i) * 128u + toff));
;         const uint4 xh = *(const uint4*)(XQ + (size_t)t * 512 + coff), xl = *(const uint4*)(XQ + 8 * MiB + (size_t)t * 512 + coff);
;         int d[16];
; #pragma unroll
;         for (int i = 0; i < 16; ++i) {
;             int sh = __builtin_amdgcn_sdot8((int)uu[i].x, (int)xh.x, 0, false); sh = __builtin_amdgcn_sdot8((int)uu[i].y, (int)xh.y, sh, false);
;             sh = __builtin_amdgcn_sdot8((int)uu[i].z, (int)xh.z, sh, false); sh = __builtin_amdgcn_sdot8((int)uu[i].w, (int)xh.w, sh, false);
;             int sl = __builtin_amdgcn_sdot8((int)uu[i].x, (int)xl.x, 0, false); sl = __builtin_amdgcn_sdot8((int)uu[i].y, (int)xl.y, sl, false);
;             sl = __builtin_amdgcn_sdot8((int)uu[i].z, (int)xl.z, sl, false); sl = __builtin_amdgcn_sdot8((int)uu[i].w, (int)xl.w, sl, false);
;             d[i] = (sh << 4) + sl;
;         }
;         int r0, r1; treduce16i<4, 2, 1>(d, lane, r0, r1);
;         { typedef int i2v __attribute__((ext_vector_type(2))); LAS i2v* ap = (LAS i2v*)(ACC + (it * 8 + wave) * 128 + 2 * lane);
;           i2v a2; if (p == 0) { a2.x = r0; a2.y = r1; } else { a2 = *ap; a2.x += r0; a2.y += r1; } *ap = a2; }
	v_dot8_i32_i4 v36, v166, v186, 0
	v_dot8_i32_i4 v37, v166, v190, 0
	v_dot8_i32_i4 v36, v167, v187, v36
	v_dot8_i32_i4 v37, v167, v191, v37
	v_dot8_i32_i4 v36, v168, v188, v36
	v_dot8_i32_i4 v37, v168, v192, v37
	v_dot8_i32_i4 v36, v169, v189, v36
	v_dot8_i32_i4 v37, v169, v193, v37
	v_lshrrev_b32_e32 v38, 16, v215
	v_lshl_add_u32 v38, v38, 7, v58
	global_load_dwordx4 v[166:169], v38, s[96:97]
	s_nop 0
	v_lshl_add_u32 v29, v36, 4, v37
	s_waitcnt vmcnt(17)
	v_dot8_i32_i4 v34, v170, v186, 0
	v_dot8_i32_i4 v35, v170, v190, 0
	v_dot8_i32_i4 v34, v171, v187, v34
	v_dot8_i32_i4 v35, v171, v191, v35
	v_dot8_i32_i4 v34, v172, v188, v34
	v_dot8_i32_i4 v35, v172, v192, v35
	v_dot8_i32_i4 v34, v173, v189, v34
	v_dot8_i32_i4 v35, v173, v193, v35
	v_and_b32_e32 v38, 0xffff, v216
	v_lshl_add_u32 v38, v38, 7, v58
	global_load_dwordx4 v[170:173], v38, s[96:97]
	s_nop 0
	v_lshl_add_u32 v30, v34, 4, v35
	s_waitcnt vmcnt(17)
	v_dot8_i32_i4 v36, v174, v186, 0
	v_dot8_i32_i4 v37, v174, v190, 0
	v_dot8_i32_i4 v36, v175, v187, v36
	v_dot8_i32_i4 v37, v175, v191, v37
	v_dot8_i32_i4 v36, v176, v188, v36
	v_dot8_i32_i4 v37, v176, v192, v37
	v_dot8_i32_i4 v36, v177, v189, v36
	v_dot8_i32_i4 v37, v177, v193, v37
	v_lshrrev_b32_e32 v38, 16, v216
	v_lshl_add_u32 v38, v38, 7, v58
	global_load_dwordx4 v[174:177], v38, s[96:97]
	s_nop 0
	v_lshl_add_u32 v31, v36, 4, v37
	s_waitcnt vmcnt(17)
	v_dot8_i32_i4 v34, v178, v186, 0
	v_dot8_i32_i4 v35, v178, v190, 0
	v_dot8_i32_i4 v34, v179, v187, v34
	v_dot8_i32_i4 v35, v179, v191, v35
	v_dot8_i32_i4 v34, v180, v188, v34
	v_dot8_i32_i4 v35, v180, v192, v35
	v_dot8_i32_i4 v34, v181, v189, v34
	v_dot8_i32_i4 v35, v181, v193, v35
	v_and_b32_e32 v38, 0xffff, v217
	v_lshl_add_u32 v38, v38, 7, v58
	global_load_dwordx4 v[178:181], v38, s[96:97]
	s_nop 0
	v_lshl_add_u32 v32, v34, 4, v35
	s_waitcnt vmcnt(17)
	v_dot8_i32_i4 v36, v182, v186, 0
	v_dot8_i32_i4 v37, v182, v190, 0
	v_dot8_i32_i4 v36, v183, v187, v36
	v_dot8_i32_i4 v37, v183, v191, v37
	v_dot8_i32_i4 v36, v184, v188, v36
	v_dot8_i32_i4 v37, v184, v192, v37
	v_dot8_i32_i4 v36, v185, v189, v36
	v_dot8_i32_i4 v37, v185, v193, v37
	v_lshrrev_b32_e32 v38, 16, v217
	v_lshl_add_u32 v38, v38, 7, v58
	global_load_dwordx4 v[182:185], v38, s[96:97]
	s_nop 0
	v_lshl_add_u32 v33, v36, 4, v37
	v_cndmask_b32_e64 v40, v26, v18, s[10:11]
	v_cndmask_b32_e64 v48, v18, v26, s[10:11]
	v_cndmask_b32_e64 v41, v27, v19, s[10:11]
	v_cndmask_b32_e64 v49, v19, v27, s[10:11]
	v_cndmask_b32_e64 v42, v28, v20, s[10:11]
	v_cndmask_b32_e64 v50, v20, v28, s[10:11]
	v_cndmask_b32_e64 v43, v29, v21, s[10:11]
	v_cndmask_b32_e64 v51, v21, v29, s[10:11]
	v_cndmask_b32_e64 v44, v30, v22, s[10:11]
	v_cndmask_b32_e64 v52, v22, v30, s[10:11]
	v_cndmask_b32_e64 v45, v31, v23, s[10:11]
	v_cndmask_b32_e64 v53, v23, v31, s[10:11]
	v_cndmask_b32_e64 v46, v32, v24, s[10:11]
	v_cndmask_b32_e64 v54, v24, v32, s[10:11]
	v_cndmask_b32_e64 v47, v33, v25, s[10:11]
	v_cndmask_b32_e64 v55, v25, v33, s[10:11]
	v_add_u32_dpp v18, v40, v48 row_shr:4 row_mask:0xf bank_mask:0xa
	v_add_u32_dpp v18, v40, v48 row_shl:4 row_mask:0xf bank_mask:0x5
	v_add_u32_dpp v19, v41, v49 row_shr:4 row_mask:0xf bank_mask:0xa
	v_add_u32_dpp v19, v41, v49 row_shl:4 row_mask:0xf bank_mask:0x5
	v_add_u32_dpp v20, v42, v50 row_shr:4 row_mask:0xf bank_mask:0xa
	v_add_u32_dpp v20, v42, v50 row_shl:4 row_mask:0xf bank_mask:0x5
	v_add_u32_dpp v21, v43, v51 row_shr:4 row_mask:0xf bank_mask:0xa
	v_add_u32_dpp v21, v43, v51 row_shl:4 row_mask:0xf bank_mask:0x5
	v_add_u32_dpp v22, v44, v52 row_shr:4 row_mask:0xf bank_mask:0xa
	v_add_u32_dpp v22, v44, v52 row_shl:4 row_mask:0xf bank_mask:0x5
	v_add_u32_dpp v23, v45, v53 row_shr:4 row_mask:0xf bank_mask:0xa
	v_add_u32_dpp v23, v45, v53 row_shl:4 row_mask:0xf bank_mask:0x5
	v_add_u32_dpp v24, v46, v54 row_shr:4 row_mask:0xf bank_mask:0xa
	v_add_u32_dpp v24, v46, v54 row_shl:4 row_mask:0xf bank_mask:0x5
	v_add_u32_dpp v25, v47, v55 row_shr:4 row_mask:0xf bank_mask:0xa
	v_add_u32_dpp v25, v47, v55 row_shl:4 row_mask:0xf bank_mask:0x5
	v_cndmask_b32_e64 v40, v22, v18, s[12:13]
	v_cndmask_b32_e64 v48, v18, v22, s[12:13]
	v_cndmask_b32_e64 v41, v23, v19, s[12:13]
	v_cndmask_b32_e64 v49, v19, v23, s[12:13]
	v_cndmask_b32_e64 v42, v24, v20, s[12:13]
	v_cndmask_b32_e64 v50, v20, v24, s[12:13]
	v_cndmask_b32_e64 v43, v25, v21, s[12:13]
	v_cndmask_b32_e64 v51, v21, v25, s[12:13]
	s_nop 0
	v_add_u32_dpp v26, v40, v48 quad_perm:[2,3,0,1] row_mask:0xf bank_mask:0xf
	v_add_u32_dpp v27, v41, v49 quad_perm:[2,3,0,1] row_mask:0xf bank_mask:0xf
	v_add_u32_dpp v28, v42, v50 quad_perm:[2,3,0,1] row_mask:0xf bank_mask:0xf
	v_add_u32_dpp v29, v43, v51 quad_perm:[2,3,0,1] row_mask:0xf bank_mask:0xf
	v_cndmask_b32_e64 v40, v28, v26, s[14:15]
	v_cndmask_b32_e64 v48, v26, v28, s[14:15]
	v_cndmask_b32_e64 v41, v29, v27, s[14:15]
	v_cndmask_b32_e64 v49, v27, v29, s[14:15]
	s_nop 1
	v_add_u32_dpp v44, v40, v48 quad_perm:[1,0,3,2] row_mask:0xf bank_mask:0xf
	v_add_u32_dpp v45, v41, v49 quad_perm:[1,0,3,2] row_mask:0xf bank_mask:0xf
	s_cmp_eq_u32 s43, 0
	s_cselect_b32 s32, 0, -1
	v_and_b32_e32 v62, s32, v62
	v_and_b32_e32 v63, s32, v63
	v_add_u32_e32 v44, v44, v62
	v_add_u32_e32 v45, v45, v63
	ds_write_b64 v61, v[44:45]
	s_mov_b32 s42, s44
	s_mov_b32 s43, s45
	s_add_i32 s44, s44, 1
	s_and_b32 s44, s44, 7
	s_cmp_eq_u32 s44, 0
	s_cselect_b32 s32, 1, 0
	s_add_i32 s45, s45, s32
	s_and_b32 s45, s45, 3
	s_lshl_b32 s32, s44, 11
	v_add_u32_e32 v39, s32, v59
	ds_read_b128 v[202:205], v39
	ds_read_b128 v[206:209], v39 offset:16
	s_lshl_b32 s32, s42, 12
	v_add_u32_e32 v61, s32, v60
	ds_read_b64 v[62:63], v61
	s_lshl_b32 s46, s44, 3
	s_add_i32 s46, s46, s40
	s_lshl_b32 s46, s46, 9
	s_lshl_b32 s32, s45, 7
	s_add_i32 s46, s46, s32
	v_add_u32_e32 v57, s46, v56
	global_load_dwordx4 v[186:189], v57, s[34:35]
	global_load_dwordx4 v[190:193], v57, s[36:37]
	s_lshl_b32 s32, s45, 21
	v_add_u32_e32 v58, s32, v56
	s_waitcnt lgkmcnt(0)
; __device__ __forceinline__ void peer_u_item(int p, int j, const LAS unsigned short* EL  , const unsigned char* __restrict__ XQ, const unsigned char* __restrict__ U8, LAS int* ACC  , int lane, int wave) {
;     ...
;         for (int i = 0; i < 16; ++i) {
;             int sh = __builtin_amdgcn_sdot8((int)uu[i].x, (int)xh.x, 0, false); sh = __builtin_amdgcn_sdot8((int)uu[i].y, (int)xh.y, sh, false);
;             sh = __builtin_amdgcn_sdot8((int)uu[i].z, (int)xh.z, sh, false); sh = __builtin_amdgcn_sdot8((int)uu[i].w, (int)xh.w, sh, false);
;             int sl = __builtin_amdgcn_sdot8((int)uu[i].x, (int)xl.x, 0, false); sl = __builtin_amdgcn_sdot8((int)uu[i].y, (int)xl.y, sl, false);
;             sl = __builtin_amdgcn_sdot8((int)uu[i].z, (int)xl.z, sl, false); sl = __builtin_amdgcn_sdot8((int)uu[i].w, (int)xl.w, sl, false);
;             d[i] = (sh << 4) + sl;
;         }
	s_waitcnt vmcnt(17)
	v_dot8_i32_i4 v34, v122, v194, 0
	v_dot8_i32_i4 v35, v122, v198, 0
	v_dot8_i32_i4 v34, v123, v195, v34
	v_dot8_i32_i4 v35, v123, v199, v35
	v_dot8_i32_i4 v34, v124, v196, v34
	v_dot8_i32_i4 v35, v124, v200, v35
	v_dot8_i32_i4 v34, v125, v197, v34
	v_dot8_i32_i4 v35, v125, v201, v35
	v_and_b32_e32 v38, 0xffff, v202
	v_lshl_add_u32 v38, v38, 7, v58
	global_load_dwordx4 v[122:125], v38, s[96:97]
	s_nop 0
	v_lshl_add_u32 v18, v34, 4, v35
	s_waitcnt vmcnt(17)
	v_dot8_i32_i4 v36, v126, v194, 0
	v_dot8_i32_i4 v37, v126, v198, 0
	v_dot8_i32_i4 v36, v127, v195, v36
	v_dot8_i32_i4 v37, v127, v199, v37
	v_dot8_i32_i4 v36, v128, v196, v36
	v_dot8_i32_i4 v37, v128, v200, v37
	v_dot8_i32_i4 v36, v129, v197, v36
	v_dot8_i32_i4 v37, v129, v201, v37
	v_lshrrev_b32_e32 v38, 16, v202
	v_lshl_add_u32 v38, v38, 7, v58
	global_load_dwordx4 v[126:129], v38, s[96:97]
	s_nop 0
	v_lshl_add_u32 v19, v36, 4, v37
	s_waitcnt vmcnt(17)
	v_dot8_i32_i4 v34, v130, v194, 0
	v_dot8_i32_i4 v35, v130, v198, 0
	v_dot8_i32_i4 v34, v131, v195, v34
	v_dot8_i32_i4 v35, v131, v199, v35
	v_dot8_i32_i4 v34, v132, v196, v34
	v_dot8_i32_i4 v35, v132, v200, v35
	v_dot8_i32_i4 v34, v133, v197, v34
	v_dot8_i32_i4 v35, v133, v201, v35
	v_and_b32_e32 v38, 0xffff, v203
	v_lshl_add_u32 v38, v38, 7, v58
	global_load_dwordx4 v[130:133], v38, s[96:97]
	s_nop 0
	v_lshl_add_u32 v20, v34, 4, v35
	s_waitcnt vmcnt(17)
	v_dot8_i32_i4 v36, v134, v194, 0
	v_dot8_i32_i4 v37, v134, v198, 0
	v_dot8_i32_i4 v36, v135, v195, v36
	v_dot8_i32_i4 v37, v135, v199, v37
	v_dot8_i32_i4 v36, v136, v196, v36
	v_dot8_i32_i4 v37, v136, v200, v37
	v_dot8_i32_i4 v36, v137, v197, v36
	v_dot8_i32_i4 v37, v137, v201, v37
	v_lshrrev_b32_e32 v38, 16, v203
	v_lshl_add_u32 v38, v38, 7, v58
	global_load_dwordx4 v[134:137], v38, s[96:97]
	s_nop 0
	v_lshl_add_u32 v21, v36, 4, v37
	s_waitcnt vmcnt(17)
	v_dot8_i32_i4 v34, v138, v194, 0
	v_dot8_i32_i4 v35, v138, v198, 0
	v_dot8_i32_i4 v34, v139, v195, v34
	v_dot8_i32_i4 v35, v139, v199, v35
	v_dot8_i32_i4 v34, v140, v196, v34
	v_dot8_i32_i4 v35, v140, v200, v35
	v_dot8_i32_i4 v34, v141, v197, v34
	v_dot8_i32_i4 v35, v141, v201, v35
	v_and_b32_e32 v38, 0xffff, v204
	v_lshl_add_u32 v38, v38, 7, v58
	global_load_dwordx4 v[138:141], v38, s[96:97]
	s_nop 0
	v_lshl_add_u32 v22, v34, 4, v35
	s_waitcnt vmcnt(17)
	v_dot8_i32_i4 v36, v142, v194, 0
	v_dot8_i32_i4 v37, v142, v198, 0
	v_dot8_i32_i4 v36, v143, v195, v36
	v_dot8_i32_i4 v37, v143, v199, v37
	v_dot8_i32_i4 v36, v144, v196, v36
	v_dot8_i32_i4 v37, v144, v200, v37
	v_dot8_i32_i4 v36, v145, v197, v36
	v_dot8_i32_i4 v37, v145, v201, v37
	v_lshrrev_b32_e32 v38, 16, v204
	v_lshl_add_u32 v38, v38, 7, v58
	global_load_dwordx4 v[142:145], v38, s[96:97]
	s_nop 0
	v_lshl_add_u32 v23, v36, 4, v37
	s_waitcnt vmcnt(17)
	v_dot8_i32_i4 v34, v146, v194, 0
	v_dot8_i32_i4 v35, v146, v198, 0
	v_dot8_i32_i4 v34, v147, v195, v34
	v_dot8_i32_i4 v35, v147, v199, v35
	v_dot8_i32_i4 v34, v148, v196, v34
	v_dot8_i32_i4 v35, v148, v200, v35
	v_dot8_i32_i4 v34, v149, v197, v34
	v_dot8_i32_i4 v35, v149, v201, v35
	v_and_b32_e32 v38, 0xffff, v205
	v_lshl_add_u32 v38, v38, 7, v58
	global_load_dwordx4 v[146:149], v38, s[96:97]
	s_nop 0
	v_lshl_add_u32 v24, v34, 4, v35
	s_waitcnt vmcnt(17)
	v_dot8_i32_i4 v36, v150, v194, 0
	v_dot8_i32_i4 v37, v150, v198, 0
	v_dot8_i32_i4 v36, v151, v195, v36
	v_dot8_i32_i4 v37, v151, v199, v37
	v_dot8_i32_i4 v36, v152, v196, v36
	v_dot8_i32_i4 v37, v152, v200, v37
	v_dot8_i32_i4 v36, v153, v197, v36
	v_dot8_i32_i4 v37, v153, v201, v37
	v_lshrrev_b32_e32 v38, 16, v205
	v_lshl_add_u32 v38, v38, 7, v58
	global_load_dwordx4 v[150:153], v38, s[96:97]
	s_nop 0
	v_lshl_add_u32 v25, v36, 4, v37
	s_waitcnt vmcnt(17)
	v_dot8_i32_i4 v34, v154, v194, 0
	v_dot8_i32_i4 v35, v154, v198, 0
	v_dot8_i32_i4 v34, v155, v195, v34
	v_dot8_i32_i4 v35, v155, v199, v35
	v_dot8_i32_i4 v34, v156, v196, v34
	v_dot8_i32_i4 v35, v156, v200, v35
	v_dot8_i32_i4 v34, v157, v197, v34
	v_dot8_i32_i4 v35, v157, v201, v35
	v_and_b32_e32 v38, 0xffff, v206
	v_lshl_add_u32 v38, v38, 7, v58
	global_load_dwordx4 v[154:157], v38, s[96:97]
	s_nop 0
	v_lshl_add_u32 v26, v34, 4, v35
	s_waitcnt vmcnt(17)
	v_dot8_i32_i4 v36, v158, v194, 0
	v_dot8_i32_i4 v37, v158, v198, 0
	v_dot8_i32_i4 v36, v159, v195, v36
	v_dot8_i32_i4 v37, v159, v199, v37
	v_dot8_i32_i4 v36, v160, v196, v36
	v_dot8_i32_i4 v37, v160, v200, v37
	v_dot8_i32_i4 v36, v161, v197, v36
	v_dot8_i32_i4 v37, v161, v201, v37
	v_lshrrev_b32_e32 v38, 16, v206
	v_lshl_add_u32 v38, v38, 7, v58
	global_load_dwordx4 v[158:161], v38, s[96:97]
	s_nop 0
	v_lshl_add_u32 v27, v36, 4, v37
	s_waitcnt vmcnt(17)
	v_dot8_i32_i4 v34, v162, v194, 0
	v_dot8_i32_i4 v35, v162, v198, 0
	v_dot8_i32_i4 v34, v163, v195, v34
	v_dot8_i32_i4 v35, v163, v199, v35
	v_dot8_i32_i4 v34, v164, v196, v34
	v_dot8_i32_i4 v35, v164, v200, v35
	v_dot8_i32_i4 v34, v165, v197, v34
	v_dot8_i32_i4 v35, v165, v201, v35
	v_and_b32_e32 v38, 0xffff, v207
	v_lshl_add_u32 v38, v38, 7, v58
	global_load_dwordx4 v[162:165], v38, s[96:97]
	s_nop 0
	v_lshl_add_u32 v28, v34, 4, v35
	s_waitcnt vmcnt(17)
	v_dot8_i32_i4 v36, v166, v194, 0
	v_dot8_i32_i4 v37, v166, v198, 0
	v_dot8_i32_i4 v36, v167, v195, v36
	v_dot8_i32_i4 v37, v167, v199, v37
	v_dot8_i32_i4 v36, v168, v196, v36
	v_dot8_i32_i4 v37, v168, v200, v37
	v_dot8_i32_i4 v36, v169, v197, v36
	v_dot8_i32_i4 v37, v169, v201, v37
	v_lshrrev_b32_e32 v38, 16, v207
	v_lshl_add_u32 v38, v38, 7, v58
	global_load_dwordx4 v[166:169], v38, s[96:97]
	s_nop 0
	v_lshl_add_u32 v29, v36, 4, v37
	s_waitcnt vmcnt(17)
; #define LAS __attribute__((address_space(3)))
; __device__ __forceinline__ void peer_u_item(int p, int j, const LAS unsigned short* EL  , const unsigned char* __restrict__ XQ, const unsigned char* __restrict__ U8, LAS int* ACC  , int lane, int wave) {
;     ...
;         for (int i = 0; i < 16; ++i) {
;             int sh = __builtin_amdgcn_sdot8((int)uu[i].x, (int)xh.x, 0, false); sh = __builtin_amdgcn_sdot8((int)uu[i].y, (int)xh.y, sh, false);
;             sh = __builtin_amdgcn_sdot8((int)uu[i].z, (int)xh.z, sh, false); sh = __builtin_amdgcn_sdot8((int)uu[i].w, (int)xh.w, sh, false);
;             int sl = __builtin_amdgcn_sdot8((int)uu[i].x, (int)xl.x, 0, false); sl = __builtin_amdgcn_sdot8((int)uu[i].y, (int)xl.y, sl, false);
;             sl = __builtin_amdgcn_sdot8((int)uu[i].z, (int)xl.z, sl, false); sl = __builtin_amdgcn_sdot8((int)uu[i].w, (int)xl.w, sl, false);
;             d[i] = (sh << 4) + sl;
;         }
;         int r0, r1; treduce16i<4, 2, 1>(d, lane, r0, r1);
;         { typedef int i2v __attribute__((ext_vector_type(2))); LAS i2v* ap = (LAS i2v*)(ACC + (it * 8 + wave) * 128 + 2 * lane);
;           i2v a2; if (p == 0) { a2.x = r0; a2.y = r1; } else { a2 = *ap; a2.x += r0; a2.y += r1; } *ap = a2; }
	v_dot8_i32_i4 v34, v170, v194, 0
	v_dot8_i32_i4 v35, v170, v198, 0
	v_dot8_i32_i4 v34, v171, v195, v34
	v_dot8_i32_i4 v35, v171, v199, v35
	v_dot8_i32_i4 v34, v172, v196, v34
	v_dot8_i32_i4 v35, v172, v200, v35
	v_dot8_i32_i4 v34, v173, v197, v34
	v_dot8_i32_i4 v35, v173, v201, v35
	v_and_b32_e32 v38, 0xffff, v208
	v_lshl_add_u32 v38, v38, 7, v58
	global_load_dwordx4 v[170:173], v38, s[96:97]
	s_nop 0
	v_lshl_add_u32 v30, v34, 4, v35
	s_waitcnt vmcnt(17)
	v_dot8_i32_i4 v36, v174, v194, 0
	v_dot8_i32_i4 v37, v174, v198, 0
	v_dot8_i32_i4 v36, v175, v195, v36
	v_dot8_i32_i4 v37, v175, v199, v37
	v_dot8_i32_i4 v36, v176, v196, v36
	v_dot8_i32_i4 v37, v176, v200, v37
	v_dot8_i32_i4 v36, v177, v197, v36
	v_dot8_i32_i4 v37, v177, v201, v37
	v_lshrrev_b32_e32 v38, 16, v208
	v_lshl_add_u32 v38, v38, 7, v58
	global_load_dwordx4 v[174:177], v38, s[96:97]
	s_nop 0
	v_lshl_add_u32 v31, v36, 4, v37
	s_waitcnt vmcnt(17)
	v_dot8_i32_i4 v34, v178, v194, 0
	v_dot8_i32_i4 v35, v178, v198, 0
	v_dot8_i32_i4 v34, v179, v195, v34
	v_dot8_i32_i4 v35, v179, v199, v35
	v_dot8_i32_i4 v34, v180, v196, v34
	v_dot8_i32_i4 v35, v180, v200, v35
	v_dot8_i32_i4 v34, v181, v197, v34
	v_dot8_i32_i4 v35, v181, v201, v35
	v_and_b32_e32 v38, 0xffff, v209
	v_lshl_add_u32 v38, v38, 7, v58
	global_load_dwordx4 v[178:181], v38, s[96:97]
	s_nop 0
	v_lshl_add_u32 v32, v34, 4, v35
	s_waitcnt vmcnt(17)
	v_dot8_i32_i4 v36, v182, v194, 0
	v_dot8_i32_i4 v37, v182, v198, 0
	v_dot8_i32_i4 v36, v183, v195, v36
	v_dot8_i32_i4 v37, v183, v199, v37
	v_dot8_i32_i4 v36, v184, v196, v36
	v_dot8_i32_i4 v37, v184, v200, v37
	v_dot8_i32_i4 v36, v185, v197, v36
	v_dot8_i32_i4 v37, v185, v201, v37
	v_lshrrev_b32_e32 v38, 16, v209
	v_lshl_add_u32 v38, v38, 7, v58
	global_load_dwordx4 v[182:185], v38, s[96:97]
	s_nop 0
	v_lshl_add_u32 v33, v36, 4, v37
	v_cndmask_b32_e64 v40, v26, v18, s[10:11]
	v_cndmask_b32_e64 v48, v18, v26, s[10:11]
	v_cndmask_b32_e64 v41, v27, v19, s[10:11]
	v_cndmask_b32_e64 v49, v19, v27, s[10:11]
	v_cndmask_b32_e64 v42, v28, v20, s[10:11]
	v_cndmask_b32_e64 v50, v20, v28, s[10:11]
	v_cndmask_b32_e64 v43, v29, v21, s[10:11]
	v_cndmask_b32_e64 v51, v21, v29, s[10:11]
	v_cndmask_b32_e64 v44, v30, v22, s[10:11]
	v_cndmask_b32_e64 v52, v22, v30, s[10:11]
	v_cndmask_b32_e64 v45, v31, v23, s[10:11]
	v_cndmask_b32_e64 v53, v23, v31, s[10:11]
	v_cndmask_b32_e64 v46, v32, v24, s[10:11]
	v_cndmask_b32_e64 v54, v24, v32, s[10:11]
	v_cndmask_b32_e64 v47, v33, v25, s[10:11]
	v_cndmask_b32_e64 v55, v25, v33, s[10:11]
	v_add_u32_dpp v18, v40, v48 row_shr:4 row_mask:0xf bank_mask:0xa
	v_add_u32_dpp v18, v40, v48 row_shl:4 row_mask:0xf bank_mask:0x5
	v_add_u32_dpp v19, v41, v49 row_shr:4 row_mask:0xf bank_mask:0xa
	v_add_u32_dpp v19, v41, v49 row_shl:4 row_mask:0xf bank_mask:0x5
	v_add_u32_dpp v20, v42, v50 row_shr:4 row_mask:0xf bank_mask:0xa
	v_add_u32_dpp v20, v42, v50 row_shl:4 row_mask:0xf bank_mask:0x5
	v_add_u32_dpp v21, v43, v51 row_shr:4 row_mask:0xf bank_mask:0xa
	v_add_u32_dpp v21, v43, v51 row_shl:4 row_mask:0xf bank_mask:0x5
	v_add_u32_dpp v22, v44, v52 row_shr:4 row_mask:0xf bank_mask:0xa
	v_add_u32_dpp v22, v44, v52 row_shl:4 row_mask:0xf bank_mask:0x5
	v_add_u32_dpp v23, v45, v53 row_shr:4 row_mask:0xf bank_mask:0xa
	v_add_u32_dpp v23, v45, v53 row_shl:4 row_mask:0xf bank_mask:0x5
	v_add_u32_dpp v24, v46, v54 row_shr:4 row_mask:0xf bank_mask:0xa
	v_add_u32_dpp v24, v46, v54 row_shl:4 row_mask:0xf bank_mask:0x5
	v_add_u32_dpp v25, v47, v55 row_shr:4 row_mask:0xf bank_mask:0xa
	v_add_u32_dpp v25, v47, v55 row_shl:4 row_mask:0xf bank_mask:0x5
	v_cndmask_b32_e64 v40, v22, v18, s[12:13]
	v_cndmask_b32_e64 v48, v18, v22, s[12:13]
	v_cndmask_b32_e64 v41, v23, v19, s[12:13]
	v_cndmask_b32_e64 v49, v19, v23, s[12:13]
	v_cndmask_b32_e64 v42, v24, v20, s[12:13]
	v_cndmask_b32_e64 v50, v20, v24, s[12:13]
	v_cndmask_b32_e64 v43, v25, v21, s[12:13]
	v_cndmask_b32_e64 v51, v21, v25, s[12:13]
	s_nop 0
	v_add_u32_dpp v26, v40, v48 quad_perm:[2,3,0,1] row_mask:0xf bank_mask:0xf
	v_add_u32_dpp v27, v41, v49 quad_perm:[2,3,0,1] row_mask:0xf bank_mask:0xf
	v_add_u32_dpp v28, v42, v50 quad_perm:[2,3,0,1] row_mask:0xf bank_mask:0xf
	v_add_u32_dpp v29, v43, v51 quad_perm:[2,3,0,1] row_mask:0xf bank_mask:0xf
	v_cndmask_b32_e64 v40, v28, v26, s[14:15]
	v_cndmask_b32_e64 v48, v26, v28, s[14:15]
	v_cndmask_b32_e64 v41, v29, v27, s[14:15]
	v_cndmask_b32_e64 v49, v27, v29, s[14:15]
	s_nop 1
	v_add_u32_dpp v44, v40, v48 quad_perm:[1,0,3,2] row_mask:0xf bank_mask:0xf
	v_add_u32_dpp v45, v41, v49 quad_perm:[1,0,3,2] row_mask:0xf bank_mask:0xf
	s_cmp_eq_u32 s43, 0
	s_cselect_b32 s32, 0, -1
	v_and_b32_e32 v62, s32, v62
	v_and_b32_e32 v63, s32, v63
	v_add_u32_e32 v44, v44, v62
	v_add_u32_e32 v45, v45, v63
	ds_write_b64 v61, v[44:45]
	s_mov_b32 s42, s44
	s_mov_b32 s43, s45
	s_add_i32 s44, s44, 1
	s_and_b32 s44, s44, 7
	s_cmp_eq_u32 s44, 0
	s_cselect_b32 s32, 1, 0
	s_add_i32 s45, s45, s32
	s_and_b32 s45, s45, 3
	s_add_i32 s47, s47, -1
	s_cmp_lg_u32 s47, 0
	s_cbranch_scc1 .Lpu_trip
; #define LAS __attribute__((address_space(3)))
; __device__ __forceinline__ void peer_u_item(int p, int j, const LAS unsigned short* EL  , const unsigned char* __restrict__ XQ, const unsigned char* __restrict__ U8, LAS int* ACC  , int lane, int wave) {
;     ...
;     for (int it = 0; it < 8; ++it) {
;         const int t = j * 64 + it * 8 + wave;
;         unsigned E[8];
;         { const LAS v4u* ep = (const LAS v4u*)(EL + (it * 8 + wave) * 128 + 16 * gidx); const v4u e0 = ep[0], e1 = ep[1];
;           E[0] = e0.x; E[1] = e0.y; E[2] = e0.z; E[3] = e0.w; E[4] = e1.x; E[5] = e1.y; E[6] = e1.z; E[7] = e1.w; }
;         uint4 uu[16];
; #pragma unroll
;         for (int i = 0; i < 16; ++i) uu[i] = *(const uint4*)(U8 + (size_t)(PE_ID(E, i) * 128u + toff));
;         const uint4 xh = *(const uint4*)(XQ + (size_t)t * 512 + coff), xl = *(const uint4*)(XQ + 8 * MiB + (size_t)t * 512 + coff);
;         int d[16];
; #pragma unroll
;         for (int i = 0; i < 16; ++i) {
;             int sh = __builtin_amdgcn_sdot8((int)uu[i].x, (int)xh.x, 0, false); sh = __builtin_amdgcn_sdot8((int)uu[i].y, (int)xh.y, sh, false);
;             sh = __builtin_amdgcn_sdot8((int)uu[i].z, (int)xh.z, sh, false); sh = __builtin_amdgcn_sdot8((int)uu[i].w, (int)xh.w, sh, false);
;             int sl = __builtin_amdgcn_sdot8((int)uu[i].x, (int)xl.x, 0, false); sl = __builtin_amdgcn_sdot8((int)uu[i].y, (int)xl.y, sl, false);
;             sl = __builtin_amdgcn_sdot8((int)uu[i].z, (int)xl.z, sl, false); sl = __builtin_amdgcn_sdot8((int)uu[i].w, (int)xl.w, sl, false);
;             d[i] = (sh << 4) + sl;
;         }
;         int r0, r1; treduce16i<4, 2, 1>(d, lane, r0, r1);
;         { typedef int i2v __attribute__((ext_vector_type(2))); LAS i2v* ap = (LAS i2v*)(ACC + (it * 8 + wave) * 128 + 2 * lane);
;           i2v a2; if (p == 0) { a2.x = r0; a2.y = r1; } else { a2 = *ap; a2.x += r0; a2.y += r1; } *ap = a2; }
	s_lshl_b32 s32, s44, 11
	v_add_u32_e32 v39, s32, v59
	ds_read_b128 v[210:213], v39
	ds_read_b128 v[214:217], v39 offset:16
	s_lshl_b32 s32, s42, 12
	v_add_u32_e32 v61, s32, v60
	ds_read_b64 v[62:63], v61
	s_lshl_b32 s46, s44, 3
	s_add_i32 s46, s46, s40
	s_lshl_b32 s46, s46, 9
	s_lshl_b32 s32, s45, 7
	s_add_i32 s46, s46, s32
	v_add_u32_e32 v57, s46, v56
	global_load_dwordx4 v[194:197], v57, s[34:35]
	global_load_dwordx4 v[198:201], v57, s[36:37]
	s_lshl_b32 s32, s45, 21
	v_add_u32_e32 v58, s32, v56
	s_waitcnt lgkmcnt(0)
	s_waitcnt vmcnt(17)
	v_dot8_i32_i4 v34, v122, v186, 0
	v_dot8_i32_i4 v35, v122, v190, 0
	v_dot8_i32_i4 v34, v123, v187, v34
	v_dot8_i32_i4 v35, v123, v191, v35
	v_dot8_i32_i4 v34, v124, v188, v34
	v_dot8_i32_i4 v35, v124, v192, v35
	v_dot8_i32_i4 v34, v125, v189, v34
	v_dot8_i32_i4 v35, v125, v193, v35
	v_and_b32_e32 v38, 0xffff, v210
	v_lshl_add_u32 v38, v38, 7, v58
	global_load_dwordx4 v[122:125], v38, s[96:97]
	s_nop 0
	v_lshl_add_u32 v18, v34, 4, v35
	s_waitcnt vmcnt(17)
	v_dot8_i32_i4 v36, v126, v186, 0
	v_dot8_i32_i4 v37, v126, v190, 0
	v_dot8_i32_i4 v36, v127, v187, v36
	v_dot8_i32_i4 v37, v127, v191, v37
	v_dot8_i32_i4 v36, v128, v188, v36
	v_dot8_i32_i4 v37, v128, v192, v37
	v_dot8_i32_i4 v36, v129, v189, v36
	v_dot8_i32_i4 v37, v129, v193, v37
	v_lshrrev_b32_e32 v38, 16, v210
	v_lshl_add_u32 v38, v38, 7, v58
	global_load_dwordx4 v[126:129], v38, s[96:97]
	s_nop 0
	v_lshl_add_u32 v19, v36, 4, v37
	s_waitcnt vmcnt(17)
	v_dot8_i32_i4 v34, v130, v186, 0
	v_dot8_i32_i4 v35, v130, v190, 0
	v_dot8_i32_i4 v34, v131, v187, v34
	v_dot8_i32_i4 v35, v131, v191, v35
	v_dot8_i32_i4 v34, v132, v188, v34
	v_dot8_i32_i4 v35, v132, v192, v35
	v_dot8_i32_i4 v34, v133, v189, v34
	v_dot8_i32_i4 v35, v133, v193, v35
	v_and_b32_e32 v38, 0xffff, v211
	v_lshl_add_u32 v38, v38, 7, v58
	global_load_dwordx4 v[130:133], v38, s[96:97]
	s_nop 0
	v_lshl_add_u32 v20, v34, 4, v35
	s_waitcnt vmcnt(17)
	v_dot8_i32_i4 v36, v134, v186, 0
	v_dot8_i32_i4 v37, v134, v190, 0
	v_dot8_i32_i4 v36, v135, v187, v36
	v_dot8_i32_i4 v37, v135, v191, v37
	v_dot8_i32_i4 v36, v136, v188, v36
	v_dot8_i32_i4 v37, v136, v192, v37
	v_dot8_i32_i4 v36, v137, v189, v36
	v_dot8_i32_i4 v37, v137, v193, v37
	v_lshrrev_b32_e32 v38, 16, v211
	v_lshl_add_u32 v38, v38, 7, v58
	global_load_dwordx4 v[134:137], v38, s[96:97]
	s_nop 0
	v_lshl_add_u32 v21, v36, 4, v37
	s_waitcnt vmcnt(17)
	v_dot8_i32_i4 v34, v138, v186, 0
	v_dot8_i32_i4 v35, v138, v190, 0
	v_dot8_i32_i4 v34, v139, v187, v34
	v_dot8_i32_i4 v35, v139, v191, v35
	v_dot8_i32_i4 v34, v140, v188, v34
	v_dot8_i32_i4 v35, v140, v192, v35
	v_dot8_i32_i4 v34, v141, v189, v34
	v_dot8_i32_i4 v35, v141, v193, v35
	v_and_b32_e32 v38, 0xffff, v212
	v_lshl_add_u32 v38, v38, 7, v58
	global_load_dwordx4 v[138:141], v38, s[96:97]
	s_nop 0
	v_lshl_add_u32 v22, v34, 4, v35
	s_waitcnt vmcnt(17)
	v_dot8_i32_i4 v36, v142, v186, 0
	v_dot8_i32_i4 v37, v142, v190, 0
	v_dot8_i32_i4 v36, v143, v187, v36
	v_dot8_i32_i4 v37, v143, v191, v37
	v_dot8_i32_i4 v36, v144, v188, v36
	v_dot8_i32_i4 v37, v144, v192, v37
	v_dot8_i32_i4 v36, v145, v189, v36
	v_dot8_i32_i4 v37, v145, v193, v37
	v_lshrrev_b32_e32 v38, 16, v212
	v_lshl_add_u32 v38, v38, 7, v58
	global_load_dwordx4 v[142:145], v38, s[96:97]
	s_nop 0
	v_lshl_add_u32 v23, v36, 4, v37
	s_waitcnt vmcnt(17)
	v_dot8_i32_i4 v34, v146, v186, 0
	v_dot8_i32_i4 v35, v146, v190, 0
	v_dot8_i32_i4 v34, v147, v187, v34
	v_dot8_i32_i4 v35, v147, v191, v35
	v_dot8_i32_i4 v34, v148, v188, v34
	v_dot8_i32_i4 v35, v148, v192, v35
	v_dot8_i32_i4 v34, v149, v189, v34
	v_dot8_i32_i4 v35, v149, v193, v35
	v_and_b32_e32 v38, 0xffff, v213
	v_lshl_add_u32 v38, v38, 7, v58
	global_load_dwordx4 v[146:149], v38, s[96:97]
	s_nop 0
	v_lshl_add_u32 v24, v34, 4, v35
	s_waitcnt vmcnt(17)
	v_dot8_i32_i4 v36, v150, v186, 0
	v_dot8_i32_i4 v37, v150, v190, 0
	v_dot8_i32_i4 v36, v151, v187, v36
	v_dot8_i32_i4 v37, v151, v191, v37
	v_dot8_i32_i4 v36, v152, v188, v36
	v_dot8_i32_i4 v37, v152, v192, v37
	v_dot8_i32_i4 v36, v153, v189, v36
	v_dot8_i32_i4 v37, v153, v193, v37
	v_lshrrev_b32_e32 v38, 16, v213
	v_lshl_add_u32 v38, v38, 7, v58
	global_load_dwordx4 v[150:153], v38, s[96:97]
	s_nop 0
	v_lshl_add_u32 v25, v36, 4, v37
	s_waitcnt vmcnt(17)
	v_dot8_i32_i4 v34, v154, v186, 0
	v_dot8_i32_i4 v35, v154, v190, 0
	v_dot8_i32_i4 v34, v155, v187, v34
	v_dot8_i32_i4 v35, v155, v191, v35
	v_dot8_i32_i4 v34, v156, v188, v34
	v_dot8_i32_i4 v35, v156, v192, v35
	v_dot8_i32_i4 v34, v157, v189, v34
	v_dot8_i32_i4 v35, v157, v193, v35
	v_and_b32_e32 v38, 0xffff, v214
	v_lshl_add_u32 v38, v38, 7, v58
	global_load_dwordx4 v[154:157], v38, s[96:97]
	s_nop 0
	v_lshl_add_u32 v26, v34, 4, v35
	s_waitcnt vmcnt(17)
	v_dot8_i32_i4 v36, v158, v186, 0
	v_dot8_i32_i4 v37, v158, v190, 0
	v_dot8_i32_i4 v36, v159, v187, v36
	v_dot8_i32_i4 v37, v159, v191, v37
	v_dot8_i32_i4 v36, v160, v188, v36
	v_dot8_i32_i4 v37, v160, v192, v37
	v_dot8_i32_i4 v36, v161, v189, v36
	v_dot8_i32_i4 v37, v161, v193, v37
	v_lshrrev_b32_e32 v38, 16, v214
	v_lshl_add_u32 v38, v38, 7, v58
	global_load_dwordx4 v[158:161], v38, s[96:97]
	s_nop 0
	v_lshl_add_u32 v27, v36, 4, v37
	s_waitcnt vmcnt(17)
	v_dot8_i32_i4 v34, v162, v186, 0
	v_dot8_i32_i4 v35, v162, v190, 0
	v_dot8_i32_i4 v34, v163, v187, v34
	v_dot8_i32_i4 v35, v163, v191, v35
	v_dot8_i32_i4 v34, v164, v188, v34
	v_dot8_i32_i4 v35, v164, v192, v35
	v_dot8_i32_i4 v34, v165, v189, v34
	v_dot8_i32_i4 v35, v165, v193, v35
	v_and_b32_e32 v38, 0xffff, v215
	v_lshl_add_u32 v38, v38, 7, v58
	global_load_dwordx4 v[162:165], v38, s[96:97]
	s_nop 0
	v_lshl_add_u32 v28, v34, 4, v35
	s_waitcnt vmcnt(17)
; #define LAS __attribute__((address_space(3)))
; __device__ __forceinline__ void peer_u_item(int p, int j, const LAS unsigned short* EL  , const unsigned char* __restrict__ XQ, const unsigned char* __restrict__ U8, LAS int* ACC  , int lane, int wave) {
;     ...
;         for (int i = 0; i < 16; ++i) {
;             int sh = __builtin_amdgcn_sdot8((int)uu[i].x, (int)xh.x, 0, false); sh = __builtin_amdgcn_sdot8((int)uu[i].y, (int)xh.y, sh, false);
;             sh = __builtin_amdgcn_sdot8((int)uu[i].z, (int)xh.z, sh, false); sh = __builtin_amdgcn_sdot8((int)uu[i].w, (int)xh.w, sh, false);
;             int sl = __builtin_amdgcn_sdot8((int)uu[i].x, (int)xl.x, 0, false); sl = __builtin_amdgcn_sdot8((int)uu[i].y, (int)xl.y, sl, false);
;             sl = __builtin_amdgcn_sdot8((int)uu[i].z, (int)xl.z, sl, false); sl = __builtin_amdgcn_sdot8((int)uu[i].w, (int)xl.w, sl, false);
;             d[i] = (sh << 4) + sl;
;         }
;         int r0, r1; treduce16i<4, 2, 1>(d, lane, r0, r1);
;         { typedef int i2v __attribute__((ext_vector_type(2))); LAS i2v* ap = (LAS i2v*)(ACC + (it * 8 + wave) * 128 + 2 * lane);
;           i2v a2; if (p == 0) { a2.x = r0; a2.y = r1; } else { a2 = *ap; a2.x += r0; a2.y += r1; } *ap = a2; }
; __global__ void __launch_bounds__(NTHR, 2) k_main(Args a) {
;     ...
;                 const int tl = it * 8 + wave, t = j * 64 + tl;
;                 const unsigned ew = *(const LAS unsigned*)(EL + tl * 128 + 2 * lane); const int e0 = (int)(ew & 0xffffu), e1 = (int)(ew >> 16);
;                 typedef int i2v __attribute__((ext_vector_type(2))); const i2v si = *(const LAS i2v*)(ACC + tl * 128 + 2 * lane);
;                 typedef float f2v __attribute__((ext_vector_type(2))); const f2v gt = *(const LAS f2v*)(GL + tl * 128 + 2 * lane); const float xs = XS[t];
	v_dot8_i32_i4 v36, v166, v186, 0
	v_dot8_i32_i4 v37, v166, v190, 0
	v_dot8_i32_i4 v36, v167, v187, v36
	v_dot8_i32_i4 v37, v167, v191, v37
	v_dot8_i32_i4 v36, v168, v188, v36
	v_dot8_i32_i4 v37, v168, v192, v37
	v_dot8_i32_i4 v36, v169, v189, v36
	v_dot8_i32_i4 v37, v169, v193, v37
	v_lshrrev_b32_e32 v38, 16, v215
	v_lshl_add_u32 v38, v38, 7, v58
	global_load_dwordx4 v[166:169], v38, s[96:97]
	s_nop 0
	v_lshl_add_u32 v29, v36, 4, v37
	s_waitcnt vmcnt(17)
	v_dot8_i32_i4 v34, v170, v186, 0
	v_dot8_i32_i4 v35, v170, v190, 0
	v_dot8_i32_i4 v34, v171, v187, v34
	v_dot8_i32_i4 v35, v171, v191, v35
	v_dot8_i32_i4 v34, v172, v188, v34
	v_dot8_i32_i4 v35, v172, v192, v35
	v_dot8_i32_i4 v34, v173, v189, v34
	v_dot8_i32_i4 v35, v173, v193, v35
	v_and_b32_e32 v38, 0xffff, v216
	v_lshl_add_u32 v38, v38, 7, v58
	global_load_dwordx4 v[170:173], v38, s[96:97]
	s_nop 0
	v_lshl_add_u32 v30, v34, 4, v35
	s_waitcnt vmcnt(17)
	v_dot8_i32_i4 v36, v174, v186, 0
	v_dot8_i32_i4 v37, v174, v190, 0
	v_dot8_i32_i4 v36, v175, v187, v36
	v_dot8_i32_i4 v37, v175, v191, v37
	v_dot8_i32_i4 v36, v176, v188, v36
	v_dot8_i32_i4 v37, v176, v192, v37
	v_dot8_i32_i4 v36, v177, v189, v36
	v_dot8_i32_i4 v37, v177, v193, v37
	v_lshrrev_b32_e32 v38, 16, v216
	v_lshl_add_u32 v38, v38, 7, v58
	global_load_dwordx4 v[174:177], v38, s[96:97]
	s_nop 0
	v_lshl_add_u32 v31, v36, 4, v37
	s_waitcnt vmcnt(17)
	v_dot8_i32_i4 v34, v178, v186, 0
	v_dot8_i32_i4 v35, v178, v190, 0
	v_dot8_i32_i4 v34, v179, v187, v34
	v_dot8_i32_i4 v35, v179, v191, v35
	v_dot8_i32_i4 v34, v180, v188, v34
	v_dot8_i32_i4 v35, v180, v192, v35
	v_dot8_i32_i4 v34, v181, v189, v34
	v_dot8_i32_i4 v35, v181, v193, v35
	v_and_b32_e32 v38, 0xffff, v217
	v_lshl_add_u32 v38, v38, 7, v58
	global_load_dwordx4 v[178:181], v38, s[96:97]
	s_nop 0
	v_lshl_add_u32 v32, v34, 4, v35
	s_waitcnt vmcnt(17)
	v_dot8_i32_i4 v36, v182, v186, 0
	v_dot8_i32_i4 v37, v182, v190, 0
	v_dot8_i32_i4 v36, v183, v187, v36
	v_dot8_i32_i4 v37, v183, v191, v37
	v_dot8_i32_i4 v36, v184, v188, v36
	v_dot8_i32_i4 v37, v184, v192, v37
	v_dot8_i32_i4 v36, v185, v189, v36
	v_dot8_i32_i4 v37, v185, v193, v37
	v_lshrrev_b32_e32 v38, 16, v217
	v_lshl_add_u32 v38, v38, 7, v58
	global_load_dwordx4 v[182:185], v38, s[96:97]
	s_nop 0
	v_lshl_add_u32 v33, v36, 4, v37
	v_cndmask_b32_e64 v40, v26, v18, s[10:11]
	v_cndmask_b32_e64 v48, v18, v26, s[10:11]
	v_cndmask_b32_e64 v41, v27, v19, s[10:11]
	v_cndmask_b32_e64 v49, v19, v27, s[10:11]
	v_cndmask_b32_e64 v42, v28, v20, s[10:11]
	v_cndmask_b32_e64 v50, v20, v28, s[10:11]
	v_cndmask_b32_e64 v43, v29, v21, s[10:11]
	v_cndmask_b32_e64 v51, v21, v29, s[10:11]
	v_cndmask_b32_e64 v44, v30, v22, s[10:11]
	v_cndmask_b32_e64 v52, v22, v30, s[10:11]
	v_cndmask_b32_e64 v45, v31, v23, s[10:11]
	v_cndmask_b32_e64 v53, v23, v31, s[10:11]
	v_cndmask_b32_e64 v46, v32, v24, s[10:11]
	v_cndmask_b32_e64 v54, v24, v32, s[10:11]
	v_cndmask_b32_e64 v47, v33, v25, s[10:11]
	v_cndmask_b32_e64 v55, v25, v33, s[10:11]
	v_add_u32_dpp v18, v40, v48 row_shr:4 row_mask:0xf bank_mask:0xa
	v_add_u32_dpp v18, v40, v48 row_shl:4 row_mask:0xf bank_mask:0x5
	v_add_u32_dpp v19, v41, v49 row_shr:4 row_mask:0xf bank_mask:0xa
	v_add_u32_dpp v19, v41, v49 row_shl:4 row_mask:0xf bank_mask:0x5
	v_add_u32_dpp v20, v42, v50 row_shr:4 row_mask:0xf bank_mask:0xa
	v_add_u32_dpp v20, v42, v50 row_shl:4 row_mask:0xf bank_mask:0x5
	v_add_u32_dpp v21, v43, v51 row_shr:4 row_mask:0xf bank_mask:0xa
	v_add_u32_dpp v21, v43, v51 row_shl:4 row_mask:0xf bank_mask:0x5
	v_add_u32_dpp v22, v44, v52 row_shr:4 row_mask:0xf bank_mask:0xa
	v_add_u32_dpp v22, v44, v52 row_shl:4 row_mask:0xf bank_mask:0x5
	v_add_u32_dpp v23, v45, v53 row_shr:4 row_mask:0xf bank_mask:0xa
	v_add_u32_dpp v23, v45, v53 row_shl:4 row_mask:0xf bank_mask:0x5
	v_add_u32_dpp v24, v46, v54 row_shr:4 row_mask:0xf bank_mask:0xa
	v_add_u32_dpp v24, v46, v54 row_shl:4 row_mask:0xf bank_mask:0x5
	v_add_u32_dpp v25, v47, v55 row_shr:4 row_mask:0xf bank_mask:0xa
	v_add_u32_dpp v25, v47, v55 row_shl:4 row_mask:0xf bank_mask:0x5
	v_cndmask_b32_e64 v40, v22, v18, s[12:13]
	v_cndmask_b32_e64 v48, v18, v22, s[12:13]
	v_cndmask_b32_e64 v41, v23, v19, s[12:13]
	v_cndmask_b32_e64 v49, v19, v23, s[12:13]
	v_cndmask_b32_e64 v42, v24, v20, s[12:13]
	v_cndmask_b32_e64 v50, v20, v24, s[12:13]
	v_cndmask_b32_e64 v43, v25, v21, s[12:13]
	v_cndmask_b32_e64 v51, v21, v25, s[12:13]
	s_nop 0
	v_add_u32_dpp v26, v40, v48 quad_perm:[2,3,0,1] row_mask:0xf bank_mask:0xf
	v_add_u32_dpp v27, v41, v49 quad_perm:[2,3,0,1] row_mask:0xf bank_mask:0xf
	v_add_u32_dpp v28, v42, v50 quad_perm:[2,3,0,1] row_mask:0xf bank_mask:0xf
	v_add_u32_dpp v29, v43, v51 quad_perm:[2,3,0,1] row_mask:0xf bank_mask:0xf
	v_cndmask_b32_e64 v40, v28, v26, s[14:15]
	v_cndmask_b32_e64 v48, v26, v28, s[14:15]
	v_cndmask_b32_e64 v41, v29, v27, s[14:15]
	v_cndmask_b32_e64 v49, v27, v29, s[14:15]
	s_nop 1
	v_add_u32_dpp v44, v40, v48 quad_perm:[1,0,3,2] row_mask:0xf bank_mask:0xf
	v_add_u32_dpp v45, v41, v49 quad_perm:[1,0,3,2] row_mask:0xf bank_mask:0xf
	s_cmp_eq_u32 s43, 0
	s_cselect_b32 s32, 0, -1
	v_and_b32_e32 v62, s32, v62
	v_and_b32_e32 v63, s32, v63
	v_add_u32_e32 v44, v44, v62
	v_add_u32_e32 v45, v45, v63
	ds_write_b64 v61, v[44:45]
	s_mov_b32 s42, s44
	s_mov_b32 s43, s45
	s_add_i32 s44, s44, 1
	s_and_b32 s44, s44, 7
	s_cmp_eq_u32 s44, 0
	s_cselect_b32 s32, 1, 0
	s_add_i32 s45, s45, s32
	s_and_b32 s45, s45, 3
	s_lshl_b32 s32, s42, 12
	v_add_u32_e32 v61, s32, v60
	ds_read_b64 v[62:63], v61
	v_readlane_b32 s98, v235, 36
	v_readlane_b32 s99, v235, 37
	ds_read_b32 v64, v92
	ds_read_b32 v65, v92 offset:2048
	ds_read_b32 v66, v92 offset:4096
	ds_read_b32 v67, v92 offset:6144
	ds_read_b32 v68, v92 offset:8192
	ds_read_b32 v69, v92 offset:10240
	ds_read_b32 v70, v92 offset:12288
	ds_read_b32 v71, v92 offset:14336
	s_waitcnt lgkmcnt(0)
; #define LAS __attribute__((address_space(3)))
; __device__ __forceinline__ void peer_u_item(int p, int j, const LAS unsigned short* EL  , const unsigned char* __restrict__ XQ, const unsigned char* __restrict__ U8, LAS int* ACC  , int lane, int wave) {
;     ...
;         for (int i = 0; i < 16; ++i) {
;             int sh = __builtin_amdgcn_sdot8((int)uu[i].x, (int)xh.x, 0, false); sh = __builtin_amdgcn_sdot8((int)uu[i].y, (int)xh.y, sh, false);
;             sh = __builtin_amdgcn_sdot8((int)uu[i].z, (int)xh.z, sh, false); sh = __builtin_amdgcn_sdot8((int)uu[i].w, (int)xh.w, sh, false);
;             int sl = __builtin_amdgcn_sdot8((int)uu[i].x, (int)xl.x, 0, false); sl = __builtin_amdgcn_sdot8((int)uu[i].y, (int)xl.y, sl, false);
;             sl = __builtin_amdgcn_sdot8((int)uu[i].z, (int)xl.z, sl, false); sl = __builtin_amdgcn_sdot8((int)uu[i].w, (int)xl.w, sl, false);
;             d[i] = (sh << 4) + sl;
;         }
; __global__ void __launch_bounds__(NTHR, 2) k_main(Args a) {
;     ...
;                 const int tl = it * 8 + wave, t = j * 64 + tl;
;                 const unsigned ew = *(const LAS unsigned*)(EL + tl * 128 + 2 * lane); const int e0 = (int)(ew & 0xffffu), e1 = (int)(ew >> 16);
;                 typedef int i2v __attribute__((ext_vector_type(2))); const i2v si = *(const LAS i2v*)(ACC + tl * 128 + 2 * lane);
;                 typedef float f2v __attribute__((ext_vector_type(2))); const f2v gt = *(const LAS f2v*)(GL + tl * 128 + 2 * lane); const float xs = XS[t];
;                 const int sx = ((const int*)(XS + T))[t];
;                 const float z0 = (float)(2 * si.x + sx) * SU[e0] * xs, z1 = (float)(2 * si.y + sx) * SU[e1] * xs;
	s_lshl_b32 s100, s40, 2
	s_add_u32 s100, s90, s100
	s_addc_u32 s101, s91, 0
	v_mov_b32_e32 v234, 3
	global_load_dword v252, v83, s[38:39] sc1
	v_lshlrev_b32_sdwa v80, v234, v64 dst_sel:DWORD dst_unused:UNUSED_PAD src0_sel:DWORD src1_sel:WORD_0
	v_lshlrev_b32_sdwa v81, v234, v64 dst_sel:DWORD dst_unused:UNUSED_PAD src0_sel:DWORD src1_sel:WORD_1
	s_nop 1
	global_load_dwordx2 v[218:219], v80, s[98:99]
	global_load_dwordx2 v[236:237], v81, s[98:99]
	v_lshlrev_b32_sdwa v80, v234, v65 dst_sel:DWORD dst_unused:UNUSED_PAD src0_sel:DWORD src1_sel:WORD_0
	v_lshlrev_b32_sdwa v81, v234, v65 dst_sel:DWORD dst_unused:UNUSED_PAD src0_sel:DWORD src1_sel:WORD_1
	s_nop 1
	global_load_dwordx2 v[220:221], v80, s[98:99]
	global_load_dwordx2 v[238:239], v81, s[98:99]
	v_lshlrev_b32_sdwa v80, v234, v66 dst_sel:DWORD dst_unused:UNUSED_PAD src0_sel:DWORD src1_sel:WORD_0
	v_lshlrev_b32_sdwa v81, v234, v66 dst_sel:DWORD dst_unused:UNUSED_PAD src0_sel:DWORD src1_sel:WORD_1
	s_nop 1
	global_load_dwordx2 v[222:223], v80, s[98:99]
	global_load_dwordx2 v[240:241], v81, s[98:99]
	v_lshlrev_b32_sdwa v80, v234, v67 dst_sel:DWORD dst_unused:UNUSED_PAD src0_sel:DWORD src1_sel:WORD_0
	v_lshlrev_b32_sdwa v81, v234, v67 dst_sel:DWORD dst_unused:UNUSED_PAD src0_sel:DWORD src1_sel:WORD_1
	s_nop 1
	global_load_dwordx2 v[224:225], v80, s[98:99]
	global_load_dwordx2 v[242:243], v81, s[98:99]
	v_lshlrev_b32_sdwa v80, v234, v68 dst_sel:DWORD dst_unused:UNUSED_PAD src0_sel:DWORD src1_sel:WORD_0
	v_lshlrev_b32_sdwa v81, v234, v68 dst_sel:DWORD dst_unused:UNUSED_PAD src0_sel:DWORD src1_sel:WORD_1
	s_nop 1
	global_load_dwordx2 v[226:227], v80, s[98:99]
	global_load_dwordx2 v[244:245], v81, s[98:99]
	v_lshlrev_b32_sdwa v80, v234, v69 dst_sel:DWORD dst_unused:UNUSED_PAD src0_sel:DWORD src1_sel:WORD_0
	v_lshlrev_b32_sdwa v81, v234, v69 dst_sel:DWORD dst_unused:UNUSED_PAD src0_sel:DWORD src1_sel:WORD_1
	s_nop 1
	global_load_dwordx2 v[228:229], v80, s[98:99]
	global_load_dwordx2 v[246:247], v81, s[98:99]
	v_lshlrev_b32_sdwa v80, v234, v70 dst_sel:DWORD dst_unused:UNUSED_PAD src0_sel:DWORD src1_sel:WORD_0
	v_lshlrev_b32_sdwa v81, v234, v70 dst_sel:DWORD dst_unused:UNUSED_PAD src0_sel:DWORD src1_sel:WORD_1
	s_nop 1
	global_load_dwordx2 v[230:231], v80, s[98:99]
	global_load_dwordx2 v[248:249], v81, s[98:99]
	v_lshlrev_b32_sdwa v80, v234, v71 dst_sel:DWORD dst_unused:UNUSED_PAD src0_sel:DWORD src1_sel:WORD_0
	v_lshlrev_b32_sdwa v81, v234, v71 dst_sel:DWORD dst_unused:UNUSED_PAD src0_sel:DWORD src1_sel:WORD_1
	s_nop 1
	global_load_dwordx2 v[232:233], v80, s[98:99]
	global_load_dwordx2 v[250:251], v81, s[98:99]
	global_load_dword v64, v109, s[100:101]
	global_load_dword v72, v108, s[100:101]
	global_load_dword v65, v109, s[100:101] offset:32
	global_load_dword v73, v108, s[100:101] offset:32
	global_load_dword v66, v109, s[100:101] offset:64
	global_load_dword v74, v108, s[100:101] offset:64
	global_load_dword v67, v109, s[100:101] offset:96
	global_load_dword v75, v108, s[100:101] offset:96
	global_load_dword v68, v109, s[100:101] offset:128
	global_load_dword v76, v108, s[100:101] offset:128
	global_load_dword v69, v109, s[100:101] offset:160
	global_load_dword v77, v108, s[100:101] offset:160
	global_load_dword v70, v109, s[100:101] offset:192
	global_load_dword v78, v108, s[100:101] offset:192
	global_load_dword v71, v109, s[100:101] offset:224
	global_load_dword v79, v108, s[100:101] offset:224
	s_waitcnt vmcnt(48)
	v_dot8_i32_i4 v34, v122, v194, 0
	v_dot8_i32_i4 v35, v122, v198, 0
	v_dot8_i32_i4 v34, v123, v195, v34
	v_dot8_i32_i4 v35, v123, v199, v35
	v_dot8_i32_i4 v34, v124, v196, v34
	v_dot8_i32_i4 v35, v124, v200, v35
	v_dot8_i32_i4 v34, v125, v197, v34
	v_dot8_i32_i4 v35, v125, v201, v35
	s_nop 2
	s_nop 0
	v_lshl_add_u32 v18, v34, 4, v35
	s_waitcnt vmcnt(47)
	v_dot8_i32_i4 v36, v126, v194, 0
	v_dot8_i32_i4 v37, v126, v198, 0
	v_dot8_i32_i4 v36, v127, v195, v36
	v_dot8_i32_i4 v37, v127, v199, v37
	v_dot8_i32_i4 v36, v128, v196, v36
	v_dot8_i32_i4 v37, v128, v200, v37
	v_dot8_i32_i4 v36, v129, v197, v36
	v_dot8_i32_i4 v37, v129, v201, v37
	s_nop 2
	s_nop 0
	v_lshl_add_u32 v19, v36, 4, v37
	s_waitcnt vmcnt(46)
	v_dot8_i32_i4 v34, v130, v194, 0
	v_dot8_i32_i4 v35, v130, v198, 0
	v_dot8_i32_i4 v34, v131, v195, v34
	v_dot8_i32_i4 v35, v131, v199, v35
	v_dot8_i32_i4 v34, v132, v196, v34
	v_dot8_i32_i4 v35, v132, v200, v35
	v_dot8_i32_i4 v34, v133, v197, v34
	v_dot8_i32_i4 v35, v133, v201, v35
	s_nop 2
	s_nop 0
	v_lshl_add_u32 v20, v34, 4, v35
	s_waitcnt vmcnt(45)
	v_dot8_i32_i4 v36, v134, v194, 0
	v_dot8_i32_i4 v37, v134, v198, 0
	v_dot8_i32_i4 v36, v135, v195, v36
	v_dot8_i32_i4 v37, v135, v199, v37
	v_dot8_i32_i4 v36, v136, v196, v36
	v_dot8_i32_i4 v37, v136, v200, v37
	v_dot8_i32_i4 v36, v137, v197, v36
	v_dot8_i32_i4 v37, v137, v201, v37
	s_nop 2
	s_nop 0
	v_lshl_add_u32 v21, v36, 4, v37
	s_waitcnt vmcnt(44)
	v_dot8_i32_i4 v34, v138, v194, 0
	v_dot8_i32_i4 v35, v138, v198, 0
	v_dot8_i32_i4 v34, v139, v195, v34
	v_dot8_i32_i4 v35, v139, v199, v35
	v_dot8_i32_i4 v34, v140, v196, v34
	v_dot8_i32_i4 v35, v140, v200, v35
	v_dot8_i32_i4 v34, v141, v197, v34
	v_dot8_i32_i4 v35, v141, v201, v35
	s_nop 2
	s_nop 0
	v_lshl_add_u32 v22, v34, 4, v35
	s_waitcnt vmcnt(43)
	v_dot8_i32_i4 v36, v142, v194, 0
	v_dot8_i32_i4 v37, v142, v198, 0
	v_dot8_i32_i4 v36, v143, v195, v36
	v_dot8_i32_i4 v37, v143, v199, v37
	v_dot8_i32_i4 v36, v144, v196, v36
	v_dot8_i32_i4 v37, v144, v200, v37
	v_dot8_i32_i4 v36, v145, v197, v36
	v_dot8_i32_i4 v37, v145, v201, v37
	s_nop 2
	s_nop 0
	v_lshl_add_u32 v23, v36, 4, v37
	s_waitcnt vmcnt(42)
; #define LAS __attribute__((address_space(3)))
; __device__ __forceinline__ void peer_u_item(int p, int j, const LAS unsigned short* EL  , const unsigned char* __restrict__ XQ, const unsigned char* __restrict__ U8, LAS int* ACC  , int lane, int wave) {
;     ...
;         for (int i = 0; i < 16; ++i) {
;             int sh = __builtin_amdgcn_sdot8((int)uu[i].x, (int)xh.x, 0, false); sh = __builtin_amdgcn_sdot8((int)uu[i].y, (int)xh.y, sh, false);
;             sh = __builtin_amdgcn_sdot8((int)uu[i].z, (int)xh.z, sh, false); sh = __builtin_amdgcn_sdot8((int)uu[i].w, (int)xh.w, sh, false);
;             int sl = __builtin_amdgcn_sdot8((int)uu[i].x, (int)xl.x, 0, false); sl = __builtin_amdgcn_sdot8((int)uu[i].y, (int)xl.y, sl, false);
;             sl = __builtin_amdgcn_sdot8((int)uu[i].z, (int)xl.z, sl, false); sl = __builtin_amdgcn_sdot8((int)uu[i].w, (int)xl.w, sl, false);
;             d[i] = (sh << 4) + sl;
;         }
;         int r0, r1; treduce16i<4, 2, 1>(d, lane, r0, r1);
;         { typedef int i2v __attribute__((ext_vector_type(2))); LAS i2v* ap = (LAS i2v*)(ACC + (it * 8 + wave) * 128 + 2 * lane);
;           i2v a2; if (p == 0) { a2.x = r0; a2.y = r1; } else { a2 = *ap; a2.x += r0; a2.y += r1; } *ap = a2; }
	v_dot8_i32_i4 v34, v146, v194, 0
	v_dot8_i32_i4 v35, v146, v198, 0
	v_dot8_i32_i4 v34, v147, v195, v34
	v_dot8_i32_i4 v35, v147, v199, v35
	v_dot8_i32_i4 v34, v148, v196, v34
	v_dot8_i32_i4 v35, v148, v200, v35
	v_dot8_i32_i4 v34, v149, v197, v34
	v_dot8_i32_i4 v35, v149, v201, v35
	s_nop 2
	s_nop 0
	v_lshl_add_u32 v24, v34, 4, v35
	s_waitcnt vmcnt(41)
	v_dot8_i32_i4 v36, v150, v194, 0
	v_dot8_i32_i4 v37, v150, v198, 0
	v_dot8_i32_i4 v36, v151, v195, v36
	v_dot8_i32_i4 v37, v151, v199, v37
	v_dot8_i32_i4 v36, v152, v196, v36
	v_dot8_i32_i4 v37, v152, v200, v37
	v_dot8_i32_i4 v36, v153, v197, v36
	v_dot8_i32_i4 v37, v153, v201, v37
	s_nop 2
	s_nop 0
	v_lshl_add_u32 v25, v36, 4, v37
	s_waitcnt vmcnt(40)
	v_dot8_i32_i4 v34, v154, v194, 0
	v_dot8_i32_i4 v35, v154, v198, 0
	v_dot8_i32_i4 v34, v155, v195, v34
	v_dot8_i32_i4 v35, v155, v199, v35
	v_dot8_i32_i4 v34, v156, v196, v34
	v_dot8_i32_i4 v35, v156, v200, v35
	v_dot8_i32_i4 v34, v157, v197, v34
	v_dot8_i32_i4 v35, v157, v201, v35
	s_nop 2
	s_nop 0
	v_lshl_add_u32 v26, v34, 4, v35
	s_waitcnt vmcnt(39)
	v_dot8_i32_i4 v36, v158, v194, 0
	v_dot8_i32_i4 v37, v158, v198, 0
	v_dot8_i32_i4 v36, v159, v195, v36
	v_dot8_i32_i4 v37, v159, v199, v37
	v_dot8_i32_i4 v36, v160, v196, v36
	v_dot8_i32_i4 v37, v160, v200, v37
	v_dot8_i32_i4 v36, v161, v197, v36
	v_dot8_i32_i4 v37, v161, v201, v37
	s_nop 2
	s_nop 0
	v_lshl_add_u32 v27, v36, 4, v37
	s_waitcnt vmcnt(38)
	v_dot8_i32_i4 v34, v162, v194, 0
	v_dot8_i32_i4 v35, v162, v198, 0
	v_dot8_i32_i4 v34, v163, v195, v34
	v_dot8_i32_i4 v35, v163, v199, v35
	v_dot8_i32_i4 v34, v164, v196, v34
	v_dot8_i32_i4 v35, v164, v200, v35
	v_dot8_i32_i4 v34, v165, v197, v34
	v_dot8_i32_i4 v35, v165, v201, v35
	s_nop 2
	s_nop 0
	v_lshl_add_u32 v28, v34, 4, v35
	s_waitcnt vmcnt(37)
	v_dot8_i32_i4 v36, v166, v194, 0
	v_dot8_i32_i4 v37, v166, v198, 0
	v_dot8_i32_i4 v36, v167, v195, v36
	v_dot8_i32_i4 v37, v167, v199, v37
	v_dot8_i32_i4 v36, v168, v196, v36
	v_dot8_i32_i4 v37, v168, v200, v37
	v_dot8_i32_i4 v36, v169, v197, v36
	v_dot8_i32_i4 v37, v169, v201, v37
	s_nop 2
	s_nop 0
	v_lshl_add_u32 v29, v36, 4, v37
	s_waitcnt vmcnt(36)
	v_dot8_i32_i4 v34, v170, v194, 0
	v_dot8_i32_i4 v35, v170, v198, 0
	v_dot8_i32_i4 v34, v171, v195, v34
	v_dot8_i32_i4 v35, v171, v199, v35
	v_dot8_i32_i4 v34, v172, v196, v34
	v_dot8_i32_i4 v35, v172, v200, v35
	v_dot8_i32_i4 v34, v173, v197, v34
	v_dot8_i32_i4 v35, v173, v201, v35
	s_nop 2
	s_nop 0
	v_lshl_add_u32 v30, v34, 4, v35
	s_waitcnt vmcnt(35)
	v_dot8_i32_i4 v36, v174, v194, 0
	v_dot8_i32_i4 v37, v174, v198, 0
	v_dot8_i32_i4 v36, v175, v195, v36
	v_dot8_i32_i4 v37, v175, v199, v37
	v_dot8_i32_i4 v36, v176, v196, v36
	v_dot8_i32_i4 v37, v176, v200, v37
	v_dot8_i32_i4 v36, v177, v197, v36
	v_dot8_i32_i4 v37, v177, v201, v37
	s_nop 2
	s_nop 0
	v_lshl_add_u32 v31, v36, 4, v37
	s_waitcnt vmcnt(34)
	v_dot8_i32_i4 v34, v178, v194, 0
	v_dot8_i32_i4 v35, v178, v198, 0
	v_dot8_i32_i4 v34, v179, v195, v34
	v_dot8_i32_i4 v35, v179, v199, v35
	v_dot8_i32_i4 v34, v180, v196, v34
	v_dot8_i32_i4 v35, v180, v200, v35
	v_dot8_i32_i4 v34, v181, v197, v34
	v_dot8_i32_i4 v35, v181, v201, v35
	s_nop 2
	s_nop 0
	v_lshl_add_u32 v32, v34, 4, v35
	s_waitcnt vmcnt(33)
	v_dot8_i32_i4 v36, v182, v194, 0
	v_dot8_i32_i4 v37, v182, v198, 0
	v_dot8_i32_i4 v36, v183, v195, v36
	v_dot8_i32_i4 v37, v183, v199, v37
	v_dot8_i32_i4 v36, v184, v196, v36
	v_dot8_i32_i4 v37, v184, v200, v37
	v_dot8_i32_i4 v36, v185, v197, v36
	v_dot8_i32_i4 v37, v185, v201, v37
	s_nop 2
	s_nop 0
	v_lshl_add_u32 v33, v36, 4, v37
	v_cndmask_b32_e64 v40, v26, v18, s[10:11]
	v_cndmask_b32_e64 v48, v18, v26, s[10:11]
	v_cndmask_b32_e64 v41, v27, v19, s[10:11]
	v_cndmask_b32_e64 v49, v19, v27, s[10:11]
	v_cndmask_b32_e64 v42, v28, v20, s[10:11]
	v_cndmask_b32_e64 v50, v20, v28, s[10:11]
	v_cndmask_b32_e64 v43, v29, v21, s[10:11]
	v_cndmask_b32_e64 v51, v21, v29, s[10:11]
	v_cndmask_b32_e64 v44, v30, v22, s[10:11]
	v_cndmask_b32_e64 v52, v22, v30, s[10:11]
	v_cndmask_b32_e64 v45, v31, v23, s[10:11]
	v_cndmask_b32_e64 v53, v23, v31, s[10:11]
	v_cndmask_b32_e64 v46, v32, v24, s[10:11]
	v_cndmask_b32_e64 v54, v24, v32, s[10:11]
	v_cndmask_b32_e64 v47, v33, v25, s[10:11]
	v_cndmask_b32_e64 v55, v25, v33, s[10:11]
	v_add_u32_dpp v18, v40, v48 row_shr:4 row_mask:0xf bank_mask:0xa
	v_add_u32_dpp v18, v40, v48 row_shl:4 row_mask:0xf bank_mask:0x5
	v_add_u32_dpp v19, v41, v49 row_shr:4 row_mask:0xf bank_mask:0xa
	v_add_u32_dpp v19, v41, v49 row_shl:4 row_mask:0xf bank_mask:0x5
	v_add_u32_dpp v20, v42, v50 row_shr:4 row_mask:0xf bank_mask:0xa
	v_add_u32_dpp v20, v42, v50 row_shl:4 row_mask:0xf bank_mask:0x5
	v_add_u32_dpp v21, v43, v51 row_shr:4 row_mask:0xf bank_mask:0xa
	v_add_u32_dpp v21, v43, v51 row_shl:4 row_mask:0xf bank_mask:0x5
	v_add_u32_dpp v22, v44, v52 row_shr:4 row_mask:0xf bank_mask:0xa
	v_add_u32_dpp v22, v44, v52 row_shl:4 row_mask:0xf bank_mask:0x5
	v_add_u32_dpp v23, v45, v53 row_shr:4 row_mask:0xf bank_mask:0xa
	v_add_u32_dpp v23, v45, v53 row_shl:4 row_mask:0xf bank_mask:0x5
	v_add_u32_dpp v24, v46, v54 row_shr:4 row_mask:0xf bank_mask:0xa
	v_add_u32_dpp v24, v46, v54 row_shl:4 row_mask:0xf bank_mask:0x5
	v_add_u32_dpp v25, v47, v55 row_shr:4 row_mask:0xf bank_mask:0xa
	v_add_u32_dpp v25, v47, v55 row_shl:4 row_mask:0xf bank_mask:0x5
	v_cndmask_b32_e64 v40, v22, v18, s[12:13]
	v_cndmask_b32_e64 v48, v18, v22, s[12:13]
	v_cndmask_b32_e64 v41, v23, v19, s[12:13]
	v_cndmask_b32_e64 v49, v19, v23, s[12:13]
	v_cndmask_b32_e64 v42, v24, v20, s[12:13]
	v_cndmask_b32_e64 v50, v20, v24, s[12:13]
	v_cndmask_b32_e64 v43, v25, v21, s[12:13]
	v_cndmask_b32_e64 v51, v21, v25, s[12:13]
	s_nop 0
	v_add_u32_dpp v26, v40, v48 quad_perm:[2,3,0,1] row_mask:0xf bank_mask:0xf
	v_add_u32_dpp v27, v41, v49 quad_perm:[2,3,0,1] row_mask:0xf bank_mask:0xf
	v_add_u32_dpp v28, v42, v50 quad_perm:[2,3,0,1] row_mask:0xf bank_mask:0xf
	v_add_u32_dpp v29, v43, v51 quad_perm:[2,3,0,1] row_mask:0xf bank_mask:0xf
	v_cndmask_b32_e64 v40, v28, v26, s[14:15]
	v_cndmask_b32_e64 v48, v26, v28, s[14:15]
	v_cndmask_b32_e64 v41, v29, v27, s[14:15]
	v_cndmask_b32_e64 v49, v27, v29, s[14:15]
	s_nop 1
	v_add_u32_dpp v44, v40, v48 quad_perm:[1,0,3,2] row_mask:0xf bank_mask:0xf
	v_add_u32_dpp v45, v41, v49 quad_perm:[1,0,3,2] row_mask:0xf bank_mask:0xf
	s_cmp_eq_u32 s43, 0
	s_cselect_b32 s32, 0, -1
	v_and_b32_e32 v62, s32, v62
	v_and_b32_e32 v63, s32, v63
	v_add_u32_e32 v44, v44, v62
	v_add_u32_e32 v45, v45, v63
	ds_write_b64 v61, v[44:45]
	s_mov_b32 s42, s44
	s_mov_b32 s43, s45
	s_add_i32 s44, s44, 1
	s_and_b32 s44, s44, 7
	s_cmp_eq_u32 s44, 0
	s_cselect_b32 s32, 1, 0
	s_add_i32 s45, s45, s32
	s_and_b32 s45, s45, 3
	s_waitcnt lgkmcnt(0)
; #define LAS __attribute__((address_space(3)))
; __device__ __forceinline__ float gelu_as(float z) {
;     const float ax = fabsf(z) * 0.70710678118654752f, t = __builtin_amdgcn_rcpf(1.f + 0.3275911f * ax);
;     const float poly = t * (0.254829592f + t * (-0.284496736f + t * (1.421413741f + t * (-1.453152027f + t * 1.061405429f))));
;     const float er = 1.f - poly * __expf(-ax * ax);
;     return 0.5f * z * (1.f + copysignf(er, z));
; __global__ void __launch_bounds__(NTHR, 2) k_main(Args a) {
;     ...
;                 const int tl = it * 8 + wave, t = j * 64 + tl;
;                 const unsigned ew = *(const LAS unsigned*)(EL + tl * 128 + 2 * lane); const int e0 = (int)(ew & 0xffffu), e1 = (int)(ew >> 16);
;                 typedef int i2v __attribute__((ext_vector_type(2))); const i2v si = *(const LAS i2v*)(ACC + tl * 128 + 2 * lane);
;                 typedef float f2v __attribute__((ext_vector_type(2))); const f2v gt = *(const LAS f2v*)(GL + tl * 128 + 2 * lane); const float xs = XS[t];
;                 const int sx = ((const int*)(XS + T))[t];
;                 const float z0 = (float)(2 * si.x + sx) * SU[e0] * xs, z1 = (float)(2 * si.y + sx) * SU[e1] * xs;
;                 const float a0 = gt.x * gelu_as(z0) * SV[e0], a1 = gt.y * gelu_as(z1) * SV[e1];
;                 const float mx = wave_max_dpp(fmaxf(fabsf(a0), fabsf(a1)));
;                 const float sc = mx > 0.f ? mx * (1.f / 119.f) : 1.f, inv = 1.f / sc;
;                 const int q0 = (int)rintf(a0 * inv), q1 = (int)rintf(a1 * inv);
;                 *(LAS unsigned short*)(AL + tl * 128 + 2 * lane) = (unsigned short)((q0 & 255) | ((q1 & 255) << 8));
;                 const int qs = wave_sum_dpp_i(q0 + q1);
;                 if (lane == 0) { ASC[tl] = sc; SAL[tl] = qs; }
.LBB0_674:
	s_nop 0
	s_nop 0
	s_nop 0
	s_nop 0
	s_nop 0
	s_nop 0
	s_nop 0
	s_nop 0
	s_nop 0
	s_nop 0
	s_nop 0
	s_nop 0
	s_nop 0
	s_nop 0
	s_ashr_i32 s41, s40, 31
	s_lshl_b64 s[10:11], s[40:41], 2
	s_add_u32 s14, s90, s10
	s_addc_u32 s15, s91, s11
	v_add_u32_e32 v58, 0x16000, v91
	ds_read_b64 v[26:27], v91
	ds_read_b64 v[42:43], v58
	ds_read_b64 v[28:29], v91 offset:4096
	ds_read_b64 v[44:45], v58 offset:4096
	ds_read_b64 v[30:31], v91 offset:8192
	ds_read_b64 v[46:47], v58 offset:8192
	ds_read_b64 v[32:33], v91 offset:12288
	ds_read_b64 v[48:49], v58 offset:12288
	ds_read_b64 v[34:35], v91 offset:16384
	ds_read_b64 v[50:51], v58 offset:16384
	ds_read_b64 v[36:37], v91 offset:20480
	ds_read_b64 v[52:53], v58 offset:20480
	ds_read_b64 v[38:39], v91 offset:24576
	ds_read_b64 v[54:55], v58 offset:24576
	ds_read_b64 v[40:41], v91 offset:28672
	ds_read_b64 v[56:57], v58 offset:28672
	s_waitcnt lgkmcnt(0)
	s_waitcnt vmcnt(0)
	v_lshl_add_u32 v154, v26, 1, v64
	v_lshl_add_u32 v155, v27, 1, v64
	v_cvt_f32_i32_e32 v154, v154
	v_cvt_f32_i32_e32 v155, v155
	v_mul_f32_e32 v154, v218, v154
	v_mul_f32_e32 v155, v236, v155
	v_mul_f32_e32 v154, v72, v154
	v_mul_f32_e32 v155, v72, v155
	v_mul_f32_e64 v156, |v154|, s82
	v_mul_f32_e64 v157, |v155|, s82
	v_fma_f32 v158, v156, s83, 1.0
	v_fma_f32 v159, v157, s83, 1.0
	v_rcp_f32_e32 v158, v158
	v_rcp_f32_e32 v159, v159
	v_mul_f32_e64 v156, v156, -v156
	v_mul_f32_e64 v157, v157, -v157
	v_mul_f32_e32 v156, 0x3fb8aa3b, v156
	v_mul_f32_e32 v157, 0x3fb8aa3b, v157
	v_fmamk_f32 v160, v158, 0x3f87dc22, v110
	v_fmamk_f32 v161, v159, 0x3f87dc22, v110
	v_exp_f32_e32 v156, v156
	v_exp_f32_e32 v157, v157
	v_fmaak_f32 v160, v158, v160, 0x3fb5f0e3
	v_fmaak_f32 v161, v159, v161, 0x3fb5f0e3
	v_fmaak_f32 v160, v158, v160, 0xbe91a98e
	v_fmaak_f32 v161, v159, v161, 0xbe91a98e
	v_fmaak_f32 v160, v158, v160, 0x3e827906
	v_fmaak_f32 v161, v159, v161, 0x3e827906
	v_mul_f32_e32 v158, v158, v160
	v_mul_f32_e32 v159, v159, v161
	v_fma_f32 v156, -v156, v158, 1.0
	v_fma_f32 v157, -v157, v159, 1.0
	v_mul_f32_e32 v162, 0.5, v154
	v_mul_f32_e32 v163, 0.5, v155
	v_bfi_b32 v154, s84, v156, v154
	v_bfi_b32 v155, s84, v157, v155
	v_add_f32_e32 v154, 1.0, v154
	v_add_f32_e32 v155, 1.0, v155
	v_mul_f32_e32 v154, v162, v154
	v_mul_f32_e32 v155, v163, v155
	v_mul_f32_e32 v154, v42, v154
	v_mul_f32_e32 v155, v43, v155
	v_mul_f32_e32 v154, v219, v154
	v_mul_f32_e32 v155, v237, v155
	v_max_f32_e64 v164, |v154|, |v155|
	s_nop 1
	v_max_f32_dpp v164, v164, v164 quad_perm:[1,0,3,2] row_mask:0xf bank_mask:0xf
	s_nop 1
	v_max_f32_dpp v164, v164, v164 quad_perm:[2,3,0,1] row_mask:0xf bank_mask:0xf
	s_nop 1
	v_max_f32_dpp v164, v164, v164 row_half_mirror row_mask:0xf bank_mask:0xf
	s_nop 1
	v_max_f32_dpp v164, v164, v164 row_mirror row_mask:0xf bank_mask:0xf
	s_nop 1
	v_readlane_b32 s46, v164, 32
	v_readlane_b32 s47, v164, 48
	v_readlane_b32 s12, v164, 0
	v_readlane_b32 s13, v164, 16
	s_nop 1
	v_mov_b32_e32 v164, s47
	v_max_f32_e32 v164, s46, v164
	v_mov_b32_e32 v165, s13
	v_max3_f32 v164, s12, v165, v164
	v_mul_f32_e32 v165, 0x3c09ae41, v164
	v_cmp_lt_f32_e32 vcc, 0, v164
	s_nop 1
	v_cndmask_b32_e32 v164, 1.0, v165, vcc
	v_div_scale_f32 v166, s[12:13], v164, v164, 1.0
	v_rcp_f32_e32 v167, v166
	v_div_scale_f32 v168, vcc, 1.0, v164, 1.0
	v_fma_f32 v169, -v166, v167, 1.0
	v_fmac_f32_e32 v167, v169, v167
	v_mul_f32_e32 v169, v168, v167
	v_fma_f32 v170, -v166, v169, v168
	v_fmac_f32_e32 v169, v170, v167
	v_fma_f32 v166, -v166, v169, v168
	v_div_fmas_f32 v166, v166, v167, v169
	v_div_fixup_f32 v166, v166, v164, 1.0
	v_mul_f32_e32 v154, v166, v154
	v_mul_f32_e32 v155, v166, v155
	v_rndne_f32_e32 v154, v154
	v_rndne_f32_e32 v155, v155
	v_cvt_i32_f32_e32 v154, v154
	v_cvt_i32_f32_e32 v155, v155
	v_perm_b32 v167, v155, v154, s85
	v_add_u32_e32 v154, v154, v155
	ds_write_b16 v90, v167
	s_nop 1
	v_add_u32_dpp v154, v154, v154 quad_perm:[1,0,3,2] row_mask:0xf bank_mask:0xf bound_ctrl:1
	s_nop 1
	v_add_u32_dpp v154, v154, v154 quad_perm:[2,3,0,1] row_mask:0xf bank_mask:0xf bound_ctrl:1
	s_nop 1
	v_add_u32_dpp v154, v154, v154 row_half_mirror row_mask:0xf bank_mask:0xf bound_ctrl:1
	s_nop 1
	v_add_u32_dpp v154, v154, v154 row_mirror row_mask:0xf bank_mask:0xf bound_ctrl:1
	s_nop 1
	v_readlane_b32 s46, v154, 0
	v_readlane_b32 s47, v154, 16
	v_readlane_b32 s12, v154, 32
	v_readlane_b32 s13, v154, 48
	s_nop 1
	s_add_i32 s46, s47, s46
	s_add_i32 s46, s46, s12
	s_add_i32 s46, s46, s13
	s_mov_b32 s47, s67
	s_and_saveexec_b64 s[12:13], s[8:9]
	v_mov_b32_e32 v154, s47
	v_mov_b32_e32 v155, s46
	ds_write2st64_b32 v154, v164, v155 offset1:1
	s_or_b64 exec, exec, s[12:13]
	v_lshl_add_u32 v154, v28, 1, v65
	v_lshl_add_u32 v155, v29, 1, v65
	v_cvt_f32_i32_e32 v154, v154
	v_cvt_f32_i32_e32 v155, v155
	v_mul_f32_e32 v154, v220, v154
	v_mul_f32_e32 v155, v238, v155
	v_mul_f32_e32 v154, v73, v154
	v_mul_f32_e32 v155, v73, v155
	v_mul_f32_e64 v156, |v154|, s82
	v_mul_f32_e64 v157, |v155|, s82
	v_fma_f32 v158, v156, s83, 1.0
	v_fma_f32 v159, v157, s83, 1.0
	v_rcp_f32_e32 v158, v158
	v_rcp_f32_e32 v159, v159
	v_mul_f32_e64 v156, v156, -v156
	v_mul_f32_e64 v157, v157, -v157
	v_mul_f32_e32 v156, 0x3fb8aa3b, v156
	v_mul_f32_e32 v157, 0x3fb8aa3b, v157
	v_fmamk_f32 v160, v158, 0x3f87dc22, v110
	v_fmamk_f32 v161, v159, 0x3f87dc22, v110
	v_exp_f32_e32 v156, v156
	v_exp_f32_e32 v157, v157
	v_fmaak_f32 v160, v158, v160, 0x3fb5f0e3
	v_fmaak_f32 v161, v159, v161, 0x3fb5f0e3
	v_fmaak_f32 v160, v158, v160, 0xbe91a98e
	v_fmaak_f32 v161, v159, v161, 0xbe91a98e
	v_fmaak_f32 v160, v158, v160, 0x3e827906
	v_fmaak_f32 v161, v159, v161, 0x3e827906
	v_mul_f32_e32 v158, v158, v160
	v_mul_f32_e32 v159, v159, v161
; #define LAS __attribute__((address_space(3)))
; __device__ __forceinline__ float gelu_as(float z) {
;     const float ax = fabsf(z) * 0.70710678118654752f, t = __builtin_amdgcn_rcpf(1.f + 0.3275911f * ax);
;     const float poly = t * (0.254829592f + t * (-0.284496736f + t * (1.421413741f + t * (-1.453152027f + t * 1.061405429f))));
;     const float er = 1.f - poly * __expf(-ax * ax);
;     return 0.5f * z * (1.f + copysignf(er, z));
; __global__ void __launch_bounds__(NTHR, 2) k_main(Args a) {
;     ...
;                 const int tl = it * 8 + wave, t = j * 64 + tl;
;                 const unsigned ew = *(const LAS unsigned*)(EL + tl * 128 + 2 * lane); const int e0 = (int)(ew & 0xffffu), e1 = (int)(ew >> 16);
;                 typedef int i2v __attribute__((ext_vector_type(2))); const i2v si = *(const LAS i2v*)(ACC + tl * 128 + 2 * lane);
;                 typedef float f2v __attribute__((ext_vector_type(2))); const f2v gt = *(const LAS f2v*)(GL + tl * 128 + 2 * lane); const float xs = XS[t];
;                 const int sx = ((const int*)(XS + T))[t];
;                 const float z0 = (float)(2 * si.x + sx) * SU[e0] * xs, z1 = (float)(2 * si.y + sx) * SU[e1] * xs;
;                 const float a0 = gt.x * gelu_as(z0) * SV[e0], a1 = gt.y * gelu_as(z1) * SV[e1];
;                 const float mx = wave_max_dpp(fmaxf(fabsf(a0), fabsf(a1)));
;                 const float sc = mx > 0.f ? mx * (1.f / 119.f) : 1.f, inv = 1.f / sc;
;                 const int q0 = (int)rintf(a0 * inv), q1 = (int)rintf(a1 * inv);
;                 *(LAS unsigned short*)(AL + tl * 128 + 2 * lane) = (unsigned short)((q0 & 255) | ((q1 & 255) << 8));
;                 const int qs = wave_sum_dpp_i(q0 + q1);
;                 if (lane == 0) { ASC[tl] = sc; SAL[tl] = qs; }
	v_fma_f32 v156, -v156, v158, 1.0
	v_fma_f32 v157, -v157, v159, 1.0
	v_mul_f32_e32 v162, 0.5, v154
	v_mul_f32_e32 v163, 0.5, v155
	v_bfi_b32 v154, s84, v156, v154
	v_bfi_b32 v155, s84, v157, v155
	v_add_f32_e32 v154, 1.0, v154
	v_add_f32_e32 v155, 1.0, v155
	v_mul_f32_e32 v154, v162, v154
	v_mul_f32_e32 v155, v163, v155
	v_mul_f32_e32 v154, v44, v154
	v_mul_f32_e32 v155, v45, v155
	v_mul_f32_e32 v154, v221, v154
	v_mul_f32_e32 v155, v239, v155
	v_max_f32_e64 v164, |v154|, |v155|
	s_nop 1
	v_max_f32_dpp v164, v164, v164 quad_perm:[1,0,3,2] row_mask:0xf bank_mask:0xf
	s_nop 1
	v_max_f32_dpp v164, v164, v164 quad_perm:[2,3,0,1] row_mask:0xf bank_mask:0xf
	s_nop 1
	v_max_f32_dpp v164, v164, v164 row_half_mirror row_mask:0xf bank_mask:0xf
	s_nop 1
	v_max_f32_dpp v164, v164, v164 row_mirror row_mask:0xf bank_mask:0xf
	s_nop 1
	v_readlane_b32 s46, v164, 32
	v_readlane_b32 s47, v164, 48
	v_readlane_b32 s12, v164, 0
	v_readlane_b32 s13, v164, 16
	s_nop 1
	v_mov_b32_e32 v164, s47
	v_max_f32_e32 v164, s46, v164
	v_mov_b32_e32 v165, s13
	v_max3_f32 v164, s12, v165, v164
	v_mul_f32_e32 v165, 0x3c09ae41, v164
	v_cmp_lt_f32_e32 vcc, 0, v164
	s_nop 1
	v_cndmask_b32_e32 v164, 1.0, v165, vcc
	v_div_scale_f32 v166, s[12:13], v164, v164, 1.0
	v_rcp_f32_e32 v167, v166
	v_div_scale_f32 v168, vcc, 1.0, v164, 1.0
	v_fma_f32 v169, -v166, v167, 1.0
	v_fmac_f32_e32 v167, v169, v167
	v_mul_f32_e32 v169, v168, v167
	v_fma_f32 v170, -v166, v169, v168
	v_fmac_f32_e32 v169, v170, v167
	v_fma_f32 v166, -v166, v169, v168
	v_div_fmas_f32 v166, v166, v167, v169
	v_div_fixup_f32 v166, v166, v164, 1.0
	v_mul_f32_e32 v154, v166, v154
	v_mul_f32_e32 v155, v166, v155
	v_rndne_f32_e32 v154, v154
	v_rndne_f32_e32 v155, v155
	v_cvt_i32_f32_e32 v154, v154
	v_cvt_i32_f32_e32 v155, v155
	v_perm_b32 v167, v155, v154, s85
	v_add_u32_e32 v154, v154, v155
	ds_write_b16 v90, v167 offset:1024
	s_nop 1
	v_add_u32_dpp v154, v154, v154 quad_perm:[1,0,3,2] row_mask:0xf bank_mask:0xf bound_ctrl:1
	s_nop 1
	v_add_u32_dpp v154, v154, v154 quad_perm:[2,3,0,1] row_mask:0xf bank_mask:0xf bound_ctrl:1
	s_nop 1
	v_add_u32_dpp v154, v154, v154 row_half_mirror row_mask:0xf bank_mask:0xf bound_ctrl:1
	s_nop 1
	v_add_u32_dpp v154, v154, v154 row_mirror row_mask:0xf bank_mask:0xf bound_ctrl:1
	s_nop 1
	v_readlane_b32 s46, v154, 0
	v_readlane_b32 s47, v154, 16
	v_readlane_b32 s12, v154, 32
	v_readlane_b32 s13, v154, 48
	s_nop 1
	s_add_i32 s46, s47, s46
	s_add_i32 s46, s46, s12
	s_add_i32 s46, s46, s13
	s_add_i32 s47, s67, 32
	s_and_saveexec_b64 s[12:13], s[8:9]
	v_mov_b32_e32 v154, s47
	v_mov_b32_e32 v155, s46
	ds_write2st64_b32 v154, v164, v155 offset1:1
	s_or_b64 exec, exec, s[12:13]
	v_lshl_add_u32 v154, v30, 1, v66
	v_lshl_add_u32 v155, v31, 1, v66
	v_cvt_f32_i32_e32 v154, v154
	v_cvt_f32_i32_e32 v155, v155
	v_mul_f32_e32 v154, v222, v154
	v_mul_f32_e32 v155, v240, v155
	v_mul_f32_e32 v154, v74, v154
	v_mul_f32_e32 v155, v74, v155
	v_mul_f32_e64 v156, |v154|, s82
	v_mul_f32_e64 v157, |v155|, s82
	v_fma_f32 v158, v156, s83, 1.0
	v_fma_f32 v159, v157, s83, 1.0
	v_rcp_f32_e32 v158, v158
	v_rcp_f32_e32 v159, v159
	v_mul_f32_e64 v156, v156, -v156
	v_mul_f32_e64 v157, v157, -v157
	v_mul_f32_e32 v156, 0x3fb8aa3b, v156
	v_mul_f32_e32 v157, 0x3fb8aa3b, v157
	v_fmamk_f32 v160, v158, 0x3f87dc22, v110
	v_fmamk_f32 v161, v159, 0x3f87dc22, v110
	v_exp_f32_e32 v156, v156
	v_exp_f32_e32 v157, v157
	v_fmaak_f32 v160, v158, v160, 0x3fb5f0e3
	v_fmaak_f32 v161, v159, v161, 0x3fb5f0e3
	v_fmaak_f32 v160, v158, v160, 0xbe91a98e
	v_fmaak_f32 v161, v159, v161, 0xbe91a98e
	v_fmaak_f32 v160, v158, v160, 0x3e827906
	v_fmaak_f32 v161, v159, v161, 0x3e827906
	v_mul_f32_e32 v158, v158, v160
	v_mul_f32_e32 v159, v159, v161
	v_fma_f32 v156, -v156, v158, 1.0
	v_fma_f32 v157, -v157, v159, 1.0
	v_mul_f32_e32 v162, 0.5, v154
	v_mul_f32_e32 v163, 0.5, v155
	v_bfi_b32 v154, s84, v156, v154
	v_bfi_b32 v155, s84, v157, v155
	v_add_f32_e32 v154, 1.0, v154
	v_add_f32_e32 v155, 1.0, v155
	v_mul_f32_e32 v154, v162, v154
	v_mul_f32_e32 v155, v163, v155
	v_mul_f32_e32 v154, v46, v154
	v_mul_f32_e32 v155, v47, v155
	v_mul_f32_e32 v154, v223, v154
	v_mul_f32_e32 v155, v241, v155
	v_max_f32_e64 v164, |v154|, |v155|
	s_nop 1
	v_max_f32_dpp v164, v164, v164 quad_perm:[1,0,3,2] row_mask:0xf bank_mask:0xf
	s_nop 1
	v_max_f32_dpp v164, v164, v164 quad_perm:[2,3,0,1] row_mask:0xf bank_mask:0xf
	s_nop 1
	v_max_f32_dpp v164, v164, v164 row_half_mirror row_mask:0xf bank_mask:0xf
	s_nop 1
	v_max_f32_dpp v164, v164, v164 row_mirror row_mask:0xf bank_mask:0xf
	s_nop 1
	v_readlane_b32 s46, v164, 32
	v_readlane_b32 s47, v164, 48
	v_readlane_b32 s12, v164, 0
	v_readlane_b32 s13, v164, 16
	s_nop 1
	v_mov_b32_e32 v164, s47
	v_max_f32_e32 v164, s46, v164
	v_mov_b32_e32 v165, s13
	v_max3_f32 v164, s12, v165, v164
	v_mul_f32_e32 v165, 0x3c09ae41, v164
	v_cmp_lt_f32_e32 vcc, 0, v164
	s_nop 1
	v_cndmask_b32_e32 v164, 1.0, v165, vcc
	v_div_scale_f32 v166, s[12:13], v164, v164, 1.0
	v_rcp_f32_e32 v167, v166
	v_div_scale_f32 v168, vcc, 1.0, v164, 1.0
	v_fma_f32 v169, -v166, v167, 1.0
	v_fmac_f32_e32 v167, v169, v167
	v_mul_f32_e32 v169, v168, v167
	v_fma_f32 v170, -v166, v169, v168
	v_fmac_f32_e32 v169, v170, v167
	v_fma_f32 v166, -v166, v169, v168
	v_div_fmas_f32 v166, v166, v167, v169
	v_div_fixup_f32 v166, v166, v164, 1.0
	v_mul_f32_e32 v154, v166, v154
	v_mul_f32_e32 v155, v166, v155
	v_rndne_f32_e32 v154, v154
	v_rndne_f32_e32 v155, v155
	v_cvt_i32_f32_e32 v154, v154
	v_cvt_i32_f32_e32 v155, v155
	v_perm_b32 v167, v155, v154, s85
	v_add_u32_e32 v154, v154, v155
	ds_write_b16 v90, v167 offset:2048
	s_nop 1
	v_add_u32_dpp v154, v154, v154 quad_perm:[1,0,3,2] row_mask:0xf bank_mask:0xf bound_ctrl:1
; #define LAS __attribute__((address_space(3)))
; __device__ __forceinline__ float gelu_as(float z) {
;     const float ax = fabsf(z) * 0.70710678118654752f, t = __builtin_amdgcn_rcpf(1.f + 0.3275911f * ax);
;     const float poly = t * (0.254829592f + t * (-0.284496736f + t * (1.421413741f + t * (-1.453152027f + t * 1.061405429f))));
;     const float er = 1.f - poly * __expf(-ax * ax);
;     return 0.5f * z * (1.f + copysignf(er, z));
; __global__ void __launch_bounds__(NTHR, 2) k_main(Args a) {
;     ...
;                 const int tl = it * 8 + wave, t = j * 64 + tl;
;                 const unsigned ew = *(const LAS unsigned*)(EL + tl * 128 + 2 * lane); const int e0 = (int)(ew & 0xffffu), e1 = (int)(ew >> 16);
;                 typedef int i2v __attribute__((ext_vector_type(2))); const i2v si = *(const LAS i2v*)(ACC + tl * 128 + 2 * lane);
;                 typedef float f2v __attribute__((ext_vector_type(2))); const f2v gt = *(const LAS f2v*)(GL + tl * 128 + 2 * lane); const float xs = XS[t];
;                 const int sx = ((const int*)(XS + T))[t];
;                 const float z0 = (float)(2 * si.x + sx) * SU[e0] * xs, z1 = (float)(2 * si.y + sx) * SU[e1] * xs;
;                 const float a0 = gt.x * gelu_as(z0) * SV[e0], a1 = gt.y * gelu_as(z1) * SV[e1];
;                 const float mx = wave_max_dpp(fmaxf(fabsf(a0), fabsf(a1)));
;                 const float sc = mx > 0.f ? mx * (1.f / 119.f) : 1.f, inv = 1.f / sc;
;                 const int q0 = (int)rintf(a0 * inv), q1 = (int)rintf(a1 * inv);
;                 *(LAS unsigned short*)(AL + tl * 128 + 2 * lane) = (unsigned short)((q0 & 255) | ((q1 & 255) << 8));
;                 const int qs = wave_sum_dpp_i(q0 + q1);
;                 if (lane == 0) { ASC[tl] = sc; SAL[tl] = qs; }
	s_nop 1
	v_add_u32_dpp v154, v154, v154 quad_perm:[2,3,0,1] row_mask:0xf bank_mask:0xf bound_ctrl:1
	s_nop 1
	v_add_u32_dpp v154, v154, v154 row_half_mirror row_mask:0xf bank_mask:0xf bound_ctrl:1
	s_nop 1
	v_add_u32_dpp v154, v154, v154 row_mirror row_mask:0xf bank_mask:0xf bound_ctrl:1
	s_nop 1
	v_readlane_b32 s46, v154, 0
	v_readlane_b32 s47, v154, 16
	v_readlane_b32 s12, v154, 32
	v_readlane_b32 s13, v154, 48
	s_nop 1
	s_add_i32 s46, s47, s46
	s_add_i32 s46, s46, s12
	s_add_i32 s46, s46, s13
	s_add_i32 s47, s67, 64
	s_and_saveexec_b64 s[12:13], s[8:9]
	v_mov_b32_e32 v154, s47
	v_mov_b32_e32 v155, s46
	ds_write2st64_b32 v154, v164, v155 offset1:1
	s_or_b64 exec, exec, s[12:13]
	v_lshl_add_u32 v154, v32, 1, v67
	v_lshl_add_u32 v155, v33, 1, v67
	v_cvt_f32_i32_e32 v154, v154
	v_cvt_f32_i32_e32 v155, v155
	v_mul_f32_e32 v154, v224, v154
	v_mul_f32_e32 v155, v242, v155
	v_mul_f32_e32 v154, v75, v154
	v_mul_f32_e32 v155, v75, v155
	v_mul_f32_e64 v156, |v154|, s82
	v_mul_f32_e64 v157, |v155|, s82
	v_fma_f32 v158, v156, s83, 1.0
	v_fma_f32 v159, v157, s83, 1.0
	v_rcp_f32_e32 v158, v158
	v_rcp_f32_e32 v159, v159
	v_mul_f32_e64 v156, v156, -v156
	v_mul_f32_e64 v157, v157, -v157
	v_mul_f32_e32 v156, 0x3fb8aa3b, v156
	v_mul_f32_e32 v157, 0x3fb8aa3b, v157
	v_fmamk_f32 v160, v158, 0x3f87dc22, v110
	v_fmamk_f32 v161, v159, 0x3f87dc22, v110
	v_exp_f32_e32 v156, v156
	v_exp_f32_e32 v157, v157
	v_fmaak_f32 v160, v158, v160, 0x3fb5f0e3
	v_fmaak_f32 v161, v159, v161, 0x3fb5f0e3
	v_fmaak_f32 v160, v158, v160, 0xbe91a98e
	v_fmaak_f32 v161, v159, v161, 0xbe91a98e
	v_fmaak_f32 v160, v158, v160, 0x3e827906
	v_fmaak_f32 v161, v159, v161, 0x3e827906
	v_mul_f32_e32 v158, v158, v160
	v_mul_f32_e32 v159, v159, v161
	v_fma_f32 v156, -v156, v158, 1.0
	v_fma_f32 v157, -v157, v159, 1.0
	v_mul_f32_e32 v162, 0.5, v154
	v_mul_f32_e32 v163, 0.5, v155
	v_bfi_b32 v154, s84, v156, v154
	v_bfi_b32 v155, s84, v157, v155
	v_add_f32_e32 v154, 1.0, v154
	v_add_f32_e32 v155, 1.0, v155
	v_mul_f32_e32 v154, v162, v154
	v_mul_f32_e32 v155, v163, v155
	v_mul_f32_e32 v154, v48, v154
	v_mul_f32_e32 v155, v49, v155
	v_mul_f32_e32 v154, v225, v154
	v_mul_f32_e32 v155, v243, v155
	v_max_f32_e64 v164, |v154|, |v155|
	s_nop 1
	v_max_f32_dpp v164, v164, v164 quad_perm:[1,0,3,2] row_mask:0xf bank_mask:0xf
	s_nop 1
	v_max_f32_dpp v164, v164, v164 quad_perm:[2,3,0,1] row_mask:0xf bank_mask:0xf
	s_nop 1
	v_max_f32_dpp v164, v164, v164 row_half_mirror row_mask:0xf bank_mask:0xf
	s_nop 1
	v_max_f32_dpp v164, v164, v164 row_mirror row_mask:0xf bank_mask:0xf
	s_nop 1
	v_readlane_b32 s46, v164, 32
	v_readlane_b32 s47, v164, 48
	v_readlane_b32 s12, v164, 0
	v_readlane_b32 s13, v164, 16
	s_nop 1
	v_mov_b32_e32 v164, s47
	v_max_f32_e32 v164, s46, v164
	v_mov_b32_e32 v165, s13
	v_max3_f32 v164, s12, v165, v164
	v_mul_f32_e32 v165, 0x3c09ae41, v164
	v_cmp_lt_f32_e32 vcc, 0, v164
	s_nop 1
	v_cndmask_b32_e32 v164, 1.0, v165, vcc
	v_div_scale_f32 v166, s[12:13], v164, v164, 1.0
	v_rcp_f32_e32 v167, v166
	v_div_scale_f32 v168, vcc, 1.0, v164, 1.0
	v_fma_f32 v169, -v166, v167, 1.0
	v_fmac_f32_e32 v167, v169, v167
	v_mul_f32_e32 v169, v168, v167
	v_fma_f32 v170, -v166, v169, v168
	v_fmac_f32_e32 v169, v170, v167
	v_fma_f32 v166, -v166, v169, v168
	v_div_fmas_f32 v166, v166, v167, v169
	v_div_fixup_f32 v166, v166, v164, 1.0
	v_mul_f32_e32 v154, v166, v154
	v_mul_f32_e32 v155, v166, v155
	v_rndne_f32_e32 v154, v154
	v_rndne_f32_e32 v155, v155
	v_cvt_i32_f32_e32 v154, v154
	v_cvt_i32_f32_e32 v155, v155
	v_perm_b32 v167, v155, v154, s85
	v_add_u32_e32 v154, v154, v155
	ds_write_b16 v90, v167 offset:3072
	s_nop 1
	v_add_u32_dpp v154, v154, v154 quad_perm:[1,0,3,2] row_mask:0xf bank_mask:0xf bound_ctrl:1
	s_nop 1
	v_add_u32_dpp v154, v154, v154 quad_perm:[2,3,0,1] row_mask:0xf bank_mask:0xf bound_ctrl:1
	s_nop 1
	v_add_u32_dpp v154, v154, v154 row_half_mirror row_mask:0xf bank_mask:0xf bound_ctrl:1
	s_nop 1
	v_add_u32_dpp v154, v154, v154 row_mirror row_mask:0xf bank_mask:0xf bound_ctrl:1
	s_nop 1
	v_readlane_b32 s46, v154, 0
	v_readlane_b32 s47, v154, 16
	v_readlane_b32 s12, v154, 32
	v_readlane_b32 s13, v154, 48
	s_nop 1
	s_add_i32 s46, s47, s46
	s_add_i32 s46, s46, s12
	s_add_i32 s46, s46, s13
	s_add_i32 s47, s67, 96
	s_and_saveexec_b64 s[12:13], s[8:9]
	v_mov_b32_e32 v154, s47
	v_mov_b32_e32 v155, s46
	ds_write2st64_b32 v154, v164, v155 offset1:1
	s_or_b64 exec, exec, s[12:13]
	v_lshl_add_u32 v154, v34, 1, v68
	v_lshl_add_u32 v155, v35, 1, v68
	v_cvt_f32_i32_e32 v154, v154
	v_cvt_f32_i32_e32 v155, v155
	v_mul_f32_e32 v154, v226, v154
	v_mul_f32_e32 v155, v244, v155
	v_mul_f32_e32 v154, v76, v154
	v_mul_f32_e32 v155, v76, v155
	v_mul_f32_e64 v156, |v154|, s82
	v_mul_f32_e64 v157, |v155|, s82
	v_fma_f32 v158, v156, s83, 1.0
	v_fma_f32 v159, v157, s83, 1.0
	v_rcp_f32_e32 v158, v158
	v_rcp_f32_e32 v159, v159
	v_mul_f32_e64 v156, v156, -v156
	v_mul_f32_e64 v157, v157, -v157
	v_mul_f32_e32 v156, 0x3fb8aa3b, v156
	v_mul_f32_e32 v157, 0x3fb8aa3b, v157
	v_fmamk_f32 v160, v158, 0x3f87dc22, v110
	v_fmamk_f32 v161, v159, 0x3f87dc22, v110
	v_exp_f32_e32 v156, v156
	v_exp_f32_e32 v157, v157
	v_fmaak_f32 v160, v158, v160, 0x3fb5f0e3
	v_fmaak_f32 v161, v159, v161, 0x3fb5f0e3
	v_fmaak_f32 v160, v158, v160, 0xbe91a98e
	v_fmaak_f32 v161, v159, v161, 0xbe91a98e
	v_fmaak_f32 v160, v158, v160, 0x3e827906
	v_fmaak_f32 v161, v159, v161, 0x3e827906
	v_mul_f32_e32 v158, v158, v160
	v_mul_f32_e32 v159, v159, v161
	v_fma_f32 v156, -v156, v158, 1.0
	v_fma_f32 v157, -v157, v159, 1.0
	v_mul_f32_e32 v162, 0.5, v154
	v_mul_f32_e32 v163, 0.5, v155
	v_bfi_b32 v154, s84, v156, v154
	v_bfi_b32 v155, s84, v157, v155
	v_add_f32_e32 v154, 1.0, v154
; #define LAS __attribute__((address_space(3)))
; __device__ __forceinline__ float gelu_as(float z) {
;     const float ax = fabsf(z) * 0.70710678118654752f, t = __builtin_amdgcn_rcpf(1.f + 0.3275911f * ax);
;     const float poly = t * (0.254829592f + t * (-0.284496736f + t * (1.421413741f + t * (-1.453152027f + t * 1.061405429f))));
;     const float er = 1.f - poly * __expf(-ax * ax);
;     return 0.5f * z * (1.f + copysignf(er, z));
; __global__ void __launch_bounds__(NTHR, 2) k_main(Args a) {
;     ...
;                 const int tl = it * 8 + wave, t = j * 64 + tl;
;                 const unsigned ew = *(const LAS unsigned*)(EL + tl * 128 + 2 * lane); const int e0 = (int)(ew & 0xffffu), e1 = (int)(ew >> 16);
;                 typedef int i2v __attribute__((ext_vector_type(2))); const i2v si = *(const LAS i2v*)(ACC + tl * 128 + 2 * lane);
;                 typedef float f2v __attribute__((ext_vector_type(2))); const f2v gt = *(const LAS f2v*)(GL + tl * 128 + 2 * lane); const float xs = XS[t];
;                 const int sx = ((const int*)(XS + T))[t];
;                 const float z0 = (float)(2 * si.x + sx) * SU[e0] * xs, z1 = (float)(2 * si.y + sx) * SU[e1] * xs;
;                 const float a0 = gt.x * gelu_as(z0) * SV[e0], a1 = gt.y * gelu_as(z1) * SV[e1];
;                 const float mx = wave_max_dpp(fmaxf(fabsf(a0), fabsf(a1)));
;                 const float sc = mx > 0.f ? mx * (1.f / 119.f) : 1.f, inv = 1.f / sc;
;                 const int q0 = (int)rintf(a0 * inv), q1 = (int)rintf(a1 * inv);
;                 *(LAS unsigned short*)(AL + tl * 128 + 2 * lane) = (unsigned short)((q0 & 255) | ((q1 & 255) << 8));
;                 const int qs = wave_sum_dpp_i(q0 + q1);
;                 if (lane == 0) { ASC[tl] = sc; SAL[tl] = qs; }
	v_add_f32_e32 v155, 1.0, v155
	v_mul_f32_e32 v154, v162, v154
	v_mul_f32_e32 v155, v163, v155
	v_mul_f32_e32 v154, v50, v154
	v_mul_f32_e32 v155, v51, v155
	v_mul_f32_e32 v154, v227, v154
	v_mul_f32_e32 v155, v245, v155
	v_max_f32_e64 v164, |v154|, |v155|
	s_nop 1
	v_max_f32_dpp v164, v164, v164 quad_perm:[1,0,3,2] row_mask:0xf bank_mask:0xf
	s_nop 1
	v_max_f32_dpp v164, v164, v164 quad_perm:[2,3,0,1] row_mask:0xf bank_mask:0xf
	s_nop 1
	v_max_f32_dpp v164, v164, v164 row_half_mirror row_mask:0xf bank_mask:0xf
	s_nop 1
	v_max_f32_dpp v164, v164, v164 row_mirror row_mask:0xf bank_mask:0xf
	s_nop 1
	v_readlane_b32 s46, v164, 32
	v_readlane_b32 s47, v164, 48
	v_readlane_b32 s12, v164, 0
	v_readlane_b32 s13, v164, 16
	s_nop 1
	v_mov_b32_e32 v164, s47
	v_max_f32_e32 v164, s46, v164
	v_mov_b32_e32 v165, s13
	v_max3_f32 v164, s12, v165, v164
	v_mul_f32_e32 v165, 0x3c09ae41, v164
	v_cmp_lt_f32_e32 vcc, 0, v164
	s_nop 1
	v_cndmask_b32_e32 v164, 1.0, v165, vcc
	v_div_scale_f32 v166, s[12:13], v164, v164, 1.0
	v_rcp_f32_e32 v167, v166
	v_div_scale_f32 v168, vcc, 1.0, v164, 1.0
	v_fma_f32 v169, -v166, v167, 1.0
	v_fmac_f32_e32 v167, v169, v167
	v_mul_f32_e32 v169, v168, v167
	v_fma_f32 v170, -v166, v169, v168
	v_fmac_f32_e32 v169, v170, v167
	v_fma_f32 v166, -v166, v169, v168
	v_div_fmas_f32 v166, v166, v167, v169
	v_div_fixup_f32 v166, v166, v164, 1.0
	v_mul_f32_e32 v154, v166, v154
	v_mul_f32_e32 v155, v166, v155
	v_rndne_f32_e32 v154, v154
	v_rndne_f32_e32 v155, v155
	v_cvt_i32_f32_e32 v154, v154
	v_cvt_i32_f32_e32 v155, v155
	v_perm_b32 v167, v155, v154, s85
	v_add_u32_e32 v154, v154, v155
	ds_write_b16 v90, v167 offset:4096
	s_nop 1
	v_add_u32_dpp v154, v154, v154 quad_perm:[1,0,3,2] row_mask:0xf bank_mask:0xf bound_ctrl:1
	s_nop 1
	v_add_u32_dpp v154, v154, v154 quad_perm:[2,3,0,1] row_mask:0xf bank_mask:0xf bound_ctrl:1
	s_nop 1
	v_add_u32_dpp v154, v154, v154 row_half_mirror row_mask:0xf bank_mask:0xf bound_ctrl:1
	s_nop 1
	v_add_u32_dpp v154, v154, v154 row_mirror row_mask:0xf bank_mask:0xf bound_ctrl:1
	s_nop 1
	v_readlane_b32 s46, v154, 0
	v_readlane_b32 s47, v154, 16
	v_readlane_b32 s12, v154, 32
	v_readlane_b32 s13, v154, 48
	s_nop 1
	s_add_i32 s46, s47, s46
	s_add_i32 s46, s46, s12
	s_add_i32 s46, s46, s13
	s_add_i32 s47, s67, 128
	s_and_saveexec_b64 s[12:13], s[8:9]
	v_mov_b32_e32 v154, s47
	v_mov_b32_e32 v155, s46
	ds_write2st64_b32 v154, v164, v155 offset1:1
	s_or_b64 exec, exec, s[12:13]
	v_lshl_add_u32 v154, v36, 1, v69
	v_lshl_add_u32 v155, v37, 1, v69
	v_cvt_f32_i32_e32 v154, v154
	v_cvt_f32_i32_e32 v155, v155
	v_mul_f32_e32 v154, v228, v154
	v_mul_f32_e32 v155, v246, v155
	v_mul_f32_e32 v154, v77, v154
	v_mul_f32_e32 v155, v77, v155
	v_mul_f32_e64 v156, |v154|, s82
	v_mul_f32_e64 v157, |v155|, s82
	v_fma_f32 v158, v156, s83, 1.0
	v_fma_f32 v159, v157, s83, 1.0
	v_rcp_f32_e32 v158, v158
	v_rcp_f32_e32 v159, v159
	v_mul_f32_e64 v156, v156, -v156
	v_mul_f32_e64 v157, v157, -v157
	v_mul_f32_e32 v156, 0x3fb8aa3b, v156
	v_mul_f32_e32 v157, 0x3fb8aa3b, v157
	v_fmamk_f32 v160, v158, 0x3f87dc22, v110
	v_fmamk_f32 v161, v159, 0x3f87dc22, v110
	v_exp_f32_e32 v156, v156
	v_exp_f32_e32 v157, v157
	v_fmaak_f32 v160, v158, v160, 0x3fb5f0e3
	v_fmaak_f32 v161, v159, v161, 0x3fb5f0e3
	v_fmaak_f32 v160, v158, v160, 0xbe91a98e
	v_fmaak_f32 v161, v159, v161, 0xbe91a98e
	v_fmaak_f32 v160, v158, v160, 0x3e827906
	v_fmaak_f32 v161, v159, v161, 0x3e827906
	v_mul_f32_e32 v158, v158, v160
	v_mul_f32_e32 v159, v159, v161
	v_fma_f32 v156, -v156, v158, 1.0
	v_fma_f32 v157, -v157, v159, 1.0
	v_mul_f32_e32 v162, 0.5, v154
	v_mul_f32_e32 v163, 0.5, v155
	v_bfi_b32 v154, s84, v156, v154
	v_bfi_b32 v155, s84, v157, v155
	v_add_f32_e32 v154, 1.0, v154
	v_add_f32_e32 v155, 1.0, v155
	v_mul_f32_e32 v154, v162, v154
	v_mul_f32_e32 v155, v163, v155
	v_mul_f32_e32 v154, v52, v154
	v_mul_f32_e32 v155, v53, v155
	v_mul_f32_e32 v154, v229, v154
	v_mul_f32_e32 v155, v247, v155
	v_max_f32_e64 v164, |v154|, |v155|
	s_nop 1
	v_max_f32_dpp v164, v164, v164 quad_perm:[1,0,3,2] row_mask:0xf bank_mask:0xf
	s_nop 1
	v_max_f32_dpp v164, v164, v164 quad_perm:[2,3,0,1] row_mask:0xf bank_mask:0xf
	s_nop 1
	v_max_f32_dpp v164, v164, v164 row_half_mirror row_mask:0xf bank_mask:0xf
	s_nop 1
	v_max_f32_dpp v164, v164, v164 row_mirror row_mask:0xf bank_mask:0xf
	s_nop 1
	v_readlane_b32 s46, v164, 32
	v_readlane_b32 s47, v164, 48
	v_readlane_b32 s12, v164, 0
	v_readlane_b32 s13, v164, 16
	s_nop 1
	v_mov_b32_e32 v164, s47
	v_max_f32_e32 v164, s46, v164
	v_mov_b32_e32 v165, s13
	v_max3_f32 v164, s12, v165, v164
	v_mul_f32_e32 v165, 0x3c09ae41, v164
	v_cmp_lt_f32_e32 vcc, 0, v164
	s_nop 1
	v_cndmask_b32_e32 v164, 1.0, v165, vcc
	v_div_scale_f32 v166, s[12:13], v164, v164, 1.0
	v_rcp_f32_e32 v167, v166
	v_div_scale_f32 v168, vcc, 1.0, v164, 1.0
	v_fma_f32 v169, -v166, v167, 1.0
	v_fmac_f32_e32 v167, v169, v167
	v_mul_f32_e32 v169, v168, v167
	v_fma_f32 v170, -v166, v169, v168
	v_fmac_f32_e32 v169, v170, v167
	v_fma_f32 v166, -v166, v169, v168
	v_div_fmas_f32 v166, v166, v167, v169
	v_div_fixup_f32 v166, v166, v164, 1.0
	v_mul_f32_e32 v154, v166, v154
	v_mul_f32_e32 v155, v166, v155
	v_rndne_f32_e32 v154, v154
	v_rndne_f32_e32 v155, v155
	v_cvt_i32_f32_e32 v154, v154
	v_cvt_i32_f32_e32 v155, v155
	v_perm_b32 v167, v155, v154, s85
	v_add_u32_e32 v154, v154, v155
	ds_write_b16 v90, v167 offset:5120
	s_nop 1
	v_add_u32_dpp v154, v154, v154 quad_perm:[1,0,3,2] row_mask:0xf bank_mask:0xf bound_ctrl:1
	s_nop 1
	v_add_u32_dpp v154, v154, v154 quad_perm:[2,3,0,1] row_mask:0xf bank_mask:0xf bound_ctrl:1
	s_nop 1
	v_add_u32_dpp v154, v154, v154 row_half_mirror row_mask:0xf bank_mask:0xf bound_ctrl:1
; #define LAS __attribute__((address_space(3)))
; __device__ __forceinline__ float gelu_as(float z) {
;     const float ax = fabsf(z) * 0.70710678118654752f, t = __builtin_amdgcn_rcpf(1.f + 0.3275911f * ax);
;     const float poly = t * (0.254829592f + t * (-0.284496736f + t * (1.421413741f + t * (-1.453152027f + t * 1.061405429f))));
;     const float er = 1.f - poly * __expf(-ax * ax);
;     return 0.5f * z * (1.f + copysignf(er, z));
; __global__ void __launch_bounds__(NTHR, 2) k_main(Args a) {
;     ...
;                 const int tl = it * 8 + wave, t = j * 64 + tl;
;                 const unsigned ew = *(const LAS unsigned*)(EL + tl * 128 + 2 * lane); const int e0 = (int)(ew & 0xffffu), e1 = (int)(ew >> 16);
;                 typedef int i2v __attribute__((ext_vector_type(2))); const i2v si = *(const LAS i2v*)(ACC + tl * 128 + 2 * lane);
;                 typedef float f2v __attribute__((ext_vector_type(2))); const f2v gt = *(const LAS f2v*)(GL + tl * 128 + 2 * lane); const float xs = XS[t];
;                 const int sx = ((const int*)(XS + T))[t];
;                 const float z0 = (float)(2 * si.x + sx) * SU[e0] * xs, z1 = (float)(2 * si.y + sx) * SU[e1] * xs;
;                 const float a0 = gt.x * gelu_as(z0) * SV[e0], a1 = gt.y * gelu_as(z1) * SV[e1];
;                 const float mx = wave_max_dpp(fmaxf(fabsf(a0), fabsf(a1)));
;                 const float sc = mx > 0.f ? mx * (1.f / 119.f) : 1.f, inv = 1.f / sc;
;                 const int q0 = (int)rintf(a0 * inv), q1 = (int)rintf(a1 * inv);
;                 *(LAS unsigned short*)(AL + tl * 128 + 2 * lane) = (unsigned short)((q0 & 255) | ((q1 & 255) << 8));
;                 const int qs = wave_sum_dpp_i(q0 + q1);
;                 if (lane == 0) { ASC[tl] = sc; SAL[tl] = qs; }
	s_nop 1
	v_add_u32_dpp v154, v154, v154 row_mirror row_mask:0xf bank_mask:0xf bound_ctrl:1
	s_nop 1
	v_readlane_b32 s46, v154, 0
	v_readlane_b32 s47, v154, 16
	v_readlane_b32 s12, v154, 32
	v_readlane_b32 s13, v154, 48
	s_nop 1
	s_add_i32 s46, s47, s46
	s_add_i32 s46, s46, s12
	s_add_i32 s46, s46, s13
	s_add_i32 s47, s67, 160
	s_and_saveexec_b64 s[12:13], s[8:9]
	v_mov_b32_e32 v154, s47
	v_mov_b32_e32 v155, s46
	ds_write2st64_b32 v154, v164, v155 offset1:1
	s_or_b64 exec, exec, s[12:13]
	v_lshl_add_u32 v154, v38, 1, v70
	v_lshl_add_u32 v155, v39, 1, v70
	v_cvt_f32_i32_e32 v154, v154
	v_cvt_f32_i32_e32 v155, v155
	v_mul_f32_e32 v154, v230, v154
	v_mul_f32_e32 v155, v248, v155
	v_mul_f32_e32 v154, v78, v154
	v_mul_f32_e32 v155, v78, v155
	v_mul_f32_e64 v156, |v154|, s82
	v_mul_f32_e64 v157, |v155|, s82
	v_fma_f32 v158, v156, s83, 1.0
	v_fma_f32 v159, v157, s83, 1.0
	v_rcp_f32_e32 v158, v158
	v_rcp_f32_e32 v159, v159
	v_mul_f32_e64 v156, v156, -v156
	v_mul_f32_e64 v157, v157, -v157
	v_mul_f32_e32 v156, 0x3fb8aa3b, v156
	v_mul_f32_e32 v157, 0x3fb8aa3b, v157
	v_fmamk_f32 v160, v158, 0x3f87dc22, v110
	v_fmamk_f32 v161, v159, 0x3f87dc22, v110
	v_exp_f32_e32 v156, v156
	v_exp_f32_e32 v157, v157
	v_fmaak_f32 v160, v158, v160, 0x3fb5f0e3
	v_fmaak_f32 v161, v159, v161, 0x3fb5f0e3
	v_fmaak_f32 v160, v158, v160, 0xbe91a98e
	v_fmaak_f32 v161, v159, v161, 0xbe91a98e
	v_fmaak_f32 v160, v158, v160, 0x3e827906
	v_fmaak_f32 v161, v159, v161, 0x3e827906
	v_mul_f32_e32 v158, v158, v160
	v_mul_f32_e32 v159, v159, v161
	v_fma_f32 v156, -v156, v158, 1.0
	v_fma_f32 v157, -v157, v159, 1.0
	v_mul_f32_e32 v162, 0.5, v154
	v_mul_f32_e32 v163, 0.5, v155
	v_bfi_b32 v154, s84, v156, v154
	v_bfi_b32 v155, s84, v157, v155
	v_add_f32_e32 v154, 1.0, v154
	v_add_f32_e32 v155, 1.0, v155
	v_mul_f32_e32 v154, v162, v154
	v_mul_f32_e32 v155, v163, v155
	v_mul_f32_e32 v154, v54, v154
	v_mul_f32_e32 v155, v55, v155
	v_mul_f32_e32 v154, v231, v154
	v_mul_f32_e32 v155, v249, v155
	v_max_f32_e64 v164, |v154|, |v155|
	s_nop 1
	v_max_f32_dpp v164, v164, v164 quad_perm:[1,0,3,2] row_mask:0xf bank_mask:0xf
	s_nop 1
	v_max_f32_dpp v164, v164, v164 quad_perm:[2,3,0,1] row_mask:0xf bank_mask:0xf
	s_nop 1
	v_max_f32_dpp v164, v164, v164 row_half_mirror row_mask:0xf bank_mask:0xf
	s_nop 1
	v_max_f32_dpp v164, v164, v164 row_mirror row_mask:0xf bank_mask:0xf
	s_nop 1
	v_readlane_b32 s46, v164, 32
	v_readlane_b32 s47, v164, 48
	v_readlane_b32 s12, v164, 0
	v_readlane_b32 s13, v164, 16
	s_nop 1
	v_mov_b32_e32 v164, s47
	v_max_f32_e32 v164, s46, v164
	v_mov_b32_e32 v165, s13
	v_max3_f32 v164, s12, v165, v164
	v_mul_f32_e32 v165, 0x3c09ae41, v164
	v_cmp_lt_f32_e32 vcc, 0, v164
	s_nop 1
	v_cndmask_b32_e32 v164, 1.0, v165, vcc
	v_div_scale_f32 v166, s[12:13], v164, v164, 1.0
	v_rcp_f32_e32 v167, v166
	v_div_scale_f32 v168, vcc, 1.0, v164, 1.0
	v_fma_f32 v169, -v166, v167, 1.0
	v_fmac_f32_e32 v167, v169, v167
	v_mul_f32_e32 v169, v168, v167
	v_fma_f32 v170, -v166, v169, v168
	v_fmac_f32_e32 v169, v170, v167
	v_fma_f32 v166, -v166, v169, v168
	v_div_fmas_f32 v166, v166, v167, v169
	v_div_fixup_f32 v166, v166, v164, 1.0
	v_mul_f32_e32 v154, v166, v154
	v_mul_f32_e32 v155, v166, v155
	v_rndne_f32_e32 v154, v154
	v_rndne_f32_e32 v155, v155
	v_cvt_i32_f32_e32 v154, v154
	v_cvt_i32_f32_e32 v155, v155
	v_perm_b32 v167, v155, v154, s85
	v_add_u32_e32 v154, v154, v155
	ds_write_b16 v90, v167 offset:6144
	s_nop 1
	v_add_u32_dpp v154, v154, v154 quad_perm:[1,0,3,2] row_mask:0xf bank_mask:0xf bound_ctrl:1
	s_nop 1
	v_add_u32_dpp v154, v154, v154 quad_perm:[2,3,0,1] row_mask:0xf bank_mask:0xf bound_ctrl:1
	s_nop 1
	v_add_u32_dpp v154, v154, v154 row_half_mirror row_mask:0xf bank_mask:0xf bound_ctrl:1
	s_nop 1
	v_add_u32_dpp v154, v154, v154 row_mirror row_mask:0xf bank_mask:0xf bound_ctrl:1
	s_nop 1
	v_readlane_b32 s46, v154, 0
	v_readlane_b32 s47, v154, 16
	v_readlane_b32 s12, v154, 32
	v_readlane_b32 s13, v154, 48
	s_nop 1
	s_add_i32 s46, s47, s46
	s_add_i32 s46, s46, s12
	s_add_i32 s46, s46, s13
	s_add_i32 s47, s67, 192
; #define LAS __attribute__((address_space(3)))
; __device__ __forceinline__ unsigned xb_ld(unsigned* p)              { return __hip_atomic_load(p, __ATOMIC_RELAXED, __HIP_MEMORY_SCOPE_AGENT); }
; #define XB_SPIN(cond, bar) do { unsigned _sp = 0; while (cond) { __builtin_amdgcn_s_sleep(1); \
;     if ((++_sp & 255u) == 0u) { if (xb_ld(&(bar)[XB_TMO])) break; if (_sp > XB_SPIN_CAP) { atomicAdd(&(bar)[XB_TMO], 1u); break; } } } } while (0)
; __device__ __forceinline__ float gelu_as(float z) {
;     const float ax = fabsf(z) * 0.70710678118654752f, t = __builtin_amdgcn_rcpf(1.f + 0.3275911f * ax);
;     const float poly = t * (0.254829592f + t * (-0.284496736f + t * (1.421413741f + t * (-1.453152027f + t * 1.061405429f))));
;     const float er = 1.f - poly * __expf(-ax * ax);
;     return 0.5f * z * (1.f + copysignf(er, z));
; __global__ void __launch_bounds__(NTHR, 2) k_main(Args a) {
;     ...
;                 const int tl = it * 8 + wave, t = j * 64 + tl;
;                 const unsigned ew = *(const LAS unsigned*)(EL + tl * 128 + 2 * lane); const int e0 = (int)(ew & 0xffffu), e1 = (int)(ew >> 16);
;                 typedef int i2v __attribute__((ext_vector_type(2))); const i2v si = *(const LAS i2v*)(ACC + tl * 128 + 2 * lane);
;                 typedef float f2v __attribute__((ext_vector_type(2))); const f2v gt = *(const LAS f2v*)(GL + tl * 128 + 2 * lane); const float xs = XS[t];
;                 const int sx = ((const int*)(XS + T))[t];
;                 const float z0 = (float)(2 * si.x + sx) * SU[e0] * xs, z1 = (float)(2 * si.y + sx) * SU[e1] * xs;
;                 const float a0 = gt.x * gelu_as(z0) * SV[e0], a1 = gt.y * gelu_as(z1) * SV[e1];
;                 const float mx = wave_max_dpp(fmaxf(fabsf(a0), fabsf(a1)));
;                 const float sc = mx > 0.f ? mx * (1.f / 119.f) : 1.f, inv = 1.f / sc;
;                 const int q0 = (int)rintf(a0 * inv), q1 = (int)rintf(a1 * inv);
;                 *(LAS unsigned short*)(AL + tl * 128 + 2 * lane) = (unsigned short)((q0 & 255) | ((q1 & 255) << 8));
;                 const int qs = wave_sum_dpp_i(q0 + q1);
;                 if (lane == 0) { ASC[tl] = sc; SAL[tl] = qs; }
;             }
;             if (tid == 0) XB_SPIN(xb_ld(&((unsigned*)ws)[14400]) < (unsigned)((T / 256) * (D / 256)), (unsigned*)ws);
	s_and_saveexec_b64 s[12:13], s[8:9]
	v_mov_b32_e32 v154, s47
	v_mov_b32_e32 v155, s46
	ds_write2st64_b32 v154, v164, v155 offset1:1
	s_or_b64 exec, exec, s[12:13]
	v_lshl_add_u32 v154, v40, 1, v71
	v_lshl_add_u32 v155, v41, 1, v71
	v_cvt_f32_i32_e32 v154, v154
	v_cvt_f32_i32_e32 v155, v155
	v_mul_f32_e32 v154, v232, v154
	v_mul_f32_e32 v155, v250, v155
	v_mul_f32_e32 v154, v79, v154
	v_mul_f32_e32 v155, v79, v155
	v_mul_f32_e64 v156, |v154|, s82
	v_mul_f32_e64 v157, |v155|, s82
	v_fma_f32 v158, v156, s83, 1.0
	v_fma_f32 v159, v157, s83, 1.0
	v_rcp_f32_e32 v158, v158
	v_rcp_f32_e32 v159, v159
	v_mul_f32_e64 v156, v156, -v156
	v_mul_f32_e64 v157, v157, -v157
	v_mul_f32_e32 v156, 0x3fb8aa3b, v156
	v_mul_f32_e32 v157, 0x3fb8aa3b, v157
	v_fmamk_f32 v160, v158, 0x3f87dc22, v110
	v_fmamk_f32 v161, v159, 0x3f87dc22, v110
	v_exp_f32_e32 v156, v156
	v_exp_f32_e32 v157, v157
	v_fmaak_f32 v160, v158, v160, 0x3fb5f0e3
	v_fmaak_f32 v161, v159, v161, 0x3fb5f0e3
	v_fmaak_f32 v160, v158, v160, 0xbe91a98e
	v_fmaak_f32 v161, v159, v161, 0xbe91a98e
	v_fmaak_f32 v160, v158, v160, 0x3e827906
	v_fmaak_f32 v161, v159, v161, 0x3e827906
	v_mul_f32_e32 v158, v158, v160
	v_mul_f32_e32 v159, v159, v161
	v_fma_f32 v156, -v156, v158, 1.0
	v_fma_f32 v157, -v157, v159, 1.0
	v_mul_f32_e32 v162, 0.5, v154
	v_mul_f32_e32 v163, 0.5, v155
	v_bfi_b32 v154, s84, v156, v154
	v_bfi_b32 v155, s84, v157, v155
	v_add_f32_e32 v154, 1.0, v154
	v_add_f32_e32 v155, 1.0, v155
	v_mul_f32_e32 v154, v162, v154
	v_mul_f32_e32 v155, v163, v155
	v_mul_f32_e32 v154, v56, v154
	v_mul_f32_e32 v155, v57, v155
	v_mul_f32_e32 v154, v233, v154
	v_mul_f32_e32 v155, v251, v155
	v_max_f32_e64 v164, |v154|, |v155|
	s_nop 1
	v_max_f32_dpp v164, v164, v164 quad_perm:[1,0,3,2] row_mask:0xf bank_mask:0xf
	s_nop 1
	v_max_f32_dpp v164, v164, v164 quad_perm:[2,3,0,1] row_mask:0xf bank_mask:0xf
	s_nop 1
	v_max_f32_dpp v164, v164, v164 row_half_mirror row_mask:0xf bank_mask:0xf
	s_nop 1
	v_max_f32_dpp v164, v164, v164 row_mirror row_mask:0xf bank_mask:0xf
	s_nop 1
	v_readlane_b32 s46, v164, 32
	v_readlane_b32 s47, v164, 48
	v_readlane_b32 s12, v164, 0
	v_readlane_b32 s13, v164, 16
	s_nop 1
	v_mov_b32_e32 v164, s47
	v_max_f32_e32 v164, s46, v164
	v_mov_b32_e32 v165, s13
	v_max3_f32 v164, s12, v165, v164
	v_mul_f32_e32 v165, 0x3c09ae41, v164
	v_cmp_lt_f32_e32 vcc, 0, v164
	s_nop 1
	v_cndmask_b32_e32 v164, 1.0, v165, vcc
	v_div_scale_f32 v166, s[12:13], v164, v164, 1.0
	v_rcp_f32_e32 v167, v166
	v_div_scale_f32 v168, vcc, 1.0, v164, 1.0
	v_fma_f32 v169, -v166, v167, 1.0
	v_fmac_f32_e32 v167, v169, v167
	v_mul_f32_e32 v169, v168, v167
	v_fma_f32 v170, -v166, v169, v168
	v_fmac_f32_e32 v169, v170, v167
	v_fma_f32 v166, -v166, v169, v168
	v_div_fmas_f32 v166, v166, v167, v169
	v_div_fixup_f32 v166, v166, v164, 1.0
	v_mul_f32_e32 v154, v166, v154
	v_mul_f32_e32 v155, v166, v155
	v_rndne_f32_e32 v154, v154
	v_rndne_f32_e32 v155, v155
	v_cvt_i32_f32_e32 v154, v154
	v_cvt_i32_f32_e32 v155, v155
	v_perm_b32 v167, v155, v154, s85
	v_add_u32_e32 v154, v154, v155
	ds_write_b16 v90, v167 offset:7168
	s_nop 1
	v_add_u32_dpp v154, v154, v154 quad_perm:[1,0,3,2] row_mask:0xf bank_mask:0xf bound_ctrl:1
	s_nop 1
	v_add_u32_dpp v154, v154, v154 quad_perm:[2,3,0,1] row_mask:0xf bank_mask:0xf bound_ctrl:1
	s_nop 1
	v_add_u32_dpp v154, v154, v154 row_half_mirror row_mask:0xf bank_mask:0xf bound_ctrl:1
	s_nop 1
	v_add_u32_dpp v154, v154, v154 row_mirror row_mask:0xf bank_mask:0xf bound_ctrl:1
	s_nop 1
	v_readlane_b32 s46, v154, 0
	v_readlane_b32 s47, v154, 16
	v_readlane_b32 s12, v154, 32
	v_readlane_b32 s13, v154, 48
	s_nop 1
	s_add_i32 s46, s47, s46
	s_add_i32 s46, s46, s12
	s_add_i32 s46, s46, s13
	s_add_i32 s47, s67, 224
	s_and_saveexec_b64 s[12:13], s[8:9]
	v_mov_b32_e32 v154, s47
	v_mov_b32_e32 v155, s46
	ds_write2st64_b32 v154, v164, v155 offset1:1
	s_or_b64 exec, exec, s[12:13]
.LBB0_678:
	s_and_saveexec_b64 s[10:11], s[0:1]
	s_cbranch_execz .LBB0_691
	v_mov_b32_e32 v18, v252
	v_cmp_lt_u32_e32 vcc, s3, v18
	s_cbranch_vccnz .LBB0_691
	s_mov_b32 s41, 1
	s_branch .LBB0_682

; __device__ __forceinline__ void peer_v_tokens(int j, const LAS unsigned short* EL, const LAS unsigned char* AL  , const LAS float* ASC  , const LAS int* SAL  , ...
;     ...
;     const int BUF[3] = {vslot(3 * wave), vslot(3 * wave + 1), vslot(3 * wave + 2)};
;     const int g = lane >> 3, j8 = lane & 7, s16 = lane & 15, grp = lane >> 4;
;     *(LAS unsigned long long*)(ldsb + BUF[0] + 8 * s16) = 0xFEDCBA9876543210ull;
;     CFENCE();
;     const v2i cal = TR4(ldsb + BUF[0] + 8 * s16);
;     const int pc = cal.x & 15;
;     asm volatile("s_waitcnt lgkmcnt(0)" ::: "memory");
;     const unsigned cx0 = 16u * (unsigned)(j8 ^ (g >> 1)), cx1 = 16u * (unsigned)(j8 ^ (4 + (g >> 1)));
;     const int fr = (4 * (s16 >> 3) + ((s16 & 7) >> 1)) & 7;
;     int roff[4];
; #pragma unroll
;     for (int r = 0; r < 4; ++r) roff[r] = 128 * s16 + 16 * ((((grp >> 1) + 2 * r)) ^ fr) + 8 * (grp & 1);
;     ...
; #pragma unroll 1
;     for (int it = 0; it < 8; ++it) {
;         const int tl = it * 8 + wave, t = j * 64 + tl;
;         unsigned E[8];
;         { const LAS v4u* ep = (const LAS v4u*)(EL + tl * 128 + 16 * g); const v4u e0 = ep[0], e1 = ep[1];
;           E[0] = e0.x; E[1] = e0.y; E[2] = e0.z; E[3] = e0.w; E[4] = e1.x; E[5] = e1.y; E[6] = e1.z; E[7] = e1.w; }
;         uint2 hv[4]; float4 gv[4];
;         { unsigned ho = (unsigned)t * (D / 4) + (unsigned)lane; asm volatile("" : "+v"(ho)); const uint2* hp = (const uint2*)HB + ho; const float4* gp = (const float4*)fng + lane;
; #pragma unroll
;           for (int jq = 0; jq < 4; ++jq) { hv[jq] = hp[64 * jq]; gv[jq] = gp[64 * jq]; } }
;         VDMA(0, 0); VDMA(1, 1);
; #pragma unroll
;         for (int m = 0; m < 2; ++m) {
;             const int idx = lane + 64 * m, tau = idx >> 4, sr = idx & 15, k = 16 * (sr & 7) + 2 * tau + (sr >> 3);
;             const int aq = (int)*(const LAS signed char*)(AL + tl * 128 + k); const int tq = aq + 8;
;             const unsigned lo = (((unsigned)tq & 15u) ^ 8u) * 0x11111111u, hi = ((unsigned)(tq >> 4) & 15u) * 0x11111111u;
;             typedef unsigned u2v __attribute__((ext_vector_type(2)));
;             u2v l2; l2.x = lo; l2.y = lo; u2v h2; h2.x = hi; h2.y = hi;
;             *(LAS u2v*)(ATL + 8 * idx) = l2; *(LAS u2v*)(ATL + 1024 + 8 * idx) = h2;
;         }
;         const float asc = ASC[tl]; const int sa = SAL[tl];
;         CFENCE();
;         int accH[4], accL[4];
; #pragma unroll
.LBB0_691:
	s_or_b64 exec, exec, s[10:11]
	v_mov_b32_e32 v18, v1
	s_waitcnt lgkmcnt(0)
	s_barrier
	v_readlane_b32 s70, v235, 50
	v_and_b32_e32 v19, 15, v18
	v_lshlrev_b32_e32 v58, 3, v19
	v_add_u32_e32 v20, s60, v58
	ds_write_b64 v20, v[84:85]
	v_lshrrev_b32_e32 v23, 1, v18
	v_ashrrev_i32_e32 v24, 5, v18
	v_and_b32_e32 v25, 8, v23
	ds_read_b64_tr_b4 v[20:21], v20
	v_lshl_or_b32 v19, v19, 7, v25
	v_bitop3_b32 v25, v23, v24, 7 bitop3:0x6c
	v_lshl_add_u32 v59, v25, 4, v19
	v_add_u32_e32 v25, 2, v24
	v_bitop3_b32 v25, v25, v23, 7 bitop3:0x78
	v_lshl_add_u32 v60, v25, 4, v19
	v_add_u32_e32 v25, 4, v24
	v_add_u32_e32 v24, 6, v24
	s_waitcnt lgkmcnt(0)
	v_ashrrev_i32_e32 v21, 4, v18
	v_bitop3_b32 v25, v25, v23, 7 bitop3:0x78
	v_bitop3_b32 v23, v24, v23, 7 bitop3:0x78
	v_bitop3_b32 v22, v18, v21, 7 bitop3:0x6c
	v_add_u32_e32 v21, 4, v21
	v_lshl_add_u32 v61, v25, 4, v19
	v_lshl_add_u32 v62, v23, 4, v19
	v_and_b32_e32 v19, 15, v20
	v_bitop3_b32 v21, v21, v18, 7 bitop3:0x78
	v_lshlrev_b32_e32 v63, 4, v22
	v_lshlrev_b32_e32 v22, 1, v19
	v_ashrrev_i32_e32 v19, 31, v18
	v_lshlrev_b32_e32 v64, 4, v21
	v_lshlrev_b64 v[20:21], 4, v[18:19]
	v_and_b32_e32 v25, 0x7ffffff0, v18
	v_lshl_add_u64 v[34:35], s[86:87], 0, v[20:21]
	v_lshlrev_b32_e32 v19, 4, v18
	v_lshlrev_b32_e32 v25, 1, v25
	v_lshl_add_u64 v[36:37], s[88:89], 0, v[20:21]
	v_add_u32_e32 v21, 64, v18
	s_waitcnt lgkmcnt(0)
	v_and_b32_e32 v19, 0x70, v19
	v_add3_u32 v65, s58, v22, v25
	v_ashrrev_i32_e32 v20, 3, v18
	v_ashrrev_i32_e32 v22, 3, v21
	v_lshrrev_b32_e32 v23, 3, v18
	v_bfe_u32 v24, v18, 3, 1
	v_and_b32_e32 v20, -2, v20
	v_and_b32_e32 v22, -2, v22
	v_lshlrev_b32_e32 v21, 3, v21
	v_add_u32_e32 v19, s72, v19
	v_lshlrev_b32_e32 v66, 3, v18
	v_add_u32_e32 v67, 0x200000, v63
	v_add_u32_e32 v68, 0x200000, v64
	v_add_u32_e32 v69, 0x400000, v63
	v_add_u32_e32 v70, 0x400000, v64
	v_add_u32_e32 v71, 0x600000, v63
	v_add_u32_e32 v72, 0x600000, v64
	v_add3_u32 v73, v19, v22, v24
	v_add3_u32 v74, v19, v20, v24
	v_lshl_add_u32 v75, v23, 5, s65
	v_add_u32_e32 v76, s73, v18
	s_mov_b32 s12, 0
	v_add_u32_e32 v77, s59, v21
	s_mov_b32 s13, s67
	v_readlane_b32 s71, v235, 51
	s_nop 0
	s_nop 0
	s_nop 0
	s_nop 0
	s_nop 0
	s_nop 0
	s_mov_b32 s76, s60
	s_add_i32 s77, s60, 0x800
	s_mov_b32 s78, s61
	s_add_i32 s79, s61, 0x800
	s_mov_b32 s98, s62
	s_add_i32 s99, s62, 0x800
	v_add_u32_e32 v159, s59, v66
	v_add_u32_e32 v160, s59, v58
	v_add_u32_e32 v154, s58, v66
	v_add_u32_e32 v227, 0x12000, v75
	v_lshlrev_b32_e32 v138, 1, v66
	v_add_u32_e32 v155, 0x11200, v138
	v_add_u32_e32 v156, 0x27400, v138
	global_load_dwordx4 v[210:213], v[34:35], off
	global_load_dwordx4 v[214:217], v[34:35], off offset:1024
	global_load_dwordx4 v[218:221], v[34:35], off offset:2048
	global_load_dwordx4 v[222:225], v[34:35], off offset:3072
	ds_read_b128 v[18:21], v227
	ds_read_b128 v[22:25], v227 offset:16
	v_mov_b32_e32 v138, v74
	ds_read_u8 v139, v138
	v_mov_b32_e32 v141, v73
	ds_read_u8 v140, v141
	v_mov_b32_e32 v150, v63
	v_mov_b32_e32 v151, v64
	s_waitcnt lgkmcnt(0)
	v_and_b32_e32 v78, 0xffff, v18
	v_lshrrev_b32_e32 v79, 16, v18
	v_lshl_add_u32 v78, v78, 7, v150
	v_lshl_add_u32 v79, v79, 7, v151
	s_mov_b32 m0, s76
	s_add_i32 s43, s76, 0x400
	global_load_lds_dwordx4 v78, s[50:51]
	s_mov_b32 m0, s43
	s_nop 0
	global_load_lds_dwordx4 v79, s[50:51]
	v_and_b32_e32 v78, 0xffff, v19
	v_lshrrev_b32_e32 v79, 16, v19
	v_lshl_add_u32 v78, v78, 7, v150
	v_lshl_add_u32 v79, v79, 7, v151
	s_mov_b32 m0, s77
	s_add_i32 s43, s77, 0x400
	global_load_lds_dwordx4 v78, s[50:51]
	s_mov_b32 m0, s43
	s_nop 0
	global_load_lds_dwordx4 v79, s[50:51]
	v_and_b32_e32 v78, 0xffff, v20
	v_lshrrev_b32_e32 v79, 16, v20
	v_lshl_add_u32 v78, v78, 7, v150
	v_lshl_add_u32 v79, v79, 7, v151
	s_mov_b32 m0, s78
	s_add_i32 s43, s78, 0x400
	global_load_lds_dwordx4 v78, s[50:51]
	s_mov_b32 m0, s43
	s_nop 0
	global_load_lds_dwordx4 v79, s[50:51]
	v_and_b32_e32 v78, 0xffff, v21
	v_lshrrev_b32_e32 v79, 16, v21
	v_lshl_add_u32 v78, v78, 7, v150
	v_lshl_add_u32 v79, v79, 7, v151
	s_mov_b32 m0, s79
	s_add_i32 s43, s79, 0x400
	global_load_lds_dwordx4 v78, s[50:51]
	s_mov_b32 m0, s43
	s_nop 0
	global_load_lds_dwordx4 v79, s[50:51]
	v_and_b32_e32 v78, 0xffff, v22
	v_lshrrev_b32_e32 v79, 16, v22
	v_lshl_add_u32 v78, v78, 7, v150
	v_lshl_add_u32 v79, v79, 7, v151
	s_mov_b32 m0, s98
	s_add_i32 s43, s98, 0x400
	global_load_lds_dwordx4 v78, s[50:51]
	s_mov_b32 m0, s43
	s_nop 0
	global_load_lds_dwordx4 v79, s[50:51]
	v_add_u32_e32 v143, 8, v139
	v_and_b32_e32 v142, 15, v143
	v_xor_b32_e32 v142, 8, v142
	v_bfe_u32 v144, v143, 4, 4
	v_mul_lo_u32 v142, v142, s92
	v_mul_lo_u32 v144, v144, s92
	v_mov_b32_e32 v143, v142
	v_mov_b32_e32 v145, v144
	ds_write2st64_b64 v159, v[142:143], v[144:145] offset1:2
	s_waitcnt vmcnt(10)
	ds_write_b128 v155, v[210:213]
	ds_write_b128 v155, v[214:217] offset:1024
	ds_write_b128 v156, v[218:221]
	ds_write_b128 v156, v[222:225] offset:1024
	s_waitcnt vmcnt(8)
	v_add_u32_e32 v54, s76, v59
	v_add_u32_e32 v55, s76, v60
	v_add_u32_e32 v56, s76, v61
	v_add_u32_e32 v57, s76, v62
	ds_read_b64_tr_b4 v[46:47], v160
	ds_read_b64_tr_b4 v[48:49], v160 offset:1024
	ds_read_b64_tr_b4 v[122:123], v54
	ds_read_b64_tr_b4 v[124:125], v55
	ds_read_b64_tr_b4 v[126:127], v56
	ds_read_b64_tr_b4 v[128:129], v57
	v_add_u32_e32 v147, 8, v140
	v_and_b32_e32 v146, 15, v147
	v_xor_b32_e32 v146, 8, v146
	v_bfe_u32 v148, v147, 4, 4
	v_mul_lo_u32 v146, v146, s92
	v_mul_lo_u32 v148, v148, s92
	v_mov_b32_e32 v147, v146
	v_mov_b32_e32 v149, v148
	ds_write2st64_b64 v77, v[146:147], v[148:149] offset1:2
	v_add_u32_e32 v138, 0x400, v74
	ds_read_u8 v139, v138
	v_add_u32_e32 v141, 0x400, v73
	ds_read_u8 v140, v141
	s_mov_b32 s43, s67
	v_mov_b32_e32 v138, s43
	ds_read2st64_b32 v[228:229], v138 offset1:1
	ds_read_b128 v[26:29], v227 offset:2048
	ds_read_b128 v[30:33], v227 offset:2064
	v_mov_b32_e32 v38, 0
	v_mov_b32_e32 v39, 0
	v_mov_b32_e32 v40, 0
	v_mov_b32_e32 v41, 0
	v_mov_b32_e32 v42, 0
	v_mov_b32_e32 v43, 0
	v_mov_b32_e32 v44, 0
	v_mov_b32_e32 v45, 0
	v_and_b32_e32 v78, 0xffff, v23
	v_lshrrev_b32_e32 v79, 16, v23
	v_lshl_add_u32 v78, v78, 7, v150
	v_lshl_add_u32 v79, v79, 7, v151
	s_mov_b32 m0, s99
	s_add_i32 s43, s99, 0x400
	global_load_lds_dwordx4 v78, s[50:51]
	s_mov_b32 m0, s43
	s_nop 0
	global_load_lds_dwordx4 v79, s[50:51]
	s_waitcnt vmcnt(8)
; __device__ __forceinline__ bf16 f2bf(float f) { return (bf16)f2bfu(f); }
; #define TR4(p_) __builtin_amdgcn_ds_read_tr4_b64_v2i32((LAS v2i*)(p_))
; #define VDMA(st_, k_) do { _Pragma("unroll") for (int i_ = 0; i_ < 4; ++i_) { \
;         const unsigned off_ = (unsigned)((st_) >> 2) * (16384u * 128u) + (PE_ID(E, 4 * ((st_) & 3) + i_) << 7) + ((i_ & 1) ? cx1 : cx0); \
;         __builtin_amdgcn_global_load_lds((const unsigned*)(V4 + off_), (LAS unsigned*)(ldsb + BUF[k_] + 1024 * i_), 16, 0, 0); } } while (0)
; __device__ __forceinline__ void peer_v_tokens(int j, const LAS unsigned short* EL, const LAS unsigned char* AL  , const LAS float* ASC  , const LAS int* SAL  , ...
;     ...
;         for (int st = 0; st < 16; ++st) {
;             const int p = st >> 2, q = st & 3;
;             if (st < 14) VDMA(st + 2, (st + 2) % 3);
;             if (st < 14) asm volatile("s_waitcnt vmcnt(8)" ::: "memory");
;             else if (st == 14) asm volatile("s_waitcnt vmcnt(4)" ::: "memory");
;             else asm volatile("s_waitcnt vmcnt(0)" ::: "memory");
;             if (q == 0) {
; #pragma unroll
;                 for (int r = 0; r < 4; ++r) { accH[r] = 0; accL[r] = 0; } }
; #pragma unroll
;             for (int tp = 0; tp < 2; ++tp) {
;                 const v2i ao = TR4(ATL + (2 * q + tp) * 128 + 8 * s16), ah = TR4(ATL + 1024 + (2 * q + tp) * 128 + 8 * s16);
; #pragma unroll
;                 for (int r = 0; r < 4; ++r) {
;                     const v2i d = TR4(ldsb + BUF[st % 3] + 2048 * tp + roff[r]);
;                     accH[r] = __builtin_amdgcn_sdot8(d.x, ah.x, accH[r], false); accH[r] = __builtin_amdgcn_sdot8(d.y, ah.y, accH[r], false);
;                     accL[r] = __builtin_amdgcn_sdot8(d.x, ao.x, accL[r], false); accL[r] = __builtin_amdgcn_sdot8(d.y, ao.y, accL[r], false);
;                 }
;             }
;             asm volatile("s_waitcnt lgkmcnt(0)" ::: "memory");
;             if (q == 3) {
; #pragma unroll
;                 for (int r = 0; r < 4; ++r) STASH[256 * p + 16 * (grp + 4 * r) + pc] = f2bf(asc * (float)(2 * ((accH[r] << 4) + accL[r]) + sa));
;             }
	v_add_u32_e32 v54, s77, v59
	v_add_u32_e32 v55, s77, v60
	v_add_u32_e32 v56, s77, v61
	v_add_u32_e32 v57, s77, v62
	ds_read_b64_tr_b4 v[50:51], v160 offset:128
	ds_read_b64_tr_b4 v[52:53], v160 offset:1152
	ds_read_b64_tr_b4 v[130:131], v54
	ds_read_b64_tr_b4 v[132:133], v55
	ds_read_b64_tr_b4 v[134:135], v56
	ds_read_b64_tr_b4 v[136:137], v57
	s_waitcnt lgkmcnt(12)
	v_dot8c_i32_i4_e32 v38, v122, v48
	v_dot8c_i32_i4_e32 v39, v122, v46
	v_dot8c_i32_i4_e32 v40, v124, v48
	v_dot8c_i32_i4_e32 v41, v124, v46
	v_dot8c_i32_i4_e32 v42, v126, v48
	v_dot8c_i32_i4_e32 v43, v126, v46
	v_dot8c_i32_i4_e32 v44, v128, v48
	v_dot8c_i32_i4_e32 v45, v128, v46
	v_dot8c_i32_i4_e32 v38, v123, v49
	v_dot8c_i32_i4_e32 v39, v123, v47
	v_dot8c_i32_i4_e32 v40, v125, v49
	v_dot8c_i32_i4_e32 v41, v125, v47
	v_dot8c_i32_i4_e32 v42, v127, v49
	v_dot8c_i32_i4_e32 v43, v127, v47
	v_dot8c_i32_i4_e32 v44, v129, v49
	v_dot8c_i32_i4_e32 v45, v129, v47
	v_and_b32_e32 v78, 0xffff, v24
	v_lshrrev_b32_e32 v79, 16, v24
	v_lshl_add_u32 v78, v78, 7, v150
	v_lshl_add_u32 v79, v79, 7, v151
	s_mov_b32 m0, s76
	s_add_i32 s43, s76, 0x400
	global_load_lds_dwordx4 v78, s[50:51]
	s_mov_b32 m0, s43
	s_nop 0
	global_load_lds_dwordx4 v79, s[50:51]
	s_waitcnt vmcnt(8)
	v_add_u32_e32 v54, s78, v59
	v_add_u32_e32 v55, s78, v60
	v_add_u32_e32 v56, s78, v61
	v_add_u32_e32 v57, s78, v62
	ds_read_b64_tr_b4 v[46:47], v160 offset:256
	ds_read_b64_tr_b4 v[48:49], v160 offset:1280
	ds_read_b64_tr_b4 v[122:123], v54
	ds_read_b64_tr_b4 v[124:125], v55
	ds_read_b64_tr_b4 v[126:127], v56
	ds_read_b64_tr_b4 v[128:129], v57
	s_waitcnt lgkmcnt(6)
	v_dot8c_i32_i4_e32 v38, v130, v52
	v_dot8c_i32_i4_e32 v39, v130, v50
	v_dot8c_i32_i4_e32 v40, v132, v52
	v_dot8c_i32_i4_e32 v41, v132, v50
	v_dot8c_i32_i4_e32 v42, v134, v52
	v_dot8c_i32_i4_e32 v43, v134, v50
	v_dot8c_i32_i4_e32 v44, v136, v52
	v_dot8c_i32_i4_e32 v45, v136, v50
	v_dot8c_i32_i4_e32 v38, v131, v53
	v_dot8c_i32_i4_e32 v39, v131, v51
	v_dot8c_i32_i4_e32 v40, v133, v53
	v_dot8c_i32_i4_e32 v41, v133, v51
	v_dot8c_i32_i4_e32 v42, v135, v53
	v_dot8c_i32_i4_e32 v43, v135, v51
	v_dot8c_i32_i4_e32 v44, v137, v53
	v_dot8c_i32_i4_e32 v45, v137, v51
	v_and_b32_e32 v78, 0xffff, v25
	v_lshrrev_b32_e32 v79, 16, v25
	v_lshl_add_u32 v78, v78, 7, v150
	v_lshl_add_u32 v79, v79, 7, v151
	s_mov_b32 m0, s77
	s_add_i32 s43, s77, 0x400
	global_load_lds_dwordx4 v78, s[50:51]
	s_mov_b32 m0, s43
	s_nop 0
	global_load_lds_dwordx4 v79, s[50:51]
	s_waitcnt vmcnt(8)
	v_add_u32_e32 v54, s79, v59
	v_add_u32_e32 v55, s79, v60
	v_add_u32_e32 v56, s79, v61
	v_add_u32_e32 v57, s79, v62
	ds_read_b64_tr_b4 v[50:51], v160 offset:384
	ds_read_b64_tr_b4 v[52:53], v160 offset:1408
	ds_read_b64_tr_b4 v[130:131], v54
	ds_read_b64_tr_b4 v[132:133], v55
	ds_read_b64_tr_b4 v[134:135], v56
	ds_read_b64_tr_b4 v[136:137], v57
	s_waitcnt lgkmcnt(6)
	v_dot8c_i32_i4_e32 v38, v122, v48
	v_dot8c_i32_i4_e32 v39, v122, v46
	v_dot8c_i32_i4_e32 v40, v124, v48
	v_dot8c_i32_i4_e32 v41, v124, v46
	v_dot8c_i32_i4_e32 v42, v126, v48
	v_dot8c_i32_i4_e32 v43, v126, v46
	v_dot8c_i32_i4_e32 v44, v128, v48
	v_dot8c_i32_i4_e32 v45, v128, v46
	v_dot8c_i32_i4_e32 v38, v123, v49
	v_dot8c_i32_i4_e32 v39, v123, v47
	v_dot8c_i32_i4_e32 v40, v125, v49
	v_dot8c_i32_i4_e32 v41, v125, v47
	v_dot8c_i32_i4_e32 v42, v127, v49
	v_dot8c_i32_i4_e32 v43, v127, v47
	v_dot8c_i32_i4_e32 v44, v129, v49
	v_dot8c_i32_i4_e32 v45, v129, v47
	s_waitcnt lgkmcnt(15)
	v_and_b32_e32 v78, 0xffff, v26
	v_lshrrev_b32_e32 v79, 16, v26
	v_lshl_add_u32 v78, v78, 7, v150
	v_lshl_add_u32 v79, v79, 7, v151
	s_mov_b32 m0, s78
	s_add_i32 s43, s78, 0x400
	global_load_lds_dwordx4 v78, s[50:51]
	s_mov_b32 m0, s43
	s_nop 0
	global_load_lds_dwordx4 v79, s[50:51]
	s_waitcnt vmcnt(8)
	v_add_u32_e32 v54, s98, v59
	v_add_u32_e32 v55, s98, v60
	v_add_u32_e32 v56, s98, v61
	v_add_u32_e32 v57, s98, v62
	ds_read_b64_tr_b4 v[46:47], v160 offset:512
	ds_read_b64_tr_b4 v[48:49], v160 offset:1536
	ds_read_b64_tr_b4 v[122:123], v54
	ds_read_b64_tr_b4 v[124:125], v55
	ds_read_b64_tr_b4 v[126:127], v56
	ds_read_b64_tr_b4 v[128:129], v57
	s_waitcnt lgkmcnt(6)
	v_dot8c_i32_i4_e32 v38, v130, v52
	v_dot8c_i32_i4_e32 v39, v130, v50
	v_dot8c_i32_i4_e32 v40, v132, v52
	v_dot8c_i32_i4_e32 v41, v132, v50
	v_dot8c_i32_i4_e32 v42, v134, v52
	v_dot8c_i32_i4_e32 v43, v134, v50
	v_dot8c_i32_i4_e32 v44, v136, v52
	v_dot8c_i32_i4_e32 v45, v136, v50
	v_dot8c_i32_i4_e32 v38, v131, v53
	v_dot8c_i32_i4_e32 v39, v131, v51
	v_dot8c_i32_i4_e32 v40, v133, v53
	v_dot8c_i32_i4_e32 v41, v133, v51
	v_dot8c_i32_i4_e32 v42, v135, v53
	v_dot8c_i32_i4_e32 v43, v135, v51
	v_dot8c_i32_i4_e32 v44, v137, v53
	v_dot8c_i32_i4_e32 v45, v137, v51
	v_and_b32_e32 v78, 0xffff, v27
	v_lshrrev_b32_e32 v79, 16, v27
	v_lshl_add_u32 v78, v78, 7, v150
	v_lshl_add_u32 v79, v79, 7, v151
	s_mov_b32 m0, s79
	s_add_i32 s43, s79, 0x400
	global_load_lds_dwordx4 v78, s[50:51]
	s_mov_b32 m0, s43
	s_nop 0
	global_load_lds_dwordx4 v79, s[50:51]
	s_waitcnt vmcnt(8)
	v_add_u32_e32 v54, s99, v59
	v_add_u32_e32 v55, s99, v60
	v_add_u32_e32 v56, s99, v61
	v_add_u32_e32 v57, s99, v62
	ds_read_b64_tr_b4 v[50:51], v160 offset:640
	ds_read_b64_tr_b4 v[52:53], v160 offset:1664
	ds_read_b64_tr_b4 v[130:131], v54
	ds_read_b64_tr_b4 v[132:133], v55
	ds_read_b64_tr_b4 v[134:135], v56
	ds_read_b64_tr_b4 v[136:137], v57
	s_waitcnt lgkmcnt(6)
	v_dot8c_i32_i4_e32 v38, v122, v48
	v_dot8c_i32_i4_e32 v39, v122, v46
	v_dot8c_i32_i4_e32 v40, v124, v48
	v_dot8c_i32_i4_e32 v41, v124, v46
	v_dot8c_i32_i4_e32 v42, v126, v48
	v_dot8c_i32_i4_e32 v43, v126, v46
	v_dot8c_i32_i4_e32 v44, v128, v48
	v_dot8c_i32_i4_e32 v45, v128, v46
	v_dot8c_i32_i4_e32 v38, v123, v49
	v_dot8c_i32_i4_e32 v39, v123, v47
	v_dot8c_i32_i4_e32 v40, v125, v49
	v_dot8c_i32_i4_e32 v41, v125, v47
	v_dot8c_i32_i4_e32 v42, v127, v49
	v_dot8c_i32_i4_e32 v43, v127, v47
	v_dot8c_i32_i4_e32 v44, v129, v49
	v_dot8c_i32_i4_e32 v45, v129, v47
	s_waitcnt lgkmcnt(15)
; __device__ __forceinline__ bf16 f2bf(float f) { return (bf16)f2bfu(f); }
; #define TR4(p_) __builtin_amdgcn_ds_read_tr4_b64_v2i32((LAS v2i*)(p_))
; #define VDMA(st_, k_) do { _Pragma("unroll") for (int i_ = 0; i_ < 4; ++i_) { \
;         const unsigned off_ = (unsigned)((st_) >> 2) * (16384u * 128u) + (PE_ID(E, 4 * ((st_) & 3) + i_) << 7) + ((i_ & 1) ? cx1 : cx0); \
;         __builtin_amdgcn_global_load_lds((const unsigned*)(V4 + off_), (LAS unsigned*)(ldsb + BUF[k_] + 1024 * i_), 16, 0, 0); } } while (0)
; __device__ __forceinline__ void peer_v_tokens(int j, const LAS unsigned short* EL, const LAS unsigned char* AL  , const LAS float* ASC  , const LAS int* SAL  , ...
;     ...
;         for (int st = 0; st < 16; ++st) {
;             const int p = st >> 2, q = st & 3;
;             if (st < 14) VDMA(st + 2, (st + 2) % 3);
;             if (st < 14) asm volatile("s_waitcnt vmcnt(8)" ::: "memory");
;             else if (st == 14) asm volatile("s_waitcnt vmcnt(4)" ::: "memory");
;             else asm volatile("s_waitcnt vmcnt(0)" ::: "memory");
;             if (q == 0) {
; #pragma unroll
;                 for (int r = 0; r < 4; ++r) { accH[r] = 0; accL[r] = 0; } }
; #pragma unroll
;             for (int tp = 0; tp < 2; ++tp) {
;                 const v2i ao = TR4(ATL + (2 * q + tp) * 128 + 8 * s16), ah = TR4(ATL + 1024 + (2 * q + tp) * 128 + 8 * s16);
; #pragma unroll
;                 for (int r = 0; r < 4; ++r) {
;                     const v2i d = TR4(ldsb + BUF[st % 3] + 2048 * tp + roff[r]);
;                     accH[r] = __builtin_amdgcn_sdot8(d.x, ah.x, accH[r], false); accH[r] = __builtin_amdgcn_sdot8(d.y, ah.y, accH[r], false);
;                     accL[r] = __builtin_amdgcn_sdot8(d.x, ao.x, accL[r], false); accL[r] = __builtin_amdgcn_sdot8(d.y, ao.y, accL[r], false);
;                 }
;             }
;             asm volatile("s_waitcnt lgkmcnt(0)" ::: "memory");
;             if (q == 3) {
; #pragma unroll
;                 for (int r = 0; r < 4; ++r) STASH[256 * p + 16 * (grp + 4 * r) + pc] = f2bf(asc * (float)(2 * ((accH[r] << 4) + accL[r]) + sa));
;             }
	v_add_u32_e32 v143, 8, v139
	v_and_b32_e32 v142, 15, v143
	v_xor_b32_e32 v142, 8, v142
	v_bfe_u32 v144, v143, 4, 4
	v_mul_lo_u32 v142, v142, s92
	v_mul_lo_u32 v144, v144, s92
	v_mov_b32_e32 v143, v142
	v_mov_b32_e32 v145, v144
	ds_write2st64_b64 v159, v[142:143], v[144:145] offset1:2
	v_and_b32_e32 v78, 0xffff, v28
	v_lshrrev_b32_e32 v79, 16, v28
	v_lshl_add_u32 v78, v78, 7, v150
	v_lshl_add_u32 v79, v79, 7, v151
	s_mov_b32 m0, s98
	s_add_i32 s43, s98, 0x400
	global_load_lds_dwordx4 v78, s[50:51]
	s_mov_b32 m0, s43
	s_nop 0
	global_load_lds_dwordx4 v79, s[50:51]
	s_waitcnt vmcnt(8)
	v_add_u32_e32 v54, s76, v59
	v_add_u32_e32 v55, s76, v60
	v_add_u32_e32 v56, s76, v61
	v_add_u32_e32 v57, s76, v62
	ds_read_b64_tr_b4 v[46:47], v160 offset:768
	ds_read_b64_tr_b4 v[48:49], v160 offset:1792
	ds_read_b64_tr_b4 v[122:123], v54
	ds_read_b64_tr_b4 v[124:125], v55
	ds_read_b64_tr_b4 v[126:127], v56
	ds_read_b64_tr_b4 v[128:129], v57
	s_waitcnt lgkmcnt(7)
	v_dot8c_i32_i4_e32 v38, v130, v52
	v_dot8c_i32_i4_e32 v39, v130, v50
	v_dot8c_i32_i4_e32 v40, v132, v52
	v_dot8c_i32_i4_e32 v41, v132, v50
	v_dot8c_i32_i4_e32 v42, v134, v52
	v_dot8c_i32_i4_e32 v43, v134, v50
	v_dot8c_i32_i4_e32 v44, v136, v52
	v_dot8c_i32_i4_e32 v45, v136, v50
	v_dot8c_i32_i4_e32 v38, v131, v53
	v_dot8c_i32_i4_e32 v39, v131, v51
	v_dot8c_i32_i4_e32 v40, v133, v53
	v_dot8c_i32_i4_e32 v41, v133, v51
	v_dot8c_i32_i4_e32 v42, v135, v53
	v_dot8c_i32_i4_e32 v43, v135, v51
	v_dot8c_i32_i4_e32 v44, v137, v53
	v_dot8c_i32_i4_e32 v45, v137, v51
	v_and_b32_e32 v78, 0xffff, v29
	v_lshrrev_b32_e32 v79, 16, v29
	v_lshl_add_u32 v78, v78, 7, v150
	v_lshl_add_u32 v79, v79, 7, v151
	s_mov_b32 m0, s99
	s_add_i32 s43, s99, 0x400
	global_load_lds_dwordx4 v78, s[50:51]
	s_mov_b32 m0, s43
	s_nop 0
	global_load_lds_dwordx4 v79, s[50:51]
	s_waitcnt vmcnt(8)
	v_add_u32_e32 v54, s77, v59
	v_add_u32_e32 v55, s77, v60
	v_add_u32_e32 v56, s77, v61
	v_add_u32_e32 v57, s77, v62
	ds_read_b64_tr_b4 v[50:51], v160 offset:896
	ds_read_b64_tr_b4 v[52:53], v160 offset:1920
	ds_read_b64_tr_b4 v[130:131], v54
	ds_read_b64_tr_b4 v[132:133], v55
	ds_read_b64_tr_b4 v[134:135], v56
	ds_read_b64_tr_b4 v[136:137], v57
	s_waitcnt lgkmcnt(6)
	v_dot8c_i32_i4_e32 v38, v122, v48
	v_dot8c_i32_i4_e32 v39, v122, v46
	v_dot8c_i32_i4_e32 v40, v124, v48
	v_dot8c_i32_i4_e32 v41, v124, v46
	v_dot8c_i32_i4_e32 v42, v126, v48
	v_dot8c_i32_i4_e32 v43, v126, v46
	v_dot8c_i32_i4_e32 v44, v128, v48
	v_dot8c_i32_i4_e32 v45, v128, v46
	v_dot8c_i32_i4_e32 v38, v123, v49
	v_dot8c_i32_i4_e32 v39, v123, v47
	v_dot8c_i32_i4_e32 v40, v125, v49
	v_dot8c_i32_i4_e32 v41, v125, v47
	v_dot8c_i32_i4_e32 v42, v127, v49
	v_dot8c_i32_i4_e32 v43, v127, v47
	v_dot8c_i32_i4_e32 v44, v129, v49
	v_dot8c_i32_i4_e32 v45, v129, v47
	v_and_b32_e32 v78, 0xffff, v30
	v_lshrrev_b32_e32 v79, 16, v30
	v_lshl_add_u32 v78, v78, 7, v150
	v_lshl_add_u32 v79, v79, 7, v151
	s_mov_b32 m0, s76
	s_add_i32 s43, s76, 0x400
	global_load_lds_dwordx4 v78, s[50:51]
	s_mov_b32 m0, s43
	s_nop 0
	global_load_lds_dwordx4 v79, s[50:51]
	s_waitcnt vmcnt(8)
	v_add_u32_e32 v54, s78, v59
	v_add_u32_e32 v55, s78, v60
	v_add_u32_e32 v56, s78, v61
	v_add_u32_e32 v57, s78, v62
	ds_read_b64_tr_b4 v[46:47], v160
	ds_read_b64_tr_b4 v[48:49], v160 offset:1024
	ds_read_b64_tr_b4 v[122:123], v54
	ds_read_b64_tr_b4 v[124:125], v55
	ds_read_b64_tr_b4 v[126:127], v56
	ds_read_b64_tr_b4 v[128:129], v57
	s_waitcnt lgkmcnt(6)
	v_dot8c_i32_i4_e32 v38, v130, v52
	v_dot8c_i32_i4_e32 v39, v130, v50
	v_dot8c_i32_i4_e32 v40, v132, v52
	v_dot8c_i32_i4_e32 v41, v132, v50
	v_dot8c_i32_i4_e32 v42, v134, v52
	v_dot8c_i32_i4_e32 v43, v134, v50
	v_dot8c_i32_i4_e32 v44, v136, v52
	v_dot8c_i32_i4_e32 v45, v136, v50
	v_dot8c_i32_i4_e32 v38, v131, v53
	v_dot8c_i32_i4_e32 v39, v131, v51
	v_dot8c_i32_i4_e32 v40, v133, v53
	v_dot8c_i32_i4_e32 v41, v133, v51
	v_dot8c_i32_i4_e32 v42, v135, v53
	v_dot8c_i32_i4_e32 v43, v135, v51
	v_dot8c_i32_i4_e32 v44, v137, v53
	v_dot8c_i32_i4_e32 v45, v137, v51
	s_nop 3
	s_waitcnt lgkmcnt(15)
	v_lshlrev_b32_e32 v38, 5, v38
	v_lshlrev_b32_e32 v39, 1, v39
	v_add3_u32 v38, v39, v229, v38
	v_cvt_f32_i32_e32 v38, v38
	v_mul_f32_e32 v38, v228, v38
	v_lshlrev_b32_e32 v40, 5, v40
	v_lshlrev_b32_e32 v41, 1, v41
	v_add3_u32 v40, v41, v229, v40
	v_cvt_f32_i32_e32 v40, v40
	v_mul_f32_e32 v40, v228, v40
	v_lshlrev_b32_e32 v42, 5, v42
	v_lshlrev_b32_e32 v43, 1, v43
	v_add3_u32 v42, v43, v229, v42
	v_cvt_f32_i32_e32 v42, v42
	v_mul_f32_e32 v42, v228, v42
	v_lshlrev_b32_e32 v44, 5, v44
	v_lshlrev_b32_e32 v45, 1, v45
	v_add3_u32 v44, v45, v229, v44
	v_cvt_f32_i32_e32 v44, v44
	v_mul_f32_e32 v44, v228, v44
	v_cvt_pk_bf16_f32 v162, v38, v40
	v_cvt_pk_bf16_f32 v163, v42, v44
	v_add_u32_e32 v147, 8, v140
	v_and_b32_e32 v146, 15, v147
	v_xor_b32_e32 v146, 8, v146
	v_bfe_u32 v148, v147, 4, 4
	v_mul_lo_u32 v146, v146, s92
	v_mul_lo_u32 v148, v148, s92
	v_mov_b32_e32 v147, v146
	v_mov_b32_e32 v149, v148
	ds_write2st64_b64 v77, v[146:147], v[148:149] offset1:2
	v_mov_b32_e32 v138, v74
	ds_read_u8 v139, v138
	v_mov_b32_e32 v141, v73
	ds_read_u8 v140, v141
	s_add_i32 s43, s67, 32
	v_mov_b32_e32 v138, s43
	ds_read2st64_b32 v[228:229], v138 offset1:1
	ds_read_b128 v[18:21], v227
	ds_read_b128 v[22:25], v227 offset:16
	v_add_u32_e32 v152, 0x200000, v63
	v_add_u32_e32 v153, 0x200000, v64
	v_mov_b32_e32 v38, 0
	v_mov_b32_e32 v39, 0
	v_mov_b32_e32 v40, 0
	v_mov_b32_e32 v41, 0
	v_mov_b32_e32 v42, 0
	v_mov_b32_e32 v43, 0
	v_mov_b32_e32 v44, 0
	v_mov_b32_e32 v45, 0
	v_and_b32_e32 v78, 0xffff, v31
	v_lshrrev_b32_e32 v79, 16, v31
	v_lshl_add_u32 v78, v78, 7, v150
	v_lshl_add_u32 v79, v79, 7, v151
	s_mov_b32 m0, s77
	s_add_i32 s43, s77, 0x400
	global_load_lds_dwordx4 v78, s[50:51]
	s_mov_b32 m0, s43
	s_nop 0
	global_load_lds_dwordx4 v79, s[50:51]
	s_waitcnt vmcnt(8)
; __device__ __forceinline__ bf16 f2bf(float f) { return (bf16)f2bfu(f); }
; #define TR4(p_) __builtin_amdgcn_ds_read_tr4_b64_v2i32((LAS v2i*)(p_))
; #define VDMA(st_, k_) do { _Pragma("unroll") for (int i_ = 0; i_ < 4; ++i_) { \
;         const unsigned off_ = (unsigned)((st_) >> 2) * (16384u * 128u) + (PE_ID(E, 4 * ((st_) & 3) + i_) << 7) + ((i_ & 1) ? cx1 : cx0); \
;         __builtin_amdgcn_global_load_lds((const unsigned*)(V4 + off_), (LAS unsigned*)(ldsb + BUF[k_] + 1024 * i_), 16, 0, 0); } } while (0)
; __device__ __forceinline__ void peer_v_tokens(int j, const LAS unsigned short* EL, const LAS unsigned char* AL  , const LAS float* ASC  , const LAS int* SAL  , ...
;     ...
;         for (int st = 0; st < 16; ++st) {
;             const int p = st >> 2, q = st & 3;
;             if (st < 14) VDMA(st + 2, (st + 2) % 3);
;             if (st < 14) asm volatile("s_waitcnt vmcnt(8)" ::: "memory");
;             else if (st == 14) asm volatile("s_waitcnt vmcnt(4)" ::: "memory");
;             else asm volatile("s_waitcnt vmcnt(0)" ::: "memory");
;             if (q == 0) {
; #pragma unroll
;                 for (int r = 0; r < 4; ++r) { accH[r] = 0; accL[r] = 0; } }
; #pragma unroll
;             for (int tp = 0; tp < 2; ++tp) {
;                 const v2i ao = TR4(ATL + (2 * q + tp) * 128 + 8 * s16), ah = TR4(ATL + 1024 + (2 * q + tp) * 128 + 8 * s16);
; #pragma unroll
;                 for (int r = 0; r < 4; ++r) {
;                     const v2i d = TR4(ldsb + BUF[st % 3] + 2048 * tp + roff[r]);
;                     accH[r] = __builtin_amdgcn_sdot8(d.x, ah.x, accH[r], false); accH[r] = __builtin_amdgcn_sdot8(d.y, ah.y, accH[r], false);
;                     accL[r] = __builtin_amdgcn_sdot8(d.x, ao.x, accL[r], false); accL[r] = __builtin_amdgcn_sdot8(d.y, ao.y, accL[r], false);
;                 }
;             }
;             asm volatile("s_waitcnt lgkmcnt(0)" ::: "memory");
;             if (q == 3) {
; #pragma unroll
;                 for (int r = 0; r < 4; ++r) STASH[256 * p + 16 * (grp + 4 * r) + pc] = f2bf(asc * (float)(2 * ((accH[r] << 4) + accL[r]) + sa));
;             }
	v_add_u32_e32 v54, s79, v59
	v_add_u32_e32 v55, s79, v60
	v_add_u32_e32 v56, s79, v61
	v_add_u32_e32 v57, s79, v62
	ds_read_b64_tr_b4 v[50:51], v160 offset:128
	ds_read_b64_tr_b4 v[52:53], v160 offset:1152
	ds_read_b64_tr_b4 v[130:131], v54
	ds_read_b64_tr_b4 v[132:133], v55
	ds_read_b64_tr_b4 v[134:135], v56
	ds_read_b64_tr_b4 v[136:137], v57
	s_waitcnt lgkmcnt(12)
	v_dot8c_i32_i4_e32 v38, v122, v48
	v_dot8c_i32_i4_e32 v39, v122, v46
	v_dot8c_i32_i4_e32 v40, v124, v48
	v_dot8c_i32_i4_e32 v41, v124, v46
	v_dot8c_i32_i4_e32 v42, v126, v48
	v_dot8c_i32_i4_e32 v43, v126, v46
	v_dot8c_i32_i4_e32 v44, v128, v48
	v_dot8c_i32_i4_e32 v45, v128, v46
	v_dot8c_i32_i4_e32 v38, v123, v49
	v_dot8c_i32_i4_e32 v39, v123, v47
	v_dot8c_i32_i4_e32 v40, v125, v49
	v_dot8c_i32_i4_e32 v41, v125, v47
	v_dot8c_i32_i4_e32 v42, v127, v49
	v_dot8c_i32_i4_e32 v43, v127, v47
	v_dot8c_i32_i4_e32 v44, v129, v49
	v_dot8c_i32_i4_e32 v45, v129, v47
	v_and_b32_e32 v78, 0xffff, v32
	v_lshrrev_b32_e32 v79, 16, v32
	v_lshl_add_u32 v78, v78, 7, v150
	v_lshl_add_u32 v79, v79, 7, v151
	s_mov_b32 m0, s78
	s_add_i32 s43, s78, 0x400
	global_load_lds_dwordx4 v78, s[50:51]
	s_mov_b32 m0, s43
	s_nop 0
	global_load_lds_dwordx4 v79, s[50:51]
	s_waitcnt vmcnt(8)
	v_add_u32_e32 v54, s98, v59
	v_add_u32_e32 v55, s98, v60
	v_add_u32_e32 v56, s98, v61
	v_add_u32_e32 v57, s98, v62
	ds_read_b64_tr_b4 v[46:47], v160 offset:256
	ds_read_b64_tr_b4 v[48:49], v160 offset:1280
	ds_read_b64_tr_b4 v[122:123], v54
	ds_read_b64_tr_b4 v[124:125], v55
	ds_read_b64_tr_b4 v[126:127], v56
	ds_read_b64_tr_b4 v[128:129], v57
	s_waitcnt lgkmcnt(6)
	v_dot8c_i32_i4_e32 v38, v130, v52
	v_dot8c_i32_i4_e32 v39, v130, v50
	v_dot8c_i32_i4_e32 v40, v132, v52
	v_dot8c_i32_i4_e32 v41, v132, v50
	v_dot8c_i32_i4_e32 v42, v134, v52
	v_dot8c_i32_i4_e32 v43, v134, v50
	v_dot8c_i32_i4_e32 v44, v136, v52
	v_dot8c_i32_i4_e32 v45, v136, v50
	v_dot8c_i32_i4_e32 v38, v131, v53
	v_dot8c_i32_i4_e32 v39, v131, v51
	v_dot8c_i32_i4_e32 v40, v133, v53
	v_dot8c_i32_i4_e32 v41, v133, v51
	v_dot8c_i32_i4_e32 v42, v135, v53
	v_dot8c_i32_i4_e32 v43, v135, v51
	v_dot8c_i32_i4_e32 v44, v137, v53
	v_dot8c_i32_i4_e32 v45, v137, v51
	v_and_b32_e32 v78, 0xffff, v33
	v_lshrrev_b32_e32 v79, 16, v33
	v_lshl_add_u32 v78, v78, 7, v150
	v_lshl_add_u32 v79, v79, 7, v151
	s_mov_b32 m0, s79
	s_add_i32 s43, s79, 0x400
	global_load_lds_dwordx4 v78, s[50:51]
	s_mov_b32 m0, s43
	s_nop 0
	global_load_lds_dwordx4 v79, s[50:51]
	s_waitcnt vmcnt(8)
	v_add_u32_e32 v54, s99, v59
	v_add_u32_e32 v55, s99, v60
	v_add_u32_e32 v56, s99, v61
	v_add_u32_e32 v57, s99, v62
	ds_read_b64_tr_b4 v[50:51], v160 offset:384
	ds_read_b64_tr_b4 v[52:53], v160 offset:1408
	ds_read_b64_tr_b4 v[130:131], v54
	ds_read_b64_tr_b4 v[132:133], v55
	ds_read_b64_tr_b4 v[134:135], v56
	ds_read_b64_tr_b4 v[136:137], v57
	s_waitcnt lgkmcnt(6)
	v_dot8c_i32_i4_e32 v38, v122, v48
	v_dot8c_i32_i4_e32 v39, v122, v46
	v_dot8c_i32_i4_e32 v40, v124, v48
	v_dot8c_i32_i4_e32 v41, v124, v46
	v_dot8c_i32_i4_e32 v42, v126, v48
	v_dot8c_i32_i4_e32 v43, v126, v46
	v_dot8c_i32_i4_e32 v44, v128, v48
	v_dot8c_i32_i4_e32 v45, v128, v46
	v_dot8c_i32_i4_e32 v38, v123, v49
	v_dot8c_i32_i4_e32 v39, v123, v47
	v_dot8c_i32_i4_e32 v40, v125, v49
	v_dot8c_i32_i4_e32 v41, v125, v47
	v_dot8c_i32_i4_e32 v42, v127, v49
	v_dot8c_i32_i4_e32 v43, v127, v47
	v_dot8c_i32_i4_e32 v44, v129, v49
	v_dot8c_i32_i4_e32 v45, v129, v47
	s_waitcnt lgkmcnt(15)
	v_and_b32_e32 v78, 0xffff, v18
	v_lshrrev_b32_e32 v79, 16, v18
	v_lshl_add_u32 v78, v78, 7, v152
	v_lshl_add_u32 v79, v79, 7, v153
	s_mov_b32 m0, s98
	s_add_i32 s43, s98, 0x400
	global_load_lds_dwordx4 v78, s[50:51]
	s_mov_b32 m0, s43
	s_nop 0
	global_load_lds_dwordx4 v79, s[50:51]
	s_waitcnt vmcnt(8)
	v_add_u32_e32 v54, s76, v59
	v_add_u32_e32 v55, s76, v60
	v_add_u32_e32 v56, s76, v61
	v_add_u32_e32 v57, s76, v62
	ds_read_b64_tr_b4 v[46:47], v160 offset:512
	ds_read_b64_tr_b4 v[48:49], v160 offset:1536
	ds_read_b64_tr_b4 v[122:123], v54
	ds_read_b64_tr_b4 v[124:125], v55
	ds_read_b64_tr_b4 v[126:127], v56
	ds_read_b64_tr_b4 v[128:129], v57
	s_waitcnt lgkmcnt(6)
	v_dot8c_i32_i4_e32 v38, v130, v52
	v_dot8c_i32_i4_e32 v39, v130, v50
	v_dot8c_i32_i4_e32 v40, v132, v52
	v_dot8c_i32_i4_e32 v41, v132, v50
	v_dot8c_i32_i4_e32 v42, v134, v52
	v_dot8c_i32_i4_e32 v43, v134, v50
	v_dot8c_i32_i4_e32 v44, v136, v52
	v_dot8c_i32_i4_e32 v45, v136, v50
	v_dot8c_i32_i4_e32 v38, v131, v53
	v_dot8c_i32_i4_e32 v39, v131, v51
	v_dot8c_i32_i4_e32 v40, v133, v53
	v_dot8c_i32_i4_e32 v41, v133, v51
	v_dot8c_i32_i4_e32 v42, v135, v53
	v_dot8c_i32_i4_e32 v43, v135, v51
	v_dot8c_i32_i4_e32 v44, v137, v53
	v_dot8c_i32_i4_e32 v45, v137, v51
	v_and_b32_e32 v78, 0xffff, v19
	v_lshrrev_b32_e32 v79, 16, v19
	v_lshl_add_u32 v78, v78, 7, v152
	v_lshl_add_u32 v79, v79, 7, v153
	s_mov_b32 m0, s99
	s_add_i32 s43, s99, 0x400
	global_load_lds_dwordx4 v78, s[50:51]
	s_mov_b32 m0, s43
	s_nop 0
	global_load_lds_dwordx4 v79, s[50:51]
	s_waitcnt vmcnt(8)
	v_add_u32_e32 v54, s77, v59
	v_add_u32_e32 v55, s77, v60
	v_add_u32_e32 v56, s77, v61
	v_add_u32_e32 v57, s77, v62
	ds_read_b64_tr_b4 v[50:51], v160 offset:640
	ds_read_b64_tr_b4 v[52:53], v160 offset:1664
	ds_read_b64_tr_b4 v[130:131], v54
	ds_read_b64_tr_b4 v[132:133], v55
	ds_read_b64_tr_b4 v[134:135], v56
	ds_read_b64_tr_b4 v[136:137], v57
	s_waitcnt lgkmcnt(6)
	v_dot8c_i32_i4_e32 v38, v122, v48
	v_dot8c_i32_i4_e32 v39, v122, v46
	v_dot8c_i32_i4_e32 v40, v124, v48
	v_dot8c_i32_i4_e32 v41, v124, v46
	v_dot8c_i32_i4_e32 v42, v126, v48
	v_dot8c_i32_i4_e32 v43, v126, v46
	v_dot8c_i32_i4_e32 v44, v128, v48
	v_dot8c_i32_i4_e32 v45, v128, v46
	v_dot8c_i32_i4_e32 v38, v123, v49
	v_dot8c_i32_i4_e32 v39, v123, v47
	v_dot8c_i32_i4_e32 v40, v125, v49
	v_dot8c_i32_i4_e32 v41, v125, v47
	v_dot8c_i32_i4_e32 v42, v127, v49
	v_dot8c_i32_i4_e32 v43, v127, v47
	v_dot8c_i32_i4_e32 v44, v129, v49
	v_dot8c_i32_i4_e32 v45, v129, v47
	s_waitcnt lgkmcnt(15)
; __device__ __forceinline__ bf16 f2bf(float f) { return (bf16)f2bfu(f); }
; #define TR4(p_) __builtin_amdgcn_ds_read_tr4_b64_v2i32((LAS v2i*)(p_))
; #define VDMA(st_, k_) do { _Pragma("unroll") for (int i_ = 0; i_ < 4; ++i_) { \
;         const unsigned off_ = (unsigned)((st_) >> 2) * (16384u * 128u) + (PE_ID(E, 4 * ((st_) & 3) + i_) << 7) + ((i_ & 1) ? cx1 : cx0); \
;         __builtin_amdgcn_global_load_lds((const unsigned*)(V4 + off_), (LAS unsigned*)(ldsb + BUF[k_] + 1024 * i_), 16, 0, 0); } } while (0)
; __device__ __forceinline__ void peer_v_tokens(int j, const LAS unsigned short* EL, const LAS unsigned char* AL  , const LAS float* ASC  , const LAS int* SAL  , ...
;     ...
;         for (int st = 0; st < 16; ++st) {
;             const int p = st >> 2, q = st & 3;
;             if (st < 14) VDMA(st + 2, (st + 2) % 3);
;             if (st < 14) asm volatile("s_waitcnt vmcnt(8)" ::: "memory");
;             else if (st == 14) asm volatile("s_waitcnt vmcnt(4)" ::: "memory");
;             else asm volatile("s_waitcnt vmcnt(0)" ::: "memory");
;             if (q == 0) {
; #pragma unroll
;                 for (int r = 0; r < 4; ++r) { accH[r] = 0; accL[r] = 0; } }
; #pragma unroll
;             for (int tp = 0; tp < 2; ++tp) {
;                 const v2i ao = TR4(ATL + (2 * q + tp) * 128 + 8 * s16), ah = TR4(ATL + 1024 + (2 * q + tp) * 128 + 8 * s16);
; #pragma unroll
;                 for (int r = 0; r < 4; ++r) {
;                     const v2i d = TR4(ldsb + BUF[st % 3] + 2048 * tp + roff[r]);
;                     accH[r] = __builtin_amdgcn_sdot8(d.x, ah.x, accH[r], false); accH[r] = __builtin_amdgcn_sdot8(d.y, ah.y, accH[r], false);
;                     accL[r] = __builtin_amdgcn_sdot8(d.x, ao.x, accL[r], false); accL[r] = __builtin_amdgcn_sdot8(d.y, ao.y, accL[r], false);
;                 }
;             }
;             asm volatile("s_waitcnt lgkmcnt(0)" ::: "memory");
;             if (q == 3) {
; #pragma unroll
;                 for (int r = 0; r < 4; ++r) STASH[256 * p + 16 * (grp + 4 * r) + pc] = f2bf(asc * (float)(2 * ((accH[r] << 4) + accL[r]) + sa));
;             }
	v_add_u32_e32 v143, 8, v139
	v_and_b32_e32 v142, 15, v143
	v_xor_b32_e32 v142, 8, v142
	v_bfe_u32 v144, v143, 4, 4
	v_mul_lo_u32 v142, v142, s92
	v_mul_lo_u32 v144, v144, s92
	v_mov_b32_e32 v143, v142
	v_mov_b32_e32 v145, v144
	ds_write2st64_b64 v159, v[142:143], v[144:145] offset1:2
	v_and_b32_e32 v78, 0xffff, v20
	v_lshrrev_b32_e32 v79, 16, v20
	v_lshl_add_u32 v78, v78, 7, v152
	v_lshl_add_u32 v79, v79, 7, v153
	s_mov_b32 m0, s76
	s_add_i32 s43, s76, 0x400
	global_load_lds_dwordx4 v78, s[50:51]
	s_mov_b32 m0, s43
	s_nop 0
	global_load_lds_dwordx4 v79, s[50:51]
	s_waitcnt vmcnt(8)
	v_add_u32_e32 v54, s78, v59
	v_add_u32_e32 v55, s78, v60
	v_add_u32_e32 v56, s78, v61
	v_add_u32_e32 v57, s78, v62
	ds_read_b64_tr_b4 v[46:47], v160 offset:768
	ds_read_b64_tr_b4 v[48:49], v160 offset:1792
	ds_read_b64_tr_b4 v[122:123], v54
	ds_read_b64_tr_b4 v[124:125], v55
	ds_read_b64_tr_b4 v[126:127], v56
	ds_read_b64_tr_b4 v[128:129], v57
	s_waitcnt lgkmcnt(7)
	v_dot8c_i32_i4_e32 v38, v130, v52
	v_dot8c_i32_i4_e32 v39, v130, v50
	v_dot8c_i32_i4_e32 v40, v132, v52
	v_dot8c_i32_i4_e32 v41, v132, v50
	v_dot8c_i32_i4_e32 v42, v134, v52
	v_dot8c_i32_i4_e32 v43, v134, v50
	v_dot8c_i32_i4_e32 v44, v136, v52
	v_dot8c_i32_i4_e32 v45, v136, v50
	v_dot8c_i32_i4_e32 v38, v131, v53
	v_dot8c_i32_i4_e32 v39, v131, v51
	v_dot8c_i32_i4_e32 v40, v133, v53
	v_dot8c_i32_i4_e32 v41, v133, v51
	v_dot8c_i32_i4_e32 v42, v135, v53
	v_dot8c_i32_i4_e32 v43, v135, v51
	v_dot8c_i32_i4_e32 v44, v137, v53
	v_dot8c_i32_i4_e32 v45, v137, v51
	v_and_b32_e32 v78, 0xffff, v21
	v_lshrrev_b32_e32 v79, 16, v21
	v_lshl_add_u32 v78, v78, 7, v152
	v_lshl_add_u32 v79, v79, 7, v153
	s_mov_b32 m0, s77
	s_add_i32 s43, s77, 0x400
	global_load_lds_dwordx4 v78, s[50:51]
	s_mov_b32 m0, s43
	s_nop 0
	global_load_lds_dwordx4 v79, s[50:51]
	s_waitcnt vmcnt(8)
	v_add_u32_e32 v54, s79, v59
	v_add_u32_e32 v55, s79, v60
	v_add_u32_e32 v56, s79, v61
	v_add_u32_e32 v57, s79, v62
	ds_read_b64_tr_b4 v[50:51], v160 offset:896
	ds_read_b64_tr_b4 v[52:53], v160 offset:1920
	ds_read_b64_tr_b4 v[130:131], v54
	ds_read_b64_tr_b4 v[132:133], v55
	ds_read_b64_tr_b4 v[134:135], v56
	ds_read_b64_tr_b4 v[136:137], v57
	s_waitcnt lgkmcnt(6)
	v_dot8c_i32_i4_e32 v38, v122, v48
	v_dot8c_i32_i4_e32 v39, v122, v46
	v_dot8c_i32_i4_e32 v40, v124, v48
	v_dot8c_i32_i4_e32 v41, v124, v46
	v_dot8c_i32_i4_e32 v42, v126, v48
	v_dot8c_i32_i4_e32 v43, v126, v46
	v_dot8c_i32_i4_e32 v44, v128, v48
	v_dot8c_i32_i4_e32 v45, v128, v46
	v_dot8c_i32_i4_e32 v38, v123, v49
	v_dot8c_i32_i4_e32 v39, v123, v47
	v_dot8c_i32_i4_e32 v40, v125, v49
	v_dot8c_i32_i4_e32 v41, v125, v47
	v_dot8c_i32_i4_e32 v42, v127, v49
	v_dot8c_i32_i4_e32 v43, v127, v47
	v_dot8c_i32_i4_e32 v44, v129, v49
	v_dot8c_i32_i4_e32 v45, v129, v47
	v_and_b32_e32 v78, 0xffff, v22
	v_lshrrev_b32_e32 v79, 16, v22
	v_lshl_add_u32 v78, v78, 7, v152
	v_lshl_add_u32 v79, v79, 7, v153
	s_mov_b32 m0, s78
	s_add_i32 s43, s78, 0x400
	global_load_lds_dwordx4 v78, s[50:51]
	s_mov_b32 m0, s43
	s_nop 0
	global_load_lds_dwordx4 v79, s[50:51]
	s_waitcnt vmcnt(8)
	v_add_u32_e32 v54, s98, v59
	v_add_u32_e32 v55, s98, v60
	v_add_u32_e32 v56, s98, v61
	v_add_u32_e32 v57, s98, v62
	ds_read_b64_tr_b4 v[46:47], v160
	ds_read_b64_tr_b4 v[48:49], v160 offset:1024
	ds_read_b64_tr_b4 v[122:123], v54
	ds_read_b64_tr_b4 v[124:125], v55
	ds_read_b64_tr_b4 v[126:127], v56
	ds_read_b64_tr_b4 v[128:129], v57
	s_waitcnt lgkmcnt(6)
	v_dot8c_i32_i4_e32 v38, v130, v52
	v_dot8c_i32_i4_e32 v39, v130, v50
	v_dot8c_i32_i4_e32 v40, v132, v52
	v_dot8c_i32_i4_e32 v41, v132, v50
	v_dot8c_i32_i4_e32 v42, v134, v52
	v_dot8c_i32_i4_e32 v43, v134, v50
	v_dot8c_i32_i4_e32 v44, v136, v52
	v_dot8c_i32_i4_e32 v45, v136, v50
	v_dot8c_i32_i4_e32 v38, v131, v53
	v_dot8c_i32_i4_e32 v39, v131, v51
	v_dot8c_i32_i4_e32 v40, v133, v53
	v_dot8c_i32_i4_e32 v41, v133, v51
	v_dot8c_i32_i4_e32 v42, v135, v53
	v_dot8c_i32_i4_e32 v43, v135, v51
	v_dot8c_i32_i4_e32 v44, v137, v53
	v_dot8c_i32_i4_e32 v45, v137, v51
	s_nop 3
	s_waitcnt lgkmcnt(15)
	v_lshlrev_b32_e32 v38, 5, v38
	v_lshlrev_b32_e32 v39, 1, v39
	v_add3_u32 v38, v39, v229, v38
	v_cvt_f32_i32_e32 v38, v38
	v_mul_f32_e32 v38, v228, v38
	v_lshlrev_b32_e32 v40, 5, v40
	v_lshlrev_b32_e32 v41, 1, v41
	v_add3_u32 v40, v41, v229, v40
	v_cvt_f32_i32_e32 v40, v40
	v_mul_f32_e32 v40, v228, v40
	v_lshlrev_b32_e32 v42, 5, v42
	v_lshlrev_b32_e32 v43, 1, v43
	v_add3_u32 v42, v43, v229, v42
	v_cvt_f32_i32_e32 v42, v42
	v_mul_f32_e32 v42, v228, v42
	v_lshlrev_b32_e32 v44, 5, v44
	v_lshlrev_b32_e32 v45, 1, v45
	v_add3_u32 v44, v45, v229, v44
	v_cvt_f32_i32_e32 v44, v44
	v_mul_f32_e32 v44, v228, v44
	v_cvt_pk_bf16_f32 v170, v38, v40
	v_cvt_pk_bf16_f32 v171, v42, v44
	v_add_u32_e32 v147, 8, v140
	v_and_b32_e32 v146, 15, v147
	v_xor_b32_e32 v146, 8, v146
	v_bfe_u32 v148, v147, 4, 4
	v_mul_lo_u32 v146, v146, s92
	v_mul_lo_u32 v148, v148, s92
	v_mov_b32_e32 v147, v146
	v_mov_b32_e32 v149, v148
	ds_write2st64_b64 v77, v[146:147], v[148:149] offset1:2
	v_add_u32_e32 v138, 0x400, v74
	ds_read_u8 v139, v138
	v_add_u32_e32 v141, 0x400, v73
	ds_read_u8 v140, v141
	s_mov_b32 s43, s67
	v_mov_b32_e32 v138, s43
	ds_read2st64_b32 v[228:229], v138 offset1:1
	ds_read_b128 v[26:29], v227 offset:2048
	ds_read_b128 v[30:33], v227 offset:2064
	v_mov_b32_e32 v38, 0
	v_mov_b32_e32 v39, 0
	v_mov_b32_e32 v40, 0
	v_mov_b32_e32 v41, 0
	v_mov_b32_e32 v42, 0
	v_mov_b32_e32 v43, 0
	v_mov_b32_e32 v44, 0
	v_mov_b32_e32 v45, 0
	v_and_b32_e32 v78, 0xffff, v23
	v_lshrrev_b32_e32 v79, 16, v23
	v_lshl_add_u32 v78, v78, 7, v152
	v_lshl_add_u32 v79, v79, 7, v153
	s_mov_b32 m0, s79
	s_add_i32 s43, s79, 0x400
	global_load_lds_dwordx4 v78, s[50:51]
	s_mov_b32 m0, s43
	s_nop 0
	global_load_lds_dwordx4 v79, s[50:51]
	s_waitcnt vmcnt(8)
; __device__ __forceinline__ bf16 f2bf(float f) { return (bf16)f2bfu(f); }
; #define TR4(p_) __builtin_amdgcn_ds_read_tr4_b64_v2i32((LAS v2i*)(p_))
; #define VDMA(st_, k_) do { _Pragma("unroll") for (int i_ = 0; i_ < 4; ++i_) { \
;         const unsigned off_ = (unsigned)((st_) >> 2) * (16384u * 128u) + (PE_ID(E, 4 * ((st_) & 3) + i_) << 7) + ((i_ & 1) ? cx1 : cx0); \
;         __builtin_amdgcn_global_load_lds((const unsigned*)(V4 + off_), (LAS unsigned*)(ldsb + BUF[k_] + 1024 * i_), 16, 0, 0); } } while (0)
; __device__ __forceinline__ void peer_v_tokens(int j, const LAS unsigned short* EL, const LAS unsigned char* AL  , const LAS float* ASC  , const LAS int* SAL  , ...
;     ...
;         for (int st = 0; st < 16; ++st) {
;             const int p = st >> 2, q = st & 3;
;             if (st < 14) VDMA(st + 2, (st + 2) % 3);
;             if (st < 14) asm volatile("s_waitcnt vmcnt(8)" ::: "memory");
;             else if (st == 14) asm volatile("s_waitcnt vmcnt(4)" ::: "memory");
;             else asm volatile("s_waitcnt vmcnt(0)" ::: "memory");
;             if (q == 0) {
; #pragma unroll
;                 for (int r = 0; r < 4; ++r) { accH[r] = 0; accL[r] = 0; } }
; #pragma unroll
;             for (int tp = 0; tp < 2; ++tp) {
;                 const v2i ao = TR4(ATL + (2 * q + tp) * 128 + 8 * s16), ah = TR4(ATL + 1024 + (2 * q + tp) * 128 + 8 * s16);
; #pragma unroll
;                 for (int r = 0; r < 4; ++r) {
;                     const v2i d = TR4(ldsb + BUF[st % 3] + 2048 * tp + roff[r]);
;                     accH[r] = __builtin_amdgcn_sdot8(d.x, ah.x, accH[r], false); accH[r] = __builtin_amdgcn_sdot8(d.y, ah.y, accH[r], false);
;                     accL[r] = __builtin_amdgcn_sdot8(d.x, ao.x, accL[r], false); accL[r] = __builtin_amdgcn_sdot8(d.y, ao.y, accL[r], false);
;                 }
;             }
;             asm volatile("s_waitcnt lgkmcnt(0)" ::: "memory");
;             if (q == 3) {
; #pragma unroll
;                 for (int r = 0; r < 4; ++r) STASH[256 * p + 16 * (grp + 4 * r) + pc] = f2bf(asc * (float)(2 * ((accH[r] << 4) + accL[r]) + sa));
;             }
	v_add_u32_e32 v54, s99, v59
	v_add_u32_e32 v55, s99, v60
	v_add_u32_e32 v56, s99, v61
	v_add_u32_e32 v57, s99, v62
	ds_read_b64_tr_b4 v[50:51], v160 offset:128
	ds_read_b64_tr_b4 v[52:53], v160 offset:1152
	ds_read_b64_tr_b4 v[130:131], v54
	ds_read_b64_tr_b4 v[132:133], v55
	ds_read_b64_tr_b4 v[134:135], v56
	ds_read_b64_tr_b4 v[136:137], v57
	s_waitcnt lgkmcnt(12)
	v_dot8c_i32_i4_e32 v38, v122, v48
	v_dot8c_i32_i4_e32 v39, v122, v46
	v_dot8c_i32_i4_e32 v40, v124, v48
	v_dot8c_i32_i4_e32 v41, v124, v46
	v_dot8c_i32_i4_e32 v42, v126, v48
	v_dot8c_i32_i4_e32 v43, v126, v46
	v_dot8c_i32_i4_e32 v44, v128, v48
	v_dot8c_i32_i4_e32 v45, v128, v46
	v_dot8c_i32_i4_e32 v38, v123, v49
	v_dot8c_i32_i4_e32 v39, v123, v47
	v_dot8c_i32_i4_e32 v40, v125, v49
	v_dot8c_i32_i4_e32 v41, v125, v47
	v_dot8c_i32_i4_e32 v42, v127, v49
	v_dot8c_i32_i4_e32 v43, v127, v47
	v_dot8c_i32_i4_e32 v44, v129, v49
	v_dot8c_i32_i4_e32 v45, v129, v47
	v_and_b32_e32 v78, 0xffff, v24
	v_lshrrev_b32_e32 v79, 16, v24
	v_lshl_add_u32 v78, v78, 7, v152
	v_lshl_add_u32 v79, v79, 7, v153
	s_mov_b32 m0, s98
	s_add_i32 s43, s98, 0x400
	global_load_lds_dwordx4 v78, s[50:51]
	s_mov_b32 m0, s43
	s_nop 0
	global_load_lds_dwordx4 v79, s[50:51]
	s_waitcnt vmcnt(8)
	v_add_u32_e32 v54, s76, v59
	v_add_u32_e32 v55, s76, v60
	v_add_u32_e32 v56, s76, v61
	v_add_u32_e32 v57, s76, v62
	ds_read_b64_tr_b4 v[46:47], v160 offset:256
	ds_read_b64_tr_b4 v[48:49], v160 offset:1280
	ds_read_b64_tr_b4 v[122:123], v54
	ds_read_b64_tr_b4 v[124:125], v55
	ds_read_b64_tr_b4 v[126:127], v56
	ds_read_b64_tr_b4 v[128:129], v57
	s_waitcnt lgkmcnt(6)
	v_dot8c_i32_i4_e32 v38, v130, v52
	v_dot8c_i32_i4_e32 v39, v130, v50
	v_dot8c_i32_i4_e32 v40, v132, v52
	v_dot8c_i32_i4_e32 v41, v132, v50
	v_dot8c_i32_i4_e32 v42, v134, v52
	v_dot8c_i32_i4_e32 v43, v134, v50
	v_dot8c_i32_i4_e32 v44, v136, v52
	v_dot8c_i32_i4_e32 v45, v136, v50
	v_dot8c_i32_i4_e32 v38, v131, v53
	v_dot8c_i32_i4_e32 v39, v131, v51
	v_dot8c_i32_i4_e32 v40, v133, v53
	v_dot8c_i32_i4_e32 v41, v133, v51
	v_dot8c_i32_i4_e32 v42, v135, v53
	v_dot8c_i32_i4_e32 v43, v135, v51
	v_dot8c_i32_i4_e32 v44, v137, v53
	v_dot8c_i32_i4_e32 v45, v137, v51
	v_and_b32_e32 v78, 0xffff, v25
	v_lshrrev_b32_e32 v79, 16, v25
	v_lshl_add_u32 v78, v78, 7, v152
	v_lshl_add_u32 v79, v79, 7, v153
	s_mov_b32 m0, s99
	s_add_i32 s43, s99, 0x400
	global_load_lds_dwordx4 v78, s[50:51]
	s_mov_b32 m0, s43
	s_nop 0
	global_load_lds_dwordx4 v79, s[50:51]
	s_waitcnt vmcnt(8)
	v_add_u32_e32 v54, s77, v59
	v_add_u32_e32 v55, s77, v60
	v_add_u32_e32 v56, s77, v61
	v_add_u32_e32 v57, s77, v62
	ds_read_b64_tr_b4 v[50:51], v160 offset:384
	ds_read_b64_tr_b4 v[52:53], v160 offset:1408
	ds_read_b64_tr_b4 v[130:131], v54
	ds_read_b64_tr_b4 v[132:133], v55
	ds_read_b64_tr_b4 v[134:135], v56
	ds_read_b64_tr_b4 v[136:137], v57
	s_waitcnt lgkmcnt(6)
	v_dot8c_i32_i4_e32 v38, v122, v48
	v_dot8c_i32_i4_e32 v39, v122, v46
	v_dot8c_i32_i4_e32 v40, v124, v48
	v_dot8c_i32_i4_e32 v41, v124, v46
	v_dot8c_i32_i4_e32 v42, v126, v48
	v_dot8c_i32_i4_e32 v43, v126, v46
	v_dot8c_i32_i4_e32 v44, v128, v48
	v_dot8c_i32_i4_e32 v45, v128, v46
	v_dot8c_i32_i4_e32 v38, v123, v49
	v_dot8c_i32_i4_e32 v39, v123, v47
	v_dot8c_i32_i4_e32 v40, v125, v49
	v_dot8c_i32_i4_e32 v41, v125, v47
	v_dot8c_i32_i4_e32 v42, v127, v49
	v_dot8c_i32_i4_e32 v43, v127, v47
	v_dot8c_i32_i4_e32 v44, v129, v49
	v_dot8c_i32_i4_e32 v45, v129, v47
	s_waitcnt lgkmcnt(15)
	v_and_b32_e32 v78, 0xffff, v26
	v_lshrrev_b32_e32 v79, 16, v26
	v_lshl_add_u32 v78, v78, 7, v152
	v_lshl_add_u32 v79, v79, 7, v153
	s_mov_b32 m0, s76
	s_add_i32 s43, s76, 0x400
	global_load_lds_dwordx4 v78, s[50:51]
	s_mov_b32 m0, s43
	s_nop 0
	global_load_lds_dwordx4 v79, s[50:51]
	s_waitcnt vmcnt(8)
	v_add_u32_e32 v54, s78, v59
	v_add_u32_e32 v55, s78, v60
	v_add_u32_e32 v56, s78, v61
	v_add_u32_e32 v57, s78, v62
	ds_read_b64_tr_b4 v[46:47], v160 offset:512
	ds_read_b64_tr_b4 v[48:49], v160 offset:1536
	ds_read_b64_tr_b4 v[122:123], v54
	ds_read_b64_tr_b4 v[124:125], v55
	ds_read_b64_tr_b4 v[126:127], v56
	ds_read_b64_tr_b4 v[128:129], v57
	s_waitcnt lgkmcnt(6)
	v_dot8c_i32_i4_e32 v38, v130, v52
	v_dot8c_i32_i4_e32 v39, v130, v50
	v_dot8c_i32_i4_e32 v40, v132, v52
	v_dot8c_i32_i4_e32 v41, v132, v50
	v_dot8c_i32_i4_e32 v42, v134, v52
	v_dot8c_i32_i4_e32 v43, v134, v50
	v_dot8c_i32_i4_e32 v44, v136, v52
	v_dot8c_i32_i4_e32 v45, v136, v50
	v_dot8c_i32_i4_e32 v38, v131, v53
	v_dot8c_i32_i4_e32 v39, v131, v51
	v_dot8c_i32_i4_e32 v40, v133, v53
	v_dot8c_i32_i4_e32 v41, v133, v51
	v_dot8c_i32_i4_e32 v42, v135, v53
	v_dot8c_i32_i4_e32 v43, v135, v51
	v_dot8c_i32_i4_e32 v44, v137, v53
	v_dot8c_i32_i4_e32 v45, v137, v51
	v_and_b32_e32 v78, 0xffff, v27
	v_lshrrev_b32_e32 v79, 16, v27
	v_lshl_add_u32 v78, v78, 7, v152
	v_lshl_add_u32 v79, v79, 7, v153
	s_mov_b32 m0, s77
	s_add_i32 s43, s77, 0x400
	global_load_lds_dwordx4 v78, s[50:51]
	s_mov_b32 m0, s43
	s_nop 0
	global_load_lds_dwordx4 v79, s[50:51]
	s_waitcnt vmcnt(8)
	v_add_u32_e32 v54, s79, v59
	v_add_u32_e32 v55, s79, v60
	v_add_u32_e32 v56, s79, v61
	v_add_u32_e32 v57, s79, v62
	ds_read_b64_tr_b4 v[50:51], v160 offset:640
	ds_read_b64_tr_b4 v[52:53], v160 offset:1664
	ds_read_b64_tr_b4 v[130:131], v54
	ds_read_b64_tr_b4 v[132:133], v55
	ds_read_b64_tr_b4 v[134:135], v56
	ds_read_b64_tr_b4 v[136:137], v57
	s_waitcnt lgkmcnt(6)
	v_dot8c_i32_i4_e32 v38, v122, v48
	v_dot8c_i32_i4_e32 v39, v122, v46
	v_dot8c_i32_i4_e32 v40, v124, v48
	v_dot8c_i32_i4_e32 v41, v124, v46
	v_dot8c_i32_i4_e32 v42, v126, v48
	v_dot8c_i32_i4_e32 v43, v126, v46
	v_dot8c_i32_i4_e32 v44, v128, v48
	v_dot8c_i32_i4_e32 v45, v128, v46
	v_dot8c_i32_i4_e32 v38, v123, v49
	v_dot8c_i32_i4_e32 v39, v123, v47
	v_dot8c_i32_i4_e32 v40, v125, v49
	v_dot8c_i32_i4_e32 v41, v125, v47
	v_dot8c_i32_i4_e32 v42, v127, v49
	v_dot8c_i32_i4_e32 v43, v127, v47
	v_dot8c_i32_i4_e32 v44, v129, v49
	v_dot8c_i32_i4_e32 v45, v129, v47
	s_waitcnt lgkmcnt(15)
; __device__ __forceinline__ void peer_v_tokens(int j, const LAS unsigned short* EL, const LAS unsigned char* AL  , const LAS float* ASC  , const LAS int* SAL  , ...
;     ...
;         for (int m = 0; m < 2; ++m) {
;             const int idx = lane + 64 * m, tau = idx >> 4, sr = idx & 15, k = 16 * (sr & 7) + 2 * tau + (sr >> 3);
;             const int aq = (int)*(const LAS signed char*)(AL + tl * 128 + k); const int tq = aq + 8;
;             const unsigned lo = (((unsigned)tq & 15u) ^ 8u) * 0x11111111u, hi = ((unsigned)(tq >> 4) & 15u) * 0x11111111u;
;             typedef unsigned u2v __attribute__((ext_vector_type(2)));
;             u2v l2; l2.x = lo; l2.y = lo; u2v h2; h2.x = hi; h2.y = hi;
;             *(LAS u2v*)(ATL + 8 * idx) = l2; *(LAS u2v*)(ATL + 1024 + 8 * idx) = h2;
;         }
;         const float asc = ASC[tl]; const int sa = SAL[tl];
;         CFENCE();
;         int accH[4], accL[4];
; #pragma unroll
;         for (int st = 0; st < 16; ++st) {
;             const int p = st >> 2, q = st & 3;
;             if (st < 14) VDMA(st + 2, (st + 2) % 3);
;             if (st < 14) asm volatile("s_waitcnt vmcnt(8)" ::: "memory");
;             else if (st == 14) asm volatile("s_waitcnt vmcnt(4)" ::: "memory");
;             else asm volatile("s_waitcnt vmcnt(0)" ::: "memory");
;             if (q == 0) {
; #pragma unroll
;                 for (int r = 0; r < 4; ++r) { accH[r] = 0; accL[r] = 0; } }
; #pragma unroll
;             for (int tp = 0; tp < 2; ++tp) {
;                 const v2i ao = TR4(ATL + (2 * q + tp) * 128 + 8 * s16), ah = TR4(ATL + 1024 + (2 * q + tp) * 128 + 8 * s16);
; #pragma unroll
;                 for (int r = 0; r < 4; ++r) {
;                     const v2i d = TR4(ldsb + BUF[st % 3] + 2048 * tp + roff[r]);
;                     accH[r] = __builtin_amdgcn_sdot8(d.x, ah.x, accH[r], false); accH[r] = __builtin_amdgcn_sdot8(d.y, ah.y, accH[r], false);
;                     accL[r] = __builtin_amdgcn_sdot8(d.x, ao.x, accL[r], false); accL[r] = __builtin_amdgcn_sdot8(d.y, ao.y, accL[r], false);
;                 }
;             }
;             asm volatile("s_waitcnt lgkmcnt(0)" ::: "memory");
;             if (q == 3) {
; #pragma unroll
;                 for (int r = 0; r < 4; ++r) STASH[256 * p + 16 * (grp + 4 * r) + pc] = f2bf(asc * (float)(2 * ((accH[r] << 4) + accL[r]) + sa));
;             }
	v_add_u32_e32 v143, 8, v139
	v_and_b32_e32 v142, 15, v143
	v_xor_b32_e32 v142, 8, v142
	v_bfe_u32 v144, v143, 4, 4
	v_mul_lo_u32 v142, v142, s92
	v_mul_lo_u32 v144, v144, s92
	v_mov_b32_e32 v143, v142
	v_mov_b32_e32 v145, v144
	ds_write2st64_b64 v159, v[142:143], v[144:145] offset1:2
	v_and_b32_e32 v78, 0xffff, v28
	v_lshrrev_b32_e32 v79, 16, v28
	v_lshl_add_u32 v78, v78, 7, v152
	v_lshl_add_u32 v79, v79, 7, v153
	s_mov_b32 m0, s78
	s_add_i32 s43, s78, 0x400
	global_load_lds_dwordx4 v78, s[50:51]
	s_mov_b32 m0, s43
	s_nop 0
	global_load_lds_dwordx4 v79, s[50:51]
	s_waitcnt vmcnt(8)
	v_add_u32_e32 v54, s98, v59
	v_add_u32_e32 v55, s98, v60
	v_add_u32_e32 v56, s98, v61
	v_add_u32_e32 v57, s98, v62
	ds_read_b64_tr_b4 v[46:47], v160 offset:768
	ds_read_b64_tr_b4 v[48:49], v160 offset:1792
	ds_read_b64_tr_b4 v[122:123], v54
	ds_read_b64_tr_b4 v[124:125], v55
	ds_read_b64_tr_b4 v[126:127], v56
	ds_read_b64_tr_b4 v[128:129], v57
	s_waitcnt lgkmcnt(7)
	v_dot8c_i32_i4_e32 v38, v130, v52
	v_dot8c_i32_i4_e32 v39, v130, v50
	v_dot8c_i32_i4_e32 v40, v132, v52
	v_dot8c_i32_i4_e32 v41, v132, v50
	v_dot8c_i32_i4_e32 v42, v134, v52
	v_dot8c_i32_i4_e32 v43, v134, v50
	v_dot8c_i32_i4_e32 v44, v136, v52
	v_dot8c_i32_i4_e32 v45, v136, v50
	v_dot8c_i32_i4_e32 v38, v131, v53
	v_dot8c_i32_i4_e32 v39, v131, v51
	v_dot8c_i32_i4_e32 v40, v133, v53
	v_dot8c_i32_i4_e32 v41, v133, v51
	v_dot8c_i32_i4_e32 v42, v135, v53
	v_dot8c_i32_i4_e32 v43, v135, v51
	v_dot8c_i32_i4_e32 v44, v137, v53
	v_dot8c_i32_i4_e32 v45, v137, v51
	v_and_b32_e32 v78, 0xffff, v29
	v_lshrrev_b32_e32 v79, 16, v29
	v_lshl_add_u32 v78, v78, 7, v152
	v_lshl_add_u32 v79, v79, 7, v153
	s_mov_b32 m0, s79
	s_add_i32 s43, s79, 0x400
	global_load_lds_dwordx4 v78, s[50:51]
	s_mov_b32 m0, s43
	s_nop 0
	global_load_lds_dwordx4 v79, s[50:51]
	s_waitcnt vmcnt(8)
	v_add_u32_e32 v54, s99, v59
	v_add_u32_e32 v55, s99, v60
	v_add_u32_e32 v56, s99, v61
	v_add_u32_e32 v57, s99, v62
	ds_read_b64_tr_b4 v[50:51], v160 offset:896
	ds_read_b64_tr_b4 v[52:53], v160 offset:1920
	ds_read_b64_tr_b4 v[130:131], v54
	ds_read_b64_tr_b4 v[132:133], v55
	ds_read_b64_tr_b4 v[134:135], v56
	ds_read_b64_tr_b4 v[136:137], v57
	s_waitcnt lgkmcnt(6)
	v_dot8c_i32_i4_e32 v38, v122, v48
	v_dot8c_i32_i4_e32 v39, v122, v46
	v_dot8c_i32_i4_e32 v40, v124, v48
	v_dot8c_i32_i4_e32 v41, v124, v46
	v_dot8c_i32_i4_e32 v42, v126, v48
	v_dot8c_i32_i4_e32 v43, v126, v46
	v_dot8c_i32_i4_e32 v44, v128, v48
	v_dot8c_i32_i4_e32 v45, v128, v46
	v_dot8c_i32_i4_e32 v38, v123, v49
	v_dot8c_i32_i4_e32 v39, v123, v47
	v_dot8c_i32_i4_e32 v40, v125, v49
	v_dot8c_i32_i4_e32 v41, v125, v47
	v_dot8c_i32_i4_e32 v42, v127, v49
	v_dot8c_i32_i4_e32 v43, v127, v47
	v_dot8c_i32_i4_e32 v44, v129, v49
	v_dot8c_i32_i4_e32 v45, v129, v47
	v_and_b32_e32 v78, 0xffff, v30
	v_lshrrev_b32_e32 v79, 16, v30
	v_lshl_add_u32 v78, v78, 7, v152
	v_lshl_add_u32 v79, v79, 7, v153
	s_mov_b32 m0, s98
	s_add_i32 s43, s98, 0x400
	global_load_lds_dwordx4 v78, s[50:51]
	s_mov_b32 m0, s43
	s_nop 0
	global_load_lds_dwordx4 v79, s[50:51]
	s_waitcnt vmcnt(8)
	v_add_u32_e32 v54, s76, v59
	v_add_u32_e32 v55, s76, v60
	v_add_u32_e32 v56, s76, v61
	v_add_u32_e32 v57, s76, v62
	ds_read_b64_tr_b4 v[46:47], v160
	ds_read_b64_tr_b4 v[48:49], v160 offset:1024
	ds_read_b64_tr_b4 v[122:123], v54
	ds_read_b64_tr_b4 v[124:125], v55
	ds_read_b64_tr_b4 v[126:127], v56
	ds_read_b64_tr_b4 v[128:129], v57
	s_waitcnt lgkmcnt(6)
	v_dot8c_i32_i4_e32 v38, v130, v52
	v_dot8c_i32_i4_e32 v39, v130, v50
	v_dot8c_i32_i4_e32 v40, v132, v52
	v_dot8c_i32_i4_e32 v41, v132, v50
	v_dot8c_i32_i4_e32 v42, v134, v52
	v_dot8c_i32_i4_e32 v43, v134, v50
	v_dot8c_i32_i4_e32 v44, v136, v52
	v_dot8c_i32_i4_e32 v45, v136, v50
	v_dot8c_i32_i4_e32 v38, v131, v53
	v_dot8c_i32_i4_e32 v39, v131, v51
	v_dot8c_i32_i4_e32 v40, v133, v53
	v_dot8c_i32_i4_e32 v41, v133, v51
	v_dot8c_i32_i4_e32 v42, v135, v53
	v_dot8c_i32_i4_e32 v43, v135, v51
	v_dot8c_i32_i4_e32 v44, v137, v53
	v_dot8c_i32_i4_e32 v45, v137, v51
	s_nop 3
	s_waitcnt lgkmcnt(15)
	v_lshlrev_b32_e32 v38, 5, v38
	v_lshlrev_b32_e32 v39, 1, v39
	v_add3_u32 v38, v39, v229, v38
	v_cvt_f32_i32_e32 v38, v38
	v_mul_f32_e32 v38, v228, v38
	v_lshlrev_b32_e32 v40, 5, v40
	v_lshlrev_b32_e32 v41, 1, v41
	v_add3_u32 v40, v41, v229, v40
	v_cvt_f32_i32_e32 v40, v40
	v_mul_f32_e32 v40, v228, v40
	v_lshlrev_b32_e32 v42, 5, v42
	v_lshlrev_b32_e32 v43, 1, v43
	v_add3_u32 v42, v43, v229, v42
	v_cvt_f32_i32_e32 v42, v42
	v_mul_f32_e32 v42, v228, v42
	v_lshlrev_b32_e32 v44, 5, v44
	v_lshlrev_b32_e32 v45, 1, v45
	v_add3_u32 v44, v45, v229, v44
	v_cvt_f32_i32_e32 v44, v44
	v_mul_f32_e32 v44, v228, v44
	v_cvt_pk_bf16_f32 v164, v38, v40
	v_cvt_pk_bf16_f32 v165, v42, v44
	v_add_u32_e32 v147, 8, v140
	v_and_b32_e32 v146, 15, v147
	v_xor_b32_e32 v146, 8, v146
	v_bfe_u32 v148, v147, 4, 4
	v_mul_lo_u32 v146, v146, s92
	v_mul_lo_u32 v148, v148, s92
	v_mov_b32_e32 v147, v146
	v_mov_b32_e32 v149, v148
	ds_write2st64_b64 v77, v[146:147], v[148:149] offset1:2
	v_mov_b32_e32 v138, v74
	ds_read_u8 v139, v138
	v_mov_b32_e32 v141, v73
	ds_read_u8 v140, v141
	s_add_i32 s43, s67, 32
	v_mov_b32_e32 v138, s43
	ds_read2st64_b32 v[228:229], v138 offset1:1
	ds_read_b128 v[18:21], v227
	ds_read_b128 v[22:25], v227 offset:16
	v_add_u32_e32 v150, 0x400000, v63
	v_add_u32_e32 v151, 0x400000, v64
	v_mov_b32_e32 v38, 0
	v_mov_b32_e32 v39, 0
	v_mov_b32_e32 v40, 0
	v_mov_b32_e32 v41, 0
	v_mov_b32_e32 v42, 0
	v_mov_b32_e32 v43, 0
	v_mov_b32_e32 v44, 0
	v_mov_b32_e32 v45, 0
	v_and_b32_e32 v78, 0xffff, v31
	v_lshrrev_b32_e32 v79, 16, v31
	v_lshl_add_u32 v78, v78, 7, v152
	v_lshl_add_u32 v79, v79, 7, v153
	s_mov_b32 m0, s99
	s_add_i32 s43, s99, 0x400
	global_load_lds_dwordx4 v78, s[50:51]
	s_mov_b32 m0, s43
	s_nop 0
	global_load_lds_dwordx4 v79, s[50:51]
	s_waitcnt vmcnt(8)
; #define TR4(p_) __builtin_amdgcn_ds_read_tr4_b64_v2i32((LAS v2i*)(p_))
; #define VDMA(st_, k_) do { _Pragma("unroll") for (int i_ = 0; i_ < 4; ++i_) { \
;         const unsigned off_ = (unsigned)((st_) >> 2) * (16384u * 128u) + (PE_ID(E, 4 * ((st_) & 3) + i_) << 7) + ((i_ & 1) ? cx1 : cx0); \
;         __builtin_amdgcn_global_load_lds((const unsigned*)(V4 + off_), (LAS unsigned*)(ldsb + BUF[k_] + 1024 * i_), 16, 0, 0); } } while (0)
; __device__ __forceinline__ void peer_v_tokens(int j, const LAS unsigned short* EL, const LAS unsigned char* AL  , const LAS float* ASC  , const LAS int* SAL  , ...
;     ...
;         for (int st = 0; st < 16; ++st) {
;             const int p = st >> 2, q = st & 3;
;             if (st < 14) VDMA(st + 2, (st + 2) % 3);
;             if (st < 14) asm volatile("s_waitcnt vmcnt(8)" ::: "memory");
;             else if (st == 14) asm volatile("s_waitcnt vmcnt(4)" ::: "memory");
;             else asm volatile("s_waitcnt vmcnt(0)" ::: "memory");
;             if (q == 0) {
; #pragma unroll
;                 for (int r = 0; r < 4; ++r) { accH[r] = 0; accL[r] = 0; } }
; #pragma unroll
;             for (int tp = 0; tp < 2; ++tp) {
;                 const v2i ao = TR4(ATL + (2 * q + tp) * 128 + 8 * s16), ah = TR4(ATL + 1024 + (2 * q + tp) * 128 + 8 * s16);
; #pragma unroll
;                 for (int r = 0; r < 4; ++r) {
;                     const v2i d = TR4(ldsb + BUF[st % 3] + 2048 * tp + roff[r]);
;                     accH[r] = __builtin_amdgcn_sdot8(d.x, ah.x, accH[r], false); accH[r] = __builtin_amdgcn_sdot8(d.y, ah.y, accH[r], false);
;                     accL[r] = __builtin_amdgcn_sdot8(d.x, ao.x, accL[r], false); accL[r] = __builtin_amdgcn_sdot8(d.y, ao.y, accL[r], false);
;                 }
;             }
	v_add_u32_e32 v54, s77, v59
	v_add_u32_e32 v55, s77, v60
	v_add_u32_e32 v56, s77, v61
	v_add_u32_e32 v57, s77, v62
	ds_read_b64_tr_b4 v[50:51], v160 offset:128
	ds_read_b64_tr_b4 v[52:53], v160 offset:1152
	ds_read_b64_tr_b4 v[130:131], v54
	ds_read_b64_tr_b4 v[132:133], v55
	ds_read_b64_tr_b4 v[134:135], v56
	ds_read_b64_tr_b4 v[136:137], v57
	s_waitcnt lgkmcnt(12)
	v_dot8c_i32_i4_e32 v38, v122, v48
	v_dot8c_i32_i4_e32 v39, v122, v46
	v_dot8c_i32_i4_e32 v40, v124, v48
	v_dot8c_i32_i4_e32 v41, v124, v46
	v_dot8c_i32_i4_e32 v42, v126, v48
	v_dot8c_i32_i4_e32 v43, v126, v46
	v_dot8c_i32_i4_e32 v44, v128, v48
	v_dot8c_i32_i4_e32 v45, v128, v46
	v_dot8c_i32_i4_e32 v38, v123, v49
	v_dot8c_i32_i4_e32 v39, v123, v47
	v_dot8c_i32_i4_e32 v40, v125, v49
	v_dot8c_i32_i4_e32 v41, v125, v47
	v_dot8c_i32_i4_e32 v42, v127, v49
	v_dot8c_i32_i4_e32 v43, v127, v47
	v_dot8c_i32_i4_e32 v44, v129, v49
	v_dot8c_i32_i4_e32 v45, v129, v47
	v_and_b32_e32 v78, 0xffff, v32
	v_lshrrev_b32_e32 v79, 16, v32
	v_lshl_add_u32 v78, v78, 7, v152
	v_lshl_add_u32 v79, v79, 7, v153
	s_mov_b32 m0, s76
	s_add_i32 s43, s76, 0x400
	global_load_lds_dwordx4 v78, s[50:51]
	s_mov_b32 m0, s43
	s_nop 0
	global_load_lds_dwordx4 v79, s[50:51]
	s_waitcnt vmcnt(8)
	v_add_u32_e32 v54, s78, v59
	v_add_u32_e32 v55, s78, v60
	v_add_u32_e32 v56, s78, v61
	v_add_u32_e32 v57, s78, v62
	ds_read_b64_tr_b4 v[46:47], v160 offset:256
	ds_read_b64_tr_b4 v[48:49], v160 offset:1280
	ds_read_b64_tr_b4 v[122:123], v54
	ds_read_b64_tr_b4 v[124:125], v55
	ds_read_b64_tr_b4 v[126:127], v56
	ds_read_b64_tr_b4 v[128:129], v57
	s_waitcnt lgkmcnt(6)
	v_dot8c_i32_i4_e32 v38, v130, v52
	v_dot8c_i32_i4_e32 v39, v130, v50
	v_dot8c_i32_i4_e32 v40, v132, v52
	v_dot8c_i32_i4_e32 v41, v132, v50
	v_dot8c_i32_i4_e32 v42, v134, v52
	v_dot8c_i32_i4_e32 v43, v134, v50
	v_dot8c_i32_i4_e32 v44, v136, v52
	v_dot8c_i32_i4_e32 v45, v136, v50
	v_dot8c_i32_i4_e32 v38, v131, v53
	v_dot8c_i32_i4_e32 v39, v131, v51
	v_dot8c_i32_i4_e32 v40, v133, v53
	v_dot8c_i32_i4_e32 v41, v133, v51
	v_dot8c_i32_i4_e32 v42, v135, v53
	v_dot8c_i32_i4_e32 v43, v135, v51
	v_dot8c_i32_i4_e32 v44, v137, v53
	v_dot8c_i32_i4_e32 v45, v137, v51
	v_and_b32_e32 v78, 0xffff, v33
	v_lshrrev_b32_e32 v79, 16, v33
	v_lshl_add_u32 v78, v78, 7, v152
	v_lshl_add_u32 v79, v79, 7, v153
	s_mov_b32 m0, s77
	s_add_i32 s43, s77, 0x400
	global_load_lds_dwordx4 v78, s[50:51]
	s_mov_b32 m0, s43
	s_nop 0
	global_load_lds_dwordx4 v79, s[50:51]
	s_waitcnt vmcnt(8)
	v_add_u32_e32 v54, s79, v59
	v_add_u32_e32 v55, s79, v60
	v_add_u32_e32 v56, s79, v61
	v_add_u32_e32 v57, s79, v62
	ds_read_b64_tr_b4 v[50:51], v160 offset:384
	ds_read_b64_tr_b4 v[52:53], v160 offset:1408
	ds_read_b64_tr_b4 v[130:131], v54
	ds_read_b64_tr_b4 v[132:133], v55
	ds_read_b64_tr_b4 v[134:135], v56
	ds_read_b64_tr_b4 v[136:137], v57
	s_waitcnt lgkmcnt(6)
	v_dot8c_i32_i4_e32 v38, v122, v48
	v_dot8c_i32_i4_e32 v39, v122, v46
	v_dot8c_i32_i4_e32 v40, v124, v48
	v_dot8c_i32_i4_e32 v41, v124, v46
	v_dot8c_i32_i4_e32 v42, v126, v48
	v_dot8c_i32_i4_e32 v43, v126, v46
	v_dot8c_i32_i4_e32 v44, v128, v48
	v_dot8c_i32_i4_e32 v45, v128, v46
	v_dot8c_i32_i4_e32 v38, v123, v49
	v_dot8c_i32_i4_e32 v39, v123, v47
	v_dot8c_i32_i4_e32 v40, v125, v49
	v_dot8c_i32_i4_e32 v41, v125, v47
	v_dot8c_i32_i4_e32 v42, v127, v49
	v_dot8c_i32_i4_e32 v43, v127, v47
	v_dot8c_i32_i4_e32 v44, v129, v49
	v_dot8c_i32_i4_e32 v45, v129, v47
	s_waitcnt lgkmcnt(15)
	v_and_b32_e32 v78, 0xffff, v18
	v_lshrrev_b32_e32 v79, 16, v18
	v_lshl_add_u32 v78, v78, 7, v150
	v_lshl_add_u32 v79, v79, 7, v151
	s_mov_b32 m0, s78
	s_add_i32 s43, s78, 0x400
	global_load_lds_dwordx4 v78, s[50:51]
	s_mov_b32 m0, s43
	s_nop 0
	global_load_lds_dwordx4 v79, s[50:51]
	s_waitcnt vmcnt(8)
	v_add_u32_e32 v54, s98, v59
	v_add_u32_e32 v55, s98, v60
	v_add_u32_e32 v56, s98, v61
	v_add_u32_e32 v57, s98, v62
	ds_read_b64_tr_b4 v[46:47], v160 offset:512
	ds_read_b64_tr_b4 v[48:49], v160 offset:1536
	ds_read_b64_tr_b4 v[122:123], v54
	ds_read_b64_tr_b4 v[124:125], v55
	ds_read_b64_tr_b4 v[126:127], v56
	ds_read_b64_tr_b4 v[128:129], v57
	s_waitcnt lgkmcnt(6)
	v_dot8c_i32_i4_e32 v38, v130, v52
	v_dot8c_i32_i4_e32 v39, v130, v50
	v_dot8c_i32_i4_e32 v40, v132, v52
	v_dot8c_i32_i4_e32 v41, v132, v50
	v_dot8c_i32_i4_e32 v42, v134, v52
	v_dot8c_i32_i4_e32 v43, v134, v50
	v_dot8c_i32_i4_e32 v44, v136, v52
	v_dot8c_i32_i4_e32 v45, v136, v50
	v_dot8c_i32_i4_e32 v38, v131, v53
	v_dot8c_i32_i4_e32 v39, v131, v51
	v_dot8c_i32_i4_e32 v40, v133, v53
	v_dot8c_i32_i4_e32 v41, v133, v51
	v_dot8c_i32_i4_e32 v42, v135, v53
	v_dot8c_i32_i4_e32 v43, v135, v51
	v_dot8c_i32_i4_e32 v44, v137, v53
	v_dot8c_i32_i4_e32 v45, v137, v51
	v_and_b32_e32 v78, 0xffff, v19
	v_lshrrev_b32_e32 v79, 16, v19
	v_lshl_add_u32 v78, v78, 7, v150
	v_lshl_add_u32 v79, v79, 7, v151
	s_mov_b32 m0, s79
	s_add_i32 s43, s79, 0x400
	global_load_lds_dwordx4 v78, s[50:51]
	s_mov_b32 m0, s43
	s_nop 0
	global_load_lds_dwordx4 v79, s[50:51]
	s_waitcnt vmcnt(8)
	v_add_u32_e32 v54, s99, v59
	v_add_u32_e32 v55, s99, v60
	v_add_u32_e32 v56, s99, v61
	v_add_u32_e32 v57, s99, v62
	ds_read_b64_tr_b4 v[50:51], v160 offset:640
	ds_read_b64_tr_b4 v[52:53], v160 offset:1664
	ds_read_b64_tr_b4 v[130:131], v54
	ds_read_b64_tr_b4 v[132:133], v55
	ds_read_b64_tr_b4 v[134:135], v56
	ds_read_b64_tr_b4 v[136:137], v57
	s_waitcnt lgkmcnt(6)
	v_dot8c_i32_i4_e32 v38, v122, v48
	v_dot8c_i32_i4_e32 v39, v122, v46
	v_dot8c_i32_i4_e32 v40, v124, v48
	v_dot8c_i32_i4_e32 v41, v124, v46
	v_dot8c_i32_i4_e32 v42, v126, v48
	v_dot8c_i32_i4_e32 v43, v126, v46
	v_dot8c_i32_i4_e32 v44, v128, v48
	v_dot8c_i32_i4_e32 v45, v128, v46
	v_dot8c_i32_i4_e32 v38, v123, v49
	v_dot8c_i32_i4_e32 v39, v123, v47
	v_dot8c_i32_i4_e32 v40, v125, v49
	v_dot8c_i32_i4_e32 v41, v125, v47
	v_dot8c_i32_i4_e32 v42, v127, v49
	v_dot8c_i32_i4_e32 v43, v127, v47
	v_dot8c_i32_i4_e32 v44, v129, v49
	v_dot8c_i32_i4_e32 v45, v129, v47
	s_waitcnt lgkmcnt(15)
; __device__ __forceinline__ void peer_v_tokens(int j, const LAS unsigned short* EL, const LAS unsigned char* AL  , const LAS float* ASC  , const LAS int* SAL  , ...
;     ...
;         for (int m = 0; m < 2; ++m) {
;             const int idx = lane + 64 * m, tau = idx >> 4, sr = idx & 15, k = 16 * (sr & 7) + 2 * tau + (sr >> 3);
;             const int aq = (int)*(const LAS signed char*)(AL + tl * 128 + k); const int tq = aq + 8;
;             const unsigned lo = (((unsigned)tq & 15u) ^ 8u) * 0x11111111u, hi = ((unsigned)(tq >> 4) & 15u) * 0x11111111u;
;             typedef unsigned u2v __attribute__((ext_vector_type(2)));
;             u2v l2; l2.x = lo; l2.y = lo; u2v h2; h2.x = hi; h2.y = hi;
;             *(LAS u2v*)(ATL + 8 * idx) = l2; *(LAS u2v*)(ATL + 1024 + 8 * idx) = h2;
;         }
;         const float asc = ASC[tl]; const int sa = SAL[tl];
;         CFENCE();
;         int accH[4], accL[4];
; #pragma unroll
;         for (int st = 0; st < 16; ++st) {
;             const int p = st >> 2, q = st & 3;
;             if (st < 14) VDMA(st + 2, (st + 2) % 3);
;             if (st < 14) asm volatile("s_waitcnt vmcnt(8)" ::: "memory");
;             else if (st == 14) asm volatile("s_waitcnt vmcnt(4)" ::: "memory");
;             else asm volatile("s_waitcnt vmcnt(0)" ::: "memory");
;             if (q == 0) {
; #pragma unroll
;                 for (int r = 0; r < 4; ++r) { accH[r] = 0; accL[r] = 0; } }
; #pragma unroll
;             for (int tp = 0; tp < 2; ++tp) {
;                 const v2i ao = TR4(ATL + (2 * q + tp) * 128 + 8 * s16), ah = TR4(ATL + 1024 + (2 * q + tp) * 128 + 8 * s16);
; #pragma unroll
;                 for (int r = 0; r < 4; ++r) {
;                     const v2i d = TR4(ldsb + BUF[st % 3] + 2048 * tp + roff[r]);
;                     accH[r] = __builtin_amdgcn_sdot8(d.x, ah.x, accH[r], false); accH[r] = __builtin_amdgcn_sdot8(d.y, ah.y, accH[r], false);
;                     accL[r] = __builtin_amdgcn_sdot8(d.x, ao.x, accL[r], false); accL[r] = __builtin_amdgcn_sdot8(d.y, ao.y, accL[r], false);
;                 }
;             }
;             asm volatile("s_waitcnt lgkmcnt(0)" ::: "memory");
;             if (q == 3) {
; #pragma unroll
;                 for (int r = 0; r < 4; ++r) STASH[256 * p + 16 * (grp + 4 * r) + pc] = f2bf(asc * (float)(2 * ((accH[r] << 4) + accL[r]) + sa));
;             }
	v_add_u32_e32 v143, 8, v139
	v_and_b32_e32 v142, 15, v143
	v_xor_b32_e32 v142, 8, v142
	v_bfe_u32 v144, v143, 4, 4
	v_mul_lo_u32 v142, v142, s92
	v_mul_lo_u32 v144, v144, s92
	v_mov_b32_e32 v143, v142
	v_mov_b32_e32 v145, v144
	ds_write2st64_b64 v159, v[142:143], v[144:145] offset1:2
	v_and_b32_e32 v78, 0xffff, v20
	v_lshrrev_b32_e32 v79, 16, v20
	v_lshl_add_u32 v78, v78, 7, v150
	v_lshl_add_u32 v79, v79, 7, v151
	s_mov_b32 m0, s98
	s_add_i32 s43, s98, 0x400
	global_load_lds_dwordx4 v78, s[50:51]
	s_mov_b32 m0, s43
	s_nop 0
	global_load_lds_dwordx4 v79, s[50:51]
	s_waitcnt vmcnt(8)
	v_add_u32_e32 v54, s76, v59
	v_add_u32_e32 v55, s76, v60
	v_add_u32_e32 v56, s76, v61
	v_add_u32_e32 v57, s76, v62
	ds_read_b64_tr_b4 v[46:47], v160 offset:768
	ds_read_b64_tr_b4 v[48:49], v160 offset:1792
	ds_read_b64_tr_b4 v[122:123], v54
	ds_read_b64_tr_b4 v[124:125], v55
	ds_read_b64_tr_b4 v[126:127], v56
	ds_read_b64_tr_b4 v[128:129], v57
	s_waitcnt lgkmcnt(7)
	v_dot8c_i32_i4_e32 v38, v130, v52
	v_dot8c_i32_i4_e32 v39, v130, v50
	v_dot8c_i32_i4_e32 v40, v132, v52
	v_dot8c_i32_i4_e32 v41, v132, v50
	v_dot8c_i32_i4_e32 v42, v134, v52
	v_dot8c_i32_i4_e32 v43, v134, v50
	v_dot8c_i32_i4_e32 v44, v136, v52
	v_dot8c_i32_i4_e32 v45, v136, v50
	v_dot8c_i32_i4_e32 v38, v131, v53
	v_dot8c_i32_i4_e32 v39, v131, v51
	v_dot8c_i32_i4_e32 v40, v133, v53
	v_dot8c_i32_i4_e32 v41, v133, v51
	v_dot8c_i32_i4_e32 v42, v135, v53
	v_dot8c_i32_i4_e32 v43, v135, v51
	v_dot8c_i32_i4_e32 v44, v137, v53
	v_dot8c_i32_i4_e32 v45, v137, v51
	v_and_b32_e32 v78, 0xffff, v21
	v_lshrrev_b32_e32 v79, 16, v21
	v_lshl_add_u32 v78, v78, 7, v150
	v_lshl_add_u32 v79, v79, 7, v151
	s_mov_b32 m0, s99
	s_add_i32 s43, s99, 0x400
	global_load_lds_dwordx4 v78, s[50:51]
	s_mov_b32 m0, s43
	s_nop 0
	global_load_lds_dwordx4 v79, s[50:51]
	s_waitcnt vmcnt(8)
	v_add_u32_e32 v54, s77, v59
	v_add_u32_e32 v55, s77, v60
	v_add_u32_e32 v56, s77, v61
	v_add_u32_e32 v57, s77, v62
	ds_read_b64_tr_b4 v[50:51], v160 offset:896
	ds_read_b64_tr_b4 v[52:53], v160 offset:1920
	ds_read_b64_tr_b4 v[130:131], v54
	ds_read_b64_tr_b4 v[132:133], v55
	ds_read_b64_tr_b4 v[134:135], v56
	ds_read_b64_tr_b4 v[136:137], v57
	s_waitcnt lgkmcnt(6)
	v_dot8c_i32_i4_e32 v38, v122, v48
	v_dot8c_i32_i4_e32 v39, v122, v46
	v_dot8c_i32_i4_e32 v40, v124, v48
	v_dot8c_i32_i4_e32 v41, v124, v46
	v_dot8c_i32_i4_e32 v42, v126, v48
	v_dot8c_i32_i4_e32 v43, v126, v46
	v_dot8c_i32_i4_e32 v44, v128, v48
	v_dot8c_i32_i4_e32 v45, v128, v46
	v_dot8c_i32_i4_e32 v38, v123, v49
	v_dot8c_i32_i4_e32 v39, v123, v47
	v_dot8c_i32_i4_e32 v40, v125, v49
	v_dot8c_i32_i4_e32 v41, v125, v47
	v_dot8c_i32_i4_e32 v42, v127, v49
	v_dot8c_i32_i4_e32 v43, v127, v47
	v_dot8c_i32_i4_e32 v44, v129, v49
	v_dot8c_i32_i4_e32 v45, v129, v47
	v_and_b32_e32 v78, 0xffff, v22
	v_lshrrev_b32_e32 v79, 16, v22
	v_lshl_add_u32 v78, v78, 7, v150
	v_lshl_add_u32 v79, v79, 7, v151
	s_mov_b32 m0, s76
	s_add_i32 s43, s76, 0x400
	global_load_lds_dwordx4 v78, s[50:51]
	s_mov_b32 m0, s43
	s_nop 0
	global_load_lds_dwordx4 v79, s[50:51]
	s_waitcnt vmcnt(8)
	v_add_u32_e32 v54, s78, v59
	v_add_u32_e32 v55, s78, v60
	v_add_u32_e32 v56, s78, v61
	v_add_u32_e32 v57, s78, v62
	ds_read_b64_tr_b4 v[46:47], v160
	ds_read_b64_tr_b4 v[48:49], v160 offset:1024
	ds_read_b64_tr_b4 v[122:123], v54
	ds_read_b64_tr_b4 v[124:125], v55
	ds_read_b64_tr_b4 v[126:127], v56
	ds_read_b64_tr_b4 v[128:129], v57
	s_waitcnt lgkmcnt(6)
	v_dot8c_i32_i4_e32 v38, v130, v52
	v_dot8c_i32_i4_e32 v39, v130, v50
	v_dot8c_i32_i4_e32 v40, v132, v52
	v_dot8c_i32_i4_e32 v41, v132, v50
	v_dot8c_i32_i4_e32 v42, v134, v52
	v_dot8c_i32_i4_e32 v43, v134, v50
	v_dot8c_i32_i4_e32 v44, v136, v52
	v_dot8c_i32_i4_e32 v45, v136, v50
	v_dot8c_i32_i4_e32 v38, v131, v53
	v_dot8c_i32_i4_e32 v39, v131, v51
	v_dot8c_i32_i4_e32 v40, v133, v53
	v_dot8c_i32_i4_e32 v41, v133, v51
	v_dot8c_i32_i4_e32 v42, v135, v53
	v_dot8c_i32_i4_e32 v43, v135, v51
	v_dot8c_i32_i4_e32 v44, v137, v53
	v_dot8c_i32_i4_e32 v45, v137, v51
	s_nop 3
	s_waitcnt lgkmcnt(15)
	v_lshlrev_b32_e32 v38, 5, v38
	v_lshlrev_b32_e32 v39, 1, v39
	v_add3_u32 v38, v39, v229, v38
	v_cvt_f32_i32_e32 v38, v38
	v_mul_f32_e32 v38, v228, v38
	v_lshlrev_b32_e32 v40, 5, v40
	v_lshlrev_b32_e32 v41, 1, v41
	v_add3_u32 v40, v41, v229, v40
	v_cvt_f32_i32_e32 v40, v40
	v_mul_f32_e32 v40, v228, v40
	v_lshlrev_b32_e32 v42, 5, v42
	v_lshlrev_b32_e32 v43, 1, v43
	v_add3_u32 v42, v43, v229, v42
	v_cvt_f32_i32_e32 v42, v42
	v_mul_f32_e32 v42, v228, v42
	v_lshlrev_b32_e32 v44, 5, v44
	v_lshlrev_b32_e32 v45, 1, v45
	v_add3_u32 v44, v45, v229, v44
	v_cvt_f32_i32_e32 v44, v44
	v_mul_f32_e32 v44, v228, v44
	v_cvt_pk_bf16_f32 v172, v38, v40
	v_cvt_pk_bf16_f32 v173, v42, v44
	v_add_u32_e32 v147, 8, v140
	v_and_b32_e32 v146, 15, v147
	v_xor_b32_e32 v146, 8, v146
	v_bfe_u32 v148, v147, 4, 4
	v_mul_lo_u32 v146, v146, s92
	v_mul_lo_u32 v148, v148, s92
	v_mov_b32_e32 v147, v146
	v_mov_b32_e32 v149, v148
	ds_write2st64_b64 v77, v[146:147], v[148:149] offset1:2
	v_add_u32_e32 v138, 0x400, v74
	ds_read_u8 v139, v138
	v_add_u32_e32 v141, 0x400, v73
	ds_read_u8 v140, v141
	s_mov_b32 s43, s67
	v_mov_b32_e32 v138, s43
	ds_read2st64_b32 v[228:229], v138 offset1:1
	ds_read_b128 v[26:29], v227 offset:2048
	ds_read_b128 v[30:33], v227 offset:2064
	v_mov_b32_e32 v38, 0
	v_mov_b32_e32 v39, 0
	v_mov_b32_e32 v40, 0
	v_mov_b32_e32 v41, 0
	v_mov_b32_e32 v42, 0
	v_mov_b32_e32 v43, 0
	v_mov_b32_e32 v44, 0
	v_mov_b32_e32 v45, 0
	v_and_b32_e32 v78, 0xffff, v23
	v_lshrrev_b32_e32 v79, 16, v23
	v_lshl_add_u32 v78, v78, 7, v150
	v_lshl_add_u32 v79, v79, 7, v151
	s_mov_b32 m0, s77
	s_add_i32 s43, s77, 0x400
	global_load_lds_dwordx4 v78, s[50:51]
	s_mov_b32 m0, s43
	s_nop 0
	global_load_lds_dwordx4 v79, s[50:51]
	s_waitcnt vmcnt(8)
; #define TR4(p_) __builtin_amdgcn_ds_read_tr4_b64_v2i32((LAS v2i*)(p_))
; #define VDMA(st_, k_) do { _Pragma("unroll") for (int i_ = 0; i_ < 4; ++i_) { \
;         const unsigned off_ = (unsigned)((st_) >> 2) * (16384u * 128u) + (PE_ID(E, 4 * ((st_) & 3) + i_) << 7) + ((i_ & 1) ? cx1 : cx0); \
;         __builtin_amdgcn_global_load_lds((const unsigned*)(V4 + off_), (LAS unsigned*)(ldsb + BUF[k_] + 1024 * i_), 16, 0, 0); } } while (0)
; __device__ __forceinline__ void peer_v_tokens(int j, const LAS unsigned short* EL, const LAS unsigned char* AL  , const LAS float* ASC  , const LAS int* SAL  , ...
;     ...
;         for (int st = 0; st < 16; ++st) {
;             const int p = st >> 2, q = st & 3;
;             if (st < 14) VDMA(st + 2, (st + 2) % 3);
;             if (st < 14) asm volatile("s_waitcnt vmcnt(8)" ::: "memory");
;             else if (st == 14) asm volatile("s_waitcnt vmcnt(4)" ::: "memory");
;             else asm volatile("s_waitcnt vmcnt(0)" ::: "memory");
;             if (q == 0) {
; #pragma unroll
;                 for (int r = 0; r < 4; ++r) { accH[r] = 0; accL[r] = 0; } }
; #pragma unroll
;             for (int tp = 0; tp < 2; ++tp) {
;                 const v2i ao = TR4(ATL + (2 * q + tp) * 128 + 8 * s16), ah = TR4(ATL + 1024 + (2 * q + tp) * 128 + 8 * s16);
; #pragma unroll
;                 for (int r = 0; r < 4; ++r) {
;                     const v2i d = TR4(ldsb + BUF[st % 3] + 2048 * tp + roff[r]);
;                     accH[r] = __builtin_amdgcn_sdot8(d.x, ah.x, accH[r], false); accH[r] = __builtin_amdgcn_sdot8(d.y, ah.y, accH[r], false);
;                     accL[r] = __builtin_amdgcn_sdot8(d.x, ao.x, accL[r], false); accL[r] = __builtin_amdgcn_sdot8(d.y, ao.y, accL[r], false);
;                 }
;             }
	v_add_u32_e32 v54, s79, v59
	v_add_u32_e32 v55, s79, v60
	v_add_u32_e32 v56, s79, v61
	v_add_u32_e32 v57, s79, v62
	ds_read_b64_tr_b4 v[50:51], v160 offset:128
	ds_read_b64_tr_b4 v[52:53], v160 offset:1152
	ds_read_b64_tr_b4 v[130:131], v54
	ds_read_b64_tr_b4 v[132:133], v55
	ds_read_b64_tr_b4 v[134:135], v56
	ds_read_b64_tr_b4 v[136:137], v57
	s_waitcnt lgkmcnt(12)
	v_dot8c_i32_i4_e32 v38, v122, v48
	v_dot8c_i32_i4_e32 v39, v122, v46
	v_dot8c_i32_i4_e32 v40, v124, v48
	v_dot8c_i32_i4_e32 v41, v124, v46
	v_dot8c_i32_i4_e32 v42, v126, v48
	v_dot8c_i32_i4_e32 v43, v126, v46
	v_dot8c_i32_i4_e32 v44, v128, v48
	v_dot8c_i32_i4_e32 v45, v128, v46
	v_dot8c_i32_i4_e32 v38, v123, v49
	v_dot8c_i32_i4_e32 v39, v123, v47
	v_dot8c_i32_i4_e32 v40, v125, v49
	v_dot8c_i32_i4_e32 v41, v125, v47
	v_dot8c_i32_i4_e32 v42, v127, v49
	v_dot8c_i32_i4_e32 v43, v127, v47
	v_dot8c_i32_i4_e32 v44, v129, v49
	v_dot8c_i32_i4_e32 v45, v129, v47
	v_and_b32_e32 v78, 0xffff, v24
	v_lshrrev_b32_e32 v79, 16, v24
	v_lshl_add_u32 v78, v78, 7, v150
	v_lshl_add_u32 v79, v79, 7, v151
	s_mov_b32 m0, s78
	s_add_i32 s43, s78, 0x400
	global_load_lds_dwordx4 v78, s[50:51]
	s_mov_b32 m0, s43
	s_nop 0
	global_load_lds_dwordx4 v79, s[50:51]
	s_waitcnt vmcnt(8)
	v_add_u32_e32 v54, s98, v59
	v_add_u32_e32 v55, s98, v60
	v_add_u32_e32 v56, s98, v61
	v_add_u32_e32 v57, s98, v62
	ds_read_b64_tr_b4 v[46:47], v160 offset:256
	ds_read_b64_tr_b4 v[48:49], v160 offset:1280
	ds_read_b64_tr_b4 v[122:123], v54
	ds_read_b64_tr_b4 v[124:125], v55
	ds_read_b64_tr_b4 v[126:127], v56
	ds_read_b64_tr_b4 v[128:129], v57
	s_waitcnt lgkmcnt(6)
	v_dot8c_i32_i4_e32 v38, v130, v52
	v_dot8c_i32_i4_e32 v39, v130, v50
	v_dot8c_i32_i4_e32 v40, v132, v52
	v_dot8c_i32_i4_e32 v41, v132, v50
	v_dot8c_i32_i4_e32 v42, v134, v52
	v_dot8c_i32_i4_e32 v43, v134, v50
	v_dot8c_i32_i4_e32 v44, v136, v52
	v_dot8c_i32_i4_e32 v45, v136, v50
	v_dot8c_i32_i4_e32 v38, v131, v53
	v_dot8c_i32_i4_e32 v39, v131, v51
	v_dot8c_i32_i4_e32 v40, v133, v53
	v_dot8c_i32_i4_e32 v41, v133, v51
	v_dot8c_i32_i4_e32 v42, v135, v53
	v_dot8c_i32_i4_e32 v43, v135, v51
	v_dot8c_i32_i4_e32 v44, v137, v53
	v_dot8c_i32_i4_e32 v45, v137, v51
	v_and_b32_e32 v78, 0xffff, v25
	v_lshrrev_b32_e32 v79, 16, v25
	v_lshl_add_u32 v78, v78, 7, v150
	v_lshl_add_u32 v79, v79, 7, v151
	s_mov_b32 m0, s79
	s_add_i32 s43, s79, 0x400
	global_load_lds_dwordx4 v78, s[50:51]
	s_mov_b32 m0, s43
	s_nop 0
	global_load_lds_dwordx4 v79, s[50:51]
	s_waitcnt vmcnt(8)
	v_add_u32_e32 v54, s99, v59
	v_add_u32_e32 v55, s99, v60
	v_add_u32_e32 v56, s99, v61
	v_add_u32_e32 v57, s99, v62
	ds_read_b64_tr_b4 v[50:51], v160 offset:384
	ds_read_b64_tr_b4 v[52:53], v160 offset:1408
	ds_read_b64_tr_b4 v[130:131], v54
	ds_read_b64_tr_b4 v[132:133], v55
	ds_read_b64_tr_b4 v[134:135], v56
	ds_read_b64_tr_b4 v[136:137], v57
	s_waitcnt lgkmcnt(6)
	v_dot8c_i32_i4_e32 v38, v122, v48
	v_dot8c_i32_i4_e32 v39, v122, v46
	v_dot8c_i32_i4_e32 v40, v124, v48
	v_dot8c_i32_i4_e32 v41, v124, v46
	v_dot8c_i32_i4_e32 v42, v126, v48
	v_dot8c_i32_i4_e32 v43, v126, v46
	v_dot8c_i32_i4_e32 v44, v128, v48
	v_dot8c_i32_i4_e32 v45, v128, v46
	v_dot8c_i32_i4_e32 v38, v123, v49
	v_dot8c_i32_i4_e32 v39, v123, v47
	v_dot8c_i32_i4_e32 v40, v125, v49
	v_dot8c_i32_i4_e32 v41, v125, v47
	v_dot8c_i32_i4_e32 v42, v127, v49
	v_dot8c_i32_i4_e32 v43, v127, v47
	v_dot8c_i32_i4_e32 v44, v129, v49
	v_dot8c_i32_i4_e32 v45, v129, v47
	s_waitcnt lgkmcnt(15)
	v_and_b32_e32 v78, 0xffff, v26
	v_lshrrev_b32_e32 v79, 16, v26
	v_lshl_add_u32 v78, v78, 7, v150
	v_lshl_add_u32 v79, v79, 7, v151
	s_mov_b32 m0, s98
	s_add_i32 s43, s98, 0x400
	global_load_lds_dwordx4 v78, s[50:51]
	s_mov_b32 m0, s43
	s_nop 0
	global_load_lds_dwordx4 v79, s[50:51]
	s_waitcnt vmcnt(8)
	v_add_u32_e32 v54, s76, v59
	v_add_u32_e32 v55, s76, v60
	v_add_u32_e32 v56, s76, v61
	v_add_u32_e32 v57, s76, v62
	ds_read_b64_tr_b4 v[46:47], v160 offset:512
	ds_read_b64_tr_b4 v[48:49], v160 offset:1536
	ds_read_b64_tr_b4 v[122:123], v54
	ds_read_b64_tr_b4 v[124:125], v55
	ds_read_b64_tr_b4 v[126:127], v56
	ds_read_b64_tr_b4 v[128:129], v57
	s_waitcnt lgkmcnt(6)
	v_dot8c_i32_i4_e32 v38, v130, v52
	v_dot8c_i32_i4_e32 v39, v130, v50
	v_dot8c_i32_i4_e32 v40, v132, v52
	v_dot8c_i32_i4_e32 v41, v132, v50
	v_dot8c_i32_i4_e32 v42, v134, v52
	v_dot8c_i32_i4_e32 v43, v134, v50
	v_dot8c_i32_i4_e32 v44, v136, v52
	v_dot8c_i32_i4_e32 v45, v136, v50
	v_dot8c_i32_i4_e32 v38, v131, v53
	v_dot8c_i32_i4_e32 v39, v131, v51
	v_dot8c_i32_i4_e32 v40, v133, v53
	v_dot8c_i32_i4_e32 v41, v133, v51
	v_dot8c_i32_i4_e32 v42, v135, v53
	v_dot8c_i32_i4_e32 v43, v135, v51
	v_dot8c_i32_i4_e32 v44, v137, v53
	v_dot8c_i32_i4_e32 v45, v137, v51
	v_and_b32_e32 v78, 0xffff, v27
	v_lshrrev_b32_e32 v79, 16, v27
	v_lshl_add_u32 v78, v78, 7, v150
	v_lshl_add_u32 v79, v79, 7, v151
	s_mov_b32 m0, s99
	s_add_i32 s43, s99, 0x400
	global_load_lds_dwordx4 v78, s[50:51]
	s_mov_b32 m0, s43
	s_nop 0
	global_load_lds_dwordx4 v79, s[50:51]
	s_waitcnt vmcnt(8)
	v_add_u32_e32 v54, s77, v59
	v_add_u32_e32 v55, s77, v60
	v_add_u32_e32 v56, s77, v61
	v_add_u32_e32 v57, s77, v62
	ds_read_b64_tr_b4 v[50:51], v160 offset:640
	ds_read_b64_tr_b4 v[52:53], v160 offset:1664
	ds_read_b64_tr_b4 v[130:131], v54
	ds_read_b64_tr_b4 v[132:133], v55
	ds_read_b64_tr_b4 v[134:135], v56
	ds_read_b64_tr_b4 v[136:137], v57
	s_waitcnt lgkmcnt(6)
	v_dot8c_i32_i4_e32 v38, v122, v48
	v_dot8c_i32_i4_e32 v39, v122, v46
	v_dot8c_i32_i4_e32 v40, v124, v48
	v_dot8c_i32_i4_e32 v41, v124, v46
	v_dot8c_i32_i4_e32 v42, v126, v48
	v_dot8c_i32_i4_e32 v43, v126, v46
	v_dot8c_i32_i4_e32 v44, v128, v48
	v_dot8c_i32_i4_e32 v45, v128, v46
	v_dot8c_i32_i4_e32 v38, v123, v49
	v_dot8c_i32_i4_e32 v39, v123, v47
	v_dot8c_i32_i4_e32 v40, v125, v49
	v_dot8c_i32_i4_e32 v41, v125, v47
	v_dot8c_i32_i4_e32 v42, v127, v49
	v_dot8c_i32_i4_e32 v43, v127, v47
	v_dot8c_i32_i4_e32 v44, v129, v49
	v_dot8c_i32_i4_e32 v45, v129, v47
	s_waitcnt lgkmcnt(15)
; __device__ __forceinline__ void peer_v_tokens(int j, const LAS unsigned short* EL, const LAS unsigned char* AL  , const LAS float* ASC  , const LAS int* SAL  , ...
;     ...
;         for (int m = 0; m < 2; ++m) {
;             const int idx = lane + 64 * m, tau = idx >> 4, sr = idx & 15, k = 16 * (sr & 7) + 2 * tau + (sr >> 3);
;             const int aq = (int)*(const LAS signed char*)(AL + tl * 128 + k); const int tq = aq + 8;
;             const unsigned lo = (((unsigned)tq & 15u) ^ 8u) * 0x11111111u, hi = ((unsigned)(tq >> 4) & 15u) * 0x11111111u;
;             typedef unsigned u2v __attribute__((ext_vector_type(2)));
;             u2v l2; l2.x = lo; l2.y = lo; u2v h2; h2.x = hi; h2.y = hi;
;             *(LAS u2v*)(ATL + 8 * idx) = l2; *(LAS u2v*)(ATL + 1024 + 8 * idx) = h2;
;         }
;         const float asc = ASC[tl]; const int sa = SAL[tl];
;         CFENCE();
;         int accH[4], accL[4];
; #pragma unroll
;         for (int st = 0; st < 16; ++st) {
;             const int p = st >> 2, q = st & 3;
;             if (st < 14) VDMA(st + 2, (st + 2) % 3);
;             if (st < 14) asm volatile("s_waitcnt vmcnt(8)" ::: "memory");
;             else if (st == 14) asm volatile("s_waitcnt vmcnt(4)" ::: "memory");
;             else asm volatile("s_waitcnt vmcnt(0)" ::: "memory");
;             if (q == 0) {
; #pragma unroll
;                 for (int r = 0; r < 4; ++r) { accH[r] = 0; accL[r] = 0; } }
; #pragma unroll
;             for (int tp = 0; tp < 2; ++tp) {
;                 const v2i ao = TR4(ATL + (2 * q + tp) * 128 + 8 * s16), ah = TR4(ATL + 1024 + (2 * q + tp) * 128 + 8 * s16);
; #pragma unroll
;                 for (int r = 0; r < 4; ++r) {
;                     const v2i d = TR4(ldsb + BUF[st % 3] + 2048 * tp + roff[r]);
;                     accH[r] = __builtin_amdgcn_sdot8(d.x, ah.x, accH[r], false); accH[r] = __builtin_amdgcn_sdot8(d.y, ah.y, accH[r], false);
;                     accL[r] = __builtin_amdgcn_sdot8(d.x, ao.x, accL[r], false); accL[r] = __builtin_amdgcn_sdot8(d.y, ao.y, accL[r], false);
;                 }
;             }
;             asm volatile("s_waitcnt lgkmcnt(0)" ::: "memory");
;             if (q == 3) {
; #pragma unroll
;                 for (int r = 0; r < 4; ++r) STASH[256 * p + 16 * (grp + 4 * r) + pc] = f2bf(asc * (float)(2 * ((accH[r] << 4) + accL[r]) + sa));
;             }
	v_add_u32_e32 v143, 8, v139
	v_and_b32_e32 v142, 15, v143
	v_xor_b32_e32 v142, 8, v142
	v_bfe_u32 v144, v143, 4, 4
	v_mul_lo_u32 v142, v142, s92
	v_mul_lo_u32 v144, v144, s92
	v_mov_b32_e32 v143, v142
	v_mov_b32_e32 v145, v144
	ds_write2st64_b64 v159, v[142:143], v[144:145] offset1:2
	v_and_b32_e32 v78, 0xffff, v28
	v_lshrrev_b32_e32 v79, 16, v28
	v_lshl_add_u32 v78, v78, 7, v150
	v_lshl_add_u32 v79, v79, 7, v151
	s_mov_b32 m0, s76
	s_add_i32 s43, s76, 0x400
	global_load_lds_dwordx4 v78, s[50:51]
	s_mov_b32 m0, s43
	s_nop 0
	global_load_lds_dwordx4 v79, s[50:51]
	s_waitcnt vmcnt(8)
	v_add_u32_e32 v54, s78, v59
	v_add_u32_e32 v55, s78, v60
	v_add_u32_e32 v56, s78, v61
	v_add_u32_e32 v57, s78, v62
	ds_read_b64_tr_b4 v[46:47], v160 offset:768
	ds_read_b64_tr_b4 v[48:49], v160 offset:1792
	ds_read_b64_tr_b4 v[122:123], v54
	ds_read_b64_tr_b4 v[124:125], v55
	ds_read_b64_tr_b4 v[126:127], v56
	ds_read_b64_tr_b4 v[128:129], v57
	s_waitcnt lgkmcnt(7)
	v_dot8c_i32_i4_e32 v38, v130, v52
	v_dot8c_i32_i4_e32 v39, v130, v50
	v_dot8c_i32_i4_e32 v40, v132, v52
	v_dot8c_i32_i4_e32 v41, v132, v50
	v_dot8c_i32_i4_e32 v42, v134, v52
	v_dot8c_i32_i4_e32 v43, v134, v50
	v_dot8c_i32_i4_e32 v44, v136, v52
	v_dot8c_i32_i4_e32 v45, v136, v50
	v_dot8c_i32_i4_e32 v38, v131, v53
	v_dot8c_i32_i4_e32 v39, v131, v51
	v_dot8c_i32_i4_e32 v40, v133, v53
	v_dot8c_i32_i4_e32 v41, v133, v51
	v_dot8c_i32_i4_e32 v42, v135, v53
	v_dot8c_i32_i4_e32 v43, v135, v51
	v_dot8c_i32_i4_e32 v44, v137, v53
	v_dot8c_i32_i4_e32 v45, v137, v51
	v_and_b32_e32 v78, 0xffff, v29
	v_lshrrev_b32_e32 v79, 16, v29
	v_lshl_add_u32 v78, v78, 7, v150
	v_lshl_add_u32 v79, v79, 7, v151
	s_mov_b32 m0, s77
	s_add_i32 s43, s77, 0x400
	global_load_lds_dwordx4 v78, s[50:51]
	s_mov_b32 m0, s43
	s_nop 0
	global_load_lds_dwordx4 v79, s[50:51]
	s_waitcnt vmcnt(8)
	v_add_u32_e32 v54, s79, v59
	v_add_u32_e32 v55, s79, v60
	v_add_u32_e32 v56, s79, v61
	v_add_u32_e32 v57, s79, v62
	ds_read_b64_tr_b4 v[50:51], v160 offset:896
	ds_read_b64_tr_b4 v[52:53], v160 offset:1920
	ds_read_b64_tr_b4 v[130:131], v54
	ds_read_b64_tr_b4 v[132:133], v55
	ds_read_b64_tr_b4 v[134:135], v56
	ds_read_b64_tr_b4 v[136:137], v57
	s_waitcnt lgkmcnt(6)
	v_dot8c_i32_i4_e32 v38, v122, v48
	v_dot8c_i32_i4_e32 v39, v122, v46
	v_dot8c_i32_i4_e32 v40, v124, v48
	v_dot8c_i32_i4_e32 v41, v124, v46
	v_dot8c_i32_i4_e32 v42, v126, v48
	v_dot8c_i32_i4_e32 v43, v126, v46
	v_dot8c_i32_i4_e32 v44, v128, v48
	v_dot8c_i32_i4_e32 v45, v128, v46
	v_dot8c_i32_i4_e32 v38, v123, v49
	v_dot8c_i32_i4_e32 v39, v123, v47
	v_dot8c_i32_i4_e32 v40, v125, v49
	v_dot8c_i32_i4_e32 v41, v125, v47
	v_dot8c_i32_i4_e32 v42, v127, v49
	v_dot8c_i32_i4_e32 v43, v127, v47
	v_dot8c_i32_i4_e32 v44, v129, v49
	v_dot8c_i32_i4_e32 v45, v129, v47
	v_and_b32_e32 v78, 0xffff, v30
	v_lshrrev_b32_e32 v79, 16, v30
	v_lshl_add_u32 v78, v78, 7, v150
	v_lshl_add_u32 v79, v79, 7, v151
	s_mov_b32 m0, s78
	s_add_i32 s43, s78, 0x400
	global_load_lds_dwordx4 v78, s[50:51]
	s_mov_b32 m0, s43
	s_nop 0
	global_load_lds_dwordx4 v79, s[50:51]
	s_waitcnt vmcnt(8)
	v_add_u32_e32 v54, s98, v59
	v_add_u32_e32 v55, s98, v60
	v_add_u32_e32 v56, s98, v61
	v_add_u32_e32 v57, s98, v62
	ds_read_b64_tr_b4 v[46:47], v160
	ds_read_b64_tr_b4 v[48:49], v160 offset:1024
	ds_read_b64_tr_b4 v[122:123], v54
	ds_read_b64_tr_b4 v[124:125], v55
	ds_read_b64_tr_b4 v[126:127], v56
	ds_read_b64_tr_b4 v[128:129], v57
	s_waitcnt lgkmcnt(6)
	v_dot8c_i32_i4_e32 v38, v130, v52
	v_dot8c_i32_i4_e32 v39, v130, v50
	v_dot8c_i32_i4_e32 v40, v132, v52
	v_dot8c_i32_i4_e32 v41, v132, v50
	v_dot8c_i32_i4_e32 v42, v134, v52
	v_dot8c_i32_i4_e32 v43, v134, v50
	v_dot8c_i32_i4_e32 v44, v136, v52
	v_dot8c_i32_i4_e32 v45, v136, v50
	v_dot8c_i32_i4_e32 v38, v131, v53
	v_dot8c_i32_i4_e32 v39, v131, v51
	v_dot8c_i32_i4_e32 v40, v133, v53
	v_dot8c_i32_i4_e32 v41, v133, v51
	v_dot8c_i32_i4_e32 v42, v135, v53
	v_dot8c_i32_i4_e32 v43, v135, v51
	v_dot8c_i32_i4_e32 v44, v137, v53
	v_dot8c_i32_i4_e32 v45, v137, v51
	s_nop 3
	s_waitcnt lgkmcnt(15)
	v_lshlrev_b32_e32 v38, 5, v38
	v_lshlrev_b32_e32 v39, 1, v39
	v_add3_u32 v38, v39, v229, v38
	v_cvt_f32_i32_e32 v38, v38
	v_mul_f32_e32 v38, v228, v38
	v_lshlrev_b32_e32 v40, 5, v40
	v_lshlrev_b32_e32 v41, 1, v41
	v_add3_u32 v40, v41, v229, v40
	v_cvt_f32_i32_e32 v40, v40
	v_mul_f32_e32 v40, v228, v40
	v_lshlrev_b32_e32 v42, 5, v42
	v_lshlrev_b32_e32 v43, 1, v43
	v_add3_u32 v42, v43, v229, v42
	v_cvt_f32_i32_e32 v42, v42
	v_mul_f32_e32 v42, v228, v42
	v_lshlrev_b32_e32 v44, 5, v44
	v_lshlrev_b32_e32 v45, 1, v45
	v_add3_u32 v44, v45, v229, v44
	v_cvt_f32_i32_e32 v44, v44
	v_mul_f32_e32 v44, v228, v44
	v_cvt_pk_bf16_f32 v166, v38, v40
	v_cvt_pk_bf16_f32 v167, v42, v44
	v_add_u32_e32 v147, 8, v140
	v_and_b32_e32 v146, 15, v147
	v_xor_b32_e32 v146, 8, v146
	v_bfe_u32 v148, v147, 4, 4
	v_mul_lo_u32 v146, v146, s92
	v_mul_lo_u32 v148, v148, s92
	v_mov_b32_e32 v147, v146
	v_mov_b32_e32 v149, v148
	ds_write2st64_b64 v77, v[146:147], v[148:149] offset1:2
	v_mov_b32_e32 v138, v74
	ds_read_u8 v139, v138
	v_mov_b32_e32 v141, v73
	ds_read_u8 v140, v141
	s_add_i32 s43, s67, 32
	v_mov_b32_e32 v138, s43
	ds_read2st64_b32 v[228:229], v138 offset1:1
	ds_read_b128 v[18:21], v227
	ds_read_b128 v[22:25], v227 offset:16
	v_add_u32_e32 v152, 0x600000, v63
	v_add_u32_e32 v153, 0x600000, v64
	v_mov_b32_e32 v38, 0
	v_mov_b32_e32 v39, 0
	v_mov_b32_e32 v40, 0
	v_mov_b32_e32 v41, 0
	v_mov_b32_e32 v42, 0
	v_mov_b32_e32 v43, 0
	v_mov_b32_e32 v44, 0
	v_mov_b32_e32 v45, 0
	v_and_b32_e32 v78, 0xffff, v31
	v_lshrrev_b32_e32 v79, 16, v31
	v_lshl_add_u32 v78, v78, 7, v150
	v_lshl_add_u32 v79, v79, 7, v151
	s_mov_b32 m0, s79
	s_add_i32 s43, s79, 0x400
	global_load_lds_dwordx4 v78, s[50:51]
	s_mov_b32 m0, s43
	s_nop 0
	global_load_lds_dwordx4 v79, s[50:51]
	s_waitcnt vmcnt(8)
; #define TR4(p_) __builtin_amdgcn_ds_read_tr4_b64_v2i32((LAS v2i*)(p_))
; #define VDMA(st_, k_) do { _Pragma("unroll") for (int i_ = 0; i_ < 4; ++i_) { \
;         const unsigned off_ = (unsigned)((st_) >> 2) * (16384u * 128u) + (PE_ID(E, 4 * ((st_) & 3) + i_) << 7) + ((i_ & 1) ? cx1 : cx0); \
;         __builtin_amdgcn_global_load_lds((const unsigned*)(V4 + off_), (LAS unsigned*)(ldsb + BUF[k_] + 1024 * i_), 16, 0, 0); } } while (0)
; __device__ __forceinline__ void peer_v_tokens(int j, const LAS unsigned short* EL, const LAS unsigned char* AL  , const LAS float* ASC  , const LAS int* SAL  , ...
;     ...
;         for (int st = 0; st < 16; ++st) {
;             const int p = st >> 2, q = st & 3;
;             if (st < 14) VDMA(st + 2, (st + 2) % 3);
;             if (st < 14) asm volatile("s_waitcnt vmcnt(8)" ::: "memory");
;             else if (st == 14) asm volatile("s_waitcnt vmcnt(4)" ::: "memory");
;             else asm volatile("s_waitcnt vmcnt(0)" ::: "memory");
;             if (q == 0) {
; #pragma unroll
;                 for (int r = 0; r < 4; ++r) { accH[r] = 0; accL[r] = 0; } }
; #pragma unroll
;             for (int tp = 0; tp < 2; ++tp) {
;                 const v2i ao = TR4(ATL + (2 * q + tp) * 128 + 8 * s16), ah = TR4(ATL + 1024 + (2 * q + tp) * 128 + 8 * s16);
; #pragma unroll
;                 for (int r = 0; r < 4; ++r) {
;                     const v2i d = TR4(ldsb + BUF[st % 3] + 2048 * tp + roff[r]);
;                     accH[r] = __builtin_amdgcn_sdot8(d.x, ah.x, accH[r], false); accH[r] = __builtin_amdgcn_sdot8(d.y, ah.y, accH[r], false);
;                     accL[r] = __builtin_amdgcn_sdot8(d.x, ao.x, accL[r], false); accL[r] = __builtin_amdgcn_sdot8(d.y, ao.y, accL[r], false);
;                 }
;             }
	v_add_u32_e32 v54, s99, v59
	v_add_u32_e32 v55, s99, v60
	v_add_u32_e32 v56, s99, v61
	v_add_u32_e32 v57, s99, v62
	ds_read_b64_tr_b4 v[50:51], v160 offset:128
	ds_read_b64_tr_b4 v[52:53], v160 offset:1152
	ds_read_b64_tr_b4 v[130:131], v54
	ds_read_b64_tr_b4 v[132:133], v55
	ds_read_b64_tr_b4 v[134:135], v56
	ds_read_b64_tr_b4 v[136:137], v57
	s_waitcnt lgkmcnt(12)
	v_dot8c_i32_i4_e32 v38, v122, v48
	v_dot8c_i32_i4_e32 v39, v122, v46
	v_dot8c_i32_i4_e32 v40, v124, v48
	v_dot8c_i32_i4_e32 v41, v124, v46
	v_dot8c_i32_i4_e32 v42, v126, v48
	v_dot8c_i32_i4_e32 v43, v126, v46
	v_dot8c_i32_i4_e32 v44, v128, v48
	v_dot8c_i32_i4_e32 v45, v128, v46
	v_dot8c_i32_i4_e32 v38, v123, v49
	v_dot8c_i32_i4_e32 v39, v123, v47
	v_dot8c_i32_i4_e32 v40, v125, v49
	v_dot8c_i32_i4_e32 v41, v125, v47
	v_dot8c_i32_i4_e32 v42, v127, v49
	v_dot8c_i32_i4_e32 v43, v127, v47
	v_dot8c_i32_i4_e32 v44, v129, v49
	v_dot8c_i32_i4_e32 v45, v129, v47
	v_and_b32_e32 v78, 0xffff, v32
	v_lshrrev_b32_e32 v79, 16, v32
	v_lshl_add_u32 v78, v78, 7, v150
	v_lshl_add_u32 v79, v79, 7, v151
	s_mov_b32 m0, s98
	s_add_i32 s43, s98, 0x400
	global_load_lds_dwordx4 v78, s[50:51]
	s_mov_b32 m0, s43
	s_nop 0
	global_load_lds_dwordx4 v79, s[50:51]
	s_waitcnt vmcnt(8)
	v_add_u32_e32 v54, s76, v59
	v_add_u32_e32 v55, s76, v60
	v_add_u32_e32 v56, s76, v61
	v_add_u32_e32 v57, s76, v62
	ds_read_b64_tr_b4 v[46:47], v160 offset:256
	ds_read_b64_tr_b4 v[48:49], v160 offset:1280
	ds_read_b64_tr_b4 v[122:123], v54
	ds_read_b64_tr_b4 v[124:125], v55
	ds_read_b64_tr_b4 v[126:127], v56
	ds_read_b64_tr_b4 v[128:129], v57
	s_waitcnt lgkmcnt(6)
	v_dot8c_i32_i4_e32 v38, v130, v52
	v_dot8c_i32_i4_e32 v39, v130, v50
	v_dot8c_i32_i4_e32 v40, v132, v52
	v_dot8c_i32_i4_e32 v41, v132, v50
	v_dot8c_i32_i4_e32 v42, v134, v52
	v_dot8c_i32_i4_e32 v43, v134, v50
	v_dot8c_i32_i4_e32 v44, v136, v52
	v_dot8c_i32_i4_e32 v45, v136, v50
	v_dot8c_i32_i4_e32 v38, v131, v53
	v_dot8c_i32_i4_e32 v39, v131, v51
	v_dot8c_i32_i4_e32 v40, v133, v53
	v_dot8c_i32_i4_e32 v41, v133, v51
	v_dot8c_i32_i4_e32 v42, v135, v53
	v_dot8c_i32_i4_e32 v43, v135, v51
	v_dot8c_i32_i4_e32 v44, v137, v53
	v_dot8c_i32_i4_e32 v45, v137, v51
	v_and_b32_e32 v78, 0xffff, v33
	v_lshrrev_b32_e32 v79, 16, v33
	v_lshl_add_u32 v78, v78, 7, v150
	v_lshl_add_u32 v79, v79, 7, v151
	s_mov_b32 m0, s99
	s_add_i32 s43, s99, 0x400
	global_load_lds_dwordx4 v78, s[50:51]
	s_mov_b32 m0, s43
	s_nop 0
	global_load_lds_dwordx4 v79, s[50:51]
	s_waitcnt vmcnt(8)
	v_add_u32_e32 v54, s77, v59
	v_add_u32_e32 v55, s77, v60
	v_add_u32_e32 v56, s77, v61
	v_add_u32_e32 v57, s77, v62
	ds_read_b64_tr_b4 v[50:51], v160 offset:384
	ds_read_b64_tr_b4 v[52:53], v160 offset:1408
	ds_read_b64_tr_b4 v[130:131], v54
	ds_read_b64_tr_b4 v[132:133], v55
	ds_read_b64_tr_b4 v[134:135], v56
	ds_read_b64_tr_b4 v[136:137], v57
	s_waitcnt lgkmcnt(6)
	v_dot8c_i32_i4_e32 v38, v122, v48
	v_dot8c_i32_i4_e32 v39, v122, v46
	v_dot8c_i32_i4_e32 v40, v124, v48
	v_dot8c_i32_i4_e32 v41, v124, v46
	v_dot8c_i32_i4_e32 v42, v126, v48
	v_dot8c_i32_i4_e32 v43, v126, v46
	v_dot8c_i32_i4_e32 v44, v128, v48
	v_dot8c_i32_i4_e32 v45, v128, v46
	v_dot8c_i32_i4_e32 v38, v123, v49
	v_dot8c_i32_i4_e32 v39, v123, v47
	v_dot8c_i32_i4_e32 v40, v125, v49
	v_dot8c_i32_i4_e32 v41, v125, v47
	v_dot8c_i32_i4_e32 v42, v127, v49
	v_dot8c_i32_i4_e32 v43, v127, v47
	v_dot8c_i32_i4_e32 v44, v129, v49
	v_dot8c_i32_i4_e32 v45, v129, v47
	s_waitcnt lgkmcnt(15)
	v_and_b32_e32 v78, 0xffff, v18
	v_lshrrev_b32_e32 v79, 16, v18
	v_lshl_add_u32 v78, v78, 7, v152
	v_lshl_add_u32 v79, v79, 7, v153
	s_mov_b32 m0, s76
	s_add_i32 s43, s76, 0x400
	global_load_lds_dwordx4 v78, s[50:51]
	s_mov_b32 m0, s43
	s_nop 0
	global_load_lds_dwordx4 v79, s[50:51]
	s_waitcnt vmcnt(8)
	v_add_u32_e32 v54, s78, v59
	v_add_u32_e32 v55, s78, v60
	v_add_u32_e32 v56, s78, v61
	v_add_u32_e32 v57, s78, v62
	ds_read_b64_tr_b4 v[46:47], v160 offset:512
	ds_read_b64_tr_b4 v[48:49], v160 offset:1536
	ds_read_b64_tr_b4 v[122:123], v54
	ds_read_b64_tr_b4 v[124:125], v55
	ds_read_b64_tr_b4 v[126:127], v56
	ds_read_b64_tr_b4 v[128:129], v57
	s_waitcnt lgkmcnt(6)
	v_dot8c_i32_i4_e32 v38, v130, v52
	v_dot8c_i32_i4_e32 v39, v130, v50
	v_dot8c_i32_i4_e32 v40, v132, v52
	v_dot8c_i32_i4_e32 v41, v132, v50
	v_dot8c_i32_i4_e32 v42, v134, v52
	v_dot8c_i32_i4_e32 v43, v134, v50
	v_dot8c_i32_i4_e32 v44, v136, v52
	v_dot8c_i32_i4_e32 v45, v136, v50
	v_dot8c_i32_i4_e32 v38, v131, v53
	v_dot8c_i32_i4_e32 v39, v131, v51
	v_dot8c_i32_i4_e32 v40, v133, v53
	v_dot8c_i32_i4_e32 v41, v133, v51
	v_dot8c_i32_i4_e32 v42, v135, v53
	v_dot8c_i32_i4_e32 v43, v135, v51
	v_dot8c_i32_i4_e32 v44, v137, v53
	v_dot8c_i32_i4_e32 v45, v137, v51
	v_and_b32_e32 v78, 0xffff, v19
	v_lshrrev_b32_e32 v79, 16, v19
	v_lshl_add_u32 v78, v78, 7, v152
	v_lshl_add_u32 v79, v79, 7, v153
	s_mov_b32 m0, s77
	s_add_i32 s43, s77, 0x400
	global_load_lds_dwordx4 v78, s[50:51]
	s_mov_b32 m0, s43
	s_nop 0
	global_load_lds_dwordx4 v79, s[50:51]
	s_waitcnt vmcnt(8)
	v_add_u32_e32 v54, s79, v59
	v_add_u32_e32 v55, s79, v60
	v_add_u32_e32 v56, s79, v61
	v_add_u32_e32 v57, s79, v62
	ds_read_b64_tr_b4 v[50:51], v160 offset:640
	ds_read_b64_tr_b4 v[52:53], v160 offset:1664
	ds_read_b64_tr_b4 v[130:131], v54
	ds_read_b64_tr_b4 v[132:133], v55
	ds_read_b64_tr_b4 v[134:135], v56
	ds_read_b64_tr_b4 v[136:137], v57
	s_waitcnt lgkmcnt(6)
	v_dot8c_i32_i4_e32 v38, v122, v48
	v_dot8c_i32_i4_e32 v39, v122, v46
	v_dot8c_i32_i4_e32 v40, v124, v48
	v_dot8c_i32_i4_e32 v41, v124, v46
	v_dot8c_i32_i4_e32 v42, v126, v48
	v_dot8c_i32_i4_e32 v43, v126, v46
	v_dot8c_i32_i4_e32 v44, v128, v48
	v_dot8c_i32_i4_e32 v45, v128, v46
	v_dot8c_i32_i4_e32 v38, v123, v49
	v_dot8c_i32_i4_e32 v39, v123, v47
	v_dot8c_i32_i4_e32 v40, v125, v49
	v_dot8c_i32_i4_e32 v41, v125, v47
	v_dot8c_i32_i4_e32 v42, v127, v49
	v_dot8c_i32_i4_e32 v43, v127, v47
	v_dot8c_i32_i4_e32 v44, v129, v49
	v_dot8c_i32_i4_e32 v45, v129, v47
	s_waitcnt lgkmcnt(15)
; __device__ __forceinline__ void peer_v_tokens(int j, const LAS unsigned short* EL, const LAS unsigned char* AL  , const LAS float* ASC  , const LAS int* SAL  , ...
;     ...
;         for (int m = 0; m < 2; ++m) {
;             const int idx = lane + 64 * m, tau = idx >> 4, sr = idx & 15, k = 16 * (sr & 7) + 2 * tau + (sr >> 3);
;             const int aq = (int)*(const LAS signed char*)(AL + tl * 128 + k); const int tq = aq + 8;
;             const unsigned lo = (((unsigned)tq & 15u) ^ 8u) * 0x11111111u, hi = ((unsigned)(tq >> 4) & 15u) * 0x11111111u;
;             typedef unsigned u2v __attribute__((ext_vector_type(2)));
;             u2v l2; l2.x = lo; l2.y = lo; u2v h2; h2.x = hi; h2.y = hi;
;             *(LAS u2v*)(ATL + 8 * idx) = l2; *(LAS u2v*)(ATL + 1024 + 8 * idx) = h2;
;         }
;         const float asc = ASC[tl]; const int sa = SAL[tl];
;         CFENCE();
;         int accH[4], accL[4];
; #pragma unroll
;         for (int st = 0; st < 16; ++st) {
;             const int p = st >> 2, q = st & 3;
;             if (st < 14) VDMA(st + 2, (st + 2) % 3);
;             if (st < 14) asm volatile("s_waitcnt vmcnt(8)" ::: "memory");
;             else if (st == 14) asm volatile("s_waitcnt vmcnt(4)" ::: "memory");
;             else asm volatile("s_waitcnt vmcnt(0)" ::: "memory");
;             if (q == 0) {
; #pragma unroll
;                 for (int r = 0; r < 4; ++r) { accH[r] = 0; accL[r] = 0; } }
; #pragma unroll
;             for (int tp = 0; tp < 2; ++tp) {
;                 const v2i ao = TR4(ATL + (2 * q + tp) * 128 + 8 * s16), ah = TR4(ATL + 1024 + (2 * q + tp) * 128 + 8 * s16);
; #pragma unroll
;                 for (int r = 0; r < 4; ++r) {
;                     const v2i d = TR4(ldsb + BUF[st % 3] + 2048 * tp + roff[r]);
;                     accH[r] = __builtin_amdgcn_sdot8(d.x, ah.x, accH[r], false); accH[r] = __builtin_amdgcn_sdot8(d.y, ah.y, accH[r], false);
;                     accL[r] = __builtin_amdgcn_sdot8(d.x, ao.x, accL[r], false); accL[r] = __builtin_amdgcn_sdot8(d.y, ao.y, accL[r], false);
;                 }
;             }
;             asm volatile("s_waitcnt lgkmcnt(0)" ::: "memory");
;             if (q == 3) {
; #pragma unroll
;                 for (int r = 0; r < 4; ++r) STASH[256 * p + 16 * (grp + 4 * r) + pc] = f2bf(asc * (float)(2 * ((accH[r] << 4) + accL[r]) + sa));
;             }
	v_add_u32_e32 v143, 8, v139
	v_and_b32_e32 v142, 15, v143
	v_xor_b32_e32 v142, 8, v142
	v_bfe_u32 v144, v143, 4, 4
	v_mul_lo_u32 v142, v142, s92
	v_mul_lo_u32 v144, v144, s92
	v_mov_b32_e32 v143, v142
	v_mov_b32_e32 v145, v144
	ds_write2st64_b64 v159, v[142:143], v[144:145] offset1:2
	v_and_b32_e32 v78, 0xffff, v20
	v_lshrrev_b32_e32 v79, 16, v20
	v_lshl_add_u32 v78, v78, 7, v152
	v_lshl_add_u32 v79, v79, 7, v153
	s_mov_b32 m0, s78
	s_add_i32 s43, s78, 0x400
	global_load_lds_dwordx4 v78, s[50:51]
	s_mov_b32 m0, s43
	s_nop 0
	global_load_lds_dwordx4 v79, s[50:51]
	s_waitcnt vmcnt(8)
	v_add_u32_e32 v54, s98, v59
	v_add_u32_e32 v55, s98, v60
	v_add_u32_e32 v56, s98, v61
	v_add_u32_e32 v57, s98, v62
	ds_read_b64_tr_b4 v[46:47], v160 offset:768
	ds_read_b64_tr_b4 v[48:49], v160 offset:1792
	ds_read_b64_tr_b4 v[122:123], v54
	ds_read_b64_tr_b4 v[124:125], v55
	ds_read_b64_tr_b4 v[126:127], v56
	ds_read_b64_tr_b4 v[128:129], v57
	s_waitcnt lgkmcnt(7)
	v_dot8c_i32_i4_e32 v38, v130, v52
	v_dot8c_i32_i4_e32 v39, v130, v50
	v_dot8c_i32_i4_e32 v40, v132, v52
	v_dot8c_i32_i4_e32 v41, v132, v50
	v_dot8c_i32_i4_e32 v42, v134, v52
	v_dot8c_i32_i4_e32 v43, v134, v50
	v_dot8c_i32_i4_e32 v44, v136, v52
	v_dot8c_i32_i4_e32 v45, v136, v50
	v_dot8c_i32_i4_e32 v38, v131, v53
	v_dot8c_i32_i4_e32 v39, v131, v51
	v_dot8c_i32_i4_e32 v40, v133, v53
	v_dot8c_i32_i4_e32 v41, v133, v51
	v_dot8c_i32_i4_e32 v42, v135, v53
	v_dot8c_i32_i4_e32 v43, v135, v51
	v_dot8c_i32_i4_e32 v44, v137, v53
	v_dot8c_i32_i4_e32 v45, v137, v51
	v_and_b32_e32 v78, 0xffff, v21
	v_lshrrev_b32_e32 v79, 16, v21
	v_lshl_add_u32 v78, v78, 7, v152
	v_lshl_add_u32 v79, v79, 7, v153
	s_mov_b32 m0, s79
	s_add_i32 s43, s79, 0x400
	global_load_lds_dwordx4 v78, s[50:51]
	s_mov_b32 m0, s43
	s_nop 0
	global_load_lds_dwordx4 v79, s[50:51]
	s_waitcnt vmcnt(8)
	v_add_u32_e32 v54, s99, v59
	v_add_u32_e32 v55, s99, v60
	v_add_u32_e32 v56, s99, v61
	v_add_u32_e32 v57, s99, v62
	ds_read_b64_tr_b4 v[50:51], v160 offset:896
	ds_read_b64_tr_b4 v[52:53], v160 offset:1920
	ds_read_b64_tr_b4 v[130:131], v54
	ds_read_b64_tr_b4 v[132:133], v55
	ds_read_b64_tr_b4 v[134:135], v56
	ds_read_b64_tr_b4 v[136:137], v57
	s_waitcnt lgkmcnt(6)
	v_dot8c_i32_i4_e32 v38, v122, v48
	v_dot8c_i32_i4_e32 v39, v122, v46
	v_dot8c_i32_i4_e32 v40, v124, v48
	v_dot8c_i32_i4_e32 v41, v124, v46
	v_dot8c_i32_i4_e32 v42, v126, v48
	v_dot8c_i32_i4_e32 v43, v126, v46
	v_dot8c_i32_i4_e32 v44, v128, v48
	v_dot8c_i32_i4_e32 v45, v128, v46
	v_dot8c_i32_i4_e32 v38, v123, v49
	v_dot8c_i32_i4_e32 v39, v123, v47
	v_dot8c_i32_i4_e32 v40, v125, v49
	v_dot8c_i32_i4_e32 v41, v125, v47
	v_dot8c_i32_i4_e32 v42, v127, v49
	v_dot8c_i32_i4_e32 v43, v127, v47
	v_dot8c_i32_i4_e32 v44, v129, v49
	v_dot8c_i32_i4_e32 v45, v129, v47
	v_and_b32_e32 v78, 0xffff, v22
	v_lshrrev_b32_e32 v79, 16, v22
	v_lshl_add_u32 v78, v78, 7, v152
	v_lshl_add_u32 v79, v79, 7, v153
	s_mov_b32 m0, s98
	s_add_i32 s43, s98, 0x400
	global_load_lds_dwordx4 v78, s[50:51]
	s_mov_b32 m0, s43
	s_nop 0
	global_load_lds_dwordx4 v79, s[50:51]
	s_waitcnt vmcnt(8)
	v_add_u32_e32 v54, s76, v59
	v_add_u32_e32 v55, s76, v60
	v_add_u32_e32 v56, s76, v61
	v_add_u32_e32 v57, s76, v62
	ds_read_b64_tr_b4 v[46:47], v160
	ds_read_b64_tr_b4 v[48:49], v160 offset:1024
	ds_read_b64_tr_b4 v[122:123], v54
	ds_read_b64_tr_b4 v[124:125], v55
	ds_read_b64_tr_b4 v[126:127], v56
	ds_read_b64_tr_b4 v[128:129], v57
	s_waitcnt lgkmcnt(6)
	v_dot8c_i32_i4_e32 v38, v130, v52
	v_dot8c_i32_i4_e32 v39, v130, v50
	v_dot8c_i32_i4_e32 v40, v132, v52
	v_dot8c_i32_i4_e32 v41, v132, v50
	v_dot8c_i32_i4_e32 v42, v134, v52
	v_dot8c_i32_i4_e32 v43, v134, v50
	v_dot8c_i32_i4_e32 v44, v136, v52
	v_dot8c_i32_i4_e32 v45, v136, v50
	v_dot8c_i32_i4_e32 v38, v131, v53
	v_dot8c_i32_i4_e32 v39, v131, v51
	v_dot8c_i32_i4_e32 v40, v133, v53
	v_dot8c_i32_i4_e32 v41, v133, v51
	v_dot8c_i32_i4_e32 v42, v135, v53
	v_dot8c_i32_i4_e32 v43, v135, v51
	v_dot8c_i32_i4_e32 v44, v137, v53
	v_dot8c_i32_i4_e32 v45, v137, v51
	s_nop 3
	s_waitcnt lgkmcnt(15)
	v_lshlrev_b32_e32 v38, 5, v38
	v_lshlrev_b32_e32 v39, 1, v39
	v_add3_u32 v38, v39, v229, v38
	v_cvt_f32_i32_e32 v38, v38
	v_mul_f32_e32 v38, v228, v38
	v_lshlrev_b32_e32 v40, 5, v40
	v_lshlrev_b32_e32 v41, 1, v41
	v_add3_u32 v40, v41, v229, v40
	v_cvt_f32_i32_e32 v40, v40
	v_mul_f32_e32 v40, v228, v40
	v_lshlrev_b32_e32 v42, 5, v42
	v_lshlrev_b32_e32 v43, 1, v43
	v_add3_u32 v42, v43, v229, v42
	v_cvt_f32_i32_e32 v42, v42
	v_mul_f32_e32 v42, v228, v42
	v_lshlrev_b32_e32 v44, 5, v44
	v_lshlrev_b32_e32 v45, 1, v45
	v_add3_u32 v44, v45, v229, v44
	v_cvt_f32_i32_e32 v44, v44
	v_mul_f32_e32 v44, v228, v44
	v_cvt_pk_bf16_f32 v174, v38, v40
	v_cvt_pk_bf16_f32 v175, v42, v44
	v_add_u32_e32 v147, 8, v140
	v_and_b32_e32 v146, 15, v147
	v_xor_b32_e32 v146, 8, v146
	v_bfe_u32 v148, v147, 4, 4
	v_mul_lo_u32 v146, v146, s92
	v_mul_lo_u32 v148, v148, s92
	v_mov_b32_e32 v147, v146
	v_mov_b32_e32 v149, v148
	ds_write2st64_b64 v77, v[146:147], v[148:149] offset1:2
	v_add_u32_e32 v138, 0x400, v74
	ds_read_u8 v139, v138
	v_add_u32_e32 v141, 0x400, v73
	ds_read_u8 v140, v141
	s_mov_b32 s43, s67
	v_mov_b32_e32 v138, s43
	ds_read2st64_b32 v[228:229], v138 offset1:1
	ds_read_b128 v[26:29], v227 offset:2048
	ds_read_b128 v[30:33], v227 offset:2064
	v_mov_b32_e32 v38, 0
	v_mov_b32_e32 v39, 0
	v_mov_b32_e32 v40, 0
	v_mov_b32_e32 v41, 0
	v_mov_b32_e32 v42, 0
	v_mov_b32_e32 v43, 0
	v_mov_b32_e32 v44, 0
	v_mov_b32_e32 v45, 0
	v_and_b32_e32 v78, 0xffff, v23
	v_lshrrev_b32_e32 v79, 16, v23
	v_lshl_add_u32 v78, v78, 7, v152
	v_lshl_add_u32 v79, v79, 7, v153
	s_mov_b32 m0, s99
	s_add_i32 s43, s99, 0x400
	global_load_lds_dwordx4 v78, s[50:51]
	s_mov_b32 m0, s43
	s_nop 0
	global_load_lds_dwordx4 v79, s[50:51]
	s_waitcnt vmcnt(8)
; #define TR4(p_) __builtin_amdgcn_ds_read_tr4_b64_v2i32((LAS v2i*)(p_))
; #define VDMA(st_, k_) do { _Pragma("unroll") for (int i_ = 0; i_ < 4; ++i_) { \
;         const unsigned off_ = (unsigned)((st_) >> 2) * (16384u * 128u) + (PE_ID(E, 4 * ((st_) & 3) + i_) << 7) + ((i_ & 1) ? cx1 : cx0); \
;         __builtin_amdgcn_global_load_lds((const unsigned*)(V4 + off_), (LAS unsigned*)(ldsb + BUF[k_] + 1024 * i_), 16, 0, 0); } } while (0)
; __device__ __forceinline__ void peer_v_tokens(int j, const LAS unsigned short* EL, const LAS unsigned char* AL  , const LAS float* ASC  , const LAS int* SAL  , ...
;     ...
;         for (int st = 0; st < 16; ++st) {
;             const int p = st >> 2, q = st & 3;
;             if (st < 14) VDMA(st + 2, (st + 2) % 3);
;             if (st < 14) asm volatile("s_waitcnt vmcnt(8)" ::: "memory");
;             else if (st == 14) asm volatile("s_waitcnt vmcnt(4)" ::: "memory");
;             else asm volatile("s_waitcnt vmcnt(0)" ::: "memory");
;             if (q == 0) {
; #pragma unroll
;                 for (int r = 0; r < 4; ++r) { accH[r] = 0; accL[r] = 0; } }
; #pragma unroll
;             for (int tp = 0; tp < 2; ++tp) {
;                 const v2i ao = TR4(ATL + (2 * q + tp) * 128 + 8 * s16), ah = TR4(ATL + 1024 + (2 * q + tp) * 128 + 8 * s16);
; #pragma unroll
;                 for (int r = 0; r < 4; ++r) {
;                     const v2i d = TR4(ldsb + BUF[st % 3] + 2048 * tp + roff[r]);
;                     accH[r] = __builtin_amdgcn_sdot8(d.x, ah.x, accH[r], false); accH[r] = __builtin_amdgcn_sdot8(d.y, ah.y, accH[r], false);
;                     accL[r] = __builtin_amdgcn_sdot8(d.x, ao.x, accL[r], false); accL[r] = __builtin_amdgcn_sdot8(d.y, ao.y, accL[r], false);
;                 }
;             }
	v_add_u32_e32 v54, s77, v59
	v_add_u32_e32 v55, s77, v60
	v_add_u32_e32 v56, s77, v61
	v_add_u32_e32 v57, s77, v62
	ds_read_b64_tr_b4 v[50:51], v160 offset:128
	ds_read_b64_tr_b4 v[52:53], v160 offset:1152
	ds_read_b64_tr_b4 v[130:131], v54
	ds_read_b64_tr_b4 v[132:133], v55
	ds_read_b64_tr_b4 v[134:135], v56
	ds_read_b64_tr_b4 v[136:137], v57
	s_waitcnt lgkmcnt(12)
	v_dot8c_i32_i4_e32 v38, v122, v48
	v_dot8c_i32_i4_e32 v39, v122, v46
	v_dot8c_i32_i4_e32 v40, v124, v48
	v_dot8c_i32_i4_e32 v41, v124, v46
	v_dot8c_i32_i4_e32 v42, v126, v48
	v_dot8c_i32_i4_e32 v43, v126, v46
	v_dot8c_i32_i4_e32 v44, v128, v48
	v_dot8c_i32_i4_e32 v45, v128, v46
	v_dot8c_i32_i4_e32 v38, v123, v49
	v_dot8c_i32_i4_e32 v39, v123, v47
	v_dot8c_i32_i4_e32 v40, v125, v49
	v_dot8c_i32_i4_e32 v41, v125, v47
	v_dot8c_i32_i4_e32 v42, v127, v49
	v_dot8c_i32_i4_e32 v43, v127, v47
	v_dot8c_i32_i4_e32 v44, v129, v49
	v_dot8c_i32_i4_e32 v45, v129, v47
	v_and_b32_e32 v78, 0xffff, v24
	v_lshrrev_b32_e32 v79, 16, v24
	v_lshl_add_u32 v78, v78, 7, v152
	v_lshl_add_u32 v79, v79, 7, v153
	s_mov_b32 m0, s76
	s_add_i32 s43, s76, 0x400
	global_load_lds_dwordx4 v78, s[50:51]
	s_mov_b32 m0, s43
	s_nop 0
	global_load_lds_dwordx4 v79, s[50:51]
	s_waitcnt vmcnt(8)
	v_add_u32_e32 v54, s78, v59
	v_add_u32_e32 v55, s78, v60
	v_add_u32_e32 v56, s78, v61
	v_add_u32_e32 v57, s78, v62
	ds_read_b64_tr_b4 v[46:47], v160 offset:256
	ds_read_b64_tr_b4 v[48:49], v160 offset:1280
	ds_read_b64_tr_b4 v[122:123], v54
	ds_read_b64_tr_b4 v[124:125], v55
	ds_read_b64_tr_b4 v[126:127], v56
	ds_read_b64_tr_b4 v[128:129], v57
	s_waitcnt lgkmcnt(6)
	v_dot8c_i32_i4_e32 v38, v130, v52
	v_dot8c_i32_i4_e32 v39, v130, v50
	v_dot8c_i32_i4_e32 v40, v132, v52
	v_dot8c_i32_i4_e32 v41, v132, v50
	v_dot8c_i32_i4_e32 v42, v134, v52
	v_dot8c_i32_i4_e32 v43, v134, v50
	v_dot8c_i32_i4_e32 v44, v136, v52
	v_dot8c_i32_i4_e32 v45, v136, v50
	v_dot8c_i32_i4_e32 v38, v131, v53
	v_dot8c_i32_i4_e32 v39, v131, v51
	v_dot8c_i32_i4_e32 v40, v133, v53
	v_dot8c_i32_i4_e32 v41, v133, v51
	v_dot8c_i32_i4_e32 v42, v135, v53
	v_dot8c_i32_i4_e32 v43, v135, v51
	v_dot8c_i32_i4_e32 v44, v137, v53
	v_dot8c_i32_i4_e32 v45, v137, v51
	v_and_b32_e32 v78, 0xffff, v25
	v_lshrrev_b32_e32 v79, 16, v25
	v_lshl_add_u32 v78, v78, 7, v152
	v_lshl_add_u32 v79, v79, 7, v153
	s_mov_b32 m0, s77
	s_add_i32 s43, s77, 0x400
	global_load_lds_dwordx4 v78, s[50:51]
	s_mov_b32 m0, s43
	s_nop 0
	global_load_lds_dwordx4 v79, s[50:51]
	s_waitcnt vmcnt(8)
	v_add_u32_e32 v54, s79, v59
	v_add_u32_e32 v55, s79, v60
	v_add_u32_e32 v56, s79, v61
	v_add_u32_e32 v57, s79, v62
	ds_read_b64_tr_b4 v[50:51], v160 offset:384
	ds_read_b64_tr_b4 v[52:53], v160 offset:1408
	ds_read_b64_tr_b4 v[130:131], v54
	ds_read_b64_tr_b4 v[132:133], v55
	ds_read_b64_tr_b4 v[134:135], v56
	ds_read_b64_tr_b4 v[136:137], v57
	s_waitcnt lgkmcnt(6)
	v_dot8c_i32_i4_e32 v38, v122, v48
	v_dot8c_i32_i4_e32 v39, v122, v46
	v_dot8c_i32_i4_e32 v40, v124, v48
	v_dot8c_i32_i4_e32 v41, v124, v46
	v_dot8c_i32_i4_e32 v42, v126, v48
	v_dot8c_i32_i4_e32 v43, v126, v46
	v_dot8c_i32_i4_e32 v44, v128, v48
	v_dot8c_i32_i4_e32 v45, v128, v46
	v_dot8c_i32_i4_e32 v38, v123, v49
	v_dot8c_i32_i4_e32 v39, v123, v47
	v_dot8c_i32_i4_e32 v40, v125, v49
	v_dot8c_i32_i4_e32 v41, v125, v47
	v_dot8c_i32_i4_e32 v42, v127, v49
	v_dot8c_i32_i4_e32 v43, v127, v47
	v_dot8c_i32_i4_e32 v44, v129, v49
	v_dot8c_i32_i4_e32 v45, v129, v47
	s_waitcnt lgkmcnt(15)
	v_and_b32_e32 v78, 0xffff, v26
	v_lshrrev_b32_e32 v79, 16, v26
	v_lshl_add_u32 v78, v78, 7, v152
	v_lshl_add_u32 v79, v79, 7, v153
	s_mov_b32 m0, s78
	s_add_i32 s43, s78, 0x400
	global_load_lds_dwordx4 v78, s[50:51]
	s_mov_b32 m0, s43
	s_nop 0
	global_load_lds_dwordx4 v79, s[50:51]
	s_waitcnt vmcnt(8)
	v_add_u32_e32 v54, s98, v59
	v_add_u32_e32 v55, s98, v60
	v_add_u32_e32 v56, s98, v61
	v_add_u32_e32 v57, s98, v62
	ds_read_b64_tr_b4 v[46:47], v160 offset:512
	ds_read_b64_tr_b4 v[48:49], v160 offset:1536
	ds_read_b64_tr_b4 v[122:123], v54
	ds_read_b64_tr_b4 v[124:125], v55
	ds_read_b64_tr_b4 v[126:127], v56
	ds_read_b64_tr_b4 v[128:129], v57
	s_waitcnt lgkmcnt(6)
	v_dot8c_i32_i4_e32 v38, v130, v52
	v_dot8c_i32_i4_e32 v39, v130, v50
	v_dot8c_i32_i4_e32 v40, v132, v52
	v_dot8c_i32_i4_e32 v41, v132, v50
	v_dot8c_i32_i4_e32 v42, v134, v52
	v_dot8c_i32_i4_e32 v43, v134, v50
	v_dot8c_i32_i4_e32 v44, v136, v52
	v_dot8c_i32_i4_e32 v45, v136, v50
	v_dot8c_i32_i4_e32 v38, v131, v53
	v_dot8c_i32_i4_e32 v39, v131, v51
	v_dot8c_i32_i4_e32 v40, v133, v53
	v_dot8c_i32_i4_e32 v41, v133, v51
	v_dot8c_i32_i4_e32 v42, v135, v53
	v_dot8c_i32_i4_e32 v43, v135, v51
	v_dot8c_i32_i4_e32 v44, v137, v53
	v_dot8c_i32_i4_e32 v45, v137, v51
	v_and_b32_e32 v78, 0xffff, v27
	v_lshrrev_b32_e32 v79, 16, v27
	v_lshl_add_u32 v78, v78, 7, v152
	v_lshl_add_u32 v79, v79, 7, v153
	s_mov_b32 m0, s79
	s_add_i32 s43, s79, 0x400
	global_load_lds_dwordx4 v78, s[50:51]
	s_mov_b32 m0, s43
	s_nop 0
	global_load_lds_dwordx4 v79, s[50:51]
	s_waitcnt vmcnt(8)
	v_add_u32_e32 v54, s99, v59
	v_add_u32_e32 v55, s99, v60
	v_add_u32_e32 v56, s99, v61
	v_add_u32_e32 v57, s99, v62
	ds_read_b64_tr_b4 v[50:51], v160 offset:640
	ds_read_b64_tr_b4 v[52:53], v160 offset:1664
	ds_read_b64_tr_b4 v[130:131], v54
	ds_read_b64_tr_b4 v[132:133], v55
	ds_read_b64_tr_b4 v[134:135], v56
	ds_read_b64_tr_b4 v[136:137], v57
	s_waitcnt lgkmcnt(6)
	v_dot8c_i32_i4_e32 v38, v122, v48
	v_dot8c_i32_i4_e32 v39, v122, v46
	v_dot8c_i32_i4_e32 v40, v124, v48
	v_dot8c_i32_i4_e32 v41, v124, v46
	v_dot8c_i32_i4_e32 v42, v126, v48
	v_dot8c_i32_i4_e32 v43, v126, v46
	v_dot8c_i32_i4_e32 v44, v128, v48
	v_dot8c_i32_i4_e32 v45, v128, v46
	v_dot8c_i32_i4_e32 v38, v123, v49
	v_dot8c_i32_i4_e32 v39, v123, v47
	v_dot8c_i32_i4_e32 v40, v125, v49
	v_dot8c_i32_i4_e32 v41, v125, v47
	v_dot8c_i32_i4_e32 v42, v127, v49
	v_dot8c_i32_i4_e32 v43, v127, v47
	v_dot8c_i32_i4_e32 v44, v129, v49
	v_dot8c_i32_i4_e32 v45, v129, v47
	s_waitcnt lgkmcnt(15)
; __device__ __forceinline__ void peer_v_tokens(int j, const LAS unsigned short* EL, const LAS unsigned char* AL  , const LAS float* ASC  , const LAS int* SAL  , ...
;     ...
;         { unsigned ho = (unsigned)t * (D / 4) + (unsigned)lane; asm volatile("" : "+v"(ho)); const uint2* hp = (const uint2*)HB + ho; const float4* gp = (const float4*)fng + lane;
; #pragma unroll
;           for (int jq = 0; jq < 4; ++jq) { hv[jq] = hp[64 * jq]; gv[jq] = gp[64 * jq]; } }
;         VDMA(0, 0); VDMA(1, 1);
; #pragma unroll
;         for (int m = 0; m < 2; ++m) {
;             const int idx = lane + 64 * m, tau = idx >> 4, sr = idx & 15, k = 16 * (sr & 7) + 2 * tau + (sr >> 3);
;             const int aq = (int)*(const LAS signed char*)(AL + tl * 128 + k); const int tq = aq + 8;
;             const unsigned lo = (((unsigned)tq & 15u) ^ 8u) * 0x11111111u, hi = ((unsigned)(tq >> 4) & 15u) * 0x11111111u;
;             typedef unsigned u2v __attribute__((ext_vector_type(2)));
;             u2v l2; l2.x = lo; l2.y = lo; u2v h2; h2.x = hi; h2.y = hi;
;             *(LAS u2v*)(ATL + 8 * idx) = l2; *(LAS u2v*)(ATL + 1024 + 8 * idx) = h2;
;         }
;         const float asc = ASC[tl]; const int sa = SAL[tl];
;         CFENCE();
;         int accH[4], accL[4];
; #pragma unroll
;         for (int st = 0; st < 16; ++st) {
;             const int p = st >> 2, q = st & 3;
;             if (st < 14) VDMA(st + 2, (st + 2) % 3);
;             if (st < 14) asm volatile("s_waitcnt vmcnt(8)" ::: "memory");
;             else if (st == 14) asm volatile("s_waitcnt vmcnt(4)" ::: "memory");
;             else asm volatile("s_waitcnt vmcnt(0)" ::: "memory");
;             if (q == 0) {
; #pragma unroll
;                 for (int r = 0; r < 4; ++r) { accH[r] = 0; accL[r] = 0; } }
; #pragma unroll
;             for (int tp = 0; tp < 2; ++tp) {
;                 const v2i ao = TR4(ATL + (2 * q + tp) * 128 + 8 * s16), ah = TR4(ATL + 1024 + (2 * q + tp) * 128 + 8 * s16);
; #pragma unroll
;                 for (int r = 0; r < 4; ++r) {
;                     const v2i d = TR4(ldsb + BUF[st % 3] + 2048 * tp + roff[r]);
;                     accH[r] = __builtin_amdgcn_sdot8(d.x, ah.x, accH[r], false); accH[r] = __builtin_amdgcn_sdot8(d.y, ah.y, accH[r], false);
;                     accL[r] = __builtin_amdgcn_sdot8(d.x, ao.x, accL[r], false); accL[r] = __builtin_amdgcn_sdot8(d.y, ao.y, accL[r], false);
	v_add_u32_e32 v143, 8, v139
	v_and_b32_e32 v142, 15, v143
	v_xor_b32_e32 v142, 8, v142
	v_bfe_u32 v144, v143, 4, 4
	v_mul_lo_u32 v142, v142, s92
	v_mul_lo_u32 v144, v144, s92
	v_mov_b32_e32 v143, v142
	v_mov_b32_e32 v145, v144
	ds_write2st64_b64 v159, v[142:143], v[144:145] offset1:2
	v_and_b32_e32 v78, 0xffff, v28
	v_lshrrev_b32_e32 v79, 16, v28
	v_lshl_add_u32 v78, v78, 7, v152
	v_lshl_add_u32 v79, v79, 7, v153
	s_mov_b32 m0, s98
	s_add_i32 s43, s98, 0x400
	global_load_lds_dwordx4 v78, s[50:51]
	s_mov_b32 m0, s43
	s_nop 0
	global_load_lds_dwordx4 v79, s[50:51]
	s_waitcnt vmcnt(8)
	v_add_u32_e32 v54, s76, v59
	v_add_u32_e32 v55, s76, v60
	v_add_u32_e32 v56, s76, v61
	v_add_u32_e32 v57, s76, v62
	ds_read_b64_tr_b4 v[46:47], v160 offset:768
	ds_read_b64_tr_b4 v[48:49], v160 offset:1792
	ds_read_b64_tr_b4 v[122:123], v54
	ds_read_b64_tr_b4 v[124:125], v55
	ds_read_b64_tr_b4 v[126:127], v56
	ds_read_b64_tr_b4 v[128:129], v57
	s_waitcnt lgkmcnt(7)
	v_dot8c_i32_i4_e32 v38, v130, v52
	v_dot8c_i32_i4_e32 v39, v130, v50
	v_dot8c_i32_i4_e32 v40, v132, v52
	v_dot8c_i32_i4_e32 v41, v132, v50
	v_dot8c_i32_i4_e32 v42, v134, v52
	v_dot8c_i32_i4_e32 v43, v134, v50
	v_dot8c_i32_i4_e32 v44, v136, v52
	v_dot8c_i32_i4_e32 v45, v136, v50
	v_dot8c_i32_i4_e32 v38, v131, v53
	v_dot8c_i32_i4_e32 v39, v131, v51
	v_dot8c_i32_i4_e32 v40, v133, v53
	v_dot8c_i32_i4_e32 v41, v133, v51
	v_dot8c_i32_i4_e32 v42, v135, v53
	v_dot8c_i32_i4_e32 v43, v135, v51
	v_dot8c_i32_i4_e32 v44, v137, v53
	v_dot8c_i32_i4_e32 v45, v137, v51
	v_and_b32_e32 v78, 0xffff, v29
	v_lshrrev_b32_e32 v79, 16, v29
	v_lshl_add_u32 v78, v78, 7, v152
	v_lshl_add_u32 v79, v79, 7, v153
	s_mov_b32 m0, s99
	s_add_i32 s43, s99, 0x400
	global_load_lds_dwordx4 v78, s[50:51]
	s_mov_b32 m0, s43
	s_nop 0
	global_load_lds_dwordx4 v79, s[50:51]
	s_waitcnt vmcnt(8)
	v_add_u32_e32 v54, s77, v59
	v_add_u32_e32 v55, s77, v60
	v_add_u32_e32 v56, s77, v61
	v_add_u32_e32 v57, s77, v62
	ds_read_b64_tr_b4 v[50:51], v160 offset:896
	ds_read_b64_tr_b4 v[52:53], v160 offset:1920
	ds_read_b64_tr_b4 v[130:131], v54
	ds_read_b64_tr_b4 v[132:133], v55
	ds_read_b64_tr_b4 v[134:135], v56
	ds_read_b64_tr_b4 v[136:137], v57
	s_waitcnt lgkmcnt(6)
	v_dot8c_i32_i4_e32 v38, v122, v48
	v_dot8c_i32_i4_e32 v39, v122, v46
	v_dot8c_i32_i4_e32 v40, v124, v48
	v_dot8c_i32_i4_e32 v41, v124, v46
	v_dot8c_i32_i4_e32 v42, v126, v48
	v_dot8c_i32_i4_e32 v43, v126, v46
	v_dot8c_i32_i4_e32 v44, v128, v48
	v_dot8c_i32_i4_e32 v45, v128, v46
	v_dot8c_i32_i4_e32 v38, v123, v49
	v_dot8c_i32_i4_e32 v39, v123, v47
	v_dot8c_i32_i4_e32 v40, v125, v49
	v_dot8c_i32_i4_e32 v41, v125, v47
	v_dot8c_i32_i4_e32 v42, v127, v49
	v_dot8c_i32_i4_e32 v43, v127, v47
	v_dot8c_i32_i4_e32 v44, v129, v49
	v_dot8c_i32_i4_e32 v45, v129, v47
	v_and_b32_e32 v78, 0xffff, v30
	v_lshrrev_b32_e32 v79, 16, v30
	v_lshl_add_u32 v78, v78, 7, v152
	v_lshl_add_u32 v79, v79, 7, v153
	s_mov_b32 m0, s76
	s_add_i32 s43, s76, 0x400
	global_load_lds_dwordx4 v78, s[50:51]
	s_mov_b32 m0, s43
	s_nop 0
	global_load_lds_dwordx4 v79, s[50:51]
	s_waitcnt vmcnt(8)
	v_add_u32_e32 v54, s78, v59
	v_add_u32_e32 v55, s78, v60
	v_add_u32_e32 v56, s78, v61
	v_add_u32_e32 v57, s78, v62
	ds_read_b64_tr_b4 v[46:47], v160
	ds_read_b64_tr_b4 v[48:49], v160 offset:1024
	ds_read_b64_tr_b4 v[122:123], v54
	ds_read_b64_tr_b4 v[124:125], v55
	ds_read_b64_tr_b4 v[126:127], v56
	ds_read_b64_tr_b4 v[128:129], v57
	s_waitcnt lgkmcnt(6)
	v_dot8c_i32_i4_e32 v38, v130, v52
	v_dot8c_i32_i4_e32 v39, v130, v50
	v_dot8c_i32_i4_e32 v40, v132, v52
	v_dot8c_i32_i4_e32 v41, v132, v50
	v_dot8c_i32_i4_e32 v42, v134, v52
	v_dot8c_i32_i4_e32 v43, v134, v50
	v_dot8c_i32_i4_e32 v44, v136, v52
	v_dot8c_i32_i4_e32 v45, v136, v50
	v_dot8c_i32_i4_e32 v38, v131, v53
	v_dot8c_i32_i4_e32 v39, v131, v51
	v_dot8c_i32_i4_e32 v40, v133, v53
	v_dot8c_i32_i4_e32 v41, v133, v51
	v_dot8c_i32_i4_e32 v42, v135, v53
	v_dot8c_i32_i4_e32 v43, v135, v51
	v_dot8c_i32_i4_e32 v44, v137, v53
	v_dot8c_i32_i4_e32 v45, v137, v51
	s_nop 3
	s_waitcnt lgkmcnt(15)
	v_lshlrev_b32_e32 v38, 5, v38
	v_lshlrev_b32_e32 v39, 1, v39
	v_add3_u32 v38, v39, v229, v38
	v_cvt_f32_i32_e32 v38, v38
	v_mul_f32_e32 v38, v228, v38
	v_lshlrev_b32_e32 v40, 5, v40
	v_lshlrev_b32_e32 v41, 1, v41
	v_add3_u32 v40, v41, v229, v40
	v_cvt_f32_i32_e32 v40, v40
	v_mul_f32_e32 v40, v228, v40
	v_lshlrev_b32_e32 v42, 5, v42
	v_lshlrev_b32_e32 v43, 1, v43
	v_add3_u32 v42, v43, v229, v42
	v_cvt_f32_i32_e32 v42, v42
	v_mul_f32_e32 v42, v228, v42
	v_lshlrev_b32_e32 v44, 5, v44
	v_lshlrev_b32_e32 v45, 1, v45
	v_add3_u32 v44, v45, v229, v44
	v_cvt_f32_i32_e32 v44, v44
	v_mul_f32_e32 v44, v228, v44
	v_cvt_pk_bf16_f32 v168, v38, v40
	v_cvt_pk_bf16_f32 v169, v42, v44
	s_add_i32 s43, s40, 0
	s_lshl_b32 s43, s43, 11
	v_add_u32_e32 v138, s43, v66
	global_load_dwordx2 v[194:195], v138, s[70:71]
	global_load_dwordx2 v[196:197], v138, s[70:71] offset:512
	global_load_dwordx2 v[198:199], v138, s[70:71] offset:1024
	global_load_dwordx2 v[200:201], v138, s[70:71] offset:1536
	v_add_u32_e32 v147, 8, v140
	v_and_b32_e32 v146, 15, v147
	v_xor_b32_e32 v146, 8, v146
	v_bfe_u32 v148, v147, 4, 4
	v_mul_lo_u32 v146, v146, s92
	v_mul_lo_u32 v148, v148, s92
	v_mov_b32_e32 v147, v146
	v_mov_b32_e32 v149, v148
	ds_write2st64_b64 v77, v[146:147], v[148:149] offset1:2
	v_add_u32_e32 v138, 0x800, v74
	ds_read_u8 v139, v138
	v_add_u32_e32 v141, 0x800, v73
	ds_read_u8 v140, v141
	s_add_i32 s43, s67, 32
	v_mov_b32_e32 v138, s43
	ds_read2st64_b32 v[228:229], v138 offset1:1
	ds_read_b128 v[18:21], v227 offset:4096
	ds_read_b128 v[22:25], v227 offset:4112
	v_mov_b32_e32 v150, v63
	v_mov_b32_e32 v151, v64
	v_mov_b32_e32 v38, 0
	v_mov_b32_e32 v39, 0
	v_mov_b32_e32 v40, 0
	v_mov_b32_e32 v41, 0
	v_mov_b32_e32 v42, 0
	v_mov_b32_e32 v43, 0
	v_mov_b32_e32 v44, 0
	v_mov_b32_e32 v45, 0
	v_and_b32_e32 v78, 0xffff, v31
	v_lshrrev_b32_e32 v79, 16, v31
	v_lshl_add_u32 v78, v78, 7, v152
	v_lshl_add_u32 v79, v79, 7, v153
	s_mov_b32 m0, s77
	s_add_i32 s43, s77, 0x400
	global_load_lds_dwordx4 v78, s[50:51]
	s_mov_b32 m0, s43
	s_nop 0
	global_load_lds_dwordx4 v79, s[50:51]
	s_waitcnt vmcnt(12)
; #define TR4(p_) __builtin_amdgcn_ds_read_tr4_b64_v2i32((LAS v2i*)(p_))
; #define VDMA(st_, k_) do { _Pragma("unroll") for (int i_ = 0; i_ < 4; ++i_) { \
;         const unsigned off_ = (unsigned)((st_) >> 2) * (16384u * 128u) + (PE_ID(E, 4 * ((st_) & 3) + i_) << 7) + ((i_ & 1) ? cx1 : cx0); \
;         __builtin_amdgcn_global_load_lds((const unsigned*)(V4 + off_), (LAS unsigned*)(ldsb + BUF[k_] + 1024 * i_), 16, 0, 0); } } while (0)
; __device__ __forceinline__ void peer_v_tokens(int j, const LAS unsigned short* EL, const LAS unsigned char* AL  , const LAS float* ASC  , const LAS int* SAL  , ...
;     ...
;         for (int st = 0; st < 16; ++st) {
;             const int p = st >> 2, q = st & 3;
;             if (st < 14) VDMA(st + 2, (st + 2) % 3);
;             if (st < 14) asm volatile("s_waitcnt vmcnt(8)" ::: "memory");
;             else if (st == 14) asm volatile("s_waitcnt vmcnt(4)" ::: "memory");
;             else asm volatile("s_waitcnt vmcnt(0)" ::: "memory");
;             if (q == 0) {
; #pragma unroll
;                 for (int r = 0; r < 4; ++r) { accH[r] = 0; accL[r] = 0; } }
; #pragma unroll
;             for (int tp = 0; tp < 2; ++tp) {
;                 const v2i ao = TR4(ATL + (2 * q + tp) * 128 + 8 * s16), ah = TR4(ATL + 1024 + (2 * q + tp) * 128 + 8 * s16);
; #pragma unroll
;                 for (int r = 0; r < 4; ++r) {
;                     const v2i d = TR4(ldsb + BUF[st % 3] + 2048 * tp + roff[r]);
;                     accH[r] = __builtin_amdgcn_sdot8(d.x, ah.x, accH[r], false); accH[r] = __builtin_amdgcn_sdot8(d.y, ah.y, accH[r], false);
;                     accL[r] = __builtin_amdgcn_sdot8(d.x, ao.x, accL[r], false); accL[r] = __builtin_amdgcn_sdot8(d.y, ao.y, accL[r], false);
;                 }
;             }
	v_add_u32_e32 v54, s79, v59
	v_add_u32_e32 v55, s79, v60
	v_add_u32_e32 v56, s79, v61
	v_add_u32_e32 v57, s79, v62
	ds_read_b64_tr_b4 v[50:51], v160 offset:128
	ds_read_b64_tr_b4 v[52:53], v160 offset:1152
	ds_read_b64_tr_b4 v[130:131], v54
	ds_read_b64_tr_b4 v[132:133], v55
	ds_read_b64_tr_b4 v[134:135], v56
	ds_read_b64_tr_b4 v[136:137], v57
	s_waitcnt lgkmcnt(12)
	v_dot8c_i32_i4_e32 v38, v122, v48
	v_dot8c_i32_i4_e32 v39, v122, v46
	v_dot8c_i32_i4_e32 v40, v124, v48
	v_dot8c_i32_i4_e32 v41, v124, v46
	v_dot8c_i32_i4_e32 v42, v126, v48
	v_dot8c_i32_i4_e32 v43, v126, v46
	v_dot8c_i32_i4_e32 v44, v128, v48
	v_dot8c_i32_i4_e32 v45, v128, v46
	v_dot8c_i32_i4_e32 v38, v123, v49
	v_dot8c_i32_i4_e32 v39, v123, v47
	v_dot8c_i32_i4_e32 v40, v125, v49
	v_dot8c_i32_i4_e32 v41, v125, v47
	v_dot8c_i32_i4_e32 v42, v127, v49
	v_dot8c_i32_i4_e32 v43, v127, v47
	v_dot8c_i32_i4_e32 v44, v129, v49
	v_dot8c_i32_i4_e32 v45, v129, v47
	v_and_b32_e32 v78, 0xffff, v32
	v_lshrrev_b32_e32 v79, 16, v32
	v_lshl_add_u32 v78, v78, 7, v152
	v_lshl_add_u32 v79, v79, 7, v153
	s_mov_b32 m0, s78
	s_add_i32 s43, s78, 0x400
	global_load_lds_dwordx4 v78, s[50:51]
	s_mov_b32 m0, s43
	s_nop 0
	global_load_lds_dwordx4 v79, s[50:51]
	s_waitcnt vmcnt(12)
	v_add_u32_e32 v54, s98, v59
	v_add_u32_e32 v55, s98, v60
	v_add_u32_e32 v56, s98, v61
	v_add_u32_e32 v57, s98, v62
	ds_read_b64_tr_b4 v[46:47], v160 offset:256
	ds_read_b64_tr_b4 v[48:49], v160 offset:1280
	ds_read_b64_tr_b4 v[122:123], v54
	ds_read_b64_tr_b4 v[124:125], v55
	ds_read_b64_tr_b4 v[126:127], v56
	ds_read_b64_tr_b4 v[128:129], v57
	s_waitcnt lgkmcnt(6)
	v_dot8c_i32_i4_e32 v38, v130, v52
	v_dot8c_i32_i4_e32 v39, v130, v50
	v_dot8c_i32_i4_e32 v40, v132, v52
	v_dot8c_i32_i4_e32 v41, v132, v50
	v_dot8c_i32_i4_e32 v42, v134, v52
	v_dot8c_i32_i4_e32 v43, v134, v50
	v_dot8c_i32_i4_e32 v44, v136, v52
	v_dot8c_i32_i4_e32 v45, v136, v50
	v_dot8c_i32_i4_e32 v38, v131, v53
	v_dot8c_i32_i4_e32 v39, v131, v51
	v_dot8c_i32_i4_e32 v40, v133, v53
	v_dot8c_i32_i4_e32 v41, v133, v51
	v_dot8c_i32_i4_e32 v42, v135, v53
	v_dot8c_i32_i4_e32 v43, v135, v51
	v_dot8c_i32_i4_e32 v44, v137, v53
	v_dot8c_i32_i4_e32 v45, v137, v51
	v_and_b32_e32 v78, 0xffff, v33
	v_lshrrev_b32_e32 v79, 16, v33
	v_lshl_add_u32 v78, v78, 7, v152
	v_lshl_add_u32 v79, v79, 7, v153
	s_mov_b32 m0, s79
	s_add_i32 s43, s79, 0x400
	global_load_lds_dwordx4 v78, s[50:51]
	s_mov_b32 m0, s43
	s_nop 0
	global_load_lds_dwordx4 v79, s[50:51]
	s_waitcnt vmcnt(12)
	v_add_u32_e32 v54, s99, v59
	v_add_u32_e32 v55, s99, v60
	v_add_u32_e32 v56, s99, v61
	v_add_u32_e32 v57, s99, v62
	ds_read_b64_tr_b4 v[50:51], v160 offset:384
	ds_read_b64_tr_b4 v[52:53], v160 offset:1408
	ds_read_b64_tr_b4 v[130:131], v54
	ds_read_b64_tr_b4 v[132:133], v55
	ds_read_b64_tr_b4 v[134:135], v56
	ds_read_b64_tr_b4 v[136:137], v57
	s_waitcnt lgkmcnt(6)
	v_dot8c_i32_i4_e32 v38, v122, v48
	v_dot8c_i32_i4_e32 v39, v122, v46
	v_dot8c_i32_i4_e32 v40, v124, v48
	v_dot8c_i32_i4_e32 v41, v124, v46
	v_dot8c_i32_i4_e32 v42, v126, v48
	v_dot8c_i32_i4_e32 v43, v126, v46
	v_dot8c_i32_i4_e32 v44, v128, v48
	v_dot8c_i32_i4_e32 v45, v128, v46
	v_dot8c_i32_i4_e32 v38, v123, v49
	v_dot8c_i32_i4_e32 v39, v123, v47
	v_dot8c_i32_i4_e32 v40, v125, v49
	v_dot8c_i32_i4_e32 v41, v125, v47
	v_dot8c_i32_i4_e32 v42, v127, v49
	v_dot8c_i32_i4_e32 v43, v127, v47
	v_dot8c_i32_i4_e32 v44, v129, v49
	v_dot8c_i32_i4_e32 v45, v129, v47
	s_waitcnt lgkmcnt(15)
	v_and_b32_e32 v78, 0xffff, v18
	v_lshrrev_b32_e32 v79, 16, v18
	v_lshl_add_u32 v78, v78, 7, v150
	v_lshl_add_u32 v79, v79, 7, v151
	s_mov_b32 m0, s98
	s_add_i32 s43, s98, 0x400
	global_load_lds_dwordx4 v78, s[50:51]
	s_mov_b32 m0, s43
	s_nop 0
	global_load_lds_dwordx4 v79, s[50:51]
	s_waitcnt vmcnt(12)
	v_add_u32_e32 v54, s76, v59
	v_add_u32_e32 v55, s76, v60
	v_add_u32_e32 v56, s76, v61
	v_add_u32_e32 v57, s76, v62
	ds_read_b64_tr_b4 v[46:47], v160 offset:512
	ds_read_b64_tr_b4 v[48:49], v160 offset:1536
	ds_read_b64_tr_b4 v[122:123], v54
	ds_read_b64_tr_b4 v[124:125], v55
	ds_read_b64_tr_b4 v[126:127], v56
	ds_read_b64_tr_b4 v[128:129], v57
	s_waitcnt lgkmcnt(6)
	v_dot8c_i32_i4_e32 v38, v130, v52
	v_dot8c_i32_i4_e32 v39, v130, v50
	v_dot8c_i32_i4_e32 v40, v132, v52
	v_dot8c_i32_i4_e32 v41, v132, v50
	v_dot8c_i32_i4_e32 v42, v134, v52
	v_dot8c_i32_i4_e32 v43, v134, v50
	v_dot8c_i32_i4_e32 v44, v136, v52
	v_dot8c_i32_i4_e32 v45, v136, v50
	v_dot8c_i32_i4_e32 v38, v131, v53
	v_dot8c_i32_i4_e32 v39, v131, v51
	v_dot8c_i32_i4_e32 v40, v133, v53
	v_dot8c_i32_i4_e32 v41, v133, v51
	v_dot8c_i32_i4_e32 v42, v135, v53
	v_dot8c_i32_i4_e32 v43, v135, v51
	v_dot8c_i32_i4_e32 v44, v137, v53
	v_dot8c_i32_i4_e32 v45, v137, v51
	v_and_b32_e32 v78, 0xffff, v19
	v_lshrrev_b32_e32 v79, 16, v19
	v_lshl_add_u32 v78, v78, 7, v150
	v_lshl_add_u32 v79, v79, 7, v151
	s_mov_b32 m0, s99
	s_add_i32 s43, s99, 0x400
	global_load_lds_dwordx4 v78, s[50:51]
	s_mov_b32 m0, s43
	s_nop 0
	global_load_lds_dwordx4 v79, s[50:51]
	s_waitcnt vmcnt(8)
	v_add_u32_e32 v54, s77, v59
	v_add_u32_e32 v55, s77, v60
	v_add_u32_e32 v56, s77, v61
	v_add_u32_e32 v57, s77, v62
	ds_read_b64_tr_b4 v[50:51], v160 offset:640
	ds_read_b64_tr_b4 v[52:53], v160 offset:1664
	ds_read_b64_tr_b4 v[130:131], v54
	ds_read_b64_tr_b4 v[132:133], v55
	ds_read_b64_tr_b4 v[134:135], v56
	ds_read_b64_tr_b4 v[136:137], v57
	s_waitcnt lgkmcnt(6)
	v_dot8c_i32_i4_e32 v38, v122, v48
	v_dot8c_i32_i4_e32 v39, v122, v46
	v_dot8c_i32_i4_e32 v40, v124, v48
	v_dot8c_i32_i4_e32 v41, v124, v46
	v_dot8c_i32_i4_e32 v42, v126, v48
	v_dot8c_i32_i4_e32 v43, v126, v46
	v_dot8c_i32_i4_e32 v44, v128, v48
	v_dot8c_i32_i4_e32 v45, v128, v46
	v_dot8c_i32_i4_e32 v38, v123, v49
	v_dot8c_i32_i4_e32 v39, v123, v47
	v_dot8c_i32_i4_e32 v40, v125, v49
	v_dot8c_i32_i4_e32 v41, v125, v47
	v_dot8c_i32_i4_e32 v42, v127, v49
	v_dot8c_i32_i4_e32 v43, v127, v47
	v_dot8c_i32_i4_e32 v44, v129, v49
	v_dot8c_i32_i4_e32 v45, v129, v47
	s_waitcnt lgkmcnt(15)
; __device__ __forceinline__ void peer_v_tokens(int j, const LAS unsigned short* EL, const LAS unsigned char* AL  , const LAS float* ASC  , const LAS int* SAL  , ...
;     ...
;         for (int m = 0; m < 2; ++m) {
;             const int idx = lane + 64 * m, tau = idx >> 4, sr = idx & 15, k = 16 * (sr & 7) + 2 * tau + (sr >> 3);
;             const int aq = (int)*(const LAS signed char*)(AL + tl * 128 + k); const int tq = aq + 8;
;             const unsigned lo = (((unsigned)tq & 15u) ^ 8u) * 0x11111111u, hi = ((unsigned)(tq >> 4) & 15u) * 0x11111111u;
;             typedef unsigned u2v __attribute__((ext_vector_type(2)));
;             u2v l2; l2.x = lo; l2.y = lo; u2v h2; h2.x = hi; h2.y = hi;
;             *(LAS u2v*)(ATL + 8 * idx) = l2; *(LAS u2v*)(ATL + 1024 + 8 * idx) = h2;
;         }
;         const float asc = ASC[tl]; const int sa = SAL[tl];
;         CFENCE();
;         int accH[4], accL[4];
; #pragma unroll
;         for (int st = 0; st < 16; ++st) {
;             const int p = st >> 2, q = st & 3;
;             if (st < 14) VDMA(st + 2, (st + 2) % 3);
;             if (st < 14) asm volatile("s_waitcnt vmcnt(8)" ::: "memory");
;             else if (st == 14) asm volatile("s_waitcnt vmcnt(4)" ::: "memory");
;             else asm volatile("s_waitcnt vmcnt(0)" ::: "memory");
;             if (q == 0) {
; #pragma unroll
;                 for (int r = 0; r < 4; ++r) { accH[r] = 0; accL[r] = 0; } }
; #pragma unroll
;             for (int tp = 0; tp < 2; ++tp) {
;                 const v2i ao = TR4(ATL + (2 * q + tp) * 128 + 8 * s16), ah = TR4(ATL + 1024 + (2 * q + tp) * 128 + 8 * s16);
; #pragma unroll
;                 for (int r = 0; r < 4; ++r) {
;                     const v2i d = TR4(ldsb + BUF[st % 3] + 2048 * tp + roff[r]);
;                     accH[r] = __builtin_amdgcn_sdot8(d.x, ah.x, accH[r], false); accH[r] = __builtin_amdgcn_sdot8(d.y, ah.y, accH[r], false);
;                     accL[r] = __builtin_amdgcn_sdot8(d.x, ao.x, accL[r], false); accL[r] = __builtin_amdgcn_sdot8(d.y, ao.y, accL[r], false);
;                 }
;             }
;             asm volatile("s_waitcnt lgkmcnt(0)" ::: "memory");
;             if (q == 3) {
; #pragma unroll
;                 for (int r = 0; r < 4; ++r) STASH[256 * p + 16 * (grp + 4 * r) + pc] = f2bf(asc * (float)(2 * ((accH[r] << 4) + accL[r]) + sa));
;             }
	v_add_u32_e32 v143, 8, v139
	v_and_b32_e32 v142, 15, v143
	v_xor_b32_e32 v142, 8, v142
	v_bfe_u32 v144, v143, 4, 4
	v_mul_lo_u32 v142, v142, s92
	v_mul_lo_u32 v144, v144, s92
	v_mov_b32_e32 v143, v142
	v_mov_b32_e32 v145, v144
	ds_write2st64_b64 v159, v[142:143], v[144:145] offset1:2
	v_and_b32_e32 v78, 0xffff, v20
	v_lshrrev_b32_e32 v79, 16, v20
	v_lshl_add_u32 v78, v78, 7, v150
	v_lshl_add_u32 v79, v79, 7, v151
	s_mov_b32 m0, s76
	s_add_i32 s43, s76, 0x400
	global_load_lds_dwordx4 v78, s[50:51]
	s_mov_b32 m0, s43
	s_nop 0
	global_load_lds_dwordx4 v79, s[50:51]
	s_waitcnt vmcnt(8)
	v_add_u32_e32 v54, s78, v59
	v_add_u32_e32 v55, s78, v60
	v_add_u32_e32 v56, s78, v61
	v_add_u32_e32 v57, s78, v62
	ds_read_b64_tr_b4 v[46:47], v160 offset:768
	ds_read_b64_tr_b4 v[48:49], v160 offset:1792
	ds_read_b64_tr_b4 v[122:123], v54
	ds_read_b64_tr_b4 v[124:125], v55
	ds_read_b64_tr_b4 v[126:127], v56
	ds_read_b64_tr_b4 v[128:129], v57
	s_waitcnt lgkmcnt(7)
	v_dot8c_i32_i4_e32 v38, v130, v52
	v_dot8c_i32_i4_e32 v39, v130, v50
	v_dot8c_i32_i4_e32 v40, v132, v52
	v_dot8c_i32_i4_e32 v41, v132, v50
	v_dot8c_i32_i4_e32 v42, v134, v52
	v_dot8c_i32_i4_e32 v43, v134, v50
	v_dot8c_i32_i4_e32 v44, v136, v52
	v_dot8c_i32_i4_e32 v45, v136, v50
	v_dot8c_i32_i4_e32 v38, v131, v53
	v_dot8c_i32_i4_e32 v39, v131, v51
	v_dot8c_i32_i4_e32 v40, v133, v53
	v_dot8c_i32_i4_e32 v41, v133, v51
	v_dot8c_i32_i4_e32 v42, v135, v53
	v_dot8c_i32_i4_e32 v43, v135, v51
	v_dot8c_i32_i4_e32 v44, v137, v53
	v_dot8c_i32_i4_e32 v45, v137, v51
	v_and_b32_e32 v78, 0xffff, v21
	v_lshrrev_b32_e32 v79, 16, v21
	v_lshl_add_u32 v78, v78, 7, v150
	v_lshl_add_u32 v79, v79, 7, v151
	s_mov_b32 m0, s77
	s_add_i32 s43, s77, 0x400
	global_load_lds_dwordx4 v78, s[50:51]
	s_mov_b32 m0, s43
	s_nop 0
	global_load_lds_dwordx4 v79, s[50:51]
	s_waitcnt vmcnt(8)
	v_add_u32_e32 v54, s79, v59
	v_add_u32_e32 v55, s79, v60
	v_add_u32_e32 v56, s79, v61
	v_add_u32_e32 v57, s79, v62
	ds_read_b64_tr_b4 v[50:51], v160 offset:896
	ds_read_b64_tr_b4 v[52:53], v160 offset:1920
	ds_read_b64_tr_b4 v[130:131], v54
	ds_read_b64_tr_b4 v[132:133], v55
	ds_read_b64_tr_b4 v[134:135], v56
	ds_read_b64_tr_b4 v[136:137], v57
	s_waitcnt lgkmcnt(6)
	v_dot8c_i32_i4_e32 v38, v122, v48
	v_dot8c_i32_i4_e32 v39, v122, v46
	v_dot8c_i32_i4_e32 v40, v124, v48
	v_dot8c_i32_i4_e32 v41, v124, v46
	v_dot8c_i32_i4_e32 v42, v126, v48
	v_dot8c_i32_i4_e32 v43, v126, v46
	v_dot8c_i32_i4_e32 v44, v128, v48
	v_dot8c_i32_i4_e32 v45, v128, v46
	v_dot8c_i32_i4_e32 v38, v123, v49
	v_dot8c_i32_i4_e32 v39, v123, v47
	v_dot8c_i32_i4_e32 v40, v125, v49
	v_dot8c_i32_i4_e32 v41, v125, v47
	v_dot8c_i32_i4_e32 v42, v127, v49
	v_dot8c_i32_i4_e32 v43, v127, v47
	v_dot8c_i32_i4_e32 v44, v129, v49
	v_dot8c_i32_i4_e32 v45, v129, v47
	v_and_b32_e32 v78, 0xffff, v22
	v_lshrrev_b32_e32 v79, 16, v22
	v_lshl_add_u32 v78, v78, 7, v150
	v_lshl_add_u32 v79, v79, 7, v151
	s_mov_b32 m0, s78
	s_add_i32 s43, s78, 0x400
	global_load_lds_dwordx4 v78, s[50:51]
	s_mov_b32 m0, s43
	s_nop 0
	global_load_lds_dwordx4 v79, s[50:51]
	s_waitcnt vmcnt(8)
	v_add_u32_e32 v54, s98, v59
	v_add_u32_e32 v55, s98, v60
	v_add_u32_e32 v56, s98, v61
	v_add_u32_e32 v57, s98, v62
	ds_read_b64_tr_b4 v[46:47], v160
	ds_read_b64_tr_b4 v[48:49], v160 offset:1024
	ds_read_b64_tr_b4 v[122:123], v54
	ds_read_b64_tr_b4 v[124:125], v55
	ds_read_b64_tr_b4 v[126:127], v56
	ds_read_b64_tr_b4 v[128:129], v57
	s_waitcnt lgkmcnt(6)
	v_dot8c_i32_i4_e32 v38, v130, v52
	v_dot8c_i32_i4_e32 v39, v130, v50
	v_dot8c_i32_i4_e32 v40, v132, v52
	v_dot8c_i32_i4_e32 v41, v132, v50
	v_dot8c_i32_i4_e32 v42, v134, v52
	v_dot8c_i32_i4_e32 v43, v134, v50
	v_dot8c_i32_i4_e32 v44, v136, v52
	v_dot8c_i32_i4_e32 v45, v136, v50
	v_dot8c_i32_i4_e32 v38, v131, v53
	v_dot8c_i32_i4_e32 v39, v131, v51
	v_dot8c_i32_i4_e32 v40, v133, v53
	v_dot8c_i32_i4_e32 v41, v133, v51
	v_dot8c_i32_i4_e32 v42, v135, v53
	v_dot8c_i32_i4_e32 v43, v135, v51
	v_dot8c_i32_i4_e32 v44, v137, v53
	v_dot8c_i32_i4_e32 v45, v137, v51
	s_nop 3
	s_waitcnt lgkmcnt(15)
	v_lshlrev_b32_e32 v38, 5, v38
	v_lshlrev_b32_e32 v39, 1, v39
	v_add3_u32 v38, v39, v229, v38
	v_cvt_f32_i32_e32 v38, v38
	v_mul_f32_e32 v38, v228, v38
	v_lshlrev_b32_e32 v40, 5, v40
	v_lshlrev_b32_e32 v41, 1, v41
	v_add3_u32 v40, v41, v229, v40
	v_cvt_f32_i32_e32 v40, v40
	v_mul_f32_e32 v40, v228, v40
	v_lshlrev_b32_e32 v42, 5, v42
	v_lshlrev_b32_e32 v43, 1, v43
	v_add3_u32 v42, v43, v229, v42
	v_cvt_f32_i32_e32 v42, v42
	v_mul_f32_e32 v42, v228, v42
	v_lshlrev_b32_e32 v44, 5, v44
	v_lshlrev_b32_e32 v45, 1, v45
	v_add3_u32 v44, v45, v229, v44
	v_cvt_f32_i32_e32 v44, v44
	v_mul_f32_e32 v44, v228, v44
	v_cvt_pk_bf16_f32 v176, v38, v40
	v_cvt_pk_bf16_f32 v177, v42, v44
	v_add_u32_e32 v147, 8, v140
	v_and_b32_e32 v146, 15, v147
	v_xor_b32_e32 v146, 8, v146
	v_bfe_u32 v148, v147, 4, 4
	v_mul_lo_u32 v146, v146, s92
	v_mul_lo_u32 v148, v148, s92
	v_mov_b32_e32 v147, v146
	v_mov_b32_e32 v149, v148
	ds_write2st64_b64 v77, v[146:147], v[148:149] offset1:2
	v_add_u32_e32 v138, 0xc00, v74
	ds_read_u8 v139, v138
	v_add_u32_e32 v141, 0xc00, v73
	ds_read_u8 v140, v141
	s_add_i32 s43, s67, 64
	v_mov_b32_e32 v138, s43
	ds_read2st64_b32 v[228:229], v138 offset1:1
	ds_read_b128 v[26:29], v227 offset:6144
	ds_read_b128 v[30:33], v227 offset:6160
	v_mov_b32_e32 v38, 0
	v_mov_b32_e32 v39, 0
	v_mov_b32_e32 v40, 0
	v_mov_b32_e32 v41, 0
	v_mov_b32_e32 v42, 0
	v_mov_b32_e32 v43, 0
	v_mov_b32_e32 v44, 0
	v_mov_b32_e32 v45, 0
	v_and_b32_e32 v78, 0xffff, v23
	v_lshrrev_b32_e32 v79, 16, v23
	v_lshl_add_u32 v78, v78, 7, v150
	v_lshl_add_u32 v79, v79, 7, v151
	s_mov_b32 m0, s79
	s_add_i32 s43, s79, 0x400
	global_load_lds_dwordx4 v78, s[50:51]
	s_mov_b32 m0, s43
	s_nop 0
	global_load_lds_dwordx4 v79, s[50:51]
	s_waitcnt vmcnt(8)
; #define LAS __attribute__((address_space(3)))
; __device__ __forceinline__ bf16 f2bf(float f) { return (bf16)f2bfu(f); }
; #define TR4(p_) __builtin_amdgcn_ds_read_tr4_b64_v2i32((LAS v2i*)(p_))
; #define CFENCE() asm volatile("" ::: "memory")
; __device__ __forceinline__ void peer_v_tokens(int j, const LAS unsigned short* EL, const LAS unsigned char* AL  , const LAS float* ASC  , const LAS int* SAL  , ...
;     ...
;         for (int st = 0; st < 16; ++st) {
;             const int p = st >> 2, q = st & 3;
;             if (st < 14) VDMA(st + 2, (st + 2) % 3);
;             if (st < 14) asm volatile("s_waitcnt vmcnt(8)" ::: "memory");
;             else if (st == 14) asm volatile("s_waitcnt vmcnt(4)" ::: "memory");
;             else asm volatile("s_waitcnt vmcnt(0)" ::: "memory");
;             if (q == 0) {
; #pragma unroll
;                 for (int r = 0; r < 4; ++r) { accH[r] = 0; accL[r] = 0; } }
; #pragma unroll
;             for (int tp = 0; tp < 2; ++tp) {
;                 const v2i ao = TR4(ATL + (2 * q + tp) * 128 + 8 * s16), ah = TR4(ATL + 1024 + (2 * q + tp) * 128 + 8 * s16);
; #pragma unroll
;                 for (int r = 0; r < 4; ++r) {
;                     const v2i d = TR4(ldsb + BUF[st % 3] + 2048 * tp + roff[r]);
;                     accH[r] = __builtin_amdgcn_sdot8(d.x, ah.x, accH[r], false); accH[r] = __builtin_amdgcn_sdot8(d.y, ah.y, accH[r], false);
;                     accL[r] = __builtin_amdgcn_sdot8(d.x, ao.x, accL[r], false); accL[r] = __builtin_amdgcn_sdot8(d.y, ao.y, accL[r], false);
;                 }
;             }
;             asm volatile("s_waitcnt lgkmcnt(0)" ::: "memory");
;             if (q == 3) {
; #pragma unroll
;                 for (int r = 0; r < 4; ++r) STASH[256 * p + 16 * (grp + 4 * r) + pc] = f2bf(asc * (float)(2 * ((accH[r] << 4) + accL[r]) + sa));
;             }
;         }
;         CFENCE();
;         {
;             float4 v[4]; float ss = 0.f;
; #pragma unroll
;             for (int jq = 0; jq < 4; ++jq) { typedef unsigned u2v __attribute__((ext_vector_type(2))); const u2v pw = *(const LAS u2v*)(STASH + 4 * lane + 256 * jq); const uint2 hw = hv[jq];
	v_add_u32_e32 v54, s99, v59
	v_add_u32_e32 v55, s99, v60
	v_add_u32_e32 v56, s99, v61
	v_add_u32_e32 v57, s99, v62
	ds_read_b64_tr_b4 v[50:51], v160 offset:128
	ds_read_b64_tr_b4 v[52:53], v160 offset:1152
	ds_read_b64_tr_b4 v[130:131], v54
	ds_read_b64_tr_b4 v[132:133], v55
	ds_read_b64_tr_b4 v[134:135], v56
	ds_read_b64_tr_b4 v[136:137], v57
	s_waitcnt lgkmcnt(12)
	v_dot8c_i32_i4_e32 v38, v122, v48
	v_dot8c_i32_i4_e32 v39, v122, v46
	v_dot8c_i32_i4_e32 v40, v124, v48
	v_dot8c_i32_i4_e32 v41, v124, v46
	v_dot8c_i32_i4_e32 v42, v126, v48
	v_dot8c_i32_i4_e32 v43, v126, v46
	v_dot8c_i32_i4_e32 v44, v128, v48
	v_dot8c_i32_i4_e32 v45, v128, v46
	v_dot8c_i32_i4_e32 v38, v123, v49
	v_dot8c_i32_i4_e32 v39, v123, v47
	v_dot8c_i32_i4_e32 v40, v125, v49
	v_dot8c_i32_i4_e32 v41, v125, v47
	v_dot8c_i32_i4_e32 v42, v127, v49
	v_dot8c_i32_i4_e32 v43, v127, v47
	v_dot8c_i32_i4_e32 v44, v129, v49
	v_dot8c_i32_i4_e32 v45, v129, v47
	v_and_b32_e32 v78, 0xffff, v24
	v_lshrrev_b32_e32 v79, 16, v24
	v_lshl_add_u32 v78, v78, 7, v150
	v_lshl_add_u32 v79, v79, 7, v151
	s_mov_b32 m0, s98
	s_add_i32 s43, s98, 0x400
	global_load_lds_dwordx4 v78, s[50:51]
	s_mov_b32 m0, s43
	s_nop 0
	global_load_lds_dwordx4 v79, s[50:51]
	s_waitcnt vmcnt(8)
	v_add_u32_e32 v54, s76, v59
	v_add_u32_e32 v55, s76, v60
	v_add_u32_e32 v56, s76, v61
	v_add_u32_e32 v57, s76, v62
	ds_read_b64_tr_b4 v[46:47], v160 offset:256
	ds_read_b64_tr_b4 v[48:49], v160 offset:1280
	ds_read_b64_tr_b4 v[122:123], v54
	ds_read_b64_tr_b4 v[124:125], v55
	ds_read_b64_tr_b4 v[126:127], v56
	ds_read_b64_tr_b4 v[128:129], v57
	s_waitcnt lgkmcnt(6)
	v_dot8c_i32_i4_e32 v38, v130, v52
	v_dot8c_i32_i4_e32 v39, v130, v50
	v_dot8c_i32_i4_e32 v40, v132, v52
	v_dot8c_i32_i4_e32 v41, v132, v50
	v_dot8c_i32_i4_e32 v42, v134, v52
	v_dot8c_i32_i4_e32 v43, v134, v50
	v_dot8c_i32_i4_e32 v44, v136, v52
	v_dot8c_i32_i4_e32 v45, v136, v50
	v_dot8c_i32_i4_e32 v38, v131, v53
	v_dot8c_i32_i4_e32 v39, v131, v51
	v_dot8c_i32_i4_e32 v40, v133, v53
	v_dot8c_i32_i4_e32 v41, v133, v51
	v_dot8c_i32_i4_e32 v42, v135, v53
	v_dot8c_i32_i4_e32 v43, v135, v51
	v_dot8c_i32_i4_e32 v44, v137, v53
	v_dot8c_i32_i4_e32 v45, v137, v51
	ds_write_b16 v65, v162
	ds_write_b16_d16_hi v65, v162 offset:128
	ds_write_b16 v65, v163 offset:256
	ds_write_b16_d16_hi v65, v163 offset:384
	ds_write_b16 v65, v164 offset:512
	ds_write_b16_d16_hi v65, v164 offset:640
	ds_write_b16 v65, v165 offset:768
	ds_write_b16_d16_hi v65, v165 offset:896
	ds_write_b16 v65, v166 offset:1024
	ds_write_b16_d16_hi v65, v166 offset:1152
	ds_write_b16 v65, v167 offset:1280
	ds_write_b16_d16_hi v65, v167 offset:1408
	ds_write_b16 v65, v168 offset:1536
	ds_write_b16_d16_hi v65, v168 offset:1664
	ds_write_b16 v65, v169 offset:1792
	ds_write_b16_d16_hi v65, v169 offset:1920
	ds_read_b64 v[202:203], v154
	ds_read_b64 v[204:205], v154 offset:512
	ds_read_b64 v[206:207], v154 offset:1024
	ds_read_b64 v[208:209], v154 offset:1536
	v_and_b32_e32 v78, 0xffff, v25
	v_lshrrev_b32_e32 v79, 16, v25
	v_lshl_add_u32 v78, v78, 7, v150
	v_lshl_add_u32 v79, v79, 7, v151
	s_mov_b32 m0, s99
	s_add_i32 s43, s99, 0x400
	global_load_lds_dwordx4 v78, s[50:51]
	s_mov_b32 m0, s43
	s_nop 0
	global_load_lds_dwordx4 v79, s[50:51]
	s_waitcnt vmcnt(8)
	v_add_u32_e32 v54, s77, v59
	v_add_u32_e32 v55, s77, v60
	v_add_u32_e32 v56, s77, v61
	v_add_u32_e32 v57, s77, v62
	ds_read_b64_tr_b4 v[50:51], v160 offset:384
	ds_read_b64_tr_b4 v[52:53], v160 offset:1408
	ds_read_b64_tr_b4 v[130:131], v54
	ds_read_b64_tr_b4 v[132:133], v55
	ds_read_b64_tr_b4 v[134:135], v56
	ds_read_b64_tr_b4 v[136:137], v57
	s_waitcnt lgkmcnt(15)
	v_dot8c_i32_i4_e32 v38, v122, v48
	v_dot8c_i32_i4_e32 v39, v122, v46
	v_dot8c_i32_i4_e32 v40, v124, v48
	v_dot8c_i32_i4_e32 v41, v124, v46
	v_dot8c_i32_i4_e32 v42, v126, v48
	v_dot8c_i32_i4_e32 v43, v126, v46
	v_dot8c_i32_i4_e32 v44, v128, v48
	v_dot8c_i32_i4_e32 v45, v128, v46
	v_dot8c_i32_i4_e32 v38, v123, v49
	v_dot8c_i32_i4_e32 v39, v123, v47
	v_dot8c_i32_i4_e32 v40, v125, v49
	v_dot8c_i32_i4_e32 v41, v125, v47
	v_dot8c_i32_i4_e32 v42, v127, v49
	v_dot8c_i32_i4_e32 v43, v127, v47
	v_dot8c_i32_i4_e32 v44, v129, v49
	v_dot8c_i32_i4_e32 v45, v129, v47
	s_waitcnt lgkmcnt(15)
	v_and_b32_e32 v78, 0xffff, v26
	v_lshrrev_b32_e32 v79, 16, v26
	v_lshl_add_u32 v78, v78, 7, v150
	v_lshl_add_u32 v79, v79, 7, v151
	s_mov_b32 m0, s76
	s_add_i32 s43, s76, 0x400
	global_load_lds_dwordx4 v78, s[50:51]
	s_mov_b32 m0, s43
	s_nop 0
	global_load_lds_dwordx4 v79, s[50:51]
	s_waitcnt vmcnt(8)
	v_add_u32_e32 v54, s78, v59
	v_add_u32_e32 v55, s78, v60
	v_add_u32_e32 v56, s78, v61
	v_add_u32_e32 v57, s78, v62
	ds_read_b64_tr_b4 v[46:47], v160 offset:512
	ds_read_b64_tr_b4 v[48:49], v160 offset:1536
	ds_read_b64_tr_b4 v[122:123], v54
	ds_read_b64_tr_b4 v[124:125], v55
	ds_read_b64_tr_b4 v[126:127], v56
	ds_read_b64_tr_b4 v[128:129], v57
	s_waitcnt lgkmcnt(6)
	v_dot8c_i32_i4_e32 v38, v130, v52
	v_dot8c_i32_i4_e32 v39, v130, v50
	v_dot8c_i32_i4_e32 v40, v132, v52
	v_dot8c_i32_i4_e32 v41, v132, v50
	v_dot8c_i32_i4_e32 v42, v134, v52
	v_dot8c_i32_i4_e32 v43, v134, v50
	v_dot8c_i32_i4_e32 v44, v136, v52
	v_dot8c_i32_i4_e32 v45, v136, v50
	v_dot8c_i32_i4_e32 v38, v131, v53
	v_dot8c_i32_i4_e32 v39, v131, v51
	v_dot8c_i32_i4_e32 v40, v133, v53
	v_dot8c_i32_i4_e32 v41, v133, v51
	v_dot8c_i32_i4_e32 v42, v135, v53
	v_dot8c_i32_i4_e32 v43, v135, v51
	v_dot8c_i32_i4_e32 v44, v137, v53
	v_dot8c_i32_i4_e32 v45, v137, v51
	v_and_b32_e32 v78, 0xffff, v27
	v_lshrrev_b32_e32 v79, 16, v27
	v_lshl_add_u32 v78, v78, 7, v150
	v_lshl_add_u32 v79, v79, 7, v151
	s_mov_b32 m0, s77
	s_add_i32 s43, s77, 0x400
	global_load_lds_dwordx4 v78, s[50:51]
	s_mov_b32 m0, s43
	s_nop 0
	global_load_lds_dwordx4 v79, s[50:51]
	s_waitcnt vmcnt(8)
; #define LAS __attribute__((address_space(3)))
; #define TR4(p_) __builtin_amdgcn_ds_read_tr4_b64_v2i32((LAS v2i*)(p_))
; #define CFENCE() asm volatile("" ::: "memory")
; __device__ __forceinline__ void peer_v_tokens(int j, const LAS unsigned short* EL, const LAS unsigned char* AL  , const LAS float* ASC  , const LAS int* SAL  , ...
;     ...
;         for (int m = 0; m < 2; ++m) {
;             const int idx = lane + 64 * m, tau = idx >> 4, sr = idx & 15, k = 16 * (sr & 7) + 2 * tau + (sr >> 3);
;             const int aq = (int)*(const LAS signed char*)(AL + tl * 128 + k); const int tq = aq + 8;
;             const unsigned lo = (((unsigned)tq & 15u) ^ 8u) * 0x11111111u, hi = ((unsigned)(tq >> 4) & 15u) * 0x11111111u;
;             typedef unsigned u2v __attribute__((ext_vector_type(2)));
;             u2v l2; l2.x = lo; l2.y = lo; u2v h2; h2.x = hi; h2.y = hi;
;             *(LAS u2v*)(ATL + 8 * idx) = l2; *(LAS u2v*)(ATL + 1024 + 8 * idx) = h2;
;         }
;         const float asc = ASC[tl]; const int sa = SAL[tl];
;         CFENCE();
;         int accH[4], accL[4];
; #pragma unroll
;         for (int st = 0; st < 16; ++st) {
;             const int p = st >> 2, q = st & 3;
;             if (st < 14) VDMA(st + 2, (st + 2) % 3);
;             if (st < 14) asm volatile("s_waitcnt vmcnt(8)" ::: "memory");
;             else if (st == 14) asm volatile("s_waitcnt vmcnt(4)" ::: "memory");
;             else asm volatile("s_waitcnt vmcnt(0)" ::: "memory");
;             if (q == 0) {
; #pragma unroll
;                 for (int r = 0; r < 4; ++r) { accH[r] = 0; accL[r] = 0; } }
; #pragma unroll
;             for (int tp = 0; tp < 2; ++tp) {
;                 const v2i ao = TR4(ATL + (2 * q + tp) * 128 + 8 * s16), ah = TR4(ATL + 1024 + (2 * q + tp) * 128 + 8 * s16);
; #pragma unroll
;                 for (int r = 0; r < 4; ++r) {
;                     const v2i d = TR4(ldsb + BUF[st % 3] + 2048 * tp + roff[r]);
;                     accH[r] = __builtin_amdgcn_sdot8(d.x, ah.x, accH[r], false); accH[r] = __builtin_amdgcn_sdot8(d.y, ah.y, accH[r], false);
;                     accL[r] = __builtin_amdgcn_sdot8(d.x, ao.x, accL[r], false); accL[r] = __builtin_amdgcn_sdot8(d.y, ao.y, accL[r], false);
;                 }
;             }
	v_add_u32_e32 v54, s79, v59
	v_add_u32_e32 v55, s79, v60
	v_add_u32_e32 v56, s79, v61
	v_add_u32_e32 v57, s79, v62
	ds_read_b64_tr_b4 v[50:51], v160 offset:640
	ds_read_b64_tr_b4 v[52:53], v160 offset:1664
	ds_read_b64_tr_b4 v[130:131], v54
	ds_read_b64_tr_b4 v[132:133], v55
	ds_read_b64_tr_b4 v[134:135], v56
	ds_read_b64_tr_b4 v[136:137], v57
	s_waitcnt lgkmcnt(6)
	v_dot8c_i32_i4_e32 v38, v122, v48
	v_dot8c_i32_i4_e32 v39, v122, v46
	v_dot8c_i32_i4_e32 v40, v124, v48
	v_dot8c_i32_i4_e32 v41, v124, v46
	v_dot8c_i32_i4_e32 v42, v126, v48
	v_dot8c_i32_i4_e32 v43, v126, v46
	v_dot8c_i32_i4_e32 v44, v128, v48
	v_dot8c_i32_i4_e32 v45, v128, v46
	v_dot8c_i32_i4_e32 v38, v123, v49
	v_dot8c_i32_i4_e32 v39, v123, v47
	v_dot8c_i32_i4_e32 v40, v125, v49
	v_dot8c_i32_i4_e32 v41, v125, v47
	v_dot8c_i32_i4_e32 v42, v127, v49
	v_dot8c_i32_i4_e32 v43, v127, v47
	v_dot8c_i32_i4_e32 v44, v129, v49
	v_dot8c_i32_i4_e32 v45, v129, v47
	s_waitcnt lgkmcnt(15)
	v_add_u32_e32 v143, 8, v139
	v_and_b32_e32 v142, 15, v143
	v_xor_b32_e32 v142, 8, v142
	v_bfe_u32 v144, v143, 4, 4
	v_mul_lo_u32 v142, v142, s92
	v_mul_lo_u32 v144, v144, s92
	v_mov_b32_e32 v143, v142
	v_mov_b32_e32 v145, v144
	ds_write2st64_b64 v159, v[142:143], v[144:145] offset1:2
	v_and_b32_e32 v78, 0xffff, v28
	v_lshrrev_b32_e32 v79, 16, v28
	v_lshl_add_u32 v78, v78, 7, v150
	v_lshl_add_u32 v79, v79, 7, v151
	s_mov_b32 m0, s78
	s_add_i32 s43, s78, 0x400
	global_load_lds_dwordx4 v78, s[50:51]
	s_mov_b32 m0, s43
	s_nop 0
	global_load_lds_dwordx4 v79, s[50:51]
	s_waitcnt vmcnt(8)
	v_add_u32_e32 v54, s98, v59
	v_add_u32_e32 v55, s98, v60
	v_add_u32_e32 v56, s98, v61
	v_add_u32_e32 v57, s98, v62
	ds_read_b64_tr_b4 v[46:47], v160 offset:768
	ds_read_b64_tr_b4 v[48:49], v160 offset:1792
	ds_read_b64_tr_b4 v[122:123], v54
	ds_read_b64_tr_b4 v[124:125], v55
	ds_read_b64_tr_b4 v[126:127], v56
	ds_read_b64_tr_b4 v[128:129], v57
	s_waitcnt lgkmcnt(7)
	v_dot8c_i32_i4_e32 v38, v130, v52
	v_dot8c_i32_i4_e32 v39, v130, v50
	v_dot8c_i32_i4_e32 v40, v132, v52
	v_dot8c_i32_i4_e32 v41, v132, v50
	v_dot8c_i32_i4_e32 v42, v134, v52
	v_dot8c_i32_i4_e32 v43, v134, v50
	v_dot8c_i32_i4_e32 v44, v136, v52
	v_dot8c_i32_i4_e32 v45, v136, v50
	v_dot8c_i32_i4_e32 v38, v131, v53
	v_dot8c_i32_i4_e32 v39, v131, v51
	v_dot8c_i32_i4_e32 v40, v133, v53
	v_dot8c_i32_i4_e32 v41, v133, v51
	v_dot8c_i32_i4_e32 v42, v135, v53
	v_dot8c_i32_i4_e32 v43, v135, v51
	v_dot8c_i32_i4_e32 v44, v137, v53
	v_dot8c_i32_i4_e32 v45, v137, v51
	v_and_b32_e32 v78, 0xffff, v29
	v_lshrrev_b32_e32 v79, 16, v29
	v_lshl_add_u32 v78, v78, 7, v150
	v_lshl_add_u32 v79, v79, 7, v151
	s_mov_b32 m0, s79
	s_add_i32 s43, s79, 0x400
	global_load_lds_dwordx4 v78, s[50:51]
	s_mov_b32 m0, s43
	s_nop 0
	global_load_lds_dwordx4 v79, s[50:51]
	s_waitcnt vmcnt(8)
	v_add_u32_e32 v54, s99, v59
	v_add_u32_e32 v55, s99, v60
	v_add_u32_e32 v56, s99, v61
	v_add_u32_e32 v57, s99, v62
	ds_read_b64_tr_b4 v[50:51], v160 offset:896
	ds_read_b64_tr_b4 v[52:53], v160 offset:1920
	ds_read_b64_tr_b4 v[130:131], v54
	ds_read_b64_tr_b4 v[132:133], v55
	ds_read_b64_tr_b4 v[134:135], v56
	ds_read_b64_tr_b4 v[136:137], v57
	s_waitcnt lgkmcnt(6)
	v_dot8c_i32_i4_e32 v38, v122, v48
	v_dot8c_i32_i4_e32 v39, v122, v46
	v_dot8c_i32_i4_e32 v40, v124, v48
	v_dot8c_i32_i4_e32 v41, v124, v46
	v_dot8c_i32_i4_e32 v42, v126, v48
	v_dot8c_i32_i4_e32 v43, v126, v46
	v_dot8c_i32_i4_e32 v44, v128, v48
	v_dot8c_i32_i4_e32 v45, v128, v46
	v_dot8c_i32_i4_e32 v38, v123, v49
	v_dot8c_i32_i4_e32 v39, v123, v47
	v_dot8c_i32_i4_e32 v40, v125, v49
	v_dot8c_i32_i4_e32 v41, v125, v47
	v_dot8c_i32_i4_e32 v42, v127, v49
	v_dot8c_i32_i4_e32 v43, v127, v47
	v_dot8c_i32_i4_e32 v44, v129, v49
	v_dot8c_i32_i4_e32 v45, v129, v47
	v_and_b32_e32 v78, 0xffff, v30
	v_lshrrev_b32_e32 v79, 16, v30
	v_lshl_add_u32 v78, v78, 7, v150
	v_lshl_add_u32 v79, v79, 7, v151
	s_mov_b32 m0, s98
	s_add_i32 s43, s98, 0x400
	global_load_lds_dwordx4 v78, s[50:51]
	s_mov_b32 m0, s43
	s_nop 0
	global_load_lds_dwordx4 v79, s[50:51]
	s_waitcnt vmcnt(8)
	v_add_u32_e32 v54, s76, v59
	v_add_u32_e32 v55, s76, v60
	v_add_u32_e32 v56, s76, v61
	v_add_u32_e32 v57, s76, v62
	ds_read_b64_tr_b4 v[46:47], v160
	ds_read_b64_tr_b4 v[48:49], v160 offset:1024
	ds_read_b64_tr_b4 v[122:123], v54
	ds_read_b64_tr_b4 v[124:125], v55
	ds_read_b64_tr_b4 v[126:127], v56
	ds_read_b64_tr_b4 v[128:129], v57
	s_waitcnt lgkmcnt(6)
	v_dot8c_i32_i4_e32 v38, v130, v52
	v_dot8c_i32_i4_e32 v39, v130, v50
	v_dot8c_i32_i4_e32 v40, v132, v52
	v_dot8c_i32_i4_e32 v41, v132, v50
	v_dot8c_i32_i4_e32 v42, v134, v52
	v_dot8c_i32_i4_e32 v43, v134, v50
	v_dot8c_i32_i4_e32 v44, v136, v52
	v_dot8c_i32_i4_e32 v45, v136, v50
	v_dot8c_i32_i4_e32 v38, v131, v53
	v_dot8c_i32_i4_e32 v39, v131, v51
	v_dot8c_i32_i4_e32 v40, v133, v53
	v_dot8c_i32_i4_e32 v41, v133, v51
	v_dot8c_i32_i4_e32 v42, v135, v53
	v_dot8c_i32_i4_e32 v43, v135, v51
	v_dot8c_i32_i4_e32 v44, v137, v53
	v_dot8c_i32_i4_e32 v45, v137, v51
	s_nop 3
	s_waitcnt lgkmcnt(15)
; #define LAS __attribute__((address_space(3)))
; __device__ __forceinline__ bf16 f2bf(float f) { return (bf16)f2bfu(f); }
; #define CFENCE() asm volatile("" ::: "memory")
; __device__ __forceinline__ void peer_v_tokens(int j, const LAS unsigned short* EL, const LAS unsigned char* AL  , const LAS float* ASC  , const LAS int* SAL  , ...
;     ...
;         for (int m = 0; m < 2; ++m) {
;             const int idx = lane + 64 * m, tau = idx >> 4, sr = idx & 15, k = 16 * (sr & 7) + 2 * tau + (sr >> 3);
;             const int aq = (int)*(const LAS signed char*)(AL + tl * 128 + k); const int tq = aq + 8;
;             const unsigned lo = (((unsigned)tq & 15u) ^ 8u) * 0x11111111u, hi = ((unsigned)(tq >> 4) & 15u) * 0x11111111u;
;             typedef unsigned u2v __attribute__((ext_vector_type(2)));
;             u2v l2; l2.x = lo; l2.y = lo; u2v h2; h2.x = hi; h2.y = hi;
;             *(LAS u2v*)(ATL + 8 * idx) = l2; *(LAS u2v*)(ATL + 1024 + 8 * idx) = h2;
;         }
;     ...
;                 for (int r = 0; r < 4; ++r) STASH[256 * p + 16 * (grp + 4 * r) + pc] = f2bf(asc * (float)(2 * ((accH[r] << 4) + accL[r]) + sa));
;             }
;         }
;         CFENCE();
;         {
;             float4 v[4]; float ss = 0.f;
; #pragma unroll
;             for (int jq = 0; jq < 4; ++jq) { typedef unsigned u2v __attribute__((ext_vector_type(2))); const u2v pw = *(const LAS u2v*)(STASH + 4 * lane + 256 * jq); const uint2 hw = hv[jq];
;                 v[jq] = make_float4(__uint_as_float(hw.x << 16) + __uint_as_float(pw.x << 16), __uint_as_float(hw.x & 0xffff0000u) + __uint_as_float(pw.x & 0xffff0000u),
;                                     __uint_as_float(hw.y << 16) + __uint_as_float(pw.y << 16), __uint_as_float(hw.y & 0xffff0000u) + __uint_as_float(pw.y & 0xffff0000u));
;                 ss += v[jq].x * v[jq].x + v[jq].y * v[jq].y + v[jq].z * v[jq].z + v[jq].w * v[jq].w; }
;             ss = wave_sum(ss);
;             const float r3 = rsqrtf(ss * (1.f / D) + EPS);
	v_lshlrev_b32_e32 v38, 5, v38
	v_lshlrev_b32_e32 v39, 1, v39
	v_add3_u32 v38, v39, v229, v38
	v_cvt_f32_i32_e32 v38, v38
	v_mul_f32_e32 v38, v228, v38
	v_lshlrev_b32_e32 v40, 5, v40
	v_lshlrev_b32_e32 v41, 1, v41
	v_add3_u32 v40, v41, v229, v40
	v_cvt_f32_i32_e32 v40, v40
	v_mul_f32_e32 v40, v228, v40
	v_lshlrev_b32_e32 v42, 5, v42
	v_lshlrev_b32_e32 v43, 1, v43
	v_add3_u32 v42, v43, v229, v42
	v_cvt_f32_i32_e32 v42, v42
	v_mul_f32_e32 v42, v228, v42
	v_lshlrev_b32_e32 v44, 5, v44
	v_lshlrev_b32_e32 v45, 1, v45
	v_add3_u32 v44, v45, v229, v44
	v_cvt_f32_i32_e32 v44, v44
	v_mul_f32_e32 v44, v228, v44
	v_cvt_pk_bf16_f32 v178, v38, v40
	v_cvt_pk_bf16_f32 v179, v42, v44
	v_add_u32_e32 v147, 8, v140
	v_and_b32_e32 v146, 15, v147
	v_xor_b32_e32 v146, 8, v146
	v_bfe_u32 v148, v147, 4, 4
	v_mul_lo_u32 v146, v146, s92
	v_mul_lo_u32 v148, v148, s92
	v_mov_b32_e32 v147, v146
	v_mov_b32_e32 v149, v148
	ds_write2st64_b64 v77, v[146:147], v[148:149] offset1:2
	v_add_u32_e32 v138, 0x800, v74
	ds_read_u8 v139, v138
	v_add_u32_e32 v141, 0x800, v73
	ds_read_u8 v140, v141
	s_add_i32 s43, s67, 96
	v_mov_b32_e32 v138, s43
	ds_read2st64_b32 v[228:229], v138 offset1:1
	ds_read_b128 v[18:21], v227 offset:4096
	ds_read_b128 v[22:25], v227 offset:4112
	v_add_u32_e32 v152, 0x200000, v63
	v_add_u32_e32 v153, 0x200000, v64
	v_mov_b32_e32 v38, 0
	v_mov_b32_e32 v39, 0
	v_mov_b32_e32 v40, 0
	v_mov_b32_e32 v41, 0
	v_mov_b32_e32 v42, 0
	v_mov_b32_e32 v43, 0
	v_mov_b32_e32 v44, 0
	v_mov_b32_e32 v45, 0
	v_and_b32_e32 v78, 0xffff, v31
	v_lshrrev_b32_e32 v79, 16, v31
	v_lshl_add_u32 v78, v78, 7, v150
	v_lshl_add_u32 v79, v79, 7, v151
	s_mov_b32 m0, s99
	s_add_i32 s43, s99, 0x400
	global_load_lds_dwordx4 v78, s[50:51]
	s_mov_b32 m0, s43
	s_nop 0
	global_load_lds_dwordx4 v79, s[50:51]
	s_waitcnt vmcnt(8)
	v_add_u32_e32 v54, s77, v59
	v_add_u32_e32 v55, s77, v60
	v_add_u32_e32 v56, s77, v61
	v_add_u32_e32 v57, s77, v62
	ds_read_b64_tr_b4 v[50:51], v160 offset:128
	ds_read_b64_tr_b4 v[52:53], v160 offset:1152
	ds_read_b64_tr_b4 v[130:131], v54
	ds_read_b64_tr_b4 v[132:133], v55
	ds_read_b64_tr_b4 v[134:135], v56
	ds_read_b64_tr_b4 v[136:137], v57
	s_waitcnt lgkmcnt(12)
	s_waitcnt vmcnt(34) lgkmcnt(15)
	v_lshlrev_b32_e32 v210, 16, v194
	v_and_b32_e32 v211, 0xffff0000, v194
	v_lshlrev_b32_e32 v142, 16, v202
	v_and_b32_e32 v143, 0xffff0000, v202
	v_add_f32_e32 v210, v210, v142
	v_add_f32_e32 v211, v211, v143
	v_lshlrev_b32_e32 v212, 16, v195
	v_and_b32_e32 v213, 0xffff0000, v195
	v_lshlrev_b32_e32 v142, 16, v203
	v_and_b32_e32 v143, 0xffff0000, v203
	v_add_f32_e32 v212, v212, v142
	v_add_f32_e32 v213, v213, v143
	v_lshlrev_b32_e32 v214, 16, v196
	v_and_b32_e32 v215, 0xffff0000, v196
	v_lshlrev_b32_e32 v142, 16, v204
	v_and_b32_e32 v143, 0xffff0000, v204
	v_add_f32_e32 v214, v214, v142
	v_add_f32_e32 v215, v215, v143
	v_lshlrev_b32_e32 v216, 16, v197
	v_and_b32_e32 v217, 0xffff0000, v197
	v_lshlrev_b32_e32 v142, 16, v205
	v_and_b32_e32 v143, 0xffff0000, v205
	v_add_f32_e32 v216, v216, v142
	v_add_f32_e32 v217, v217, v143
	v_lshlrev_b32_e32 v218, 16, v198
	v_and_b32_e32 v219, 0xffff0000, v198
	v_lshlrev_b32_e32 v142, 16, v206
	v_and_b32_e32 v143, 0xffff0000, v206
	v_add_f32_e32 v218, v218, v142
	v_add_f32_e32 v219, v219, v143
	v_lshlrev_b32_e32 v220, 16, v199
	v_and_b32_e32 v221, 0xffff0000, v199
	v_lshlrev_b32_e32 v142, 16, v207
	v_and_b32_e32 v143, 0xffff0000, v207
	v_add_f32_e32 v220, v220, v142
	v_add_f32_e32 v221, v221, v143
	v_lshlrev_b32_e32 v222, 16, v200
	v_and_b32_e32 v223, 0xffff0000, v200
	v_lshlrev_b32_e32 v142, 16, v208
	v_and_b32_e32 v143, 0xffff0000, v208
	v_add_f32_e32 v222, v222, v142
	v_add_f32_e32 v223, v223, v143
	v_lshlrev_b32_e32 v224, 16, v201
	v_and_b32_e32 v225, 0xffff0000, v201
	v_lshlrev_b32_e32 v142, 16, v209
	v_and_b32_e32 v143, 0xffff0000, v209
	v_add_f32_e32 v224, v224, v142
	v_add_f32_e32 v225, v225, v143
	v_mov_b32_e32 v144, 0
	v_mul_f32_e32 v145, v210, v210
	v_fmac_f32_e32 v145, v211, v211
	v_fmac_f32_e32 v145, v212, v212
	v_fmac_f32_e32 v145, v213, v213
	v_add_f32_e32 v144, v144, v145
	v_mul_f32_e32 v145, v214, v214
	v_fmac_f32_e32 v145, v215, v215
	v_fmac_f32_e32 v145, v216, v216
	v_fmac_f32_e32 v145, v217, v217
	v_add_f32_e32 v144, v144, v145
	v_mul_f32_e32 v145, v218, v218
	v_fmac_f32_e32 v145, v219, v219
	v_fmac_f32_e32 v145, v220, v220
	v_fmac_f32_e32 v145, v221, v221
	v_add_f32_e32 v144, v144, v145
	v_mul_f32_e32 v145, v222, v222
	v_fmac_f32_e32 v145, v223, v223
	v_fmac_f32_e32 v145, v224, v224
	v_fmac_f32_e32 v145, v225, v225
	v_add_f32_e32 v144, v144, v145
	s_nop 1
	v_add_f32_dpp v144, v144, v144 quad_perm:[1,0,3,2] row_mask:0xf bank_mask:0xf bound_ctrl:1
	s_nop 1
	v_add_f32_dpp v144, v144, v144 quad_perm:[2,3,0,1] row_mask:0xf bank_mask:0xf bound_ctrl:1
	s_nop 1
	v_add_f32_dpp v144, v144, v144 row_half_mirror row_mask:0xf bank_mask:0xf bound_ctrl:1
	s_nop 1
	v_add_f32_dpp v144, v144, v144 row_mirror row_mask:0xf bank_mask:0xf bound_ctrl:1
	s_nop 1
	v_readlane_b32 s10, v144, 0
	v_readlane_b32 s11, v144, 16
	v_readlane_b32 s14, v144, 32
	v_readlane_b32 s15, v144, 48
	s_nop 3
	v_mov_b32_e32 v144, s11
	v_mov_b32_e32 v145, s15
	v_add_f32_e32 v144, s10, v144
	v_add_f32_e32 v145, s14, v145
	v_add_f32_e32 v144, v144, v145
	v_fmamk_f32 v144, v144, 0x3a800000, v111
	v_rsq_f32_e32 v144, v144
	s_nop 0
	v_mul_f32_e32 v210, v210, v144
	v_mul_f32_e32 v211, v211, v144
	v_mul_f32_e32 v212, v212, v144
	v_mul_f32_e32 v213, v213, v144
	v_mul_f32_e32 v214, v214, v144
	v_mul_f32_e32 v215, v215, v144
	v_mul_f32_e32 v216, v216, v144
	v_mul_f32_e32 v217, v217, v144
	v_mul_f32_e32 v218, v218, v144
	v_mul_f32_e32 v219, v219, v144
	v_mul_f32_e32 v220, v220, v144
	v_mul_f32_e32 v221, v221, v144
	v_mul_f32_e32 v222, v222, v144
	v_mul_f32_e32 v223, v223, v144
	v_mul_f32_e32 v224, v224, v144
	v_mul_f32_e32 v225, v225, v144
	v_dot8c_i32_i4_e32 v38, v122, v48
	v_dot8c_i32_i4_e32 v39, v122, v46
	v_dot8c_i32_i4_e32 v40, v124, v48
	v_dot8c_i32_i4_e32 v41, v124, v46
	v_dot8c_i32_i4_e32 v42, v126, v48
	v_dot8c_i32_i4_e32 v43, v126, v46
	v_dot8c_i32_i4_e32 v44, v128, v48
	v_dot8c_i32_i4_e32 v45, v128, v46
	v_dot8c_i32_i4_e32 v38, v123, v49
	v_dot8c_i32_i4_e32 v39, v123, v47
	v_dot8c_i32_i4_e32 v40, v125, v49
	v_dot8c_i32_i4_e32 v41, v125, v47
	v_dot8c_i32_i4_e32 v42, v127, v49
	v_dot8c_i32_i4_e32 v43, v127, v47
	v_dot8c_i32_i4_e32 v44, v129, v49
	v_dot8c_i32_i4_e32 v45, v129, v47
	v_and_b32_e32 v78, 0xffff, v32
	v_lshrrev_b32_e32 v79, 16, v32
	v_lshl_add_u32 v78, v78, 7, v150
	v_lshl_add_u32 v79, v79, 7, v151
	s_mov_b32 m0, s76
	s_add_i32 s43, s76, 0x400
	global_load_lds_dwordx4 v78, s[50:51]
	s_mov_b32 m0, s43
	s_nop 0
	global_load_lds_dwordx4 v79, s[50:51]
	s_waitcnt vmcnt(8)
; #define TR4(p_) __builtin_amdgcn_ds_read_tr4_b64_v2i32((LAS v2i*)(p_))
; #define VDMA(st_, k_) do { _Pragma("unroll") for (int i_ = 0; i_ < 4; ++i_) { \
;         const unsigned off_ = (unsigned)((st_) >> 2) * (16384u * 128u) + (PE_ID(E, 4 * ((st_) & 3) + i_) << 7) + ((i_ & 1) ? cx1 : cx0); \
;         __builtin_amdgcn_global_load_lds((const unsigned*)(V4 + off_), (LAS unsigned*)(ldsb + BUF[k_] + 1024 * i_), 16, 0, 0); } } while (0)
; __device__ __forceinline__ void peer_v_tokens(int j, const LAS unsigned short* EL, const LAS unsigned char* AL  , const LAS float* ASC  , const LAS int* SAL  , ...
;     ...
;         for (int st = 0; st < 16; ++st) {
;             const int p = st >> 2, q = st & 3;
;             if (st < 14) VDMA(st + 2, (st + 2) % 3);
;             if (st < 14) asm volatile("s_waitcnt vmcnt(8)" ::: "memory");
;             else if (st == 14) asm volatile("s_waitcnt vmcnt(4)" ::: "memory");
;             else asm volatile("s_waitcnt vmcnt(0)" ::: "memory");
;             if (q == 0) {
; #pragma unroll
;                 for (int r = 0; r < 4; ++r) { accH[r] = 0; accL[r] = 0; } }
; #pragma unroll
;             for (int tp = 0; tp < 2; ++tp) {
;                 const v2i ao = TR4(ATL + (2 * q + tp) * 128 + 8 * s16), ah = TR4(ATL + 1024 + (2 * q + tp) * 128 + 8 * s16);
; #pragma unroll
;                 for (int r = 0; r < 4; ++r) {
;                     const v2i d = TR4(ldsb + BUF[st % 3] + 2048 * tp + roff[r]);
;                     accH[r] = __builtin_amdgcn_sdot8(d.x, ah.x, accH[r], false); accH[r] = __builtin_amdgcn_sdot8(d.y, ah.y, accH[r], false);
;                     accL[r] = __builtin_amdgcn_sdot8(d.x, ao.x, accL[r], false); accL[r] = __builtin_amdgcn_sdot8(d.y, ao.y, accL[r], false);
;                 }
;             }
	v_add_u32_e32 v54, s78, v59
	v_add_u32_e32 v55, s78, v60
	v_add_u32_e32 v56, s78, v61
	v_add_u32_e32 v57, s78, v62
	ds_read_b64_tr_b4 v[46:47], v160 offset:256
	ds_read_b64_tr_b4 v[48:49], v160 offset:1280
	ds_read_b64_tr_b4 v[122:123], v54
	ds_read_b64_tr_b4 v[124:125], v55
	ds_read_b64_tr_b4 v[126:127], v56
	ds_read_b64_tr_b4 v[128:129], v57
	s_waitcnt lgkmcnt(6)
	v_dot8c_i32_i4_e32 v38, v130, v52
	v_dot8c_i32_i4_e32 v39, v130, v50
	v_dot8c_i32_i4_e32 v40, v132, v52
	v_dot8c_i32_i4_e32 v41, v132, v50
	v_dot8c_i32_i4_e32 v42, v134, v52
	v_dot8c_i32_i4_e32 v43, v134, v50
	v_dot8c_i32_i4_e32 v44, v136, v52
	v_dot8c_i32_i4_e32 v45, v136, v50
	v_dot8c_i32_i4_e32 v38, v131, v53
	v_dot8c_i32_i4_e32 v39, v131, v51
	v_dot8c_i32_i4_e32 v40, v133, v53
	v_dot8c_i32_i4_e32 v41, v133, v51
	v_dot8c_i32_i4_e32 v42, v135, v53
	v_dot8c_i32_i4_e32 v43, v135, v51
	v_dot8c_i32_i4_e32 v44, v137, v53
	v_dot8c_i32_i4_e32 v45, v137, v51
	v_and_b32_e32 v78, 0xffff, v33
	v_lshrrev_b32_e32 v79, 16, v33
	v_lshl_add_u32 v78, v78, 7, v150
	v_lshl_add_u32 v79, v79, 7, v151
	s_mov_b32 m0, s77
	s_add_i32 s43, s77, 0x400
	global_load_lds_dwordx4 v78, s[50:51]
	s_mov_b32 m0, s43
	s_nop 0
	global_load_lds_dwordx4 v79, s[50:51]
	s_waitcnt vmcnt(8)
	v_add_u32_e32 v54, s79, v59
	v_add_u32_e32 v55, s79, v60
	v_add_u32_e32 v56, s79, v61
	v_add_u32_e32 v57, s79, v62
	ds_read_b64_tr_b4 v[50:51], v160 offset:384
	ds_read_b64_tr_b4 v[52:53], v160 offset:1408
	ds_read_b64_tr_b4 v[130:131], v54
	ds_read_b64_tr_b4 v[132:133], v55
	ds_read_b64_tr_b4 v[134:135], v56
	ds_read_b64_tr_b4 v[136:137], v57
	s_waitcnt lgkmcnt(6)
	v_dot8c_i32_i4_e32 v38, v122, v48
	v_dot8c_i32_i4_e32 v39, v122, v46
	v_dot8c_i32_i4_e32 v40, v124, v48
	v_dot8c_i32_i4_e32 v41, v124, v46
	v_dot8c_i32_i4_e32 v42, v126, v48
	v_dot8c_i32_i4_e32 v43, v126, v46
	v_dot8c_i32_i4_e32 v44, v128, v48
	v_dot8c_i32_i4_e32 v45, v128, v46
	v_dot8c_i32_i4_e32 v38, v123, v49
	v_dot8c_i32_i4_e32 v39, v123, v47
	v_dot8c_i32_i4_e32 v40, v125, v49
	v_dot8c_i32_i4_e32 v41, v125, v47
	v_dot8c_i32_i4_e32 v42, v127, v49
	v_dot8c_i32_i4_e32 v43, v127, v47
	v_dot8c_i32_i4_e32 v44, v129, v49
	v_dot8c_i32_i4_e32 v45, v129, v47
	s_waitcnt lgkmcnt(15)
	v_and_b32_e32 v78, 0xffff, v18
	v_lshrrev_b32_e32 v79, 16, v18
	v_lshl_add_u32 v78, v78, 7, v152
	v_lshl_add_u32 v79, v79, 7, v153
	s_mov_b32 m0, s78
	s_add_i32 s43, s78, 0x400
	global_load_lds_dwordx4 v78, s[50:51]
	s_mov_b32 m0, s43
	s_nop 0
	global_load_lds_dwordx4 v79, s[50:51]
	s_waitcnt vmcnt(8)
	v_add_u32_e32 v54, s98, v59
	v_add_u32_e32 v55, s98, v60
	v_add_u32_e32 v56, s98, v61
	v_add_u32_e32 v57, s98, v62
	ds_read_b64_tr_b4 v[46:47], v160 offset:512
	ds_read_b64_tr_b4 v[48:49], v160 offset:1536
	ds_read_b64_tr_b4 v[122:123], v54
	ds_read_b64_tr_b4 v[124:125], v55
	ds_read_b64_tr_b4 v[126:127], v56
	ds_read_b64_tr_b4 v[128:129], v57
	s_waitcnt lgkmcnt(6)
	v_dot8c_i32_i4_e32 v38, v130, v52
	v_dot8c_i32_i4_e32 v39, v130, v50
	v_dot8c_i32_i4_e32 v40, v132, v52
	v_dot8c_i32_i4_e32 v41, v132, v50
	v_dot8c_i32_i4_e32 v42, v134, v52
	v_dot8c_i32_i4_e32 v43, v134, v50
	v_dot8c_i32_i4_e32 v44, v136, v52
	v_dot8c_i32_i4_e32 v45, v136, v50
	v_dot8c_i32_i4_e32 v38, v131, v53
	v_dot8c_i32_i4_e32 v39, v131, v51
	v_dot8c_i32_i4_e32 v40, v133, v53
	v_dot8c_i32_i4_e32 v41, v133, v51
	v_dot8c_i32_i4_e32 v42, v135, v53
	v_dot8c_i32_i4_e32 v43, v135, v51
	v_dot8c_i32_i4_e32 v44, v137, v53
	v_dot8c_i32_i4_e32 v45, v137, v51
	v_and_b32_e32 v78, 0xffff, v19
	v_lshrrev_b32_e32 v79, 16, v19
	v_lshl_add_u32 v78, v78, 7, v152
	v_lshl_add_u32 v79, v79, 7, v153
	s_mov_b32 m0, s79
	s_add_i32 s43, s79, 0x400
	global_load_lds_dwordx4 v78, s[50:51]
	s_mov_b32 m0, s43
	s_nop 0
	global_load_lds_dwordx4 v79, s[50:51]
	s_waitcnt vmcnt(8)
	v_add_u32_e32 v54, s99, v59
	v_add_u32_e32 v55, s99, v60
	v_add_u32_e32 v56, s99, v61
	v_add_u32_e32 v57, s99, v62
	ds_read_b64_tr_b4 v[50:51], v160 offset:640
	ds_read_b64_tr_b4 v[52:53], v160 offset:1664
	ds_read_b64_tr_b4 v[130:131], v54
	ds_read_b64_tr_b4 v[132:133], v55
	ds_read_b64_tr_b4 v[134:135], v56
	ds_read_b64_tr_b4 v[136:137], v57
	s_waitcnt lgkmcnt(6)
	v_dot8c_i32_i4_e32 v38, v122, v48
	v_dot8c_i32_i4_e32 v39, v122, v46
	v_dot8c_i32_i4_e32 v40, v124, v48
	v_dot8c_i32_i4_e32 v41, v124, v46
	v_dot8c_i32_i4_e32 v42, v126, v48
	v_dot8c_i32_i4_e32 v43, v126, v46
	v_dot8c_i32_i4_e32 v44, v128, v48
	v_dot8c_i32_i4_e32 v45, v128, v46
	v_dot8c_i32_i4_e32 v38, v123, v49
	v_dot8c_i32_i4_e32 v39, v123, v47
	v_dot8c_i32_i4_e32 v40, v125, v49
	v_dot8c_i32_i4_e32 v41, v125, v47
	v_dot8c_i32_i4_e32 v42, v127, v49
	v_dot8c_i32_i4_e32 v43, v127, v47
	v_dot8c_i32_i4_e32 v44, v129, v49
	v_dot8c_i32_i4_e32 v45, v129, v47
	s_waitcnt lgkmcnt(15)
	v_add_u32_e32 v143, 8, v139
	v_and_b32_e32 v142, 15, v143
	v_xor_b32_e32 v142, 8, v142
	v_bfe_u32 v144, v143, 4, 4
	v_mul_lo_u32 v142, v142, s92
	v_mul_lo_u32 v144, v144, s92
	v_mov_b32_e32 v143, v142
	v_mov_b32_e32 v145, v144
	ds_write2st64_b64 v159, v[142:143], v[144:145] offset1:2
	v_and_b32_e32 v78, 0xffff, v20
	v_lshrrev_b32_e32 v79, 16, v20
	v_lshl_add_u32 v78, v78, 7, v152
	v_lshl_add_u32 v79, v79, 7, v153
	s_mov_b32 m0, s98
	s_add_i32 s43, s98, 0x400
	global_load_lds_dwordx4 v78, s[50:51]
	s_mov_b32 m0, s43
	s_nop 0
	global_load_lds_dwordx4 v79, s[50:51]
	s_waitcnt vmcnt(8)
	v_add_u32_e32 v54, s76, v59
	v_add_u32_e32 v55, s76, v60
	v_add_u32_e32 v56, s76, v61
	v_add_u32_e32 v57, s76, v62
	ds_read_b64_tr_b4 v[46:47], v160 offset:768
	ds_read_b64_tr_b4 v[48:49], v160 offset:1792
	ds_read_b64_tr_b4 v[122:123], v54
	ds_read_b64_tr_b4 v[124:125], v55
	ds_read_b64_tr_b4 v[126:127], v56
	ds_read_b64_tr_b4 v[128:129], v57
	s_waitcnt lgkmcnt(7)
; __device__ __forceinline__ void peer_v_tokens(int j, const LAS unsigned short* EL, const LAS unsigned char* AL  , const LAS float* ASC  , const LAS int* SAL  , ...
;     ...
;         for (int st = 0; st < 16; ++st) {
;             const int p = st >> 2, q = st & 3;
;             if (st < 14) VDMA(st + 2, (st + 2) % 3);
;             if (st < 14) asm volatile("s_waitcnt vmcnt(8)" ::: "memory");
;             else if (st == 14) asm volatile("s_waitcnt vmcnt(4)" ::: "memory");
;             else asm volatile("s_waitcnt vmcnt(0)" ::: "memory");
;             if (q == 0) {
; #pragma unroll
;                 for (int r = 0; r < 4; ++r) { accH[r] = 0; accL[r] = 0; } }
; #pragma unroll
;             for (int tp = 0; tp < 2; ++tp) {
;                 const v2i ao = TR4(ATL + (2 * q + tp) * 128 + 8 * s16), ah = TR4(ATL + 1024 + (2 * q + tp) * 128 + 8 * s16);
; #pragma unroll
;                 for (int r = 0; r < 4; ++r) {
;                     const v2i d = TR4(ldsb + BUF[st % 3] + 2048 * tp + roff[r]);
;                     accH[r] = __builtin_amdgcn_sdot8(d.x, ah.x, accH[r], false); accH[r] = __builtin_amdgcn_sdot8(d.y, ah.y, accH[r], false);
;                     accL[r] = __builtin_amdgcn_sdot8(d.x, ao.x, accL[r], false); accL[r] = __builtin_amdgcn_sdot8(d.y, ao.y, accL[r], false);
;                 }
;             }
;             asm volatile("s_waitcnt lgkmcnt(0)" ::: "memory");
;             if (q == 3) {
; #pragma unroll
;                 for (int r = 0; r < 4; ++r) STASH[256 * p + 16 * (grp + 4 * r) + pc] = f2bf(asc * (float)(2 * ((accH[r] << 4) + accL[r]) + sa));
;             }
;         }
;         CFENCE();
;         {
;             float4 v[4]; float ss = 0.f;
; #pragma unroll
;             for (int jq = 0; jq < 4; ++jq) { typedef unsigned u2v __attribute__((ext_vector_type(2))); const u2v pw = *(const LAS u2v*)(STASH + 4 * lane + 256 * jq); const uint2 hw = hv[jq];
;                 v[jq] = make_float4(__uint_as_float(hw.x << 16) + __uint_as_float(pw.x << 16), __uint_as_float(hw.x & 0xffff0000u) + __uint_as_float(pw.x & 0xffff0000u),
;                                     __uint_as_float(hw.y << 16) + __uint_as_float(pw.y << 16), __uint_as_float(hw.y & 0xffff0000u) + __uint_as_float(pw.y & 0xffff0000u));
;                 ss += v[jq].x * v[jq].x + v[jq].y * v[jq].y + v[jq].z * v[jq].z + v[jq].w * v[jq].w; }
;             ss = wave_sum(ss);
	v_dot8c_i32_i4_e32 v38, v130, v52
	v_dot8c_i32_i4_e32 v39, v130, v50
	v_dot8c_i32_i4_e32 v40, v132, v52
	v_dot8c_i32_i4_e32 v41, v132, v50
	v_dot8c_i32_i4_e32 v42, v134, v52
	v_dot8c_i32_i4_e32 v43, v134, v50
	v_dot8c_i32_i4_e32 v44, v136, v52
	v_dot8c_i32_i4_e32 v45, v136, v50
	v_dot8c_i32_i4_e32 v38, v131, v53
	v_dot8c_i32_i4_e32 v39, v131, v51
	v_dot8c_i32_i4_e32 v40, v133, v53
	v_dot8c_i32_i4_e32 v41, v133, v51
	v_dot8c_i32_i4_e32 v42, v135, v53
	v_dot8c_i32_i4_e32 v43, v135, v51
	v_dot8c_i32_i4_e32 v44, v137, v53
	v_dot8c_i32_i4_e32 v45, v137, v51
	v_and_b32_e32 v78, 0xffff, v21
	v_lshrrev_b32_e32 v79, 16, v21
	v_lshl_add_u32 v78, v78, 7, v152
	v_lshl_add_u32 v79, v79, 7, v153
	s_mov_b32 m0, s99
	s_add_i32 s43, s99, 0x400
	global_load_lds_dwordx4 v78, s[50:51]
	s_mov_b32 m0, s43
	s_nop 0
	global_load_lds_dwordx4 v79, s[50:51]
	s_waitcnt vmcnt(8)
	v_add_u32_e32 v54, s77, v59
	v_add_u32_e32 v55, s77, v60
	v_add_u32_e32 v56, s77, v61
	v_add_u32_e32 v57, s77, v62
	ds_read_b64_tr_b4 v[50:51], v160 offset:896
	ds_read_b64_tr_b4 v[52:53], v160 offset:1920
	ds_read_b64_tr_b4 v[130:131], v54
	ds_read_b64_tr_b4 v[132:133], v55
	ds_read_b64_tr_b4 v[134:135], v56
	ds_read_b64_tr_b4 v[136:137], v57
	s_waitcnt lgkmcnt(6)
	v_dot8c_i32_i4_e32 v38, v122, v48
	v_dot8c_i32_i4_e32 v39, v122, v46
	v_dot8c_i32_i4_e32 v40, v124, v48
	v_dot8c_i32_i4_e32 v41, v124, v46
	v_dot8c_i32_i4_e32 v42, v126, v48
	v_dot8c_i32_i4_e32 v43, v126, v46
	v_dot8c_i32_i4_e32 v44, v128, v48
	v_dot8c_i32_i4_e32 v45, v128, v46
	v_dot8c_i32_i4_e32 v38, v123, v49
	v_dot8c_i32_i4_e32 v39, v123, v47
	v_dot8c_i32_i4_e32 v40, v125, v49
	v_dot8c_i32_i4_e32 v41, v125, v47
	v_dot8c_i32_i4_e32 v42, v127, v49
	v_dot8c_i32_i4_e32 v43, v127, v47
	v_dot8c_i32_i4_e32 v44, v129, v49
	v_dot8c_i32_i4_e32 v45, v129, v47
	v_and_b32_e32 v78, 0xffff, v22
	v_lshrrev_b32_e32 v79, 16, v22
	v_lshl_add_u32 v78, v78, 7, v152
	v_lshl_add_u32 v79, v79, 7, v153
	s_mov_b32 m0, s76
	s_add_i32 s43, s76, 0x400
	global_load_lds_dwordx4 v78, s[50:51]
	s_mov_b32 m0, s43
	s_nop 0
	global_load_lds_dwordx4 v79, s[50:51]
	s_waitcnt vmcnt(8)
	v_add_u32_e32 v54, s78, v59
	v_add_u32_e32 v55, s78, v60
	v_add_u32_e32 v56, s78, v61
	v_add_u32_e32 v57, s78, v62
	ds_read_b64_tr_b4 v[46:47], v160
	ds_read_b64_tr_b4 v[48:49], v160 offset:1024
	ds_read_b64_tr_b4 v[122:123], v54
	ds_read_b64_tr_b4 v[124:125], v55
	ds_read_b64_tr_b4 v[126:127], v56
	ds_read_b64_tr_b4 v[128:129], v57
	s_waitcnt lgkmcnt(6)
	v_dot8c_i32_i4_e32 v38, v130, v52
	v_dot8c_i32_i4_e32 v39, v130, v50
	v_dot8c_i32_i4_e32 v40, v132, v52
	v_dot8c_i32_i4_e32 v41, v132, v50
	v_dot8c_i32_i4_e32 v42, v134, v52
	v_dot8c_i32_i4_e32 v43, v134, v50
	v_dot8c_i32_i4_e32 v44, v136, v52
	v_dot8c_i32_i4_e32 v45, v136, v50
	v_dot8c_i32_i4_e32 v38, v131, v53
	v_dot8c_i32_i4_e32 v39, v131, v51
	v_dot8c_i32_i4_e32 v40, v133, v53
	v_dot8c_i32_i4_e32 v41, v133, v51
	v_dot8c_i32_i4_e32 v42, v135, v53
	v_dot8c_i32_i4_e32 v43, v135, v51
	v_dot8c_i32_i4_e32 v44, v137, v53
	v_dot8c_i32_i4_e32 v45, v137, v51
	s_nop 3
	s_waitcnt lgkmcnt(15)
	v_lshlrev_b32_e32 v38, 5, v38
	v_lshlrev_b32_e32 v39, 1, v39
	v_add3_u32 v38, v39, v229, v38
	v_cvt_f32_i32_e32 v38, v38
	v_mul_f32_e32 v38, v228, v38
	v_lshlrev_b32_e32 v40, 5, v40
	v_lshlrev_b32_e32 v41, 1, v41
	v_add3_u32 v40, v41, v229, v40
	v_cvt_f32_i32_e32 v40, v40
	v_mul_f32_e32 v40, v228, v40
	v_lshlrev_b32_e32 v42, 5, v42
	v_lshlrev_b32_e32 v43, 1, v43
	v_add3_u32 v42, v43, v229, v42
	v_cvt_f32_i32_e32 v42, v42
	v_mul_f32_e32 v42, v228, v42
	v_lshlrev_b32_e32 v44, 5, v44
	v_lshlrev_b32_e32 v45, 1, v45
	v_add3_u32 v44, v45, v229, v44
	v_cvt_f32_i32_e32 v44, v44
	v_mul_f32_e32 v44, v228, v44
	v_cvt_pk_bf16_f32 v186, v38, v40
	v_cvt_pk_bf16_f32 v187, v42, v44
	ds_read_b128 v[252:255], v155
	s_add_i32 s44, s40, 0
	s_ashr_i32 s45, s44, 31
	s_lshl_b64 s[44:45], s[44:45], 12
	v_lshl_add_u64 v[80:81], v[36:37], 0, s[44:45]
	s_waitcnt lgkmcnt(0)
	v_mul_f32_e32 v210, v210, v252
	v_mul_f32_e32 v211, v211, v253
	v_mul_f32_e32 v212, v212, v254
	v_mul_f32_e32 v213, v213, v255
	global_store_dwordx4 v[80:81], v[210:213], off nt
	s_add_i32 s43, s40, 8
	s_lshl_b32 s43, s43, 11
	v_add_u32_e32 v138, s43, v66
	global_load_dwordx2 v[194:195], v138, s[70:71]
	global_load_dwordx2 v[196:197], v138, s[70:71] offset:512
	global_load_dwordx2 v[198:199], v138, s[70:71] offset:1024
	global_load_dwordx2 v[200:201], v138, s[70:71] offset:1536
	v_add_u32_e32 v147, 8, v140
	v_and_b32_e32 v146, 15, v147
	v_xor_b32_e32 v146, 8, v146
	v_bfe_u32 v148, v147, 4, 4
	v_mul_lo_u32 v146, v146, s92
	v_mul_lo_u32 v148, v148, s92
	v_mov_b32_e32 v147, v146
	v_mov_b32_e32 v149, v148
	ds_write2st64_b64 v77, v[146:147], v[148:149] offset1:2
	v_add_u32_e32 v138, 0xc00, v74
	ds_read_u8 v139, v138
	v_add_u32_e32 v141, 0xc00, v73
	ds_read_u8 v140, v141
	s_add_i32 s43, s67, 64
	v_mov_b32_e32 v138, s43
	ds_read2st64_b32 v[228:229], v138 offset1:1
	ds_read_b128 v[26:29], v227 offset:6144
	ds_read_b128 v[30:33], v227 offset:6160
	v_mov_b32_e32 v38, 0
	v_mov_b32_e32 v39, 0
	v_mov_b32_e32 v40, 0
	v_mov_b32_e32 v41, 0
	v_mov_b32_e32 v42, 0
	v_mov_b32_e32 v43, 0
	v_mov_b32_e32 v44, 0
	v_mov_b32_e32 v45, 0
	v_and_b32_e32 v78, 0xffff, v23
	v_lshrrev_b32_e32 v79, 16, v23
	v_lshl_add_u32 v78, v78, 7, v152
	v_lshl_add_u32 v79, v79, 7, v153
	s_mov_b32 m0, s77
	s_add_i32 s43, s77, 0x400
	global_load_lds_dwordx4 v78, s[50:51]
	s_mov_b32 m0, s43
	s_nop 0
	global_load_lds_dwordx4 v79, s[50:51]
	s_waitcnt vmcnt(13)
	v_add_u32_e32 v54, s79, v59
	v_add_u32_e32 v55, s79, v60
	v_add_u32_e32 v56, s79, v61
	v_add_u32_e32 v57, s79, v62
	ds_read_b64_tr_b4 v[50:51], v160 offset:128
	ds_read_b64_tr_b4 v[52:53], v160 offset:1152
	ds_read_b64_tr_b4 v[130:131], v54
	ds_read_b64_tr_b4 v[132:133], v55
	ds_read_b64_tr_b4 v[134:135], v56
	ds_read_b64_tr_b4 v[136:137], v57
	s_waitcnt lgkmcnt(13)
; #define TR4(p_) __builtin_amdgcn_ds_read_tr4_b64_v2i32((LAS v2i*)(p_))
; #define VDMA(st_, k_) do { _Pragma("unroll") for (int i_ = 0; i_ < 4; ++i_) { \
;         const unsigned off_ = (unsigned)((st_) >> 2) * (16384u * 128u) + (PE_ID(E, 4 * ((st_) & 3) + i_) << 7) + ((i_ & 1) ? cx1 : cx0); \
;         __builtin_amdgcn_global_load_lds((const unsigned*)(V4 + off_), (LAS unsigned*)(ldsb + BUF[k_] + 1024 * i_), 16, 0, 0); } } while (0)
; __device__ __forceinline__ void peer_v_tokens(int j, const LAS unsigned short* EL, const LAS unsigned char* AL  , const LAS float* ASC  , const LAS int* SAL  , ...
;     ...
;         for (int st = 0; st < 16; ++st) {
;             const int p = st >> 2, q = st & 3;
;             if (st < 14) VDMA(st + 2, (st + 2) % 3);
;             if (st < 14) asm volatile("s_waitcnt vmcnt(8)" ::: "memory");
;             else if (st == 14) asm volatile("s_waitcnt vmcnt(4)" ::: "memory");
;             else asm volatile("s_waitcnt vmcnt(0)" ::: "memory");
;             if (q == 0) {
; #pragma unroll
;                 for (int r = 0; r < 4; ++r) { accH[r] = 0; accL[r] = 0; } }
; #pragma unroll
;             for (int tp = 0; tp < 2; ++tp) {
;                 const v2i ao = TR4(ATL + (2 * q + tp) * 128 + 8 * s16), ah = TR4(ATL + 1024 + (2 * q + tp) * 128 + 8 * s16);
; #pragma unroll
;                 for (int r = 0; r < 4; ++r) {
;                     const v2i d = TR4(ldsb + BUF[st % 3] + 2048 * tp + roff[r]);
;                     accH[r] = __builtin_amdgcn_sdot8(d.x, ah.x, accH[r], false); accH[r] = __builtin_amdgcn_sdot8(d.y, ah.y, accH[r], false);
;                     accL[r] = __builtin_amdgcn_sdot8(d.x, ao.x, accL[r], false); accL[r] = __builtin_amdgcn_sdot8(d.y, ao.y, accL[r], false);
;                 }
;             }
	v_dot8c_i32_i4_e32 v38, v122, v48
	v_dot8c_i32_i4_e32 v39, v122, v46
	v_dot8c_i32_i4_e32 v40, v124, v48
	v_dot8c_i32_i4_e32 v41, v124, v46
	v_dot8c_i32_i4_e32 v42, v126, v48
	v_dot8c_i32_i4_e32 v43, v126, v46
	v_dot8c_i32_i4_e32 v44, v128, v48
	v_dot8c_i32_i4_e32 v45, v128, v46
	v_dot8c_i32_i4_e32 v38, v123, v49
	v_dot8c_i32_i4_e32 v39, v123, v47
	v_dot8c_i32_i4_e32 v40, v125, v49
	v_dot8c_i32_i4_e32 v41, v125, v47
	v_dot8c_i32_i4_e32 v42, v127, v49
	v_dot8c_i32_i4_e32 v43, v127, v47
	v_dot8c_i32_i4_e32 v44, v129, v49
	v_dot8c_i32_i4_e32 v45, v129, v47
	v_and_b32_e32 v78, 0xffff, v24
	v_lshrrev_b32_e32 v79, 16, v24
	v_lshl_add_u32 v78, v78, 7, v152
	v_lshl_add_u32 v79, v79, 7, v153
	s_mov_b32 m0, s78
	s_add_i32 s43, s78, 0x400
	global_load_lds_dwordx4 v78, s[50:51]
	s_mov_b32 m0, s43
	s_nop 0
	global_load_lds_dwordx4 v79, s[50:51]
	s_waitcnt vmcnt(13)
	v_add_u32_e32 v54, s98, v59
	v_add_u32_e32 v55, s98, v60
	v_add_u32_e32 v56, s98, v61
	v_add_u32_e32 v57, s98, v62
	ds_read_b64_tr_b4 v[46:47], v160 offset:256
	ds_read_b64_tr_b4 v[48:49], v160 offset:1280
	ds_read_b64_tr_b4 v[122:123], v54
	ds_read_b64_tr_b4 v[124:125], v55
	ds_read_b64_tr_b4 v[126:127], v56
	ds_read_b64_tr_b4 v[128:129], v57
	s_waitcnt lgkmcnt(6)
	v_dot8c_i32_i4_e32 v38, v130, v52
	v_dot8c_i32_i4_e32 v39, v130, v50
	v_dot8c_i32_i4_e32 v40, v132, v52
	v_dot8c_i32_i4_e32 v41, v132, v50
	v_dot8c_i32_i4_e32 v42, v134, v52
	v_dot8c_i32_i4_e32 v43, v134, v50
	v_dot8c_i32_i4_e32 v44, v136, v52
	v_dot8c_i32_i4_e32 v45, v136, v50
	v_dot8c_i32_i4_e32 v38, v131, v53
	v_dot8c_i32_i4_e32 v39, v131, v51
	v_dot8c_i32_i4_e32 v40, v133, v53
	v_dot8c_i32_i4_e32 v41, v133, v51
	v_dot8c_i32_i4_e32 v42, v135, v53
	v_dot8c_i32_i4_e32 v43, v135, v51
	v_dot8c_i32_i4_e32 v44, v137, v53
	v_dot8c_i32_i4_e32 v45, v137, v51
	v_and_b32_e32 v78, 0xffff, v25
	v_lshrrev_b32_e32 v79, 16, v25
	v_lshl_add_u32 v78, v78, 7, v152
	v_lshl_add_u32 v79, v79, 7, v153
	s_mov_b32 m0, s79
	s_add_i32 s43, s79, 0x400
	global_load_lds_dwordx4 v78, s[50:51]
	s_mov_b32 m0, s43
	s_nop 0
	global_load_lds_dwordx4 v79, s[50:51]
	s_waitcnt vmcnt(13)
	v_add_u32_e32 v54, s99, v59
	v_add_u32_e32 v55, s99, v60
	v_add_u32_e32 v56, s99, v61
	v_add_u32_e32 v57, s99, v62
	ds_read_b64_tr_b4 v[50:51], v160 offset:384
	ds_read_b64_tr_b4 v[52:53], v160 offset:1408
	ds_read_b64_tr_b4 v[130:131], v54
	ds_read_b64_tr_b4 v[132:133], v55
	ds_read_b64_tr_b4 v[134:135], v56
	ds_read_b64_tr_b4 v[136:137], v57
	s_waitcnt lgkmcnt(6)
	v_dot8c_i32_i4_e32 v38, v122, v48
	v_dot8c_i32_i4_e32 v39, v122, v46
	v_dot8c_i32_i4_e32 v40, v124, v48
	v_dot8c_i32_i4_e32 v41, v124, v46
	v_dot8c_i32_i4_e32 v42, v126, v48
	v_dot8c_i32_i4_e32 v43, v126, v46
	v_dot8c_i32_i4_e32 v44, v128, v48
	v_dot8c_i32_i4_e32 v45, v128, v46
	v_dot8c_i32_i4_e32 v38, v123, v49
	v_dot8c_i32_i4_e32 v39, v123, v47
	v_dot8c_i32_i4_e32 v40, v125, v49
	v_dot8c_i32_i4_e32 v41, v125, v47
	v_dot8c_i32_i4_e32 v42, v127, v49
	v_dot8c_i32_i4_e32 v43, v127, v47
	v_dot8c_i32_i4_e32 v44, v129, v49
	v_dot8c_i32_i4_e32 v45, v129, v47
	s_waitcnt lgkmcnt(15)
	v_and_b32_e32 v78, 0xffff, v26
	v_lshrrev_b32_e32 v79, 16, v26
	v_lshl_add_u32 v78, v78, 7, v152
	v_lshl_add_u32 v79, v79, 7, v153
	s_mov_b32 m0, s98
	s_add_i32 s43, s98, 0x400
	global_load_lds_dwordx4 v78, s[50:51]
	s_mov_b32 m0, s43
	s_nop 0
	global_load_lds_dwordx4 v79, s[50:51]
	s_waitcnt vmcnt(13)
	v_add_u32_e32 v54, s76, v59
	v_add_u32_e32 v55, s76, v60
	v_add_u32_e32 v56, s76, v61
	v_add_u32_e32 v57, s76, v62
	ds_read_b64_tr_b4 v[46:47], v160 offset:512
	ds_read_b64_tr_b4 v[48:49], v160 offset:1536
	ds_read_b64_tr_b4 v[122:123], v54
	ds_read_b64_tr_b4 v[124:125], v55
	ds_read_b64_tr_b4 v[126:127], v56
	ds_read_b64_tr_b4 v[128:129], v57
	s_waitcnt lgkmcnt(6)
	v_dot8c_i32_i4_e32 v38, v130, v52
	v_dot8c_i32_i4_e32 v39, v130, v50
	v_dot8c_i32_i4_e32 v40, v132, v52
	v_dot8c_i32_i4_e32 v41, v132, v50
	v_dot8c_i32_i4_e32 v42, v134, v52
	v_dot8c_i32_i4_e32 v43, v134, v50
	v_dot8c_i32_i4_e32 v44, v136, v52
	v_dot8c_i32_i4_e32 v45, v136, v50
	v_dot8c_i32_i4_e32 v38, v131, v53
	v_dot8c_i32_i4_e32 v39, v131, v51
	v_dot8c_i32_i4_e32 v40, v133, v53
	v_dot8c_i32_i4_e32 v41, v133, v51
	v_dot8c_i32_i4_e32 v42, v135, v53
	v_dot8c_i32_i4_e32 v43, v135, v51
	v_dot8c_i32_i4_e32 v44, v137, v53
	v_dot8c_i32_i4_e32 v45, v137, v51
	v_and_b32_e32 v78, 0xffff, v27
	v_lshrrev_b32_e32 v79, 16, v27
	v_lshl_add_u32 v78, v78, 7, v152
	v_lshl_add_u32 v79, v79, 7, v153
	s_mov_b32 m0, s99
	s_add_i32 s43, s99, 0x400
	global_load_lds_dwordx4 v78, s[50:51]
	s_mov_b32 m0, s43
	s_nop 0
	global_load_lds_dwordx4 v79, s[50:51]
	s_waitcnt vmcnt(8)
	v_add_u32_e32 v54, s77, v59
	v_add_u32_e32 v55, s77, v60
	v_add_u32_e32 v56, s77, v61
	v_add_u32_e32 v57, s77, v62
	ds_read_b64_tr_b4 v[50:51], v160 offset:640
	ds_read_b64_tr_b4 v[52:53], v160 offset:1664
	ds_read_b64_tr_b4 v[130:131], v54
	ds_read_b64_tr_b4 v[132:133], v55
	ds_read_b64_tr_b4 v[134:135], v56
	ds_read_b64_tr_b4 v[136:137], v57
	s_waitcnt lgkmcnt(6)
	v_dot8c_i32_i4_e32 v38, v122, v48
	v_dot8c_i32_i4_e32 v39, v122, v46
	v_dot8c_i32_i4_e32 v40, v124, v48
	v_dot8c_i32_i4_e32 v41, v124, v46
	v_dot8c_i32_i4_e32 v42, v126, v48
	v_dot8c_i32_i4_e32 v43, v126, v46
	v_dot8c_i32_i4_e32 v44, v128, v48
	v_dot8c_i32_i4_e32 v45, v128, v46
	v_dot8c_i32_i4_e32 v38, v123, v49
	v_dot8c_i32_i4_e32 v39, v123, v47
	v_dot8c_i32_i4_e32 v40, v125, v49
	v_dot8c_i32_i4_e32 v41, v125, v47
	v_dot8c_i32_i4_e32 v42, v127, v49
	v_dot8c_i32_i4_e32 v43, v127, v47
	v_dot8c_i32_i4_e32 v44, v129, v49
	v_dot8c_i32_i4_e32 v45, v129, v47
	s_waitcnt lgkmcnt(15)
; __device__ __forceinline__ void peer_v_tokens(int j, const LAS unsigned short* EL, const LAS unsigned char* AL  , const LAS float* ASC  , const LAS int* SAL  , ...
;     ...
;         for (int st = 0; st < 16; ++st) {
;             const int p = st >> 2, q = st & 3;
;             if (st < 14) VDMA(st + 2, (st + 2) % 3);
;             if (st < 14) asm volatile("s_waitcnt vmcnt(8)" ::: "memory");
;             else if (st == 14) asm volatile("s_waitcnt vmcnt(4)" ::: "memory");
;             else asm volatile("s_waitcnt vmcnt(0)" ::: "memory");
;             if (q == 0) {
; #pragma unroll
;                 for (int r = 0; r < 4; ++r) { accH[r] = 0; accL[r] = 0; } }
; #pragma unroll
;             for (int tp = 0; tp < 2; ++tp) {
;                 const v2i ao = TR4(ATL + (2 * q + tp) * 128 + 8 * s16), ah = TR4(ATL + 1024 + (2 * q + tp) * 128 + 8 * s16);
; #pragma unroll
;                 for (int r = 0; r < 4; ++r) {
;                     const v2i d = TR4(ldsb + BUF[st % 3] + 2048 * tp + roff[r]);
;                     accH[r] = __builtin_amdgcn_sdot8(d.x, ah.x, accH[r], false); accH[r] = __builtin_amdgcn_sdot8(d.y, ah.y, accH[r], false);
;                     accL[r] = __builtin_amdgcn_sdot8(d.x, ao.x, accL[r], false); accL[r] = __builtin_amdgcn_sdot8(d.y, ao.y, accL[r], false);
;                 }
;             }
;             asm volatile("s_waitcnt lgkmcnt(0)" ::: "memory");
;             if (q == 3) {
; #pragma unroll
;                 for (int r = 0; r < 4; ++r) STASH[256 * p + 16 * (grp + 4 * r) + pc] = f2bf(asc * (float)(2 * ((accH[r] << 4) + accL[r]) + sa));
;             }
;         }
;         CFENCE();
;         {
;             float4 v[4]; float ss = 0.f;
; #pragma unroll
;             for (int jq = 0; jq < 4; ++jq) { typedef unsigned u2v __attribute__((ext_vector_type(2))); const u2v pw = *(const LAS u2v*)(STASH + 4 * lane + 256 * jq); const uint2 hw = hv[jq];
;                 v[jq] = make_float4(__uint_as_float(hw.x << 16) + __uint_as_float(pw.x << 16), __uint_as_float(hw.x & 0xffff0000u) + __uint_as_float(pw.x & 0xffff0000u),
;                                     __uint_as_float(hw.y << 16) + __uint_as_float(pw.y << 16), __uint_as_float(hw.y & 0xffff0000u) + __uint_as_float(pw.y & 0xffff0000u));
;                 ss += v[jq].x * v[jq].x + v[jq].y * v[jq].y + v[jq].z * v[jq].z + v[jq].w * v[jq].w; }
;             ss = wave_sum(ss);
	v_add_u32_e32 v143, 8, v139
	v_and_b32_e32 v142, 15, v143
	v_xor_b32_e32 v142, 8, v142
	v_bfe_u32 v144, v143, 4, 4
	v_mul_lo_u32 v142, v142, s92
	v_mul_lo_u32 v144, v144, s92
	v_mov_b32_e32 v143, v142
	v_mov_b32_e32 v145, v144
	ds_write2st64_b64 v159, v[142:143], v[144:145] offset1:2
	v_and_b32_e32 v78, 0xffff, v28
	v_lshrrev_b32_e32 v79, 16, v28
	v_lshl_add_u32 v78, v78, 7, v152
	v_lshl_add_u32 v79, v79, 7, v153
	s_mov_b32 m0, s76
	s_add_i32 s43, s76, 0x400
	global_load_lds_dwordx4 v78, s[50:51]
	s_mov_b32 m0, s43
	s_nop 0
	global_load_lds_dwordx4 v79, s[50:51]
	s_waitcnt vmcnt(8)
	v_add_u32_e32 v54, s78, v59
	v_add_u32_e32 v55, s78, v60
	v_add_u32_e32 v56, s78, v61
	v_add_u32_e32 v57, s78, v62
	ds_read_b64_tr_b4 v[46:47], v160 offset:768
	ds_read_b64_tr_b4 v[48:49], v160 offset:1792
	ds_read_b64_tr_b4 v[122:123], v54
	ds_read_b64_tr_b4 v[124:125], v55
	ds_read_b64_tr_b4 v[126:127], v56
	ds_read_b64_tr_b4 v[128:129], v57
	s_waitcnt lgkmcnt(7)
	v_dot8c_i32_i4_e32 v38, v130, v52
	v_dot8c_i32_i4_e32 v39, v130, v50
	v_dot8c_i32_i4_e32 v40, v132, v52
	v_dot8c_i32_i4_e32 v41, v132, v50
	v_dot8c_i32_i4_e32 v42, v134, v52
	v_dot8c_i32_i4_e32 v43, v134, v50
	v_dot8c_i32_i4_e32 v44, v136, v52
	v_dot8c_i32_i4_e32 v45, v136, v50
	v_dot8c_i32_i4_e32 v38, v131, v53
	v_dot8c_i32_i4_e32 v39, v131, v51
	v_dot8c_i32_i4_e32 v40, v133, v53
	v_dot8c_i32_i4_e32 v41, v133, v51
	v_dot8c_i32_i4_e32 v42, v135, v53
	v_dot8c_i32_i4_e32 v43, v135, v51
	v_dot8c_i32_i4_e32 v44, v137, v53
	v_dot8c_i32_i4_e32 v45, v137, v51
	v_and_b32_e32 v78, 0xffff, v29
	v_lshrrev_b32_e32 v79, 16, v29
	v_lshl_add_u32 v78, v78, 7, v152
	v_lshl_add_u32 v79, v79, 7, v153
	s_mov_b32 m0, s77
	s_add_i32 s43, s77, 0x400
	global_load_lds_dwordx4 v78, s[50:51]
	s_mov_b32 m0, s43
	s_nop 0
	global_load_lds_dwordx4 v79, s[50:51]
	s_waitcnt vmcnt(8)
	v_add_u32_e32 v54, s79, v59
	v_add_u32_e32 v55, s79, v60
	v_add_u32_e32 v56, s79, v61
	v_add_u32_e32 v57, s79, v62
	ds_read_b64_tr_b4 v[50:51], v160 offset:896
	ds_read_b64_tr_b4 v[52:53], v160 offset:1920
	ds_read_b64_tr_b4 v[130:131], v54
	ds_read_b64_tr_b4 v[132:133], v55
	ds_read_b64_tr_b4 v[134:135], v56
	ds_read_b64_tr_b4 v[136:137], v57
	s_waitcnt lgkmcnt(6)
	v_dot8c_i32_i4_e32 v38, v122, v48
	v_dot8c_i32_i4_e32 v39, v122, v46
	v_dot8c_i32_i4_e32 v40, v124, v48
	v_dot8c_i32_i4_e32 v41, v124, v46
	v_dot8c_i32_i4_e32 v42, v126, v48
	v_dot8c_i32_i4_e32 v43, v126, v46
	v_dot8c_i32_i4_e32 v44, v128, v48
	v_dot8c_i32_i4_e32 v45, v128, v46
	v_dot8c_i32_i4_e32 v38, v123, v49
	v_dot8c_i32_i4_e32 v39, v123, v47
	v_dot8c_i32_i4_e32 v40, v125, v49
	v_dot8c_i32_i4_e32 v41, v125, v47
	v_dot8c_i32_i4_e32 v42, v127, v49
	v_dot8c_i32_i4_e32 v43, v127, v47
	v_dot8c_i32_i4_e32 v44, v129, v49
	v_dot8c_i32_i4_e32 v45, v129, v47
	v_and_b32_e32 v78, 0xffff, v30
	v_lshrrev_b32_e32 v79, 16, v30
	v_lshl_add_u32 v78, v78, 7, v152
	v_lshl_add_u32 v79, v79, 7, v153
	s_mov_b32 m0, s78
	s_add_i32 s43, s78, 0x400
	global_load_lds_dwordx4 v78, s[50:51]
	s_mov_b32 m0, s43
	s_nop 0
	global_load_lds_dwordx4 v79, s[50:51]
	s_waitcnt vmcnt(8)
	v_add_u32_e32 v54, s98, v59
	v_add_u32_e32 v55, s98, v60
	v_add_u32_e32 v56, s98, v61
	v_add_u32_e32 v57, s98, v62
	ds_read_b64_tr_b4 v[46:47], v160
	ds_read_b64_tr_b4 v[48:49], v160 offset:1024
	ds_read_b64_tr_b4 v[122:123], v54
	ds_read_b64_tr_b4 v[124:125], v55
	ds_read_b64_tr_b4 v[126:127], v56
	ds_read_b64_tr_b4 v[128:129], v57
	s_waitcnt lgkmcnt(6)
	v_dot8c_i32_i4_e32 v38, v130, v52
	v_dot8c_i32_i4_e32 v39, v130, v50
	v_dot8c_i32_i4_e32 v40, v132, v52
	v_dot8c_i32_i4_e32 v41, v132, v50
	v_dot8c_i32_i4_e32 v42, v134, v52
	v_dot8c_i32_i4_e32 v43, v134, v50
	v_dot8c_i32_i4_e32 v44, v136, v52
	v_dot8c_i32_i4_e32 v45, v136, v50
	v_dot8c_i32_i4_e32 v38, v131, v53
	v_dot8c_i32_i4_e32 v39, v131, v51
	v_dot8c_i32_i4_e32 v40, v133, v53
	v_dot8c_i32_i4_e32 v41, v133, v51
	v_dot8c_i32_i4_e32 v42, v135, v53
	v_dot8c_i32_i4_e32 v43, v135, v51
	v_dot8c_i32_i4_e32 v44, v137, v53
	v_dot8c_i32_i4_e32 v45, v137, v51
	s_nop 3
	s_waitcnt lgkmcnt(15)
	v_lshlrev_b32_e32 v38, 5, v38
	v_lshlrev_b32_e32 v39, 1, v39
	v_add3_u32 v38, v39, v229, v38
	v_cvt_f32_i32_e32 v38, v38
	v_mul_f32_e32 v38, v228, v38
	v_lshlrev_b32_e32 v40, 5, v40
	v_lshlrev_b32_e32 v41, 1, v41
	v_add3_u32 v40, v41, v229, v40
	v_cvt_f32_i32_e32 v40, v40
	v_mul_f32_e32 v40, v228, v40
	v_lshlrev_b32_e32 v42, 5, v42
	v_lshlrev_b32_e32 v43, 1, v43
	v_add3_u32 v42, v43, v229, v42
	v_cvt_f32_i32_e32 v42, v42
	v_mul_f32_e32 v42, v228, v42
	v_lshlrev_b32_e32 v44, 5, v44
	v_lshlrev_b32_e32 v45, 1, v45
	v_add3_u32 v44, v45, v229, v44
	v_cvt_f32_i32_e32 v44, v44
	v_mul_f32_e32 v44, v228, v44
	v_cvt_pk_bf16_f32 v180, v38, v40
	v_cvt_pk_bf16_f32 v181, v42, v44
	ds_read_b128 v[252:255], v155 offset:1024
	s_add_i32 s44, s40, 0
	s_ashr_i32 s45, s44, 31
	s_lshl_b64 s[44:45], s[44:45], 12
	v_lshl_add_u64 v[80:81], v[36:37], 0, s[44:45]
	s_waitcnt lgkmcnt(0)
	v_mul_f32_e32 v214, v214, v252
	v_mul_f32_e32 v215, v215, v253
	v_mul_f32_e32 v216, v216, v254
	v_mul_f32_e32 v217, v217, v255
	global_store_dwordx4 v[80:81], v[214:217], off offset:1024 nt
	v_add_u32_e32 v147, 8, v140
	v_and_b32_e32 v146, 15, v147
	v_xor_b32_e32 v146, 8, v146
	v_bfe_u32 v148, v147, 4, 4
	v_mul_lo_u32 v146, v146, s92
	v_mul_lo_u32 v148, v148, s92
	v_mov_b32_e32 v147, v146
	v_mov_b32_e32 v149, v148
	ds_write2st64_b64 v77, v[146:147], v[148:149] offset1:2
	v_add_u32_e32 v138, 0x800, v74
	ds_read_u8 v139, v138
	v_add_u32_e32 v141, 0x800, v73
	ds_read_u8 v140, v141
	s_add_i32 s43, s67, 96
	v_mov_b32_e32 v138, s43
	ds_read2st64_b32 v[228:229], v138 offset1:1
	ds_read_b128 v[18:21], v227 offset:4096
	ds_read_b128 v[22:25], v227 offset:4112
	v_add_u32_e32 v150, 0x400000, v63
	v_add_u32_e32 v151, 0x400000, v64
	v_mov_b32_e32 v38, 0
	v_mov_b32_e32 v39, 0
	v_mov_b32_e32 v40, 0
	v_mov_b32_e32 v41, 0
	v_mov_b32_e32 v42, 0
	v_mov_b32_e32 v43, 0
	v_mov_b32_e32 v44, 0
	v_mov_b32_e32 v45, 0
	v_and_b32_e32 v78, 0xffff, v31
	v_lshrrev_b32_e32 v79, 16, v31
	v_lshl_add_u32 v78, v78, 7, v152
	v_lshl_add_u32 v79, v79, 7, v153
	s_mov_b32 m0, s79
	s_add_i32 s43, s79, 0x400
	global_load_lds_dwordx4 v78, s[50:51]
	s_mov_b32 m0, s43
	s_nop 0
	global_load_lds_dwordx4 v79, s[50:51]
	s_waitcnt vmcnt(9)
; #define LAS __attribute__((address_space(3)))
; __device__ __forceinline__ bf16 f2bf(float f) { return (bf16)f2bfu(f); }
; #define TR4(p_) __builtin_amdgcn_ds_read_tr4_b64_v2i32((LAS v2i*)(p_))
; #define CFENCE() asm volatile("" ::: "memory")
; __device__ __forceinline__ void peer_v_tokens(int j, const LAS unsigned short* EL, const LAS unsigned char* AL  , const LAS float* ASC  , const LAS int* SAL  , ...
;     ...
;         for (int st = 0; st < 16; ++st) {
;             const int p = st >> 2, q = st & 3;
;             if (st < 14) VDMA(st + 2, (st + 2) % 3);
;             if (st < 14) asm volatile("s_waitcnt vmcnt(8)" ::: "memory");
;             else if (st == 14) asm volatile("s_waitcnt vmcnt(4)" ::: "memory");
;             else asm volatile("s_waitcnt vmcnt(0)" ::: "memory");
;             if (q == 0) {
; #pragma unroll
;                 for (int r = 0; r < 4; ++r) { accH[r] = 0; accL[r] = 0; } }
; #pragma unroll
;             for (int tp = 0; tp < 2; ++tp) {
;                 const v2i ao = TR4(ATL + (2 * q + tp) * 128 + 8 * s16), ah = TR4(ATL + 1024 + (2 * q + tp) * 128 + 8 * s16);
; #pragma unroll
;                 for (int r = 0; r < 4; ++r) {
;                     const v2i d = TR4(ldsb + BUF[st % 3] + 2048 * tp + roff[r]);
;                     accH[r] = __builtin_amdgcn_sdot8(d.x, ah.x, accH[r], false); accH[r] = __builtin_amdgcn_sdot8(d.y, ah.y, accH[r], false);
;                     accL[r] = __builtin_amdgcn_sdot8(d.x, ao.x, accL[r], false); accL[r] = __builtin_amdgcn_sdot8(d.y, ao.y, accL[r], false);
;                 }
;             }
;             asm volatile("s_waitcnt lgkmcnt(0)" ::: "memory");
;             if (q == 3) {
; #pragma unroll
;                 for (int r = 0; r < 4; ++r) STASH[256 * p + 16 * (grp + 4 * r) + pc] = f2bf(asc * (float)(2 * ((accH[r] << 4) + accL[r]) + sa));
;             }
;         }
;         CFENCE();
;         {
;             float4 v[4]; float ss = 0.f;
; #pragma unroll
;             for (int jq = 0; jq < 4; ++jq) { typedef unsigned u2v __attribute__((ext_vector_type(2))); const u2v pw = *(const LAS u2v*)(STASH + 4 * lane + 256 * jq); const uint2 hw = hv[jq];
	v_add_u32_e32 v54, s99, v59
	v_add_u32_e32 v55, s99, v60
	v_add_u32_e32 v56, s99, v61
	v_add_u32_e32 v57, s99, v62
	ds_read_b64_tr_b4 v[50:51], v160 offset:128
	ds_read_b64_tr_b4 v[52:53], v160 offset:1152
	ds_read_b64_tr_b4 v[130:131], v54
	ds_read_b64_tr_b4 v[132:133], v55
	ds_read_b64_tr_b4 v[134:135], v56
	ds_read_b64_tr_b4 v[136:137], v57
	s_waitcnt lgkmcnt(13)
	v_dot8c_i32_i4_e32 v38, v122, v48
	v_dot8c_i32_i4_e32 v39, v122, v46
	v_dot8c_i32_i4_e32 v40, v124, v48
	v_dot8c_i32_i4_e32 v41, v124, v46
	v_dot8c_i32_i4_e32 v42, v126, v48
	v_dot8c_i32_i4_e32 v43, v126, v46
	v_dot8c_i32_i4_e32 v44, v128, v48
	v_dot8c_i32_i4_e32 v45, v128, v46
	v_dot8c_i32_i4_e32 v38, v123, v49
	v_dot8c_i32_i4_e32 v39, v123, v47
	v_dot8c_i32_i4_e32 v40, v125, v49
	v_dot8c_i32_i4_e32 v41, v125, v47
	v_dot8c_i32_i4_e32 v42, v127, v49
	v_dot8c_i32_i4_e32 v43, v127, v47
	v_dot8c_i32_i4_e32 v44, v129, v49
	v_dot8c_i32_i4_e32 v45, v129, v47
	v_and_b32_e32 v78, 0xffff, v32
	v_lshrrev_b32_e32 v79, 16, v32
	v_lshl_add_u32 v78, v78, 7, v152
	v_lshl_add_u32 v79, v79, 7, v153
	s_mov_b32 m0, s98
	s_add_i32 s43, s98, 0x400
	global_load_lds_dwordx4 v78, s[50:51]
	s_mov_b32 m0, s43
	s_nop 0
	global_load_lds_dwordx4 v79, s[50:51]
	s_waitcnt vmcnt(9)
	v_add_u32_e32 v54, s76, v59
	v_add_u32_e32 v55, s76, v60
	v_add_u32_e32 v56, s76, v61
	v_add_u32_e32 v57, s76, v62
	ds_read_b64_tr_b4 v[46:47], v160 offset:256
	ds_read_b64_tr_b4 v[48:49], v160 offset:1280
	ds_read_b64_tr_b4 v[122:123], v54
	ds_read_b64_tr_b4 v[124:125], v55
	ds_read_b64_tr_b4 v[126:127], v56
	ds_read_b64_tr_b4 v[128:129], v57
	s_waitcnt lgkmcnt(6)
	v_dot8c_i32_i4_e32 v38, v130, v52
	v_dot8c_i32_i4_e32 v39, v130, v50
	v_dot8c_i32_i4_e32 v40, v132, v52
	v_dot8c_i32_i4_e32 v41, v132, v50
	v_dot8c_i32_i4_e32 v42, v134, v52
	v_dot8c_i32_i4_e32 v43, v134, v50
	v_dot8c_i32_i4_e32 v44, v136, v52
	v_dot8c_i32_i4_e32 v45, v136, v50
	v_dot8c_i32_i4_e32 v38, v131, v53
	v_dot8c_i32_i4_e32 v39, v131, v51
	v_dot8c_i32_i4_e32 v40, v133, v53
	v_dot8c_i32_i4_e32 v41, v133, v51
	v_dot8c_i32_i4_e32 v42, v135, v53
	v_dot8c_i32_i4_e32 v43, v135, v51
	v_dot8c_i32_i4_e32 v44, v137, v53
	v_dot8c_i32_i4_e32 v45, v137, v51
	ds_write_b16 v65, v170
	ds_write_b16_d16_hi v65, v170 offset:128
	ds_write_b16 v65, v171 offset:256
	ds_write_b16_d16_hi v65, v171 offset:384
	ds_write_b16 v65, v172 offset:512
	ds_write_b16_d16_hi v65, v172 offset:640
	ds_write_b16 v65, v173 offset:768
	ds_write_b16_d16_hi v65, v173 offset:896
	ds_write_b16 v65, v174 offset:1024
	ds_write_b16_d16_hi v65, v174 offset:1152
	ds_write_b16 v65, v175 offset:1280
	ds_write_b16_d16_hi v65, v175 offset:1408
	ds_write_b16 v65, v176 offset:1536
	ds_write_b16_d16_hi v65, v176 offset:1664
	ds_write_b16 v65, v177 offset:1792
	ds_write_b16_d16_hi v65, v177 offset:1920
	ds_read_b64 v[202:203], v154
	ds_read_b64 v[204:205], v154 offset:512
	ds_read_b64 v[206:207], v154 offset:1024
	ds_read_b64 v[208:209], v154 offset:1536
	v_and_b32_e32 v78, 0xffff, v33
	v_lshrrev_b32_e32 v79, 16, v33
	v_lshl_add_u32 v78, v78, 7, v152
	v_lshl_add_u32 v79, v79, 7, v153
	s_mov_b32 m0, s99
	s_add_i32 s43, s99, 0x400
	global_load_lds_dwordx4 v78, s[50:51]
	s_mov_b32 m0, s43
	s_nop 0
	global_load_lds_dwordx4 v79, s[50:51]
	s_waitcnt vmcnt(9)
	v_add_u32_e32 v54, s77, v59
	v_add_u32_e32 v55, s77, v60
	v_add_u32_e32 v56, s77, v61
	v_add_u32_e32 v57, s77, v62
	ds_read_b64_tr_b4 v[50:51], v160 offset:384
	ds_read_b64_tr_b4 v[52:53], v160 offset:1408
	ds_read_b64_tr_b4 v[130:131], v54
	ds_read_b64_tr_b4 v[132:133], v55
	ds_read_b64_tr_b4 v[134:135], v56
	ds_read_b64_tr_b4 v[136:137], v57
	s_waitcnt lgkmcnt(15)
	v_dot8c_i32_i4_e32 v38, v122, v48
	v_dot8c_i32_i4_e32 v39, v122, v46
	v_dot8c_i32_i4_e32 v40, v124, v48
	v_dot8c_i32_i4_e32 v41, v124, v46
	v_dot8c_i32_i4_e32 v42, v126, v48
	v_dot8c_i32_i4_e32 v43, v126, v46
	v_dot8c_i32_i4_e32 v44, v128, v48
	v_dot8c_i32_i4_e32 v45, v128, v46
	v_dot8c_i32_i4_e32 v38, v123, v49
	v_dot8c_i32_i4_e32 v39, v123, v47
	v_dot8c_i32_i4_e32 v40, v125, v49
	v_dot8c_i32_i4_e32 v41, v125, v47
	v_dot8c_i32_i4_e32 v42, v127, v49
	v_dot8c_i32_i4_e32 v43, v127, v47
	v_dot8c_i32_i4_e32 v44, v129, v49
	v_dot8c_i32_i4_e32 v45, v129, v47
	s_waitcnt lgkmcnt(15)
	v_and_b32_e32 v78, 0xffff, v18
	v_lshrrev_b32_e32 v79, 16, v18
	v_lshl_add_u32 v78, v78, 7, v150
	v_lshl_add_u32 v79, v79, 7, v151
	s_mov_b32 m0, s76
	s_add_i32 s43, s76, 0x400
	global_load_lds_dwordx4 v78, s[50:51]
	s_mov_b32 m0, s43
	s_nop 0
	global_load_lds_dwordx4 v79, s[50:51]
	s_waitcnt vmcnt(9)
	v_add_u32_e32 v54, s78, v59
	v_add_u32_e32 v55, s78, v60
	v_add_u32_e32 v56, s78, v61
	v_add_u32_e32 v57, s78, v62
	ds_read_b64_tr_b4 v[46:47], v160 offset:512
	ds_read_b64_tr_b4 v[48:49], v160 offset:1536
	ds_read_b64_tr_b4 v[122:123], v54
	ds_read_b64_tr_b4 v[124:125], v55
	ds_read_b64_tr_b4 v[126:127], v56
	ds_read_b64_tr_b4 v[128:129], v57
	s_waitcnt lgkmcnt(6)
	v_dot8c_i32_i4_e32 v38, v130, v52
	v_dot8c_i32_i4_e32 v39, v130, v50
	v_dot8c_i32_i4_e32 v40, v132, v52
	v_dot8c_i32_i4_e32 v41, v132, v50
	v_dot8c_i32_i4_e32 v42, v134, v52
	v_dot8c_i32_i4_e32 v43, v134, v50
	v_dot8c_i32_i4_e32 v44, v136, v52
	v_dot8c_i32_i4_e32 v45, v136, v50
	v_dot8c_i32_i4_e32 v38, v131, v53
	v_dot8c_i32_i4_e32 v39, v131, v51
	v_dot8c_i32_i4_e32 v40, v133, v53
	v_dot8c_i32_i4_e32 v41, v133, v51
	v_dot8c_i32_i4_e32 v42, v135, v53
	v_dot8c_i32_i4_e32 v43, v135, v51
	v_dot8c_i32_i4_e32 v44, v137, v53
	v_dot8c_i32_i4_e32 v45, v137, v51
	v_and_b32_e32 v78, 0xffff, v19
	v_lshrrev_b32_e32 v79, 16, v19
	v_lshl_add_u32 v78, v78, 7, v150
	v_lshl_add_u32 v79, v79, 7, v151
	s_mov_b32 m0, s77
	s_add_i32 s43, s77, 0x400
	global_load_lds_dwordx4 v78, s[50:51]
	s_mov_b32 m0, s43
	s_nop 0
	global_load_lds_dwordx4 v79, s[50:51]
	s_waitcnt vmcnt(8)
; __device__ __forceinline__ bf16 f2bf(float f) { return (bf16)f2bfu(f); }
; #define TR4(p_) __builtin_amdgcn_ds_read_tr4_b64_v2i32((LAS v2i*)(p_))
; #define VDMA(st_, k_) do { _Pragma("unroll") for (int i_ = 0; i_ < 4; ++i_) { \
;         const unsigned off_ = (unsigned)((st_) >> 2) * (16384u * 128u) + (PE_ID(E, 4 * ((st_) & 3) + i_) << 7) + ((i_ & 1) ? cx1 : cx0); \
;         __builtin_amdgcn_global_load_lds((const unsigned*)(V4 + off_), (LAS unsigned*)(ldsb + BUF[k_] + 1024 * i_), 16, 0, 0); } } while (0)
; __device__ __forceinline__ void peer_v_tokens(int j, const LAS unsigned short* EL, const LAS unsigned char* AL  , const LAS float* ASC  , const LAS int* SAL  , ...
;     ...
;         for (int st = 0; st < 16; ++st) {
;             const int p = st >> 2, q = st & 3;
;             if (st < 14) VDMA(st + 2, (st + 2) % 3);
;             if (st < 14) asm volatile("s_waitcnt vmcnt(8)" ::: "memory");
;             else if (st == 14) asm volatile("s_waitcnt vmcnt(4)" ::: "memory");
;             else asm volatile("s_waitcnt vmcnt(0)" ::: "memory");
;             if (q == 0) {
; #pragma unroll
;                 for (int r = 0; r < 4; ++r) { accH[r] = 0; accL[r] = 0; } }
; #pragma unroll
;             for (int tp = 0; tp < 2; ++tp) {
;                 const v2i ao = TR4(ATL + (2 * q + tp) * 128 + 8 * s16), ah = TR4(ATL + 1024 + (2 * q + tp) * 128 + 8 * s16);
; #pragma unroll
;                 for (int r = 0; r < 4; ++r) {
;                     const v2i d = TR4(ldsb + BUF[st % 3] + 2048 * tp + roff[r]);
;                     accH[r] = __builtin_amdgcn_sdot8(d.x, ah.x, accH[r], false); accH[r] = __builtin_amdgcn_sdot8(d.y, ah.y, accH[r], false);
;                     accL[r] = __builtin_amdgcn_sdot8(d.x, ao.x, accL[r], false); accL[r] = __builtin_amdgcn_sdot8(d.y, ao.y, accL[r], false);
;                 }
;             }
;             asm volatile("s_waitcnt lgkmcnt(0)" ::: "memory");
;             if (q == 3) {
; #pragma unroll
;                 for (int r = 0; r < 4; ++r) STASH[256 * p + 16 * (grp + 4 * r) + pc] = f2bf(asc * (float)(2 * ((accH[r] << 4) + accL[r]) + sa));
	v_add_u32_e32 v54, s79, v59
	v_add_u32_e32 v55, s79, v60
	v_add_u32_e32 v56, s79, v61
	v_add_u32_e32 v57, s79, v62
	ds_read_b64_tr_b4 v[50:51], v160 offset:640
	ds_read_b64_tr_b4 v[52:53], v160 offset:1664
	ds_read_b64_tr_b4 v[130:131], v54
	ds_read_b64_tr_b4 v[132:133], v55
	ds_read_b64_tr_b4 v[134:135], v56
	ds_read_b64_tr_b4 v[136:137], v57
	s_waitcnt lgkmcnt(6)
	v_dot8c_i32_i4_e32 v38, v122, v48
	v_dot8c_i32_i4_e32 v39, v122, v46
	v_dot8c_i32_i4_e32 v40, v124, v48
	v_dot8c_i32_i4_e32 v41, v124, v46
	v_dot8c_i32_i4_e32 v42, v126, v48
	v_dot8c_i32_i4_e32 v43, v126, v46
	v_dot8c_i32_i4_e32 v44, v128, v48
	v_dot8c_i32_i4_e32 v45, v128, v46
	v_dot8c_i32_i4_e32 v38, v123, v49
	v_dot8c_i32_i4_e32 v39, v123, v47
	v_dot8c_i32_i4_e32 v40, v125, v49
	v_dot8c_i32_i4_e32 v41, v125, v47
	v_dot8c_i32_i4_e32 v42, v127, v49
	v_dot8c_i32_i4_e32 v43, v127, v47
	v_dot8c_i32_i4_e32 v44, v129, v49
	v_dot8c_i32_i4_e32 v45, v129, v47
	s_waitcnt lgkmcnt(15)
	v_add_u32_e32 v143, 8, v139
	v_and_b32_e32 v142, 15, v143
	v_xor_b32_e32 v142, 8, v142
	v_bfe_u32 v144, v143, 4, 4
	v_mul_lo_u32 v142, v142, s92
	v_mul_lo_u32 v144, v144, s92
	v_mov_b32_e32 v143, v142
	v_mov_b32_e32 v145, v144
	ds_write2st64_b64 v159, v[142:143], v[144:145] offset1:2
	v_and_b32_e32 v78, 0xffff, v20
	v_lshrrev_b32_e32 v79, 16, v20
	v_lshl_add_u32 v78, v78, 7, v150
	v_lshl_add_u32 v79, v79, 7, v151
	s_mov_b32 m0, s78
	s_add_i32 s43, s78, 0x400
	global_load_lds_dwordx4 v78, s[50:51]
	s_mov_b32 m0, s43
	s_nop 0
	global_load_lds_dwordx4 v79, s[50:51]
	s_waitcnt vmcnt(8)
	v_add_u32_e32 v54, s98, v59
	v_add_u32_e32 v55, s98, v60
	v_add_u32_e32 v56, s98, v61
	v_add_u32_e32 v57, s98, v62
	ds_read_b64_tr_b4 v[46:47], v160 offset:768
	ds_read_b64_tr_b4 v[48:49], v160 offset:1792
	ds_read_b64_tr_b4 v[122:123], v54
	ds_read_b64_tr_b4 v[124:125], v55
	ds_read_b64_tr_b4 v[126:127], v56
	ds_read_b64_tr_b4 v[128:129], v57
	s_waitcnt lgkmcnt(7)
	v_dot8c_i32_i4_e32 v38, v130, v52
	v_dot8c_i32_i4_e32 v39, v130, v50
	v_dot8c_i32_i4_e32 v40, v132, v52
	v_dot8c_i32_i4_e32 v41, v132, v50
	v_dot8c_i32_i4_e32 v42, v134, v52
	v_dot8c_i32_i4_e32 v43, v134, v50
	v_dot8c_i32_i4_e32 v44, v136, v52
	v_dot8c_i32_i4_e32 v45, v136, v50
	v_dot8c_i32_i4_e32 v38, v131, v53
	v_dot8c_i32_i4_e32 v39, v131, v51
	v_dot8c_i32_i4_e32 v40, v133, v53
	v_dot8c_i32_i4_e32 v41, v133, v51
	v_dot8c_i32_i4_e32 v42, v135, v53
	v_dot8c_i32_i4_e32 v43, v135, v51
	v_dot8c_i32_i4_e32 v44, v137, v53
	v_dot8c_i32_i4_e32 v45, v137, v51
	v_and_b32_e32 v78, 0xffff, v21
	v_lshrrev_b32_e32 v79, 16, v21
	v_lshl_add_u32 v78, v78, 7, v150
	v_lshl_add_u32 v79, v79, 7, v151
	s_mov_b32 m0, s79
	s_add_i32 s43, s79, 0x400
	global_load_lds_dwordx4 v78, s[50:51]
	s_mov_b32 m0, s43
	s_nop 0
	global_load_lds_dwordx4 v79, s[50:51]
	s_waitcnt vmcnt(8)
	v_add_u32_e32 v54, s99, v59
	v_add_u32_e32 v55, s99, v60
	v_add_u32_e32 v56, s99, v61
	v_add_u32_e32 v57, s99, v62
	ds_read_b64_tr_b4 v[50:51], v160 offset:896
	ds_read_b64_tr_b4 v[52:53], v160 offset:1920
	ds_read_b64_tr_b4 v[130:131], v54
	ds_read_b64_tr_b4 v[132:133], v55
	ds_read_b64_tr_b4 v[134:135], v56
	ds_read_b64_tr_b4 v[136:137], v57
	s_waitcnt lgkmcnt(6)
	v_dot8c_i32_i4_e32 v38, v122, v48
	v_dot8c_i32_i4_e32 v39, v122, v46
	v_dot8c_i32_i4_e32 v40, v124, v48
	v_dot8c_i32_i4_e32 v41, v124, v46
	v_dot8c_i32_i4_e32 v42, v126, v48
	v_dot8c_i32_i4_e32 v43, v126, v46
	v_dot8c_i32_i4_e32 v44, v128, v48
	v_dot8c_i32_i4_e32 v45, v128, v46
	v_dot8c_i32_i4_e32 v38, v123, v49
	v_dot8c_i32_i4_e32 v39, v123, v47
	v_dot8c_i32_i4_e32 v40, v125, v49
	v_dot8c_i32_i4_e32 v41, v125, v47
	v_dot8c_i32_i4_e32 v42, v127, v49
	v_dot8c_i32_i4_e32 v43, v127, v47
	v_dot8c_i32_i4_e32 v44, v129, v49
	v_dot8c_i32_i4_e32 v45, v129, v47
	v_and_b32_e32 v78, 0xffff, v22
	v_lshrrev_b32_e32 v79, 16, v22
	v_lshl_add_u32 v78, v78, 7, v150
	v_lshl_add_u32 v79, v79, 7, v151
	s_mov_b32 m0, s98
	s_add_i32 s43, s98, 0x400
	global_load_lds_dwordx4 v78, s[50:51]
	s_mov_b32 m0, s43
	s_nop 0
	global_load_lds_dwordx4 v79, s[50:51]
	s_waitcnt vmcnt(8)
	v_add_u32_e32 v54, s76, v59
	v_add_u32_e32 v55, s76, v60
	v_add_u32_e32 v56, s76, v61
	v_add_u32_e32 v57, s76, v62
	ds_read_b64_tr_b4 v[46:47], v160
	ds_read_b64_tr_b4 v[48:49], v160 offset:1024
	ds_read_b64_tr_b4 v[122:123], v54
	ds_read_b64_tr_b4 v[124:125], v55
	ds_read_b64_tr_b4 v[126:127], v56
	ds_read_b64_tr_b4 v[128:129], v57
	s_waitcnt lgkmcnt(6)
	v_dot8c_i32_i4_e32 v38, v130, v52
	v_dot8c_i32_i4_e32 v39, v130, v50
	v_dot8c_i32_i4_e32 v40, v132, v52
	v_dot8c_i32_i4_e32 v41, v132, v50
	v_dot8c_i32_i4_e32 v42, v134, v52
	v_dot8c_i32_i4_e32 v43, v134, v50
	v_dot8c_i32_i4_e32 v44, v136, v52
	v_dot8c_i32_i4_e32 v45, v136, v50
	v_dot8c_i32_i4_e32 v38, v131, v53
	v_dot8c_i32_i4_e32 v39, v131, v51
	v_dot8c_i32_i4_e32 v40, v133, v53
	v_dot8c_i32_i4_e32 v41, v133, v51
	v_dot8c_i32_i4_e32 v42, v135, v53
	v_dot8c_i32_i4_e32 v43, v135, v51
	v_dot8c_i32_i4_e32 v44, v137, v53
	v_dot8c_i32_i4_e32 v45, v137, v51
	s_nop 3
	s_waitcnt lgkmcnt(15)
	v_lshlrev_b32_e32 v38, 5, v38
	v_lshlrev_b32_e32 v39, 1, v39
	v_add3_u32 v38, v39, v229, v38
	v_cvt_f32_i32_e32 v38, v38
	v_mul_f32_e32 v38, v228, v38
	v_lshlrev_b32_e32 v40, 5, v40
	v_lshlrev_b32_e32 v41, 1, v41
	v_add3_u32 v40, v41, v229, v40
	v_cvt_f32_i32_e32 v40, v40
	v_mul_f32_e32 v40, v228, v40
	v_lshlrev_b32_e32 v42, 5, v42
	v_lshlrev_b32_e32 v43, 1, v43
	v_add3_u32 v42, v43, v229, v42
	v_cvt_f32_i32_e32 v42, v42
	v_mul_f32_e32 v42, v228, v42
	v_lshlrev_b32_e32 v44, 5, v44
	v_lshlrev_b32_e32 v45, 1, v45
	v_add3_u32 v44, v45, v229, v44
	v_cvt_f32_i32_e32 v44, v44
	v_mul_f32_e32 v44, v228, v44
	v_cvt_pk_bf16_f32 v188, v38, v40
	v_cvt_pk_bf16_f32 v189, v42, v44
	ds_read_b128 v[252:255], v156
	s_add_i32 s44, s40, 0
	s_ashr_i32 s45, s44, 31
	s_lshl_b64 s[44:45], s[44:45], 12
	v_lshl_add_u64 v[80:81], v[36:37], 0, s[44:45]
	s_waitcnt lgkmcnt(0)
; #define LAS __attribute__((address_space(3)))
; __device__ __forceinline__ void peer_v_tokens(int j, const LAS unsigned short* EL, const LAS unsigned char* AL  , const LAS float* ASC  , const LAS int* SAL  , ...
;     ...
;         {
;             float4 v[4]; float ss = 0.f;
; #pragma unroll
;             for (int jq = 0; jq < 4; ++jq) { typedef unsigned u2v __attribute__((ext_vector_type(2))); const u2v pw = *(const LAS u2v*)(STASH + 4 * lane + 256 * jq); const uint2 hw = hv[jq];
;                 v[jq] = make_float4(__uint_as_float(hw.x << 16) + __uint_as_float(pw.x << 16), __uint_as_float(hw.x & 0xffff0000u) + __uint_as_float(pw.x & 0xffff0000u),
;                                     __uint_as_float(hw.y << 16) + __uint_as_float(pw.y << 16), __uint_as_float(hw.y & 0xffff0000u) + __uint_as_float(pw.y & 0xffff0000u));
;                 ss += v[jq].x * v[jq].x + v[jq].y * v[jq].y + v[jq].z * v[jq].z + v[jq].w * v[jq].w; }
;             ss = wave_sum(ss);
;             const float r3 = rsqrtf(ss * (1.f / D) + EPS);
;             float4* op = (float4*)(outp + (size_t)t * D) + lane;
; #pragma unroll
;             for (int jq = 0; jq < 4; ++jq) { typedef float f4v __attribute__((ext_vector_type(4))); f4v o4; o4.x = v[jq].x * r3 * gv[jq].x; o4.y = v[jq].y * r3 * gv[jq].y; o4.z = v[jq].z * r3 * gv[jq].z; o4.w = v[jq].w * r3 * gv[jq].w;
;                 __builtin_nontemporal_store(o4, (f4v*)op + 64 * jq); }
	v_mul_f32_e32 v218, v218, v252
	v_mul_f32_e32 v219, v219, v253
	v_mul_f32_e32 v220, v220, v254
	v_mul_f32_e32 v221, v221, v255
	global_store_dwordx4 v[80:81], v[218:221], off offset:2048 nt
	v_add_u32_e32 v147, 8, v140
	v_and_b32_e32 v146, 15, v147
	v_xor_b32_e32 v146, 8, v146
	v_bfe_u32 v148, v147, 4, 4
	v_mul_lo_u32 v146, v146, s92
	v_mul_lo_u32 v148, v148, s92
	v_mov_b32_e32 v147, v146
	v_mov_b32_e32 v149, v148
	ds_write2st64_b64 v77, v[146:147], v[148:149] offset1:2
	v_add_u32_e32 v138, 0xc00, v74
	ds_read_u8 v139, v138
	v_add_u32_e32 v141, 0xc00, v73
	ds_read_u8 v140, v141
	s_add_i32 s43, s67, 64
	v_mov_b32_e32 v138, s43
	ds_read2st64_b32 v[228:229], v138 offset1:1
	ds_read_b128 v[26:29], v227 offset:6144
	ds_read_b128 v[30:33], v227 offset:6160
	v_mov_b32_e32 v38, 0
	v_mov_b32_e32 v39, 0
	v_mov_b32_e32 v40, 0
	v_mov_b32_e32 v41, 0
	v_mov_b32_e32 v42, 0
	v_mov_b32_e32 v43, 0
	v_mov_b32_e32 v44, 0
	v_mov_b32_e32 v45, 0
	v_and_b32_e32 v78, 0xffff, v23
	v_lshrrev_b32_e32 v79, 16, v23
	v_lshl_add_u32 v78, v78, 7, v150
	v_lshl_add_u32 v79, v79, 7, v151
	s_mov_b32 m0, s99
	s_add_i32 s43, s99, 0x400
	global_load_lds_dwordx4 v78, s[50:51]
	s_mov_b32 m0, s43
	s_nop 0
	global_load_lds_dwordx4 v79, s[50:51]
	s_waitcnt vmcnt(9)
	v_add_u32_e32 v54, s77, v59
	v_add_u32_e32 v55, s77, v60
	v_add_u32_e32 v56, s77, v61
	v_add_u32_e32 v57, s77, v62
	ds_read_b64_tr_b4 v[50:51], v160 offset:128
	ds_read_b64_tr_b4 v[52:53], v160 offset:1152
	ds_read_b64_tr_b4 v[130:131], v54
	ds_read_b64_tr_b4 v[132:133], v55
	ds_read_b64_tr_b4 v[134:135], v56
	ds_read_b64_tr_b4 v[136:137], v57
	s_waitcnt lgkmcnt(13)
	s_waitcnt vmcnt(36) lgkmcnt(15)
	v_lshlrev_b32_e32 v236, 16, v194
	v_and_b32_e32 v237, 0xffff0000, v194
	v_lshlrev_b32_e32 v142, 16, v202
	v_and_b32_e32 v143, 0xffff0000, v202
	v_add_f32_e32 v236, v236, v142
	v_add_f32_e32 v237, v237, v143
	v_lshlrev_b32_e32 v238, 16, v195
	v_and_b32_e32 v239, 0xffff0000, v195
	v_lshlrev_b32_e32 v142, 16, v203
	v_and_b32_e32 v143, 0xffff0000, v203
	v_add_f32_e32 v238, v238, v142
	v_add_f32_e32 v239, v239, v143
	v_lshlrev_b32_e32 v240, 16, v196
	v_and_b32_e32 v241, 0xffff0000, v196
	v_lshlrev_b32_e32 v142, 16, v204
	v_and_b32_e32 v143, 0xffff0000, v204
	v_add_f32_e32 v240, v240, v142
	v_add_f32_e32 v241, v241, v143
	v_lshlrev_b32_e32 v242, 16, v197
	v_and_b32_e32 v243, 0xffff0000, v197
	v_lshlrev_b32_e32 v142, 16, v205
	v_and_b32_e32 v143, 0xffff0000, v205
	v_add_f32_e32 v242, v242, v142
	v_add_f32_e32 v243, v243, v143
	v_lshlrev_b32_e32 v244, 16, v198
	v_and_b32_e32 v245, 0xffff0000, v198
	v_lshlrev_b32_e32 v142, 16, v206
	v_and_b32_e32 v143, 0xffff0000, v206
	v_add_f32_e32 v244, v244, v142
	v_add_f32_e32 v245, v245, v143
	v_lshlrev_b32_e32 v246, 16, v199
	v_and_b32_e32 v247, 0xffff0000, v199
	v_lshlrev_b32_e32 v142, 16, v207
	v_and_b32_e32 v143, 0xffff0000, v207
	v_add_f32_e32 v246, v246, v142
	v_add_f32_e32 v247, v247, v143
	v_lshlrev_b32_e32 v248, 16, v200
	v_and_b32_e32 v249, 0xffff0000, v200
	v_lshlrev_b32_e32 v142, 16, v208
	v_and_b32_e32 v143, 0xffff0000, v208
	v_add_f32_e32 v248, v248, v142
	v_add_f32_e32 v249, v249, v143
	v_lshlrev_b32_e32 v250, 16, v201
	v_and_b32_e32 v251, 0xffff0000, v201
	v_lshlrev_b32_e32 v142, 16, v209
	v_and_b32_e32 v143, 0xffff0000, v209
	v_add_f32_e32 v250, v250, v142
	v_add_f32_e32 v251, v251, v143
	v_mov_b32_e32 v144, 0
	v_mul_f32_e32 v145, v236, v236
	v_fmac_f32_e32 v145, v237, v237
	v_fmac_f32_e32 v145, v238, v238
	v_fmac_f32_e32 v145, v239, v239
	v_add_f32_e32 v144, v144, v145
	v_mul_f32_e32 v145, v240, v240
	v_fmac_f32_e32 v145, v241, v241
	v_fmac_f32_e32 v145, v242, v242
	v_fmac_f32_e32 v145, v243, v243
	v_add_f32_e32 v144, v144, v145
	v_mul_f32_e32 v145, v244, v244
	v_fmac_f32_e32 v145, v245, v245
	v_fmac_f32_e32 v145, v246, v246
	v_fmac_f32_e32 v145, v247, v247
	v_add_f32_e32 v144, v144, v145
	v_mul_f32_e32 v145, v248, v248
	v_fmac_f32_e32 v145, v249, v249
	v_fmac_f32_e32 v145, v250, v250
	v_fmac_f32_e32 v145, v251, v251
	v_add_f32_e32 v144, v144, v145
	s_nop 1
	v_add_f32_dpp v144, v144, v144 quad_perm:[1,0,3,2] row_mask:0xf bank_mask:0xf bound_ctrl:1
	s_nop 1
	v_add_f32_dpp v144, v144, v144 quad_perm:[2,3,0,1] row_mask:0xf bank_mask:0xf bound_ctrl:1
	s_nop 1
	v_add_f32_dpp v144, v144, v144 row_half_mirror row_mask:0xf bank_mask:0xf bound_ctrl:1
	s_nop 1
	v_add_f32_dpp v144, v144, v144 row_mirror row_mask:0xf bank_mask:0xf bound_ctrl:1
	s_nop 1
	v_readlane_b32 s10, v144, 0
	v_readlane_b32 s11, v144, 16
	v_readlane_b32 s14, v144, 32
	v_readlane_b32 s15, v144, 48
	s_nop 3
	v_mov_b32_e32 v144, s11
	v_mov_b32_e32 v145, s15
	v_add_f32_e32 v144, s10, v144
	v_add_f32_e32 v145, s14, v145
	v_add_f32_e32 v144, v144, v145
	v_fmamk_f32 v144, v144, 0x3a800000, v111
	v_rsq_f32_e32 v144, v144
	s_nop 0
	v_mul_f32_e32 v236, v236, v144
	v_mul_f32_e32 v237, v237, v144
	v_mul_f32_e32 v238, v238, v144
	v_mul_f32_e32 v239, v239, v144
	v_mul_f32_e32 v240, v240, v144
	v_mul_f32_e32 v241, v241, v144
	v_mul_f32_e32 v242, v242, v144
	v_mul_f32_e32 v243, v243, v144
	v_mul_f32_e32 v244, v244, v144
	v_mul_f32_e32 v245, v245, v144
	v_mul_f32_e32 v246, v246, v144
	v_mul_f32_e32 v247, v247, v144
	v_mul_f32_e32 v248, v248, v144
	v_mul_f32_e32 v249, v249, v144
	v_mul_f32_e32 v250, v250, v144
	v_mul_f32_e32 v251, v251, v144
	v_dot8c_i32_i4_e32 v38, v122, v48
	v_dot8c_i32_i4_e32 v39, v122, v46
	v_dot8c_i32_i4_e32 v40, v124, v48
	v_dot8c_i32_i4_e32 v41, v124, v46
	v_dot8c_i32_i4_e32 v42, v126, v48
	v_dot8c_i32_i4_e32 v43, v126, v46
	v_dot8c_i32_i4_e32 v44, v128, v48
	v_dot8c_i32_i4_e32 v45, v128, v46
	v_dot8c_i32_i4_e32 v38, v123, v49
	v_dot8c_i32_i4_e32 v39, v123, v47
	v_dot8c_i32_i4_e32 v40, v125, v49
	v_dot8c_i32_i4_e32 v41, v125, v47
	v_dot8c_i32_i4_e32 v42, v127, v49
	v_dot8c_i32_i4_e32 v43, v127, v47
	v_dot8c_i32_i4_e32 v44, v129, v49
	v_dot8c_i32_i4_e32 v45, v129, v47
	v_and_b32_e32 v78, 0xffff, v24
	v_lshrrev_b32_e32 v79, 16, v24
	v_lshl_add_u32 v78, v78, 7, v150
	v_lshl_add_u32 v79, v79, 7, v151
	s_mov_b32 m0, s76
	s_add_i32 s43, s76, 0x400
	global_load_lds_dwordx4 v78, s[50:51]
	s_mov_b32 m0, s43
	s_nop 0
	global_load_lds_dwordx4 v79, s[50:51]
	s_waitcnt vmcnt(9)
; __device__ __forceinline__ void peer_v_tokens(int j, const LAS unsigned short* EL, const LAS unsigned char* AL  , const LAS float* ASC  , const LAS int* SAL  , ...
;     ...
; #pragma unroll 1
;     for (int it = 0; it < 8; ++it) {
;         const int tl = it * 8 + wave, t = j * 64 + tl;
;         unsigned E[8];
;         { const LAS v4u* ep = (const LAS v4u*)(EL + tl * 128 + 16 * g); const v4u e0 = ep[0], e1 = ep[1];
;           E[0] = e0.x; E[1] = e0.y; E[2] = e0.z; E[3] = e0.w; E[4] = e1.x; E[5] = e1.y; E[6] = e1.z; E[7] = e1.w; }
;         uint2 hv[4]; float4 gv[4];
;         { unsigned ho = (unsigned)t * (D / 4) + (unsigned)lane; asm volatile("" : "+v"(ho)); const uint2* hp = (const uint2*)HB + ho; const float4* gp = (const float4*)fng + lane;
; #pragma unroll
;           for (int jq = 0; jq < 4; ++jq) { hv[jq] = hp[64 * jq]; gv[jq] = gp[64 * jq]; } }
;         VDMA(0, 0); VDMA(1, 1);
; #pragma unroll
;         for (int m = 0; m < 2; ++m) {
;             const int idx = lane + 64 * m, tau = idx >> 4, sr = idx & 15, k = 16 * (sr & 7) + 2 * tau + (sr >> 3);
;             const int aq = (int)*(const LAS signed char*)(AL + tl * 128 + k); const int tq = aq + 8;
;             const unsigned lo = (((unsigned)tq & 15u) ^ 8u) * 0x11111111u, hi = ((unsigned)(tq >> 4) & 15u) * 0x11111111u;
;             typedef unsigned u2v __attribute__((ext_vector_type(2)));
;             u2v l2; l2.x = lo; l2.y = lo; u2v h2; h2.x = hi; h2.y = hi;
;             *(LAS u2v*)(ATL + 8 * idx) = l2; *(LAS u2v*)(ATL + 1024 + 8 * idx) = h2;
;         }
;         const float asc = ASC[tl]; const int sa = SAL[tl];
;         CFENCE();
;         int accH[4], accL[4];
; #pragma unroll
;         for (int st = 0; st < 16; ++st) {
;             const int p = st >> 2, q = st & 3;
;             if (st < 14) VDMA(st + 2, (st + 2) % 3);
;             if (st < 14) asm volatile("s_waitcnt vmcnt(8)" ::: "memory");
;             else if (st == 14) asm volatile("s_waitcnt vmcnt(4)" ::: "memory");
;             else asm volatile("s_waitcnt vmcnt(0)" ::: "memory");
;             if (q == 0) {
; #pragma unroll
;                 for (int r = 0; r < 4; ++r) { accH[r] = 0; accL[r] = 0; } }
; #pragma unroll
;             for (int tp = 0; tp < 2; ++tp) {
;                 const v2i ao = TR4(ATL + (2 * q + tp) * 128 + 8 * s16), ah = TR4(ATL + 1024 + (2 * q + tp) * 128 + 8 * s16);
; #pragma unroll
	v_add_u32_e32 v54, s78, v59
	v_add_u32_e32 v55, s78, v60
	v_add_u32_e32 v56, s78, v61
	v_add_u32_e32 v57, s78, v62
	ds_read_b64_tr_b4 v[46:47], v160 offset:256
	ds_read_b64_tr_b4 v[48:49], v160 offset:1280
	ds_read_b64_tr_b4 v[122:123], v54
	ds_read_b64_tr_b4 v[124:125], v55
	ds_read_b64_tr_b4 v[126:127], v56
	ds_read_b64_tr_b4 v[128:129], v57
	s_waitcnt lgkmcnt(6)
	v_dot8c_i32_i4_e32 v38, v130, v52
	v_dot8c_i32_i4_e32 v39, v130, v50
	v_dot8c_i32_i4_e32 v40, v132, v52
	v_dot8c_i32_i4_e32 v41, v132, v50
	v_dot8c_i32_i4_e32 v42, v134, v52
	v_dot8c_i32_i4_e32 v43, v134, v50
	v_dot8c_i32_i4_e32 v44, v136, v52
	v_dot8c_i32_i4_e32 v45, v136, v50
	v_dot8c_i32_i4_e32 v38, v131, v53
	v_dot8c_i32_i4_e32 v39, v131, v51
	v_dot8c_i32_i4_e32 v40, v133, v53
	v_dot8c_i32_i4_e32 v41, v133, v51
	v_dot8c_i32_i4_e32 v42, v135, v53
	v_dot8c_i32_i4_e32 v43, v135, v51
	v_dot8c_i32_i4_e32 v44, v137, v53
	v_dot8c_i32_i4_e32 v45, v137, v51
	v_and_b32_e32 v78, 0xffff, v25
	v_lshrrev_b32_e32 v79, 16, v25
	v_lshl_add_u32 v78, v78, 7, v150
	v_lshl_add_u32 v79, v79, 7, v151
	s_mov_b32 m0, s77
	s_add_i32 s43, s77, 0x400
	global_load_lds_dwordx4 v78, s[50:51]
	s_mov_b32 m0, s43
	s_nop 0
	global_load_lds_dwordx4 v79, s[50:51]
	s_waitcnt vmcnt(9)
	v_add_u32_e32 v54, s79, v59
	v_add_u32_e32 v55, s79, v60
	v_add_u32_e32 v56, s79, v61
	v_add_u32_e32 v57, s79, v62
	ds_read_b64_tr_b4 v[50:51], v160 offset:384
	ds_read_b64_tr_b4 v[52:53], v160 offset:1408
	ds_read_b64_tr_b4 v[130:131], v54
	ds_read_b64_tr_b4 v[132:133], v55
	ds_read_b64_tr_b4 v[134:135], v56
	ds_read_b64_tr_b4 v[136:137], v57
	s_waitcnt lgkmcnt(6)
	v_dot8c_i32_i4_e32 v38, v122, v48
	v_dot8c_i32_i4_e32 v39, v122, v46
	v_dot8c_i32_i4_e32 v40, v124, v48
	v_dot8c_i32_i4_e32 v41, v124, v46
	v_dot8c_i32_i4_e32 v42, v126, v48
	v_dot8c_i32_i4_e32 v43, v126, v46
	v_dot8c_i32_i4_e32 v44, v128, v48
	v_dot8c_i32_i4_e32 v45, v128, v46
	v_dot8c_i32_i4_e32 v38, v123, v49
	v_dot8c_i32_i4_e32 v39, v123, v47
	v_dot8c_i32_i4_e32 v40, v125, v49
	v_dot8c_i32_i4_e32 v41, v125, v47
	v_dot8c_i32_i4_e32 v42, v127, v49
	v_dot8c_i32_i4_e32 v43, v127, v47
	v_dot8c_i32_i4_e32 v44, v129, v49
	v_dot8c_i32_i4_e32 v45, v129, v47
	s_waitcnt lgkmcnt(15)
	v_and_b32_e32 v78, 0xffff, v26
	v_lshrrev_b32_e32 v79, 16, v26
	v_lshl_add_u32 v78, v78, 7, v150
	v_lshl_add_u32 v79, v79, 7, v151
	s_mov_b32 m0, s78
	s_add_i32 s43, s78, 0x400
	global_load_lds_dwordx4 v78, s[50:51]
	s_mov_b32 m0, s43
	s_nop 0
	global_load_lds_dwordx4 v79, s[50:51]
	s_waitcnt vmcnt(9)
	v_add_u32_e32 v54, s98, v59
	v_add_u32_e32 v55, s98, v60
	v_add_u32_e32 v56, s98, v61
	v_add_u32_e32 v57, s98, v62
	ds_read_b64_tr_b4 v[46:47], v160 offset:512
	ds_read_b64_tr_b4 v[48:49], v160 offset:1536
	ds_read_b64_tr_b4 v[122:123], v54
	ds_read_b64_tr_b4 v[124:125], v55
	ds_read_b64_tr_b4 v[126:127], v56
	ds_read_b64_tr_b4 v[128:129], v57
	s_waitcnt lgkmcnt(6)
	v_dot8c_i32_i4_e32 v38, v130, v52
	v_dot8c_i32_i4_e32 v39, v130, v50
	v_dot8c_i32_i4_e32 v40, v132, v52
	v_dot8c_i32_i4_e32 v41, v132, v50
	v_dot8c_i32_i4_e32 v42, v134, v52
	v_dot8c_i32_i4_e32 v43, v134, v50
	v_dot8c_i32_i4_e32 v44, v136, v52
	v_dot8c_i32_i4_e32 v45, v136, v50
	v_dot8c_i32_i4_e32 v38, v131, v53
	v_dot8c_i32_i4_e32 v39, v131, v51
	v_dot8c_i32_i4_e32 v40, v133, v53
	v_dot8c_i32_i4_e32 v41, v133, v51
	v_dot8c_i32_i4_e32 v42, v135, v53
	v_dot8c_i32_i4_e32 v43, v135, v51
	v_dot8c_i32_i4_e32 v44, v137, v53
	v_dot8c_i32_i4_e32 v45, v137, v51
	v_and_b32_e32 v78, 0xffff, v27
	v_lshrrev_b32_e32 v79, 16, v27
	v_lshl_add_u32 v78, v78, 7, v150
	v_lshl_add_u32 v79, v79, 7, v151
	s_mov_b32 m0, s79
	s_add_i32 s43, s79, 0x400
	global_load_lds_dwordx4 v78, s[50:51]
	s_mov_b32 m0, s43
	s_nop 0
	global_load_lds_dwordx4 v79, s[50:51]
	s_waitcnt vmcnt(8)
	v_add_u32_e32 v54, s99, v59
	v_add_u32_e32 v55, s99, v60
	v_add_u32_e32 v56, s99, v61
	v_add_u32_e32 v57, s99, v62
	ds_read_b64_tr_b4 v[50:51], v160 offset:640
	ds_read_b64_tr_b4 v[52:53], v160 offset:1664
	ds_read_b64_tr_b4 v[130:131], v54
	ds_read_b64_tr_b4 v[132:133], v55
	ds_read_b64_tr_b4 v[134:135], v56
	ds_read_b64_tr_b4 v[136:137], v57
	s_waitcnt lgkmcnt(6)
	v_dot8c_i32_i4_e32 v38, v122, v48
	v_dot8c_i32_i4_e32 v39, v122, v46
	v_dot8c_i32_i4_e32 v40, v124, v48
	v_dot8c_i32_i4_e32 v41, v124, v46
	v_dot8c_i32_i4_e32 v42, v126, v48
	v_dot8c_i32_i4_e32 v43, v126, v46
	v_dot8c_i32_i4_e32 v44, v128, v48
	v_dot8c_i32_i4_e32 v45, v128, v46
	v_dot8c_i32_i4_e32 v38, v123, v49
	v_dot8c_i32_i4_e32 v39, v123, v47
	v_dot8c_i32_i4_e32 v40, v125, v49
	v_dot8c_i32_i4_e32 v41, v125, v47
	v_dot8c_i32_i4_e32 v42, v127, v49
	v_dot8c_i32_i4_e32 v43, v127, v47
	v_dot8c_i32_i4_e32 v44, v129, v49
	v_dot8c_i32_i4_e32 v45, v129, v47
	s_waitcnt lgkmcnt(15)
	v_add_u32_e32 v143, 8, v139
	v_and_b32_e32 v142, 15, v143
	v_xor_b32_e32 v142, 8, v142
	v_bfe_u32 v144, v143, 4, 4
	v_mul_lo_u32 v142, v142, s92
	v_mul_lo_u32 v144, v144, s92
	v_mov_b32_e32 v143, v142
	v_mov_b32_e32 v145, v144
	ds_write2st64_b64 v159, v[142:143], v[144:145] offset1:2
	v_and_b32_e32 v78, 0xffff, v28
	v_lshrrev_b32_e32 v79, 16, v28
	v_lshl_add_u32 v78, v78, 7, v150
	v_lshl_add_u32 v79, v79, 7, v151
	s_mov_b32 m0, s98
	s_add_i32 s43, s98, 0x400
	global_load_lds_dwordx4 v78, s[50:51]
	s_mov_b32 m0, s43
	s_nop 0
	global_load_lds_dwordx4 v79, s[50:51]
	s_waitcnt vmcnt(8)
	v_add_u32_e32 v54, s76, v59
	v_add_u32_e32 v55, s76, v60
	v_add_u32_e32 v56, s76, v61
	v_add_u32_e32 v57, s76, v62
	ds_read_b64_tr_b4 v[46:47], v160 offset:768
	ds_read_b64_tr_b4 v[48:49], v160 offset:1792
	ds_read_b64_tr_b4 v[122:123], v54
	ds_read_b64_tr_b4 v[124:125], v55
	ds_read_b64_tr_b4 v[126:127], v56
	ds_read_b64_tr_b4 v[128:129], v57
	s_waitcnt lgkmcnt(7)
; __device__ __forceinline__ void peer_v_tokens(int j, const LAS unsigned short* EL, const LAS unsigned char* AL  , const LAS float* ASC  , const LAS int* SAL  , ...
;     ...
; #pragma unroll
;         for (int st = 0; st < 16; ++st) {
;             const int p = st >> 2, q = st & 3;
;             if (st < 14) VDMA(st + 2, (st + 2) % 3);
;             if (st < 14) asm volatile("s_waitcnt vmcnt(8)" ::: "memory");
;             else if (st == 14) asm volatile("s_waitcnt vmcnt(4)" ::: "memory");
;             else asm volatile("s_waitcnt vmcnt(0)" ::: "memory");
;             if (q == 0) {
; #pragma unroll
;                 for (int r = 0; r < 4; ++r) { accH[r] = 0; accL[r] = 0; } }
; #pragma unroll
;             for (int tp = 0; tp < 2; ++tp) {
;                 const v2i ao = TR4(ATL + (2 * q + tp) * 128 + 8 * s16), ah = TR4(ATL + 1024 + (2 * q + tp) * 128 + 8 * s16);
; #pragma unroll
;                 for (int r = 0; r < 4; ++r) {
;                     const v2i d = TR4(ldsb + BUF[st % 3] + 2048 * tp + roff[r]);
;                     accH[r] = __builtin_amdgcn_sdot8(d.x, ah.x, accH[r], false); accH[r] = __builtin_amdgcn_sdot8(d.y, ah.y, accH[r], false);
;                     accL[r] = __builtin_amdgcn_sdot8(d.x, ao.x, accL[r], false); accL[r] = __builtin_amdgcn_sdot8(d.y, ao.y, accL[r], false);
;                 }
;             }
;             asm volatile("s_waitcnt lgkmcnt(0)" ::: "memory");
;             if (q == 3) {
; #pragma unroll
;                 for (int r = 0; r < 4; ++r) STASH[256 * p + 16 * (grp + 4 * r) + pc] = f2bf(asc * (float)(2 * ((accH[r] << 4) + accL[r]) + sa));
;             }
;         }
;     ...
;         {
;             float4 v[4]; float ss = 0.f;
; #pragma unroll
;             for (int jq = 0; jq < 4; ++jq) { typedef unsigned u2v __attribute__((ext_vector_type(2))); const u2v pw = *(const LAS u2v*)(STASH + 4 * lane + 256 * jq); const uint2 hw = hv[jq];
;                 v[jq] = make_float4(__uint_as_float(hw.x << 16) + __uint_as_float(pw.x << 16), __uint_as_float(hw.x & 0xffff0000u) + __uint_as_float(pw.x & 0xffff0000u),
;                                     __uint_as_float(hw.y << 16) + __uint_as_float(pw.y << 16), __uint_as_float(hw.y & 0xffff0000u) + __uint_as_float(pw.y & 0xffff0000u));
;                 ss += v[jq].x * v[jq].x + v[jq].y * v[jq].y + v[jq].z * v[jq].z + v[jq].w * v[jq].w; }
;             ss = wave_sum(ss);
	v_dot8c_i32_i4_e32 v38, v130, v52
	v_dot8c_i32_i4_e32 v39, v130, v50
	v_dot8c_i32_i4_e32 v40, v132, v52
	v_dot8c_i32_i4_e32 v41, v132, v50
	v_dot8c_i32_i4_e32 v42, v134, v52
	v_dot8c_i32_i4_e32 v43, v134, v50
	v_dot8c_i32_i4_e32 v44, v136, v52
	v_dot8c_i32_i4_e32 v45, v136, v50
	v_dot8c_i32_i4_e32 v38, v131, v53
	v_dot8c_i32_i4_e32 v39, v131, v51
	v_dot8c_i32_i4_e32 v40, v133, v53
	v_dot8c_i32_i4_e32 v41, v133, v51
	v_dot8c_i32_i4_e32 v42, v135, v53
	v_dot8c_i32_i4_e32 v43, v135, v51
	v_dot8c_i32_i4_e32 v44, v137, v53
	v_dot8c_i32_i4_e32 v45, v137, v51
	v_and_b32_e32 v78, 0xffff, v29
	v_lshrrev_b32_e32 v79, 16, v29
	v_lshl_add_u32 v78, v78, 7, v150
	v_lshl_add_u32 v79, v79, 7, v151
	s_mov_b32 m0, s99
	s_add_i32 s43, s99, 0x400
	global_load_lds_dwordx4 v78, s[50:51]
	s_mov_b32 m0, s43
	s_nop 0
	global_load_lds_dwordx4 v79, s[50:51]
	s_waitcnt vmcnt(8)
	v_add_u32_e32 v54, s77, v59
	v_add_u32_e32 v55, s77, v60
	v_add_u32_e32 v56, s77, v61
	v_add_u32_e32 v57, s77, v62
	ds_read_b64_tr_b4 v[50:51], v160 offset:896
	ds_read_b64_tr_b4 v[52:53], v160 offset:1920
	ds_read_b64_tr_b4 v[130:131], v54
	ds_read_b64_tr_b4 v[132:133], v55
	ds_read_b64_tr_b4 v[134:135], v56
	ds_read_b64_tr_b4 v[136:137], v57
	s_waitcnt lgkmcnt(6)
	v_dot8c_i32_i4_e32 v38, v122, v48
	v_dot8c_i32_i4_e32 v39, v122, v46
	v_dot8c_i32_i4_e32 v40, v124, v48
	v_dot8c_i32_i4_e32 v41, v124, v46
	v_dot8c_i32_i4_e32 v42, v126, v48
	v_dot8c_i32_i4_e32 v43, v126, v46
	v_dot8c_i32_i4_e32 v44, v128, v48
	v_dot8c_i32_i4_e32 v45, v128, v46
	v_dot8c_i32_i4_e32 v38, v123, v49
	v_dot8c_i32_i4_e32 v39, v123, v47
	v_dot8c_i32_i4_e32 v40, v125, v49
	v_dot8c_i32_i4_e32 v41, v125, v47
	v_dot8c_i32_i4_e32 v42, v127, v49
	v_dot8c_i32_i4_e32 v43, v127, v47
	v_dot8c_i32_i4_e32 v44, v129, v49
	v_dot8c_i32_i4_e32 v45, v129, v47
	v_and_b32_e32 v78, 0xffff, v30
	v_lshrrev_b32_e32 v79, 16, v30
	v_lshl_add_u32 v78, v78, 7, v150
	v_lshl_add_u32 v79, v79, 7, v151
	s_mov_b32 m0, s76
	s_add_i32 s43, s76, 0x400
	global_load_lds_dwordx4 v78, s[50:51]
	s_mov_b32 m0, s43
	s_nop 0
	global_load_lds_dwordx4 v79, s[50:51]
	s_waitcnt vmcnt(8)
	v_add_u32_e32 v54, s78, v59
	v_add_u32_e32 v55, s78, v60
	v_add_u32_e32 v56, s78, v61
	v_add_u32_e32 v57, s78, v62
	ds_read_b64_tr_b4 v[46:47], v160
	ds_read_b64_tr_b4 v[48:49], v160 offset:1024
	ds_read_b64_tr_b4 v[122:123], v54
	ds_read_b64_tr_b4 v[124:125], v55
	ds_read_b64_tr_b4 v[126:127], v56
	ds_read_b64_tr_b4 v[128:129], v57
	s_waitcnt lgkmcnt(6)
	v_dot8c_i32_i4_e32 v38, v130, v52
	v_dot8c_i32_i4_e32 v39, v130, v50
	v_dot8c_i32_i4_e32 v40, v132, v52
	v_dot8c_i32_i4_e32 v41, v132, v50
	v_dot8c_i32_i4_e32 v42, v134, v52
	v_dot8c_i32_i4_e32 v43, v134, v50
	v_dot8c_i32_i4_e32 v44, v136, v52
	v_dot8c_i32_i4_e32 v45, v136, v50
	v_dot8c_i32_i4_e32 v38, v131, v53
	v_dot8c_i32_i4_e32 v39, v131, v51
	v_dot8c_i32_i4_e32 v40, v133, v53
	v_dot8c_i32_i4_e32 v41, v133, v51
	v_dot8c_i32_i4_e32 v42, v135, v53
	v_dot8c_i32_i4_e32 v43, v135, v51
	v_dot8c_i32_i4_e32 v44, v137, v53
	v_dot8c_i32_i4_e32 v45, v137, v51
	s_nop 3
	s_waitcnt lgkmcnt(15)
	v_lshlrev_b32_e32 v38, 5, v38
	v_lshlrev_b32_e32 v39, 1, v39
	v_add3_u32 v38, v39, v229, v38
	v_cvt_f32_i32_e32 v38, v38
	v_mul_f32_e32 v38, v228, v38
	v_lshlrev_b32_e32 v40, 5, v40
	v_lshlrev_b32_e32 v41, 1, v41
	v_add3_u32 v40, v41, v229, v40
	v_cvt_f32_i32_e32 v40, v40
	v_mul_f32_e32 v40, v228, v40
	v_lshlrev_b32_e32 v42, 5, v42
	v_lshlrev_b32_e32 v43, 1, v43
	v_add3_u32 v42, v43, v229, v42
	v_cvt_f32_i32_e32 v42, v42
	v_mul_f32_e32 v42, v228, v42
	v_lshlrev_b32_e32 v44, 5, v44
	v_lshlrev_b32_e32 v45, 1, v45
	v_add3_u32 v44, v45, v229, v44
	v_cvt_f32_i32_e32 v44, v44
	v_mul_f32_e32 v44, v228, v44
	v_cvt_pk_bf16_f32 v182, v38, v40
	v_cvt_pk_bf16_f32 v183, v42, v44
	ds_read_b128 v[252:255], v156 offset:1024
	s_add_i32 s44, s40, 0
	s_ashr_i32 s45, s44, 31
	s_lshl_b64 s[44:45], s[44:45], 12
	v_lshl_add_u64 v[80:81], v[36:37], 0, s[44:45]
	s_waitcnt lgkmcnt(0)
	v_mul_f32_e32 v222, v222, v252
	v_mul_f32_e32 v223, v223, v253
	v_mul_f32_e32 v224, v224, v254
	v_mul_f32_e32 v225, v225, v255
	global_store_dwordx4 v[80:81], v[222:225], off offset:3072 nt
	ds_read_b128 v[252:255], v155
	s_add_i32 s44, s40, 8
	s_ashr_i32 s45, s44, 31
	s_lshl_b64 s[44:45], s[44:45], 12
	v_lshl_add_u64 v[80:81], v[36:37], 0, s[44:45]
	s_waitcnt lgkmcnt(0)
	v_mul_f32_e32 v236, v236, v252
	v_mul_f32_e32 v237, v237, v253
	v_mul_f32_e32 v238, v238, v254
	v_mul_f32_e32 v239, v239, v255
	global_store_dwordx4 v[80:81], v[236:239], off nt
	v_add_u32_e32 v147, 8, v140
	v_and_b32_e32 v146, 15, v147
	v_xor_b32_e32 v146, 8, v146
	v_bfe_u32 v148, v147, 4, 4
	v_mul_lo_u32 v146, v146, s92
	v_mul_lo_u32 v148, v148, s92
	v_mov_b32_e32 v147, v146
	v_mov_b32_e32 v149, v148
	ds_write2st64_b64 v77, v[146:147], v[148:149] offset1:2
	v_add_u32_e32 v138, 0x800, v74
	ds_read_u8 v139, v138
	v_add_u32_e32 v141, 0x800, v73
	ds_read_u8 v140, v141
	s_add_i32 s43, s67, 96
	v_mov_b32_e32 v138, s43
	ds_read2st64_b32 v[228:229], v138 offset1:1
	ds_read_b128 v[18:21], v227 offset:4096
	ds_read_b128 v[22:25], v227 offset:4112
	v_add_u32_e32 v152, 0x600000, v63
	v_add_u32_e32 v153, 0x600000, v64
	v_mov_b32_e32 v38, 0
	v_mov_b32_e32 v39, 0
	v_mov_b32_e32 v40, 0
	v_mov_b32_e32 v41, 0
	v_mov_b32_e32 v42, 0
	v_mov_b32_e32 v43, 0
	v_mov_b32_e32 v44, 0
	v_mov_b32_e32 v45, 0
	v_and_b32_e32 v78, 0xffff, v31
	v_lshrrev_b32_e32 v79, 16, v31
	v_lshl_add_u32 v78, v78, 7, v150
	v_lshl_add_u32 v79, v79, 7, v151
	s_mov_b32 m0, s77
	s_add_i32 s43, s77, 0x400
	global_load_lds_dwordx4 v78, s[50:51]
	s_mov_b32 m0, s43
	s_nop 0
	global_load_lds_dwordx4 v79, s[50:51]
	s_waitcnt vmcnt(10)
; __device__ __forceinline__ void peer_v_tokens(int j, const LAS unsigned short* EL, const LAS unsigned char* AL  , const LAS float* ASC  , const LAS int* SAL  , ...
;     ...
; #pragma unroll 1
;     for (int it = 0; it < 8; ++it) {
;         const int tl = it * 8 + wave, t = j * 64 + tl;
;         unsigned E[8];
;         { const LAS v4u* ep = (const LAS v4u*)(EL + tl * 128 + 16 * g); const v4u e0 = ep[0], e1 = ep[1];
;           E[0] = e0.x; E[1] = e0.y; E[2] = e0.z; E[3] = e0.w; E[4] = e1.x; E[5] = e1.y; E[6] = e1.z; E[7] = e1.w; }
;         uint2 hv[4]; float4 gv[4];
;         { unsigned ho = (unsigned)t * (D / 4) + (unsigned)lane; asm volatile("" : "+v"(ho)); const uint2* hp = (const uint2*)HB + ho; const float4* gp = (const float4*)fng + lane;
; #pragma unroll
;           for (int jq = 0; jq < 4; ++jq) { hv[jq] = hp[64 * jq]; gv[jq] = gp[64 * jq]; } }
;         VDMA(0, 0); VDMA(1, 1);
; #pragma unroll
;         for (int m = 0; m < 2; ++m) {
;             const int idx = lane + 64 * m, tau = idx >> 4, sr = idx & 15, k = 16 * (sr & 7) + 2 * tau + (sr >> 3);
;             const int aq = (int)*(const LAS signed char*)(AL + tl * 128 + k); const int tq = aq + 8;
;             const unsigned lo = (((unsigned)tq & 15u) ^ 8u) * 0x11111111u, hi = ((unsigned)(tq >> 4) & 15u) * 0x11111111u;
;             typedef unsigned u2v __attribute__((ext_vector_type(2)));
;             u2v l2; l2.x = lo; l2.y = lo; u2v h2; h2.x = hi; h2.y = hi;
;             *(LAS u2v*)(ATL + 8 * idx) = l2; *(LAS u2v*)(ATL + 1024 + 8 * idx) = h2;
;         }
;         const float asc = ASC[tl]; const int sa = SAL[tl];
;         CFENCE();
;         int accH[4], accL[4];
; #pragma unroll
;         for (int st = 0; st < 16; ++st) {
;             const int p = st >> 2, q = st & 3;
;             if (st < 14) VDMA(st + 2, (st + 2) % 3);
;             if (st < 14) asm volatile("s_waitcnt vmcnt(8)" ::: "memory");
;             else if (st == 14) asm volatile("s_waitcnt vmcnt(4)" ::: "memory");
;             else asm volatile("s_waitcnt vmcnt(0)" ::: "memory");
;             if (q == 0) {
; #pragma unroll
;                 for (int r = 0; r < 4; ++r) { accH[r] = 0; accL[r] = 0; } }
; #pragma unroll
;             for (int tp = 0; tp < 2; ++tp) {
;                 const v2i ao = TR4(ATL + (2 * q + tp) * 128 + 8 * s16), ah = TR4(ATL + 1024 + (2 * q + tp) * 128 + 8 * s16);
; #pragma unroll
	v_add_u32_e32 v54, s79, v59
	v_add_u32_e32 v55, s79, v60
	v_add_u32_e32 v56, s79, v61
	v_add_u32_e32 v57, s79, v62
	ds_read_b64_tr_b4 v[50:51], v160 offset:128
	ds_read_b64_tr_b4 v[52:53], v160 offset:1152
	ds_read_b64_tr_b4 v[130:131], v54
	ds_read_b64_tr_b4 v[132:133], v55
	ds_read_b64_tr_b4 v[134:135], v56
	ds_read_b64_tr_b4 v[136:137], v57
	s_waitcnt lgkmcnt(14)
	v_dot8c_i32_i4_e32 v38, v122, v48
	v_dot8c_i32_i4_e32 v39, v122, v46
	v_dot8c_i32_i4_e32 v40, v124, v48
	v_dot8c_i32_i4_e32 v41, v124, v46
	v_dot8c_i32_i4_e32 v42, v126, v48
	v_dot8c_i32_i4_e32 v43, v126, v46
	v_dot8c_i32_i4_e32 v44, v128, v48
	v_dot8c_i32_i4_e32 v45, v128, v46
	v_dot8c_i32_i4_e32 v38, v123, v49
	v_dot8c_i32_i4_e32 v39, v123, v47
	v_dot8c_i32_i4_e32 v40, v125, v49
	v_dot8c_i32_i4_e32 v41, v125, v47
	v_dot8c_i32_i4_e32 v42, v127, v49
	v_dot8c_i32_i4_e32 v43, v127, v47
	v_dot8c_i32_i4_e32 v44, v129, v49
	v_dot8c_i32_i4_e32 v45, v129, v47
	v_and_b32_e32 v78, 0xffff, v32
	v_lshrrev_b32_e32 v79, 16, v32
	v_lshl_add_u32 v78, v78, 7, v150
	v_lshl_add_u32 v79, v79, 7, v151
	s_mov_b32 m0, s78
	s_add_i32 s43, s78, 0x400
	global_load_lds_dwordx4 v78, s[50:51]
	s_mov_b32 m0, s43
	s_nop 0
	global_load_lds_dwordx4 v79, s[50:51]
	s_waitcnt vmcnt(10)
	v_add_u32_e32 v54, s98, v59
	v_add_u32_e32 v55, s98, v60
	v_add_u32_e32 v56, s98, v61
	v_add_u32_e32 v57, s98, v62
	ds_read_b64_tr_b4 v[46:47], v160 offset:256
	ds_read_b64_tr_b4 v[48:49], v160 offset:1280
	ds_read_b64_tr_b4 v[122:123], v54
	ds_read_b64_tr_b4 v[124:125], v55
	ds_read_b64_tr_b4 v[126:127], v56
	ds_read_b64_tr_b4 v[128:129], v57
	s_waitcnt lgkmcnt(6)
	v_dot8c_i32_i4_e32 v38, v130, v52
	v_dot8c_i32_i4_e32 v39, v130, v50
	v_dot8c_i32_i4_e32 v40, v132, v52
	v_dot8c_i32_i4_e32 v41, v132, v50
	v_dot8c_i32_i4_e32 v42, v134, v52
	v_dot8c_i32_i4_e32 v43, v134, v50
	v_dot8c_i32_i4_e32 v44, v136, v52
	v_dot8c_i32_i4_e32 v45, v136, v50
	v_dot8c_i32_i4_e32 v38, v131, v53
	v_dot8c_i32_i4_e32 v39, v131, v51
	v_dot8c_i32_i4_e32 v40, v133, v53
	v_dot8c_i32_i4_e32 v41, v133, v51
	v_dot8c_i32_i4_e32 v42, v135, v53
	v_dot8c_i32_i4_e32 v43, v135, v51
	v_dot8c_i32_i4_e32 v44, v137, v53
	v_dot8c_i32_i4_e32 v45, v137, v51
	v_and_b32_e32 v78, 0xffff, v33
	v_lshrrev_b32_e32 v79, 16, v33
	v_lshl_add_u32 v78, v78, 7, v150
	v_lshl_add_u32 v79, v79, 7, v151
	s_mov_b32 m0, s79
	s_add_i32 s43, s79, 0x400
	global_load_lds_dwordx4 v78, s[50:51]
	s_mov_b32 m0, s43
	s_nop 0
	global_load_lds_dwordx4 v79, s[50:51]
	s_waitcnt vmcnt(10)
	v_add_u32_e32 v54, s99, v59
	v_add_u32_e32 v55, s99, v60
	v_add_u32_e32 v56, s99, v61
	v_add_u32_e32 v57, s99, v62
	ds_read_b64_tr_b4 v[50:51], v160 offset:384
	ds_read_b64_tr_b4 v[52:53], v160 offset:1408
	ds_read_b64_tr_b4 v[130:131], v54
	ds_read_b64_tr_b4 v[132:133], v55
	ds_read_b64_tr_b4 v[134:135], v56
	ds_read_b64_tr_b4 v[136:137], v57
	s_waitcnt lgkmcnt(6)
	v_dot8c_i32_i4_e32 v38, v122, v48
	v_dot8c_i32_i4_e32 v39, v122, v46
	v_dot8c_i32_i4_e32 v40, v124, v48
	v_dot8c_i32_i4_e32 v41, v124, v46
	v_dot8c_i32_i4_e32 v42, v126, v48
	v_dot8c_i32_i4_e32 v43, v126, v46
	v_dot8c_i32_i4_e32 v44, v128, v48
	v_dot8c_i32_i4_e32 v45, v128, v46
	v_dot8c_i32_i4_e32 v38, v123, v49
	v_dot8c_i32_i4_e32 v39, v123, v47
	v_dot8c_i32_i4_e32 v40, v125, v49
	v_dot8c_i32_i4_e32 v41, v125, v47
	v_dot8c_i32_i4_e32 v42, v127, v49
	v_dot8c_i32_i4_e32 v43, v127, v47
	v_dot8c_i32_i4_e32 v44, v129, v49
	v_dot8c_i32_i4_e32 v45, v129, v47
	s_waitcnt lgkmcnt(15)
	v_and_b32_e32 v78, 0xffff, v18
	v_lshrrev_b32_e32 v79, 16, v18
	v_lshl_add_u32 v78, v78, 7, v152
	v_lshl_add_u32 v79, v79, 7, v153
	s_mov_b32 m0, s98
	s_add_i32 s43, s98, 0x400
	global_load_lds_dwordx4 v78, s[50:51]
	s_mov_b32 m0, s43
	s_nop 0
	global_load_lds_dwordx4 v79, s[50:51]
	s_waitcnt vmcnt(10)
	v_add_u32_e32 v54, s76, v59
	v_add_u32_e32 v55, s76, v60
	v_add_u32_e32 v56, s76, v61
	v_add_u32_e32 v57, s76, v62
	ds_read_b64_tr_b4 v[46:47], v160 offset:512
	ds_read_b64_tr_b4 v[48:49], v160 offset:1536
	ds_read_b64_tr_b4 v[122:123], v54
	ds_read_b64_tr_b4 v[124:125], v55
	ds_read_b64_tr_b4 v[126:127], v56
	ds_read_b64_tr_b4 v[128:129], v57
	s_waitcnt lgkmcnt(6)
	v_dot8c_i32_i4_e32 v38, v130, v52
	v_dot8c_i32_i4_e32 v39, v130, v50
	v_dot8c_i32_i4_e32 v40, v132, v52
	v_dot8c_i32_i4_e32 v41, v132, v50
	v_dot8c_i32_i4_e32 v42, v134, v52
	v_dot8c_i32_i4_e32 v43, v134, v50
	v_dot8c_i32_i4_e32 v44, v136, v52
	v_dot8c_i32_i4_e32 v45, v136, v50
	v_dot8c_i32_i4_e32 v38, v131, v53
	v_dot8c_i32_i4_e32 v39, v131, v51
	v_dot8c_i32_i4_e32 v40, v133, v53
	v_dot8c_i32_i4_e32 v41, v133, v51
	v_dot8c_i32_i4_e32 v42, v135, v53
	v_dot8c_i32_i4_e32 v43, v135, v51
	v_dot8c_i32_i4_e32 v44, v137, v53
	v_dot8c_i32_i4_e32 v45, v137, v51
	v_and_b32_e32 v78, 0xffff, v19
	v_lshrrev_b32_e32 v79, 16, v19
	v_lshl_add_u32 v78, v78, 7, v152
	v_lshl_add_u32 v79, v79, 7, v153
	s_mov_b32 m0, s99
	s_add_i32 s43, s99, 0x400
	global_load_lds_dwordx4 v78, s[50:51]
	s_mov_b32 m0, s43
	s_nop 0
	global_load_lds_dwordx4 v79, s[50:51]
	s_waitcnt vmcnt(8)
	v_add_u32_e32 v54, s77, v59
	v_add_u32_e32 v55, s77, v60
	v_add_u32_e32 v56, s77, v61
	v_add_u32_e32 v57, s77, v62
	ds_read_b64_tr_b4 v[50:51], v160 offset:640
	ds_read_b64_tr_b4 v[52:53], v160 offset:1664
	ds_read_b64_tr_b4 v[130:131], v54
	ds_read_b64_tr_b4 v[132:133], v55
	ds_read_b64_tr_b4 v[134:135], v56
	ds_read_b64_tr_b4 v[136:137], v57
	s_waitcnt lgkmcnt(6)
	v_dot8c_i32_i4_e32 v38, v122, v48
	v_dot8c_i32_i4_e32 v39, v122, v46
	v_dot8c_i32_i4_e32 v40, v124, v48
	v_dot8c_i32_i4_e32 v41, v124, v46
	v_dot8c_i32_i4_e32 v42, v126, v48
	v_dot8c_i32_i4_e32 v43, v126, v46
	v_dot8c_i32_i4_e32 v44, v128, v48
	v_dot8c_i32_i4_e32 v45, v128, v46
	v_dot8c_i32_i4_e32 v38, v123, v49
	v_dot8c_i32_i4_e32 v39, v123, v47
	v_dot8c_i32_i4_e32 v40, v125, v49
	v_dot8c_i32_i4_e32 v41, v125, v47
	v_dot8c_i32_i4_e32 v42, v127, v49
	v_dot8c_i32_i4_e32 v43, v127, v47
	v_dot8c_i32_i4_e32 v44, v129, v49
	v_dot8c_i32_i4_e32 v45, v129, v47
	s_waitcnt lgkmcnt(15)
; #define LAS __attribute__((address_space(3)))
; __device__ __forceinline__ void peer_v_tokens(int j, const LAS unsigned short* EL, const LAS unsigned char* AL  , const LAS float* ASC  , const LAS int* SAL  , ...
;     ...
;         for (int m = 0; m < 2; ++m) {
;             const int idx = lane + 64 * m, tau = idx >> 4, sr = idx & 15, k = 16 * (sr & 7) + 2 * tau + (sr >> 3);
;             const int aq = (int)*(const LAS signed char*)(AL + tl * 128 + k); const int tq = aq + 8;
;             const unsigned lo = (((unsigned)tq & 15u) ^ 8u) * 0x11111111u, hi = ((unsigned)(tq >> 4) & 15u) * 0x11111111u;
;             typedef unsigned u2v __attribute__((ext_vector_type(2)));
;             u2v l2; l2.x = lo; l2.y = lo; u2v h2; h2.x = hi; h2.y = hi;
;             *(LAS u2v*)(ATL + 8 * idx) = l2; *(LAS u2v*)(ATL + 1024 + 8 * idx) = h2;
;         }
;     ...
; #pragma unroll
;         for (int st = 0; st < 16; ++st) {
;             const int p = st >> 2, q = st & 3;
;             if (st < 14) VDMA(st + 2, (st + 2) % 3);
;             if (st < 14) asm volatile("s_waitcnt vmcnt(8)" ::: "memory");
;             else if (st == 14) asm volatile("s_waitcnt vmcnt(4)" ::: "memory");
;             else asm volatile("s_waitcnt vmcnt(0)" ::: "memory");
;             if (q == 0) {
; #pragma unroll
;                 for (int r = 0; r < 4; ++r) { accH[r] = 0; accL[r] = 0; } }
; #pragma unroll
;             for (int tp = 0; tp < 2; ++tp) {
;                 const v2i ao = TR4(ATL + (2 * q + tp) * 128 + 8 * s16), ah = TR4(ATL + 1024 + (2 * q + tp) * 128 + 8 * s16);
; #pragma unroll
;                 for (int r = 0; r < 4; ++r) {
;                     const v2i d = TR4(ldsb + BUF[st % 3] + 2048 * tp + roff[r]);
;                     accH[r] = __builtin_amdgcn_sdot8(d.x, ah.x, accH[r], false); accH[r] = __builtin_amdgcn_sdot8(d.y, ah.y, accH[r], false);
;                     accL[r] = __builtin_amdgcn_sdot8(d.x, ao.x, accL[r], false); accL[r] = __builtin_amdgcn_sdot8(d.y, ao.y, accL[r], false);
;                 }
;             }
;             asm volatile("s_waitcnt lgkmcnt(0)" ::: "memory");
;             if (q == 3) {
; #pragma unroll
;                 for (int r = 0; r < 4; ++r) STASH[256 * p + 16 * (grp + 4 * r) + pc] = f2bf(asc * (float)(2 * ((accH[r] << 4) + accL[r]) + sa));
;             }
;         }
;         CFENCE();
;         {
;             float4 v[4]; float ss = 0.f;
; #pragma unroll
	v_add_u32_e32 v143, 8, v139
	v_and_b32_e32 v142, 15, v143
	v_xor_b32_e32 v142, 8, v142
	v_bfe_u32 v144, v143, 4, 4
	v_mul_lo_u32 v142, v142, s92
	v_mul_lo_u32 v144, v144, s92
	v_mov_b32_e32 v143, v142
	v_mov_b32_e32 v145, v144
	ds_write2st64_b64 v159, v[142:143], v[144:145] offset1:2
	v_and_b32_e32 v78, 0xffff, v20
	v_lshrrev_b32_e32 v79, 16, v20
	v_lshl_add_u32 v78, v78, 7, v152
	v_lshl_add_u32 v79, v79, 7, v153
	s_mov_b32 m0, s76
	s_add_i32 s43, s76, 0x400
	global_load_lds_dwordx4 v78, s[50:51]
	s_mov_b32 m0, s43
	s_nop 0
	global_load_lds_dwordx4 v79, s[50:51]
	s_waitcnt vmcnt(8)
	v_add_u32_e32 v54, s78, v59
	v_add_u32_e32 v55, s78, v60
	v_add_u32_e32 v56, s78, v61
	v_add_u32_e32 v57, s78, v62
	ds_read_b64_tr_b4 v[46:47], v160 offset:768
	ds_read_b64_tr_b4 v[48:49], v160 offset:1792
	ds_read_b64_tr_b4 v[122:123], v54
	ds_read_b64_tr_b4 v[124:125], v55
	ds_read_b64_tr_b4 v[126:127], v56
	ds_read_b64_tr_b4 v[128:129], v57
	s_waitcnt lgkmcnt(7)
	v_dot8c_i32_i4_e32 v38, v130, v52
	v_dot8c_i32_i4_e32 v39, v130, v50
	v_dot8c_i32_i4_e32 v40, v132, v52
	v_dot8c_i32_i4_e32 v41, v132, v50
	v_dot8c_i32_i4_e32 v42, v134, v52
	v_dot8c_i32_i4_e32 v43, v134, v50
	v_dot8c_i32_i4_e32 v44, v136, v52
	v_dot8c_i32_i4_e32 v45, v136, v50
	v_dot8c_i32_i4_e32 v38, v131, v53
	v_dot8c_i32_i4_e32 v39, v131, v51
	v_dot8c_i32_i4_e32 v40, v133, v53
	v_dot8c_i32_i4_e32 v41, v133, v51
	v_dot8c_i32_i4_e32 v42, v135, v53
	v_dot8c_i32_i4_e32 v43, v135, v51
	v_dot8c_i32_i4_e32 v44, v137, v53
	v_dot8c_i32_i4_e32 v45, v137, v51
	v_and_b32_e32 v78, 0xffff, v21
	v_lshrrev_b32_e32 v79, 16, v21
	v_lshl_add_u32 v78, v78, 7, v152
	v_lshl_add_u32 v79, v79, 7, v153
	s_mov_b32 m0, s77
	s_add_i32 s43, s77, 0x400
	global_load_lds_dwordx4 v78, s[50:51]
	s_mov_b32 m0, s43
	s_nop 0
	global_load_lds_dwordx4 v79, s[50:51]
	s_waitcnt vmcnt(8)
	v_add_u32_e32 v54, s79, v59
	v_add_u32_e32 v55, s79, v60
	v_add_u32_e32 v56, s79, v61
	v_add_u32_e32 v57, s79, v62
	ds_read_b64_tr_b4 v[50:51], v160 offset:896
	ds_read_b64_tr_b4 v[52:53], v160 offset:1920
	ds_read_b64_tr_b4 v[130:131], v54
	ds_read_b64_tr_b4 v[132:133], v55
	ds_read_b64_tr_b4 v[134:135], v56
	ds_read_b64_tr_b4 v[136:137], v57
	s_waitcnt lgkmcnt(6)
	v_dot8c_i32_i4_e32 v38, v122, v48
	v_dot8c_i32_i4_e32 v39, v122, v46
	v_dot8c_i32_i4_e32 v40, v124, v48
	v_dot8c_i32_i4_e32 v41, v124, v46
	v_dot8c_i32_i4_e32 v42, v126, v48
	v_dot8c_i32_i4_e32 v43, v126, v46
	v_dot8c_i32_i4_e32 v44, v128, v48
	v_dot8c_i32_i4_e32 v45, v128, v46
	v_dot8c_i32_i4_e32 v38, v123, v49
	v_dot8c_i32_i4_e32 v39, v123, v47
	v_dot8c_i32_i4_e32 v40, v125, v49
	v_dot8c_i32_i4_e32 v41, v125, v47
	v_dot8c_i32_i4_e32 v42, v127, v49
	v_dot8c_i32_i4_e32 v43, v127, v47
	v_dot8c_i32_i4_e32 v44, v129, v49
	v_dot8c_i32_i4_e32 v45, v129, v47
	v_and_b32_e32 v78, 0xffff, v22
	v_lshrrev_b32_e32 v79, 16, v22
	v_lshl_add_u32 v78, v78, 7, v152
	v_lshl_add_u32 v79, v79, 7, v153
	s_mov_b32 m0, s78
	s_add_i32 s43, s78, 0x400
	global_load_lds_dwordx4 v78, s[50:51]
	s_mov_b32 m0, s43
	s_nop 0
	global_load_lds_dwordx4 v79, s[50:51]
	s_waitcnt vmcnt(8)
	v_add_u32_e32 v54, s98, v59
	v_add_u32_e32 v55, s98, v60
	v_add_u32_e32 v56, s98, v61
	v_add_u32_e32 v57, s98, v62
	ds_read_b64_tr_b4 v[46:47], v160
	ds_read_b64_tr_b4 v[48:49], v160 offset:1024
	ds_read_b64_tr_b4 v[122:123], v54
	ds_read_b64_tr_b4 v[124:125], v55
	ds_read_b64_tr_b4 v[126:127], v56
	ds_read_b64_tr_b4 v[128:129], v57
	s_waitcnt lgkmcnt(6)
	v_dot8c_i32_i4_e32 v38, v130, v52
	v_dot8c_i32_i4_e32 v39, v130, v50
	v_dot8c_i32_i4_e32 v40, v132, v52
	v_dot8c_i32_i4_e32 v41, v132, v50
	v_dot8c_i32_i4_e32 v42, v134, v52
	v_dot8c_i32_i4_e32 v43, v134, v50
	v_dot8c_i32_i4_e32 v44, v136, v52
	v_dot8c_i32_i4_e32 v45, v136, v50
	v_dot8c_i32_i4_e32 v38, v131, v53
	v_dot8c_i32_i4_e32 v39, v131, v51
	v_dot8c_i32_i4_e32 v40, v133, v53
	v_dot8c_i32_i4_e32 v41, v133, v51
	v_dot8c_i32_i4_e32 v42, v135, v53
	v_dot8c_i32_i4_e32 v43, v135, v51
	v_dot8c_i32_i4_e32 v44, v137, v53
	v_dot8c_i32_i4_e32 v45, v137, v51
	s_nop 3
	s_waitcnt lgkmcnt(15)
	v_lshlrev_b32_e32 v38, 5, v38
	v_lshlrev_b32_e32 v39, 1, v39
	v_add3_u32 v38, v39, v229, v38
	v_cvt_f32_i32_e32 v38, v38
	v_mul_f32_e32 v38, v228, v38
	v_lshlrev_b32_e32 v40, 5, v40
	v_lshlrev_b32_e32 v41, 1, v41
	v_add3_u32 v40, v41, v229, v40
	v_cvt_f32_i32_e32 v40, v40
	v_mul_f32_e32 v40, v228, v40
	v_lshlrev_b32_e32 v42, 5, v42
	v_lshlrev_b32_e32 v43, 1, v43
	v_add3_u32 v42, v43, v229, v42
	v_cvt_f32_i32_e32 v42, v42
	v_mul_f32_e32 v42, v228, v42
	v_lshlrev_b32_e32 v44, 5, v44
	v_lshlrev_b32_e32 v45, 1, v45
	v_add3_u32 v44, v45, v229, v44
	v_cvt_f32_i32_e32 v44, v44
	v_mul_f32_e32 v44, v228, v44
	v_cvt_pk_bf16_f32 v190, v38, v40
	v_cvt_pk_bf16_f32 v191, v42, v44
	ds_read_b128 v[252:255], v155 offset:1024
	s_add_i32 s44, s40, 8
	s_ashr_i32 s45, s44, 31
	s_lshl_b64 s[44:45], s[44:45], 12
	v_lshl_add_u64 v[80:81], v[36:37], 0, s[44:45]
	s_waitcnt lgkmcnt(0)
	v_mul_f32_e32 v240, v240, v252
	v_mul_f32_e32 v241, v241, v253
	v_mul_f32_e32 v242, v242, v254
	v_mul_f32_e32 v243, v243, v255
	global_store_dwordx4 v[80:81], v[240:243], off offset:1024 nt
	v_add_u32_e32 v147, 8, v140
	v_and_b32_e32 v146, 15, v147
	v_xor_b32_e32 v146, 8, v146
	v_bfe_u32 v148, v147, 4, 4
	v_mul_lo_u32 v146, v146, s92
	v_mul_lo_u32 v148, v148, s92
	v_mov_b32_e32 v147, v146
	v_mov_b32_e32 v149, v148
	ds_write2st64_b64 v77, v[146:147], v[148:149] offset1:2
	v_add_u32_e32 v138, 0xc00, v74
	ds_read_u8 v139, v138
	v_add_u32_e32 v141, 0xc00, v73
	ds_read_u8 v140, v141
	s_add_i32 s43, s67, 64
	v_mov_b32_e32 v138, s43
	ds_read2st64_b32 v[228:229], v138 offset1:1
	ds_read_b128 v[26:29], v227 offset:6144
	ds_read_b128 v[30:33], v227 offset:6160
	v_mov_b32_e32 v38, 0
	v_mov_b32_e32 v39, 0
	v_mov_b32_e32 v40, 0
	v_mov_b32_e32 v41, 0
	v_mov_b32_e32 v42, 0
	v_mov_b32_e32 v43, 0
	v_mov_b32_e32 v44, 0
	v_mov_b32_e32 v45, 0
	v_and_b32_e32 v78, 0xffff, v23
	v_lshrrev_b32_e32 v79, 16, v23
	v_lshl_add_u32 v78, v78, 7, v152
	v_lshl_add_u32 v79, v79, 7, v153
	s_mov_b32 m0, s79
	s_add_i32 s43, s79, 0x400
	global_load_lds_dwordx4 v78, s[50:51]
	s_mov_b32 m0, s43
	s_nop 0
	global_load_lds_dwordx4 v79, s[50:51]
	s_waitcnt vmcnt(9)
; __device__ __forceinline__ void peer_v_tokens(int j, const LAS unsigned short* EL, const LAS unsigned char* AL  , const LAS float* ASC  , const LAS int* SAL  , ...
;     ...
; #pragma unroll 1
;     for (int it = 0; it < 8; ++it) {
;         const int tl = it * 8 + wave, t = j * 64 + tl;
;         unsigned E[8];
;         { const LAS v4u* ep = (const LAS v4u*)(EL + tl * 128 + 16 * g); const v4u e0 = ep[0], e1 = ep[1];
;           E[0] = e0.x; E[1] = e0.y; E[2] = e0.z; E[3] = e0.w; E[4] = e1.x; E[5] = e1.y; E[6] = e1.z; E[7] = e1.w; }
;         uint2 hv[4]; float4 gv[4];
;         { unsigned ho = (unsigned)t * (D / 4) + (unsigned)lane; asm volatile("" : "+v"(ho)); const uint2* hp = (const uint2*)HB + ho; const float4* gp = (const float4*)fng + lane;
; #pragma unroll
;           for (int jq = 0; jq < 4; ++jq) { hv[jq] = hp[64 * jq]; gv[jq] = gp[64 * jq]; } }
;         VDMA(0, 0); VDMA(1, 1);
; #pragma unroll
;         for (int m = 0; m < 2; ++m) {
;             const int idx = lane + 64 * m, tau = idx >> 4, sr = idx & 15, k = 16 * (sr & 7) + 2 * tau + (sr >> 3);
;             const int aq = (int)*(const LAS signed char*)(AL + tl * 128 + k); const int tq = aq + 8;
;             const unsigned lo = (((unsigned)tq & 15u) ^ 8u) * 0x11111111u, hi = ((unsigned)(tq >> 4) & 15u) * 0x11111111u;
;             typedef unsigned u2v __attribute__((ext_vector_type(2)));
;             u2v l2; l2.x = lo; l2.y = lo; u2v h2; h2.x = hi; h2.y = hi;
;             *(LAS u2v*)(ATL + 8 * idx) = l2; *(LAS u2v*)(ATL + 1024 + 8 * idx) = h2;
;         }
;         const float asc = ASC[tl]; const int sa = SAL[tl];
;         CFENCE();
;         int accH[4], accL[4];
; #pragma unroll
;         for (int st = 0; st < 16; ++st) {
;             const int p = st >> 2, q = st & 3;
;             if (st < 14) VDMA(st + 2, (st + 2) % 3);
;             if (st < 14) asm volatile("s_waitcnt vmcnt(8)" ::: "memory");
;             else if (st == 14) asm volatile("s_waitcnt vmcnt(4)" ::: "memory");
;             else asm volatile("s_waitcnt vmcnt(0)" ::: "memory");
;             if (q == 0) {
; #pragma unroll
;                 for (int r = 0; r < 4; ++r) { accH[r] = 0; accL[r] = 0; } }
; #pragma unroll
;             for (int tp = 0; tp < 2; ++tp) {
;                 const v2i ao = TR4(ATL + (2 * q + tp) * 128 + 8 * s16), ah = TR4(ATL + 1024 + (2 * q + tp) * 128 + 8 * s16);
; #pragma unroll
	v_add_u32_e32 v54, s99, v59
	v_add_u32_e32 v55, s99, v60
	v_add_u32_e32 v56, s99, v61
	v_add_u32_e32 v57, s99, v62
	ds_read_b64_tr_b4 v[50:51], v160 offset:128
	ds_read_b64_tr_b4 v[52:53], v160 offset:1152
	ds_read_b64_tr_b4 v[130:131], v54
	ds_read_b64_tr_b4 v[132:133], v55
	ds_read_b64_tr_b4 v[134:135], v56
	ds_read_b64_tr_b4 v[136:137], v57
	s_waitcnt lgkmcnt(13)
	v_dot8c_i32_i4_e32 v38, v122, v48
	v_dot8c_i32_i4_e32 v39, v122, v46
	v_dot8c_i32_i4_e32 v40, v124, v48
	v_dot8c_i32_i4_e32 v41, v124, v46
	v_dot8c_i32_i4_e32 v42, v126, v48
	v_dot8c_i32_i4_e32 v43, v126, v46
	v_dot8c_i32_i4_e32 v44, v128, v48
	v_dot8c_i32_i4_e32 v45, v128, v46
	v_dot8c_i32_i4_e32 v38, v123, v49
	v_dot8c_i32_i4_e32 v39, v123, v47
	v_dot8c_i32_i4_e32 v40, v125, v49
	v_dot8c_i32_i4_e32 v41, v125, v47
	v_dot8c_i32_i4_e32 v42, v127, v49
	v_dot8c_i32_i4_e32 v43, v127, v47
	v_dot8c_i32_i4_e32 v44, v129, v49
	v_dot8c_i32_i4_e32 v45, v129, v47
	v_and_b32_e32 v78, 0xffff, v24
	v_lshrrev_b32_e32 v79, 16, v24
	v_lshl_add_u32 v78, v78, 7, v152
	v_lshl_add_u32 v79, v79, 7, v153
	s_mov_b32 m0, s98
	s_add_i32 s43, s98, 0x400
	global_load_lds_dwordx4 v78, s[50:51]
	s_mov_b32 m0, s43
	s_nop 0
	global_load_lds_dwordx4 v79, s[50:51]
	s_waitcnt vmcnt(9)
	v_add_u32_e32 v54, s76, v59
	v_add_u32_e32 v55, s76, v60
	v_add_u32_e32 v56, s76, v61
	v_add_u32_e32 v57, s76, v62
	ds_read_b64_tr_b4 v[46:47], v160 offset:256
	ds_read_b64_tr_b4 v[48:49], v160 offset:1280
	ds_read_b64_tr_b4 v[122:123], v54
	ds_read_b64_tr_b4 v[124:125], v55
	ds_read_b64_tr_b4 v[126:127], v56
	ds_read_b64_tr_b4 v[128:129], v57
	s_waitcnt lgkmcnt(6)
	v_dot8c_i32_i4_e32 v38, v130, v52
	v_dot8c_i32_i4_e32 v39, v130, v50
	v_dot8c_i32_i4_e32 v40, v132, v52
	v_dot8c_i32_i4_e32 v41, v132, v50
	v_dot8c_i32_i4_e32 v42, v134, v52
	v_dot8c_i32_i4_e32 v43, v134, v50
	v_dot8c_i32_i4_e32 v44, v136, v52
	v_dot8c_i32_i4_e32 v45, v136, v50
	v_dot8c_i32_i4_e32 v38, v131, v53
	v_dot8c_i32_i4_e32 v39, v131, v51
	v_dot8c_i32_i4_e32 v40, v133, v53
	v_dot8c_i32_i4_e32 v41, v133, v51
	v_dot8c_i32_i4_e32 v42, v135, v53
	v_dot8c_i32_i4_e32 v43, v135, v51
	v_dot8c_i32_i4_e32 v44, v137, v53
	v_dot8c_i32_i4_e32 v45, v137, v51
	v_and_b32_e32 v78, 0xffff, v25
	v_lshrrev_b32_e32 v79, 16, v25
	v_lshl_add_u32 v78, v78, 7, v152
	v_lshl_add_u32 v79, v79, 7, v153
	s_mov_b32 m0, s99
	s_add_i32 s43, s99, 0x400
	global_load_lds_dwordx4 v78, s[50:51]
	s_mov_b32 m0, s43
	s_nop 0
	global_load_lds_dwordx4 v79, s[50:51]
	s_waitcnt vmcnt(9)
	v_add_u32_e32 v54, s77, v59
	v_add_u32_e32 v55, s77, v60
	v_add_u32_e32 v56, s77, v61
	v_add_u32_e32 v57, s77, v62
	ds_read_b64_tr_b4 v[50:51], v160 offset:384
	ds_read_b64_tr_b4 v[52:53], v160 offset:1408
	ds_read_b64_tr_b4 v[130:131], v54
	ds_read_b64_tr_b4 v[132:133], v55
	ds_read_b64_tr_b4 v[134:135], v56
	ds_read_b64_tr_b4 v[136:137], v57
	s_waitcnt lgkmcnt(6)
	v_dot8c_i32_i4_e32 v38, v122, v48
	v_dot8c_i32_i4_e32 v39, v122, v46
	v_dot8c_i32_i4_e32 v40, v124, v48
	v_dot8c_i32_i4_e32 v41, v124, v46
	v_dot8c_i32_i4_e32 v42, v126, v48
	v_dot8c_i32_i4_e32 v43, v126, v46
	v_dot8c_i32_i4_e32 v44, v128, v48
	v_dot8c_i32_i4_e32 v45, v128, v46
	v_dot8c_i32_i4_e32 v38, v123, v49
	v_dot8c_i32_i4_e32 v39, v123, v47
	v_dot8c_i32_i4_e32 v40, v125, v49
	v_dot8c_i32_i4_e32 v41, v125, v47
	v_dot8c_i32_i4_e32 v42, v127, v49
	v_dot8c_i32_i4_e32 v43, v127, v47
	v_dot8c_i32_i4_e32 v44, v129, v49
	v_dot8c_i32_i4_e32 v45, v129, v47
	s_waitcnt lgkmcnt(15)
	v_and_b32_e32 v78, 0xffff, v26
	v_lshrrev_b32_e32 v79, 16, v26
	v_lshl_add_u32 v78, v78, 7, v152
	v_lshl_add_u32 v79, v79, 7, v153
	s_mov_b32 m0, s76
	s_add_i32 s43, s76, 0x400
	global_load_lds_dwordx4 v78, s[50:51]
	s_mov_b32 m0, s43
	s_nop 0
	global_load_lds_dwordx4 v79, s[50:51]
	s_waitcnt vmcnt(9)
	v_add_u32_e32 v54, s78, v59
	v_add_u32_e32 v55, s78, v60
	v_add_u32_e32 v56, s78, v61
	v_add_u32_e32 v57, s78, v62
	ds_read_b64_tr_b4 v[46:47], v160 offset:512
	ds_read_b64_tr_b4 v[48:49], v160 offset:1536
	ds_read_b64_tr_b4 v[122:123], v54
	ds_read_b64_tr_b4 v[124:125], v55
	ds_read_b64_tr_b4 v[126:127], v56
	ds_read_b64_tr_b4 v[128:129], v57
	s_waitcnt lgkmcnt(6)
	v_dot8c_i32_i4_e32 v38, v130, v52
	v_dot8c_i32_i4_e32 v39, v130, v50
	v_dot8c_i32_i4_e32 v40, v132, v52
	v_dot8c_i32_i4_e32 v41, v132, v50
	v_dot8c_i32_i4_e32 v42, v134, v52
	v_dot8c_i32_i4_e32 v43, v134, v50
	v_dot8c_i32_i4_e32 v44, v136, v52
	v_dot8c_i32_i4_e32 v45, v136, v50
	v_dot8c_i32_i4_e32 v38, v131, v53
	v_dot8c_i32_i4_e32 v39, v131, v51
	v_dot8c_i32_i4_e32 v40, v133, v53
	v_dot8c_i32_i4_e32 v41, v133, v51
	v_dot8c_i32_i4_e32 v42, v135, v53
	v_dot8c_i32_i4_e32 v43, v135, v51
	v_dot8c_i32_i4_e32 v44, v137, v53
	v_dot8c_i32_i4_e32 v45, v137, v51
	v_and_b32_e32 v78, 0xffff, v27
	v_lshrrev_b32_e32 v79, 16, v27
	v_lshl_add_u32 v78, v78, 7, v152
	v_lshl_add_u32 v79, v79, 7, v153
	s_mov_b32 m0, s77
	s_add_i32 s43, s77, 0x400
	global_load_lds_dwordx4 v78, s[50:51]
	s_mov_b32 m0, s43
	s_nop 0
	global_load_lds_dwordx4 v79, s[50:51]
	s_waitcnt vmcnt(8)
	v_add_u32_e32 v54, s79, v59
	v_add_u32_e32 v55, s79, v60
	v_add_u32_e32 v56, s79, v61
	v_add_u32_e32 v57, s79, v62
	ds_read_b64_tr_b4 v[50:51], v160 offset:640
	ds_read_b64_tr_b4 v[52:53], v160 offset:1664
	ds_read_b64_tr_b4 v[130:131], v54
	ds_read_b64_tr_b4 v[132:133], v55
	ds_read_b64_tr_b4 v[134:135], v56
	ds_read_b64_tr_b4 v[136:137], v57
	s_waitcnt lgkmcnt(6)
	v_dot8c_i32_i4_e32 v38, v122, v48
	v_dot8c_i32_i4_e32 v39, v122, v46
	v_dot8c_i32_i4_e32 v40, v124, v48
	v_dot8c_i32_i4_e32 v41, v124, v46
	v_dot8c_i32_i4_e32 v42, v126, v48
	v_dot8c_i32_i4_e32 v43, v126, v46
	v_dot8c_i32_i4_e32 v44, v128, v48
	v_dot8c_i32_i4_e32 v45, v128, v46
	v_dot8c_i32_i4_e32 v38, v123, v49
	v_dot8c_i32_i4_e32 v39, v123, v47
	v_dot8c_i32_i4_e32 v40, v125, v49
	v_dot8c_i32_i4_e32 v41, v125, v47
	v_dot8c_i32_i4_e32 v42, v127, v49
	v_dot8c_i32_i4_e32 v43, v127, v47
	v_dot8c_i32_i4_e32 v44, v129, v49
	v_dot8c_i32_i4_e32 v45, v129, v47
	s_waitcnt lgkmcnt(15)
; #define LAS __attribute__((address_space(3)))
; __device__ __forceinline__ void peer_v_tokens(int j, const LAS unsigned short* EL, const LAS unsigned char* AL  , const LAS float* ASC  , const LAS int* SAL  , ...
;     ...
;         for (int m = 0; m < 2; ++m) {
;             const int idx = lane + 64 * m, tau = idx >> 4, sr = idx & 15, k = 16 * (sr & 7) + 2 * tau + (sr >> 3);
;             const int aq = (int)*(const LAS signed char*)(AL + tl * 128 + k); const int tq = aq + 8;
;             const unsigned lo = (((unsigned)tq & 15u) ^ 8u) * 0x11111111u, hi = ((unsigned)(tq >> 4) & 15u) * 0x11111111u;
;             typedef unsigned u2v __attribute__((ext_vector_type(2)));
;             u2v l2; l2.x = lo; l2.y = lo; u2v h2; h2.x = hi; h2.y = hi;
;             *(LAS u2v*)(ATL + 8 * idx) = l2; *(LAS u2v*)(ATL + 1024 + 8 * idx) = h2;
;         }
;     ...
; #pragma unroll
;         for (int st = 0; st < 16; ++st) {
;             const int p = st >> 2, q = st & 3;
;             if (st < 14) VDMA(st + 2, (st + 2) % 3);
;             if (st < 14) asm volatile("s_waitcnt vmcnt(8)" ::: "memory");
;             else if (st == 14) asm volatile("s_waitcnt vmcnt(4)" ::: "memory");
;             else asm volatile("s_waitcnt vmcnt(0)" ::: "memory");
;             if (q == 0) {
; #pragma unroll
;                 for (int r = 0; r < 4; ++r) { accH[r] = 0; accL[r] = 0; } }
; #pragma unroll
;             for (int tp = 0; tp < 2; ++tp) {
;                 const v2i ao = TR4(ATL + (2 * q + tp) * 128 + 8 * s16), ah = TR4(ATL + 1024 + (2 * q + tp) * 128 + 8 * s16);
; #pragma unroll
;                 for (int r = 0; r < 4; ++r) {
;                     const v2i d = TR4(ldsb + BUF[st % 3] + 2048 * tp + roff[r]);
;                     accH[r] = __builtin_amdgcn_sdot8(d.x, ah.x, accH[r], false); accH[r] = __builtin_amdgcn_sdot8(d.y, ah.y, accH[r], false);
;                     accL[r] = __builtin_amdgcn_sdot8(d.x, ao.x, accL[r], false); accL[r] = __builtin_amdgcn_sdot8(d.y, ao.y, accL[r], false);
;                 }
;             }
;             asm volatile("s_waitcnt lgkmcnt(0)" ::: "memory");
;             if (q == 3) {
; #pragma unroll
;                 for (int r = 0; r < 4; ++r) STASH[256 * p + 16 * (grp + 4 * r) + pc] = f2bf(asc * (float)(2 * ((accH[r] << 4) + accL[r]) + sa));
;             }
;         }
;         CFENCE();
;         {
;             float4 v[4]; float ss = 0.f;
; #pragma unroll
	v_add_u32_e32 v143, 8, v139
	v_and_b32_e32 v142, 15, v143
	v_xor_b32_e32 v142, 8, v142
	v_bfe_u32 v144, v143, 4, 4
	v_mul_lo_u32 v142, v142, s92
	v_mul_lo_u32 v144, v144, s92
	v_mov_b32_e32 v143, v142
	v_mov_b32_e32 v145, v144
	ds_write2st64_b64 v159, v[142:143], v[144:145] offset1:2
	v_and_b32_e32 v78, 0xffff, v28
	v_lshrrev_b32_e32 v79, 16, v28
	v_lshl_add_u32 v78, v78, 7, v152
	v_lshl_add_u32 v79, v79, 7, v153
	s_mov_b32 m0, s78
	s_add_i32 s43, s78, 0x400
	global_load_lds_dwordx4 v78, s[50:51]
	s_mov_b32 m0, s43
	s_nop 0
	global_load_lds_dwordx4 v79, s[50:51]
	s_waitcnt vmcnt(8)
	v_add_u32_e32 v54, s98, v59
	v_add_u32_e32 v55, s98, v60
	v_add_u32_e32 v56, s98, v61
	v_add_u32_e32 v57, s98, v62
	ds_read_b64_tr_b4 v[46:47], v160 offset:768
	ds_read_b64_tr_b4 v[48:49], v160 offset:1792
	ds_read_b64_tr_b4 v[122:123], v54
	ds_read_b64_tr_b4 v[124:125], v55
	ds_read_b64_tr_b4 v[126:127], v56
	ds_read_b64_tr_b4 v[128:129], v57
	s_waitcnt lgkmcnt(7)
	v_dot8c_i32_i4_e32 v38, v130, v52
	v_dot8c_i32_i4_e32 v39, v130, v50
	v_dot8c_i32_i4_e32 v40, v132, v52
	v_dot8c_i32_i4_e32 v41, v132, v50
	v_dot8c_i32_i4_e32 v42, v134, v52
	v_dot8c_i32_i4_e32 v43, v134, v50
	v_dot8c_i32_i4_e32 v44, v136, v52
	v_dot8c_i32_i4_e32 v45, v136, v50
	v_dot8c_i32_i4_e32 v38, v131, v53
	v_dot8c_i32_i4_e32 v39, v131, v51
	v_dot8c_i32_i4_e32 v40, v133, v53
	v_dot8c_i32_i4_e32 v41, v133, v51
	v_dot8c_i32_i4_e32 v42, v135, v53
	v_dot8c_i32_i4_e32 v43, v135, v51
	v_dot8c_i32_i4_e32 v44, v137, v53
	v_dot8c_i32_i4_e32 v45, v137, v51
	v_and_b32_e32 v78, 0xffff, v29
	v_lshrrev_b32_e32 v79, 16, v29
	v_lshl_add_u32 v78, v78, 7, v152
	v_lshl_add_u32 v79, v79, 7, v153
	s_mov_b32 m0, s79
	s_add_i32 s43, s79, 0x400
	global_load_lds_dwordx4 v78, s[50:51]
	s_mov_b32 m0, s43
	s_nop 0
	global_load_lds_dwordx4 v79, s[50:51]
	s_waitcnt vmcnt(8)
	v_add_u32_e32 v54, s99, v59
	v_add_u32_e32 v55, s99, v60
	v_add_u32_e32 v56, s99, v61
	v_add_u32_e32 v57, s99, v62
	ds_read_b64_tr_b4 v[50:51], v160 offset:896
	ds_read_b64_tr_b4 v[52:53], v160 offset:1920
	ds_read_b64_tr_b4 v[130:131], v54
	ds_read_b64_tr_b4 v[132:133], v55
	ds_read_b64_tr_b4 v[134:135], v56
	ds_read_b64_tr_b4 v[136:137], v57
	s_waitcnt lgkmcnt(6)
	v_dot8c_i32_i4_e32 v38, v122, v48
	v_dot8c_i32_i4_e32 v39, v122, v46
	v_dot8c_i32_i4_e32 v40, v124, v48
	v_dot8c_i32_i4_e32 v41, v124, v46
	v_dot8c_i32_i4_e32 v42, v126, v48
	v_dot8c_i32_i4_e32 v43, v126, v46
	v_dot8c_i32_i4_e32 v44, v128, v48
	v_dot8c_i32_i4_e32 v45, v128, v46
	v_dot8c_i32_i4_e32 v38, v123, v49
	v_dot8c_i32_i4_e32 v39, v123, v47
	v_dot8c_i32_i4_e32 v40, v125, v49
	v_dot8c_i32_i4_e32 v41, v125, v47
	v_dot8c_i32_i4_e32 v42, v127, v49
	v_dot8c_i32_i4_e32 v43, v127, v47
	v_dot8c_i32_i4_e32 v44, v129, v49
	v_dot8c_i32_i4_e32 v45, v129, v47
	v_and_b32_e32 v78, 0xffff, v30
	v_lshrrev_b32_e32 v79, 16, v30
	v_lshl_add_u32 v78, v78, 7, v152
	v_lshl_add_u32 v79, v79, 7, v153
	s_mov_b32 m0, s98
	s_add_i32 s43, s98, 0x400
	global_load_lds_dwordx4 v78, s[50:51]
	s_mov_b32 m0, s43
	s_nop 0
	global_load_lds_dwordx4 v79, s[50:51]
	s_waitcnt vmcnt(8)
	v_add_u32_e32 v54, s76, v59
	v_add_u32_e32 v55, s76, v60
	v_add_u32_e32 v56, s76, v61
	v_add_u32_e32 v57, s76, v62
	ds_read_b64_tr_b4 v[46:47], v160
	ds_read_b64_tr_b4 v[48:49], v160 offset:1024
	ds_read_b64_tr_b4 v[122:123], v54
	ds_read_b64_tr_b4 v[124:125], v55
	ds_read_b64_tr_b4 v[126:127], v56
	ds_read_b64_tr_b4 v[128:129], v57
	s_waitcnt lgkmcnt(6)
	v_dot8c_i32_i4_e32 v38, v130, v52
	v_dot8c_i32_i4_e32 v39, v130, v50
	v_dot8c_i32_i4_e32 v40, v132, v52
	v_dot8c_i32_i4_e32 v41, v132, v50
	v_dot8c_i32_i4_e32 v42, v134, v52
	v_dot8c_i32_i4_e32 v43, v134, v50
	v_dot8c_i32_i4_e32 v44, v136, v52
	v_dot8c_i32_i4_e32 v45, v136, v50
	v_dot8c_i32_i4_e32 v38, v131, v53
	v_dot8c_i32_i4_e32 v39, v131, v51
	v_dot8c_i32_i4_e32 v40, v133, v53
	v_dot8c_i32_i4_e32 v41, v133, v51
	v_dot8c_i32_i4_e32 v42, v135, v53
	v_dot8c_i32_i4_e32 v43, v135, v51
	v_dot8c_i32_i4_e32 v44, v137, v53
	v_dot8c_i32_i4_e32 v45, v137, v51
	s_nop 3
	s_waitcnt lgkmcnt(15)
	v_lshlrev_b32_e32 v38, 5, v38
	v_lshlrev_b32_e32 v39, 1, v39
	v_add3_u32 v38, v39, v229, v38
	v_cvt_f32_i32_e32 v38, v38
	v_mul_f32_e32 v38, v228, v38
	v_lshlrev_b32_e32 v40, 5, v40
	v_lshlrev_b32_e32 v41, 1, v41
	v_add3_u32 v40, v41, v229, v40
	v_cvt_f32_i32_e32 v40, v40
	v_mul_f32_e32 v40, v228, v40
	v_lshlrev_b32_e32 v42, 5, v42
	v_lshlrev_b32_e32 v43, 1, v43
	v_add3_u32 v42, v43, v229, v42
	v_cvt_f32_i32_e32 v42, v42
	v_mul_f32_e32 v42, v228, v42
	v_lshlrev_b32_e32 v44, 5, v44
	v_lshlrev_b32_e32 v45, 1, v45
	v_add3_u32 v44, v45, v229, v44
	v_cvt_f32_i32_e32 v44, v44
	v_mul_f32_e32 v44, v228, v44
	v_cvt_pk_bf16_f32 v184, v38, v40
	v_cvt_pk_bf16_f32 v185, v42, v44
	ds_read_b128 v[252:255], v156
	s_add_i32 s44, s40, 8
	s_ashr_i32 s45, s44, 31
	s_lshl_b64 s[44:45], s[44:45], 12
	v_lshl_add_u64 v[80:81], v[36:37], 0, s[44:45]
	s_waitcnt lgkmcnt(0)
; __device__ __forceinline__ void peer_v_tokens(int j, const LAS unsigned short* EL, const LAS unsigned char* AL  , const LAS float* ASC  , const LAS int* SAL  , ...
;     ...
; #pragma unroll 1
;     for (int it = 0; it < 8; ++it) {
;         const int tl = it * 8 + wave, t = j * 64 + tl;
;         unsigned E[8];
;         { const LAS v4u* ep = (const LAS v4u*)(EL + tl * 128 + 16 * g); const v4u e0 = ep[0], e1 = ep[1];
;           E[0] = e0.x; E[1] = e0.y; E[2] = e0.z; E[3] = e0.w; E[4] = e1.x; E[5] = e1.y; E[6] = e1.z; E[7] = e1.w; }
;         uint2 hv[4]; float4 gv[4];
;         { unsigned ho = (unsigned)t * (D / 4) + (unsigned)lane; asm volatile("" : "+v"(ho)); const uint2* hp = (const uint2*)HB + ho; const float4* gp = (const float4*)fng + lane;
; #pragma unroll
;           for (int jq = 0; jq < 4; ++jq) { hv[jq] = hp[64 * jq]; gv[jq] = gp[64 * jq]; } }
;         VDMA(0, 0); VDMA(1, 1);
; #pragma unroll
;         for (int m = 0; m < 2; ++m) {
;             const int idx = lane + 64 * m, tau = idx >> 4, sr = idx & 15, k = 16 * (sr & 7) + 2 * tau + (sr >> 3);
;             const int aq = (int)*(const LAS signed char*)(AL + tl * 128 + k); const int tq = aq + 8;
;     ...
;         {
;             float4 v[4]; float ss = 0.f;
; #pragma unroll
;             for (int jq = 0; jq < 4; ++jq) { typedef unsigned u2v __attribute__((ext_vector_type(2))); const u2v pw = *(const LAS u2v*)(STASH + 4 * lane + 256 * jq); const uint2 hw = hv[jq];
;                 v[jq] = make_float4(__uint_as_float(hw.x << 16) + __uint_as_float(pw.x << 16), __uint_as_float(hw.x & 0xffff0000u) + __uint_as_float(pw.x & 0xffff0000u),
;                                     __uint_as_float(hw.y << 16) + __uint_as_float(pw.y << 16), __uint_as_float(hw.y & 0xffff0000u) + __uint_as_float(pw.y & 0xffff0000u));
;                 ss += v[jq].x * v[jq].x + v[jq].y * v[jq].y + v[jq].z * v[jq].z + v[jq].w * v[jq].w; }
;             ss = wave_sum(ss);
;             const float r3 = rsqrtf(ss * (1.f / D) + EPS);
;             float4* op = (float4*)(outp + (size_t)t * D) + lane;
; #pragma unroll
;             for (int jq = 0; jq < 4; ++jq) { typedef float f4v __attribute__((ext_vector_type(4))); f4v o4; o4.x = v[jq].x * r3 * gv[jq].x; o4.y = v[jq].y * r3 * gv[jq].y; o4.z = v[jq].z * r3 * gv[jq].z; o4.w = v[jq].w * r3 * gv[jq].w;
;                 __builtin_nontemporal_store(o4, (f4v*)op + 64 * jq); }
;         }
	v_mul_f32_e32 v244, v244, v252
	v_mul_f32_e32 v245, v245, v253
	v_mul_f32_e32 v246, v246, v254
	v_mul_f32_e32 v247, v247, v255
	global_store_dwordx4 v[80:81], v[244:247], off offset:2048 nt
	s_add_i32 s43, s40, 16
	s_lshl_b32 s43, s43, 11
	v_add_u32_e32 v138, s43, v66
	global_load_dwordx2 v[194:195], v138, s[70:71]
	global_load_dwordx2 v[196:197], v138, s[70:71] offset:512
	global_load_dwordx2 v[198:199], v138, s[70:71] offset:1024
	global_load_dwordx2 v[200:201], v138, s[70:71] offset:1536
	v_add_u32_e32 v147, 8, v140
	v_and_b32_e32 v146, 15, v147
	v_xor_b32_e32 v146, 8, v146
	v_bfe_u32 v148, v147, 4, 4
	v_mul_lo_u32 v146, v146, s92
	v_mul_lo_u32 v148, v148, s92
	v_mov_b32_e32 v147, v146
	v_mov_b32_e32 v149, v148
	ds_write2st64_b64 v77, v[146:147], v[148:149] offset1:2
	v_add_u32_e32 v138, 0x1000, v74
	ds_read_u8 v139, v138
	v_add_u32_e32 v141, 0x1000, v73
	ds_read_u8 v140, v141
	s_add_i32 s43, s67, 96
	v_mov_b32_e32 v138, s43
	ds_read2st64_b32 v[228:229], v138 offset1:1
	ds_read_b128 v[18:21], v227 offset:8192
	ds_read_b128 v[22:25], v227 offset:8208
	v_mov_b32_e32 v150, v63
	v_mov_b32_e32 v151, v64
	v_mov_b32_e32 v38, 0
	v_mov_b32_e32 v39, 0
	v_mov_b32_e32 v40, 0
	v_mov_b32_e32 v41, 0
	v_mov_b32_e32 v42, 0
	v_mov_b32_e32 v43, 0
	v_mov_b32_e32 v44, 0
	v_mov_b32_e32 v45, 0
	v_and_b32_e32 v78, 0xffff, v31
	v_lshrrev_b32_e32 v79, 16, v31
	v_lshl_add_u32 v78, v78, 7, v152
	v_lshl_add_u32 v79, v79, 7, v153
	s_mov_b32 m0, s99
	s_add_i32 s43, s99, 0x400
	global_load_lds_dwordx4 v78, s[50:51]
	s_mov_b32 m0, s43
	s_nop 0
	global_load_lds_dwordx4 v79, s[50:51]
	s_waitcnt vmcnt(13)
	v_add_u32_e32 v54, s77, v59
	v_add_u32_e32 v55, s77, v60
	v_add_u32_e32 v56, s77, v61
	v_add_u32_e32 v57, s77, v62
	ds_read_b64_tr_b4 v[50:51], v160 offset:128
	ds_read_b64_tr_b4 v[52:53], v160 offset:1152
	ds_read_b64_tr_b4 v[130:131], v54
	ds_read_b64_tr_b4 v[132:133], v55
	ds_read_b64_tr_b4 v[134:135], v56
	ds_read_b64_tr_b4 v[136:137], v57
	s_waitcnt lgkmcnt(13)
	v_dot8c_i32_i4_e32 v38, v122, v48
	v_dot8c_i32_i4_e32 v39, v122, v46
	v_dot8c_i32_i4_e32 v40, v124, v48
	v_dot8c_i32_i4_e32 v41, v124, v46
	v_dot8c_i32_i4_e32 v42, v126, v48
	v_dot8c_i32_i4_e32 v43, v126, v46
	v_dot8c_i32_i4_e32 v44, v128, v48
	v_dot8c_i32_i4_e32 v45, v128, v46
	v_dot8c_i32_i4_e32 v38, v123, v49
	v_dot8c_i32_i4_e32 v39, v123, v47
	v_dot8c_i32_i4_e32 v40, v125, v49
	v_dot8c_i32_i4_e32 v41, v125, v47
	v_dot8c_i32_i4_e32 v42, v127, v49
	v_dot8c_i32_i4_e32 v43, v127, v47
	v_dot8c_i32_i4_e32 v44, v129, v49
	v_dot8c_i32_i4_e32 v45, v129, v47
	v_and_b32_e32 v78, 0xffff, v32
	v_lshrrev_b32_e32 v79, 16, v32
	v_lshl_add_u32 v78, v78, 7, v152
	v_lshl_add_u32 v79, v79, 7, v153
	s_mov_b32 m0, s76
	s_add_i32 s43, s76, 0x400
	global_load_lds_dwordx4 v78, s[50:51]
	s_mov_b32 m0, s43
	s_nop 0
	global_load_lds_dwordx4 v79, s[50:51]
	s_waitcnt vmcnt(13)
	v_add_u32_e32 v54, s78, v59
	v_add_u32_e32 v55, s78, v60
	v_add_u32_e32 v56, s78, v61
	v_add_u32_e32 v57, s78, v62
	ds_read_b64_tr_b4 v[46:47], v160 offset:256
	ds_read_b64_tr_b4 v[48:49], v160 offset:1280
	ds_read_b64_tr_b4 v[122:123], v54
	ds_read_b64_tr_b4 v[124:125], v55
	ds_read_b64_tr_b4 v[126:127], v56
	ds_read_b64_tr_b4 v[128:129], v57
	s_waitcnt lgkmcnt(6)
	v_dot8c_i32_i4_e32 v38, v130, v52
	v_dot8c_i32_i4_e32 v39, v130, v50
	v_dot8c_i32_i4_e32 v40, v132, v52
	v_dot8c_i32_i4_e32 v41, v132, v50
	v_dot8c_i32_i4_e32 v42, v134, v52
	v_dot8c_i32_i4_e32 v43, v134, v50
	v_dot8c_i32_i4_e32 v44, v136, v52
	v_dot8c_i32_i4_e32 v45, v136, v50
	v_dot8c_i32_i4_e32 v38, v131, v53
	v_dot8c_i32_i4_e32 v39, v131, v51
	v_dot8c_i32_i4_e32 v40, v133, v53
	v_dot8c_i32_i4_e32 v41, v133, v51
	v_dot8c_i32_i4_e32 v42, v135, v53
	v_dot8c_i32_i4_e32 v43, v135, v51
	v_dot8c_i32_i4_e32 v44, v137, v53
	v_dot8c_i32_i4_e32 v45, v137, v51
	v_and_b32_e32 v78, 0xffff, v33
	v_lshrrev_b32_e32 v79, 16, v33
	v_lshl_add_u32 v78, v78, 7, v152
	v_lshl_add_u32 v79, v79, 7, v153
	s_mov_b32 m0, s77
	s_add_i32 s43, s77, 0x400
	global_load_lds_dwordx4 v78, s[50:51]
	s_mov_b32 m0, s43
	s_nop 0
	global_load_lds_dwordx4 v79, s[50:51]
	s_waitcnt vmcnt(13)
	v_add_u32_e32 v54, s79, v59
	v_add_u32_e32 v55, s79, v60
	v_add_u32_e32 v56, s79, v61
	v_add_u32_e32 v57, s79, v62
	ds_read_b64_tr_b4 v[50:51], v160 offset:384
	ds_read_b64_tr_b4 v[52:53], v160 offset:1408
	ds_read_b64_tr_b4 v[130:131], v54
	ds_read_b64_tr_b4 v[132:133], v55
	ds_read_b64_tr_b4 v[134:135], v56
	ds_read_b64_tr_b4 v[136:137], v57
	s_waitcnt lgkmcnt(6)
	v_dot8c_i32_i4_e32 v38, v122, v48
	v_dot8c_i32_i4_e32 v39, v122, v46
	v_dot8c_i32_i4_e32 v40, v124, v48
	v_dot8c_i32_i4_e32 v41, v124, v46
	v_dot8c_i32_i4_e32 v42, v126, v48
	v_dot8c_i32_i4_e32 v43, v126, v46
	v_dot8c_i32_i4_e32 v44, v128, v48
	v_dot8c_i32_i4_e32 v45, v128, v46
	v_dot8c_i32_i4_e32 v38, v123, v49
	v_dot8c_i32_i4_e32 v39, v123, v47
	v_dot8c_i32_i4_e32 v40, v125, v49
	v_dot8c_i32_i4_e32 v41, v125, v47
	v_dot8c_i32_i4_e32 v42, v127, v49
	v_dot8c_i32_i4_e32 v43, v127, v47
	v_dot8c_i32_i4_e32 v44, v129, v49
	v_dot8c_i32_i4_e32 v45, v129, v47
	s_waitcnt lgkmcnt(15)
	v_and_b32_e32 v78, 0xffff, v18
	v_lshrrev_b32_e32 v79, 16, v18
	v_lshl_add_u32 v78, v78, 7, v150
	v_lshl_add_u32 v79, v79, 7, v151
	s_mov_b32 m0, s78
	s_add_i32 s43, s78, 0x400
	global_load_lds_dwordx4 v78, s[50:51]
	s_mov_b32 m0, s43
	s_nop 0
	global_load_lds_dwordx4 v79, s[50:51]
	s_waitcnt vmcnt(13)
	v_add_u32_e32 v54, s98, v59
	v_add_u32_e32 v55, s98, v60
	v_add_u32_e32 v56, s98, v61
	v_add_u32_e32 v57, s98, v62
	ds_read_b64_tr_b4 v[46:47], v160 offset:512
	ds_read_b64_tr_b4 v[48:49], v160 offset:1536
	ds_read_b64_tr_b4 v[122:123], v54
	ds_read_b64_tr_b4 v[124:125], v55
	ds_read_b64_tr_b4 v[126:127], v56
	ds_read_b64_tr_b4 v[128:129], v57
	s_waitcnt lgkmcnt(6)
; __device__ __forceinline__ void peer_v_tokens(int j, const LAS unsigned short* EL, const LAS unsigned char* AL  , const LAS float* ASC  , const LAS int* SAL  , ...
;     ...
; #pragma unroll 1
;     for (int it = 0; it < 8; ++it) {
;         const int tl = it * 8 + wave, t = j * 64 + tl;
;         unsigned E[8];
;         { const LAS v4u* ep = (const LAS v4u*)(EL + tl * 128 + 16 * g); const v4u e0 = ep[0], e1 = ep[1];
;           E[0] = e0.x; E[1] = e0.y; E[2] = e0.z; E[3] = e0.w; E[4] = e1.x; E[5] = e1.y; E[6] = e1.z; E[7] = e1.w; }
;         uint2 hv[4]; float4 gv[4];
;         { unsigned ho = (unsigned)t * (D / 4) + (unsigned)lane; asm volatile("" : "+v"(ho)); const uint2* hp = (const uint2*)HB + ho; const float4* gp = (const float4*)fng + lane;
; #pragma unroll
;           for (int jq = 0; jq < 4; ++jq) { hv[jq] = hp[64 * jq]; gv[jq] = gp[64 * jq]; } }
;         VDMA(0, 0); VDMA(1, 1);
; #pragma unroll
;         for (int m = 0; m < 2; ++m) {
;             const int idx = lane + 64 * m, tau = idx >> 4, sr = idx & 15, k = 16 * (sr & 7) + 2 * tau + (sr >> 3);
;             const int aq = (int)*(const LAS signed char*)(AL + tl * 128 + k); const int tq = aq + 8;
;             const unsigned lo = (((unsigned)tq & 15u) ^ 8u) * 0x11111111u, hi = ((unsigned)(tq >> 4) & 15u) * 0x11111111u;
;             typedef unsigned u2v __attribute__((ext_vector_type(2)));
;             u2v l2; l2.x = lo; l2.y = lo; u2v h2; h2.x = hi; h2.y = hi;
;             *(LAS u2v*)(ATL + 8 * idx) = l2; *(LAS u2v*)(ATL + 1024 + 8 * idx) = h2;
;         }
;         const float asc = ASC[tl]; const int sa = SAL[tl];
;         CFENCE();
;         int accH[4], accL[4];
; #pragma unroll
;         for (int st = 0; st < 16; ++st) {
;             const int p = st >> 2, q = st & 3;
;             if (st < 14) VDMA(st + 2, (st + 2) % 3);
;             if (st < 14) asm volatile("s_waitcnt vmcnt(8)" ::: "memory");
;             else if (st == 14) asm volatile("s_waitcnt vmcnt(4)" ::: "memory");
;             else asm volatile("s_waitcnt vmcnt(0)" ::: "memory");
;             if (q == 0) {
; #pragma unroll
;                 for (int r = 0; r < 4; ++r) { accH[r] = 0; accL[r] = 0; } }
; #pragma unroll
;             for (int tp = 0; tp < 2; ++tp) {
;                 const v2i ao = TR4(ATL + (2 * q + tp) * 128 + 8 * s16), ah = TR4(ATL + 1024 + (2 * q + tp) * 128 + 8 * s16);
; #pragma unroll
	v_dot8c_i32_i4_e32 v38, v130, v52
	v_dot8c_i32_i4_e32 v39, v130, v50
	v_dot8c_i32_i4_e32 v40, v132, v52
	v_dot8c_i32_i4_e32 v41, v132, v50
	v_dot8c_i32_i4_e32 v42, v134, v52
	v_dot8c_i32_i4_e32 v43, v134, v50
	v_dot8c_i32_i4_e32 v44, v136, v52
	v_dot8c_i32_i4_e32 v45, v136, v50
	v_dot8c_i32_i4_e32 v38, v131, v53
	v_dot8c_i32_i4_e32 v39, v131, v51
	v_dot8c_i32_i4_e32 v40, v133, v53
	v_dot8c_i32_i4_e32 v41, v133, v51
	v_dot8c_i32_i4_e32 v42, v135, v53
	v_dot8c_i32_i4_e32 v43, v135, v51
	v_dot8c_i32_i4_e32 v44, v137, v53
	v_dot8c_i32_i4_e32 v45, v137, v51
	v_and_b32_e32 v78, 0xffff, v19
	v_lshrrev_b32_e32 v79, 16, v19
	v_lshl_add_u32 v78, v78, 7, v150
	v_lshl_add_u32 v79, v79, 7, v151
	s_mov_b32 m0, s79
	s_add_i32 s43, s79, 0x400
	global_load_lds_dwordx4 v78, s[50:51]
	s_mov_b32 m0, s43
	s_nop 0
	global_load_lds_dwordx4 v79, s[50:51]
	s_waitcnt vmcnt(8)
	v_add_u32_e32 v54, s99, v59
	v_add_u32_e32 v55, s99, v60
	v_add_u32_e32 v56, s99, v61
	v_add_u32_e32 v57, s99, v62
	ds_read_b64_tr_b4 v[50:51], v160 offset:640
	ds_read_b64_tr_b4 v[52:53], v160 offset:1664
	ds_read_b64_tr_b4 v[130:131], v54
	ds_read_b64_tr_b4 v[132:133], v55
	ds_read_b64_tr_b4 v[134:135], v56
	ds_read_b64_tr_b4 v[136:137], v57
	s_waitcnt lgkmcnt(6)
	v_dot8c_i32_i4_e32 v38, v122, v48
	v_dot8c_i32_i4_e32 v39, v122, v46
	v_dot8c_i32_i4_e32 v40, v124, v48
	v_dot8c_i32_i4_e32 v41, v124, v46
	v_dot8c_i32_i4_e32 v42, v126, v48
	v_dot8c_i32_i4_e32 v43, v126, v46
	v_dot8c_i32_i4_e32 v44, v128, v48
	v_dot8c_i32_i4_e32 v45, v128, v46
	v_dot8c_i32_i4_e32 v38, v123, v49
	v_dot8c_i32_i4_e32 v39, v123, v47
	v_dot8c_i32_i4_e32 v40, v125, v49
	v_dot8c_i32_i4_e32 v41, v125, v47
	v_dot8c_i32_i4_e32 v42, v127, v49
	v_dot8c_i32_i4_e32 v43, v127, v47
	v_dot8c_i32_i4_e32 v44, v129, v49
	v_dot8c_i32_i4_e32 v45, v129, v47
	s_waitcnt lgkmcnt(15)
	v_add_u32_e32 v143, 8, v139
	v_and_b32_e32 v142, 15, v143
	v_xor_b32_e32 v142, 8, v142
	v_bfe_u32 v144, v143, 4, 4
	v_mul_lo_u32 v142, v142, s92
	v_mul_lo_u32 v144, v144, s92
	v_mov_b32_e32 v143, v142
	v_mov_b32_e32 v145, v144
	ds_write2st64_b64 v159, v[142:143], v[144:145] offset1:2
	v_and_b32_e32 v78, 0xffff, v20
	v_lshrrev_b32_e32 v79, 16, v20
	v_lshl_add_u32 v78, v78, 7, v150
	v_lshl_add_u32 v79, v79, 7, v151
	s_mov_b32 m0, s98
	s_add_i32 s43, s98, 0x400
	global_load_lds_dwordx4 v78, s[50:51]
	s_mov_b32 m0, s43
	s_nop 0
	global_load_lds_dwordx4 v79, s[50:51]
	s_waitcnt vmcnt(8)
	v_add_u32_e32 v54, s76, v59
	v_add_u32_e32 v55, s76, v60
	v_add_u32_e32 v56, s76, v61
	v_add_u32_e32 v57, s76, v62
	ds_read_b64_tr_b4 v[46:47], v160 offset:768
	ds_read_b64_tr_b4 v[48:49], v160 offset:1792
	ds_read_b64_tr_b4 v[122:123], v54
	ds_read_b64_tr_b4 v[124:125], v55
	ds_read_b64_tr_b4 v[126:127], v56
	ds_read_b64_tr_b4 v[128:129], v57
	s_waitcnt lgkmcnt(7)
	v_dot8c_i32_i4_e32 v38, v130, v52
	v_dot8c_i32_i4_e32 v39, v130, v50
	v_dot8c_i32_i4_e32 v40, v132, v52
	v_dot8c_i32_i4_e32 v41, v132, v50
	v_dot8c_i32_i4_e32 v42, v134, v52
	v_dot8c_i32_i4_e32 v43, v134, v50
	v_dot8c_i32_i4_e32 v44, v136, v52
	v_dot8c_i32_i4_e32 v45, v136, v50
	v_dot8c_i32_i4_e32 v38, v131, v53
	v_dot8c_i32_i4_e32 v39, v131, v51
	v_dot8c_i32_i4_e32 v40, v133, v53
	v_dot8c_i32_i4_e32 v41, v133, v51
	v_dot8c_i32_i4_e32 v42, v135, v53
	v_dot8c_i32_i4_e32 v43, v135, v51
	v_dot8c_i32_i4_e32 v44, v137, v53
	v_dot8c_i32_i4_e32 v45, v137, v51
	v_and_b32_e32 v78, 0xffff, v21
	v_lshrrev_b32_e32 v79, 16, v21
	v_lshl_add_u32 v78, v78, 7, v150
	v_lshl_add_u32 v79, v79, 7, v151
	s_mov_b32 m0, s99
	s_add_i32 s43, s99, 0x400
	global_load_lds_dwordx4 v78, s[50:51]
	s_mov_b32 m0, s43
	s_nop 0
	global_load_lds_dwordx4 v79, s[50:51]
	s_waitcnt vmcnt(8)
	v_add_u32_e32 v54, s77, v59
	v_add_u32_e32 v55, s77, v60
	v_add_u32_e32 v56, s77, v61
	v_add_u32_e32 v57, s77, v62
	ds_read_b64_tr_b4 v[50:51], v160 offset:896
	ds_read_b64_tr_b4 v[52:53], v160 offset:1920
	ds_read_b64_tr_b4 v[130:131], v54
	ds_read_b64_tr_b4 v[132:133], v55
	ds_read_b64_tr_b4 v[134:135], v56
	ds_read_b64_tr_b4 v[136:137], v57
	s_waitcnt lgkmcnt(6)
	v_dot8c_i32_i4_e32 v38, v122, v48
	v_dot8c_i32_i4_e32 v39, v122, v46
	v_dot8c_i32_i4_e32 v40, v124, v48
	v_dot8c_i32_i4_e32 v41, v124, v46
	v_dot8c_i32_i4_e32 v42, v126, v48
	v_dot8c_i32_i4_e32 v43, v126, v46
	v_dot8c_i32_i4_e32 v44, v128, v48
	v_dot8c_i32_i4_e32 v45, v128, v46
	v_dot8c_i32_i4_e32 v38, v123, v49
	v_dot8c_i32_i4_e32 v39, v123, v47
	v_dot8c_i32_i4_e32 v40, v125, v49
	v_dot8c_i32_i4_e32 v41, v125, v47
	v_dot8c_i32_i4_e32 v42, v127, v49
	v_dot8c_i32_i4_e32 v43, v127, v47
	v_dot8c_i32_i4_e32 v44, v129, v49
	v_dot8c_i32_i4_e32 v45, v129, v47
	v_and_b32_e32 v78, 0xffff, v22
	v_lshrrev_b32_e32 v79, 16, v22
	v_lshl_add_u32 v78, v78, 7, v150
	v_lshl_add_u32 v79, v79, 7, v151
	s_mov_b32 m0, s76
	s_add_i32 s43, s76, 0x400
	global_load_lds_dwordx4 v78, s[50:51]
	s_mov_b32 m0, s43
	s_nop 0
	global_load_lds_dwordx4 v79, s[50:51]
	s_waitcnt vmcnt(8)
	v_add_u32_e32 v54, s78, v59
	v_add_u32_e32 v55, s78, v60
	v_add_u32_e32 v56, s78, v61
	v_add_u32_e32 v57, s78, v62
	ds_read_b64_tr_b4 v[46:47], v160
	ds_read_b64_tr_b4 v[48:49], v160 offset:1024
	ds_read_b64_tr_b4 v[122:123], v54
	ds_read_b64_tr_b4 v[124:125], v55
	ds_read_b64_tr_b4 v[126:127], v56
	ds_read_b64_tr_b4 v[128:129], v57
	s_waitcnt lgkmcnt(6)
	v_dot8c_i32_i4_e32 v38, v130, v52
	v_dot8c_i32_i4_e32 v39, v130, v50
	v_dot8c_i32_i4_e32 v40, v132, v52
	v_dot8c_i32_i4_e32 v41, v132, v50
	v_dot8c_i32_i4_e32 v42, v134, v52
	v_dot8c_i32_i4_e32 v43, v134, v50
	v_dot8c_i32_i4_e32 v44, v136, v52
	v_dot8c_i32_i4_e32 v45, v136, v50
	v_dot8c_i32_i4_e32 v38, v131, v53
	v_dot8c_i32_i4_e32 v39, v131, v51
	v_dot8c_i32_i4_e32 v40, v133, v53
	v_dot8c_i32_i4_e32 v41, v133, v51
	v_dot8c_i32_i4_e32 v42, v135, v53
	v_dot8c_i32_i4_e32 v43, v135, v51
	v_dot8c_i32_i4_e32 v44, v137, v53
	v_dot8c_i32_i4_e32 v45, v137, v51
	s_nop 3
	s_waitcnt lgkmcnt(15)
; __device__ __forceinline__ void peer_v_tokens(int j, const LAS unsigned short* EL, const LAS unsigned char* AL  , const LAS float* ASC  , const LAS int* SAL  , ...
;     ...
; #pragma unroll
;         for (int st = 0; st < 16; ++st) {
;             const int p = st >> 2, q = st & 3;
;             if (st < 14) VDMA(st + 2, (st + 2) % 3);
;             if (st < 14) asm volatile("s_waitcnt vmcnt(8)" ::: "memory");
;             else if (st == 14) asm volatile("s_waitcnt vmcnt(4)" ::: "memory");
;             else asm volatile("s_waitcnt vmcnt(0)" ::: "memory");
;             if (q == 0) {
; #pragma unroll
;                 for (int r = 0; r < 4; ++r) { accH[r] = 0; accL[r] = 0; } }
; #pragma unroll
;             for (int tp = 0; tp < 2; ++tp) {
;                 const v2i ao = TR4(ATL + (2 * q + tp) * 128 + 8 * s16), ah = TR4(ATL + 1024 + (2 * q + tp) * 128 + 8 * s16);
; #pragma unroll
;                 for (int r = 0; r < 4; ++r) {
;                     const v2i d = TR4(ldsb + BUF[st % 3] + 2048 * tp + roff[r]);
;                     accH[r] = __builtin_amdgcn_sdot8(d.x, ah.x, accH[r], false); accH[r] = __builtin_amdgcn_sdot8(d.y, ah.y, accH[r], false);
;                     accL[r] = __builtin_amdgcn_sdot8(d.x, ao.x, accL[r], false); accL[r] = __builtin_amdgcn_sdot8(d.y, ao.y, accL[r], false);
;                 }
;             }
;             asm volatile("s_waitcnt lgkmcnt(0)" ::: "memory");
;             if (q == 3) {
; #pragma unroll
;                 for (int r = 0; r < 4; ++r) STASH[256 * p + 16 * (grp + 4 * r) + pc] = f2bf(asc * (float)(2 * ((accH[r] << 4) + accL[r]) + sa));
;             }
;         }
;     ...
;         {
;             float4 v[4]; float ss = 0.f;
; #pragma unroll
;             for (int jq = 0; jq < 4; ++jq) { typedef unsigned u2v __attribute__((ext_vector_type(2))); const u2v pw = *(const LAS u2v*)(STASH + 4 * lane + 256 * jq); const uint2 hw = hv[jq];
;                 v[jq] = make_float4(__uint_as_float(hw.x << 16) + __uint_as_float(pw.x << 16), __uint_as_float(hw.x & 0xffff0000u) + __uint_as_float(pw.x & 0xffff0000u),
;                                     __uint_as_float(hw.y << 16) + __uint_as_float(pw.y << 16), __uint_as_float(hw.y & 0xffff0000u) + __uint_as_float(pw.y & 0xffff0000u));
;                 ss += v[jq].x * v[jq].x + v[jq].y * v[jq].y + v[jq].z * v[jq].z + v[jq].w * v[jq].w; }
;             ss = wave_sum(ss);
	v_lshlrev_b32_e32 v38, 5, v38
	v_lshlrev_b32_e32 v39, 1, v39
	v_add3_u32 v38, v39, v229, v38
	v_cvt_f32_i32_e32 v38, v38
	v_mul_f32_e32 v38, v228, v38
	v_lshlrev_b32_e32 v40, 5, v40
	v_lshlrev_b32_e32 v41, 1, v41
	v_add3_u32 v40, v41, v229, v40
	v_cvt_f32_i32_e32 v40, v40
	v_mul_f32_e32 v40, v228, v40
	v_lshlrev_b32_e32 v42, 5, v42
	v_lshlrev_b32_e32 v43, 1, v43
	v_add3_u32 v42, v43, v229, v42
	v_cvt_f32_i32_e32 v42, v42
	v_mul_f32_e32 v42, v228, v42
	v_lshlrev_b32_e32 v44, 5, v44
	v_lshlrev_b32_e32 v45, 1, v45
	v_add3_u32 v44, v45, v229, v44
	v_cvt_f32_i32_e32 v44, v44
	v_mul_f32_e32 v44, v228, v44
	v_cvt_pk_bf16_f32 v192, v38, v40
	v_cvt_pk_bf16_f32 v193, v42, v44
	ds_read_b128 v[252:255], v156 offset:1024
	s_add_i32 s44, s40, 8
	s_ashr_i32 s45, s44, 31
	s_lshl_b64 s[44:45], s[44:45], 12
	v_lshl_add_u64 v[80:81], v[36:37], 0, s[44:45]
	s_waitcnt lgkmcnt(0)
	v_mul_f32_e32 v248, v248, v252
	v_mul_f32_e32 v249, v249, v253
	v_mul_f32_e32 v250, v250, v254
	v_mul_f32_e32 v251, v251, v255
	global_store_dwordx4 v[80:81], v[248:251], off offset:3072 nt
	v_add_u32_e32 v147, 8, v140
	v_and_b32_e32 v146, 15, v147
	v_xor_b32_e32 v146, 8, v146
	v_bfe_u32 v148, v147, 4, 4
	v_mul_lo_u32 v146, v146, s92
	v_mul_lo_u32 v148, v148, s92
	v_mov_b32_e32 v147, v146
	v_mov_b32_e32 v149, v148
	ds_write2st64_b64 v77, v[146:147], v[148:149] offset1:2
	v_add_u32_e32 v138, 0x1400, v74
	ds_read_u8 v139, v138
	v_add_u32_e32 v141, 0x1400, v73
	ds_read_u8 v140, v141
	s_add_i32 s43, s67, 128
	v_mov_b32_e32 v138, s43
	ds_read2st64_b32 v[228:229], v138 offset1:1
	ds_read_b128 v[26:29], v227 offset:10240
	ds_read_b128 v[30:33], v227 offset:10256
	v_mov_b32_e32 v38, 0
	v_mov_b32_e32 v39, 0
	v_mov_b32_e32 v40, 0
	v_mov_b32_e32 v41, 0
	v_mov_b32_e32 v42, 0
	v_mov_b32_e32 v43, 0
	v_mov_b32_e32 v44, 0
	v_mov_b32_e32 v45, 0
	v_and_b32_e32 v78, 0xffff, v23
	v_lshrrev_b32_e32 v79, 16, v23
	v_lshl_add_u32 v78, v78, 7, v150
	v_lshl_add_u32 v79, v79, 7, v151
	s_mov_b32 m0, s77
	s_add_i32 s43, s77, 0x400
	global_load_lds_dwordx4 v78, s[50:51]
	s_mov_b32 m0, s43
	s_nop 0
	global_load_lds_dwordx4 v79, s[50:51]
	s_waitcnt vmcnt(9)
	v_add_u32_e32 v54, s79, v59
	v_add_u32_e32 v55, s79, v60
	v_add_u32_e32 v56, s79, v61
	v_add_u32_e32 v57, s79, v62
	ds_read_b64_tr_b4 v[50:51], v160 offset:128
	ds_read_b64_tr_b4 v[52:53], v160 offset:1152
	ds_read_b64_tr_b4 v[130:131], v54
	ds_read_b64_tr_b4 v[132:133], v55
	ds_read_b64_tr_b4 v[134:135], v56
	ds_read_b64_tr_b4 v[136:137], v57
	s_waitcnt lgkmcnt(13)
	v_dot8c_i32_i4_e32 v38, v122, v48
	v_dot8c_i32_i4_e32 v39, v122, v46
	v_dot8c_i32_i4_e32 v40, v124, v48
	v_dot8c_i32_i4_e32 v41, v124, v46
	v_dot8c_i32_i4_e32 v42, v126, v48
	v_dot8c_i32_i4_e32 v43, v126, v46
	v_dot8c_i32_i4_e32 v44, v128, v48
	v_dot8c_i32_i4_e32 v45, v128, v46
	v_dot8c_i32_i4_e32 v38, v123, v49
	v_dot8c_i32_i4_e32 v39, v123, v47
	v_dot8c_i32_i4_e32 v40, v125, v49
	v_dot8c_i32_i4_e32 v41, v125, v47
	v_dot8c_i32_i4_e32 v42, v127, v49
	v_dot8c_i32_i4_e32 v43, v127, v47
	v_dot8c_i32_i4_e32 v44, v129, v49
	v_dot8c_i32_i4_e32 v45, v129, v47
	v_and_b32_e32 v78, 0xffff, v24
	v_lshrrev_b32_e32 v79, 16, v24
	v_lshl_add_u32 v78, v78, 7, v150
	v_lshl_add_u32 v79, v79, 7, v151
	s_mov_b32 m0, s78
	s_add_i32 s43, s78, 0x400
	global_load_lds_dwordx4 v78, s[50:51]
	s_mov_b32 m0, s43
	s_nop 0
	global_load_lds_dwordx4 v79, s[50:51]
	s_waitcnt vmcnt(9)
	v_add_u32_e32 v54, s98, v59
	v_add_u32_e32 v55, s98, v60
	v_add_u32_e32 v56, s98, v61
	v_add_u32_e32 v57, s98, v62
	ds_read_b64_tr_b4 v[46:47], v160 offset:256
	ds_read_b64_tr_b4 v[48:49], v160 offset:1280
	ds_read_b64_tr_b4 v[122:123], v54
	ds_read_b64_tr_b4 v[124:125], v55
	ds_read_b64_tr_b4 v[126:127], v56
	ds_read_b64_tr_b4 v[128:129], v57
	s_waitcnt lgkmcnt(6)
	v_dot8c_i32_i4_e32 v38, v130, v52
	v_dot8c_i32_i4_e32 v39, v130, v50
	v_dot8c_i32_i4_e32 v40, v132, v52
	v_dot8c_i32_i4_e32 v41, v132, v50
	v_dot8c_i32_i4_e32 v42, v134, v52
	v_dot8c_i32_i4_e32 v43, v134, v50
	v_dot8c_i32_i4_e32 v44, v136, v52
	v_dot8c_i32_i4_e32 v45, v136, v50
	v_dot8c_i32_i4_e32 v38, v131, v53
	v_dot8c_i32_i4_e32 v39, v131, v51
	v_dot8c_i32_i4_e32 v40, v133, v53
	v_dot8c_i32_i4_e32 v41, v133, v51
	v_dot8c_i32_i4_e32 v42, v135, v53
	v_dot8c_i32_i4_e32 v43, v135, v51
	v_dot8c_i32_i4_e32 v44, v137, v53
	v_dot8c_i32_i4_e32 v45, v137, v51
	ds_write_b16 v65, v178
	ds_write_b16_d16_hi v65, v178 offset:128
	ds_write_b16 v65, v179 offset:256
	ds_write_b16_d16_hi v65, v179 offset:384
	ds_write_b16 v65, v180 offset:512
	ds_write_b16_d16_hi v65, v180 offset:640
	ds_write_b16 v65, v181 offset:768
	ds_write_b16_d16_hi v65, v181 offset:896
	ds_write_b16 v65, v182 offset:1024
	ds_write_b16_d16_hi v65, v182 offset:1152
	ds_write_b16 v65, v183 offset:1280
	ds_write_b16_d16_hi v65, v183 offset:1408
	ds_write_b16 v65, v184 offset:1536
	ds_write_b16_d16_hi v65, v184 offset:1664
	ds_write_b16 v65, v185 offset:1792
	ds_write_b16_d16_hi v65, v185 offset:1920
	ds_read_b64 v[202:203], v154
	ds_read_b64 v[204:205], v154 offset:512
	ds_read_b64 v[206:207], v154 offset:1024
	ds_read_b64 v[208:209], v154 offset:1536
	v_and_b32_e32 v78, 0xffff, v25
	v_lshrrev_b32_e32 v79, 16, v25
	v_lshl_add_u32 v78, v78, 7, v150
	v_lshl_add_u32 v79, v79, 7, v151
	s_mov_b32 m0, s79
	s_add_i32 s43, s79, 0x400
	global_load_lds_dwordx4 v78, s[50:51]
	s_mov_b32 m0, s43
	s_nop 0
	global_load_lds_dwordx4 v79, s[50:51]
	s_waitcnt vmcnt(9)
	v_add_u32_e32 v54, s99, v59
	v_add_u32_e32 v55, s99, v60
	v_add_u32_e32 v56, s99, v61
	v_add_u32_e32 v57, s99, v62
	ds_read_b64_tr_b4 v[50:51], v160 offset:384
	ds_read_b64_tr_b4 v[52:53], v160 offset:1408
	ds_read_b64_tr_b4 v[130:131], v54
	ds_read_b64_tr_b4 v[132:133], v55
	ds_read_b64_tr_b4 v[134:135], v56
	ds_read_b64_tr_b4 v[136:137], v57
	s_waitcnt lgkmcnt(15)
; __device__ __forceinline__ void peer_v_tokens(int j, const LAS unsigned short* EL, const LAS unsigned char* AL  , const LAS float* ASC  , const LAS int* SAL  , ...
;     ...
; #pragma unroll 1
;     for (int it = 0; it < 8; ++it) {
;         const int tl = it * 8 + wave, t = j * 64 + tl;
;         unsigned E[8];
;         { const LAS v4u* ep = (const LAS v4u*)(EL + tl * 128 + 16 * g); const v4u e0 = ep[0], e1 = ep[1];
;           E[0] = e0.x; E[1] = e0.y; E[2] = e0.z; E[3] = e0.w; E[4] = e1.x; E[5] = e1.y; E[6] = e1.z; E[7] = e1.w; }
;         uint2 hv[4]; float4 gv[4];
;         { unsigned ho = (unsigned)t * (D / 4) + (unsigned)lane; asm volatile("" : "+v"(ho)); const uint2* hp = (const uint2*)HB + ho; const float4* gp = (const float4*)fng + lane;
; #pragma unroll
;           for (int jq = 0; jq < 4; ++jq) { hv[jq] = hp[64 * jq]; gv[jq] = gp[64 * jq]; } }
;         VDMA(0, 0); VDMA(1, 1);
; #pragma unroll
;         for (int m = 0; m < 2; ++m) {
;             const int idx = lane + 64 * m, tau = idx >> 4, sr = idx & 15, k = 16 * (sr & 7) + 2 * tau + (sr >> 3);
;             const int aq = (int)*(const LAS signed char*)(AL + tl * 128 + k); const int tq = aq + 8;
;             const unsigned lo = (((unsigned)tq & 15u) ^ 8u) * 0x11111111u, hi = ((unsigned)(tq >> 4) & 15u) * 0x11111111u;
;             typedef unsigned u2v __attribute__((ext_vector_type(2)));
;             u2v l2; l2.x = lo; l2.y = lo; u2v h2; h2.x = hi; h2.y = hi;
;             *(LAS u2v*)(ATL + 8 * idx) = l2; *(LAS u2v*)(ATL + 1024 + 8 * idx) = h2;
;         }
;         const float asc = ASC[tl]; const int sa = SAL[tl];
;         CFENCE();
;         int accH[4], accL[4];
; #pragma unroll
;         for (int st = 0; st < 16; ++st) {
;             const int p = st >> 2, q = st & 3;
;             if (st < 14) VDMA(st + 2, (st + 2) % 3);
;             if (st < 14) asm volatile("s_waitcnt vmcnt(8)" ::: "memory");
;             else if (st == 14) asm volatile("s_waitcnt vmcnt(4)" ::: "memory");
;             else asm volatile("s_waitcnt vmcnt(0)" ::: "memory");
;             if (q == 0) {
; #pragma unroll
;                 for (int r = 0; r < 4; ++r) { accH[r] = 0; accL[r] = 0; } }
; #pragma unroll
;             for (int tp = 0; tp < 2; ++tp) {
;                 const v2i ao = TR4(ATL + (2 * q + tp) * 128 + 8 * s16), ah = TR4(ATL + 1024 + (2 * q + tp) * 128 + 8 * s16);
; #pragma unroll
	v_dot8c_i32_i4_e32 v38, v122, v48
	v_dot8c_i32_i4_e32 v39, v122, v46
	v_dot8c_i32_i4_e32 v40, v124, v48
	v_dot8c_i32_i4_e32 v41, v124, v46
	v_dot8c_i32_i4_e32 v42, v126, v48
	v_dot8c_i32_i4_e32 v43, v126, v46
	v_dot8c_i32_i4_e32 v44, v128, v48
	v_dot8c_i32_i4_e32 v45, v128, v46
	v_dot8c_i32_i4_e32 v38, v123, v49
	v_dot8c_i32_i4_e32 v39, v123, v47
	v_dot8c_i32_i4_e32 v40, v125, v49
	v_dot8c_i32_i4_e32 v41, v125, v47
	v_dot8c_i32_i4_e32 v42, v127, v49
	v_dot8c_i32_i4_e32 v43, v127, v47
	v_dot8c_i32_i4_e32 v44, v129, v49
	v_dot8c_i32_i4_e32 v45, v129, v47
	s_waitcnt lgkmcnt(15)
	v_and_b32_e32 v78, 0xffff, v26
	v_lshrrev_b32_e32 v79, 16, v26
	v_lshl_add_u32 v78, v78, 7, v150
	v_lshl_add_u32 v79, v79, 7, v151
	s_mov_b32 m0, s98
	s_add_i32 s43, s98, 0x400
	global_load_lds_dwordx4 v78, s[50:51]
	s_mov_b32 m0, s43
	s_nop 0
	global_load_lds_dwordx4 v79, s[50:51]
	s_waitcnt vmcnt(9)
	v_add_u32_e32 v54, s76, v59
	v_add_u32_e32 v55, s76, v60
	v_add_u32_e32 v56, s76, v61
	v_add_u32_e32 v57, s76, v62
	ds_read_b64_tr_b4 v[46:47], v160 offset:512
	ds_read_b64_tr_b4 v[48:49], v160 offset:1536
	ds_read_b64_tr_b4 v[122:123], v54
	ds_read_b64_tr_b4 v[124:125], v55
	ds_read_b64_tr_b4 v[126:127], v56
	ds_read_b64_tr_b4 v[128:129], v57
	s_waitcnt lgkmcnt(6)
	v_dot8c_i32_i4_e32 v38, v130, v52
	v_dot8c_i32_i4_e32 v39, v130, v50
	v_dot8c_i32_i4_e32 v40, v132, v52
	v_dot8c_i32_i4_e32 v41, v132, v50
	v_dot8c_i32_i4_e32 v42, v134, v52
	v_dot8c_i32_i4_e32 v43, v134, v50
	v_dot8c_i32_i4_e32 v44, v136, v52
	v_dot8c_i32_i4_e32 v45, v136, v50
	v_dot8c_i32_i4_e32 v38, v131, v53
	v_dot8c_i32_i4_e32 v39, v131, v51
	v_dot8c_i32_i4_e32 v40, v133, v53
	v_dot8c_i32_i4_e32 v41, v133, v51
	v_dot8c_i32_i4_e32 v42, v135, v53
	v_dot8c_i32_i4_e32 v43, v135, v51
	v_dot8c_i32_i4_e32 v44, v137, v53
	v_dot8c_i32_i4_e32 v45, v137, v51
	v_and_b32_e32 v78, 0xffff, v27
	v_lshrrev_b32_e32 v79, 16, v27
	v_lshl_add_u32 v78, v78, 7, v150
	v_lshl_add_u32 v79, v79, 7, v151
	s_mov_b32 m0, s99
	s_add_i32 s43, s99, 0x400
	global_load_lds_dwordx4 v78, s[50:51]
	s_mov_b32 m0, s43
	s_nop 0
	global_load_lds_dwordx4 v79, s[50:51]
	s_waitcnt vmcnt(8)
	v_add_u32_e32 v54, s77, v59
	v_add_u32_e32 v55, s77, v60
	v_add_u32_e32 v56, s77, v61
	v_add_u32_e32 v57, s77, v62
	ds_read_b64_tr_b4 v[50:51], v160 offset:640
	ds_read_b64_tr_b4 v[52:53], v160 offset:1664
	ds_read_b64_tr_b4 v[130:131], v54
	ds_read_b64_tr_b4 v[132:133], v55
	ds_read_b64_tr_b4 v[134:135], v56
	ds_read_b64_tr_b4 v[136:137], v57
	s_waitcnt lgkmcnt(6)
	v_dot8c_i32_i4_e32 v38, v122, v48
	v_dot8c_i32_i4_e32 v39, v122, v46
	v_dot8c_i32_i4_e32 v40, v124, v48
	v_dot8c_i32_i4_e32 v41, v124, v46
	v_dot8c_i32_i4_e32 v42, v126, v48
	v_dot8c_i32_i4_e32 v43, v126, v46
	v_dot8c_i32_i4_e32 v44, v128, v48
	v_dot8c_i32_i4_e32 v45, v128, v46
	v_dot8c_i32_i4_e32 v38, v123, v49
	v_dot8c_i32_i4_e32 v39, v123, v47
	v_dot8c_i32_i4_e32 v40, v125, v49
	v_dot8c_i32_i4_e32 v41, v125, v47
	v_dot8c_i32_i4_e32 v42, v127, v49
	v_dot8c_i32_i4_e32 v43, v127, v47
	v_dot8c_i32_i4_e32 v44, v129, v49
	v_dot8c_i32_i4_e32 v45, v129, v47
	s_waitcnt lgkmcnt(15)
	v_add_u32_e32 v143, 8, v139
	v_and_b32_e32 v142, 15, v143
	v_xor_b32_e32 v142, 8, v142
	v_bfe_u32 v144, v143, 4, 4
	v_mul_lo_u32 v142, v142, s92
	v_mul_lo_u32 v144, v144, s92
	v_mov_b32_e32 v143, v142
	v_mov_b32_e32 v145, v144
	ds_write2st64_b64 v159, v[142:143], v[144:145] offset1:2
	v_and_b32_e32 v78, 0xffff, v28
	v_lshrrev_b32_e32 v79, 16, v28
	v_lshl_add_u32 v78, v78, 7, v150
	v_lshl_add_u32 v79, v79, 7, v151
	s_mov_b32 m0, s76
	s_add_i32 s43, s76, 0x400
	global_load_lds_dwordx4 v78, s[50:51]
	s_mov_b32 m0, s43
	s_nop 0
	global_load_lds_dwordx4 v79, s[50:51]
	s_waitcnt vmcnt(8)
	v_add_u32_e32 v54, s78, v59
	v_add_u32_e32 v55, s78, v60
	v_add_u32_e32 v56, s78, v61
	v_add_u32_e32 v57, s78, v62
	ds_read_b64_tr_b4 v[46:47], v160 offset:768
	ds_read_b64_tr_b4 v[48:49], v160 offset:1792
	ds_read_b64_tr_b4 v[122:123], v54
	ds_read_b64_tr_b4 v[124:125], v55
	ds_read_b64_tr_b4 v[126:127], v56
	ds_read_b64_tr_b4 v[128:129], v57
	s_waitcnt lgkmcnt(7)
	v_dot8c_i32_i4_e32 v38, v130, v52
	v_dot8c_i32_i4_e32 v39, v130, v50
	v_dot8c_i32_i4_e32 v40, v132, v52
	v_dot8c_i32_i4_e32 v41, v132, v50
	v_dot8c_i32_i4_e32 v42, v134, v52
	v_dot8c_i32_i4_e32 v43, v134, v50
	v_dot8c_i32_i4_e32 v44, v136, v52
	v_dot8c_i32_i4_e32 v45, v136, v50
	v_dot8c_i32_i4_e32 v38, v131, v53
	v_dot8c_i32_i4_e32 v39, v131, v51
	v_dot8c_i32_i4_e32 v40, v133, v53
	v_dot8c_i32_i4_e32 v41, v133, v51
	v_dot8c_i32_i4_e32 v42, v135, v53
	v_dot8c_i32_i4_e32 v43, v135, v51
	v_dot8c_i32_i4_e32 v44, v137, v53
	v_dot8c_i32_i4_e32 v45, v137, v51
	v_and_b32_e32 v78, 0xffff, v29
	v_lshrrev_b32_e32 v79, 16, v29
	v_lshl_add_u32 v78, v78, 7, v150
	v_lshl_add_u32 v79, v79, 7, v151
	s_mov_b32 m0, s77
	s_add_i32 s43, s77, 0x400
	global_load_lds_dwordx4 v78, s[50:51]
	s_mov_b32 m0, s43
	s_nop 0
	global_load_lds_dwordx4 v79, s[50:51]
	s_waitcnt vmcnt(8)
	v_add_u32_e32 v54, s79, v59
	v_add_u32_e32 v55, s79, v60
	v_add_u32_e32 v56, s79, v61
	v_add_u32_e32 v57, s79, v62
	ds_read_b64_tr_b4 v[50:51], v160 offset:896
	ds_read_b64_tr_b4 v[52:53], v160 offset:1920
	ds_read_b64_tr_b4 v[130:131], v54
	ds_read_b64_tr_b4 v[132:133], v55
	ds_read_b64_tr_b4 v[134:135], v56
	ds_read_b64_tr_b4 v[136:137], v57
	s_waitcnt lgkmcnt(6)
; __device__ __forceinline__ void peer_v_tokens(int j, const LAS unsigned short* EL, const LAS unsigned char* AL  , const LAS float* ASC  , const LAS int* SAL  , ...
;     ...
; #pragma unroll
;         for (int st = 0; st < 16; ++st) {
;             const int p = st >> 2, q = st & 3;
;             if (st < 14) VDMA(st + 2, (st + 2) % 3);
;             if (st < 14) asm volatile("s_waitcnt vmcnt(8)" ::: "memory");
;             else if (st == 14) asm volatile("s_waitcnt vmcnt(4)" ::: "memory");
;             else asm volatile("s_waitcnt vmcnt(0)" ::: "memory");
;             if (q == 0) {
; #pragma unroll
;                 for (int r = 0; r < 4; ++r) { accH[r] = 0; accL[r] = 0; } }
; #pragma unroll
;             for (int tp = 0; tp < 2; ++tp) {
;                 const v2i ao = TR4(ATL + (2 * q + tp) * 128 + 8 * s16), ah = TR4(ATL + 1024 + (2 * q + tp) * 128 + 8 * s16);
; #pragma unroll
;                 for (int r = 0; r < 4; ++r) {
;                     const v2i d = TR4(ldsb + BUF[st % 3] + 2048 * tp + roff[r]);
;                     accH[r] = __builtin_amdgcn_sdot8(d.x, ah.x, accH[r], false); accH[r] = __builtin_amdgcn_sdot8(d.y, ah.y, accH[r], false);
;                     accL[r] = __builtin_amdgcn_sdot8(d.x, ao.x, accL[r], false); accL[r] = __builtin_amdgcn_sdot8(d.y, ao.y, accL[r], false);
;                 }
;             }
;             asm volatile("s_waitcnt lgkmcnt(0)" ::: "memory");
;             if (q == 3) {
; #pragma unroll
;                 for (int r = 0; r < 4; ++r) STASH[256 * p + 16 * (grp + 4 * r) + pc] = f2bf(asc * (float)(2 * ((accH[r] << 4) + accL[r]) + sa));
;             }
;         }
;     ...
;         {
;             float4 v[4]; float ss = 0.f;
; #pragma unroll
;             for (int jq = 0; jq < 4; ++jq) { typedef unsigned u2v __attribute__((ext_vector_type(2))); const u2v pw = *(const LAS u2v*)(STASH + 4 * lane + 256 * jq); const uint2 hw = hv[jq];
;                 v[jq] = make_float4(__uint_as_float(hw.x << 16) + __uint_as_float(pw.x << 16), __uint_as_float(hw.x & 0xffff0000u) + __uint_as_float(pw.x & 0xffff0000u),
;                                     __uint_as_float(hw.y << 16) + __uint_as_float(pw.y << 16), __uint_as_float(hw.y & 0xffff0000u) + __uint_as_float(pw.y & 0xffff0000u));
;                 ss += v[jq].x * v[jq].x + v[jq].y * v[jq].y + v[jq].z * v[jq].z + v[jq].w * v[jq].w; }
;             ss = wave_sum(ss);
	v_dot8c_i32_i4_e32 v38, v122, v48
	v_dot8c_i32_i4_e32 v39, v122, v46
	v_dot8c_i32_i4_e32 v40, v124, v48
	v_dot8c_i32_i4_e32 v41, v124, v46
	v_dot8c_i32_i4_e32 v42, v126, v48
	v_dot8c_i32_i4_e32 v43, v126, v46
	v_dot8c_i32_i4_e32 v44, v128, v48
	v_dot8c_i32_i4_e32 v45, v128, v46
	v_dot8c_i32_i4_e32 v38, v123, v49
	v_dot8c_i32_i4_e32 v39, v123, v47
	v_dot8c_i32_i4_e32 v40, v125, v49
	v_dot8c_i32_i4_e32 v41, v125, v47
	v_dot8c_i32_i4_e32 v42, v127, v49
	v_dot8c_i32_i4_e32 v43, v127, v47
	v_dot8c_i32_i4_e32 v44, v129, v49
	v_dot8c_i32_i4_e32 v45, v129, v47
	v_and_b32_e32 v78, 0xffff, v30
	v_lshrrev_b32_e32 v79, 16, v30
	v_lshl_add_u32 v78, v78, 7, v150
	v_lshl_add_u32 v79, v79, 7, v151
	s_mov_b32 m0, s78
	s_add_i32 s43, s78, 0x400
	global_load_lds_dwordx4 v78, s[50:51]
	s_mov_b32 m0, s43
	s_nop 0
	global_load_lds_dwordx4 v79, s[50:51]
	s_waitcnt vmcnt(8)
	v_add_u32_e32 v54, s98, v59
	v_add_u32_e32 v55, s98, v60
	v_add_u32_e32 v56, s98, v61
	v_add_u32_e32 v57, s98, v62
	ds_read_b64_tr_b4 v[46:47], v160
	ds_read_b64_tr_b4 v[48:49], v160 offset:1024
	ds_read_b64_tr_b4 v[122:123], v54
	ds_read_b64_tr_b4 v[124:125], v55
	ds_read_b64_tr_b4 v[126:127], v56
	ds_read_b64_tr_b4 v[128:129], v57
	s_waitcnt lgkmcnt(6)
	v_dot8c_i32_i4_e32 v38, v130, v52
	v_dot8c_i32_i4_e32 v39, v130, v50
	v_dot8c_i32_i4_e32 v40, v132, v52
	v_dot8c_i32_i4_e32 v41, v132, v50
	v_dot8c_i32_i4_e32 v42, v134, v52
	v_dot8c_i32_i4_e32 v43, v134, v50
	v_dot8c_i32_i4_e32 v44, v136, v52
	v_dot8c_i32_i4_e32 v45, v136, v50
	v_dot8c_i32_i4_e32 v38, v131, v53
	v_dot8c_i32_i4_e32 v39, v131, v51
	v_dot8c_i32_i4_e32 v40, v133, v53
	v_dot8c_i32_i4_e32 v41, v133, v51
	v_dot8c_i32_i4_e32 v42, v135, v53
	v_dot8c_i32_i4_e32 v43, v135, v51
	v_dot8c_i32_i4_e32 v44, v137, v53
	v_dot8c_i32_i4_e32 v45, v137, v51
	s_nop 3
	s_waitcnt lgkmcnt(15)
	v_lshlrev_b32_e32 v38, 5, v38
	v_lshlrev_b32_e32 v39, 1, v39
	v_add3_u32 v38, v39, v229, v38
	v_cvt_f32_i32_e32 v38, v38
	v_mul_f32_e32 v38, v228, v38
	v_lshlrev_b32_e32 v40, 5, v40
	v_lshlrev_b32_e32 v41, 1, v41
	v_add3_u32 v40, v41, v229, v40
	v_cvt_f32_i32_e32 v40, v40
	v_mul_f32_e32 v40, v228, v40
	v_lshlrev_b32_e32 v42, 5, v42
	v_lshlrev_b32_e32 v43, 1, v43
	v_add3_u32 v42, v43, v229, v42
	v_cvt_f32_i32_e32 v42, v42
	v_mul_f32_e32 v42, v228, v42
	v_lshlrev_b32_e32 v44, 5, v44
	v_lshlrev_b32_e32 v45, 1, v45
	v_add3_u32 v44, v45, v229, v44
	v_cvt_f32_i32_e32 v44, v44
	v_mul_f32_e32 v44, v228, v44
	v_cvt_pk_bf16_f32 v162, v38, v40
	v_cvt_pk_bf16_f32 v163, v42, v44
	v_add_u32_e32 v147, 8, v140
	v_and_b32_e32 v146, 15, v147
	v_xor_b32_e32 v146, 8, v146
	v_bfe_u32 v148, v147, 4, 4
	v_mul_lo_u32 v146, v146, s92
	v_mul_lo_u32 v148, v148, s92
	v_mov_b32_e32 v147, v146
	v_mov_b32_e32 v149, v148
	ds_write2st64_b64 v77, v[146:147], v[148:149] offset1:2
	v_add_u32_e32 v138, 0x1000, v74
	ds_read_u8 v139, v138
	v_add_u32_e32 v141, 0x1000, v73
	ds_read_u8 v140, v141
	s_add_i32 s43, s67, 160
	v_mov_b32_e32 v138, s43
	ds_read2st64_b32 v[228:229], v138 offset1:1
	ds_read_b128 v[18:21], v227 offset:8192
	ds_read_b128 v[22:25], v227 offset:8208
	v_add_u32_e32 v152, 0x200000, v63
	v_add_u32_e32 v153, 0x200000, v64
	v_mov_b32_e32 v38, 0
	v_mov_b32_e32 v39, 0
	v_mov_b32_e32 v40, 0
	v_mov_b32_e32 v41, 0
	v_mov_b32_e32 v42, 0
	v_mov_b32_e32 v43, 0
	v_mov_b32_e32 v44, 0
	v_mov_b32_e32 v45, 0
	v_and_b32_e32 v78, 0xffff, v31
	v_lshrrev_b32_e32 v79, 16, v31
	v_lshl_add_u32 v78, v78, 7, v150
	v_lshl_add_u32 v79, v79, 7, v151
	s_mov_b32 m0, s79
	s_add_i32 s43, s79, 0x400
	global_load_lds_dwordx4 v78, s[50:51]
	s_mov_b32 m0, s43
	s_nop 0
	global_load_lds_dwordx4 v79, s[50:51]
	s_waitcnt vmcnt(8)
	v_add_u32_e32 v54, s99, v59
	v_add_u32_e32 v55, s99, v60
	v_add_u32_e32 v56, s99, v61
	v_add_u32_e32 v57, s99, v62
	ds_read_b64_tr_b4 v[50:51], v160 offset:128
	ds_read_b64_tr_b4 v[52:53], v160 offset:1152
	ds_read_b64_tr_b4 v[130:131], v54
	ds_read_b64_tr_b4 v[132:133], v55
	ds_read_b64_tr_b4 v[134:135], v56
	ds_read_b64_tr_b4 v[136:137], v57
	s_waitcnt lgkmcnt(12)
	s_waitcnt vmcnt(35) lgkmcnt(15)
	v_lshlrev_b32_e32 v210, 16, v194
	v_and_b32_e32 v211, 0xffff0000, v194
	v_lshlrev_b32_e32 v142, 16, v202
	v_and_b32_e32 v143, 0xffff0000, v202
	v_add_f32_e32 v210, v210, v142
	v_add_f32_e32 v211, v211, v143
	v_lshlrev_b32_e32 v212, 16, v195
	v_and_b32_e32 v213, 0xffff0000, v195
	v_lshlrev_b32_e32 v142, 16, v203
	v_and_b32_e32 v143, 0xffff0000, v203
	v_add_f32_e32 v212, v212, v142
	v_add_f32_e32 v213, v213, v143
	v_lshlrev_b32_e32 v214, 16, v196
	v_and_b32_e32 v215, 0xffff0000, v196
	v_lshlrev_b32_e32 v142, 16, v204
	v_and_b32_e32 v143, 0xffff0000, v204
	v_add_f32_e32 v214, v214, v142
	v_add_f32_e32 v215, v215, v143
	v_lshlrev_b32_e32 v216, 16, v197
	v_and_b32_e32 v217, 0xffff0000, v197
	v_lshlrev_b32_e32 v142, 16, v205
	v_and_b32_e32 v143, 0xffff0000, v205
	v_add_f32_e32 v216, v216, v142
	v_add_f32_e32 v217, v217, v143
	v_lshlrev_b32_e32 v218, 16, v198
	v_and_b32_e32 v219, 0xffff0000, v198
	v_lshlrev_b32_e32 v142, 16, v206
	v_and_b32_e32 v143, 0xffff0000, v206
	v_add_f32_e32 v218, v218, v142
	v_add_f32_e32 v219, v219, v143
	v_lshlrev_b32_e32 v220, 16, v199
	v_and_b32_e32 v221, 0xffff0000, v199
	v_lshlrev_b32_e32 v142, 16, v207
	v_and_b32_e32 v143, 0xffff0000, v207
	v_add_f32_e32 v220, v220, v142
	v_add_f32_e32 v221, v221, v143
	v_lshlrev_b32_e32 v222, 16, v200
	v_and_b32_e32 v223, 0xffff0000, v200
	v_lshlrev_b32_e32 v142, 16, v208
	v_and_b32_e32 v143, 0xffff0000, v208
	v_add_f32_e32 v222, v222, v142
	v_add_f32_e32 v223, v223, v143
	v_lshlrev_b32_e32 v224, 16, v201
	v_and_b32_e32 v225, 0xffff0000, v201
	v_lshlrev_b32_e32 v142, 16, v209
	v_and_b32_e32 v143, 0xffff0000, v209
	v_add_f32_e32 v224, v224, v142
; #define LAS __attribute__((address_space(3)))
; __device__ __forceinline__ void peer_v_tokens(int j, const LAS unsigned short* EL, const LAS unsigned char* AL  , const LAS float* ASC  , const LAS int* SAL  , ...
;     ...
; #pragma unroll 1
;     for (int it = 0; it < 8; ++it) {
;         const int tl = it * 8 + wave, t = j * 64 + tl;
;         unsigned E[8];
;         { const LAS v4u* ep = (const LAS v4u*)(EL + tl * 128 + 16 * g); const v4u e0 = ep[0], e1 = ep[1];
;           E[0] = e0.x; E[1] = e0.y; E[2] = e0.z; E[3] = e0.w; E[4] = e1.x; E[5] = e1.y; E[6] = e1.z; E[7] = e1.w; }
;         uint2 hv[4]; float4 gv[4];
;         { unsigned ho = (unsigned)t * (D / 4) + (unsigned)lane; asm volatile("" : "+v"(ho)); const uint2* hp = (const uint2*)HB + ho; const float4* gp = (const float4*)fng + lane;
; #pragma unroll
;           for (int jq = 0; jq < 4; ++jq) { hv[jq] = hp[64 * jq]; gv[jq] = gp[64 * jq]; } }
;         VDMA(0, 0); VDMA(1, 1);
; #pragma unroll
;         for (int m = 0; m < 2; ++m) {
;             const int idx = lane + 64 * m, tau = idx >> 4, sr = idx & 15, k = 16 * (sr & 7) + 2 * tau + (sr >> 3);
;             const int aq = (int)*(const LAS signed char*)(AL + tl * 128 + k); const int tq = aq + 8;
;             const unsigned lo = (((unsigned)tq & 15u) ^ 8u) * 0x11111111u, hi = ((unsigned)(tq >> 4) & 15u) * 0x11111111u;
;             typedef unsigned u2v __attribute__((ext_vector_type(2)));
;             u2v l2; l2.x = lo; l2.y = lo; u2v h2; h2.x = hi; h2.y = hi;
;     ...
;         {
;             float4 v[4]; float ss = 0.f;
; #pragma unroll
;             for (int jq = 0; jq < 4; ++jq) { typedef unsigned u2v __attribute__((ext_vector_type(2))); const u2v pw = *(const LAS u2v*)(STASH + 4 * lane + 256 * jq); const uint2 hw = hv[jq];
;                 v[jq] = make_float4(__uint_as_float(hw.x << 16) + __uint_as_float(pw.x << 16), __uint_as_float(hw.x & 0xffff0000u) + __uint_as_float(pw.x & 0xffff0000u),
;                                     __uint_as_float(hw.y << 16) + __uint_as_float(pw.y << 16), __uint_as_float(hw.y & 0xffff0000u) + __uint_as_float(pw.y & 0xffff0000u));
;                 ss += v[jq].x * v[jq].x + v[jq].y * v[jq].y + v[jq].z * v[jq].z + v[jq].w * v[jq].w; }
;             ss = wave_sum(ss);
;             const float r3 = rsqrtf(ss * (1.f / D) + EPS);
;             float4* op = (float4*)(outp + (size_t)t * D) + lane;
	v_add_f32_e32 v225, v225, v143
	v_mov_b32_e32 v144, 0
	v_mul_f32_e32 v145, v210, v210
	v_fmac_f32_e32 v145, v211, v211
	v_fmac_f32_e32 v145, v212, v212
	v_fmac_f32_e32 v145, v213, v213
	v_add_f32_e32 v144, v144, v145
	v_mul_f32_e32 v145, v214, v214
	v_fmac_f32_e32 v145, v215, v215
	v_fmac_f32_e32 v145, v216, v216
	v_fmac_f32_e32 v145, v217, v217
	v_add_f32_e32 v144, v144, v145
	v_mul_f32_e32 v145, v218, v218
	v_fmac_f32_e32 v145, v219, v219
	v_fmac_f32_e32 v145, v220, v220
	v_fmac_f32_e32 v145, v221, v221
	v_add_f32_e32 v144, v144, v145
	v_mul_f32_e32 v145, v222, v222
	v_fmac_f32_e32 v145, v223, v223
	v_fmac_f32_e32 v145, v224, v224
	v_fmac_f32_e32 v145, v225, v225
	v_add_f32_e32 v144, v144, v145
	s_nop 1
	v_add_f32_dpp v144, v144, v144 quad_perm:[1,0,3,2] row_mask:0xf bank_mask:0xf bound_ctrl:1
	s_nop 1
	v_add_f32_dpp v144, v144, v144 quad_perm:[2,3,0,1] row_mask:0xf bank_mask:0xf bound_ctrl:1
	s_nop 1
	v_add_f32_dpp v144, v144, v144 row_half_mirror row_mask:0xf bank_mask:0xf bound_ctrl:1
	s_nop 1
	v_add_f32_dpp v144, v144, v144 row_mirror row_mask:0xf bank_mask:0xf bound_ctrl:1
	s_nop 1
	v_readlane_b32 s10, v144, 0
	v_readlane_b32 s11, v144, 16
	v_readlane_b32 s14, v144, 32
	v_readlane_b32 s15, v144, 48
	s_nop 3
	v_mov_b32_e32 v144, s11
	v_mov_b32_e32 v145, s15
	v_add_f32_e32 v144, s10, v144
	v_add_f32_e32 v145, s14, v145
	v_add_f32_e32 v144, v144, v145
	v_fmamk_f32 v144, v144, 0x3a800000, v111
	v_rsq_f32_e32 v144, v144
	s_nop 0
	v_mul_f32_e32 v210, v210, v144
	v_mul_f32_e32 v211, v211, v144
	v_mul_f32_e32 v212, v212, v144
	v_mul_f32_e32 v213, v213, v144
	v_mul_f32_e32 v214, v214, v144
	v_mul_f32_e32 v215, v215, v144
	v_mul_f32_e32 v216, v216, v144
	v_mul_f32_e32 v217, v217, v144
	v_mul_f32_e32 v218, v218, v144
	v_mul_f32_e32 v219, v219, v144
	v_mul_f32_e32 v220, v220, v144
	v_mul_f32_e32 v221, v221, v144
	v_mul_f32_e32 v222, v222, v144
	v_mul_f32_e32 v223, v223, v144
	v_mul_f32_e32 v224, v224, v144
	v_mul_f32_e32 v225, v225, v144
	v_dot8c_i32_i4_e32 v38, v122, v48
	v_dot8c_i32_i4_e32 v39, v122, v46
	v_dot8c_i32_i4_e32 v40, v124, v48
	v_dot8c_i32_i4_e32 v41, v124, v46
	v_dot8c_i32_i4_e32 v42, v126, v48
	v_dot8c_i32_i4_e32 v43, v126, v46
	v_dot8c_i32_i4_e32 v44, v128, v48
	v_dot8c_i32_i4_e32 v45, v128, v46
	v_dot8c_i32_i4_e32 v38, v123, v49
	v_dot8c_i32_i4_e32 v39, v123, v47
	v_dot8c_i32_i4_e32 v40, v125, v49
	v_dot8c_i32_i4_e32 v41, v125, v47
	v_dot8c_i32_i4_e32 v42, v127, v49
	v_dot8c_i32_i4_e32 v43, v127, v47
	v_dot8c_i32_i4_e32 v44, v129, v49
	v_dot8c_i32_i4_e32 v45, v129, v47
	v_and_b32_e32 v78, 0xffff, v32
	v_lshrrev_b32_e32 v79, 16, v32
	v_lshl_add_u32 v78, v78, 7, v150
	v_lshl_add_u32 v79, v79, 7, v151
	s_mov_b32 m0, s98
	s_add_i32 s43, s98, 0x400
	global_load_lds_dwordx4 v78, s[50:51]
	s_mov_b32 m0, s43
	s_nop 0
	global_load_lds_dwordx4 v79, s[50:51]
	s_waitcnt vmcnt(8)
	v_add_u32_e32 v54, s76, v59
	v_add_u32_e32 v55, s76, v60
	v_add_u32_e32 v56, s76, v61
	v_add_u32_e32 v57, s76, v62
	ds_read_b64_tr_b4 v[46:47], v160 offset:256
	ds_read_b64_tr_b4 v[48:49], v160 offset:1280
	ds_read_b64_tr_b4 v[122:123], v54
	ds_read_b64_tr_b4 v[124:125], v55
	ds_read_b64_tr_b4 v[126:127], v56
	ds_read_b64_tr_b4 v[128:129], v57
	s_waitcnt lgkmcnt(6)
	v_dot8c_i32_i4_e32 v38, v130, v52
	v_dot8c_i32_i4_e32 v39, v130, v50
	v_dot8c_i32_i4_e32 v40, v132, v52
	v_dot8c_i32_i4_e32 v41, v132, v50
	v_dot8c_i32_i4_e32 v42, v134, v52
	v_dot8c_i32_i4_e32 v43, v134, v50
	v_dot8c_i32_i4_e32 v44, v136, v52
	v_dot8c_i32_i4_e32 v45, v136, v50
	v_dot8c_i32_i4_e32 v38, v131, v53
	v_dot8c_i32_i4_e32 v39, v131, v51
	v_dot8c_i32_i4_e32 v40, v133, v53
	v_dot8c_i32_i4_e32 v41, v133, v51
	v_dot8c_i32_i4_e32 v42, v135, v53
	v_dot8c_i32_i4_e32 v43, v135, v51
	v_dot8c_i32_i4_e32 v44, v137, v53
	v_dot8c_i32_i4_e32 v45, v137, v51
	v_and_b32_e32 v78, 0xffff, v33
	v_lshrrev_b32_e32 v79, 16, v33
	v_lshl_add_u32 v78, v78, 7, v150
	v_lshl_add_u32 v79, v79, 7, v151
	s_mov_b32 m0, s99
	s_add_i32 s43, s99, 0x400
	global_load_lds_dwordx4 v78, s[50:51]
	s_mov_b32 m0, s43
	s_nop 0
	global_load_lds_dwordx4 v79, s[50:51]
	s_waitcnt vmcnt(8)
	v_add_u32_e32 v54, s77, v59
	v_add_u32_e32 v55, s77, v60
	v_add_u32_e32 v56, s77, v61
	v_add_u32_e32 v57, s77, v62
	ds_read_b64_tr_b4 v[50:51], v160 offset:384
	ds_read_b64_tr_b4 v[52:53], v160 offset:1408
	ds_read_b64_tr_b4 v[130:131], v54
	ds_read_b64_tr_b4 v[132:133], v55
	ds_read_b64_tr_b4 v[134:135], v56
	ds_read_b64_tr_b4 v[136:137], v57
	s_waitcnt lgkmcnt(6)
	v_dot8c_i32_i4_e32 v38, v122, v48
	v_dot8c_i32_i4_e32 v39, v122, v46
	v_dot8c_i32_i4_e32 v40, v124, v48
	v_dot8c_i32_i4_e32 v41, v124, v46
	v_dot8c_i32_i4_e32 v42, v126, v48
	v_dot8c_i32_i4_e32 v43, v126, v46
	v_dot8c_i32_i4_e32 v44, v128, v48
	v_dot8c_i32_i4_e32 v45, v128, v46
	v_dot8c_i32_i4_e32 v38, v123, v49
	v_dot8c_i32_i4_e32 v39, v123, v47
	v_dot8c_i32_i4_e32 v40, v125, v49
	v_dot8c_i32_i4_e32 v41, v125, v47
	v_dot8c_i32_i4_e32 v42, v127, v49
	v_dot8c_i32_i4_e32 v43, v127, v47
	v_dot8c_i32_i4_e32 v44, v129, v49
	v_dot8c_i32_i4_e32 v45, v129, v47
	s_waitcnt lgkmcnt(15)
	v_and_b32_e32 v78, 0xffff, v18
	v_lshrrev_b32_e32 v79, 16, v18
	v_lshl_add_u32 v78, v78, 7, v152
	v_lshl_add_u32 v79, v79, 7, v153
	s_mov_b32 m0, s76
	s_add_i32 s43, s76, 0x400
	global_load_lds_dwordx4 v78, s[50:51]
	s_mov_b32 m0, s43
	s_nop 0
	global_load_lds_dwordx4 v79, s[50:51]
	s_waitcnt vmcnt(8)
	v_add_u32_e32 v54, s78, v59
	v_add_u32_e32 v55, s78, v60
	v_add_u32_e32 v56, s78, v61
	v_add_u32_e32 v57, s78, v62
	ds_read_b64_tr_b4 v[46:47], v160 offset:512
	ds_read_b64_tr_b4 v[48:49], v160 offset:1536
	ds_read_b64_tr_b4 v[122:123], v54
	ds_read_b64_tr_b4 v[124:125], v55
	ds_read_b64_tr_b4 v[126:127], v56
	ds_read_b64_tr_b4 v[128:129], v57
	s_waitcnt lgkmcnt(6)
; __device__ __forceinline__ void peer_v_tokens(int j, const LAS unsigned short* EL, const LAS unsigned char* AL  , const LAS float* ASC  , const LAS int* SAL  , ...
;     ...
; #pragma unroll 1
;     for (int it = 0; it < 8; ++it) {
;         const int tl = it * 8 + wave, t = j * 64 + tl;
;         unsigned E[8];
;         { const LAS v4u* ep = (const LAS v4u*)(EL + tl * 128 + 16 * g); const v4u e0 = ep[0], e1 = ep[1];
;           E[0] = e0.x; E[1] = e0.y; E[2] = e0.z; E[3] = e0.w; E[4] = e1.x; E[5] = e1.y; E[6] = e1.z; E[7] = e1.w; }
;         uint2 hv[4]; float4 gv[4];
;         { unsigned ho = (unsigned)t * (D / 4) + (unsigned)lane; asm volatile("" : "+v"(ho)); const uint2* hp = (const uint2*)HB + ho; const float4* gp = (const float4*)fng + lane;
; #pragma unroll
;           for (int jq = 0; jq < 4; ++jq) { hv[jq] = hp[64 * jq]; gv[jq] = gp[64 * jq]; } }
;         VDMA(0, 0); VDMA(1, 1);
; #pragma unroll
;         for (int m = 0; m < 2; ++m) {
;             const int idx = lane + 64 * m, tau = idx >> 4, sr = idx & 15, k = 16 * (sr & 7) + 2 * tau + (sr >> 3);
;             const int aq = (int)*(const LAS signed char*)(AL + tl * 128 + k); const int tq = aq + 8;
;             const unsigned lo = (((unsigned)tq & 15u) ^ 8u) * 0x11111111u, hi = ((unsigned)(tq >> 4) & 15u) * 0x11111111u;
;             typedef unsigned u2v __attribute__((ext_vector_type(2)));
;             u2v l2; l2.x = lo; l2.y = lo; u2v h2; h2.x = hi; h2.y = hi;
;             *(LAS u2v*)(ATL + 8 * idx) = l2; *(LAS u2v*)(ATL + 1024 + 8 * idx) = h2;
;         }
;         const float asc = ASC[tl]; const int sa = SAL[tl];
;         CFENCE();
;         int accH[4], accL[4];
; #pragma unroll
;         for (int st = 0; st < 16; ++st) {
;             const int p = st >> 2, q = st & 3;
;             if (st < 14) VDMA(st + 2, (st + 2) % 3);
;             if (st < 14) asm volatile("s_waitcnt vmcnt(8)" ::: "memory");
;             else if (st == 14) asm volatile("s_waitcnt vmcnt(4)" ::: "memory");
;             else asm volatile("s_waitcnt vmcnt(0)" ::: "memory");
;             if (q == 0) {
; #pragma unroll
;                 for (int r = 0; r < 4; ++r) { accH[r] = 0; accL[r] = 0; } }
; #pragma unroll
;             for (int tp = 0; tp < 2; ++tp) {
;                 const v2i ao = TR4(ATL + (2 * q + tp) * 128 + 8 * s16), ah = TR4(ATL + 1024 + (2 * q + tp) * 128 + 8 * s16);
; #pragma unroll
	v_dot8c_i32_i4_e32 v38, v130, v52
	v_dot8c_i32_i4_e32 v39, v130, v50
	v_dot8c_i32_i4_e32 v40, v132, v52
	v_dot8c_i32_i4_e32 v41, v132, v50
	v_dot8c_i32_i4_e32 v42, v134, v52
	v_dot8c_i32_i4_e32 v43, v134, v50
	v_dot8c_i32_i4_e32 v44, v136, v52
	v_dot8c_i32_i4_e32 v45, v136, v50
	v_dot8c_i32_i4_e32 v38, v131, v53
	v_dot8c_i32_i4_e32 v39, v131, v51
	v_dot8c_i32_i4_e32 v40, v133, v53
	v_dot8c_i32_i4_e32 v41, v133, v51
	v_dot8c_i32_i4_e32 v42, v135, v53
	v_dot8c_i32_i4_e32 v43, v135, v51
	v_dot8c_i32_i4_e32 v44, v137, v53
	v_dot8c_i32_i4_e32 v45, v137, v51
	v_and_b32_e32 v78, 0xffff, v19
	v_lshrrev_b32_e32 v79, 16, v19
	v_lshl_add_u32 v78, v78, 7, v152
	v_lshl_add_u32 v79, v79, 7, v153
	s_mov_b32 m0, s77
	s_add_i32 s43, s77, 0x400
	global_load_lds_dwordx4 v78, s[50:51]
	s_mov_b32 m0, s43
	s_nop 0
	global_load_lds_dwordx4 v79, s[50:51]
	s_waitcnt vmcnt(8)
	v_add_u32_e32 v54, s79, v59
	v_add_u32_e32 v55, s79, v60
	v_add_u32_e32 v56, s79, v61
	v_add_u32_e32 v57, s79, v62
	ds_read_b64_tr_b4 v[50:51], v160 offset:640
	ds_read_b64_tr_b4 v[52:53], v160 offset:1664
	ds_read_b64_tr_b4 v[130:131], v54
	ds_read_b64_tr_b4 v[132:133], v55
	ds_read_b64_tr_b4 v[134:135], v56
	ds_read_b64_tr_b4 v[136:137], v57
	s_waitcnt lgkmcnt(6)
	v_dot8c_i32_i4_e32 v38, v122, v48
	v_dot8c_i32_i4_e32 v39, v122, v46
	v_dot8c_i32_i4_e32 v40, v124, v48
	v_dot8c_i32_i4_e32 v41, v124, v46
	v_dot8c_i32_i4_e32 v42, v126, v48
	v_dot8c_i32_i4_e32 v43, v126, v46
	v_dot8c_i32_i4_e32 v44, v128, v48
	v_dot8c_i32_i4_e32 v45, v128, v46
	v_dot8c_i32_i4_e32 v38, v123, v49
	v_dot8c_i32_i4_e32 v39, v123, v47
	v_dot8c_i32_i4_e32 v40, v125, v49
	v_dot8c_i32_i4_e32 v41, v125, v47
	v_dot8c_i32_i4_e32 v42, v127, v49
	v_dot8c_i32_i4_e32 v43, v127, v47
	v_dot8c_i32_i4_e32 v44, v129, v49
	v_dot8c_i32_i4_e32 v45, v129, v47
	s_waitcnt lgkmcnt(15)
	v_add_u32_e32 v143, 8, v139
	v_and_b32_e32 v142, 15, v143
	v_xor_b32_e32 v142, 8, v142
	v_bfe_u32 v144, v143, 4, 4
	v_mul_lo_u32 v142, v142, s92
	v_mul_lo_u32 v144, v144, s92
	v_mov_b32_e32 v143, v142
	v_mov_b32_e32 v145, v144
	ds_write2st64_b64 v159, v[142:143], v[144:145] offset1:2
	v_and_b32_e32 v78, 0xffff, v20
	v_lshrrev_b32_e32 v79, 16, v20
	v_lshl_add_u32 v78, v78, 7, v152
	v_lshl_add_u32 v79, v79, 7, v153
	s_mov_b32 m0, s78
	s_add_i32 s43, s78, 0x400
	global_load_lds_dwordx4 v78, s[50:51]
	s_mov_b32 m0, s43
	s_nop 0
	global_load_lds_dwordx4 v79, s[50:51]
	s_waitcnt vmcnt(8)
	v_add_u32_e32 v54, s98, v59
	v_add_u32_e32 v55, s98, v60
	v_add_u32_e32 v56, s98, v61
	v_add_u32_e32 v57, s98, v62
	ds_read_b64_tr_b4 v[46:47], v160 offset:768
	ds_read_b64_tr_b4 v[48:49], v160 offset:1792
	ds_read_b64_tr_b4 v[122:123], v54
	ds_read_b64_tr_b4 v[124:125], v55
	ds_read_b64_tr_b4 v[126:127], v56
	ds_read_b64_tr_b4 v[128:129], v57
	s_waitcnt lgkmcnt(7)
	v_dot8c_i32_i4_e32 v38, v130, v52
	v_dot8c_i32_i4_e32 v39, v130, v50
	v_dot8c_i32_i4_e32 v40, v132, v52
	v_dot8c_i32_i4_e32 v41, v132, v50
	v_dot8c_i32_i4_e32 v42, v134, v52
	v_dot8c_i32_i4_e32 v43, v134, v50
	v_dot8c_i32_i4_e32 v44, v136, v52
	v_dot8c_i32_i4_e32 v45, v136, v50
	v_dot8c_i32_i4_e32 v38, v131, v53
	v_dot8c_i32_i4_e32 v39, v131, v51
	v_dot8c_i32_i4_e32 v40, v133, v53
	v_dot8c_i32_i4_e32 v41, v133, v51
	v_dot8c_i32_i4_e32 v42, v135, v53
	v_dot8c_i32_i4_e32 v43, v135, v51
	v_dot8c_i32_i4_e32 v44, v137, v53
	v_dot8c_i32_i4_e32 v45, v137, v51
	v_and_b32_e32 v78, 0xffff, v21
	v_lshrrev_b32_e32 v79, 16, v21
	v_lshl_add_u32 v78, v78, 7, v152
	v_lshl_add_u32 v79, v79, 7, v153
	s_mov_b32 m0, s79
	s_add_i32 s43, s79, 0x400
	global_load_lds_dwordx4 v78, s[50:51]
	s_mov_b32 m0, s43
	s_nop 0
	global_load_lds_dwordx4 v79, s[50:51]
	s_waitcnt vmcnt(8)
	v_add_u32_e32 v54, s99, v59
	v_add_u32_e32 v55, s99, v60
	v_add_u32_e32 v56, s99, v61
	v_add_u32_e32 v57, s99, v62
	ds_read_b64_tr_b4 v[50:51], v160 offset:896
	ds_read_b64_tr_b4 v[52:53], v160 offset:1920
	ds_read_b64_tr_b4 v[130:131], v54
	ds_read_b64_tr_b4 v[132:133], v55
	ds_read_b64_tr_b4 v[134:135], v56
	ds_read_b64_tr_b4 v[136:137], v57
	s_waitcnt lgkmcnt(6)
	v_dot8c_i32_i4_e32 v38, v122, v48
	v_dot8c_i32_i4_e32 v39, v122, v46
	v_dot8c_i32_i4_e32 v40, v124, v48
	v_dot8c_i32_i4_e32 v41, v124, v46
	v_dot8c_i32_i4_e32 v42, v126, v48
	v_dot8c_i32_i4_e32 v43, v126, v46
	v_dot8c_i32_i4_e32 v44, v128, v48
	v_dot8c_i32_i4_e32 v45, v128, v46
	v_dot8c_i32_i4_e32 v38, v123, v49
	v_dot8c_i32_i4_e32 v39, v123, v47
	v_dot8c_i32_i4_e32 v40, v125, v49
	v_dot8c_i32_i4_e32 v41, v125, v47
	v_dot8c_i32_i4_e32 v42, v127, v49
	v_dot8c_i32_i4_e32 v43, v127, v47
	v_dot8c_i32_i4_e32 v44, v129, v49
	v_dot8c_i32_i4_e32 v45, v129, v47
	v_and_b32_e32 v78, 0xffff, v22
	v_lshrrev_b32_e32 v79, 16, v22
	v_lshl_add_u32 v78, v78, 7, v152
	v_lshl_add_u32 v79, v79, 7, v153
	s_mov_b32 m0, s98
	s_add_i32 s43, s98, 0x400
	global_load_lds_dwordx4 v78, s[50:51]
	s_mov_b32 m0, s43
	s_nop 0
	global_load_lds_dwordx4 v79, s[50:51]
	s_waitcnt vmcnt(8)
	v_add_u32_e32 v54, s76, v59
	v_add_u32_e32 v55, s76, v60
	v_add_u32_e32 v56, s76, v61
	v_add_u32_e32 v57, s76, v62
	ds_read_b64_tr_b4 v[46:47], v160
	ds_read_b64_tr_b4 v[48:49], v160 offset:1024
	ds_read_b64_tr_b4 v[122:123], v54
	ds_read_b64_tr_b4 v[124:125], v55
	ds_read_b64_tr_b4 v[126:127], v56
	ds_read_b64_tr_b4 v[128:129], v57
	s_waitcnt lgkmcnt(6)
	v_dot8c_i32_i4_e32 v38, v130, v52
	v_dot8c_i32_i4_e32 v39, v130, v50
	v_dot8c_i32_i4_e32 v40, v132, v52
	v_dot8c_i32_i4_e32 v41, v132, v50
	v_dot8c_i32_i4_e32 v42, v134, v52
	v_dot8c_i32_i4_e32 v43, v134, v50
	v_dot8c_i32_i4_e32 v44, v136, v52
	v_dot8c_i32_i4_e32 v45, v136, v50
	v_dot8c_i32_i4_e32 v38, v131, v53
	v_dot8c_i32_i4_e32 v39, v131, v51
	v_dot8c_i32_i4_e32 v40, v133, v53
	v_dot8c_i32_i4_e32 v41, v133, v51
	v_dot8c_i32_i4_e32 v42, v135, v53
	v_dot8c_i32_i4_e32 v43, v135, v51
	v_dot8c_i32_i4_e32 v44, v137, v53
	v_dot8c_i32_i4_e32 v45, v137, v51
	s_nop 3
	s_waitcnt lgkmcnt(15)
; __device__ __forceinline__ void peer_v_tokens(int j, const LAS unsigned short* EL, const LAS unsigned char* AL  , const LAS float* ASC  , const LAS int* SAL  , ...
;     ...
; #pragma unroll
;         for (int st = 0; st < 16; ++st) {
;             const int p = st >> 2, q = st & 3;
;             if (st < 14) VDMA(st + 2, (st + 2) % 3);
;             if (st < 14) asm volatile("s_waitcnt vmcnt(8)" ::: "memory");
;             else if (st == 14) asm volatile("s_waitcnt vmcnt(4)" ::: "memory");
;             else asm volatile("s_waitcnt vmcnt(0)" ::: "memory");
;             if (q == 0) {
; #pragma unroll
;                 for (int r = 0; r < 4; ++r) { accH[r] = 0; accL[r] = 0; } }
; #pragma unroll
;             for (int tp = 0; tp < 2; ++tp) {
;                 const v2i ao = TR4(ATL + (2 * q + tp) * 128 + 8 * s16), ah = TR4(ATL + 1024 + (2 * q + tp) * 128 + 8 * s16);
; #pragma unroll
;                 for (int r = 0; r < 4; ++r) {
;                     const v2i d = TR4(ldsb + BUF[st % 3] + 2048 * tp + roff[r]);
;                     accH[r] = __builtin_amdgcn_sdot8(d.x, ah.x, accH[r], false); accH[r] = __builtin_amdgcn_sdot8(d.y, ah.y, accH[r], false);
;                     accL[r] = __builtin_amdgcn_sdot8(d.x, ao.x, accL[r], false); accL[r] = __builtin_amdgcn_sdot8(d.y, ao.y, accL[r], false);
;                 }
;             }
;             asm volatile("s_waitcnt lgkmcnt(0)" ::: "memory");
;             if (q == 3) {
; #pragma unroll
;                 for (int r = 0; r < 4; ++r) STASH[256 * p + 16 * (grp + 4 * r) + pc] = f2bf(asc * (float)(2 * ((accH[r] << 4) + accL[r]) + sa));
;             }
;         }
;         CFENCE();
;         {
;             float4 v[4]; float ss = 0.f;
; #pragma unroll
;             for (int jq = 0; jq < 4; ++jq) { typedef unsigned u2v __attribute__((ext_vector_type(2))); const u2v pw = *(const LAS u2v*)(STASH + 4 * lane + 256 * jq); const uint2 hw = hv[jq];
;                 v[jq] = make_float4(__uint_as_float(hw.x << 16) + __uint_as_float(pw.x << 16), __uint_as_float(hw.x & 0xffff0000u) + __uint_as_float(pw.x & 0xffff0000u),
;                                     __uint_as_float(hw.y << 16) + __uint_as_float(pw.y << 16), __uint_as_float(hw.y & 0xffff0000u) + __uint_as_float(pw.y & 0xffff0000u));
;                 ss += v[jq].x * v[jq].x + v[jq].y * v[jq].y + v[jq].z * v[jq].z + v[jq].w * v[jq].w; }
;             ss = wave_sum(ss);
	v_lshlrev_b32_e32 v38, 5, v38
	v_lshlrev_b32_e32 v39, 1, v39
	v_add3_u32 v38, v39, v229, v38
	v_cvt_f32_i32_e32 v38, v38
	v_mul_f32_e32 v38, v228, v38
	v_lshlrev_b32_e32 v40, 5, v40
	v_lshlrev_b32_e32 v41, 1, v41
	v_add3_u32 v40, v41, v229, v40
	v_cvt_f32_i32_e32 v40, v40
	v_mul_f32_e32 v40, v228, v40
	v_lshlrev_b32_e32 v42, 5, v42
	v_lshlrev_b32_e32 v43, 1, v43
	v_add3_u32 v42, v43, v229, v42
	v_cvt_f32_i32_e32 v42, v42
	v_mul_f32_e32 v42, v228, v42
	v_lshlrev_b32_e32 v44, 5, v44
	v_lshlrev_b32_e32 v45, 1, v45
	v_add3_u32 v44, v45, v229, v44
	v_cvt_f32_i32_e32 v44, v44
	v_mul_f32_e32 v44, v228, v44
	v_cvt_pk_bf16_f32 v170, v38, v40
	v_cvt_pk_bf16_f32 v171, v42, v44
	ds_read_b128 v[252:255], v155
	s_add_i32 s44, s40, 16
	s_ashr_i32 s45, s44, 31
	s_lshl_b64 s[44:45], s[44:45], 12
	v_lshl_add_u64 v[80:81], v[36:37], 0, s[44:45]
	s_waitcnt lgkmcnt(0)
	v_mul_f32_e32 v210, v210, v252
	v_mul_f32_e32 v211, v211, v253
	v_mul_f32_e32 v212, v212, v254
	v_mul_f32_e32 v213, v213, v255
	global_store_dwordx4 v[80:81], v[210:213], off nt
	s_add_i32 s43, s40, 24
	s_lshl_b32 s43, s43, 11
	v_add_u32_e32 v138, s43, v66
	global_load_dwordx2 v[194:195], v138, s[70:71]
	global_load_dwordx2 v[196:197], v138, s[70:71] offset:512
	global_load_dwordx2 v[198:199], v138, s[70:71] offset:1024
	global_load_dwordx2 v[200:201], v138, s[70:71] offset:1536
	v_add_u32_e32 v147, 8, v140
	v_and_b32_e32 v146, 15, v147
	v_xor_b32_e32 v146, 8, v146
	v_bfe_u32 v148, v147, 4, 4
	v_mul_lo_u32 v146, v146, s92
	v_mul_lo_u32 v148, v148, s92
	v_mov_b32_e32 v147, v146
	v_mov_b32_e32 v149, v148
	ds_write2st64_b64 v77, v[146:147], v[148:149] offset1:2
	v_add_u32_e32 v138, 0x1400, v74
	ds_read_u8 v139, v138
	v_add_u32_e32 v141, 0x1400, v73
	ds_read_u8 v140, v141
	s_add_i32 s43, s67, 128
	v_mov_b32_e32 v138, s43
	ds_read2st64_b32 v[228:229], v138 offset1:1
	ds_read_b128 v[26:29], v227 offset:10240
	ds_read_b128 v[30:33], v227 offset:10256
	v_mov_b32_e32 v38, 0
	v_mov_b32_e32 v39, 0
	v_mov_b32_e32 v40, 0
	v_mov_b32_e32 v41, 0
	v_mov_b32_e32 v42, 0
	v_mov_b32_e32 v43, 0
	v_mov_b32_e32 v44, 0
	v_mov_b32_e32 v45, 0
	v_and_b32_e32 v78, 0xffff, v23
	v_lshrrev_b32_e32 v79, 16, v23
	v_lshl_add_u32 v78, v78, 7, v152
	v_lshl_add_u32 v79, v79, 7, v153
	s_mov_b32 m0, s99
	s_add_i32 s43, s99, 0x400
	global_load_lds_dwordx4 v78, s[50:51]
	s_mov_b32 m0, s43
	s_nop 0
	global_load_lds_dwordx4 v79, s[50:51]
	s_waitcnt vmcnt(13)
	v_add_u32_e32 v54, s77, v59
	v_add_u32_e32 v55, s77, v60
	v_add_u32_e32 v56, s77, v61
	v_add_u32_e32 v57, s77, v62
	ds_read_b64_tr_b4 v[50:51], v160 offset:128
	ds_read_b64_tr_b4 v[52:53], v160 offset:1152
	ds_read_b64_tr_b4 v[130:131], v54
	ds_read_b64_tr_b4 v[132:133], v55
	ds_read_b64_tr_b4 v[134:135], v56
	ds_read_b64_tr_b4 v[136:137], v57
	s_waitcnt lgkmcnt(13)
	v_dot8c_i32_i4_e32 v38, v122, v48
	v_dot8c_i32_i4_e32 v39, v122, v46
	v_dot8c_i32_i4_e32 v40, v124, v48
	v_dot8c_i32_i4_e32 v41, v124, v46
	v_dot8c_i32_i4_e32 v42, v126, v48
	v_dot8c_i32_i4_e32 v43, v126, v46
	v_dot8c_i32_i4_e32 v44, v128, v48
	v_dot8c_i32_i4_e32 v45, v128, v46
	v_dot8c_i32_i4_e32 v38, v123, v49
	v_dot8c_i32_i4_e32 v39, v123, v47
	v_dot8c_i32_i4_e32 v40, v125, v49
	v_dot8c_i32_i4_e32 v41, v125, v47
	v_dot8c_i32_i4_e32 v42, v127, v49
	v_dot8c_i32_i4_e32 v43, v127, v47
	v_dot8c_i32_i4_e32 v44, v129, v49
	v_dot8c_i32_i4_e32 v45, v129, v47
	v_and_b32_e32 v78, 0xffff, v24
	v_lshrrev_b32_e32 v79, 16, v24
	v_lshl_add_u32 v78, v78, 7, v152
	v_lshl_add_u32 v79, v79, 7, v153
	s_mov_b32 m0, s76
	s_add_i32 s43, s76, 0x400
	global_load_lds_dwordx4 v78, s[50:51]
	s_mov_b32 m0, s43
	s_nop 0
	global_load_lds_dwordx4 v79, s[50:51]
	s_waitcnt vmcnt(13)
	v_add_u32_e32 v54, s78, v59
	v_add_u32_e32 v55, s78, v60
	v_add_u32_e32 v56, s78, v61
	v_add_u32_e32 v57, s78, v62
	ds_read_b64_tr_b4 v[46:47], v160 offset:256
	ds_read_b64_tr_b4 v[48:49], v160 offset:1280
	ds_read_b64_tr_b4 v[122:123], v54
	ds_read_b64_tr_b4 v[124:125], v55
	ds_read_b64_tr_b4 v[126:127], v56
	ds_read_b64_tr_b4 v[128:129], v57
	s_waitcnt lgkmcnt(6)
	v_dot8c_i32_i4_e32 v38, v130, v52
	v_dot8c_i32_i4_e32 v39, v130, v50
	v_dot8c_i32_i4_e32 v40, v132, v52
	v_dot8c_i32_i4_e32 v41, v132, v50
	v_dot8c_i32_i4_e32 v42, v134, v52
	v_dot8c_i32_i4_e32 v43, v134, v50
	v_dot8c_i32_i4_e32 v44, v136, v52
	v_dot8c_i32_i4_e32 v45, v136, v50
	v_dot8c_i32_i4_e32 v38, v131, v53
	v_dot8c_i32_i4_e32 v39, v131, v51
	v_dot8c_i32_i4_e32 v40, v133, v53
	v_dot8c_i32_i4_e32 v41, v133, v51
	v_dot8c_i32_i4_e32 v42, v135, v53
	v_dot8c_i32_i4_e32 v43, v135, v51
	v_dot8c_i32_i4_e32 v44, v137, v53
	v_dot8c_i32_i4_e32 v45, v137, v51
	v_and_b32_e32 v78, 0xffff, v25
	v_lshrrev_b32_e32 v79, 16, v25
	v_lshl_add_u32 v78, v78, 7, v152
	v_lshl_add_u32 v79, v79, 7, v153
	s_mov_b32 m0, s77
	s_add_i32 s43, s77, 0x400
	global_load_lds_dwordx4 v78, s[50:51]
	s_mov_b32 m0, s43
	s_nop 0
	global_load_lds_dwordx4 v79, s[50:51]
	s_waitcnt vmcnt(13)
	v_add_u32_e32 v54, s79, v59
	v_add_u32_e32 v55, s79, v60
	v_add_u32_e32 v56, s79, v61
	v_add_u32_e32 v57, s79, v62
	ds_read_b64_tr_b4 v[50:51], v160 offset:384
	ds_read_b64_tr_b4 v[52:53], v160 offset:1408
	ds_read_b64_tr_b4 v[130:131], v54
	ds_read_b64_tr_b4 v[132:133], v55
	ds_read_b64_tr_b4 v[134:135], v56
	ds_read_b64_tr_b4 v[136:137], v57
	s_waitcnt lgkmcnt(6)
	v_dot8c_i32_i4_e32 v38, v122, v48
	v_dot8c_i32_i4_e32 v39, v122, v46
	v_dot8c_i32_i4_e32 v40, v124, v48
	v_dot8c_i32_i4_e32 v41, v124, v46
	v_dot8c_i32_i4_e32 v42, v126, v48
	v_dot8c_i32_i4_e32 v43, v126, v46
	v_dot8c_i32_i4_e32 v44, v128, v48
	v_dot8c_i32_i4_e32 v45, v128, v46
	v_dot8c_i32_i4_e32 v38, v123, v49
	v_dot8c_i32_i4_e32 v39, v123, v47
	v_dot8c_i32_i4_e32 v40, v125, v49
	v_dot8c_i32_i4_e32 v41, v125, v47
	v_dot8c_i32_i4_e32 v42, v127, v49
	v_dot8c_i32_i4_e32 v43, v127, v47
	v_dot8c_i32_i4_e32 v44, v129, v49
	v_dot8c_i32_i4_e32 v45, v129, v47
	s_waitcnt lgkmcnt(15)
; __device__ __forceinline__ void peer_v_tokens(int j, const LAS unsigned short* EL, const LAS unsigned char* AL  , const LAS float* ASC  , const LAS int* SAL  , ...
;     ...
; #pragma unroll 1
;     for (int it = 0; it < 8; ++it) {
;         const int tl = it * 8 + wave, t = j * 64 + tl;
;         unsigned E[8];
;         { const LAS v4u* ep = (const LAS v4u*)(EL + tl * 128 + 16 * g); const v4u e0 = ep[0], e1 = ep[1];
;           E[0] = e0.x; E[1] = e0.y; E[2] = e0.z; E[3] = e0.w; E[4] = e1.x; E[5] = e1.y; E[6] = e1.z; E[7] = e1.w; }
;         uint2 hv[4]; float4 gv[4];
;         { unsigned ho = (unsigned)t * (D / 4) + (unsigned)lane; asm volatile("" : "+v"(ho)); const uint2* hp = (const uint2*)HB + ho; const float4* gp = (const float4*)fng + lane;
; #pragma unroll
;           for (int jq = 0; jq < 4; ++jq) { hv[jq] = hp[64 * jq]; gv[jq] = gp[64 * jq]; } }
;         VDMA(0, 0); VDMA(1, 1);
; #pragma unroll
;         for (int m = 0; m < 2; ++m) {
;             const int idx = lane + 64 * m, tau = idx >> 4, sr = idx & 15, k = 16 * (sr & 7) + 2 * tau + (sr >> 3);
;             const int aq = (int)*(const LAS signed char*)(AL + tl * 128 + k); const int tq = aq + 8;
;             const unsigned lo = (((unsigned)tq & 15u) ^ 8u) * 0x11111111u, hi = ((unsigned)(tq >> 4) & 15u) * 0x11111111u;
;             typedef unsigned u2v __attribute__((ext_vector_type(2)));
;             u2v l2; l2.x = lo; l2.y = lo; u2v h2; h2.x = hi; h2.y = hi;
;             *(LAS u2v*)(ATL + 8 * idx) = l2; *(LAS u2v*)(ATL + 1024 + 8 * idx) = h2;
;         }
;         const float asc = ASC[tl]; const int sa = SAL[tl];
;         CFENCE();
;         int accH[4], accL[4];
; #pragma unroll
;         for (int st = 0; st < 16; ++st) {
;             const int p = st >> 2, q = st & 3;
;             if (st < 14) VDMA(st + 2, (st + 2) % 3);
;             if (st < 14) asm volatile("s_waitcnt vmcnt(8)" ::: "memory");
;             else if (st == 14) asm volatile("s_waitcnt vmcnt(4)" ::: "memory");
;             else asm volatile("s_waitcnt vmcnt(0)" ::: "memory");
;             if (q == 0) {
; #pragma unroll
;                 for (int r = 0; r < 4; ++r) { accH[r] = 0; accL[r] = 0; } }
; #pragma unroll
;             for (int tp = 0; tp < 2; ++tp) {
;                 const v2i ao = TR4(ATL + (2 * q + tp) * 128 + 8 * s16), ah = TR4(ATL + 1024 + (2 * q + tp) * 128 + 8 * s16);
; #pragma unroll
	v_and_b32_e32 v78, 0xffff, v26
	v_lshrrev_b32_e32 v79, 16, v26
	v_lshl_add_u32 v78, v78, 7, v152
	v_lshl_add_u32 v79, v79, 7, v153
	s_mov_b32 m0, s78
	s_add_i32 s43, s78, 0x400
	global_load_lds_dwordx4 v78, s[50:51]
	s_mov_b32 m0, s43
	s_nop 0
	global_load_lds_dwordx4 v79, s[50:51]
	s_waitcnt vmcnt(13)
	v_add_u32_e32 v54, s98, v59
	v_add_u32_e32 v55, s98, v60
	v_add_u32_e32 v56, s98, v61
	v_add_u32_e32 v57, s98, v62
	ds_read_b64_tr_b4 v[46:47], v160 offset:512
	ds_read_b64_tr_b4 v[48:49], v160 offset:1536
	ds_read_b64_tr_b4 v[122:123], v54
	ds_read_b64_tr_b4 v[124:125], v55
	ds_read_b64_tr_b4 v[126:127], v56
	ds_read_b64_tr_b4 v[128:129], v57
	s_waitcnt lgkmcnt(6)
	v_dot8c_i32_i4_e32 v38, v130, v52
	v_dot8c_i32_i4_e32 v39, v130, v50
	v_dot8c_i32_i4_e32 v40, v132, v52
	v_dot8c_i32_i4_e32 v41, v132, v50
	v_dot8c_i32_i4_e32 v42, v134, v52
	v_dot8c_i32_i4_e32 v43, v134, v50
	v_dot8c_i32_i4_e32 v44, v136, v52
	v_dot8c_i32_i4_e32 v45, v136, v50
	v_dot8c_i32_i4_e32 v38, v131, v53
	v_dot8c_i32_i4_e32 v39, v131, v51
	v_dot8c_i32_i4_e32 v40, v133, v53
	v_dot8c_i32_i4_e32 v41, v133, v51
	v_dot8c_i32_i4_e32 v42, v135, v53
	v_dot8c_i32_i4_e32 v43, v135, v51
	v_dot8c_i32_i4_e32 v44, v137, v53
	v_dot8c_i32_i4_e32 v45, v137, v51
	v_and_b32_e32 v78, 0xffff, v27
	v_lshrrev_b32_e32 v79, 16, v27
	v_lshl_add_u32 v78, v78, 7, v152
	v_lshl_add_u32 v79, v79, 7, v153
	s_mov_b32 m0, s79
	s_add_i32 s43, s79, 0x400
	global_load_lds_dwordx4 v78, s[50:51]
	s_mov_b32 m0, s43
	s_nop 0
	global_load_lds_dwordx4 v79, s[50:51]
	s_waitcnt vmcnt(8)
	v_add_u32_e32 v54, s99, v59
	v_add_u32_e32 v55, s99, v60
	v_add_u32_e32 v56, s99, v61
	v_add_u32_e32 v57, s99, v62
	ds_read_b64_tr_b4 v[50:51], v160 offset:640
	ds_read_b64_tr_b4 v[52:53], v160 offset:1664
	ds_read_b64_tr_b4 v[130:131], v54
	ds_read_b64_tr_b4 v[132:133], v55
	ds_read_b64_tr_b4 v[134:135], v56
	ds_read_b64_tr_b4 v[136:137], v57
	s_waitcnt lgkmcnt(6)
	v_dot8c_i32_i4_e32 v38, v122, v48
	v_dot8c_i32_i4_e32 v39, v122, v46
	v_dot8c_i32_i4_e32 v40, v124, v48
	v_dot8c_i32_i4_e32 v41, v124, v46
	v_dot8c_i32_i4_e32 v42, v126, v48
	v_dot8c_i32_i4_e32 v43, v126, v46
	v_dot8c_i32_i4_e32 v44, v128, v48
	v_dot8c_i32_i4_e32 v45, v128, v46
	v_dot8c_i32_i4_e32 v38, v123, v49
	v_dot8c_i32_i4_e32 v39, v123, v47
	v_dot8c_i32_i4_e32 v40, v125, v49
	v_dot8c_i32_i4_e32 v41, v125, v47
	v_dot8c_i32_i4_e32 v42, v127, v49
	v_dot8c_i32_i4_e32 v43, v127, v47
	v_dot8c_i32_i4_e32 v44, v129, v49
	v_dot8c_i32_i4_e32 v45, v129, v47
	s_waitcnt lgkmcnt(15)
	v_add_u32_e32 v143, 8, v139
	v_and_b32_e32 v142, 15, v143
	v_xor_b32_e32 v142, 8, v142
	v_bfe_u32 v144, v143, 4, 4
	v_mul_lo_u32 v142, v142, s92
	v_mul_lo_u32 v144, v144, s92
	v_mov_b32_e32 v143, v142
	v_mov_b32_e32 v145, v144
	ds_write2st64_b64 v159, v[142:143], v[144:145] offset1:2
	v_and_b32_e32 v78, 0xffff, v28
	v_lshrrev_b32_e32 v79, 16, v28
	v_lshl_add_u32 v78, v78, 7, v152
	v_lshl_add_u32 v79, v79, 7, v153
	s_mov_b32 m0, s98
	s_add_i32 s43, s98, 0x400
	global_load_lds_dwordx4 v78, s[50:51]
	s_mov_b32 m0, s43
	s_nop 0
	global_load_lds_dwordx4 v79, s[50:51]
	s_waitcnt vmcnt(8)
	v_add_u32_e32 v54, s76, v59
	v_add_u32_e32 v55, s76, v60
	v_add_u32_e32 v56, s76, v61
	v_add_u32_e32 v57, s76, v62
	ds_read_b64_tr_b4 v[46:47], v160 offset:768
	ds_read_b64_tr_b4 v[48:49], v160 offset:1792
	ds_read_b64_tr_b4 v[122:123], v54
	ds_read_b64_tr_b4 v[124:125], v55
	ds_read_b64_tr_b4 v[126:127], v56
	ds_read_b64_tr_b4 v[128:129], v57
	s_waitcnt lgkmcnt(7)
	v_dot8c_i32_i4_e32 v38, v130, v52
	v_dot8c_i32_i4_e32 v39, v130, v50
	v_dot8c_i32_i4_e32 v40, v132, v52
	v_dot8c_i32_i4_e32 v41, v132, v50
	v_dot8c_i32_i4_e32 v42, v134, v52
	v_dot8c_i32_i4_e32 v43, v134, v50
	v_dot8c_i32_i4_e32 v44, v136, v52
	v_dot8c_i32_i4_e32 v45, v136, v50
	v_dot8c_i32_i4_e32 v38, v131, v53
	v_dot8c_i32_i4_e32 v39, v131, v51
	v_dot8c_i32_i4_e32 v40, v133, v53
	v_dot8c_i32_i4_e32 v41, v133, v51
	v_dot8c_i32_i4_e32 v42, v135, v53
	v_dot8c_i32_i4_e32 v43, v135, v51
	v_dot8c_i32_i4_e32 v44, v137, v53
	v_dot8c_i32_i4_e32 v45, v137, v51
	v_and_b32_e32 v78, 0xffff, v29
	v_lshrrev_b32_e32 v79, 16, v29
	v_lshl_add_u32 v78, v78, 7, v152
	v_lshl_add_u32 v79, v79, 7, v153
	s_mov_b32 m0, s99
	s_add_i32 s43, s99, 0x400
	global_load_lds_dwordx4 v78, s[50:51]
	s_mov_b32 m0, s43
	s_nop 0
	global_load_lds_dwordx4 v79, s[50:51]
	s_waitcnt vmcnt(8)
	v_add_u32_e32 v54, s77, v59
	v_add_u32_e32 v55, s77, v60
	v_add_u32_e32 v56, s77, v61
	v_add_u32_e32 v57, s77, v62
	ds_read_b64_tr_b4 v[50:51], v160 offset:896
	ds_read_b64_tr_b4 v[52:53], v160 offset:1920
	ds_read_b64_tr_b4 v[130:131], v54
	ds_read_b64_tr_b4 v[132:133], v55
	ds_read_b64_tr_b4 v[134:135], v56
	ds_read_b64_tr_b4 v[136:137], v57
	s_waitcnt lgkmcnt(6)
	v_dot8c_i32_i4_e32 v38, v122, v48
	v_dot8c_i32_i4_e32 v39, v122, v46
	v_dot8c_i32_i4_e32 v40, v124, v48
	v_dot8c_i32_i4_e32 v41, v124, v46
	v_dot8c_i32_i4_e32 v42, v126, v48
	v_dot8c_i32_i4_e32 v43, v126, v46
	v_dot8c_i32_i4_e32 v44, v128, v48
	v_dot8c_i32_i4_e32 v45, v128, v46
	v_dot8c_i32_i4_e32 v38, v123, v49
	v_dot8c_i32_i4_e32 v39, v123, v47
	v_dot8c_i32_i4_e32 v40, v125, v49
	v_dot8c_i32_i4_e32 v41, v125, v47
	v_dot8c_i32_i4_e32 v42, v127, v49
	v_dot8c_i32_i4_e32 v43, v127, v47
	v_dot8c_i32_i4_e32 v44, v129, v49
	v_dot8c_i32_i4_e32 v45, v129, v47
	v_and_b32_e32 v78, 0xffff, v30
	v_lshrrev_b32_e32 v79, 16, v30
	v_lshl_add_u32 v78, v78, 7, v152
	v_lshl_add_u32 v79, v79, 7, v153
	s_mov_b32 m0, s76
	s_add_i32 s43, s76, 0x400
	global_load_lds_dwordx4 v78, s[50:51]
	s_mov_b32 m0, s43
	s_nop 0
	global_load_lds_dwordx4 v79, s[50:51]
	s_waitcnt vmcnt(8)
; __device__ __forceinline__ void peer_v_tokens(int j, const LAS unsigned short* EL, const LAS unsigned char* AL  , const LAS float* ASC  , const LAS int* SAL  , ...
;     ...
; #pragma unroll
;         for (int st = 0; st < 16; ++st) {
;             const int p = st >> 2, q = st & 3;
;             if (st < 14) VDMA(st + 2, (st + 2) % 3);
;             if (st < 14) asm volatile("s_waitcnt vmcnt(8)" ::: "memory");
;             else if (st == 14) asm volatile("s_waitcnt vmcnt(4)" ::: "memory");
;             else asm volatile("s_waitcnt vmcnt(0)" ::: "memory");
;             if (q == 0) {
; #pragma unroll
;                 for (int r = 0; r < 4; ++r) { accH[r] = 0; accL[r] = 0; } }
; #pragma unroll
;             for (int tp = 0; tp < 2; ++tp) {
;                 const v2i ao = TR4(ATL + (2 * q + tp) * 128 + 8 * s16), ah = TR4(ATL + 1024 + (2 * q + tp) * 128 + 8 * s16);
; #pragma unroll
;                 for (int r = 0; r < 4; ++r) {
;                     const v2i d = TR4(ldsb + BUF[st % 3] + 2048 * tp + roff[r]);
;                     accH[r] = __builtin_amdgcn_sdot8(d.x, ah.x, accH[r], false); accH[r] = __builtin_amdgcn_sdot8(d.y, ah.y, accH[r], false);
;                     accL[r] = __builtin_amdgcn_sdot8(d.x, ao.x, accL[r], false); accL[r] = __builtin_amdgcn_sdot8(d.y, ao.y, accL[r], false);
;                 }
;             }
;             asm volatile("s_waitcnt lgkmcnt(0)" ::: "memory");
;             if (q == 3) {
; #pragma unroll
;                 for (int r = 0; r < 4; ++r) STASH[256 * p + 16 * (grp + 4 * r) + pc] = f2bf(asc * (float)(2 * ((accH[r] << 4) + accL[r]) + sa));
;             }
;         }
;         CFENCE();
;         {
;             float4 v[4]; float ss = 0.f;
; #pragma unroll
;             for (int jq = 0; jq < 4; ++jq) { typedef unsigned u2v __attribute__((ext_vector_type(2))); const u2v pw = *(const LAS u2v*)(STASH + 4 * lane + 256 * jq); const uint2 hw = hv[jq];
;                 v[jq] = make_float4(__uint_as_float(hw.x << 16) + __uint_as_float(pw.x << 16), __uint_as_float(hw.x & 0xffff0000u) + __uint_as_float(pw.x & 0xffff0000u),
;                                     __uint_as_float(hw.y << 16) + __uint_as_float(pw.y << 16), __uint_as_float(hw.y & 0xffff0000u) + __uint_as_float(pw.y & 0xffff0000u));
;                 ss += v[jq].x * v[jq].x + v[jq].y * v[jq].y + v[jq].z * v[jq].z + v[jq].w * v[jq].w; }
;             ss = wave_sum(ss);
	v_add_u32_e32 v54, s78, v59
	v_add_u32_e32 v55, s78, v60
	v_add_u32_e32 v56, s78, v61
	v_add_u32_e32 v57, s78, v62
	ds_read_b64_tr_b4 v[46:47], v160
	ds_read_b64_tr_b4 v[48:49], v160 offset:1024
	ds_read_b64_tr_b4 v[122:123], v54
	ds_read_b64_tr_b4 v[124:125], v55
	ds_read_b64_tr_b4 v[126:127], v56
	ds_read_b64_tr_b4 v[128:129], v57
	s_waitcnt lgkmcnt(6)
	v_dot8c_i32_i4_e32 v38, v130, v52
	v_dot8c_i32_i4_e32 v39, v130, v50
	v_dot8c_i32_i4_e32 v40, v132, v52
	v_dot8c_i32_i4_e32 v41, v132, v50
	v_dot8c_i32_i4_e32 v42, v134, v52
	v_dot8c_i32_i4_e32 v43, v134, v50
	v_dot8c_i32_i4_e32 v44, v136, v52
	v_dot8c_i32_i4_e32 v45, v136, v50
	v_dot8c_i32_i4_e32 v38, v131, v53
	v_dot8c_i32_i4_e32 v39, v131, v51
	v_dot8c_i32_i4_e32 v40, v133, v53
	v_dot8c_i32_i4_e32 v41, v133, v51
	v_dot8c_i32_i4_e32 v42, v135, v53
	v_dot8c_i32_i4_e32 v43, v135, v51
	v_dot8c_i32_i4_e32 v44, v137, v53
	v_dot8c_i32_i4_e32 v45, v137, v51
	s_nop 3
	s_waitcnt lgkmcnt(15)
	v_lshlrev_b32_e32 v38, 5, v38
	v_lshlrev_b32_e32 v39, 1, v39
	v_add3_u32 v38, v39, v229, v38
	v_cvt_f32_i32_e32 v38, v38
	v_mul_f32_e32 v38, v228, v38
	v_lshlrev_b32_e32 v40, 5, v40
	v_lshlrev_b32_e32 v41, 1, v41
	v_add3_u32 v40, v41, v229, v40
	v_cvt_f32_i32_e32 v40, v40
	v_mul_f32_e32 v40, v228, v40
	v_lshlrev_b32_e32 v42, 5, v42
	v_lshlrev_b32_e32 v43, 1, v43
	v_add3_u32 v42, v43, v229, v42
	v_cvt_f32_i32_e32 v42, v42
	v_mul_f32_e32 v42, v228, v42
	v_lshlrev_b32_e32 v44, 5, v44
	v_lshlrev_b32_e32 v45, 1, v45
	v_add3_u32 v44, v45, v229, v44
	v_cvt_f32_i32_e32 v44, v44
	v_mul_f32_e32 v44, v228, v44
	v_cvt_pk_bf16_f32 v164, v38, v40
	v_cvt_pk_bf16_f32 v165, v42, v44
	ds_read_b128 v[252:255], v155 offset:1024
	s_add_i32 s44, s40, 16
	s_ashr_i32 s45, s44, 31
	s_lshl_b64 s[44:45], s[44:45], 12
	v_lshl_add_u64 v[80:81], v[36:37], 0, s[44:45]
	s_waitcnt lgkmcnt(0)
	v_mul_f32_e32 v214, v214, v252
	v_mul_f32_e32 v215, v215, v253
	v_mul_f32_e32 v216, v216, v254
	v_mul_f32_e32 v217, v217, v255
	global_store_dwordx4 v[80:81], v[214:217], off offset:1024 nt
	v_add_u32_e32 v147, 8, v140
	v_and_b32_e32 v146, 15, v147
	v_xor_b32_e32 v146, 8, v146
	v_bfe_u32 v148, v147, 4, 4
	v_mul_lo_u32 v146, v146, s92
	v_mul_lo_u32 v148, v148, s92
	v_mov_b32_e32 v147, v146
	v_mov_b32_e32 v149, v148
	ds_write2st64_b64 v77, v[146:147], v[148:149] offset1:2
	v_add_u32_e32 v138, 0x1000, v74
	ds_read_u8 v139, v138
	v_add_u32_e32 v141, 0x1000, v73
	ds_read_u8 v140, v141
	s_add_i32 s43, s67, 160
	v_mov_b32_e32 v138, s43
	ds_read2st64_b32 v[228:229], v138 offset1:1
	ds_read_b128 v[18:21], v227 offset:8192
	ds_read_b128 v[22:25], v227 offset:8208
	v_add_u32_e32 v150, 0x400000, v63
	v_add_u32_e32 v151, 0x400000, v64
	v_mov_b32_e32 v38, 0
	v_mov_b32_e32 v39, 0
	v_mov_b32_e32 v40, 0
	v_mov_b32_e32 v41, 0
	v_mov_b32_e32 v42, 0
	v_mov_b32_e32 v43, 0
	v_mov_b32_e32 v44, 0
	v_mov_b32_e32 v45, 0
	v_and_b32_e32 v78, 0xffff, v31
	v_lshrrev_b32_e32 v79, 16, v31
	v_lshl_add_u32 v78, v78, 7, v152
	v_lshl_add_u32 v79, v79, 7, v153
	s_mov_b32 m0, s77
	s_add_i32 s43, s77, 0x400
	global_load_lds_dwordx4 v78, s[50:51]
	s_mov_b32 m0, s43
	s_nop 0
	global_load_lds_dwordx4 v79, s[50:51]
	s_waitcnt vmcnt(9)
	v_add_u32_e32 v54, s79, v59
	v_add_u32_e32 v55, s79, v60
	v_add_u32_e32 v56, s79, v61
	v_add_u32_e32 v57, s79, v62
	ds_read_b64_tr_b4 v[50:51], v160 offset:128
	ds_read_b64_tr_b4 v[52:53], v160 offset:1152
	ds_read_b64_tr_b4 v[130:131], v54
	ds_read_b64_tr_b4 v[132:133], v55
	ds_read_b64_tr_b4 v[134:135], v56
	ds_read_b64_tr_b4 v[136:137], v57
	s_waitcnt lgkmcnt(13)
	v_dot8c_i32_i4_e32 v38, v122, v48
	v_dot8c_i32_i4_e32 v39, v122, v46
	v_dot8c_i32_i4_e32 v40, v124, v48
	v_dot8c_i32_i4_e32 v41, v124, v46
	v_dot8c_i32_i4_e32 v42, v126, v48
	v_dot8c_i32_i4_e32 v43, v126, v46
	v_dot8c_i32_i4_e32 v44, v128, v48
	v_dot8c_i32_i4_e32 v45, v128, v46
	v_dot8c_i32_i4_e32 v38, v123, v49
	v_dot8c_i32_i4_e32 v39, v123, v47
	v_dot8c_i32_i4_e32 v40, v125, v49
	v_dot8c_i32_i4_e32 v41, v125, v47
	v_dot8c_i32_i4_e32 v42, v127, v49
	v_dot8c_i32_i4_e32 v43, v127, v47
	v_dot8c_i32_i4_e32 v44, v129, v49
	v_dot8c_i32_i4_e32 v45, v129, v47
	v_and_b32_e32 v78, 0xffff, v32
	v_lshrrev_b32_e32 v79, 16, v32
	v_lshl_add_u32 v78, v78, 7, v152
	v_lshl_add_u32 v79, v79, 7, v153
	s_mov_b32 m0, s78
	s_add_i32 s43, s78, 0x400
	global_load_lds_dwordx4 v78, s[50:51]
	s_mov_b32 m0, s43
	s_nop 0
	global_load_lds_dwordx4 v79, s[50:51]
	s_waitcnt vmcnt(9)
	v_add_u32_e32 v54, s98, v59
	v_add_u32_e32 v55, s98, v60
	v_add_u32_e32 v56, s98, v61
	v_add_u32_e32 v57, s98, v62
	ds_read_b64_tr_b4 v[46:47], v160 offset:256
	ds_read_b64_tr_b4 v[48:49], v160 offset:1280
	ds_read_b64_tr_b4 v[122:123], v54
	ds_read_b64_tr_b4 v[124:125], v55
	ds_read_b64_tr_b4 v[126:127], v56
	ds_read_b64_tr_b4 v[128:129], v57
	s_waitcnt lgkmcnt(6)
	v_dot8c_i32_i4_e32 v38, v130, v52
	v_dot8c_i32_i4_e32 v39, v130, v50
	v_dot8c_i32_i4_e32 v40, v132, v52
	v_dot8c_i32_i4_e32 v41, v132, v50
	v_dot8c_i32_i4_e32 v42, v134, v52
	v_dot8c_i32_i4_e32 v43, v134, v50
	v_dot8c_i32_i4_e32 v44, v136, v52
	v_dot8c_i32_i4_e32 v45, v136, v50
	v_dot8c_i32_i4_e32 v38, v131, v53
	v_dot8c_i32_i4_e32 v39, v131, v51
	v_dot8c_i32_i4_e32 v40, v133, v53
	v_dot8c_i32_i4_e32 v41, v133, v51
	v_dot8c_i32_i4_e32 v42, v135, v53
	v_dot8c_i32_i4_e32 v43, v135, v51
	v_dot8c_i32_i4_e32 v44, v137, v53
	v_dot8c_i32_i4_e32 v45, v137, v51
	ds_write_b16 v65, v186
	ds_write_b16_d16_hi v65, v186 offset:128
	ds_write_b16 v65, v187 offset:256
	ds_write_b16_d16_hi v65, v187 offset:384
	ds_write_b16 v65, v188 offset:512
	ds_write_b16_d16_hi v65, v188 offset:640
	ds_write_b16 v65, v189 offset:768
	ds_write_b16_d16_hi v65, v189 offset:896
	ds_write_b16 v65, v190 offset:1024
	ds_write_b16_d16_hi v65, v190 offset:1152
	ds_write_b16 v65, v191 offset:1280
	ds_write_b16_d16_hi v65, v191 offset:1408
	ds_write_b16 v65, v192 offset:1536
	ds_write_b16_d16_hi v65, v192 offset:1664
	ds_write_b16 v65, v193 offset:1792
	ds_write_b16_d16_hi v65, v193 offset:1920
	ds_read_b64 v[202:203], v154
	ds_read_b64 v[204:205], v154 offset:512
	ds_read_b64 v[206:207], v154 offset:1024
	ds_read_b64 v[208:209], v154 offset:1536
	v_and_b32_e32 v78, 0xffff, v33
	v_lshrrev_b32_e32 v79, 16, v33
	v_lshl_add_u32 v78, v78, 7, v152
	v_lshl_add_u32 v79, v79, 7, v153
	s_mov_b32 m0, s79
	s_add_i32 s43, s79, 0x400
	global_load_lds_dwordx4 v78, s[50:51]
	s_mov_b32 m0, s43
	s_nop 0
	global_load_lds_dwordx4 v79, s[50:51]
	s_waitcnt vmcnt(9)
; __device__ __forceinline__ void peer_v_tokens(int j, const LAS unsigned short* EL, const LAS unsigned char* AL  , const LAS float* ASC  , const LAS int* SAL  , ...
;     ...
; #pragma unroll 1
;     for (int it = 0; it < 8; ++it) {
;         const int tl = it * 8 + wave, t = j * 64 + tl;
;         unsigned E[8];
;         { const LAS v4u* ep = (const LAS v4u*)(EL + tl * 128 + 16 * g); const v4u e0 = ep[0], e1 = ep[1];
;           E[0] = e0.x; E[1] = e0.y; E[2] = e0.z; E[3] = e0.w; E[4] = e1.x; E[5] = e1.y; E[6] = e1.z; E[7] = e1.w; }
;         uint2 hv[4]; float4 gv[4];
;         { unsigned ho = (unsigned)t * (D / 4) + (unsigned)lane; asm volatile("" : "+v"(ho)); const uint2* hp = (const uint2*)HB + ho; const float4* gp = (const float4*)fng + lane;
; #pragma unroll
;           for (int jq = 0; jq < 4; ++jq) { hv[jq] = hp[64 * jq]; gv[jq] = gp[64 * jq]; } }
;         VDMA(0, 0); VDMA(1, 1);
; #pragma unroll
;         for (int m = 0; m < 2; ++m) {
;             const int idx = lane + 64 * m, tau = idx >> 4, sr = idx & 15, k = 16 * (sr & 7) + 2 * tau + (sr >> 3);
;             const int aq = (int)*(const LAS signed char*)(AL + tl * 128 + k); const int tq = aq + 8;
;             const unsigned lo = (((unsigned)tq & 15u) ^ 8u) * 0x11111111u, hi = ((unsigned)(tq >> 4) & 15u) * 0x11111111u;
;             typedef unsigned u2v __attribute__((ext_vector_type(2)));
;             u2v l2; l2.x = lo; l2.y = lo; u2v h2; h2.x = hi; h2.y = hi;
;             *(LAS u2v*)(ATL + 8 * idx) = l2; *(LAS u2v*)(ATL + 1024 + 8 * idx) = h2;
;         }
;         const float asc = ASC[tl]; const int sa = SAL[tl];
;         CFENCE();
;         int accH[4], accL[4];
; #pragma unroll
;         for (int st = 0; st < 16; ++st) {
;             const int p = st >> 2, q = st & 3;
;             if (st < 14) VDMA(st + 2, (st + 2) % 3);
;             if (st < 14) asm volatile("s_waitcnt vmcnt(8)" ::: "memory");
;             else if (st == 14) asm volatile("s_waitcnt vmcnt(4)" ::: "memory");
;             else asm volatile("s_waitcnt vmcnt(0)" ::: "memory");
;             if (q == 0) {
; #pragma unroll
;                 for (int r = 0; r < 4; ++r) { accH[r] = 0; accL[r] = 0; } }
; #pragma unroll
;             for (int tp = 0; tp < 2; ++tp) {
;                 const v2i ao = TR4(ATL + (2 * q + tp) * 128 + 8 * s16), ah = TR4(ATL + 1024 + (2 * q + tp) * 128 + 8 * s16);
; #pragma unroll
	v_add_u32_e32 v54, s99, v59
	v_add_u32_e32 v55, s99, v60
	v_add_u32_e32 v56, s99, v61
	v_add_u32_e32 v57, s99, v62
	ds_read_b64_tr_b4 v[50:51], v160 offset:384
	ds_read_b64_tr_b4 v[52:53], v160 offset:1408
	ds_read_b64_tr_b4 v[130:131], v54
	ds_read_b64_tr_b4 v[132:133], v55
	ds_read_b64_tr_b4 v[134:135], v56
	ds_read_b64_tr_b4 v[136:137], v57
	s_waitcnt lgkmcnt(15)
	v_dot8c_i32_i4_e32 v38, v122, v48
	v_dot8c_i32_i4_e32 v39, v122, v46
	v_dot8c_i32_i4_e32 v40, v124, v48
	v_dot8c_i32_i4_e32 v41, v124, v46
	v_dot8c_i32_i4_e32 v42, v126, v48
	v_dot8c_i32_i4_e32 v43, v126, v46
	v_dot8c_i32_i4_e32 v44, v128, v48
	v_dot8c_i32_i4_e32 v45, v128, v46
	v_dot8c_i32_i4_e32 v38, v123, v49
	v_dot8c_i32_i4_e32 v39, v123, v47
	v_dot8c_i32_i4_e32 v40, v125, v49
	v_dot8c_i32_i4_e32 v41, v125, v47
	v_dot8c_i32_i4_e32 v42, v127, v49
	v_dot8c_i32_i4_e32 v43, v127, v47
	v_dot8c_i32_i4_e32 v44, v129, v49
	v_dot8c_i32_i4_e32 v45, v129, v47
	s_waitcnt lgkmcnt(15)
	v_and_b32_e32 v78, 0xffff, v18
	v_lshrrev_b32_e32 v79, 16, v18
	v_lshl_add_u32 v78, v78, 7, v150
	v_lshl_add_u32 v79, v79, 7, v151
	s_mov_b32 m0, s98
	s_add_i32 s43, s98, 0x400
	global_load_lds_dwordx4 v78, s[50:51]
	s_mov_b32 m0, s43
	s_nop 0
	global_load_lds_dwordx4 v79, s[50:51]
	s_waitcnt vmcnt(9)
	v_add_u32_e32 v54, s76, v59
	v_add_u32_e32 v55, s76, v60
	v_add_u32_e32 v56, s76, v61
	v_add_u32_e32 v57, s76, v62
	ds_read_b64_tr_b4 v[46:47], v160 offset:512
	ds_read_b64_tr_b4 v[48:49], v160 offset:1536
	ds_read_b64_tr_b4 v[122:123], v54
	ds_read_b64_tr_b4 v[124:125], v55
	ds_read_b64_tr_b4 v[126:127], v56
	ds_read_b64_tr_b4 v[128:129], v57
	s_waitcnt lgkmcnt(6)
	v_dot8c_i32_i4_e32 v38, v130, v52
	v_dot8c_i32_i4_e32 v39, v130, v50
	v_dot8c_i32_i4_e32 v40, v132, v52
	v_dot8c_i32_i4_e32 v41, v132, v50
	v_dot8c_i32_i4_e32 v42, v134, v52
	v_dot8c_i32_i4_e32 v43, v134, v50
	v_dot8c_i32_i4_e32 v44, v136, v52
	v_dot8c_i32_i4_e32 v45, v136, v50
	v_dot8c_i32_i4_e32 v38, v131, v53
	v_dot8c_i32_i4_e32 v39, v131, v51
	v_dot8c_i32_i4_e32 v40, v133, v53
	v_dot8c_i32_i4_e32 v41, v133, v51
	v_dot8c_i32_i4_e32 v42, v135, v53
	v_dot8c_i32_i4_e32 v43, v135, v51
	v_dot8c_i32_i4_e32 v44, v137, v53
	v_dot8c_i32_i4_e32 v45, v137, v51
	v_and_b32_e32 v78, 0xffff, v19
	v_lshrrev_b32_e32 v79, 16, v19
	v_lshl_add_u32 v78, v78, 7, v150
	v_lshl_add_u32 v79, v79, 7, v151
	s_mov_b32 m0, s99
	s_add_i32 s43, s99, 0x400
	global_load_lds_dwordx4 v78, s[50:51]
	s_mov_b32 m0, s43
	s_nop 0
	global_load_lds_dwordx4 v79, s[50:51]
	s_waitcnt vmcnt(8)
	v_add_u32_e32 v54, s77, v59
	v_add_u32_e32 v55, s77, v60
	v_add_u32_e32 v56, s77, v61
	v_add_u32_e32 v57, s77, v62
	ds_read_b64_tr_b4 v[50:51], v160 offset:640
	ds_read_b64_tr_b4 v[52:53], v160 offset:1664
	ds_read_b64_tr_b4 v[130:131], v54
	ds_read_b64_tr_b4 v[132:133], v55
	ds_read_b64_tr_b4 v[134:135], v56
	ds_read_b64_tr_b4 v[136:137], v57
	s_waitcnt lgkmcnt(6)
	v_dot8c_i32_i4_e32 v38, v122, v48
	v_dot8c_i32_i4_e32 v39, v122, v46
	v_dot8c_i32_i4_e32 v40, v124, v48
	v_dot8c_i32_i4_e32 v41, v124, v46
	v_dot8c_i32_i4_e32 v42, v126, v48
	v_dot8c_i32_i4_e32 v43, v126, v46
	v_dot8c_i32_i4_e32 v44, v128, v48
	v_dot8c_i32_i4_e32 v45, v128, v46
	v_dot8c_i32_i4_e32 v38, v123, v49
	v_dot8c_i32_i4_e32 v39, v123, v47
	v_dot8c_i32_i4_e32 v40, v125, v49
	v_dot8c_i32_i4_e32 v41, v125, v47
	v_dot8c_i32_i4_e32 v42, v127, v49
	v_dot8c_i32_i4_e32 v43, v127, v47
	v_dot8c_i32_i4_e32 v44, v129, v49
	v_dot8c_i32_i4_e32 v45, v129, v47
	s_waitcnt lgkmcnt(15)
	v_add_u32_e32 v143, 8, v139
	v_and_b32_e32 v142, 15, v143
	v_xor_b32_e32 v142, 8, v142
	v_bfe_u32 v144, v143, 4, 4
	v_mul_lo_u32 v142, v142, s92
	v_mul_lo_u32 v144, v144, s92
	v_mov_b32_e32 v143, v142
	v_mov_b32_e32 v145, v144
	ds_write2st64_b64 v159, v[142:143], v[144:145] offset1:2
	v_and_b32_e32 v78, 0xffff, v20
	v_lshrrev_b32_e32 v79, 16, v20
	v_lshl_add_u32 v78, v78, 7, v150
	v_lshl_add_u32 v79, v79, 7, v151
	s_mov_b32 m0, s76
	s_add_i32 s43, s76, 0x400
	global_load_lds_dwordx4 v78, s[50:51]
	s_mov_b32 m0, s43
	s_nop 0
	global_load_lds_dwordx4 v79, s[50:51]
	s_waitcnt vmcnt(8)
	v_add_u32_e32 v54, s78, v59
	v_add_u32_e32 v55, s78, v60
	v_add_u32_e32 v56, s78, v61
	v_add_u32_e32 v57, s78, v62
	ds_read_b64_tr_b4 v[46:47], v160 offset:768
	ds_read_b64_tr_b4 v[48:49], v160 offset:1792
	ds_read_b64_tr_b4 v[122:123], v54
	ds_read_b64_tr_b4 v[124:125], v55
	ds_read_b64_tr_b4 v[126:127], v56
	ds_read_b64_tr_b4 v[128:129], v57
	s_waitcnt lgkmcnt(7)
	v_dot8c_i32_i4_e32 v38, v130, v52
	v_dot8c_i32_i4_e32 v39, v130, v50
	v_dot8c_i32_i4_e32 v40, v132, v52
	v_dot8c_i32_i4_e32 v41, v132, v50
	v_dot8c_i32_i4_e32 v42, v134, v52
	v_dot8c_i32_i4_e32 v43, v134, v50
	v_dot8c_i32_i4_e32 v44, v136, v52
	v_dot8c_i32_i4_e32 v45, v136, v50
	v_dot8c_i32_i4_e32 v38, v131, v53
	v_dot8c_i32_i4_e32 v39, v131, v51
	v_dot8c_i32_i4_e32 v40, v133, v53
	v_dot8c_i32_i4_e32 v41, v133, v51
	v_dot8c_i32_i4_e32 v42, v135, v53
	v_dot8c_i32_i4_e32 v43, v135, v51
	v_dot8c_i32_i4_e32 v44, v137, v53
	v_dot8c_i32_i4_e32 v45, v137, v51
	v_and_b32_e32 v78, 0xffff, v21
	v_lshrrev_b32_e32 v79, 16, v21
	v_lshl_add_u32 v78, v78, 7, v150
	v_lshl_add_u32 v79, v79, 7, v151
	s_mov_b32 m0, s77
	s_add_i32 s43, s77, 0x400
	global_load_lds_dwordx4 v78, s[50:51]
	s_mov_b32 m0, s43
	s_nop 0
	global_load_lds_dwordx4 v79, s[50:51]
	s_waitcnt vmcnt(8)
	v_add_u32_e32 v54, s79, v59
	v_add_u32_e32 v55, s79, v60
	v_add_u32_e32 v56, s79, v61
	v_add_u32_e32 v57, s79, v62
	ds_read_b64_tr_b4 v[50:51], v160 offset:896
	ds_read_b64_tr_b4 v[52:53], v160 offset:1920
	ds_read_b64_tr_b4 v[130:131], v54
	ds_read_b64_tr_b4 v[132:133], v55
	ds_read_b64_tr_b4 v[134:135], v56
	ds_read_b64_tr_b4 v[136:137], v57
	s_waitcnt lgkmcnt(6)
; __device__ __forceinline__ void peer_v_tokens(int j, const LAS unsigned short* EL, const LAS unsigned char* AL  , const LAS float* ASC  , const LAS int* SAL  , ...
;     ...
; #pragma unroll
;         for (int st = 0; st < 16; ++st) {
;             const int p = st >> 2, q = st & 3;
;             if (st < 14) VDMA(st + 2, (st + 2) % 3);
;             if (st < 14) asm volatile("s_waitcnt vmcnt(8)" ::: "memory");
;             else if (st == 14) asm volatile("s_waitcnt vmcnt(4)" ::: "memory");
;             else asm volatile("s_waitcnt vmcnt(0)" ::: "memory");
;             if (q == 0) {
; #pragma unroll
;                 for (int r = 0; r < 4; ++r) { accH[r] = 0; accL[r] = 0; } }
; #pragma unroll
;             for (int tp = 0; tp < 2; ++tp) {
;                 const v2i ao = TR4(ATL + (2 * q + tp) * 128 + 8 * s16), ah = TR4(ATL + 1024 + (2 * q + tp) * 128 + 8 * s16);
; #pragma unroll
;                 for (int r = 0; r < 4; ++r) {
;                     const v2i d = TR4(ldsb + BUF[st % 3] + 2048 * tp + roff[r]);
;                     accH[r] = __builtin_amdgcn_sdot8(d.x, ah.x, accH[r], false); accH[r] = __builtin_amdgcn_sdot8(d.y, ah.y, accH[r], false);
;                     accL[r] = __builtin_amdgcn_sdot8(d.x, ao.x, accL[r], false); accL[r] = __builtin_amdgcn_sdot8(d.y, ao.y, accL[r], false);
;                 }
;             }
;             asm volatile("s_waitcnt lgkmcnt(0)" ::: "memory");
;             if (q == 3) {
; #pragma unroll
;                 for (int r = 0; r < 4; ++r) STASH[256 * p + 16 * (grp + 4 * r) + pc] = f2bf(asc * (float)(2 * ((accH[r] << 4) + accL[r]) + sa));
;             }
;         }
;         CFENCE();
;         {
;             float4 v[4]; float ss = 0.f;
; #pragma unroll
;             for (int jq = 0; jq < 4; ++jq) { typedef unsigned u2v __attribute__((ext_vector_type(2))); const u2v pw = *(const LAS u2v*)(STASH + 4 * lane + 256 * jq); const uint2 hw = hv[jq];
;                 v[jq] = make_float4(__uint_as_float(hw.x << 16) + __uint_as_float(pw.x << 16), __uint_as_float(hw.x & 0xffff0000u) + __uint_as_float(pw.x & 0xffff0000u),
;                                     __uint_as_float(hw.y << 16) + __uint_as_float(pw.y << 16), __uint_as_float(hw.y & 0xffff0000u) + __uint_as_float(pw.y & 0xffff0000u));
;                 ss += v[jq].x * v[jq].x + v[jq].y * v[jq].y + v[jq].z * v[jq].z + v[jq].w * v[jq].w; }
;             ss = wave_sum(ss);
	v_dot8c_i32_i4_e32 v38, v122, v48
	v_dot8c_i32_i4_e32 v39, v122, v46
	v_dot8c_i32_i4_e32 v40, v124, v48
	v_dot8c_i32_i4_e32 v41, v124, v46
	v_dot8c_i32_i4_e32 v42, v126, v48
	v_dot8c_i32_i4_e32 v43, v126, v46
	v_dot8c_i32_i4_e32 v44, v128, v48
	v_dot8c_i32_i4_e32 v45, v128, v46
	v_dot8c_i32_i4_e32 v38, v123, v49
	v_dot8c_i32_i4_e32 v39, v123, v47
	v_dot8c_i32_i4_e32 v40, v125, v49
	v_dot8c_i32_i4_e32 v41, v125, v47
	v_dot8c_i32_i4_e32 v42, v127, v49
	v_dot8c_i32_i4_e32 v43, v127, v47
	v_dot8c_i32_i4_e32 v44, v129, v49
	v_dot8c_i32_i4_e32 v45, v129, v47
	v_and_b32_e32 v78, 0xffff, v22
	v_lshrrev_b32_e32 v79, 16, v22
	v_lshl_add_u32 v78, v78, 7, v150
	v_lshl_add_u32 v79, v79, 7, v151
	s_mov_b32 m0, s78
	s_add_i32 s43, s78, 0x400
	global_load_lds_dwordx4 v78, s[50:51]
	s_mov_b32 m0, s43
	s_nop 0
	global_load_lds_dwordx4 v79, s[50:51]
	s_waitcnt vmcnt(8)
	v_add_u32_e32 v54, s98, v59
	v_add_u32_e32 v55, s98, v60
	v_add_u32_e32 v56, s98, v61
	v_add_u32_e32 v57, s98, v62
	ds_read_b64_tr_b4 v[46:47], v160
	ds_read_b64_tr_b4 v[48:49], v160 offset:1024
	ds_read_b64_tr_b4 v[122:123], v54
	ds_read_b64_tr_b4 v[124:125], v55
	ds_read_b64_tr_b4 v[126:127], v56
	ds_read_b64_tr_b4 v[128:129], v57
	s_waitcnt lgkmcnt(6)
	v_dot8c_i32_i4_e32 v38, v130, v52
	v_dot8c_i32_i4_e32 v39, v130, v50
	v_dot8c_i32_i4_e32 v40, v132, v52
	v_dot8c_i32_i4_e32 v41, v132, v50
	v_dot8c_i32_i4_e32 v42, v134, v52
	v_dot8c_i32_i4_e32 v43, v134, v50
	v_dot8c_i32_i4_e32 v44, v136, v52
	v_dot8c_i32_i4_e32 v45, v136, v50
	v_dot8c_i32_i4_e32 v38, v131, v53
	v_dot8c_i32_i4_e32 v39, v131, v51
	v_dot8c_i32_i4_e32 v40, v133, v53
	v_dot8c_i32_i4_e32 v41, v133, v51
	v_dot8c_i32_i4_e32 v42, v135, v53
	v_dot8c_i32_i4_e32 v43, v135, v51
	v_dot8c_i32_i4_e32 v44, v137, v53
	v_dot8c_i32_i4_e32 v45, v137, v51
	s_nop 3
	s_waitcnt lgkmcnt(15)
	v_lshlrev_b32_e32 v38, 5, v38
	v_lshlrev_b32_e32 v39, 1, v39
	v_add3_u32 v38, v39, v229, v38
	v_cvt_f32_i32_e32 v38, v38
	v_mul_f32_e32 v38, v228, v38
	v_lshlrev_b32_e32 v40, 5, v40
	v_lshlrev_b32_e32 v41, 1, v41
	v_add3_u32 v40, v41, v229, v40
	v_cvt_f32_i32_e32 v40, v40
	v_mul_f32_e32 v40, v228, v40
	v_lshlrev_b32_e32 v42, 5, v42
	v_lshlrev_b32_e32 v43, 1, v43
	v_add3_u32 v42, v43, v229, v42
	v_cvt_f32_i32_e32 v42, v42
	v_mul_f32_e32 v42, v228, v42
	v_lshlrev_b32_e32 v44, 5, v44
	v_lshlrev_b32_e32 v45, 1, v45
	v_add3_u32 v44, v45, v229, v44
	v_cvt_f32_i32_e32 v44, v44
	v_mul_f32_e32 v44, v228, v44
	v_cvt_pk_bf16_f32 v172, v38, v40
	v_cvt_pk_bf16_f32 v173, v42, v44
	ds_read_b128 v[252:255], v156
	s_add_i32 s44, s40, 16
	s_ashr_i32 s45, s44, 31
	s_lshl_b64 s[44:45], s[44:45], 12
	v_lshl_add_u64 v[80:81], v[36:37], 0, s[44:45]
	s_waitcnt lgkmcnt(0)
	v_mul_f32_e32 v218, v218, v252
	v_mul_f32_e32 v219, v219, v253
	v_mul_f32_e32 v220, v220, v254
	v_mul_f32_e32 v221, v221, v255
	global_store_dwordx4 v[80:81], v[218:221], off offset:2048 nt
	v_add_u32_e32 v147, 8, v140
	v_and_b32_e32 v146, 15, v147
	v_xor_b32_e32 v146, 8, v146
	v_bfe_u32 v148, v147, 4, 4
	v_mul_lo_u32 v146, v146, s92
	v_mul_lo_u32 v148, v148, s92
	v_mov_b32_e32 v147, v146
	v_mov_b32_e32 v149, v148
	ds_write2st64_b64 v77, v[146:147], v[148:149] offset1:2
	v_add_u32_e32 v138, 0x1400, v74
	ds_read_u8 v139, v138
	v_add_u32_e32 v141, 0x1400, v73
	ds_read_u8 v140, v141
	s_add_i32 s43, s67, 128
	v_mov_b32_e32 v138, s43
	ds_read2st64_b32 v[228:229], v138 offset1:1
	ds_read_b128 v[26:29], v227 offset:10240
	ds_read_b128 v[30:33], v227 offset:10256
	v_mov_b32_e32 v38, 0
	v_mov_b32_e32 v39, 0
	v_mov_b32_e32 v40, 0
	v_mov_b32_e32 v41, 0
	v_mov_b32_e32 v42, 0
	v_mov_b32_e32 v43, 0
	v_mov_b32_e32 v44, 0
	v_mov_b32_e32 v45, 0
	v_and_b32_e32 v78, 0xffff, v23
	v_lshrrev_b32_e32 v79, 16, v23
	v_lshl_add_u32 v78, v78, 7, v150
	v_lshl_add_u32 v79, v79, 7, v151
	s_mov_b32 m0, s79
	s_add_i32 s43, s79, 0x400
	global_load_lds_dwordx4 v78, s[50:51]
	s_mov_b32 m0, s43
	s_nop 0
	global_load_lds_dwordx4 v79, s[50:51]
	s_waitcnt vmcnt(9)
	v_add_u32_e32 v54, s99, v59
	v_add_u32_e32 v55, s99, v60
	v_add_u32_e32 v56, s99, v61
	v_add_u32_e32 v57, s99, v62
	ds_read_b64_tr_b4 v[50:51], v160 offset:128
	ds_read_b64_tr_b4 v[52:53], v160 offset:1152
	ds_read_b64_tr_b4 v[130:131], v54
	ds_read_b64_tr_b4 v[132:133], v55
	ds_read_b64_tr_b4 v[134:135], v56
	ds_read_b64_tr_b4 v[136:137], v57
	s_waitcnt lgkmcnt(13)
	s_waitcnt vmcnt(36) lgkmcnt(15)
; #define LAS __attribute__((address_space(3)))
; __device__ __forceinline__ void peer_v_tokens(int j, const LAS unsigned short* EL, const LAS unsigned char* AL  , const LAS float* ASC  , const LAS int* SAL  , ...
;     ...
; #pragma unroll 1
;     for (int it = 0; it < 8; ++it) {
;         const int tl = it * 8 + wave, t = j * 64 + tl;
;         unsigned E[8];
;         { const LAS v4u* ep = (const LAS v4u*)(EL + tl * 128 + 16 * g); const v4u e0 = ep[0], e1 = ep[1];
;           E[0] = e0.x; E[1] = e0.y; E[2] = e0.z; E[3] = e0.w; E[4] = e1.x; E[5] = e1.y; E[6] = e1.z; E[7] = e1.w; }
;         uint2 hv[4]; float4 gv[4];
;         { unsigned ho = (unsigned)t * (D / 4) + (unsigned)lane; asm volatile("" : "+v"(ho)); const uint2* hp = (const uint2*)HB + ho; const float4* gp = (const float4*)fng + lane;
; #pragma unroll
;           for (int jq = 0; jq < 4; ++jq) { hv[jq] = hp[64 * jq]; gv[jq] = gp[64 * jq]; } }
;         VDMA(0, 0); VDMA(1, 1);
; #pragma unroll
;         for (int m = 0; m < 2; ++m) {
;             const int idx = lane + 64 * m, tau = idx >> 4, sr = idx & 15, k = 16 * (sr & 7) + 2 * tau + (sr >> 3);
;             const int aq = (int)*(const LAS signed char*)(AL + tl * 128 + k); const int tq = aq + 8;
;             const unsigned lo = (((unsigned)tq & 15u) ^ 8u) * 0x11111111u, hi = ((unsigned)(tq >> 4) & 15u) * 0x11111111u;
;             typedef unsigned u2v __attribute__((ext_vector_type(2)));
;             u2v l2; l2.x = lo; l2.y = lo; u2v h2; h2.x = hi; h2.y = hi;
;     ...
;         {
;             float4 v[4]; float ss = 0.f;
; #pragma unroll
;             for (int jq = 0; jq < 4; ++jq) { typedef unsigned u2v __attribute__((ext_vector_type(2))); const u2v pw = *(const LAS u2v*)(STASH + 4 * lane + 256 * jq); const uint2 hw = hv[jq];
;                 v[jq] = make_float4(__uint_as_float(hw.x << 16) + __uint_as_float(pw.x << 16), __uint_as_float(hw.x & 0xffff0000u) + __uint_as_float(pw.x & 0xffff0000u),
;                                     __uint_as_float(hw.y << 16) + __uint_as_float(pw.y << 16), __uint_as_float(hw.y & 0xffff0000u) + __uint_as_float(pw.y & 0xffff0000u));
;                 ss += v[jq].x * v[jq].x + v[jq].y * v[jq].y + v[jq].z * v[jq].z + v[jq].w * v[jq].w; }
;             ss = wave_sum(ss);
;             const float r3 = rsqrtf(ss * (1.f / D) + EPS);
;             float4* op = (float4*)(outp + (size_t)t * D) + lane;
	v_lshlrev_b32_e32 v236, 16, v194
	v_and_b32_e32 v237, 0xffff0000, v194
	v_lshlrev_b32_e32 v142, 16, v202
	v_and_b32_e32 v143, 0xffff0000, v202
	v_add_f32_e32 v236, v236, v142
	v_add_f32_e32 v237, v237, v143
	v_lshlrev_b32_e32 v238, 16, v195
	v_and_b32_e32 v239, 0xffff0000, v195
	v_lshlrev_b32_e32 v142, 16, v203
	v_and_b32_e32 v143, 0xffff0000, v203
	v_add_f32_e32 v238, v238, v142
	v_add_f32_e32 v239, v239, v143
	v_lshlrev_b32_e32 v240, 16, v196
	v_and_b32_e32 v241, 0xffff0000, v196
	v_lshlrev_b32_e32 v142, 16, v204
	v_and_b32_e32 v143, 0xffff0000, v204
	v_add_f32_e32 v240, v240, v142
	v_add_f32_e32 v241, v241, v143
	v_lshlrev_b32_e32 v242, 16, v197
	v_and_b32_e32 v243, 0xffff0000, v197
	v_lshlrev_b32_e32 v142, 16, v205
	v_and_b32_e32 v143, 0xffff0000, v205
	v_add_f32_e32 v242, v242, v142
	v_add_f32_e32 v243, v243, v143
	v_lshlrev_b32_e32 v244, 16, v198
	v_and_b32_e32 v245, 0xffff0000, v198
	v_lshlrev_b32_e32 v142, 16, v206
	v_and_b32_e32 v143, 0xffff0000, v206
	v_add_f32_e32 v244, v244, v142
	v_add_f32_e32 v245, v245, v143
	v_lshlrev_b32_e32 v246, 16, v199
	v_and_b32_e32 v247, 0xffff0000, v199
	v_lshlrev_b32_e32 v142, 16, v207
	v_and_b32_e32 v143, 0xffff0000, v207
	v_add_f32_e32 v246, v246, v142
	v_add_f32_e32 v247, v247, v143
	v_lshlrev_b32_e32 v248, 16, v200
	v_and_b32_e32 v249, 0xffff0000, v200
	v_lshlrev_b32_e32 v142, 16, v208
	v_and_b32_e32 v143, 0xffff0000, v208
	v_add_f32_e32 v248, v248, v142
	v_add_f32_e32 v249, v249, v143
	v_lshlrev_b32_e32 v250, 16, v201
	v_and_b32_e32 v251, 0xffff0000, v201
	v_lshlrev_b32_e32 v142, 16, v209
	v_and_b32_e32 v143, 0xffff0000, v209
	v_add_f32_e32 v250, v250, v142
	v_add_f32_e32 v251, v251, v143
	v_mov_b32_e32 v144, 0
	v_mul_f32_e32 v145, v236, v236
	v_fmac_f32_e32 v145, v237, v237
	v_fmac_f32_e32 v145, v238, v238
	v_fmac_f32_e32 v145, v239, v239
	v_add_f32_e32 v144, v144, v145
	v_mul_f32_e32 v145, v240, v240
	v_fmac_f32_e32 v145, v241, v241
	v_fmac_f32_e32 v145, v242, v242
	v_fmac_f32_e32 v145, v243, v243
	v_add_f32_e32 v144, v144, v145
	v_mul_f32_e32 v145, v244, v244
	v_fmac_f32_e32 v145, v245, v245
	v_fmac_f32_e32 v145, v246, v246
	v_fmac_f32_e32 v145, v247, v247
	v_add_f32_e32 v144, v144, v145
	v_mul_f32_e32 v145, v248, v248
	v_fmac_f32_e32 v145, v249, v249
	v_fmac_f32_e32 v145, v250, v250
	v_fmac_f32_e32 v145, v251, v251
	v_add_f32_e32 v144, v144, v145
	s_nop 1
	v_add_f32_dpp v144, v144, v144 quad_perm:[1,0,3,2] row_mask:0xf bank_mask:0xf bound_ctrl:1
	s_nop 1
	v_add_f32_dpp v144, v144, v144 quad_perm:[2,3,0,1] row_mask:0xf bank_mask:0xf bound_ctrl:1
	s_nop 1
	v_add_f32_dpp v144, v144, v144 row_half_mirror row_mask:0xf bank_mask:0xf bound_ctrl:1
	s_nop 1
	v_add_f32_dpp v144, v144, v144 row_mirror row_mask:0xf bank_mask:0xf bound_ctrl:1
	s_nop 1
	v_readlane_b32 s10, v144, 0
	v_readlane_b32 s11, v144, 16
	v_readlane_b32 s14, v144, 32
	v_readlane_b32 s15, v144, 48
	s_nop 3
	v_mov_b32_e32 v144, s11
	v_mov_b32_e32 v145, s15
	v_add_f32_e32 v144, s10, v144
	v_add_f32_e32 v145, s14, v145
	v_add_f32_e32 v144, v144, v145
	v_fmamk_f32 v144, v144, 0x3a800000, v111
	v_rsq_f32_e32 v144, v144
	s_nop 0
	v_mul_f32_e32 v236, v236, v144
	v_mul_f32_e32 v237, v237, v144
	v_mul_f32_e32 v238, v238, v144
	v_mul_f32_e32 v239, v239, v144
	v_mul_f32_e32 v240, v240, v144
	v_mul_f32_e32 v241, v241, v144
	v_mul_f32_e32 v242, v242, v144
	v_mul_f32_e32 v243, v243, v144
	v_mul_f32_e32 v244, v244, v144
	v_mul_f32_e32 v245, v245, v144
	v_mul_f32_e32 v246, v246, v144
	v_mul_f32_e32 v247, v247, v144
	v_mul_f32_e32 v248, v248, v144
	v_mul_f32_e32 v249, v249, v144
	v_mul_f32_e32 v250, v250, v144
	v_mul_f32_e32 v251, v251, v144
	v_dot8c_i32_i4_e32 v38, v122, v48
	v_dot8c_i32_i4_e32 v39, v122, v46
	v_dot8c_i32_i4_e32 v40, v124, v48
	v_dot8c_i32_i4_e32 v41, v124, v46
	v_dot8c_i32_i4_e32 v42, v126, v48
	v_dot8c_i32_i4_e32 v43, v126, v46
	v_dot8c_i32_i4_e32 v44, v128, v48
	v_dot8c_i32_i4_e32 v45, v128, v46
	v_dot8c_i32_i4_e32 v38, v123, v49
	v_dot8c_i32_i4_e32 v39, v123, v47
	v_dot8c_i32_i4_e32 v40, v125, v49
	v_dot8c_i32_i4_e32 v41, v125, v47
	v_dot8c_i32_i4_e32 v42, v127, v49
	v_dot8c_i32_i4_e32 v43, v127, v47
	v_dot8c_i32_i4_e32 v44, v129, v49
	v_dot8c_i32_i4_e32 v45, v129, v47
	v_and_b32_e32 v78, 0xffff, v24
	v_lshrrev_b32_e32 v79, 16, v24
	v_lshl_add_u32 v78, v78, 7, v150
	v_lshl_add_u32 v79, v79, 7, v151
	s_mov_b32 m0, s98
	s_add_i32 s43, s98, 0x400
	global_load_lds_dwordx4 v78, s[50:51]
	s_mov_b32 m0, s43
	s_nop 0
	global_load_lds_dwordx4 v79, s[50:51]
	s_waitcnt vmcnt(9)
	v_add_u32_e32 v54, s76, v59
	v_add_u32_e32 v55, s76, v60
	v_add_u32_e32 v56, s76, v61
	v_add_u32_e32 v57, s76, v62
	ds_read_b64_tr_b4 v[46:47], v160 offset:256
	ds_read_b64_tr_b4 v[48:49], v160 offset:1280
	ds_read_b64_tr_b4 v[122:123], v54
	ds_read_b64_tr_b4 v[124:125], v55
	ds_read_b64_tr_b4 v[126:127], v56
	ds_read_b64_tr_b4 v[128:129], v57
	s_waitcnt lgkmcnt(6)
	v_dot8c_i32_i4_e32 v38, v130, v52
	v_dot8c_i32_i4_e32 v39, v130, v50
	v_dot8c_i32_i4_e32 v40, v132, v52
	v_dot8c_i32_i4_e32 v41, v132, v50
	v_dot8c_i32_i4_e32 v42, v134, v52
	v_dot8c_i32_i4_e32 v43, v134, v50
	v_dot8c_i32_i4_e32 v44, v136, v52
	v_dot8c_i32_i4_e32 v45, v136, v50
	v_dot8c_i32_i4_e32 v38, v131, v53
	v_dot8c_i32_i4_e32 v39, v131, v51
	v_dot8c_i32_i4_e32 v40, v133, v53
	v_dot8c_i32_i4_e32 v41, v133, v51
	v_dot8c_i32_i4_e32 v42, v135, v53
	v_dot8c_i32_i4_e32 v43, v135, v51
	v_dot8c_i32_i4_e32 v44, v137, v53
	v_dot8c_i32_i4_e32 v45, v137, v51
	v_and_b32_e32 v78, 0xffff, v25
	v_lshrrev_b32_e32 v79, 16, v25
	v_lshl_add_u32 v78, v78, 7, v150
	v_lshl_add_u32 v79, v79, 7, v151
	s_mov_b32 m0, s99
	s_add_i32 s43, s99, 0x400
	global_load_lds_dwordx4 v78, s[50:51]
	s_mov_b32 m0, s43
	s_nop 0
	global_load_lds_dwordx4 v79, s[50:51]
	s_waitcnt vmcnt(9)
; __device__ __forceinline__ void peer_v_tokens(int j, const LAS unsigned short* EL, const LAS unsigned char* AL  , const LAS float* ASC  , const LAS int* SAL  , ...
;     ...
; #pragma unroll 1
;     for (int it = 0; it < 8; ++it) {
;         const int tl = it * 8 + wave, t = j * 64 + tl;
;         unsigned E[8];
;         { const LAS v4u* ep = (const LAS v4u*)(EL + tl * 128 + 16 * g); const v4u e0 = ep[0], e1 = ep[1];
;           E[0] = e0.x; E[1] = e0.y; E[2] = e0.z; E[3] = e0.w; E[4] = e1.x; E[5] = e1.y; E[6] = e1.z; E[7] = e1.w; }
;         uint2 hv[4]; float4 gv[4];
;         { unsigned ho = (unsigned)t * (D / 4) + (unsigned)lane; asm volatile("" : "+v"(ho)); const uint2* hp = (const uint2*)HB + ho; const float4* gp = (const float4*)fng + lane;
; #pragma unroll
;           for (int jq = 0; jq < 4; ++jq) { hv[jq] = hp[64 * jq]; gv[jq] = gp[64 * jq]; } }
;         VDMA(0, 0); VDMA(1, 1);
; #pragma unroll
;         for (int m = 0; m < 2; ++m) {
;             const int idx = lane + 64 * m, tau = idx >> 4, sr = idx & 15, k = 16 * (sr & 7) + 2 * tau + (sr >> 3);
;             const int aq = (int)*(const LAS signed char*)(AL + tl * 128 + k); const int tq = aq + 8;
;             const unsigned lo = (((unsigned)tq & 15u) ^ 8u) * 0x11111111u, hi = ((unsigned)(tq >> 4) & 15u) * 0x11111111u;
;             typedef unsigned u2v __attribute__((ext_vector_type(2)));
;             u2v l2; l2.x = lo; l2.y = lo; u2v h2; h2.x = hi; h2.y = hi;
;             *(LAS u2v*)(ATL + 8 * idx) = l2; *(LAS u2v*)(ATL + 1024 + 8 * idx) = h2;
;         }
;         const float asc = ASC[tl]; const int sa = SAL[tl];
;         CFENCE();
;         int accH[4], accL[4];
; #pragma unroll
;         for (int st = 0; st < 16; ++st) {
;             const int p = st >> 2, q = st & 3;
;             if (st < 14) VDMA(st + 2, (st + 2) % 3);
;             if (st < 14) asm volatile("s_waitcnt vmcnt(8)" ::: "memory");
;             else if (st == 14) asm volatile("s_waitcnt vmcnt(4)" ::: "memory");
;             else asm volatile("s_waitcnt vmcnt(0)" ::: "memory");
;             if (q == 0) {
; #pragma unroll
;                 for (int r = 0; r < 4; ++r) { accH[r] = 0; accL[r] = 0; } }
; #pragma unroll
;             for (int tp = 0; tp < 2; ++tp) {
;                 const v2i ao = TR4(ATL + (2 * q + tp) * 128 + 8 * s16), ah = TR4(ATL + 1024 + (2 * q + tp) * 128 + 8 * s16);
; #pragma unroll
	v_add_u32_e32 v54, s77, v59
	v_add_u32_e32 v55, s77, v60
	v_add_u32_e32 v56, s77, v61
	v_add_u32_e32 v57, s77, v62
	ds_read_b64_tr_b4 v[50:51], v160 offset:384
	ds_read_b64_tr_b4 v[52:53], v160 offset:1408
	ds_read_b64_tr_b4 v[130:131], v54
	ds_read_b64_tr_b4 v[132:133], v55
	ds_read_b64_tr_b4 v[134:135], v56
	ds_read_b64_tr_b4 v[136:137], v57
	s_waitcnt lgkmcnt(6)
	v_dot8c_i32_i4_e32 v38, v122, v48
	v_dot8c_i32_i4_e32 v39, v122, v46
	v_dot8c_i32_i4_e32 v40, v124, v48
	v_dot8c_i32_i4_e32 v41, v124, v46
	v_dot8c_i32_i4_e32 v42, v126, v48
	v_dot8c_i32_i4_e32 v43, v126, v46
	v_dot8c_i32_i4_e32 v44, v128, v48
	v_dot8c_i32_i4_e32 v45, v128, v46
	v_dot8c_i32_i4_e32 v38, v123, v49
	v_dot8c_i32_i4_e32 v39, v123, v47
	v_dot8c_i32_i4_e32 v40, v125, v49
	v_dot8c_i32_i4_e32 v41, v125, v47
	v_dot8c_i32_i4_e32 v42, v127, v49
	v_dot8c_i32_i4_e32 v43, v127, v47
	v_dot8c_i32_i4_e32 v44, v129, v49
	v_dot8c_i32_i4_e32 v45, v129, v47
	s_waitcnt lgkmcnt(15)
	v_and_b32_e32 v78, 0xffff, v26
	v_lshrrev_b32_e32 v79, 16, v26
	v_lshl_add_u32 v78, v78, 7, v150
	v_lshl_add_u32 v79, v79, 7, v151
	s_mov_b32 m0, s76
	s_add_i32 s43, s76, 0x400
	global_load_lds_dwordx4 v78, s[50:51]
	s_mov_b32 m0, s43
	s_nop 0
	global_load_lds_dwordx4 v79, s[50:51]
	s_waitcnt vmcnt(9)
	v_add_u32_e32 v54, s78, v59
	v_add_u32_e32 v55, s78, v60
	v_add_u32_e32 v56, s78, v61
	v_add_u32_e32 v57, s78, v62
	ds_read_b64_tr_b4 v[46:47], v160 offset:512
	ds_read_b64_tr_b4 v[48:49], v160 offset:1536
	ds_read_b64_tr_b4 v[122:123], v54
	ds_read_b64_tr_b4 v[124:125], v55
	ds_read_b64_tr_b4 v[126:127], v56
	ds_read_b64_tr_b4 v[128:129], v57
	s_waitcnt lgkmcnt(6)
	v_dot8c_i32_i4_e32 v38, v130, v52
	v_dot8c_i32_i4_e32 v39, v130, v50
	v_dot8c_i32_i4_e32 v40, v132, v52
	v_dot8c_i32_i4_e32 v41, v132, v50
	v_dot8c_i32_i4_e32 v42, v134, v52
	v_dot8c_i32_i4_e32 v43, v134, v50
	v_dot8c_i32_i4_e32 v44, v136, v52
	v_dot8c_i32_i4_e32 v45, v136, v50
	v_dot8c_i32_i4_e32 v38, v131, v53
	v_dot8c_i32_i4_e32 v39, v131, v51
	v_dot8c_i32_i4_e32 v40, v133, v53
	v_dot8c_i32_i4_e32 v41, v133, v51
	v_dot8c_i32_i4_e32 v42, v135, v53
	v_dot8c_i32_i4_e32 v43, v135, v51
	v_dot8c_i32_i4_e32 v44, v137, v53
	v_dot8c_i32_i4_e32 v45, v137, v51
	v_and_b32_e32 v78, 0xffff, v27
	v_lshrrev_b32_e32 v79, 16, v27
	v_lshl_add_u32 v78, v78, 7, v150
	v_lshl_add_u32 v79, v79, 7, v151
	s_mov_b32 m0, s77
	s_add_i32 s43, s77, 0x400
	global_load_lds_dwordx4 v78, s[50:51]
	s_mov_b32 m0, s43
	s_nop 0
	global_load_lds_dwordx4 v79, s[50:51]
	s_waitcnt vmcnt(8)
	v_add_u32_e32 v54, s79, v59
	v_add_u32_e32 v55, s79, v60
	v_add_u32_e32 v56, s79, v61
	v_add_u32_e32 v57, s79, v62
	ds_read_b64_tr_b4 v[50:51], v160 offset:640
	ds_read_b64_tr_b4 v[52:53], v160 offset:1664
	ds_read_b64_tr_b4 v[130:131], v54
	ds_read_b64_tr_b4 v[132:133], v55
	ds_read_b64_tr_b4 v[134:135], v56
	ds_read_b64_tr_b4 v[136:137], v57
	s_waitcnt lgkmcnt(6)
	v_dot8c_i32_i4_e32 v38, v122, v48
	v_dot8c_i32_i4_e32 v39, v122, v46
	v_dot8c_i32_i4_e32 v40, v124, v48
	v_dot8c_i32_i4_e32 v41, v124, v46
	v_dot8c_i32_i4_e32 v42, v126, v48
	v_dot8c_i32_i4_e32 v43, v126, v46
	v_dot8c_i32_i4_e32 v44, v128, v48
	v_dot8c_i32_i4_e32 v45, v128, v46
	v_dot8c_i32_i4_e32 v38, v123, v49
	v_dot8c_i32_i4_e32 v39, v123, v47
	v_dot8c_i32_i4_e32 v40, v125, v49
	v_dot8c_i32_i4_e32 v41, v125, v47
	v_dot8c_i32_i4_e32 v42, v127, v49
	v_dot8c_i32_i4_e32 v43, v127, v47
	v_dot8c_i32_i4_e32 v44, v129, v49
	v_dot8c_i32_i4_e32 v45, v129, v47
	s_waitcnt lgkmcnt(15)
	v_add_u32_e32 v143, 8, v139
	v_and_b32_e32 v142, 15, v143
	v_xor_b32_e32 v142, 8, v142
	v_bfe_u32 v144, v143, 4, 4
	v_mul_lo_u32 v142, v142, s92
	v_mul_lo_u32 v144, v144, s92
	v_mov_b32_e32 v143, v142
	v_mov_b32_e32 v145, v144
	ds_write2st64_b64 v159, v[142:143], v[144:145] offset1:2
	v_and_b32_e32 v78, 0xffff, v28
	v_lshrrev_b32_e32 v79, 16, v28
	v_lshl_add_u32 v78, v78, 7, v150
	v_lshl_add_u32 v79, v79, 7, v151
	s_mov_b32 m0, s78
	s_add_i32 s43, s78, 0x400
	global_load_lds_dwordx4 v78, s[50:51]
	s_mov_b32 m0, s43
	s_nop 0
	global_load_lds_dwordx4 v79, s[50:51]
	s_waitcnt vmcnt(8)
	v_add_u32_e32 v54, s98, v59
	v_add_u32_e32 v55, s98, v60
	v_add_u32_e32 v56, s98, v61
	v_add_u32_e32 v57, s98, v62
	ds_read_b64_tr_b4 v[46:47], v160 offset:768
	ds_read_b64_tr_b4 v[48:49], v160 offset:1792
	ds_read_b64_tr_b4 v[122:123], v54
	ds_read_b64_tr_b4 v[124:125], v55
	ds_read_b64_tr_b4 v[126:127], v56
	ds_read_b64_tr_b4 v[128:129], v57
	s_waitcnt lgkmcnt(7)
	v_dot8c_i32_i4_e32 v38, v130, v52
	v_dot8c_i32_i4_e32 v39, v130, v50
	v_dot8c_i32_i4_e32 v40, v132, v52
	v_dot8c_i32_i4_e32 v41, v132, v50
	v_dot8c_i32_i4_e32 v42, v134, v52
	v_dot8c_i32_i4_e32 v43, v134, v50
	v_dot8c_i32_i4_e32 v44, v136, v52
	v_dot8c_i32_i4_e32 v45, v136, v50
	v_dot8c_i32_i4_e32 v38, v131, v53
	v_dot8c_i32_i4_e32 v39, v131, v51
	v_dot8c_i32_i4_e32 v40, v133, v53
	v_dot8c_i32_i4_e32 v41, v133, v51
	v_dot8c_i32_i4_e32 v42, v135, v53
	v_dot8c_i32_i4_e32 v43, v135, v51
	v_dot8c_i32_i4_e32 v44, v137, v53
	v_dot8c_i32_i4_e32 v45, v137, v51
	v_and_b32_e32 v78, 0xffff, v29
	v_lshrrev_b32_e32 v79, 16, v29
	v_lshl_add_u32 v78, v78, 7, v150
	v_lshl_add_u32 v79, v79, 7, v151
	s_mov_b32 m0, s79
	s_add_i32 s43, s79, 0x400
	global_load_lds_dwordx4 v78, s[50:51]
	s_mov_b32 m0, s43
	s_nop 0
	global_load_lds_dwordx4 v79, s[50:51]
	s_waitcnt vmcnt(8)
	v_add_u32_e32 v54, s99, v59
	v_add_u32_e32 v55, s99, v60
	v_add_u32_e32 v56, s99, v61
	v_add_u32_e32 v57, s99, v62
	ds_read_b64_tr_b4 v[50:51], v160 offset:896
	ds_read_b64_tr_b4 v[52:53], v160 offset:1920
	ds_read_b64_tr_b4 v[130:131], v54
	ds_read_b64_tr_b4 v[132:133], v55
	ds_read_b64_tr_b4 v[134:135], v56
	ds_read_b64_tr_b4 v[136:137], v57
	s_waitcnt lgkmcnt(6)
; __device__ __forceinline__ void peer_v_tokens(int j, const LAS unsigned short* EL, const LAS unsigned char* AL  , const LAS float* ASC  , const LAS int* SAL  , ...
;     ...
; #pragma unroll
;         for (int st = 0; st < 16; ++st) {
;             const int p = st >> 2, q = st & 3;
;             if (st < 14) VDMA(st + 2, (st + 2) % 3);
;             if (st < 14) asm volatile("s_waitcnt vmcnt(8)" ::: "memory");
;             else if (st == 14) asm volatile("s_waitcnt vmcnt(4)" ::: "memory");
;             else asm volatile("s_waitcnt vmcnt(0)" ::: "memory");
;             if (q == 0) {
; #pragma unroll
;                 for (int r = 0; r < 4; ++r) { accH[r] = 0; accL[r] = 0; } }
; #pragma unroll
;             for (int tp = 0; tp < 2; ++tp) {
;                 const v2i ao = TR4(ATL + (2 * q + tp) * 128 + 8 * s16), ah = TR4(ATL + 1024 + (2 * q + tp) * 128 + 8 * s16);
; #pragma unroll
;                 for (int r = 0; r < 4; ++r) {
;                     const v2i d = TR4(ldsb + BUF[st % 3] + 2048 * tp + roff[r]);
;                     accH[r] = __builtin_amdgcn_sdot8(d.x, ah.x, accH[r], false); accH[r] = __builtin_amdgcn_sdot8(d.y, ah.y, accH[r], false);
;                     accL[r] = __builtin_amdgcn_sdot8(d.x, ao.x, accL[r], false); accL[r] = __builtin_amdgcn_sdot8(d.y, ao.y, accL[r], false);
;                 }
;             }
;             asm volatile("s_waitcnt lgkmcnt(0)" ::: "memory");
;             if (q == 3) {
; #pragma unroll
;                 for (int r = 0; r < 4; ++r) STASH[256 * p + 16 * (grp + 4 * r) + pc] = f2bf(asc * (float)(2 * ((accH[r] << 4) + accL[r]) + sa));
;             }
;         }
;         CFENCE();
;         {
;             float4 v[4]; float ss = 0.f;
; #pragma unroll
;             for (int jq = 0; jq < 4; ++jq) { typedef unsigned u2v __attribute__((ext_vector_type(2))); const u2v pw = *(const LAS u2v*)(STASH + 4 * lane + 256 * jq); const uint2 hw = hv[jq];
;                 v[jq] = make_float4(__uint_as_float(hw.x << 16) + __uint_as_float(pw.x << 16), __uint_as_float(hw.x & 0xffff0000u) + __uint_as_float(pw.x & 0xffff0000u),
;                                     __uint_as_float(hw.y << 16) + __uint_as_float(pw.y << 16), __uint_as_float(hw.y & 0xffff0000u) + __uint_as_float(pw.y & 0xffff0000u));
;                 ss += v[jq].x * v[jq].x + v[jq].y * v[jq].y + v[jq].z * v[jq].z + v[jq].w * v[jq].w; }
;             ss = wave_sum(ss);
	v_dot8c_i32_i4_e32 v38, v122, v48
	v_dot8c_i32_i4_e32 v39, v122, v46
	v_dot8c_i32_i4_e32 v40, v124, v48
	v_dot8c_i32_i4_e32 v41, v124, v46
	v_dot8c_i32_i4_e32 v42, v126, v48
	v_dot8c_i32_i4_e32 v43, v126, v46
	v_dot8c_i32_i4_e32 v44, v128, v48
	v_dot8c_i32_i4_e32 v45, v128, v46
	v_dot8c_i32_i4_e32 v38, v123, v49
	v_dot8c_i32_i4_e32 v39, v123, v47
	v_dot8c_i32_i4_e32 v40, v125, v49
	v_dot8c_i32_i4_e32 v41, v125, v47
	v_dot8c_i32_i4_e32 v42, v127, v49
	v_dot8c_i32_i4_e32 v43, v127, v47
	v_dot8c_i32_i4_e32 v44, v129, v49
	v_dot8c_i32_i4_e32 v45, v129, v47
	v_and_b32_e32 v78, 0xffff, v30
	v_lshrrev_b32_e32 v79, 16, v30
	v_lshl_add_u32 v78, v78, 7, v150
	v_lshl_add_u32 v79, v79, 7, v151
	s_mov_b32 m0, s98
	s_add_i32 s43, s98, 0x400
	global_load_lds_dwordx4 v78, s[50:51]
	s_mov_b32 m0, s43
	s_nop 0
	global_load_lds_dwordx4 v79, s[50:51]
	s_waitcnt vmcnt(8)
	v_add_u32_e32 v54, s76, v59
	v_add_u32_e32 v55, s76, v60
	v_add_u32_e32 v56, s76, v61
	v_add_u32_e32 v57, s76, v62
	ds_read_b64_tr_b4 v[46:47], v160
	ds_read_b64_tr_b4 v[48:49], v160 offset:1024
	ds_read_b64_tr_b4 v[122:123], v54
	ds_read_b64_tr_b4 v[124:125], v55
	ds_read_b64_tr_b4 v[126:127], v56
	ds_read_b64_tr_b4 v[128:129], v57
	s_waitcnt lgkmcnt(6)
	v_dot8c_i32_i4_e32 v38, v130, v52
	v_dot8c_i32_i4_e32 v39, v130, v50
	v_dot8c_i32_i4_e32 v40, v132, v52
	v_dot8c_i32_i4_e32 v41, v132, v50
	v_dot8c_i32_i4_e32 v42, v134, v52
	v_dot8c_i32_i4_e32 v43, v134, v50
	v_dot8c_i32_i4_e32 v44, v136, v52
	v_dot8c_i32_i4_e32 v45, v136, v50
	v_dot8c_i32_i4_e32 v38, v131, v53
	v_dot8c_i32_i4_e32 v39, v131, v51
	v_dot8c_i32_i4_e32 v40, v133, v53
	v_dot8c_i32_i4_e32 v41, v133, v51
	v_dot8c_i32_i4_e32 v42, v135, v53
	v_dot8c_i32_i4_e32 v43, v135, v51
	v_dot8c_i32_i4_e32 v44, v137, v53
	v_dot8c_i32_i4_e32 v45, v137, v51
	s_nop 3
	s_waitcnt lgkmcnt(15)
	v_lshlrev_b32_e32 v38, 5, v38
	v_lshlrev_b32_e32 v39, 1, v39
	v_add3_u32 v38, v39, v229, v38
	v_cvt_f32_i32_e32 v38, v38
	v_mul_f32_e32 v38, v228, v38
	v_lshlrev_b32_e32 v40, 5, v40
	v_lshlrev_b32_e32 v41, 1, v41
	v_add3_u32 v40, v41, v229, v40
	v_cvt_f32_i32_e32 v40, v40
	v_mul_f32_e32 v40, v228, v40
	v_lshlrev_b32_e32 v42, 5, v42
	v_lshlrev_b32_e32 v43, 1, v43
	v_add3_u32 v42, v43, v229, v42
	v_cvt_f32_i32_e32 v42, v42
	v_mul_f32_e32 v42, v228, v42
	v_lshlrev_b32_e32 v44, 5, v44
	v_lshlrev_b32_e32 v45, 1, v45
	v_add3_u32 v44, v45, v229, v44
	v_cvt_f32_i32_e32 v44, v44
	v_mul_f32_e32 v44, v228, v44
	v_cvt_pk_bf16_f32 v166, v38, v40
	v_cvt_pk_bf16_f32 v167, v42, v44
	ds_read_b128 v[252:255], v156 offset:1024
	s_add_i32 s44, s40, 16
	s_ashr_i32 s45, s44, 31
	s_lshl_b64 s[44:45], s[44:45], 12
	v_lshl_add_u64 v[80:81], v[36:37], 0, s[44:45]
	s_waitcnt lgkmcnt(0)
	v_mul_f32_e32 v222, v222, v252
	v_mul_f32_e32 v223, v223, v253
	v_mul_f32_e32 v224, v224, v254
	v_mul_f32_e32 v225, v225, v255
	global_store_dwordx4 v[80:81], v[222:225], off offset:3072 nt
	ds_read_b128 v[252:255], v155
	s_add_i32 s44, s40, 24
	s_ashr_i32 s45, s44, 31
	s_lshl_b64 s[44:45], s[44:45], 12
	v_lshl_add_u64 v[80:81], v[36:37], 0, s[44:45]
	s_waitcnt lgkmcnt(0)
	v_mul_f32_e32 v236, v236, v252
	v_mul_f32_e32 v237, v237, v253
	v_mul_f32_e32 v238, v238, v254
	v_mul_f32_e32 v239, v239, v255
	global_store_dwordx4 v[80:81], v[236:239], off nt
	v_add_u32_e32 v147, 8, v140
	v_and_b32_e32 v146, 15, v147
	v_xor_b32_e32 v146, 8, v146
	v_bfe_u32 v148, v147, 4, 4
	v_mul_lo_u32 v146, v146, s92
	v_mul_lo_u32 v148, v148, s92
	v_mov_b32_e32 v147, v146
	v_mov_b32_e32 v149, v148
	ds_write2st64_b64 v77, v[146:147], v[148:149] offset1:2
	v_add_u32_e32 v138, 0x1000, v74
	ds_read_u8 v139, v138
	v_add_u32_e32 v141, 0x1000, v73
	ds_read_u8 v140, v141
	s_add_i32 s43, s67, 160
	v_mov_b32_e32 v138, s43
	ds_read2st64_b32 v[228:229], v138 offset1:1
	ds_read_b128 v[18:21], v227 offset:8192
	ds_read_b128 v[22:25], v227 offset:8208
	v_add_u32_e32 v152, 0x600000, v63
	v_add_u32_e32 v153, 0x600000, v64
	v_mov_b32_e32 v38, 0
	v_mov_b32_e32 v39, 0
	v_mov_b32_e32 v40, 0
	v_mov_b32_e32 v41, 0
	v_mov_b32_e32 v42, 0
	v_mov_b32_e32 v43, 0
	v_mov_b32_e32 v44, 0
	v_mov_b32_e32 v45, 0
	v_and_b32_e32 v78, 0xffff, v31
	v_lshrrev_b32_e32 v79, 16, v31
	v_lshl_add_u32 v78, v78, 7, v150
	v_lshl_add_u32 v79, v79, 7, v151
	s_mov_b32 m0, s99
	s_add_i32 s43, s99, 0x400
	global_load_lds_dwordx4 v78, s[50:51]
	s_mov_b32 m0, s43
	s_nop 0
	global_load_lds_dwordx4 v79, s[50:51]
	s_waitcnt vmcnt(10)
	v_add_u32_e32 v54, s77, v59
	v_add_u32_e32 v55, s77, v60
	v_add_u32_e32 v56, s77, v61
	v_add_u32_e32 v57, s77, v62
	ds_read_b64_tr_b4 v[50:51], v160 offset:128
	ds_read_b64_tr_b4 v[52:53], v160 offset:1152
	ds_read_b64_tr_b4 v[130:131], v54
	ds_read_b64_tr_b4 v[132:133], v55
	ds_read_b64_tr_b4 v[134:135], v56
	ds_read_b64_tr_b4 v[136:137], v57
	s_waitcnt lgkmcnt(14)
	v_dot8c_i32_i4_e32 v38, v122, v48
	v_dot8c_i32_i4_e32 v39, v122, v46
	v_dot8c_i32_i4_e32 v40, v124, v48
	v_dot8c_i32_i4_e32 v41, v124, v46
	v_dot8c_i32_i4_e32 v42, v126, v48
	v_dot8c_i32_i4_e32 v43, v126, v46
	v_dot8c_i32_i4_e32 v44, v128, v48
	v_dot8c_i32_i4_e32 v45, v128, v46
	v_dot8c_i32_i4_e32 v38, v123, v49
	v_dot8c_i32_i4_e32 v39, v123, v47
	v_dot8c_i32_i4_e32 v40, v125, v49
	v_dot8c_i32_i4_e32 v41, v125, v47
	v_dot8c_i32_i4_e32 v42, v127, v49
	v_dot8c_i32_i4_e32 v43, v127, v47
	v_dot8c_i32_i4_e32 v44, v129, v49
	v_dot8c_i32_i4_e32 v45, v129, v47
	v_and_b32_e32 v78, 0xffff, v32
	v_lshrrev_b32_e32 v79, 16, v32
	v_lshl_add_u32 v78, v78, 7, v150
	v_lshl_add_u32 v79, v79, 7, v151
	s_mov_b32 m0, s76
	s_add_i32 s43, s76, 0x400
	global_load_lds_dwordx4 v78, s[50:51]
	s_mov_b32 m0, s43
	s_nop 0
	global_load_lds_dwordx4 v79, s[50:51]
	s_waitcnt vmcnt(10)
; #define LAS __attribute__((address_space(3)))
; #define TR4(p_) __builtin_amdgcn_ds_read_tr4_b64_v2i32((LAS v2i*)(p_))
; __device__ __forceinline__ void peer_v_tokens(int j, const LAS unsigned short* EL, const LAS unsigned char* AL  , const LAS float* ASC  , const LAS int* SAL  , ...
;     ...
;         for (int m = 0; m < 2; ++m) {
;             const int idx = lane + 64 * m, tau = idx >> 4, sr = idx & 15, k = 16 * (sr & 7) + 2 * tau + (sr >> 3);
;             const int aq = (int)*(const LAS signed char*)(AL + tl * 128 + k); const int tq = aq + 8;
;             const unsigned lo = (((unsigned)tq & 15u) ^ 8u) * 0x11111111u, hi = ((unsigned)(tq >> 4) & 15u) * 0x11111111u;
;             typedef unsigned u2v __attribute__((ext_vector_type(2)));
;             u2v l2; l2.x = lo; l2.y = lo; u2v h2; h2.x = hi; h2.y = hi;
;             *(LAS u2v*)(ATL + 8 * idx) = l2; *(LAS u2v*)(ATL + 1024 + 8 * idx) = h2;
;         }
;     ...
;         for (int st = 0; st < 16; ++st) {
;             const int p = st >> 2, q = st & 3;
;             if (st < 14) VDMA(st + 2, (st + 2) % 3);
;             if (st < 14) asm volatile("s_waitcnt vmcnt(8)" ::: "memory");
;             else if (st == 14) asm volatile("s_waitcnt vmcnt(4)" ::: "memory");
;             else asm volatile("s_waitcnt vmcnt(0)" ::: "memory");
;             if (q == 0) {
; #pragma unroll
;                 for (int r = 0; r < 4; ++r) { accH[r] = 0; accL[r] = 0; } }
; #pragma unroll
;             for (int tp = 0; tp < 2; ++tp) {
;                 const v2i ao = TR4(ATL + (2 * q + tp) * 128 + 8 * s16), ah = TR4(ATL + 1024 + (2 * q + tp) * 128 + 8 * s16);
; #pragma unroll
;                 for (int r = 0; r < 4; ++r) {
;                     const v2i d = TR4(ldsb + BUF[st % 3] + 2048 * tp + roff[r]);
;                     accH[r] = __builtin_amdgcn_sdot8(d.x, ah.x, accH[r], false); accH[r] = __builtin_amdgcn_sdot8(d.y, ah.y, accH[r], false);
;                     accL[r] = __builtin_amdgcn_sdot8(d.x, ao.x, accL[r], false); accL[r] = __builtin_amdgcn_sdot8(d.y, ao.y, accL[r], false);
;                 }
;             }
	v_add_u32_e32 v54, s78, v59
	v_add_u32_e32 v55, s78, v60
	v_add_u32_e32 v56, s78, v61
	v_add_u32_e32 v57, s78, v62
	ds_read_b64_tr_b4 v[46:47], v160 offset:256
	ds_read_b64_tr_b4 v[48:49], v160 offset:1280
	ds_read_b64_tr_b4 v[122:123], v54
	ds_read_b64_tr_b4 v[124:125], v55
	ds_read_b64_tr_b4 v[126:127], v56
	ds_read_b64_tr_b4 v[128:129], v57
	s_waitcnt lgkmcnt(6)
	v_dot8c_i32_i4_e32 v38, v130, v52
	v_dot8c_i32_i4_e32 v39, v130, v50
	v_dot8c_i32_i4_e32 v40, v132, v52
	v_dot8c_i32_i4_e32 v41, v132, v50
	v_dot8c_i32_i4_e32 v42, v134, v52
	v_dot8c_i32_i4_e32 v43, v134, v50
	v_dot8c_i32_i4_e32 v44, v136, v52
	v_dot8c_i32_i4_e32 v45, v136, v50
	v_dot8c_i32_i4_e32 v38, v131, v53
	v_dot8c_i32_i4_e32 v39, v131, v51
	v_dot8c_i32_i4_e32 v40, v133, v53
	v_dot8c_i32_i4_e32 v41, v133, v51
	v_dot8c_i32_i4_e32 v42, v135, v53
	v_dot8c_i32_i4_e32 v43, v135, v51
	v_dot8c_i32_i4_e32 v44, v137, v53
	v_dot8c_i32_i4_e32 v45, v137, v51
	v_and_b32_e32 v78, 0xffff, v33
	v_lshrrev_b32_e32 v79, 16, v33
	v_lshl_add_u32 v78, v78, 7, v150
	v_lshl_add_u32 v79, v79, 7, v151
	s_mov_b32 m0, s77
	s_add_i32 s43, s77, 0x400
	global_load_lds_dwordx4 v78, s[50:51]
	s_mov_b32 m0, s43
	s_nop 0
	global_load_lds_dwordx4 v79, s[50:51]
	s_waitcnt vmcnt(10)
	v_add_u32_e32 v54, s79, v59
	v_add_u32_e32 v55, s79, v60
	v_add_u32_e32 v56, s79, v61
	v_add_u32_e32 v57, s79, v62
	ds_read_b64_tr_b4 v[50:51], v160 offset:384
	ds_read_b64_tr_b4 v[52:53], v160 offset:1408
	ds_read_b64_tr_b4 v[130:131], v54
	ds_read_b64_tr_b4 v[132:133], v55
	ds_read_b64_tr_b4 v[134:135], v56
	ds_read_b64_tr_b4 v[136:137], v57
	s_waitcnt lgkmcnt(6)
	v_dot8c_i32_i4_e32 v38, v122, v48
	v_dot8c_i32_i4_e32 v39, v122, v46
	v_dot8c_i32_i4_e32 v40, v124, v48
	v_dot8c_i32_i4_e32 v41, v124, v46
	v_dot8c_i32_i4_e32 v42, v126, v48
	v_dot8c_i32_i4_e32 v43, v126, v46
	v_dot8c_i32_i4_e32 v44, v128, v48
	v_dot8c_i32_i4_e32 v45, v128, v46
	v_dot8c_i32_i4_e32 v38, v123, v49
	v_dot8c_i32_i4_e32 v39, v123, v47
	v_dot8c_i32_i4_e32 v40, v125, v49
	v_dot8c_i32_i4_e32 v41, v125, v47
	v_dot8c_i32_i4_e32 v42, v127, v49
	v_dot8c_i32_i4_e32 v43, v127, v47
	v_dot8c_i32_i4_e32 v44, v129, v49
	v_dot8c_i32_i4_e32 v45, v129, v47
	s_waitcnt lgkmcnt(15)
	v_and_b32_e32 v78, 0xffff, v18
	v_lshrrev_b32_e32 v79, 16, v18
	v_lshl_add_u32 v78, v78, 7, v152
	v_lshl_add_u32 v79, v79, 7, v153
	s_mov_b32 m0, s78
	s_add_i32 s43, s78, 0x400
	global_load_lds_dwordx4 v78, s[50:51]
	s_mov_b32 m0, s43
	s_nop 0
	global_load_lds_dwordx4 v79, s[50:51]
	s_waitcnt vmcnt(10)
	v_add_u32_e32 v54, s98, v59
	v_add_u32_e32 v55, s98, v60
	v_add_u32_e32 v56, s98, v61
	v_add_u32_e32 v57, s98, v62
	ds_read_b64_tr_b4 v[46:47], v160 offset:512
	ds_read_b64_tr_b4 v[48:49], v160 offset:1536
	ds_read_b64_tr_b4 v[122:123], v54
	ds_read_b64_tr_b4 v[124:125], v55
	ds_read_b64_tr_b4 v[126:127], v56
	ds_read_b64_tr_b4 v[128:129], v57
	s_waitcnt lgkmcnt(6)
	v_dot8c_i32_i4_e32 v38, v130, v52
	v_dot8c_i32_i4_e32 v39, v130, v50
	v_dot8c_i32_i4_e32 v40, v132, v52
	v_dot8c_i32_i4_e32 v41, v132, v50
	v_dot8c_i32_i4_e32 v42, v134, v52
	v_dot8c_i32_i4_e32 v43, v134, v50
	v_dot8c_i32_i4_e32 v44, v136, v52
	v_dot8c_i32_i4_e32 v45, v136, v50
	v_dot8c_i32_i4_e32 v38, v131, v53
	v_dot8c_i32_i4_e32 v39, v131, v51
	v_dot8c_i32_i4_e32 v40, v133, v53
	v_dot8c_i32_i4_e32 v41, v133, v51
	v_dot8c_i32_i4_e32 v42, v135, v53
	v_dot8c_i32_i4_e32 v43, v135, v51
	v_dot8c_i32_i4_e32 v44, v137, v53
	v_dot8c_i32_i4_e32 v45, v137, v51
	v_and_b32_e32 v78, 0xffff, v19
	v_lshrrev_b32_e32 v79, 16, v19
	v_lshl_add_u32 v78, v78, 7, v152
	v_lshl_add_u32 v79, v79, 7, v153
	s_mov_b32 m0, s79
	s_add_i32 s43, s79, 0x400
	global_load_lds_dwordx4 v78, s[50:51]
	s_mov_b32 m0, s43
	s_nop 0
	global_load_lds_dwordx4 v79, s[50:51]
	s_waitcnt vmcnt(8)
	v_add_u32_e32 v54, s99, v59
	v_add_u32_e32 v55, s99, v60
	v_add_u32_e32 v56, s99, v61
	v_add_u32_e32 v57, s99, v62
	ds_read_b64_tr_b4 v[50:51], v160 offset:640
	ds_read_b64_tr_b4 v[52:53], v160 offset:1664
	ds_read_b64_tr_b4 v[130:131], v54
	ds_read_b64_tr_b4 v[132:133], v55
	ds_read_b64_tr_b4 v[134:135], v56
	ds_read_b64_tr_b4 v[136:137], v57
	s_waitcnt lgkmcnt(6)
	v_dot8c_i32_i4_e32 v38, v122, v48
	v_dot8c_i32_i4_e32 v39, v122, v46
	v_dot8c_i32_i4_e32 v40, v124, v48
	v_dot8c_i32_i4_e32 v41, v124, v46
	v_dot8c_i32_i4_e32 v42, v126, v48
	v_dot8c_i32_i4_e32 v43, v126, v46
	v_dot8c_i32_i4_e32 v44, v128, v48
	v_dot8c_i32_i4_e32 v45, v128, v46
	v_dot8c_i32_i4_e32 v38, v123, v49
	v_dot8c_i32_i4_e32 v39, v123, v47
	v_dot8c_i32_i4_e32 v40, v125, v49
	v_dot8c_i32_i4_e32 v41, v125, v47
	v_dot8c_i32_i4_e32 v42, v127, v49
	v_dot8c_i32_i4_e32 v43, v127, v47
	v_dot8c_i32_i4_e32 v44, v129, v49
	v_dot8c_i32_i4_e32 v45, v129, v47
	s_waitcnt lgkmcnt(15)
	v_add_u32_e32 v143, 8, v139
	v_and_b32_e32 v142, 15, v143
	v_xor_b32_e32 v142, 8, v142
	v_bfe_u32 v144, v143, 4, 4
	v_mul_lo_u32 v142, v142, s92
	v_mul_lo_u32 v144, v144, s92
	v_mov_b32_e32 v143, v142
	v_mov_b32_e32 v145, v144
	ds_write2st64_b64 v159, v[142:143], v[144:145] offset1:2
	v_and_b32_e32 v78, 0xffff, v20
	v_lshrrev_b32_e32 v79, 16, v20
	v_lshl_add_u32 v78, v78, 7, v152
	v_lshl_add_u32 v79, v79, 7, v153
	s_mov_b32 m0, s98
	s_add_i32 s43, s98, 0x400
	global_load_lds_dwordx4 v78, s[50:51]
	s_mov_b32 m0, s43
	s_nop 0
	global_load_lds_dwordx4 v79, s[50:51]
	s_waitcnt vmcnt(8)
	v_add_u32_e32 v54, s76, v59
	v_add_u32_e32 v55, s76, v60
	v_add_u32_e32 v56, s76, v61
	v_add_u32_e32 v57, s76, v62
	ds_read_b64_tr_b4 v[46:47], v160 offset:768
	ds_read_b64_tr_b4 v[48:49], v160 offset:1792
	ds_read_b64_tr_b4 v[122:123], v54
	ds_read_b64_tr_b4 v[124:125], v55
	ds_read_b64_tr_b4 v[126:127], v56
	ds_read_b64_tr_b4 v[128:129], v57
	s_waitcnt lgkmcnt(7)
; #define LAS __attribute__((address_space(3)))
; __device__ __forceinline__ void peer_v_tokens(int j, const LAS unsigned short* EL, const LAS unsigned char* AL  , const LAS float* ASC  , const LAS int* SAL  , ...
;     ...
;         { const LAS v4u* ep = (const LAS v4u*)(EL + tl * 128 + 16 * g); const v4u e0 = ep[0], e1 = ep[1];
;           E[0] = e0.x; E[1] = e0.y; E[2] = e0.z; E[3] = e0.w; E[4] = e1.x; E[5] = e1.y; E[6] = e1.z; E[7] = e1.w; }
;         uint2 hv[4]; float4 gv[4];
;         { unsigned ho = (unsigned)t * (D / 4) + (unsigned)lane; asm volatile("" : "+v"(ho)); const uint2* hp = (const uint2*)HB + ho; const float4* gp = (const float4*)fng + lane;
; #pragma unroll
;           for (int jq = 0; jq < 4; ++jq) { hv[jq] = hp[64 * jq]; gv[jq] = gp[64 * jq]; } }
;         VDMA(0, 0); VDMA(1, 1);
; #pragma unroll
;         for (int m = 0; m < 2; ++m) {
;             const int idx = lane + 64 * m, tau = idx >> 4, sr = idx & 15, k = 16 * (sr & 7) + 2 * tau + (sr >> 3);
;             const int aq = (int)*(const LAS signed char*)(AL + tl * 128 + k); const int tq = aq + 8;
;             const unsigned lo = (((unsigned)tq & 15u) ^ 8u) * 0x11111111u, hi = ((unsigned)(tq >> 4) & 15u) * 0x11111111u;
;             typedef unsigned u2v __attribute__((ext_vector_type(2)));
;             u2v l2; l2.x = lo; l2.y = lo; u2v h2; h2.x = hi; h2.y = hi;
;     ...
;                 for (int r = 0; r < 4; ++r) { accH[r] = 0; accL[r] = 0; } }
; #pragma unroll
;             for (int tp = 0; tp < 2; ++tp) {
;                 const v2i ao = TR4(ATL + (2 * q + tp) * 128 + 8 * s16), ah = TR4(ATL + 1024 + (2 * q + tp) * 128 + 8 * s16);
; #pragma unroll
;                 for (int r = 0; r < 4; ++r) {
;                     const v2i d = TR4(ldsb + BUF[st % 3] + 2048 * tp + roff[r]);
;                     accH[r] = __builtin_amdgcn_sdot8(d.x, ah.x, accH[r], false); accH[r] = __builtin_amdgcn_sdot8(d.y, ah.y, accH[r], false);
;                     accL[r] = __builtin_amdgcn_sdot8(d.x, ao.x, accL[r], false); accL[r] = __builtin_amdgcn_sdot8(d.y, ao.y, accL[r], false);
;                 }
;             }
;             asm volatile("s_waitcnt lgkmcnt(0)" ::: "memory");
;             if (q == 3) {
; #pragma unroll
;                 for (int r = 0; r < 4; ++r) STASH[256 * p + 16 * (grp + 4 * r) + pc] = f2bf(asc * (float)(2 * ((accH[r] << 4) + accL[r]) + sa));
;             }
	v_dot8c_i32_i4_e32 v38, v130, v52
	v_dot8c_i32_i4_e32 v39, v130, v50
	v_dot8c_i32_i4_e32 v40, v132, v52
	v_dot8c_i32_i4_e32 v41, v132, v50
	v_dot8c_i32_i4_e32 v42, v134, v52
	v_dot8c_i32_i4_e32 v43, v134, v50
	v_dot8c_i32_i4_e32 v44, v136, v52
	v_dot8c_i32_i4_e32 v45, v136, v50
	v_dot8c_i32_i4_e32 v38, v131, v53
	v_dot8c_i32_i4_e32 v39, v131, v51
	v_dot8c_i32_i4_e32 v40, v133, v53
	v_dot8c_i32_i4_e32 v41, v133, v51
	v_dot8c_i32_i4_e32 v42, v135, v53
	v_dot8c_i32_i4_e32 v43, v135, v51
	v_dot8c_i32_i4_e32 v44, v137, v53
	v_dot8c_i32_i4_e32 v45, v137, v51
	v_and_b32_e32 v78, 0xffff, v21
	v_lshrrev_b32_e32 v79, 16, v21
	v_lshl_add_u32 v78, v78, 7, v152
	v_lshl_add_u32 v79, v79, 7, v153
	s_mov_b32 m0, s99
	s_add_i32 s43, s99, 0x400
	global_load_lds_dwordx4 v78, s[50:51]
	s_mov_b32 m0, s43
	s_nop 0
	global_load_lds_dwordx4 v79, s[50:51]
	s_waitcnt vmcnt(8)
	v_add_u32_e32 v54, s77, v59
	v_add_u32_e32 v55, s77, v60
	v_add_u32_e32 v56, s77, v61
	v_add_u32_e32 v57, s77, v62
	ds_read_b64_tr_b4 v[50:51], v160 offset:896
	ds_read_b64_tr_b4 v[52:53], v160 offset:1920
	ds_read_b64_tr_b4 v[130:131], v54
	ds_read_b64_tr_b4 v[132:133], v55
	ds_read_b64_tr_b4 v[134:135], v56
	ds_read_b64_tr_b4 v[136:137], v57
	s_waitcnt lgkmcnt(6)
	v_dot8c_i32_i4_e32 v38, v122, v48
	v_dot8c_i32_i4_e32 v39, v122, v46
	v_dot8c_i32_i4_e32 v40, v124, v48
	v_dot8c_i32_i4_e32 v41, v124, v46
	v_dot8c_i32_i4_e32 v42, v126, v48
	v_dot8c_i32_i4_e32 v43, v126, v46
	v_dot8c_i32_i4_e32 v44, v128, v48
	v_dot8c_i32_i4_e32 v45, v128, v46
	v_dot8c_i32_i4_e32 v38, v123, v49
	v_dot8c_i32_i4_e32 v39, v123, v47
	v_dot8c_i32_i4_e32 v40, v125, v49
	v_dot8c_i32_i4_e32 v41, v125, v47
	v_dot8c_i32_i4_e32 v42, v127, v49
	v_dot8c_i32_i4_e32 v43, v127, v47
	v_dot8c_i32_i4_e32 v44, v129, v49
	v_dot8c_i32_i4_e32 v45, v129, v47
	v_and_b32_e32 v78, 0xffff, v22
	v_lshrrev_b32_e32 v79, 16, v22
	v_lshl_add_u32 v78, v78, 7, v152
	v_lshl_add_u32 v79, v79, 7, v153
	s_mov_b32 m0, s76
	s_add_i32 s43, s76, 0x400
	global_load_lds_dwordx4 v78, s[50:51]
	s_mov_b32 m0, s43
	s_nop 0
	global_load_lds_dwordx4 v79, s[50:51]
	s_waitcnt vmcnt(8)
	v_add_u32_e32 v54, s78, v59
	v_add_u32_e32 v55, s78, v60
	v_add_u32_e32 v56, s78, v61
	v_add_u32_e32 v57, s78, v62
	ds_read_b64_tr_b4 v[46:47], v160
	ds_read_b64_tr_b4 v[48:49], v160 offset:1024
	ds_read_b64_tr_b4 v[122:123], v54
	ds_read_b64_tr_b4 v[124:125], v55
	ds_read_b64_tr_b4 v[126:127], v56
	ds_read_b64_tr_b4 v[128:129], v57
	s_waitcnt lgkmcnt(6)
	v_dot8c_i32_i4_e32 v38, v130, v52
	v_dot8c_i32_i4_e32 v39, v130, v50
	v_dot8c_i32_i4_e32 v40, v132, v52
	v_dot8c_i32_i4_e32 v41, v132, v50
	v_dot8c_i32_i4_e32 v42, v134, v52
	v_dot8c_i32_i4_e32 v43, v134, v50
	v_dot8c_i32_i4_e32 v44, v136, v52
	v_dot8c_i32_i4_e32 v45, v136, v50
	v_dot8c_i32_i4_e32 v38, v131, v53
	v_dot8c_i32_i4_e32 v39, v131, v51
	v_dot8c_i32_i4_e32 v40, v133, v53
	v_dot8c_i32_i4_e32 v41, v133, v51
	v_dot8c_i32_i4_e32 v42, v135, v53
	v_dot8c_i32_i4_e32 v43, v135, v51
	v_dot8c_i32_i4_e32 v44, v137, v53
	v_dot8c_i32_i4_e32 v45, v137, v51
	s_nop 3
	s_waitcnt lgkmcnt(15)
	v_lshlrev_b32_e32 v38, 5, v38
	v_lshlrev_b32_e32 v39, 1, v39
	v_add3_u32 v38, v39, v229, v38
	v_cvt_f32_i32_e32 v38, v38
	v_mul_f32_e32 v38, v228, v38
	v_lshlrev_b32_e32 v40, 5, v40
	v_lshlrev_b32_e32 v41, 1, v41
	v_add3_u32 v40, v41, v229, v40
	v_cvt_f32_i32_e32 v40, v40
	v_mul_f32_e32 v40, v228, v40
	v_lshlrev_b32_e32 v42, 5, v42
	v_lshlrev_b32_e32 v43, 1, v43
	v_add3_u32 v42, v43, v229, v42
	v_cvt_f32_i32_e32 v42, v42
	v_mul_f32_e32 v42, v228, v42
	v_lshlrev_b32_e32 v44, 5, v44
	v_lshlrev_b32_e32 v45, 1, v45
	v_add3_u32 v44, v45, v229, v44
	v_cvt_f32_i32_e32 v44, v44
	v_mul_f32_e32 v44, v228, v44
	v_cvt_pk_bf16_f32 v174, v38, v40
	v_cvt_pk_bf16_f32 v175, v42, v44
	ds_read_b128 v[252:255], v155 offset:1024
	s_add_i32 s44, s40, 24
	s_ashr_i32 s45, s44, 31
	s_lshl_b64 s[44:45], s[44:45], 12
	v_lshl_add_u64 v[80:81], v[36:37], 0, s[44:45]
	s_waitcnt lgkmcnt(0)
	v_mul_f32_e32 v240, v240, v252
	v_mul_f32_e32 v241, v241, v253
	v_mul_f32_e32 v242, v242, v254
	v_mul_f32_e32 v243, v243, v255
	global_store_dwordx4 v[80:81], v[240:243], off offset:1024 nt
	v_add_u32_e32 v147, 8, v140
	v_and_b32_e32 v146, 15, v147
	v_xor_b32_e32 v146, 8, v146
	v_bfe_u32 v148, v147, 4, 4
	v_mul_lo_u32 v146, v146, s92
	v_mul_lo_u32 v148, v148, s92
	v_mov_b32_e32 v147, v146
	v_mov_b32_e32 v149, v148
	ds_write2st64_b64 v77, v[146:147], v[148:149] offset1:2
	v_add_u32_e32 v138, 0x1400, v74
	ds_read_u8 v139, v138
	v_add_u32_e32 v141, 0x1400, v73
	ds_read_u8 v140, v141
	s_add_i32 s43, s67, 128
	v_mov_b32_e32 v138, s43
	ds_read2st64_b32 v[228:229], v138 offset1:1
	ds_read_b128 v[26:29], v227 offset:10240
	ds_read_b128 v[30:33], v227 offset:10256
	v_mov_b32_e32 v38, 0
	v_mov_b32_e32 v39, 0
	v_mov_b32_e32 v40, 0
	v_mov_b32_e32 v41, 0
	v_mov_b32_e32 v42, 0
	v_mov_b32_e32 v43, 0
	v_mov_b32_e32 v44, 0
	v_mov_b32_e32 v45, 0
	v_and_b32_e32 v78, 0xffff, v23
	v_lshrrev_b32_e32 v79, 16, v23
	v_lshl_add_u32 v78, v78, 7, v152
	v_lshl_add_u32 v79, v79, 7, v153
	s_mov_b32 m0, s77
	s_add_i32 s43, s77, 0x400
	global_load_lds_dwordx4 v78, s[50:51]
	s_mov_b32 m0, s43
	s_nop 0
	global_load_lds_dwordx4 v79, s[50:51]
	s_waitcnt vmcnt(9)
	v_add_u32_e32 v54, s79, v59
	v_add_u32_e32 v55, s79, v60
	v_add_u32_e32 v56, s79, v61
	v_add_u32_e32 v57, s79, v62
	ds_read_b64_tr_b4 v[50:51], v160 offset:128
	ds_read_b64_tr_b4 v[52:53], v160 offset:1152
	ds_read_b64_tr_b4 v[130:131], v54
	ds_read_b64_tr_b4 v[132:133], v55
	ds_read_b64_tr_b4 v[134:135], v56
	ds_read_b64_tr_b4 v[136:137], v57
	s_waitcnt lgkmcnt(13)
; #define TR4(p_) __builtin_amdgcn_ds_read_tr4_b64_v2i32((LAS v2i*)(p_))
; #define VDMA(st_, k_) do { _Pragma("unroll") for (int i_ = 0; i_ < 4; ++i_) { \
;         const unsigned off_ = (unsigned)((st_) >> 2) * (16384u * 128u) + (PE_ID(E, 4 * ((st_) & 3) + i_) << 7) + ((i_ & 1) ? cx1 : cx0); \
;         __builtin_amdgcn_global_load_lds((const unsigned*)(V4 + off_), (LAS unsigned*)(ldsb + BUF[k_] + 1024 * i_), 16, 0, 0); } } while (0)
; __device__ __forceinline__ void peer_v_tokens(int j, const LAS unsigned short* EL, const LAS unsigned char* AL  , const LAS float* ASC  , const LAS int* SAL  , ...
;     ...
;         for (int st = 0; st < 16; ++st) {
;             const int p = st >> 2, q = st & 3;
;             if (st < 14) VDMA(st + 2, (st + 2) % 3);
;             if (st < 14) asm volatile("s_waitcnt vmcnt(8)" ::: "memory");
;             else if (st == 14) asm volatile("s_waitcnt vmcnt(4)" ::: "memory");
;             else asm volatile("s_waitcnt vmcnt(0)" ::: "memory");
;             if (q == 0) {
; #pragma unroll
;                 for (int r = 0; r < 4; ++r) { accH[r] = 0; accL[r] = 0; } }
; #pragma unroll
;             for (int tp = 0; tp < 2; ++tp) {
;                 const v2i ao = TR4(ATL + (2 * q + tp) * 128 + 8 * s16), ah = TR4(ATL + 1024 + (2 * q + tp) * 128 + 8 * s16);
; #pragma unroll
;                 for (int r = 0; r < 4; ++r) {
;                     const v2i d = TR4(ldsb + BUF[st % 3] + 2048 * tp + roff[r]);
;                     accH[r] = __builtin_amdgcn_sdot8(d.x, ah.x, accH[r], false); accH[r] = __builtin_amdgcn_sdot8(d.y, ah.y, accH[r], false);
;                     accL[r] = __builtin_amdgcn_sdot8(d.x, ao.x, accL[r], false); accL[r] = __builtin_amdgcn_sdot8(d.y, ao.y, accL[r], false);
;                 }
;             }
	v_dot8c_i32_i4_e32 v38, v122, v48
	v_dot8c_i32_i4_e32 v39, v122, v46
	v_dot8c_i32_i4_e32 v40, v124, v48
	v_dot8c_i32_i4_e32 v41, v124, v46
	v_dot8c_i32_i4_e32 v42, v126, v48
	v_dot8c_i32_i4_e32 v43, v126, v46
	v_dot8c_i32_i4_e32 v44, v128, v48
	v_dot8c_i32_i4_e32 v45, v128, v46
	v_dot8c_i32_i4_e32 v38, v123, v49
	v_dot8c_i32_i4_e32 v39, v123, v47
	v_dot8c_i32_i4_e32 v40, v125, v49
	v_dot8c_i32_i4_e32 v41, v125, v47
	v_dot8c_i32_i4_e32 v42, v127, v49
	v_dot8c_i32_i4_e32 v43, v127, v47
	v_dot8c_i32_i4_e32 v44, v129, v49
	v_dot8c_i32_i4_e32 v45, v129, v47
	v_and_b32_e32 v78, 0xffff, v24
	v_lshrrev_b32_e32 v79, 16, v24
	v_lshl_add_u32 v78, v78, 7, v152
	v_lshl_add_u32 v79, v79, 7, v153
	s_mov_b32 m0, s78
	s_add_i32 s43, s78, 0x400
	global_load_lds_dwordx4 v78, s[50:51]
	s_mov_b32 m0, s43
	s_nop 0
	global_load_lds_dwordx4 v79, s[50:51]
	s_waitcnt vmcnt(9)
	v_add_u32_e32 v54, s98, v59
	v_add_u32_e32 v55, s98, v60
	v_add_u32_e32 v56, s98, v61
	v_add_u32_e32 v57, s98, v62
	ds_read_b64_tr_b4 v[46:47], v160 offset:256
	ds_read_b64_tr_b4 v[48:49], v160 offset:1280
	ds_read_b64_tr_b4 v[122:123], v54
	ds_read_b64_tr_b4 v[124:125], v55
	ds_read_b64_tr_b4 v[126:127], v56
	ds_read_b64_tr_b4 v[128:129], v57
	s_waitcnt lgkmcnt(6)
	v_dot8c_i32_i4_e32 v38, v130, v52
	v_dot8c_i32_i4_e32 v39, v130, v50
	v_dot8c_i32_i4_e32 v40, v132, v52
	v_dot8c_i32_i4_e32 v41, v132, v50
	v_dot8c_i32_i4_e32 v42, v134, v52
	v_dot8c_i32_i4_e32 v43, v134, v50
	v_dot8c_i32_i4_e32 v44, v136, v52
	v_dot8c_i32_i4_e32 v45, v136, v50
	v_dot8c_i32_i4_e32 v38, v131, v53
	v_dot8c_i32_i4_e32 v39, v131, v51
	v_dot8c_i32_i4_e32 v40, v133, v53
	v_dot8c_i32_i4_e32 v41, v133, v51
	v_dot8c_i32_i4_e32 v42, v135, v53
	v_dot8c_i32_i4_e32 v43, v135, v51
	v_dot8c_i32_i4_e32 v44, v137, v53
	v_dot8c_i32_i4_e32 v45, v137, v51
	v_and_b32_e32 v78, 0xffff, v25
	v_lshrrev_b32_e32 v79, 16, v25
	v_lshl_add_u32 v78, v78, 7, v152
	v_lshl_add_u32 v79, v79, 7, v153
	s_mov_b32 m0, s79
	s_add_i32 s43, s79, 0x400
	global_load_lds_dwordx4 v78, s[50:51]
	s_mov_b32 m0, s43
	s_nop 0
	global_load_lds_dwordx4 v79, s[50:51]
	s_waitcnt vmcnt(9)
	v_add_u32_e32 v54, s99, v59
	v_add_u32_e32 v55, s99, v60
	v_add_u32_e32 v56, s99, v61
	v_add_u32_e32 v57, s99, v62
	ds_read_b64_tr_b4 v[50:51], v160 offset:384
	ds_read_b64_tr_b4 v[52:53], v160 offset:1408
	ds_read_b64_tr_b4 v[130:131], v54
	ds_read_b64_tr_b4 v[132:133], v55
	ds_read_b64_tr_b4 v[134:135], v56
	ds_read_b64_tr_b4 v[136:137], v57
	s_waitcnt lgkmcnt(6)
	v_dot8c_i32_i4_e32 v38, v122, v48
	v_dot8c_i32_i4_e32 v39, v122, v46
	v_dot8c_i32_i4_e32 v40, v124, v48
	v_dot8c_i32_i4_e32 v41, v124, v46
	v_dot8c_i32_i4_e32 v42, v126, v48
	v_dot8c_i32_i4_e32 v43, v126, v46
	v_dot8c_i32_i4_e32 v44, v128, v48
	v_dot8c_i32_i4_e32 v45, v128, v46
	v_dot8c_i32_i4_e32 v38, v123, v49
	v_dot8c_i32_i4_e32 v39, v123, v47
	v_dot8c_i32_i4_e32 v40, v125, v49
	v_dot8c_i32_i4_e32 v41, v125, v47
	v_dot8c_i32_i4_e32 v42, v127, v49
	v_dot8c_i32_i4_e32 v43, v127, v47
	v_dot8c_i32_i4_e32 v44, v129, v49
	v_dot8c_i32_i4_e32 v45, v129, v47
	s_waitcnt lgkmcnt(15)
	v_and_b32_e32 v78, 0xffff, v26
	v_lshrrev_b32_e32 v79, 16, v26
	v_lshl_add_u32 v78, v78, 7, v152
	v_lshl_add_u32 v79, v79, 7, v153
	s_mov_b32 m0, s98
	s_add_i32 s43, s98, 0x400
	global_load_lds_dwordx4 v78, s[50:51]
	s_mov_b32 m0, s43
	s_nop 0
	global_load_lds_dwordx4 v79, s[50:51]
	s_waitcnt vmcnt(9)
	v_add_u32_e32 v54, s76, v59
	v_add_u32_e32 v55, s76, v60
	v_add_u32_e32 v56, s76, v61
	v_add_u32_e32 v57, s76, v62
	ds_read_b64_tr_b4 v[46:47], v160 offset:512
	ds_read_b64_tr_b4 v[48:49], v160 offset:1536
	ds_read_b64_tr_b4 v[122:123], v54
	ds_read_b64_tr_b4 v[124:125], v55
	ds_read_b64_tr_b4 v[126:127], v56
	ds_read_b64_tr_b4 v[128:129], v57
	s_waitcnt lgkmcnt(6)
	v_dot8c_i32_i4_e32 v38, v130, v52
	v_dot8c_i32_i4_e32 v39, v130, v50
	v_dot8c_i32_i4_e32 v40, v132, v52
	v_dot8c_i32_i4_e32 v41, v132, v50
	v_dot8c_i32_i4_e32 v42, v134, v52
	v_dot8c_i32_i4_e32 v43, v134, v50
	v_dot8c_i32_i4_e32 v44, v136, v52
	v_dot8c_i32_i4_e32 v45, v136, v50
	v_dot8c_i32_i4_e32 v38, v131, v53
	v_dot8c_i32_i4_e32 v39, v131, v51
	v_dot8c_i32_i4_e32 v40, v133, v53
	v_dot8c_i32_i4_e32 v41, v133, v51
	v_dot8c_i32_i4_e32 v42, v135, v53
	v_dot8c_i32_i4_e32 v43, v135, v51
	v_dot8c_i32_i4_e32 v44, v137, v53
	v_dot8c_i32_i4_e32 v45, v137, v51
	v_and_b32_e32 v78, 0xffff, v27
	v_lshrrev_b32_e32 v79, 16, v27
	v_lshl_add_u32 v78, v78, 7, v152
	v_lshl_add_u32 v79, v79, 7, v153
	s_mov_b32 m0, s99
	s_add_i32 s43, s99, 0x400
	global_load_lds_dwordx4 v78, s[50:51]
	s_mov_b32 m0, s43
	s_nop 0
	global_load_lds_dwordx4 v79, s[50:51]
	s_waitcnt vmcnt(8)
	v_add_u32_e32 v54, s77, v59
	v_add_u32_e32 v55, s77, v60
	v_add_u32_e32 v56, s77, v61
	v_add_u32_e32 v57, s77, v62
	ds_read_b64_tr_b4 v[50:51], v160 offset:640
	ds_read_b64_tr_b4 v[52:53], v160 offset:1664
	ds_read_b64_tr_b4 v[130:131], v54
	ds_read_b64_tr_b4 v[132:133], v55
	ds_read_b64_tr_b4 v[134:135], v56
	ds_read_b64_tr_b4 v[136:137], v57
	s_waitcnt lgkmcnt(6)
	v_dot8c_i32_i4_e32 v38, v122, v48
	v_dot8c_i32_i4_e32 v39, v122, v46
	v_dot8c_i32_i4_e32 v40, v124, v48
	v_dot8c_i32_i4_e32 v41, v124, v46
	v_dot8c_i32_i4_e32 v42, v126, v48
	v_dot8c_i32_i4_e32 v43, v126, v46
	v_dot8c_i32_i4_e32 v44, v128, v48
	v_dot8c_i32_i4_e32 v45, v128, v46
	v_dot8c_i32_i4_e32 v38, v123, v49
	v_dot8c_i32_i4_e32 v39, v123, v47
	v_dot8c_i32_i4_e32 v40, v125, v49
	v_dot8c_i32_i4_e32 v41, v125, v47
	v_dot8c_i32_i4_e32 v42, v127, v49
	v_dot8c_i32_i4_e32 v43, v127, v47
	v_dot8c_i32_i4_e32 v44, v129, v49
	v_dot8c_i32_i4_e32 v45, v129, v47
	s_waitcnt lgkmcnt(15)
; __device__ __forceinline__ bf16 f2bf(float f) { return (bf16)f2bfu(f); }
; #define TR4(p_) __builtin_amdgcn_ds_read_tr4_b64_v2i32((LAS v2i*)(p_))
; __device__ __forceinline__ void peer_v_tokens(int j, const LAS unsigned short* EL, const LAS unsigned char* AL  , const LAS float* ASC  , const LAS int* SAL  , ...
;     ...
;             for (int tp = 0; tp < 2; ++tp) {
;                 const v2i ao = TR4(ATL + (2 * q + tp) * 128 + 8 * s16), ah = TR4(ATL + 1024 + (2 * q + tp) * 128 + 8 * s16);
; #pragma unroll
;                 for (int r = 0; r < 4; ++r) {
;                     const v2i d = TR4(ldsb + BUF[st % 3] + 2048 * tp + roff[r]);
;                     accH[r] = __builtin_amdgcn_sdot8(d.x, ah.x, accH[r], false); accH[r] = __builtin_amdgcn_sdot8(d.y, ah.y, accH[r], false);
;                     accL[r] = __builtin_amdgcn_sdot8(d.x, ao.x, accL[r], false); accL[r] = __builtin_amdgcn_sdot8(d.y, ao.y, accL[r], false);
;                 }
;             }
;             asm volatile("s_waitcnt lgkmcnt(0)" ::: "memory");
;             if (q == 3) {
; #pragma unroll
;                 for (int r = 0; r < 4; ++r) STASH[256 * p + 16 * (grp + 4 * r) + pc] = f2bf(asc * (float)(2 * ((accH[r] << 4) + accL[r]) + sa));
;             }
;     ...
;             for (int jq = 0; jq < 4; ++jq) { typedef float f4v __attribute__((ext_vector_type(4))); f4v o4; o4.x = v[jq].x * r3 * gv[jq].x; o4.y = v[jq].y * r3 * gv[jq].y; o4.z = v[jq].z * r3 * gv[jq].z; o4.w = v[jq].w * r3 * gv[jq].w;
;                 __builtin_nontemporal_store(o4, (f4v*)op + 64 * jq); }
	v_add_u32_e32 v143, 8, v139
	v_and_b32_e32 v142, 15, v143
	v_xor_b32_e32 v142, 8, v142
	v_bfe_u32 v144, v143, 4, 4
	v_mul_lo_u32 v142, v142, s92
	v_mul_lo_u32 v144, v144, s92
	v_mov_b32_e32 v143, v142
	v_mov_b32_e32 v145, v144
	ds_write2st64_b64 v159, v[142:143], v[144:145] offset1:2
	v_and_b32_e32 v78, 0xffff, v28
	v_lshrrev_b32_e32 v79, 16, v28
	v_lshl_add_u32 v78, v78, 7, v152
	v_lshl_add_u32 v79, v79, 7, v153
	s_mov_b32 m0, s76
	s_add_i32 s43, s76, 0x400
	global_load_lds_dwordx4 v78, s[50:51]
	s_mov_b32 m0, s43
	s_nop 0
	global_load_lds_dwordx4 v79, s[50:51]
	s_waitcnt vmcnt(8)
	v_add_u32_e32 v54, s78, v59
	v_add_u32_e32 v55, s78, v60
	v_add_u32_e32 v56, s78, v61
	v_add_u32_e32 v57, s78, v62
	ds_read_b64_tr_b4 v[46:47], v160 offset:768
	ds_read_b64_tr_b4 v[48:49], v160 offset:1792
	ds_read_b64_tr_b4 v[122:123], v54
	ds_read_b64_tr_b4 v[124:125], v55
	ds_read_b64_tr_b4 v[126:127], v56
	ds_read_b64_tr_b4 v[128:129], v57
	s_waitcnt lgkmcnt(7)
	v_dot8c_i32_i4_e32 v38, v130, v52
	v_dot8c_i32_i4_e32 v39, v130, v50
	v_dot8c_i32_i4_e32 v40, v132, v52
	v_dot8c_i32_i4_e32 v41, v132, v50
	v_dot8c_i32_i4_e32 v42, v134, v52
	v_dot8c_i32_i4_e32 v43, v134, v50
	v_dot8c_i32_i4_e32 v44, v136, v52
	v_dot8c_i32_i4_e32 v45, v136, v50
	v_dot8c_i32_i4_e32 v38, v131, v53
	v_dot8c_i32_i4_e32 v39, v131, v51
	v_dot8c_i32_i4_e32 v40, v133, v53
	v_dot8c_i32_i4_e32 v41, v133, v51
	v_dot8c_i32_i4_e32 v42, v135, v53
	v_dot8c_i32_i4_e32 v43, v135, v51
	v_dot8c_i32_i4_e32 v44, v137, v53
	v_dot8c_i32_i4_e32 v45, v137, v51
	v_and_b32_e32 v78, 0xffff, v29
	v_lshrrev_b32_e32 v79, 16, v29
	v_lshl_add_u32 v78, v78, 7, v152
	v_lshl_add_u32 v79, v79, 7, v153
	s_mov_b32 m0, s77
	s_add_i32 s43, s77, 0x400
	global_load_lds_dwordx4 v78, s[50:51]
	s_mov_b32 m0, s43
	s_nop 0
	global_load_lds_dwordx4 v79, s[50:51]
	s_waitcnt vmcnt(8)
	v_add_u32_e32 v54, s79, v59
	v_add_u32_e32 v55, s79, v60
	v_add_u32_e32 v56, s79, v61
	v_add_u32_e32 v57, s79, v62
	ds_read_b64_tr_b4 v[50:51], v160 offset:896
	ds_read_b64_tr_b4 v[52:53], v160 offset:1920
	ds_read_b64_tr_b4 v[130:131], v54
	ds_read_b64_tr_b4 v[132:133], v55
	ds_read_b64_tr_b4 v[134:135], v56
	ds_read_b64_tr_b4 v[136:137], v57
	s_waitcnt lgkmcnt(6)
	v_dot8c_i32_i4_e32 v38, v122, v48
	v_dot8c_i32_i4_e32 v39, v122, v46
	v_dot8c_i32_i4_e32 v40, v124, v48
	v_dot8c_i32_i4_e32 v41, v124, v46
	v_dot8c_i32_i4_e32 v42, v126, v48
	v_dot8c_i32_i4_e32 v43, v126, v46
	v_dot8c_i32_i4_e32 v44, v128, v48
	v_dot8c_i32_i4_e32 v45, v128, v46
	v_dot8c_i32_i4_e32 v38, v123, v49
	v_dot8c_i32_i4_e32 v39, v123, v47
	v_dot8c_i32_i4_e32 v40, v125, v49
	v_dot8c_i32_i4_e32 v41, v125, v47
	v_dot8c_i32_i4_e32 v42, v127, v49
	v_dot8c_i32_i4_e32 v43, v127, v47
	v_dot8c_i32_i4_e32 v44, v129, v49
	v_dot8c_i32_i4_e32 v45, v129, v47
	v_and_b32_e32 v78, 0xffff, v30
	v_lshrrev_b32_e32 v79, 16, v30
	v_lshl_add_u32 v78, v78, 7, v152
	v_lshl_add_u32 v79, v79, 7, v153
	s_mov_b32 m0, s78
	s_add_i32 s43, s78, 0x400
	global_load_lds_dwordx4 v78, s[50:51]
	s_mov_b32 m0, s43
	s_nop 0
	global_load_lds_dwordx4 v79, s[50:51]
	s_waitcnt vmcnt(8)
	v_add_u32_e32 v54, s98, v59
	v_add_u32_e32 v55, s98, v60
	v_add_u32_e32 v56, s98, v61
	v_add_u32_e32 v57, s98, v62
	ds_read_b64_tr_b4 v[46:47], v160
	ds_read_b64_tr_b4 v[48:49], v160 offset:1024
	ds_read_b64_tr_b4 v[122:123], v54
	ds_read_b64_tr_b4 v[124:125], v55
	ds_read_b64_tr_b4 v[126:127], v56
	ds_read_b64_tr_b4 v[128:129], v57
	s_waitcnt lgkmcnt(6)
	v_dot8c_i32_i4_e32 v38, v130, v52
	v_dot8c_i32_i4_e32 v39, v130, v50
	v_dot8c_i32_i4_e32 v40, v132, v52
	v_dot8c_i32_i4_e32 v41, v132, v50
	v_dot8c_i32_i4_e32 v42, v134, v52
	v_dot8c_i32_i4_e32 v43, v134, v50
	v_dot8c_i32_i4_e32 v44, v136, v52
	v_dot8c_i32_i4_e32 v45, v136, v50
	v_dot8c_i32_i4_e32 v38, v131, v53
	v_dot8c_i32_i4_e32 v39, v131, v51
	v_dot8c_i32_i4_e32 v40, v133, v53
	v_dot8c_i32_i4_e32 v41, v133, v51
	v_dot8c_i32_i4_e32 v42, v135, v53
	v_dot8c_i32_i4_e32 v43, v135, v51
	v_dot8c_i32_i4_e32 v44, v137, v53
	v_dot8c_i32_i4_e32 v45, v137, v51
	s_nop 3
	s_waitcnt lgkmcnt(15)
	v_lshlrev_b32_e32 v38, 5, v38
	v_lshlrev_b32_e32 v39, 1, v39
	v_add3_u32 v38, v39, v229, v38
	v_cvt_f32_i32_e32 v38, v38
	v_mul_f32_e32 v38, v228, v38
	v_lshlrev_b32_e32 v40, 5, v40
	v_lshlrev_b32_e32 v41, 1, v41
	v_add3_u32 v40, v41, v229, v40
	v_cvt_f32_i32_e32 v40, v40
	v_mul_f32_e32 v40, v228, v40
	v_lshlrev_b32_e32 v42, 5, v42
	v_lshlrev_b32_e32 v43, 1, v43
	v_add3_u32 v42, v43, v229, v42
	v_cvt_f32_i32_e32 v42, v42
	v_mul_f32_e32 v42, v228, v42
	v_lshlrev_b32_e32 v44, 5, v44
	v_lshlrev_b32_e32 v45, 1, v45
	v_add3_u32 v44, v45, v229, v44
	v_cvt_f32_i32_e32 v44, v44
	v_mul_f32_e32 v44, v228, v44
	v_cvt_pk_bf16_f32 v168, v38, v40
	v_cvt_pk_bf16_f32 v169, v42, v44
	ds_read_b128 v[252:255], v156
	s_add_i32 s44, s40, 24
	s_ashr_i32 s45, s44, 31
	s_lshl_b64 s[44:45], s[44:45], 12
	v_lshl_add_u64 v[80:81], v[36:37], 0, s[44:45]
	s_waitcnt lgkmcnt(0)
; __device__ __forceinline__ void peer_v_tokens(int j, const LAS unsigned short* EL, const LAS unsigned char* AL  , const LAS float* ASC  , const LAS int* SAL  , ...
;     ...
;         { const LAS v4u* ep = (const LAS v4u*)(EL + tl * 128 + 16 * g); const v4u e0 = ep[0], e1 = ep[1];
;           E[0] = e0.x; E[1] = e0.y; E[2] = e0.z; E[3] = e0.w; E[4] = e1.x; E[5] = e1.y; E[6] = e1.z; E[7] = e1.w; }
;         uint2 hv[4]; float4 gv[4];
;         { unsigned ho = (unsigned)t * (D / 4) + (unsigned)lane; asm volatile("" : "+v"(ho)); const uint2* hp = (const uint2*)HB + ho; const float4* gp = (const float4*)fng + lane;
; #pragma unroll
;           for (int jq = 0; jq < 4; ++jq) { hv[jq] = hp[64 * jq]; gv[jq] = gp[64 * jq]; } }
;         VDMA(0, 0); VDMA(1, 1);
; #pragma unroll
;         for (int m = 0; m < 2; ++m) {
;             const int idx = lane + 64 * m, tau = idx >> 4, sr = idx & 15, k = 16 * (sr & 7) + 2 * tau + (sr >> 3);
;             const int aq = (int)*(const LAS signed char*)(AL + tl * 128 + k); const int tq = aq + 8;
;             const unsigned lo = (((unsigned)tq & 15u) ^ 8u) * 0x11111111u, hi = ((unsigned)(tq >> 4) & 15u) * 0x11111111u;
;             typedef unsigned u2v __attribute__((ext_vector_type(2)));
;     ...
;         for (int st = 0; st < 16; ++st) {
;             const int p = st >> 2, q = st & 3;
;             if (st < 14) VDMA(st + 2, (st + 2) % 3);
;             if (st < 14) asm volatile("s_waitcnt vmcnt(8)" ::: "memory");
;             else if (st == 14) asm volatile("s_waitcnt vmcnt(4)" ::: "memory");
;             else asm volatile("s_waitcnt vmcnt(0)" ::: "memory");
;             if (q == 0) {
; #pragma unroll
;                 for (int r = 0; r < 4; ++r) { accH[r] = 0; accL[r] = 0; } }
; #pragma unroll
;             for (int tp = 0; tp < 2; ++tp) {
;                 const v2i ao = TR4(ATL + (2 * q + tp) * 128 + 8 * s16), ah = TR4(ATL + 1024 + (2 * q + tp) * 128 + 8 * s16);
; #pragma unroll
;                 for (int r = 0; r < 4; ++r) {
;                     const v2i d = TR4(ldsb + BUF[st % 3] + 2048 * tp + roff[r]);
;                     accH[r] = __builtin_amdgcn_sdot8(d.x, ah.x, accH[r], false); accH[r] = __builtin_amdgcn_sdot8(d.y, ah.y, accH[r], false);
;                     accL[r] = __builtin_amdgcn_sdot8(d.x, ao.x, accL[r], false); accL[r] = __builtin_amdgcn_sdot8(d.y, ao.y, accL[r], false);
;                 }
;             }
	v_mul_f32_e32 v244, v244, v252
	v_mul_f32_e32 v245, v245, v253
	v_mul_f32_e32 v246, v246, v254
	v_mul_f32_e32 v247, v247, v255
	global_store_dwordx4 v[80:81], v[244:247], off offset:2048 nt
	s_add_i32 s43, s40, 32
	s_lshl_b32 s43, s43, 11
	v_add_u32_e32 v138, s43, v66
	global_load_dwordx2 v[194:195], v138, s[70:71]
	global_load_dwordx2 v[196:197], v138, s[70:71] offset:512
	global_load_dwordx2 v[198:199], v138, s[70:71] offset:1024
	global_load_dwordx2 v[200:201], v138, s[70:71] offset:1536
	v_add_u32_e32 v147, 8, v140
	v_and_b32_e32 v146, 15, v147
	v_xor_b32_e32 v146, 8, v146
	v_bfe_u32 v148, v147, 4, 4
	v_mul_lo_u32 v146, v146, s92
	v_mul_lo_u32 v148, v148, s92
	v_mov_b32_e32 v147, v146
	v_mov_b32_e32 v149, v148
	ds_write2st64_b64 v77, v[146:147], v[148:149] offset1:2
	v_add_u32_e32 v138, 0x1800, v74
	ds_read_u8 v139, v138
	v_add_u32_e32 v141, 0x1800, v73
	ds_read_u8 v140, v141
	s_add_i32 s43, s67, 160
	v_mov_b32_e32 v138, s43
	ds_read2st64_b32 v[228:229], v138 offset1:1
	ds_read_b128 v[18:21], v227 offset:12288
	ds_read_b128 v[22:25], v227 offset:12304
	v_mov_b32_e32 v150, v63
	v_mov_b32_e32 v151, v64
	v_mov_b32_e32 v38, 0
	v_mov_b32_e32 v39, 0
	v_mov_b32_e32 v40, 0
	v_mov_b32_e32 v41, 0
	v_mov_b32_e32 v42, 0
	v_mov_b32_e32 v43, 0
	v_mov_b32_e32 v44, 0
	v_mov_b32_e32 v45, 0
	v_and_b32_e32 v78, 0xffff, v31
	v_lshrrev_b32_e32 v79, 16, v31
	v_lshl_add_u32 v78, v78, 7, v152
	v_lshl_add_u32 v79, v79, 7, v153
	s_mov_b32 m0, s79
	s_add_i32 s43, s79, 0x400
	global_load_lds_dwordx4 v78, s[50:51]
	s_mov_b32 m0, s43
	s_nop 0
	global_load_lds_dwordx4 v79, s[50:51]
	s_waitcnt vmcnt(13)
	v_add_u32_e32 v54, s99, v59
	v_add_u32_e32 v55, s99, v60
	v_add_u32_e32 v56, s99, v61
	v_add_u32_e32 v57, s99, v62
	ds_read_b64_tr_b4 v[50:51], v160 offset:128
	ds_read_b64_tr_b4 v[52:53], v160 offset:1152
	ds_read_b64_tr_b4 v[130:131], v54
	ds_read_b64_tr_b4 v[132:133], v55
	ds_read_b64_tr_b4 v[134:135], v56
	ds_read_b64_tr_b4 v[136:137], v57
	s_waitcnt lgkmcnt(13)
	v_dot8c_i32_i4_e32 v38, v122, v48
	v_dot8c_i32_i4_e32 v39, v122, v46
	v_dot8c_i32_i4_e32 v40, v124, v48
	v_dot8c_i32_i4_e32 v41, v124, v46
	v_dot8c_i32_i4_e32 v42, v126, v48
	v_dot8c_i32_i4_e32 v43, v126, v46
	v_dot8c_i32_i4_e32 v44, v128, v48
	v_dot8c_i32_i4_e32 v45, v128, v46
	v_dot8c_i32_i4_e32 v38, v123, v49
	v_dot8c_i32_i4_e32 v39, v123, v47
	v_dot8c_i32_i4_e32 v40, v125, v49
	v_dot8c_i32_i4_e32 v41, v125, v47
	v_dot8c_i32_i4_e32 v42, v127, v49
	v_dot8c_i32_i4_e32 v43, v127, v47
	v_dot8c_i32_i4_e32 v44, v129, v49
	v_dot8c_i32_i4_e32 v45, v129, v47
	v_and_b32_e32 v78, 0xffff, v32
	v_lshrrev_b32_e32 v79, 16, v32
	v_lshl_add_u32 v78, v78, 7, v152
	v_lshl_add_u32 v79, v79, 7, v153
	s_mov_b32 m0, s98
	s_add_i32 s43, s98, 0x400
	global_load_lds_dwordx4 v78, s[50:51]
	s_mov_b32 m0, s43
	s_nop 0
	global_load_lds_dwordx4 v79, s[50:51]
	s_waitcnt vmcnt(13)
	v_add_u32_e32 v54, s76, v59
	v_add_u32_e32 v55, s76, v60
	v_add_u32_e32 v56, s76, v61
	v_add_u32_e32 v57, s76, v62
	ds_read_b64_tr_b4 v[46:47], v160 offset:256
	ds_read_b64_tr_b4 v[48:49], v160 offset:1280
	ds_read_b64_tr_b4 v[122:123], v54
	ds_read_b64_tr_b4 v[124:125], v55
	ds_read_b64_tr_b4 v[126:127], v56
	ds_read_b64_tr_b4 v[128:129], v57
	s_waitcnt lgkmcnt(6)
	v_dot8c_i32_i4_e32 v38, v130, v52
	v_dot8c_i32_i4_e32 v39, v130, v50
	v_dot8c_i32_i4_e32 v40, v132, v52
	v_dot8c_i32_i4_e32 v41, v132, v50
	v_dot8c_i32_i4_e32 v42, v134, v52
	v_dot8c_i32_i4_e32 v43, v134, v50
	v_dot8c_i32_i4_e32 v44, v136, v52
	v_dot8c_i32_i4_e32 v45, v136, v50
	v_dot8c_i32_i4_e32 v38, v131, v53
	v_dot8c_i32_i4_e32 v39, v131, v51
	v_dot8c_i32_i4_e32 v40, v133, v53
	v_dot8c_i32_i4_e32 v41, v133, v51
	v_dot8c_i32_i4_e32 v42, v135, v53
	v_dot8c_i32_i4_e32 v43, v135, v51
	v_dot8c_i32_i4_e32 v44, v137, v53
	v_dot8c_i32_i4_e32 v45, v137, v51
	v_and_b32_e32 v78, 0xffff, v33
	v_lshrrev_b32_e32 v79, 16, v33
	v_lshl_add_u32 v78, v78, 7, v152
	v_lshl_add_u32 v79, v79, 7, v153
	s_mov_b32 m0, s99
	s_add_i32 s43, s99, 0x400
	global_load_lds_dwordx4 v78, s[50:51]
	s_mov_b32 m0, s43
	s_nop 0
	global_load_lds_dwordx4 v79, s[50:51]
	s_waitcnt vmcnt(13)
	v_add_u32_e32 v54, s77, v59
	v_add_u32_e32 v55, s77, v60
	v_add_u32_e32 v56, s77, v61
	v_add_u32_e32 v57, s77, v62
	ds_read_b64_tr_b4 v[50:51], v160 offset:384
	ds_read_b64_tr_b4 v[52:53], v160 offset:1408
	ds_read_b64_tr_b4 v[130:131], v54
	ds_read_b64_tr_b4 v[132:133], v55
	ds_read_b64_tr_b4 v[134:135], v56
	ds_read_b64_tr_b4 v[136:137], v57
	s_waitcnt lgkmcnt(6)
	v_dot8c_i32_i4_e32 v38, v122, v48
	v_dot8c_i32_i4_e32 v39, v122, v46
	v_dot8c_i32_i4_e32 v40, v124, v48
	v_dot8c_i32_i4_e32 v41, v124, v46
	v_dot8c_i32_i4_e32 v42, v126, v48
	v_dot8c_i32_i4_e32 v43, v126, v46
	v_dot8c_i32_i4_e32 v44, v128, v48
	v_dot8c_i32_i4_e32 v45, v128, v46
	v_dot8c_i32_i4_e32 v38, v123, v49
	v_dot8c_i32_i4_e32 v39, v123, v47
	v_dot8c_i32_i4_e32 v40, v125, v49
	v_dot8c_i32_i4_e32 v41, v125, v47
	v_dot8c_i32_i4_e32 v42, v127, v49
	v_dot8c_i32_i4_e32 v43, v127, v47
	v_dot8c_i32_i4_e32 v44, v129, v49
	v_dot8c_i32_i4_e32 v45, v129, v47
	s_waitcnt lgkmcnt(15)
	v_and_b32_e32 v78, 0xffff, v18
	v_lshrrev_b32_e32 v79, 16, v18
	v_lshl_add_u32 v78, v78, 7, v150
	v_lshl_add_u32 v79, v79, 7, v151
	s_mov_b32 m0, s76
	s_add_i32 s43, s76, 0x400
	global_load_lds_dwordx4 v78, s[50:51]
	s_mov_b32 m0, s43
	s_nop 0
	global_load_lds_dwordx4 v79, s[50:51]
	s_waitcnt vmcnt(13)
	v_add_u32_e32 v54, s78, v59
	v_add_u32_e32 v55, s78, v60
	v_add_u32_e32 v56, s78, v61
	v_add_u32_e32 v57, s78, v62
	ds_read_b64_tr_b4 v[46:47], v160 offset:512
	ds_read_b64_tr_b4 v[48:49], v160 offset:1536
	ds_read_b64_tr_b4 v[122:123], v54
	ds_read_b64_tr_b4 v[124:125], v55
	ds_read_b64_tr_b4 v[126:127], v56
	ds_read_b64_tr_b4 v[128:129], v57
	s_waitcnt lgkmcnt(6)
; #define TR4(p_) __builtin_amdgcn_ds_read_tr4_b64_v2i32((LAS v2i*)(p_))
; #define VDMA(st_, k_) do { _Pragma("unroll") for (int i_ = 0; i_ < 4; ++i_) { \
;         const unsigned off_ = (unsigned)((st_) >> 2) * (16384u * 128u) + (PE_ID(E, 4 * ((st_) & 3) + i_) << 7) + ((i_ & 1) ? cx1 : cx0); \
;         __builtin_amdgcn_global_load_lds((const unsigned*)(V4 + off_), (LAS unsigned*)(ldsb + BUF[k_] + 1024 * i_), 16, 0, 0); } } while (0)
; __device__ __forceinline__ void peer_v_tokens(int j, const LAS unsigned short* EL, const LAS unsigned char* AL  , const LAS float* ASC  , const LAS int* SAL  , ...
;     ...
;         for (int st = 0; st < 16; ++st) {
;             const int p = st >> 2, q = st & 3;
;             if (st < 14) VDMA(st + 2, (st + 2) % 3);
;             if (st < 14) asm volatile("s_waitcnt vmcnt(8)" ::: "memory");
;             else if (st == 14) asm volatile("s_waitcnt vmcnt(4)" ::: "memory");
;             else asm volatile("s_waitcnt vmcnt(0)" ::: "memory");
;             if (q == 0) {
; #pragma unroll
;                 for (int r = 0; r < 4; ++r) { accH[r] = 0; accL[r] = 0; } }
; #pragma unroll
;             for (int tp = 0; tp < 2; ++tp) {
;                 const v2i ao = TR4(ATL + (2 * q + tp) * 128 + 8 * s16), ah = TR4(ATL + 1024 + (2 * q + tp) * 128 + 8 * s16);
; #pragma unroll
;                 for (int r = 0; r < 4; ++r) {
;                     const v2i d = TR4(ldsb + BUF[st % 3] + 2048 * tp + roff[r]);
;                     accH[r] = __builtin_amdgcn_sdot8(d.x, ah.x, accH[r], false); accH[r] = __builtin_amdgcn_sdot8(d.y, ah.y, accH[r], false);
;                     accL[r] = __builtin_amdgcn_sdot8(d.x, ao.x, accL[r], false); accL[r] = __builtin_amdgcn_sdot8(d.y, ao.y, accL[r], false);
;                 }
;             }
	v_dot8c_i32_i4_e32 v38, v130, v52
	v_dot8c_i32_i4_e32 v39, v130, v50
	v_dot8c_i32_i4_e32 v40, v132, v52
	v_dot8c_i32_i4_e32 v41, v132, v50
	v_dot8c_i32_i4_e32 v42, v134, v52
	v_dot8c_i32_i4_e32 v43, v134, v50
	v_dot8c_i32_i4_e32 v44, v136, v52
	v_dot8c_i32_i4_e32 v45, v136, v50
	v_dot8c_i32_i4_e32 v38, v131, v53
	v_dot8c_i32_i4_e32 v39, v131, v51
	v_dot8c_i32_i4_e32 v40, v133, v53
	v_dot8c_i32_i4_e32 v41, v133, v51
	v_dot8c_i32_i4_e32 v42, v135, v53
	v_dot8c_i32_i4_e32 v43, v135, v51
	v_dot8c_i32_i4_e32 v44, v137, v53
	v_dot8c_i32_i4_e32 v45, v137, v51
	v_and_b32_e32 v78, 0xffff, v19
	v_lshrrev_b32_e32 v79, 16, v19
	v_lshl_add_u32 v78, v78, 7, v150
	v_lshl_add_u32 v79, v79, 7, v151
	s_mov_b32 m0, s77
	s_add_i32 s43, s77, 0x400
	global_load_lds_dwordx4 v78, s[50:51]
	s_mov_b32 m0, s43
	s_nop 0
	global_load_lds_dwordx4 v79, s[50:51]
	s_waitcnt vmcnt(8)
	v_add_u32_e32 v54, s79, v59
	v_add_u32_e32 v55, s79, v60
	v_add_u32_e32 v56, s79, v61
	v_add_u32_e32 v57, s79, v62
	ds_read_b64_tr_b4 v[50:51], v160 offset:640
	ds_read_b64_tr_b4 v[52:53], v160 offset:1664
	ds_read_b64_tr_b4 v[130:131], v54
	ds_read_b64_tr_b4 v[132:133], v55
	ds_read_b64_tr_b4 v[134:135], v56
	ds_read_b64_tr_b4 v[136:137], v57
	s_waitcnt lgkmcnt(6)
	v_dot8c_i32_i4_e32 v38, v122, v48
	v_dot8c_i32_i4_e32 v39, v122, v46
	v_dot8c_i32_i4_e32 v40, v124, v48
	v_dot8c_i32_i4_e32 v41, v124, v46
	v_dot8c_i32_i4_e32 v42, v126, v48
	v_dot8c_i32_i4_e32 v43, v126, v46
	v_dot8c_i32_i4_e32 v44, v128, v48
	v_dot8c_i32_i4_e32 v45, v128, v46
	v_dot8c_i32_i4_e32 v38, v123, v49
	v_dot8c_i32_i4_e32 v39, v123, v47
	v_dot8c_i32_i4_e32 v40, v125, v49
	v_dot8c_i32_i4_e32 v41, v125, v47
	v_dot8c_i32_i4_e32 v42, v127, v49
	v_dot8c_i32_i4_e32 v43, v127, v47
	v_dot8c_i32_i4_e32 v44, v129, v49
	v_dot8c_i32_i4_e32 v45, v129, v47
	s_waitcnt lgkmcnt(15)
	v_add_u32_e32 v143, 8, v139
	v_and_b32_e32 v142, 15, v143
	v_xor_b32_e32 v142, 8, v142
	v_bfe_u32 v144, v143, 4, 4
	v_mul_lo_u32 v142, v142, s92
	v_mul_lo_u32 v144, v144, s92
	v_mov_b32_e32 v143, v142
	v_mov_b32_e32 v145, v144
	ds_write2st64_b64 v159, v[142:143], v[144:145] offset1:2
	v_and_b32_e32 v78, 0xffff, v20
	v_lshrrev_b32_e32 v79, 16, v20
	v_lshl_add_u32 v78, v78, 7, v150
	v_lshl_add_u32 v79, v79, 7, v151
	s_mov_b32 m0, s78
	s_add_i32 s43, s78, 0x400
	global_load_lds_dwordx4 v78, s[50:51]
	s_mov_b32 m0, s43
	s_nop 0
	global_load_lds_dwordx4 v79, s[50:51]
	s_waitcnt vmcnt(8)
	v_add_u32_e32 v54, s98, v59
	v_add_u32_e32 v55, s98, v60
	v_add_u32_e32 v56, s98, v61
	v_add_u32_e32 v57, s98, v62
	ds_read_b64_tr_b4 v[46:47], v160 offset:768
	ds_read_b64_tr_b4 v[48:49], v160 offset:1792
	ds_read_b64_tr_b4 v[122:123], v54
	ds_read_b64_tr_b4 v[124:125], v55
	ds_read_b64_tr_b4 v[126:127], v56
	ds_read_b64_tr_b4 v[128:129], v57
	s_waitcnt lgkmcnt(7)
	v_dot8c_i32_i4_e32 v38, v130, v52
	v_dot8c_i32_i4_e32 v39, v130, v50
	v_dot8c_i32_i4_e32 v40, v132, v52
	v_dot8c_i32_i4_e32 v41, v132, v50
	v_dot8c_i32_i4_e32 v42, v134, v52
	v_dot8c_i32_i4_e32 v43, v134, v50
	v_dot8c_i32_i4_e32 v44, v136, v52
	v_dot8c_i32_i4_e32 v45, v136, v50
	v_dot8c_i32_i4_e32 v38, v131, v53
	v_dot8c_i32_i4_e32 v39, v131, v51
	v_dot8c_i32_i4_e32 v40, v133, v53
	v_dot8c_i32_i4_e32 v41, v133, v51
	v_dot8c_i32_i4_e32 v42, v135, v53
	v_dot8c_i32_i4_e32 v43, v135, v51
	v_dot8c_i32_i4_e32 v44, v137, v53
	v_dot8c_i32_i4_e32 v45, v137, v51
	v_and_b32_e32 v78, 0xffff, v21
	v_lshrrev_b32_e32 v79, 16, v21
	v_lshl_add_u32 v78, v78, 7, v150
	v_lshl_add_u32 v79, v79, 7, v151
	s_mov_b32 m0, s79
	s_add_i32 s43, s79, 0x400
	global_load_lds_dwordx4 v78, s[50:51]
	s_mov_b32 m0, s43
	s_nop 0
	global_load_lds_dwordx4 v79, s[50:51]
	s_waitcnt vmcnt(8)
	v_add_u32_e32 v54, s99, v59
	v_add_u32_e32 v55, s99, v60
	v_add_u32_e32 v56, s99, v61
	v_add_u32_e32 v57, s99, v62
	ds_read_b64_tr_b4 v[50:51], v160 offset:896
	ds_read_b64_tr_b4 v[52:53], v160 offset:1920
	ds_read_b64_tr_b4 v[130:131], v54
	ds_read_b64_tr_b4 v[132:133], v55
	ds_read_b64_tr_b4 v[134:135], v56
	ds_read_b64_tr_b4 v[136:137], v57
	s_waitcnt lgkmcnt(6)
	v_dot8c_i32_i4_e32 v38, v122, v48
	v_dot8c_i32_i4_e32 v39, v122, v46
	v_dot8c_i32_i4_e32 v40, v124, v48
	v_dot8c_i32_i4_e32 v41, v124, v46
	v_dot8c_i32_i4_e32 v42, v126, v48
	v_dot8c_i32_i4_e32 v43, v126, v46
	v_dot8c_i32_i4_e32 v44, v128, v48
	v_dot8c_i32_i4_e32 v45, v128, v46
	v_dot8c_i32_i4_e32 v38, v123, v49
	v_dot8c_i32_i4_e32 v39, v123, v47
	v_dot8c_i32_i4_e32 v40, v125, v49
	v_dot8c_i32_i4_e32 v41, v125, v47
	v_dot8c_i32_i4_e32 v42, v127, v49
	v_dot8c_i32_i4_e32 v43, v127, v47
	v_dot8c_i32_i4_e32 v44, v129, v49
	v_dot8c_i32_i4_e32 v45, v129, v47
	v_and_b32_e32 v78, 0xffff, v22
	v_lshrrev_b32_e32 v79, 16, v22
	v_lshl_add_u32 v78, v78, 7, v150
	v_lshl_add_u32 v79, v79, 7, v151
	s_mov_b32 m0, s98
	s_add_i32 s43, s98, 0x400
	global_load_lds_dwordx4 v78, s[50:51]
	s_mov_b32 m0, s43
	s_nop 0
	global_load_lds_dwordx4 v79, s[50:51]
	s_waitcnt vmcnt(8)
	v_add_u32_e32 v54, s76, v59
	v_add_u32_e32 v55, s76, v60
	v_add_u32_e32 v56, s76, v61
	v_add_u32_e32 v57, s76, v62
	ds_read_b64_tr_b4 v[46:47], v160
	ds_read_b64_tr_b4 v[48:49], v160 offset:1024
	ds_read_b64_tr_b4 v[122:123], v54
	ds_read_b64_tr_b4 v[124:125], v55
	ds_read_b64_tr_b4 v[126:127], v56
	ds_read_b64_tr_b4 v[128:129], v57
	s_waitcnt lgkmcnt(6)
	v_dot8c_i32_i4_e32 v38, v130, v52
	v_dot8c_i32_i4_e32 v39, v130, v50
	v_dot8c_i32_i4_e32 v40, v132, v52
	v_dot8c_i32_i4_e32 v41, v132, v50
	v_dot8c_i32_i4_e32 v42, v134, v52
	v_dot8c_i32_i4_e32 v43, v134, v50
	v_dot8c_i32_i4_e32 v44, v136, v52
	v_dot8c_i32_i4_e32 v45, v136, v50
	v_dot8c_i32_i4_e32 v38, v131, v53
	v_dot8c_i32_i4_e32 v39, v131, v51
	v_dot8c_i32_i4_e32 v40, v133, v53
	v_dot8c_i32_i4_e32 v41, v133, v51
	v_dot8c_i32_i4_e32 v42, v135, v53
	v_dot8c_i32_i4_e32 v43, v135, v51
	v_dot8c_i32_i4_e32 v44, v137, v53
	v_dot8c_i32_i4_e32 v45, v137, v51
	s_nop 3
	s_waitcnt lgkmcnt(15)
; #define LAS __attribute__((address_space(3)))
; __device__ __forceinline__ bf16 f2bf(float f) { return (bf16)f2bfu(f); }
; #define TR4(p_) __builtin_amdgcn_ds_read_tr4_b64_v2i32((LAS v2i*)(p_))
; #define VDMA(st_, k_) do { _Pragma("unroll") for (int i_ = 0; i_ < 4; ++i_) { \
;         const unsigned off_ = (unsigned)((st_) >> 2) * (16384u * 128u) + (PE_ID(E, 4 * ((st_) & 3) + i_) << 7) + ((i_ & 1) ? cx1 : cx0); \
;         __builtin_amdgcn_global_load_lds((const unsigned*)(V4 + off_), (LAS unsigned*)(ldsb + BUF[k_] + 1024 * i_), 16, 0, 0); } } while (0)
; __device__ __forceinline__ void peer_v_tokens(int j, const LAS unsigned short* EL, const LAS unsigned char* AL  , const LAS float* ASC  , const LAS int* SAL  , ...
;     ...
;         for (int st = 0; st < 16; ++st) {
;             const int p = st >> 2, q = st & 3;
;             if (st < 14) VDMA(st + 2, (st + 2) % 3);
;             if (st < 14) asm volatile("s_waitcnt vmcnt(8)" ::: "memory");
;             else if (st == 14) asm volatile("s_waitcnt vmcnt(4)" ::: "memory");
;             else asm volatile("s_waitcnt vmcnt(0)" ::: "memory");
;             if (q == 0) {
; #pragma unroll
;                 for (int r = 0; r < 4; ++r) { accH[r] = 0; accL[r] = 0; } }
; #pragma unroll
;             for (int tp = 0; tp < 2; ++tp) {
;                 const v2i ao = TR4(ATL + (2 * q + tp) * 128 + 8 * s16), ah = TR4(ATL + 1024 + (2 * q + tp) * 128 + 8 * s16);
; #pragma unroll
;                 for (int r = 0; r < 4; ++r) {
;                     const v2i d = TR4(ldsb + BUF[st % 3] + 2048 * tp + roff[r]);
;                     accH[r] = __builtin_amdgcn_sdot8(d.x, ah.x, accH[r], false); accH[r] = __builtin_amdgcn_sdot8(d.y, ah.y, accH[r], false);
;                     accL[r] = __builtin_amdgcn_sdot8(d.x, ao.x, accL[r], false); accL[r] = __builtin_amdgcn_sdot8(d.y, ao.y, accL[r], false);
;                 }
;             }
;             asm volatile("s_waitcnt lgkmcnt(0)" ::: "memory");
;             if (q == 3) {
; #pragma unroll
;                 for (int r = 0; r < 4; ++r) STASH[256 * p + 16 * (grp + 4 * r) + pc] = f2bf(asc * (float)(2 * ((accH[r] << 4) + accL[r]) + sa));
;             }
;     ...
;             for (int jq = 0; jq < 4; ++jq) { typedef unsigned u2v __attribute__((ext_vector_type(2))); const u2v pw = *(const LAS u2v*)(STASH + 4 * lane + 256 * jq); const uint2 hw = hv[jq];
	v_lshlrev_b32_e32 v38, 5, v38
	v_lshlrev_b32_e32 v39, 1, v39
	v_add3_u32 v38, v39, v229, v38
	v_cvt_f32_i32_e32 v38, v38
	v_mul_f32_e32 v38, v228, v38
	v_lshlrev_b32_e32 v40, 5, v40
	v_lshlrev_b32_e32 v41, 1, v41
	v_add3_u32 v40, v41, v229, v40
	v_cvt_f32_i32_e32 v40, v40
	v_mul_f32_e32 v40, v228, v40
	v_lshlrev_b32_e32 v42, 5, v42
	v_lshlrev_b32_e32 v43, 1, v43
	v_add3_u32 v42, v43, v229, v42
	v_cvt_f32_i32_e32 v42, v42
	v_mul_f32_e32 v42, v228, v42
	v_lshlrev_b32_e32 v44, 5, v44
	v_lshlrev_b32_e32 v45, 1, v45
	v_add3_u32 v44, v45, v229, v44
	v_cvt_f32_i32_e32 v44, v44
	v_mul_f32_e32 v44, v228, v44
	v_cvt_pk_bf16_f32 v176, v38, v40
	v_cvt_pk_bf16_f32 v177, v42, v44
	ds_read_b128 v[252:255], v156 offset:1024
	s_add_i32 s44, s40, 24
	s_ashr_i32 s45, s44, 31
	s_lshl_b64 s[44:45], s[44:45], 12
	v_lshl_add_u64 v[80:81], v[36:37], 0, s[44:45]
	s_waitcnt lgkmcnt(0)
	v_mul_f32_e32 v248, v248, v252
	v_mul_f32_e32 v249, v249, v253
	v_mul_f32_e32 v250, v250, v254
	v_mul_f32_e32 v251, v251, v255
	global_store_dwordx4 v[80:81], v[248:251], off offset:3072 nt
	v_add_u32_e32 v147, 8, v140
	v_and_b32_e32 v146, 15, v147
	v_xor_b32_e32 v146, 8, v146
	v_bfe_u32 v148, v147, 4, 4
	v_mul_lo_u32 v146, v146, s92
	v_mul_lo_u32 v148, v148, s92
	v_mov_b32_e32 v147, v146
	v_mov_b32_e32 v149, v148
	ds_write2st64_b64 v77, v[146:147], v[148:149] offset1:2
	v_add_u32_e32 v138, 0x1c00, v74
	ds_read_u8 v139, v138
	v_add_u32_e32 v141, 0x1c00, v73
	ds_read_u8 v140, v141
	s_add_i32 s43, s67, 192
	v_mov_b32_e32 v138, s43
	ds_read2st64_b32 v[228:229], v138 offset1:1
	ds_read_b128 v[26:29], v227 offset:14336
	ds_read_b128 v[30:33], v227 offset:14352
	v_mov_b32_e32 v38, 0
	v_mov_b32_e32 v39, 0
	v_mov_b32_e32 v40, 0
	v_mov_b32_e32 v41, 0
	v_mov_b32_e32 v42, 0
	v_mov_b32_e32 v43, 0
	v_mov_b32_e32 v44, 0
	v_mov_b32_e32 v45, 0
	v_and_b32_e32 v78, 0xffff, v23
	v_lshrrev_b32_e32 v79, 16, v23
	v_lshl_add_u32 v78, v78, 7, v150
	v_lshl_add_u32 v79, v79, 7, v151
	s_mov_b32 m0, s99
	s_add_i32 s43, s99, 0x400
	global_load_lds_dwordx4 v78, s[50:51]
	s_mov_b32 m0, s43
	s_nop 0
	global_load_lds_dwordx4 v79, s[50:51]
	s_waitcnt vmcnt(9)
	v_add_u32_e32 v54, s77, v59
	v_add_u32_e32 v55, s77, v60
	v_add_u32_e32 v56, s77, v61
	v_add_u32_e32 v57, s77, v62
	ds_read_b64_tr_b4 v[50:51], v160 offset:128
	ds_read_b64_tr_b4 v[52:53], v160 offset:1152
	ds_read_b64_tr_b4 v[130:131], v54
	ds_read_b64_tr_b4 v[132:133], v55
	ds_read_b64_tr_b4 v[134:135], v56
	ds_read_b64_tr_b4 v[136:137], v57
	s_waitcnt lgkmcnt(13)
	v_dot8c_i32_i4_e32 v38, v122, v48
	v_dot8c_i32_i4_e32 v39, v122, v46
	v_dot8c_i32_i4_e32 v40, v124, v48
	v_dot8c_i32_i4_e32 v41, v124, v46
	v_dot8c_i32_i4_e32 v42, v126, v48
	v_dot8c_i32_i4_e32 v43, v126, v46
	v_dot8c_i32_i4_e32 v44, v128, v48
	v_dot8c_i32_i4_e32 v45, v128, v46
	v_dot8c_i32_i4_e32 v38, v123, v49
	v_dot8c_i32_i4_e32 v39, v123, v47
	v_dot8c_i32_i4_e32 v40, v125, v49
	v_dot8c_i32_i4_e32 v41, v125, v47
	v_dot8c_i32_i4_e32 v42, v127, v49
	v_dot8c_i32_i4_e32 v43, v127, v47
	v_dot8c_i32_i4_e32 v44, v129, v49
	v_dot8c_i32_i4_e32 v45, v129, v47
	v_and_b32_e32 v78, 0xffff, v24
	v_lshrrev_b32_e32 v79, 16, v24
	v_lshl_add_u32 v78, v78, 7, v150
	v_lshl_add_u32 v79, v79, 7, v151
	s_mov_b32 m0, s76
	s_add_i32 s43, s76, 0x400
	global_load_lds_dwordx4 v78, s[50:51]
	s_mov_b32 m0, s43
	s_nop 0
	global_load_lds_dwordx4 v79, s[50:51]
	s_waitcnt vmcnt(9)
	v_add_u32_e32 v54, s78, v59
	v_add_u32_e32 v55, s78, v60
	v_add_u32_e32 v56, s78, v61
	v_add_u32_e32 v57, s78, v62
	ds_read_b64_tr_b4 v[46:47], v160 offset:256
	ds_read_b64_tr_b4 v[48:49], v160 offset:1280
	ds_read_b64_tr_b4 v[122:123], v54
	ds_read_b64_tr_b4 v[124:125], v55
	ds_read_b64_tr_b4 v[126:127], v56
	ds_read_b64_tr_b4 v[128:129], v57
	s_waitcnt lgkmcnt(6)
	v_dot8c_i32_i4_e32 v38, v130, v52
	v_dot8c_i32_i4_e32 v39, v130, v50
	v_dot8c_i32_i4_e32 v40, v132, v52
	v_dot8c_i32_i4_e32 v41, v132, v50
	v_dot8c_i32_i4_e32 v42, v134, v52
	v_dot8c_i32_i4_e32 v43, v134, v50
	v_dot8c_i32_i4_e32 v44, v136, v52
	v_dot8c_i32_i4_e32 v45, v136, v50
	v_dot8c_i32_i4_e32 v38, v131, v53
	v_dot8c_i32_i4_e32 v39, v131, v51
	v_dot8c_i32_i4_e32 v40, v133, v53
	v_dot8c_i32_i4_e32 v41, v133, v51
	v_dot8c_i32_i4_e32 v42, v135, v53
	v_dot8c_i32_i4_e32 v43, v135, v51
	v_dot8c_i32_i4_e32 v44, v137, v53
	v_dot8c_i32_i4_e32 v45, v137, v51
	ds_write_b16 v65, v162
	ds_write_b16_d16_hi v65, v162 offset:128
	ds_write_b16 v65, v163 offset:256
	ds_write_b16_d16_hi v65, v163 offset:384
	ds_write_b16 v65, v164 offset:512
	ds_write_b16_d16_hi v65, v164 offset:640
	ds_write_b16 v65, v165 offset:768
	ds_write_b16_d16_hi v65, v165 offset:896
	ds_write_b16 v65, v166 offset:1024
	ds_write_b16_d16_hi v65, v166 offset:1152
	ds_write_b16 v65, v167 offset:1280
	ds_write_b16_d16_hi v65, v167 offset:1408
	ds_write_b16 v65, v168 offset:1536
	ds_write_b16_d16_hi v65, v168 offset:1664
	ds_write_b16 v65, v169 offset:1792
	ds_write_b16_d16_hi v65, v169 offset:1920
	ds_read_b64 v[202:203], v154
	ds_read_b64 v[204:205], v154 offset:512
	ds_read_b64 v[206:207], v154 offset:1024
	ds_read_b64 v[208:209], v154 offset:1536
	v_and_b32_e32 v78, 0xffff, v25
	v_lshrrev_b32_e32 v79, 16, v25
	v_lshl_add_u32 v78, v78, 7, v150
	v_lshl_add_u32 v79, v79, 7, v151
	s_mov_b32 m0, s77
	s_add_i32 s43, s77, 0x400
	global_load_lds_dwordx4 v78, s[50:51]
	s_mov_b32 m0, s43
	s_nop 0
	global_load_lds_dwordx4 v79, s[50:51]
	s_waitcnt vmcnt(9)
	v_add_u32_e32 v54, s79, v59
	v_add_u32_e32 v55, s79, v60
	v_add_u32_e32 v56, s79, v61
	v_add_u32_e32 v57, s79, v62
	ds_read_b64_tr_b4 v[50:51], v160 offset:384
	ds_read_b64_tr_b4 v[52:53], v160 offset:1408
	ds_read_b64_tr_b4 v[130:131], v54
	ds_read_b64_tr_b4 v[132:133], v55
	ds_read_b64_tr_b4 v[134:135], v56
	ds_read_b64_tr_b4 v[136:137], v57
	s_waitcnt lgkmcnt(15)
; #define TR4(p_) __builtin_amdgcn_ds_read_tr4_b64_v2i32((LAS v2i*)(p_))
; #define VDMA(st_, k_) do { _Pragma("unroll") for (int i_ = 0; i_ < 4; ++i_) { \
;         const unsigned off_ = (unsigned)((st_) >> 2) * (16384u * 128u) + (PE_ID(E, 4 * ((st_) & 3) + i_) << 7) + ((i_ & 1) ? cx1 : cx0); \
;         __builtin_amdgcn_global_load_lds((const unsigned*)(V4 + off_), (LAS unsigned*)(ldsb + BUF[k_] + 1024 * i_), 16, 0, 0); } } while (0)
; __device__ __forceinline__ void peer_v_tokens(int j, const LAS unsigned short* EL, const LAS unsigned char* AL  , const LAS float* ASC  , const LAS int* SAL  , ...
;     ...
;         for (int st = 0; st < 16; ++st) {
;             const int p = st >> 2, q = st & 3;
;             if (st < 14) VDMA(st + 2, (st + 2) % 3);
;             if (st < 14) asm volatile("s_waitcnt vmcnt(8)" ::: "memory");
;             else if (st == 14) asm volatile("s_waitcnt vmcnt(4)" ::: "memory");
;             else asm volatile("s_waitcnt vmcnt(0)" ::: "memory");
;             if (q == 0) {
; #pragma unroll
;                 for (int r = 0; r < 4; ++r) { accH[r] = 0; accL[r] = 0; } }
; #pragma unroll
;             for (int tp = 0; tp < 2; ++tp) {
;                 const v2i ao = TR4(ATL + (2 * q + tp) * 128 + 8 * s16), ah = TR4(ATL + 1024 + (2 * q + tp) * 128 + 8 * s16);
; #pragma unroll
;                 for (int r = 0; r < 4; ++r) {
;                     const v2i d = TR4(ldsb + BUF[st % 3] + 2048 * tp + roff[r]);
;                     accH[r] = __builtin_amdgcn_sdot8(d.x, ah.x, accH[r], false); accH[r] = __builtin_amdgcn_sdot8(d.y, ah.y, accH[r], false);
;                     accL[r] = __builtin_amdgcn_sdot8(d.x, ao.x, accL[r], false); accL[r] = __builtin_amdgcn_sdot8(d.y, ao.y, accL[r], false);
;                 }
;             }
	v_dot8c_i32_i4_e32 v38, v122, v48
	v_dot8c_i32_i4_e32 v39, v122, v46
	v_dot8c_i32_i4_e32 v40, v124, v48
	v_dot8c_i32_i4_e32 v41, v124, v46
	v_dot8c_i32_i4_e32 v42, v126, v48
	v_dot8c_i32_i4_e32 v43, v126, v46
	v_dot8c_i32_i4_e32 v44, v128, v48
	v_dot8c_i32_i4_e32 v45, v128, v46
	v_dot8c_i32_i4_e32 v38, v123, v49
	v_dot8c_i32_i4_e32 v39, v123, v47
	v_dot8c_i32_i4_e32 v40, v125, v49
	v_dot8c_i32_i4_e32 v41, v125, v47
	v_dot8c_i32_i4_e32 v42, v127, v49
	v_dot8c_i32_i4_e32 v43, v127, v47
	v_dot8c_i32_i4_e32 v44, v129, v49
	v_dot8c_i32_i4_e32 v45, v129, v47
	s_waitcnt lgkmcnt(15)
	v_and_b32_e32 v78, 0xffff, v26
	v_lshrrev_b32_e32 v79, 16, v26
	v_lshl_add_u32 v78, v78, 7, v150
	v_lshl_add_u32 v79, v79, 7, v151
	s_mov_b32 m0, s78
	s_add_i32 s43, s78, 0x400
	global_load_lds_dwordx4 v78, s[50:51]
	s_mov_b32 m0, s43
	s_nop 0
	global_load_lds_dwordx4 v79, s[50:51]
	s_waitcnt vmcnt(9)
	v_add_u32_e32 v54, s98, v59
	v_add_u32_e32 v55, s98, v60
	v_add_u32_e32 v56, s98, v61
	v_add_u32_e32 v57, s98, v62
	ds_read_b64_tr_b4 v[46:47], v160 offset:512
	ds_read_b64_tr_b4 v[48:49], v160 offset:1536
	ds_read_b64_tr_b4 v[122:123], v54
	ds_read_b64_tr_b4 v[124:125], v55
	ds_read_b64_tr_b4 v[126:127], v56
	ds_read_b64_tr_b4 v[128:129], v57
	s_waitcnt lgkmcnt(6)
	v_dot8c_i32_i4_e32 v38, v130, v52
	v_dot8c_i32_i4_e32 v39, v130, v50
	v_dot8c_i32_i4_e32 v40, v132, v52
	v_dot8c_i32_i4_e32 v41, v132, v50
	v_dot8c_i32_i4_e32 v42, v134, v52
	v_dot8c_i32_i4_e32 v43, v134, v50
	v_dot8c_i32_i4_e32 v44, v136, v52
	v_dot8c_i32_i4_e32 v45, v136, v50
	v_dot8c_i32_i4_e32 v38, v131, v53
	v_dot8c_i32_i4_e32 v39, v131, v51
	v_dot8c_i32_i4_e32 v40, v133, v53
	v_dot8c_i32_i4_e32 v41, v133, v51
	v_dot8c_i32_i4_e32 v42, v135, v53
	v_dot8c_i32_i4_e32 v43, v135, v51
	v_dot8c_i32_i4_e32 v44, v137, v53
	v_dot8c_i32_i4_e32 v45, v137, v51
	v_and_b32_e32 v78, 0xffff, v27
	v_lshrrev_b32_e32 v79, 16, v27
	v_lshl_add_u32 v78, v78, 7, v150
	v_lshl_add_u32 v79, v79, 7, v151
	s_mov_b32 m0, s79
	s_add_i32 s43, s79, 0x400
	global_load_lds_dwordx4 v78, s[50:51]
	s_mov_b32 m0, s43
	s_nop 0
	global_load_lds_dwordx4 v79, s[50:51]
	s_waitcnt vmcnt(8)
	v_add_u32_e32 v54, s99, v59
	v_add_u32_e32 v55, s99, v60
	v_add_u32_e32 v56, s99, v61
	v_add_u32_e32 v57, s99, v62
	ds_read_b64_tr_b4 v[50:51], v160 offset:640
	ds_read_b64_tr_b4 v[52:53], v160 offset:1664
	ds_read_b64_tr_b4 v[130:131], v54
	ds_read_b64_tr_b4 v[132:133], v55
	ds_read_b64_tr_b4 v[134:135], v56
	ds_read_b64_tr_b4 v[136:137], v57
	s_waitcnt lgkmcnt(6)
	v_dot8c_i32_i4_e32 v38, v122, v48
	v_dot8c_i32_i4_e32 v39, v122, v46
	v_dot8c_i32_i4_e32 v40, v124, v48
	v_dot8c_i32_i4_e32 v41, v124, v46
	v_dot8c_i32_i4_e32 v42, v126, v48
	v_dot8c_i32_i4_e32 v43, v126, v46
	v_dot8c_i32_i4_e32 v44, v128, v48
	v_dot8c_i32_i4_e32 v45, v128, v46
	v_dot8c_i32_i4_e32 v38, v123, v49
	v_dot8c_i32_i4_e32 v39, v123, v47
	v_dot8c_i32_i4_e32 v40, v125, v49
	v_dot8c_i32_i4_e32 v41, v125, v47
	v_dot8c_i32_i4_e32 v42, v127, v49
	v_dot8c_i32_i4_e32 v43, v127, v47
	v_dot8c_i32_i4_e32 v44, v129, v49
	v_dot8c_i32_i4_e32 v45, v129, v47
	s_waitcnt lgkmcnt(15)
	v_add_u32_e32 v143, 8, v139
	v_and_b32_e32 v142, 15, v143
	v_xor_b32_e32 v142, 8, v142
	v_bfe_u32 v144, v143, 4, 4
	v_mul_lo_u32 v142, v142, s92
	v_mul_lo_u32 v144, v144, s92
	v_mov_b32_e32 v143, v142
	v_mov_b32_e32 v145, v144
	ds_write2st64_b64 v159, v[142:143], v[144:145] offset1:2
	v_and_b32_e32 v78, 0xffff, v28
	v_lshrrev_b32_e32 v79, 16, v28
	v_lshl_add_u32 v78, v78, 7, v150
	v_lshl_add_u32 v79, v79, 7, v151
	s_mov_b32 m0, s98
	s_add_i32 s43, s98, 0x400
	global_load_lds_dwordx4 v78, s[50:51]
	s_mov_b32 m0, s43
	s_nop 0
	global_load_lds_dwordx4 v79, s[50:51]
	s_waitcnt vmcnt(8)
	v_add_u32_e32 v54, s76, v59
	v_add_u32_e32 v55, s76, v60
	v_add_u32_e32 v56, s76, v61
	v_add_u32_e32 v57, s76, v62
	ds_read_b64_tr_b4 v[46:47], v160 offset:768
	ds_read_b64_tr_b4 v[48:49], v160 offset:1792
	ds_read_b64_tr_b4 v[122:123], v54
	ds_read_b64_tr_b4 v[124:125], v55
	ds_read_b64_tr_b4 v[126:127], v56
	ds_read_b64_tr_b4 v[128:129], v57
	s_waitcnt lgkmcnt(7)
	v_dot8c_i32_i4_e32 v38, v130, v52
	v_dot8c_i32_i4_e32 v39, v130, v50
	v_dot8c_i32_i4_e32 v40, v132, v52
	v_dot8c_i32_i4_e32 v41, v132, v50
	v_dot8c_i32_i4_e32 v42, v134, v52
	v_dot8c_i32_i4_e32 v43, v134, v50
	v_dot8c_i32_i4_e32 v44, v136, v52
	v_dot8c_i32_i4_e32 v45, v136, v50
	v_dot8c_i32_i4_e32 v38, v131, v53
	v_dot8c_i32_i4_e32 v39, v131, v51
	v_dot8c_i32_i4_e32 v40, v133, v53
	v_dot8c_i32_i4_e32 v41, v133, v51
	v_dot8c_i32_i4_e32 v42, v135, v53
	v_dot8c_i32_i4_e32 v43, v135, v51
	v_dot8c_i32_i4_e32 v44, v137, v53
	v_dot8c_i32_i4_e32 v45, v137, v51
	v_and_b32_e32 v78, 0xffff, v29
	v_lshrrev_b32_e32 v79, 16, v29
	v_lshl_add_u32 v78, v78, 7, v150
	v_lshl_add_u32 v79, v79, 7, v151
	s_mov_b32 m0, s99
	s_add_i32 s43, s99, 0x400
	global_load_lds_dwordx4 v78, s[50:51]
	s_mov_b32 m0, s43
	s_nop 0
	global_load_lds_dwordx4 v79, s[50:51]
	s_waitcnt vmcnt(8)
	v_add_u32_e32 v54, s77, v59
	v_add_u32_e32 v55, s77, v60
	v_add_u32_e32 v56, s77, v61
	v_add_u32_e32 v57, s77, v62
	ds_read_b64_tr_b4 v[50:51], v160 offset:896
	ds_read_b64_tr_b4 v[52:53], v160 offset:1920
	ds_read_b64_tr_b4 v[130:131], v54
	ds_read_b64_tr_b4 v[132:133], v55
	ds_read_b64_tr_b4 v[134:135], v56
	ds_read_b64_tr_b4 v[136:137], v57
	s_waitcnt lgkmcnt(6)
; #define LAS __attribute__((address_space(3)))
; __device__ __forceinline__ bf16 f2bf(float f) { return (bf16)f2bfu(f); }
; #define TR4(p_) __builtin_amdgcn_ds_read_tr4_b64_v2i32((LAS v2i*)(p_))
; __device__ __forceinline__ void peer_v_tokens(int j, const LAS unsigned short* EL, const LAS unsigned char* AL  , const LAS float* ASC  , const LAS int* SAL  , ...
;     ...
;             for (int tp = 0; tp < 2; ++tp) {
;                 const v2i ao = TR4(ATL + (2 * q + tp) * 128 + 8 * s16), ah = TR4(ATL + 1024 + (2 * q + tp) * 128 + 8 * s16);
; #pragma unroll
;                 for (int r = 0; r < 4; ++r) {
;                     const v2i d = TR4(ldsb + BUF[st % 3] + 2048 * tp + roff[r]);
;                     accH[r] = __builtin_amdgcn_sdot8(d.x, ah.x, accH[r], false); accH[r] = __builtin_amdgcn_sdot8(d.y, ah.y, accH[r], false);
;                     accL[r] = __builtin_amdgcn_sdot8(d.x, ao.x, accL[r], false); accL[r] = __builtin_amdgcn_sdot8(d.y, ao.y, accL[r], false);
;                 }
;             }
;             asm volatile("s_waitcnt lgkmcnt(0)" ::: "memory");
;             if (q == 3) {
; #pragma unroll
;                 for (int r = 0; r < 4; ++r) STASH[256 * p + 16 * (grp + 4 * r) + pc] = f2bf(asc * (float)(2 * ((accH[r] << 4) + accL[r]) + sa));
;             }
;     ...
;             for (int jq = 0; jq < 4; ++jq) { typedef unsigned u2v __attribute__((ext_vector_type(2))); const u2v pw = *(const LAS u2v*)(STASH + 4 * lane + 256 * jq); const uint2 hw = hv[jq];
;                 v[jq] = make_float4(__uint_as_float(hw.x << 16) + __uint_as_float(pw.x << 16), __uint_as_float(hw.x & 0xffff0000u) + __uint_as_float(pw.x & 0xffff0000u),
;                                     __uint_as_float(hw.y << 16) + __uint_as_float(pw.y << 16), __uint_as_float(hw.y & 0xffff0000u) + __uint_as_float(pw.y & 0xffff0000u));
;                 ss += v[jq].x * v[jq].x + v[jq].y * v[jq].y + v[jq].z * v[jq].z + v[jq].w * v[jq].w; }
	v_dot8c_i32_i4_e32 v38, v122, v48
	v_dot8c_i32_i4_e32 v39, v122, v46
	v_dot8c_i32_i4_e32 v40, v124, v48
	v_dot8c_i32_i4_e32 v41, v124, v46
	v_dot8c_i32_i4_e32 v42, v126, v48
	v_dot8c_i32_i4_e32 v43, v126, v46
	v_dot8c_i32_i4_e32 v44, v128, v48
	v_dot8c_i32_i4_e32 v45, v128, v46
	v_dot8c_i32_i4_e32 v38, v123, v49
	v_dot8c_i32_i4_e32 v39, v123, v47
	v_dot8c_i32_i4_e32 v40, v125, v49
	v_dot8c_i32_i4_e32 v41, v125, v47
	v_dot8c_i32_i4_e32 v42, v127, v49
	v_dot8c_i32_i4_e32 v43, v127, v47
	v_dot8c_i32_i4_e32 v44, v129, v49
	v_dot8c_i32_i4_e32 v45, v129, v47
	v_and_b32_e32 v78, 0xffff, v30
	v_lshrrev_b32_e32 v79, 16, v30
	v_lshl_add_u32 v78, v78, 7, v150
	v_lshl_add_u32 v79, v79, 7, v151
	s_mov_b32 m0, s76
	s_add_i32 s43, s76, 0x400
	global_load_lds_dwordx4 v78, s[50:51]
	s_mov_b32 m0, s43
	s_nop 0
	global_load_lds_dwordx4 v79, s[50:51]
	s_waitcnt vmcnt(8)
	v_add_u32_e32 v54, s78, v59
	v_add_u32_e32 v55, s78, v60
	v_add_u32_e32 v56, s78, v61
	v_add_u32_e32 v57, s78, v62
	ds_read_b64_tr_b4 v[46:47], v160
	ds_read_b64_tr_b4 v[48:49], v160 offset:1024
	ds_read_b64_tr_b4 v[122:123], v54
	ds_read_b64_tr_b4 v[124:125], v55
	ds_read_b64_tr_b4 v[126:127], v56
	ds_read_b64_tr_b4 v[128:129], v57
	s_waitcnt lgkmcnt(6)
	v_dot8c_i32_i4_e32 v38, v130, v52
	v_dot8c_i32_i4_e32 v39, v130, v50
	v_dot8c_i32_i4_e32 v40, v132, v52
	v_dot8c_i32_i4_e32 v41, v132, v50
	v_dot8c_i32_i4_e32 v42, v134, v52
	v_dot8c_i32_i4_e32 v43, v134, v50
	v_dot8c_i32_i4_e32 v44, v136, v52
	v_dot8c_i32_i4_e32 v45, v136, v50
	v_dot8c_i32_i4_e32 v38, v131, v53
	v_dot8c_i32_i4_e32 v39, v131, v51
	v_dot8c_i32_i4_e32 v40, v133, v53
	v_dot8c_i32_i4_e32 v41, v133, v51
	v_dot8c_i32_i4_e32 v42, v135, v53
	v_dot8c_i32_i4_e32 v43, v135, v51
	v_dot8c_i32_i4_e32 v44, v137, v53
	v_dot8c_i32_i4_e32 v45, v137, v51
	s_nop 3
	s_waitcnt lgkmcnt(15)
	v_lshlrev_b32_e32 v38, 5, v38
	v_lshlrev_b32_e32 v39, 1, v39
	v_add3_u32 v38, v39, v229, v38
	v_cvt_f32_i32_e32 v38, v38
	v_mul_f32_e32 v38, v228, v38
	v_lshlrev_b32_e32 v40, 5, v40
	v_lshlrev_b32_e32 v41, 1, v41
	v_add3_u32 v40, v41, v229, v40
	v_cvt_f32_i32_e32 v40, v40
	v_mul_f32_e32 v40, v228, v40
	v_lshlrev_b32_e32 v42, 5, v42
	v_lshlrev_b32_e32 v43, 1, v43
	v_add3_u32 v42, v43, v229, v42
	v_cvt_f32_i32_e32 v42, v42
	v_mul_f32_e32 v42, v228, v42
	v_lshlrev_b32_e32 v44, 5, v44
	v_lshlrev_b32_e32 v45, 1, v45
	v_add3_u32 v44, v45, v229, v44
	v_cvt_f32_i32_e32 v44, v44
	v_mul_f32_e32 v44, v228, v44
	v_cvt_pk_bf16_f32 v178, v38, v40
	v_cvt_pk_bf16_f32 v179, v42, v44
	v_add_u32_e32 v147, 8, v140
	v_and_b32_e32 v146, 15, v147
	v_xor_b32_e32 v146, 8, v146
	v_bfe_u32 v148, v147, 4, 4
	v_mul_lo_u32 v146, v146, s92
	v_mul_lo_u32 v148, v148, s92
	v_mov_b32_e32 v147, v146
	v_mov_b32_e32 v149, v148
	ds_write2st64_b64 v77, v[146:147], v[148:149] offset1:2
	v_add_u32_e32 v138, 0x1800, v74
	ds_read_u8 v139, v138
	v_add_u32_e32 v141, 0x1800, v73
	ds_read_u8 v140, v141
	s_add_i32 s43, s67, 224
	v_mov_b32_e32 v138, s43
	ds_read2st64_b32 v[228:229], v138 offset1:1
	ds_read_b128 v[18:21], v227 offset:12288
	ds_read_b128 v[22:25], v227 offset:12304
	v_add_u32_e32 v152, 0x200000, v63
	v_add_u32_e32 v153, 0x200000, v64
	v_mov_b32_e32 v38, 0
	v_mov_b32_e32 v39, 0
	v_mov_b32_e32 v40, 0
	v_mov_b32_e32 v41, 0
	v_mov_b32_e32 v42, 0
	v_mov_b32_e32 v43, 0
	v_mov_b32_e32 v44, 0
	v_mov_b32_e32 v45, 0
	v_and_b32_e32 v78, 0xffff, v31
	v_lshrrev_b32_e32 v79, 16, v31
	v_lshl_add_u32 v78, v78, 7, v150
	v_lshl_add_u32 v79, v79, 7, v151
	s_mov_b32 m0, s77
	s_add_i32 s43, s77, 0x400
	global_load_lds_dwordx4 v78, s[50:51]
	s_mov_b32 m0, s43
	s_nop 0
	global_load_lds_dwordx4 v79, s[50:51]
	s_waitcnt vmcnt(8)
	v_add_u32_e32 v54, s79, v59
	v_add_u32_e32 v55, s79, v60
	v_add_u32_e32 v56, s79, v61
	v_add_u32_e32 v57, s79, v62
	ds_read_b64_tr_b4 v[50:51], v160 offset:128
	ds_read_b64_tr_b4 v[52:53], v160 offset:1152
	ds_read_b64_tr_b4 v[130:131], v54
	ds_read_b64_tr_b4 v[132:133], v55
	ds_read_b64_tr_b4 v[134:135], v56
	ds_read_b64_tr_b4 v[136:137], v57
	s_waitcnt lgkmcnt(12)
	s_waitcnt vmcnt(35) lgkmcnt(15)
	v_lshlrev_b32_e32 v210, 16, v194
	v_and_b32_e32 v211, 0xffff0000, v194
	v_lshlrev_b32_e32 v142, 16, v202
	v_and_b32_e32 v143, 0xffff0000, v202
	v_add_f32_e32 v210, v210, v142
	v_add_f32_e32 v211, v211, v143
	v_lshlrev_b32_e32 v212, 16, v195
	v_and_b32_e32 v213, 0xffff0000, v195
	v_lshlrev_b32_e32 v142, 16, v203
	v_and_b32_e32 v143, 0xffff0000, v203
	v_add_f32_e32 v212, v212, v142
	v_add_f32_e32 v213, v213, v143
	v_lshlrev_b32_e32 v214, 16, v196
	v_and_b32_e32 v215, 0xffff0000, v196
	v_lshlrev_b32_e32 v142, 16, v204
	v_and_b32_e32 v143, 0xffff0000, v204
	v_add_f32_e32 v214, v214, v142
	v_add_f32_e32 v215, v215, v143
	v_lshlrev_b32_e32 v216, 16, v197
	v_and_b32_e32 v217, 0xffff0000, v197
	v_lshlrev_b32_e32 v142, 16, v205
	v_and_b32_e32 v143, 0xffff0000, v205
	v_add_f32_e32 v216, v216, v142
	v_add_f32_e32 v217, v217, v143
	v_lshlrev_b32_e32 v218, 16, v198
	v_and_b32_e32 v219, 0xffff0000, v198
	v_lshlrev_b32_e32 v142, 16, v206
	v_and_b32_e32 v143, 0xffff0000, v206
	v_add_f32_e32 v218, v218, v142
	v_add_f32_e32 v219, v219, v143
	v_lshlrev_b32_e32 v220, 16, v199
	v_and_b32_e32 v221, 0xffff0000, v199
	v_lshlrev_b32_e32 v142, 16, v207
	v_and_b32_e32 v143, 0xffff0000, v207
	v_add_f32_e32 v220, v220, v142
	v_add_f32_e32 v221, v221, v143
	v_lshlrev_b32_e32 v222, 16, v200
	v_and_b32_e32 v223, 0xffff0000, v200
	v_lshlrev_b32_e32 v142, 16, v208
	v_and_b32_e32 v143, 0xffff0000, v208
	v_add_f32_e32 v222, v222, v142
	v_add_f32_e32 v223, v223, v143
	v_lshlrev_b32_e32 v224, 16, v201
	v_and_b32_e32 v225, 0xffff0000, v201
	v_lshlrev_b32_e32 v142, 16, v209
	v_and_b32_e32 v143, 0xffff0000, v209
	v_add_f32_e32 v224, v224, v142
; #define LAS __attribute__((address_space(3)))
; #define WS_DPP_(x, ctrl) __builtin_bit_cast(float, __builtin_amdgcn_update_dpp(0, __builtin_bit_cast(int, x), ctrl, 0xf, 0xf, false))
; __device__ __forceinline__ float wave_sum(float v) {
;     ...
;     v += WS_DPP_(v, 0xB1); v += WS_DPP_(v, 0x4E); v += WS_DPP_(v, 0x141); v += WS_DPP_(v, 0x140);
;     ...
;     const int vi = __builtin_bit_cast(int, v);
;     return (__builtin_bit_cast(float, __builtin_amdgcn_readlane(vi, 0)) + __builtin_bit_cast(float, __builtin_amdgcn_readlane(vi, 16))) +
;            (__builtin_bit_cast(float, __builtin_amdgcn_readlane(vi, 32)) + __builtin_bit_cast(float, __builtin_amdgcn_readlane(vi, 48)));
; }
; __device__ __forceinline__ void peer_v_tokens(int j, const LAS unsigned short* EL, const LAS unsigned char* AL  , const LAS float* ASC  , const LAS int* SAL  , ...
;     ...
;         {
;             float4 v[4]; float ss = 0.f;
; #pragma unroll
;             for (int jq = 0; jq < 4; ++jq) { typedef unsigned u2v __attribute__((ext_vector_type(2))); const u2v pw = *(const LAS u2v*)(STASH + 4 * lane + 256 * jq); const uint2 hw = hv[jq];
;                 v[jq] = make_float4(__uint_as_float(hw.x << 16) + __uint_as_float(pw.x << 16), __uint_as_float(hw.x & 0xffff0000u) + __uint_as_float(pw.x & 0xffff0000u),
;                                     __uint_as_float(hw.y << 16) + __uint_as_float(pw.y << 16), __uint_as_float(hw.y & 0xffff0000u) + __uint_as_float(pw.y & 0xffff0000u));
;                 ss += v[jq].x * v[jq].x + v[jq].y * v[jq].y + v[jq].z * v[jq].z + v[jq].w * v[jq].w; }
;             ss = wave_sum(ss);
;             const float r3 = rsqrtf(ss * (1.f / D) + EPS);
;             float4* op = (float4*)(outp + (size_t)t * D) + lane;
; #pragma unroll
;             for (int jq = 0; jq < 4; ++jq) { typedef float f4v __attribute__((ext_vector_type(4))); f4v o4; o4.x = v[jq].x * r3 * gv[jq].x; o4.y = v[jq].y * r3 * gv[jq].y; o4.z = v[jq].z * r3 * gv[jq].z; o4.w = v[jq].w * r3 * gv[jq].w;
	v_add_f32_e32 v225, v225, v143
	v_mov_b32_e32 v144, 0
	v_mul_f32_e32 v145, v210, v210
	v_fmac_f32_e32 v145, v211, v211
	v_fmac_f32_e32 v145, v212, v212
	v_fmac_f32_e32 v145, v213, v213
	v_add_f32_e32 v144, v144, v145
	v_mul_f32_e32 v145, v214, v214
	v_fmac_f32_e32 v145, v215, v215
	v_fmac_f32_e32 v145, v216, v216
	v_fmac_f32_e32 v145, v217, v217
	v_add_f32_e32 v144, v144, v145
	v_mul_f32_e32 v145, v218, v218
	v_fmac_f32_e32 v145, v219, v219
	v_fmac_f32_e32 v145, v220, v220
	v_fmac_f32_e32 v145, v221, v221
	v_add_f32_e32 v144, v144, v145
	v_mul_f32_e32 v145, v222, v222
	v_fmac_f32_e32 v145, v223, v223
	v_fmac_f32_e32 v145, v224, v224
	v_fmac_f32_e32 v145, v225, v225
	v_add_f32_e32 v144, v144, v145
	s_nop 1
	v_add_f32_dpp v144, v144, v144 quad_perm:[1,0,3,2] row_mask:0xf bank_mask:0xf bound_ctrl:1
	s_nop 1
	v_add_f32_dpp v144, v144, v144 quad_perm:[2,3,0,1] row_mask:0xf bank_mask:0xf bound_ctrl:1
	s_nop 1
	v_add_f32_dpp v144, v144, v144 row_half_mirror row_mask:0xf bank_mask:0xf bound_ctrl:1
	s_nop 1
	v_add_f32_dpp v144, v144, v144 row_mirror row_mask:0xf bank_mask:0xf bound_ctrl:1
	s_nop 1
	v_readlane_b32 s10, v144, 0
	v_readlane_b32 s11, v144, 16
	v_readlane_b32 s14, v144, 32
	v_readlane_b32 s15, v144, 48
	s_nop 3
	v_mov_b32_e32 v144, s11
	v_mov_b32_e32 v145, s15
	v_add_f32_e32 v144, s10, v144
	v_add_f32_e32 v145, s14, v145
	v_add_f32_e32 v144, v144, v145
	v_fmamk_f32 v144, v144, 0x3a800000, v111
	v_rsq_f32_e32 v144, v144
	s_nop 0
	v_mul_f32_e32 v210, v210, v144
	v_mul_f32_e32 v211, v211, v144
	v_mul_f32_e32 v212, v212, v144
	v_mul_f32_e32 v213, v213, v144
	v_mul_f32_e32 v214, v214, v144
	v_mul_f32_e32 v215, v215, v144
	v_mul_f32_e32 v216, v216, v144
	v_mul_f32_e32 v217, v217, v144
	v_mul_f32_e32 v218, v218, v144
	v_mul_f32_e32 v219, v219, v144
	v_mul_f32_e32 v220, v220, v144
	v_mul_f32_e32 v221, v221, v144
	v_mul_f32_e32 v222, v222, v144
	v_mul_f32_e32 v223, v223, v144
	v_mul_f32_e32 v224, v224, v144
	v_mul_f32_e32 v225, v225, v144
	v_dot8c_i32_i4_e32 v38, v122, v48
	v_dot8c_i32_i4_e32 v39, v122, v46
	v_dot8c_i32_i4_e32 v40, v124, v48
	v_dot8c_i32_i4_e32 v41, v124, v46
	v_dot8c_i32_i4_e32 v42, v126, v48
	v_dot8c_i32_i4_e32 v43, v126, v46
	v_dot8c_i32_i4_e32 v44, v128, v48
	v_dot8c_i32_i4_e32 v45, v128, v46
	v_dot8c_i32_i4_e32 v38, v123, v49
	v_dot8c_i32_i4_e32 v39, v123, v47
	v_dot8c_i32_i4_e32 v40, v125, v49
	v_dot8c_i32_i4_e32 v41, v125, v47
	v_dot8c_i32_i4_e32 v42, v127, v49
	v_dot8c_i32_i4_e32 v43, v127, v47
	v_dot8c_i32_i4_e32 v44, v129, v49
	v_dot8c_i32_i4_e32 v45, v129, v47
	v_and_b32_e32 v78, 0xffff, v32
	v_lshrrev_b32_e32 v79, 16, v32
	v_lshl_add_u32 v78, v78, 7, v150
	v_lshl_add_u32 v79, v79, 7, v151
	s_mov_b32 m0, s78
	s_add_i32 s43, s78, 0x400
	global_load_lds_dwordx4 v78, s[50:51]
	s_mov_b32 m0, s43
	s_nop 0
	global_load_lds_dwordx4 v79, s[50:51]
	s_waitcnt vmcnt(8)
	v_add_u32_e32 v54, s98, v59
	v_add_u32_e32 v55, s98, v60
	v_add_u32_e32 v56, s98, v61
	v_add_u32_e32 v57, s98, v62
	ds_read_b64_tr_b4 v[46:47], v160 offset:256
	ds_read_b64_tr_b4 v[48:49], v160 offset:1280
	ds_read_b64_tr_b4 v[122:123], v54
	ds_read_b64_tr_b4 v[124:125], v55
	ds_read_b64_tr_b4 v[126:127], v56
	ds_read_b64_tr_b4 v[128:129], v57
	s_waitcnt lgkmcnt(6)
	v_dot8c_i32_i4_e32 v38, v130, v52
	v_dot8c_i32_i4_e32 v39, v130, v50
	v_dot8c_i32_i4_e32 v40, v132, v52
	v_dot8c_i32_i4_e32 v41, v132, v50
	v_dot8c_i32_i4_e32 v42, v134, v52
	v_dot8c_i32_i4_e32 v43, v134, v50
	v_dot8c_i32_i4_e32 v44, v136, v52
	v_dot8c_i32_i4_e32 v45, v136, v50
	v_dot8c_i32_i4_e32 v38, v131, v53
	v_dot8c_i32_i4_e32 v39, v131, v51
	v_dot8c_i32_i4_e32 v40, v133, v53
	v_dot8c_i32_i4_e32 v41, v133, v51
	v_dot8c_i32_i4_e32 v42, v135, v53
	v_dot8c_i32_i4_e32 v43, v135, v51
	v_dot8c_i32_i4_e32 v44, v137, v53
	v_dot8c_i32_i4_e32 v45, v137, v51
	v_and_b32_e32 v78, 0xffff, v33
	v_lshrrev_b32_e32 v79, 16, v33
	v_lshl_add_u32 v78, v78, 7, v150
	v_lshl_add_u32 v79, v79, 7, v151
	s_mov_b32 m0, s79
	s_add_i32 s43, s79, 0x400
	global_load_lds_dwordx4 v78, s[50:51]
	s_mov_b32 m0, s43
	s_nop 0
	global_load_lds_dwordx4 v79, s[50:51]
	s_waitcnt vmcnt(8)
	v_add_u32_e32 v54, s99, v59
	v_add_u32_e32 v55, s99, v60
	v_add_u32_e32 v56, s99, v61
	v_add_u32_e32 v57, s99, v62
	ds_read_b64_tr_b4 v[50:51], v160 offset:384
	ds_read_b64_tr_b4 v[52:53], v160 offset:1408
	ds_read_b64_tr_b4 v[130:131], v54
	ds_read_b64_tr_b4 v[132:133], v55
	ds_read_b64_tr_b4 v[134:135], v56
	ds_read_b64_tr_b4 v[136:137], v57
	s_waitcnt lgkmcnt(6)
	v_dot8c_i32_i4_e32 v38, v122, v48
	v_dot8c_i32_i4_e32 v39, v122, v46
	v_dot8c_i32_i4_e32 v40, v124, v48
	v_dot8c_i32_i4_e32 v41, v124, v46
	v_dot8c_i32_i4_e32 v42, v126, v48
	v_dot8c_i32_i4_e32 v43, v126, v46
	v_dot8c_i32_i4_e32 v44, v128, v48
	v_dot8c_i32_i4_e32 v45, v128, v46
	v_dot8c_i32_i4_e32 v38, v123, v49
	v_dot8c_i32_i4_e32 v39, v123, v47
	v_dot8c_i32_i4_e32 v40, v125, v49
	v_dot8c_i32_i4_e32 v41, v125, v47
	v_dot8c_i32_i4_e32 v42, v127, v49
	v_dot8c_i32_i4_e32 v43, v127, v47
	v_dot8c_i32_i4_e32 v44, v129, v49
	v_dot8c_i32_i4_e32 v45, v129, v47
	s_waitcnt lgkmcnt(15)
	v_and_b32_e32 v78, 0xffff, v18
	v_lshrrev_b32_e32 v79, 16, v18
	v_lshl_add_u32 v78, v78, 7, v152
	v_lshl_add_u32 v79, v79, 7, v153
	s_mov_b32 m0, s98
	s_add_i32 s43, s98, 0x400
	global_load_lds_dwordx4 v78, s[50:51]
	s_mov_b32 m0, s43
	s_nop 0
	global_load_lds_dwordx4 v79, s[50:51]
	s_waitcnt vmcnt(8)
	v_add_u32_e32 v54, s76, v59
	v_add_u32_e32 v55, s76, v60
	v_add_u32_e32 v56, s76, v61
	v_add_u32_e32 v57, s76, v62
	ds_read_b64_tr_b4 v[46:47], v160 offset:512
	ds_read_b64_tr_b4 v[48:49], v160 offset:1536
	ds_read_b64_tr_b4 v[122:123], v54
	ds_read_b64_tr_b4 v[124:125], v55
	ds_read_b64_tr_b4 v[126:127], v56
	ds_read_b64_tr_b4 v[128:129], v57
	s_waitcnt lgkmcnt(6)
; #define TR4(p_) __builtin_amdgcn_ds_read_tr4_b64_v2i32((LAS v2i*)(p_))
; #define VDMA(st_, k_) do { _Pragma("unroll") for (int i_ = 0; i_ < 4; ++i_) { \
;         const unsigned off_ = (unsigned)((st_) >> 2) * (16384u * 128u) + (PE_ID(E, 4 * ((st_) & 3) + i_) << 7) + ((i_ & 1) ? cx1 : cx0); \
;         __builtin_amdgcn_global_load_lds((const unsigned*)(V4 + off_), (LAS unsigned*)(ldsb + BUF[k_] + 1024 * i_), 16, 0, 0); } } while (0)
; __device__ __forceinline__ void peer_v_tokens(int j, const LAS unsigned short* EL, const LAS unsigned char* AL  , const LAS float* ASC  , const LAS int* SAL  , ...
;     ...
;         for (int st = 0; st < 16; ++st) {
;             const int p = st >> 2, q = st & 3;
;             if (st < 14) VDMA(st + 2, (st + 2) % 3);
;             if (st < 14) asm volatile("s_waitcnt vmcnt(8)" ::: "memory");
;             else if (st == 14) asm volatile("s_waitcnt vmcnt(4)" ::: "memory");
;             else asm volatile("s_waitcnt vmcnt(0)" ::: "memory");
;             if (q == 0) {
; #pragma unroll
;                 for (int r = 0; r < 4; ++r) { accH[r] = 0; accL[r] = 0; } }
; #pragma unroll
;             for (int tp = 0; tp < 2; ++tp) {
;                 const v2i ao = TR4(ATL + (2 * q + tp) * 128 + 8 * s16), ah = TR4(ATL + 1024 + (2 * q + tp) * 128 + 8 * s16);
; #pragma unroll
;                 for (int r = 0; r < 4; ++r) {
;                     const v2i d = TR4(ldsb + BUF[st % 3] + 2048 * tp + roff[r]);
;                     accH[r] = __builtin_amdgcn_sdot8(d.x, ah.x, accH[r], false); accH[r] = __builtin_amdgcn_sdot8(d.y, ah.y, accH[r], false);
;                     accL[r] = __builtin_amdgcn_sdot8(d.x, ao.x, accL[r], false); accL[r] = __builtin_amdgcn_sdot8(d.y, ao.y, accL[r], false);
;                 }
;             }
	v_dot8c_i32_i4_e32 v38, v130, v52
	v_dot8c_i32_i4_e32 v39, v130, v50
	v_dot8c_i32_i4_e32 v40, v132, v52
	v_dot8c_i32_i4_e32 v41, v132, v50
	v_dot8c_i32_i4_e32 v42, v134, v52
	v_dot8c_i32_i4_e32 v43, v134, v50
	v_dot8c_i32_i4_e32 v44, v136, v52
	v_dot8c_i32_i4_e32 v45, v136, v50
	v_dot8c_i32_i4_e32 v38, v131, v53
	v_dot8c_i32_i4_e32 v39, v131, v51
	v_dot8c_i32_i4_e32 v40, v133, v53
	v_dot8c_i32_i4_e32 v41, v133, v51
	v_dot8c_i32_i4_e32 v42, v135, v53
	v_dot8c_i32_i4_e32 v43, v135, v51
	v_dot8c_i32_i4_e32 v44, v137, v53
	v_dot8c_i32_i4_e32 v45, v137, v51
	v_and_b32_e32 v78, 0xffff, v19
	v_lshrrev_b32_e32 v79, 16, v19
	v_lshl_add_u32 v78, v78, 7, v152
	v_lshl_add_u32 v79, v79, 7, v153
	s_mov_b32 m0, s99
	s_add_i32 s43, s99, 0x400
	global_load_lds_dwordx4 v78, s[50:51]
	s_mov_b32 m0, s43
	s_nop 0
	global_load_lds_dwordx4 v79, s[50:51]
	s_waitcnt vmcnt(8)
	v_add_u32_e32 v54, s77, v59
	v_add_u32_e32 v55, s77, v60
	v_add_u32_e32 v56, s77, v61
	v_add_u32_e32 v57, s77, v62
	ds_read_b64_tr_b4 v[50:51], v160 offset:640
	ds_read_b64_tr_b4 v[52:53], v160 offset:1664
	ds_read_b64_tr_b4 v[130:131], v54
	ds_read_b64_tr_b4 v[132:133], v55
	ds_read_b64_tr_b4 v[134:135], v56
	ds_read_b64_tr_b4 v[136:137], v57
	s_waitcnt lgkmcnt(6)
	v_dot8c_i32_i4_e32 v38, v122, v48
	v_dot8c_i32_i4_e32 v39, v122, v46
	v_dot8c_i32_i4_e32 v40, v124, v48
	v_dot8c_i32_i4_e32 v41, v124, v46
	v_dot8c_i32_i4_e32 v42, v126, v48
	v_dot8c_i32_i4_e32 v43, v126, v46
	v_dot8c_i32_i4_e32 v44, v128, v48
	v_dot8c_i32_i4_e32 v45, v128, v46
	v_dot8c_i32_i4_e32 v38, v123, v49
	v_dot8c_i32_i4_e32 v39, v123, v47
	v_dot8c_i32_i4_e32 v40, v125, v49
	v_dot8c_i32_i4_e32 v41, v125, v47
	v_dot8c_i32_i4_e32 v42, v127, v49
	v_dot8c_i32_i4_e32 v43, v127, v47
	v_dot8c_i32_i4_e32 v44, v129, v49
	v_dot8c_i32_i4_e32 v45, v129, v47
	s_waitcnt lgkmcnt(15)
	v_add_u32_e32 v143, 8, v139
	v_and_b32_e32 v142, 15, v143
	v_xor_b32_e32 v142, 8, v142
	v_bfe_u32 v144, v143, 4, 4
	v_mul_lo_u32 v142, v142, s92
	v_mul_lo_u32 v144, v144, s92
	v_mov_b32_e32 v143, v142
	v_mov_b32_e32 v145, v144
	ds_write2st64_b64 v159, v[142:143], v[144:145] offset1:2
	v_and_b32_e32 v78, 0xffff, v20
	v_lshrrev_b32_e32 v79, 16, v20
	v_lshl_add_u32 v78, v78, 7, v152
	v_lshl_add_u32 v79, v79, 7, v153
	s_mov_b32 m0, s76
	s_add_i32 s43, s76, 0x400
	global_load_lds_dwordx4 v78, s[50:51]
	s_mov_b32 m0, s43
	s_nop 0
	global_load_lds_dwordx4 v79, s[50:51]
	s_waitcnt vmcnt(8)
	v_add_u32_e32 v54, s78, v59
	v_add_u32_e32 v55, s78, v60
	v_add_u32_e32 v56, s78, v61
	v_add_u32_e32 v57, s78, v62
	ds_read_b64_tr_b4 v[46:47], v160 offset:768
	ds_read_b64_tr_b4 v[48:49], v160 offset:1792
	ds_read_b64_tr_b4 v[122:123], v54
	ds_read_b64_tr_b4 v[124:125], v55
	ds_read_b64_tr_b4 v[126:127], v56
	ds_read_b64_tr_b4 v[128:129], v57
	s_waitcnt lgkmcnt(7)
	v_dot8c_i32_i4_e32 v38, v130, v52
	v_dot8c_i32_i4_e32 v39, v130, v50
	v_dot8c_i32_i4_e32 v40, v132, v52
	v_dot8c_i32_i4_e32 v41, v132, v50
	v_dot8c_i32_i4_e32 v42, v134, v52
	v_dot8c_i32_i4_e32 v43, v134, v50
	v_dot8c_i32_i4_e32 v44, v136, v52
	v_dot8c_i32_i4_e32 v45, v136, v50
	v_dot8c_i32_i4_e32 v38, v131, v53
	v_dot8c_i32_i4_e32 v39, v131, v51
	v_dot8c_i32_i4_e32 v40, v133, v53
	v_dot8c_i32_i4_e32 v41, v133, v51
	v_dot8c_i32_i4_e32 v42, v135, v53
	v_dot8c_i32_i4_e32 v43, v135, v51
	v_dot8c_i32_i4_e32 v44, v137, v53
	v_dot8c_i32_i4_e32 v45, v137, v51
	v_and_b32_e32 v78, 0xffff, v21
	v_lshrrev_b32_e32 v79, 16, v21
	v_lshl_add_u32 v78, v78, 7, v152
	v_lshl_add_u32 v79, v79, 7, v153
	s_mov_b32 m0, s77
	s_add_i32 s43, s77, 0x400
	global_load_lds_dwordx4 v78, s[50:51]
	s_mov_b32 m0, s43
	s_nop 0
	global_load_lds_dwordx4 v79, s[50:51]
	s_waitcnt vmcnt(8)
	v_add_u32_e32 v54, s79, v59
	v_add_u32_e32 v55, s79, v60
	v_add_u32_e32 v56, s79, v61
	v_add_u32_e32 v57, s79, v62
	ds_read_b64_tr_b4 v[50:51], v160 offset:896
	ds_read_b64_tr_b4 v[52:53], v160 offset:1920
	ds_read_b64_tr_b4 v[130:131], v54
	ds_read_b64_tr_b4 v[132:133], v55
	ds_read_b64_tr_b4 v[134:135], v56
	ds_read_b64_tr_b4 v[136:137], v57
	s_waitcnt lgkmcnt(6)
	v_dot8c_i32_i4_e32 v38, v122, v48
	v_dot8c_i32_i4_e32 v39, v122, v46
	v_dot8c_i32_i4_e32 v40, v124, v48
	v_dot8c_i32_i4_e32 v41, v124, v46
	v_dot8c_i32_i4_e32 v42, v126, v48
	v_dot8c_i32_i4_e32 v43, v126, v46
	v_dot8c_i32_i4_e32 v44, v128, v48
	v_dot8c_i32_i4_e32 v45, v128, v46
	v_dot8c_i32_i4_e32 v38, v123, v49
	v_dot8c_i32_i4_e32 v39, v123, v47
	v_dot8c_i32_i4_e32 v40, v125, v49
	v_dot8c_i32_i4_e32 v41, v125, v47
	v_dot8c_i32_i4_e32 v42, v127, v49
	v_dot8c_i32_i4_e32 v43, v127, v47
	v_dot8c_i32_i4_e32 v44, v129, v49
	v_dot8c_i32_i4_e32 v45, v129, v47
	v_and_b32_e32 v78, 0xffff, v22
	v_lshrrev_b32_e32 v79, 16, v22
	v_lshl_add_u32 v78, v78, 7, v152
	v_lshl_add_u32 v79, v79, 7, v153
	s_mov_b32 m0, s78
	s_add_i32 s43, s78, 0x400
	global_load_lds_dwordx4 v78, s[50:51]
	s_mov_b32 m0, s43
	s_nop 0
	global_load_lds_dwordx4 v79, s[50:51]
	s_waitcnt vmcnt(8)
	v_add_u32_e32 v54, s98, v59
	v_add_u32_e32 v55, s98, v60
	v_add_u32_e32 v56, s98, v61
	v_add_u32_e32 v57, s98, v62
	ds_read_b64_tr_b4 v[46:47], v160
	ds_read_b64_tr_b4 v[48:49], v160 offset:1024
	ds_read_b64_tr_b4 v[122:123], v54
	ds_read_b64_tr_b4 v[124:125], v55
	ds_read_b64_tr_b4 v[126:127], v56
	ds_read_b64_tr_b4 v[128:129], v57
	s_waitcnt lgkmcnt(6)
	v_dot8c_i32_i4_e32 v38, v130, v52
	v_dot8c_i32_i4_e32 v39, v130, v50
	v_dot8c_i32_i4_e32 v40, v132, v52
	v_dot8c_i32_i4_e32 v41, v132, v50
	v_dot8c_i32_i4_e32 v42, v134, v52
	v_dot8c_i32_i4_e32 v43, v134, v50
	v_dot8c_i32_i4_e32 v44, v136, v52
	v_dot8c_i32_i4_e32 v45, v136, v50
	v_dot8c_i32_i4_e32 v38, v131, v53
	v_dot8c_i32_i4_e32 v39, v131, v51
	v_dot8c_i32_i4_e32 v40, v133, v53
	v_dot8c_i32_i4_e32 v41, v133, v51
	v_dot8c_i32_i4_e32 v42, v135, v53
	v_dot8c_i32_i4_e32 v43, v135, v51
	v_dot8c_i32_i4_e32 v44, v137, v53
	v_dot8c_i32_i4_e32 v45, v137, v51
	s_nop 3
	s_waitcnt lgkmcnt(15)
; __device__ __forceinline__ void peer_v_tokens(int j, const LAS unsigned short* EL, const LAS unsigned char* AL  , const LAS float* ASC  , const LAS int* SAL  , ...
;     ...
;         { const LAS v4u* ep = (const LAS v4u*)(EL + tl * 128 + 16 * g); const v4u e0 = ep[0], e1 = ep[1];
;           E[0] = e0.x; E[1] = e0.y; E[2] = e0.z; E[3] = e0.w; E[4] = e1.x; E[5] = e1.y; E[6] = e1.z; E[7] = e1.w; }
;         uint2 hv[4]; float4 gv[4];
;         { unsigned ho = (unsigned)t * (D / 4) + (unsigned)lane; asm volatile("" : "+v"(ho)); const uint2* hp = (const uint2*)HB + ho; const float4* gp = (const float4*)fng + lane;
; #pragma unroll
;           for (int jq = 0; jq < 4; ++jq) { hv[jq] = hp[64 * jq]; gv[jq] = gp[64 * jq]; } }
;         VDMA(0, 0); VDMA(1, 1);
; #pragma unroll
;         for (int m = 0; m < 2; ++m) {
;             const int idx = lane + 64 * m, tau = idx >> 4, sr = idx & 15, k = 16 * (sr & 7) + 2 * tau + (sr >> 3);
;     ...
;         for (int st = 0; st < 16; ++st) {
;             const int p = st >> 2, q = st & 3;
;             if (st < 14) VDMA(st + 2, (st + 2) % 3);
;             if (st < 14) asm volatile("s_waitcnt vmcnt(8)" ::: "memory");
;             else if (st == 14) asm volatile("s_waitcnt vmcnt(4)" ::: "memory");
;             else asm volatile("s_waitcnt vmcnt(0)" ::: "memory");
;             if (q == 0) {
; #pragma unroll
;                 for (int r = 0; r < 4; ++r) { accH[r] = 0; accL[r] = 0; } }
; #pragma unroll
;             for (int tp = 0; tp < 2; ++tp) {
;                 const v2i ao = TR4(ATL + (2 * q + tp) * 128 + 8 * s16), ah = TR4(ATL + 1024 + (2 * q + tp) * 128 + 8 * s16);
; #pragma unroll
;                 for (int r = 0; r < 4; ++r) {
;                     const v2i d = TR4(ldsb + BUF[st % 3] + 2048 * tp + roff[r]);
;                     accH[r] = __builtin_amdgcn_sdot8(d.x, ah.x, accH[r], false); accH[r] = __builtin_amdgcn_sdot8(d.y, ah.y, accH[r], false);
;                     accL[r] = __builtin_amdgcn_sdot8(d.x, ao.x, accL[r], false); accL[r] = __builtin_amdgcn_sdot8(d.y, ao.y, accL[r], false);
;                 }
;             }
;             asm volatile("s_waitcnt lgkmcnt(0)" ::: "memory");
;             if (q == 3) {
; #pragma unroll
;                 for (int r = 0; r < 4; ++r) STASH[256 * p + 16 * (grp + 4 * r) + pc] = f2bf(asc * (float)(2 * ((accH[r] << 4) + accL[r]) + sa));
;             }
	v_lshlrev_b32_e32 v38, 5, v38
	v_lshlrev_b32_e32 v39, 1, v39
	v_add3_u32 v38, v39, v229, v38
	v_cvt_f32_i32_e32 v38, v38
	v_mul_f32_e32 v38, v228, v38
	v_lshlrev_b32_e32 v40, 5, v40
	v_lshlrev_b32_e32 v41, 1, v41
	v_add3_u32 v40, v41, v229, v40
	v_cvt_f32_i32_e32 v40, v40
	v_mul_f32_e32 v40, v228, v40
	v_lshlrev_b32_e32 v42, 5, v42
	v_lshlrev_b32_e32 v43, 1, v43
	v_add3_u32 v42, v43, v229, v42
	v_cvt_f32_i32_e32 v42, v42
	v_mul_f32_e32 v42, v228, v42
	v_lshlrev_b32_e32 v44, 5, v44
	v_lshlrev_b32_e32 v45, 1, v45
	v_add3_u32 v44, v45, v229, v44
	v_cvt_f32_i32_e32 v44, v44
	v_mul_f32_e32 v44, v228, v44
	v_cvt_pk_bf16_f32 v186, v38, v40
	v_cvt_pk_bf16_f32 v187, v42, v44
	ds_read_b128 v[252:255], v155
	s_add_i32 s44, s40, 32
	s_ashr_i32 s45, s44, 31
	s_lshl_b64 s[44:45], s[44:45], 12
	v_lshl_add_u64 v[80:81], v[36:37], 0, s[44:45]
	s_waitcnt lgkmcnt(0)
	v_mul_f32_e32 v210, v210, v252
	v_mul_f32_e32 v211, v211, v253
	v_mul_f32_e32 v212, v212, v254
	v_mul_f32_e32 v213, v213, v255
	global_store_dwordx4 v[80:81], v[210:213], off nt
	s_add_i32 s43, s40, 40
	s_lshl_b32 s43, s43, 11
	v_add_u32_e32 v138, s43, v66
	global_load_dwordx2 v[194:195], v138, s[70:71]
	global_load_dwordx2 v[196:197], v138, s[70:71] offset:512
	global_load_dwordx2 v[198:199], v138, s[70:71] offset:1024
	global_load_dwordx2 v[200:201], v138, s[70:71] offset:1536
	v_add_u32_e32 v147, 8, v140
	v_and_b32_e32 v146, 15, v147
	v_xor_b32_e32 v146, 8, v146
	v_bfe_u32 v148, v147, 4, 4
	v_mul_lo_u32 v146, v146, s92
	v_mul_lo_u32 v148, v148, s92
	v_mov_b32_e32 v147, v146
	v_mov_b32_e32 v149, v148
	ds_write2st64_b64 v77, v[146:147], v[148:149] offset1:2
	v_add_u32_e32 v138, 0x1c00, v74
	ds_read_u8 v139, v138
	v_add_u32_e32 v141, 0x1c00, v73
	ds_read_u8 v140, v141
	s_add_i32 s43, s67, 192
	v_mov_b32_e32 v138, s43
	ds_read2st64_b32 v[228:229], v138 offset1:1
	ds_read_b128 v[26:29], v227 offset:14336
	ds_read_b128 v[30:33], v227 offset:14352
	v_mov_b32_e32 v38, 0
	v_mov_b32_e32 v39, 0
	v_mov_b32_e32 v40, 0
	v_mov_b32_e32 v41, 0
	v_mov_b32_e32 v42, 0
	v_mov_b32_e32 v43, 0
	v_mov_b32_e32 v44, 0
	v_mov_b32_e32 v45, 0
	v_and_b32_e32 v78, 0xffff, v23
	v_lshrrev_b32_e32 v79, 16, v23
	v_lshl_add_u32 v78, v78, 7, v152
	v_lshl_add_u32 v79, v79, 7, v153
	s_mov_b32 m0, s79
	s_add_i32 s43, s79, 0x400
	global_load_lds_dwordx4 v78, s[50:51]
	s_mov_b32 m0, s43
	s_nop 0
	global_load_lds_dwordx4 v79, s[50:51]
	s_waitcnt vmcnt(13)
	v_add_u32_e32 v54, s99, v59
	v_add_u32_e32 v55, s99, v60
	v_add_u32_e32 v56, s99, v61
	v_add_u32_e32 v57, s99, v62
	ds_read_b64_tr_b4 v[50:51], v160 offset:128
	ds_read_b64_tr_b4 v[52:53], v160 offset:1152
	ds_read_b64_tr_b4 v[130:131], v54
	ds_read_b64_tr_b4 v[132:133], v55
	ds_read_b64_tr_b4 v[134:135], v56
	ds_read_b64_tr_b4 v[136:137], v57
	s_waitcnt lgkmcnt(13)
	v_dot8c_i32_i4_e32 v38, v122, v48
	v_dot8c_i32_i4_e32 v39, v122, v46
	v_dot8c_i32_i4_e32 v40, v124, v48
	v_dot8c_i32_i4_e32 v41, v124, v46
	v_dot8c_i32_i4_e32 v42, v126, v48
	v_dot8c_i32_i4_e32 v43, v126, v46
	v_dot8c_i32_i4_e32 v44, v128, v48
	v_dot8c_i32_i4_e32 v45, v128, v46
	v_dot8c_i32_i4_e32 v38, v123, v49
	v_dot8c_i32_i4_e32 v39, v123, v47
	v_dot8c_i32_i4_e32 v40, v125, v49
	v_dot8c_i32_i4_e32 v41, v125, v47
	v_dot8c_i32_i4_e32 v42, v127, v49
	v_dot8c_i32_i4_e32 v43, v127, v47
	v_dot8c_i32_i4_e32 v44, v129, v49
	v_dot8c_i32_i4_e32 v45, v129, v47
	v_and_b32_e32 v78, 0xffff, v24
	v_lshrrev_b32_e32 v79, 16, v24
	v_lshl_add_u32 v78, v78, 7, v152
	v_lshl_add_u32 v79, v79, 7, v153
	s_mov_b32 m0, s98
	s_add_i32 s43, s98, 0x400
	global_load_lds_dwordx4 v78, s[50:51]
	s_mov_b32 m0, s43
	s_nop 0
	global_load_lds_dwordx4 v79, s[50:51]
	s_waitcnt vmcnt(13)
	v_add_u32_e32 v54, s76, v59
	v_add_u32_e32 v55, s76, v60
	v_add_u32_e32 v56, s76, v61
	v_add_u32_e32 v57, s76, v62
	ds_read_b64_tr_b4 v[46:47], v160 offset:256
	ds_read_b64_tr_b4 v[48:49], v160 offset:1280
	ds_read_b64_tr_b4 v[122:123], v54
	ds_read_b64_tr_b4 v[124:125], v55
	ds_read_b64_tr_b4 v[126:127], v56
	ds_read_b64_tr_b4 v[128:129], v57
	s_waitcnt lgkmcnt(6)
	v_dot8c_i32_i4_e32 v38, v130, v52
	v_dot8c_i32_i4_e32 v39, v130, v50
	v_dot8c_i32_i4_e32 v40, v132, v52
	v_dot8c_i32_i4_e32 v41, v132, v50
	v_dot8c_i32_i4_e32 v42, v134, v52
	v_dot8c_i32_i4_e32 v43, v134, v50
	v_dot8c_i32_i4_e32 v44, v136, v52
	v_dot8c_i32_i4_e32 v45, v136, v50
	v_dot8c_i32_i4_e32 v38, v131, v53
	v_dot8c_i32_i4_e32 v39, v131, v51
	v_dot8c_i32_i4_e32 v40, v133, v53
	v_dot8c_i32_i4_e32 v41, v133, v51
	v_dot8c_i32_i4_e32 v42, v135, v53
	v_dot8c_i32_i4_e32 v43, v135, v51
	v_dot8c_i32_i4_e32 v44, v137, v53
	v_dot8c_i32_i4_e32 v45, v137, v51
	v_and_b32_e32 v78, 0xffff, v25
	v_lshrrev_b32_e32 v79, 16, v25
	v_lshl_add_u32 v78, v78, 7, v152
	v_lshl_add_u32 v79, v79, 7, v153
	s_mov_b32 m0, s99
	s_add_i32 s43, s99, 0x400
	global_load_lds_dwordx4 v78, s[50:51]
	s_mov_b32 m0, s43
	s_nop 0
	global_load_lds_dwordx4 v79, s[50:51]
	s_waitcnt vmcnt(13)
	v_add_u32_e32 v54, s77, v59
	v_add_u32_e32 v55, s77, v60
	v_add_u32_e32 v56, s77, v61
	v_add_u32_e32 v57, s77, v62
	ds_read_b64_tr_b4 v[50:51], v160 offset:384
	ds_read_b64_tr_b4 v[52:53], v160 offset:1408
	ds_read_b64_tr_b4 v[130:131], v54
	ds_read_b64_tr_b4 v[132:133], v55
	ds_read_b64_tr_b4 v[134:135], v56
	ds_read_b64_tr_b4 v[136:137], v57
	s_waitcnt lgkmcnt(6)
	v_dot8c_i32_i4_e32 v38, v122, v48
	v_dot8c_i32_i4_e32 v39, v122, v46
	v_dot8c_i32_i4_e32 v40, v124, v48
	v_dot8c_i32_i4_e32 v41, v124, v46
	v_dot8c_i32_i4_e32 v42, v126, v48
	v_dot8c_i32_i4_e32 v43, v126, v46
	v_dot8c_i32_i4_e32 v44, v128, v48
	v_dot8c_i32_i4_e32 v45, v128, v46
	v_dot8c_i32_i4_e32 v38, v123, v49
	v_dot8c_i32_i4_e32 v39, v123, v47
	v_dot8c_i32_i4_e32 v40, v125, v49
	v_dot8c_i32_i4_e32 v41, v125, v47
	v_dot8c_i32_i4_e32 v42, v127, v49
	v_dot8c_i32_i4_e32 v43, v127, v47
	v_dot8c_i32_i4_e32 v44, v129, v49
	v_dot8c_i32_i4_e32 v45, v129, v47
	s_waitcnt lgkmcnt(15)
; #define TR4(p_) __builtin_amdgcn_ds_read_tr4_b64_v2i32((LAS v2i*)(p_))
; #define VDMA(st_, k_) do { _Pragma("unroll") for (int i_ = 0; i_ < 4; ++i_) { \
;         const unsigned off_ = (unsigned)((st_) >> 2) * (16384u * 128u) + (PE_ID(E, 4 * ((st_) & 3) + i_) << 7) + ((i_ & 1) ? cx1 : cx0); \
;         __builtin_amdgcn_global_load_lds((const unsigned*)(V4 + off_), (LAS unsigned*)(ldsb + BUF[k_] + 1024 * i_), 16, 0, 0); } } while (0)
; __device__ __forceinline__ void peer_v_tokens(int j, const LAS unsigned short* EL, const LAS unsigned char* AL  , const LAS float* ASC  , const LAS int* SAL  , ...
;     ...
;         for (int st = 0; st < 16; ++st) {
;             const int p = st >> 2, q = st & 3;
;             if (st < 14) VDMA(st + 2, (st + 2) % 3);
;             if (st < 14) asm volatile("s_waitcnt vmcnt(8)" ::: "memory");
;             else if (st == 14) asm volatile("s_waitcnt vmcnt(4)" ::: "memory");
;             else asm volatile("s_waitcnt vmcnt(0)" ::: "memory");
;             if (q == 0) {
; #pragma unroll
;                 for (int r = 0; r < 4; ++r) { accH[r] = 0; accL[r] = 0; } }
; #pragma unroll
;             for (int tp = 0; tp < 2; ++tp) {
;                 const v2i ao = TR4(ATL + (2 * q + tp) * 128 + 8 * s16), ah = TR4(ATL + 1024 + (2 * q + tp) * 128 + 8 * s16);
; #pragma unroll
;                 for (int r = 0; r < 4; ++r) {
;                     const v2i d = TR4(ldsb + BUF[st % 3] + 2048 * tp + roff[r]);
;                     accH[r] = __builtin_amdgcn_sdot8(d.x, ah.x, accH[r], false); accH[r] = __builtin_amdgcn_sdot8(d.y, ah.y, accH[r], false);
;                     accL[r] = __builtin_amdgcn_sdot8(d.x, ao.x, accL[r], false); accL[r] = __builtin_amdgcn_sdot8(d.y, ao.y, accL[r], false);
;                 }
;             }
	v_and_b32_e32 v78, 0xffff, v26
	v_lshrrev_b32_e32 v79, 16, v26
	v_lshl_add_u32 v78, v78, 7, v152
	v_lshl_add_u32 v79, v79, 7, v153
	s_mov_b32 m0, s76
	s_add_i32 s43, s76, 0x400
	global_load_lds_dwordx4 v78, s[50:51]
	s_mov_b32 m0, s43
	s_nop 0
	global_load_lds_dwordx4 v79, s[50:51]
	s_waitcnt vmcnt(13)
	v_add_u32_e32 v54, s78, v59
	v_add_u32_e32 v55, s78, v60
	v_add_u32_e32 v56, s78, v61
	v_add_u32_e32 v57, s78, v62
	ds_read_b64_tr_b4 v[46:47], v160 offset:512
	ds_read_b64_tr_b4 v[48:49], v160 offset:1536
	ds_read_b64_tr_b4 v[122:123], v54
	ds_read_b64_tr_b4 v[124:125], v55
	ds_read_b64_tr_b4 v[126:127], v56
	ds_read_b64_tr_b4 v[128:129], v57
	s_waitcnt lgkmcnt(6)
	v_dot8c_i32_i4_e32 v38, v130, v52
	v_dot8c_i32_i4_e32 v39, v130, v50
	v_dot8c_i32_i4_e32 v40, v132, v52
	v_dot8c_i32_i4_e32 v41, v132, v50
	v_dot8c_i32_i4_e32 v42, v134, v52
	v_dot8c_i32_i4_e32 v43, v134, v50
	v_dot8c_i32_i4_e32 v44, v136, v52
	v_dot8c_i32_i4_e32 v45, v136, v50
	v_dot8c_i32_i4_e32 v38, v131, v53
	v_dot8c_i32_i4_e32 v39, v131, v51
	v_dot8c_i32_i4_e32 v40, v133, v53
	v_dot8c_i32_i4_e32 v41, v133, v51
	v_dot8c_i32_i4_e32 v42, v135, v53
	v_dot8c_i32_i4_e32 v43, v135, v51
	v_dot8c_i32_i4_e32 v44, v137, v53
	v_dot8c_i32_i4_e32 v45, v137, v51
	v_and_b32_e32 v78, 0xffff, v27
	v_lshrrev_b32_e32 v79, 16, v27
	v_lshl_add_u32 v78, v78, 7, v152
	v_lshl_add_u32 v79, v79, 7, v153
	s_mov_b32 m0, s77
	s_add_i32 s43, s77, 0x400
	global_load_lds_dwordx4 v78, s[50:51]
	s_mov_b32 m0, s43
	s_nop 0
	global_load_lds_dwordx4 v79, s[50:51]
	s_waitcnt vmcnt(8)
	v_add_u32_e32 v54, s79, v59
	v_add_u32_e32 v55, s79, v60
	v_add_u32_e32 v56, s79, v61
	v_add_u32_e32 v57, s79, v62
	ds_read_b64_tr_b4 v[50:51], v160 offset:640
	ds_read_b64_tr_b4 v[52:53], v160 offset:1664
	ds_read_b64_tr_b4 v[130:131], v54
	ds_read_b64_tr_b4 v[132:133], v55
	ds_read_b64_tr_b4 v[134:135], v56
	ds_read_b64_tr_b4 v[136:137], v57
	s_waitcnt lgkmcnt(6)
	v_dot8c_i32_i4_e32 v38, v122, v48
	v_dot8c_i32_i4_e32 v39, v122, v46
	v_dot8c_i32_i4_e32 v40, v124, v48
	v_dot8c_i32_i4_e32 v41, v124, v46
	v_dot8c_i32_i4_e32 v42, v126, v48
	v_dot8c_i32_i4_e32 v43, v126, v46
	v_dot8c_i32_i4_e32 v44, v128, v48
	v_dot8c_i32_i4_e32 v45, v128, v46
	v_dot8c_i32_i4_e32 v38, v123, v49
	v_dot8c_i32_i4_e32 v39, v123, v47
	v_dot8c_i32_i4_e32 v40, v125, v49
	v_dot8c_i32_i4_e32 v41, v125, v47
	v_dot8c_i32_i4_e32 v42, v127, v49
	v_dot8c_i32_i4_e32 v43, v127, v47
	v_dot8c_i32_i4_e32 v44, v129, v49
	v_dot8c_i32_i4_e32 v45, v129, v47
	s_waitcnt lgkmcnt(15)
	v_add_u32_e32 v143, 8, v139
	v_and_b32_e32 v142, 15, v143
	v_xor_b32_e32 v142, 8, v142
	v_bfe_u32 v144, v143, 4, 4
	v_mul_lo_u32 v142, v142, s92
	v_mul_lo_u32 v144, v144, s92
	v_mov_b32_e32 v143, v142
	v_mov_b32_e32 v145, v144
	ds_write2st64_b64 v159, v[142:143], v[144:145] offset1:2
	v_and_b32_e32 v78, 0xffff, v28
	v_lshrrev_b32_e32 v79, 16, v28
	v_lshl_add_u32 v78, v78, 7, v152
	v_lshl_add_u32 v79, v79, 7, v153
	s_mov_b32 m0, s78
	s_add_i32 s43, s78, 0x400
	global_load_lds_dwordx4 v78, s[50:51]
	s_mov_b32 m0, s43
	s_nop 0
	global_load_lds_dwordx4 v79, s[50:51]
	s_waitcnt vmcnt(8)
	v_add_u32_e32 v54, s98, v59
	v_add_u32_e32 v55, s98, v60
	v_add_u32_e32 v56, s98, v61
	v_add_u32_e32 v57, s98, v62
	ds_read_b64_tr_b4 v[46:47], v160 offset:768
	ds_read_b64_tr_b4 v[48:49], v160 offset:1792
	ds_read_b64_tr_b4 v[122:123], v54
	ds_read_b64_tr_b4 v[124:125], v55
	ds_read_b64_tr_b4 v[126:127], v56
	ds_read_b64_tr_b4 v[128:129], v57
	s_waitcnt lgkmcnt(7)
	v_dot8c_i32_i4_e32 v38, v130, v52
	v_dot8c_i32_i4_e32 v39, v130, v50
	v_dot8c_i32_i4_e32 v40, v132, v52
	v_dot8c_i32_i4_e32 v41, v132, v50
	v_dot8c_i32_i4_e32 v42, v134, v52
	v_dot8c_i32_i4_e32 v43, v134, v50
	v_dot8c_i32_i4_e32 v44, v136, v52
	v_dot8c_i32_i4_e32 v45, v136, v50
	v_dot8c_i32_i4_e32 v38, v131, v53
	v_dot8c_i32_i4_e32 v39, v131, v51
	v_dot8c_i32_i4_e32 v40, v133, v53
	v_dot8c_i32_i4_e32 v41, v133, v51
	v_dot8c_i32_i4_e32 v42, v135, v53
	v_dot8c_i32_i4_e32 v43, v135, v51
	v_dot8c_i32_i4_e32 v44, v137, v53
	v_dot8c_i32_i4_e32 v45, v137, v51
	v_and_b32_e32 v78, 0xffff, v29
	v_lshrrev_b32_e32 v79, 16, v29
	v_lshl_add_u32 v78, v78, 7, v152
	v_lshl_add_u32 v79, v79, 7, v153
	s_mov_b32 m0, s79
	s_add_i32 s43, s79, 0x400
	global_load_lds_dwordx4 v78, s[50:51]
	s_mov_b32 m0, s43
	s_nop 0
	global_load_lds_dwordx4 v79, s[50:51]
	s_waitcnt vmcnt(8)
	v_add_u32_e32 v54, s99, v59
	v_add_u32_e32 v55, s99, v60
	v_add_u32_e32 v56, s99, v61
	v_add_u32_e32 v57, s99, v62
	ds_read_b64_tr_b4 v[50:51], v160 offset:896
	ds_read_b64_tr_b4 v[52:53], v160 offset:1920
	ds_read_b64_tr_b4 v[130:131], v54
	ds_read_b64_tr_b4 v[132:133], v55
	ds_read_b64_tr_b4 v[134:135], v56
	ds_read_b64_tr_b4 v[136:137], v57
	s_waitcnt lgkmcnt(6)
	v_dot8c_i32_i4_e32 v38, v122, v48
	v_dot8c_i32_i4_e32 v39, v122, v46
	v_dot8c_i32_i4_e32 v40, v124, v48
	v_dot8c_i32_i4_e32 v41, v124, v46
	v_dot8c_i32_i4_e32 v42, v126, v48
	v_dot8c_i32_i4_e32 v43, v126, v46
	v_dot8c_i32_i4_e32 v44, v128, v48
	v_dot8c_i32_i4_e32 v45, v128, v46
	v_dot8c_i32_i4_e32 v38, v123, v49
	v_dot8c_i32_i4_e32 v39, v123, v47
	v_dot8c_i32_i4_e32 v40, v125, v49
	v_dot8c_i32_i4_e32 v41, v125, v47
	v_dot8c_i32_i4_e32 v42, v127, v49
	v_dot8c_i32_i4_e32 v43, v127, v47
	v_dot8c_i32_i4_e32 v44, v129, v49
	v_dot8c_i32_i4_e32 v45, v129, v47
	v_and_b32_e32 v78, 0xffff, v30
	v_lshrrev_b32_e32 v79, 16, v30
	v_lshl_add_u32 v78, v78, 7, v152
	v_lshl_add_u32 v79, v79, 7, v153
	s_mov_b32 m0, s98
	s_add_i32 s43, s98, 0x400
	global_load_lds_dwordx4 v78, s[50:51]
	s_mov_b32 m0, s43
	s_nop 0
	global_load_lds_dwordx4 v79, s[50:51]
	s_waitcnt vmcnt(8)
; #define LAS __attribute__((address_space(3)))
; __device__ __forceinline__ bf16 f2bf(float f) { return (bf16)f2bfu(f); }
; #define TR4(p_) __builtin_amdgcn_ds_read_tr4_b64_v2i32((LAS v2i*)(p_))
; #define CFENCE() asm volatile("" ::: "memory")
; __device__ __forceinline__ void peer_v_tokens(int j, const LAS unsigned short* EL, const LAS unsigned char* AL  , const LAS float* ASC  , const LAS int* SAL  , ...
;     ...
;         for (int st = 0; st < 16; ++st) {
;             const int p = st >> 2, q = st & 3;
;             if (st < 14) VDMA(st + 2, (st + 2) % 3);
;             if (st < 14) asm volatile("s_waitcnt vmcnt(8)" ::: "memory");
;             else if (st == 14) asm volatile("s_waitcnt vmcnt(4)" ::: "memory");
;             else asm volatile("s_waitcnt vmcnt(0)" ::: "memory");
;             if (q == 0) {
; #pragma unroll
;                 for (int r = 0; r < 4; ++r) { accH[r] = 0; accL[r] = 0; } }
; #pragma unroll
;             for (int tp = 0; tp < 2; ++tp) {
;                 const v2i ao = TR4(ATL + (2 * q + tp) * 128 + 8 * s16), ah = TR4(ATL + 1024 + (2 * q + tp) * 128 + 8 * s16);
; #pragma unroll
;                 for (int r = 0; r < 4; ++r) {
;                     const v2i d = TR4(ldsb + BUF[st % 3] + 2048 * tp + roff[r]);
;                     accH[r] = __builtin_amdgcn_sdot8(d.x, ah.x, accH[r], false); accH[r] = __builtin_amdgcn_sdot8(d.y, ah.y, accH[r], false);
;                     accL[r] = __builtin_amdgcn_sdot8(d.x, ao.x, accL[r], false); accL[r] = __builtin_amdgcn_sdot8(d.y, ao.y, accL[r], false);
;                 }
;             }
;             asm volatile("s_waitcnt lgkmcnt(0)" ::: "memory");
;             if (q == 3) {
; #pragma unroll
;                 for (int r = 0; r < 4; ++r) STASH[256 * p + 16 * (grp + 4 * r) + pc] = f2bf(asc * (float)(2 * ((accH[r] << 4) + accL[r]) + sa));
;             }
;         }
;         CFENCE();
;         {
;             float4 v[4]; float ss = 0.f;
; #pragma unroll
;             for (int jq = 0; jq < 4; ++jq) { typedef unsigned u2v __attribute__((ext_vector_type(2))); const u2v pw = *(const LAS u2v*)(STASH + 4 * lane + 256 * jq); const uint2 hw = hv[jq];
	v_add_u32_e32 v54, s76, v59
	v_add_u32_e32 v55, s76, v60
	v_add_u32_e32 v56, s76, v61
	v_add_u32_e32 v57, s76, v62
	ds_read_b64_tr_b4 v[46:47], v160
	ds_read_b64_tr_b4 v[48:49], v160 offset:1024
	ds_read_b64_tr_b4 v[122:123], v54
	ds_read_b64_tr_b4 v[124:125], v55
	ds_read_b64_tr_b4 v[126:127], v56
	ds_read_b64_tr_b4 v[128:129], v57
	s_waitcnt lgkmcnt(6)
	v_dot8c_i32_i4_e32 v38, v130, v52
	v_dot8c_i32_i4_e32 v39, v130, v50
	v_dot8c_i32_i4_e32 v40, v132, v52
	v_dot8c_i32_i4_e32 v41, v132, v50
	v_dot8c_i32_i4_e32 v42, v134, v52
	v_dot8c_i32_i4_e32 v43, v134, v50
	v_dot8c_i32_i4_e32 v44, v136, v52
	v_dot8c_i32_i4_e32 v45, v136, v50
	v_dot8c_i32_i4_e32 v38, v131, v53
	v_dot8c_i32_i4_e32 v39, v131, v51
	v_dot8c_i32_i4_e32 v40, v133, v53
	v_dot8c_i32_i4_e32 v41, v133, v51
	v_dot8c_i32_i4_e32 v42, v135, v53
	v_dot8c_i32_i4_e32 v43, v135, v51
	v_dot8c_i32_i4_e32 v44, v137, v53
	v_dot8c_i32_i4_e32 v45, v137, v51
	s_nop 3
	s_waitcnt lgkmcnt(15)
	v_lshlrev_b32_e32 v38, 5, v38
	v_lshlrev_b32_e32 v39, 1, v39
	v_add3_u32 v38, v39, v229, v38
	v_cvt_f32_i32_e32 v38, v38
	v_mul_f32_e32 v38, v228, v38
	v_lshlrev_b32_e32 v40, 5, v40
	v_lshlrev_b32_e32 v41, 1, v41
	v_add3_u32 v40, v41, v229, v40
	v_cvt_f32_i32_e32 v40, v40
	v_mul_f32_e32 v40, v228, v40
	v_lshlrev_b32_e32 v42, 5, v42
	v_lshlrev_b32_e32 v43, 1, v43
	v_add3_u32 v42, v43, v229, v42
	v_cvt_f32_i32_e32 v42, v42
	v_mul_f32_e32 v42, v228, v42
	v_lshlrev_b32_e32 v44, 5, v44
	v_lshlrev_b32_e32 v45, 1, v45
	v_add3_u32 v44, v45, v229, v44
	v_cvt_f32_i32_e32 v44, v44
	v_mul_f32_e32 v44, v228, v44
	v_cvt_pk_bf16_f32 v180, v38, v40
	v_cvt_pk_bf16_f32 v181, v42, v44
	ds_read_b128 v[252:255], v155 offset:1024
	s_add_i32 s44, s40, 32
	s_ashr_i32 s45, s44, 31
	s_lshl_b64 s[44:45], s[44:45], 12
	v_lshl_add_u64 v[80:81], v[36:37], 0, s[44:45]
	s_waitcnt lgkmcnt(0)
	v_mul_f32_e32 v214, v214, v252
	v_mul_f32_e32 v215, v215, v253
	v_mul_f32_e32 v216, v216, v254
	v_mul_f32_e32 v217, v217, v255
	global_store_dwordx4 v[80:81], v[214:217], off offset:1024 nt
	v_add_u32_e32 v147, 8, v140
	v_and_b32_e32 v146, 15, v147
	v_xor_b32_e32 v146, 8, v146
	v_bfe_u32 v148, v147, 4, 4
	v_mul_lo_u32 v146, v146, s92
	v_mul_lo_u32 v148, v148, s92
	v_mov_b32_e32 v147, v146
	v_mov_b32_e32 v149, v148
	ds_write2st64_b64 v77, v[146:147], v[148:149] offset1:2
	v_add_u32_e32 v138, 0x1800, v74
	ds_read_u8 v139, v138
	v_add_u32_e32 v141, 0x1800, v73
	ds_read_u8 v140, v141
	s_add_i32 s43, s67, 224
	v_mov_b32_e32 v138, s43
	ds_read2st64_b32 v[228:229], v138 offset1:1
	ds_read_b128 v[18:21], v227 offset:12288
	ds_read_b128 v[22:25], v227 offset:12304
	v_add_u32_e32 v150, 0x400000, v63
	v_add_u32_e32 v151, 0x400000, v64
	v_mov_b32_e32 v38, 0
	v_mov_b32_e32 v39, 0
	v_mov_b32_e32 v40, 0
	v_mov_b32_e32 v41, 0
	v_mov_b32_e32 v42, 0
	v_mov_b32_e32 v43, 0
	v_mov_b32_e32 v44, 0
	v_mov_b32_e32 v45, 0
	v_and_b32_e32 v78, 0xffff, v31
	v_lshrrev_b32_e32 v79, 16, v31
	v_lshl_add_u32 v78, v78, 7, v152
	v_lshl_add_u32 v79, v79, 7, v153
	s_mov_b32 m0, s99
	s_add_i32 s43, s99, 0x400
	global_load_lds_dwordx4 v78, s[50:51]
	s_mov_b32 m0, s43
	s_nop 0
	global_load_lds_dwordx4 v79, s[50:51]
	s_waitcnt vmcnt(9)
	v_add_u32_e32 v54, s77, v59
	v_add_u32_e32 v55, s77, v60
	v_add_u32_e32 v56, s77, v61
	v_add_u32_e32 v57, s77, v62
	ds_read_b64_tr_b4 v[50:51], v160 offset:128
	ds_read_b64_tr_b4 v[52:53], v160 offset:1152
	ds_read_b64_tr_b4 v[130:131], v54
	ds_read_b64_tr_b4 v[132:133], v55
	ds_read_b64_tr_b4 v[134:135], v56
	ds_read_b64_tr_b4 v[136:137], v57
	s_waitcnt lgkmcnt(13)
	v_dot8c_i32_i4_e32 v38, v122, v48
	v_dot8c_i32_i4_e32 v39, v122, v46
	v_dot8c_i32_i4_e32 v40, v124, v48
	v_dot8c_i32_i4_e32 v41, v124, v46
	v_dot8c_i32_i4_e32 v42, v126, v48
	v_dot8c_i32_i4_e32 v43, v126, v46
	v_dot8c_i32_i4_e32 v44, v128, v48
	v_dot8c_i32_i4_e32 v45, v128, v46
	v_dot8c_i32_i4_e32 v38, v123, v49
	v_dot8c_i32_i4_e32 v39, v123, v47
	v_dot8c_i32_i4_e32 v40, v125, v49
	v_dot8c_i32_i4_e32 v41, v125, v47
	v_dot8c_i32_i4_e32 v42, v127, v49
	v_dot8c_i32_i4_e32 v43, v127, v47
	v_dot8c_i32_i4_e32 v44, v129, v49
	v_dot8c_i32_i4_e32 v45, v129, v47
	v_and_b32_e32 v78, 0xffff, v32
	v_lshrrev_b32_e32 v79, 16, v32
	v_lshl_add_u32 v78, v78, 7, v152
	v_lshl_add_u32 v79, v79, 7, v153
	s_mov_b32 m0, s76
	s_add_i32 s43, s76, 0x400
	global_load_lds_dwordx4 v78, s[50:51]
	s_mov_b32 m0, s43
	s_nop 0
	global_load_lds_dwordx4 v79, s[50:51]
	s_waitcnt vmcnt(9)
	v_add_u32_e32 v54, s78, v59
	v_add_u32_e32 v55, s78, v60
	v_add_u32_e32 v56, s78, v61
	v_add_u32_e32 v57, s78, v62
	ds_read_b64_tr_b4 v[46:47], v160 offset:256
	ds_read_b64_tr_b4 v[48:49], v160 offset:1280
	ds_read_b64_tr_b4 v[122:123], v54
	ds_read_b64_tr_b4 v[124:125], v55
	ds_read_b64_tr_b4 v[126:127], v56
	ds_read_b64_tr_b4 v[128:129], v57
	s_waitcnt lgkmcnt(6)
	v_dot8c_i32_i4_e32 v38, v130, v52
	v_dot8c_i32_i4_e32 v39, v130, v50
	v_dot8c_i32_i4_e32 v40, v132, v52
	v_dot8c_i32_i4_e32 v41, v132, v50
	v_dot8c_i32_i4_e32 v42, v134, v52
	v_dot8c_i32_i4_e32 v43, v134, v50
	v_dot8c_i32_i4_e32 v44, v136, v52
	v_dot8c_i32_i4_e32 v45, v136, v50
	v_dot8c_i32_i4_e32 v38, v131, v53
	v_dot8c_i32_i4_e32 v39, v131, v51
	v_dot8c_i32_i4_e32 v40, v133, v53
	v_dot8c_i32_i4_e32 v41, v133, v51
	v_dot8c_i32_i4_e32 v42, v135, v53
	v_dot8c_i32_i4_e32 v43, v135, v51
	v_dot8c_i32_i4_e32 v44, v137, v53
	v_dot8c_i32_i4_e32 v45, v137, v51
	ds_write_b16 v65, v170
	ds_write_b16_d16_hi v65, v170 offset:128
	ds_write_b16 v65, v171 offset:256
	ds_write_b16_d16_hi v65, v171 offset:384
	ds_write_b16 v65, v172 offset:512
	ds_write_b16_d16_hi v65, v172 offset:640
	ds_write_b16 v65, v173 offset:768
	ds_write_b16_d16_hi v65, v173 offset:896
	ds_write_b16 v65, v174 offset:1024
	ds_write_b16_d16_hi v65, v174 offset:1152
	ds_write_b16 v65, v175 offset:1280
	ds_write_b16_d16_hi v65, v175 offset:1408
	ds_write_b16 v65, v176 offset:1536
	ds_write_b16_d16_hi v65, v176 offset:1664
	ds_write_b16 v65, v177 offset:1792
	ds_write_b16_d16_hi v65, v177 offset:1920
	ds_read_b64 v[202:203], v154
	ds_read_b64 v[204:205], v154 offset:512
	ds_read_b64 v[206:207], v154 offset:1024
	ds_read_b64 v[208:209], v154 offset:1536
	v_and_b32_e32 v78, 0xffff, v33
	v_lshrrev_b32_e32 v79, 16, v33
	v_lshl_add_u32 v78, v78, 7, v152
	v_lshl_add_u32 v79, v79, 7, v153
	s_mov_b32 m0, s77
	s_add_i32 s43, s77, 0x400
	global_load_lds_dwordx4 v78, s[50:51]
	s_mov_b32 m0, s43
	s_nop 0
	global_load_lds_dwordx4 v79, s[50:51]
	s_waitcnt vmcnt(9)
; #define TR4(p_) __builtin_amdgcn_ds_read_tr4_b64_v2i32((LAS v2i*)(p_))
; #define VDMA(st_, k_) do { _Pragma("unroll") for (int i_ = 0; i_ < 4; ++i_) { \
;         const unsigned off_ = (unsigned)((st_) >> 2) * (16384u * 128u) + (PE_ID(E, 4 * ((st_) & 3) + i_) << 7) + ((i_ & 1) ? cx1 : cx0); \
;         __builtin_amdgcn_global_load_lds((const unsigned*)(V4 + off_), (LAS unsigned*)(ldsb + BUF[k_] + 1024 * i_), 16, 0, 0); } } while (0)
; __device__ __forceinline__ void peer_v_tokens(int j, const LAS unsigned short* EL, const LAS unsigned char* AL  , const LAS float* ASC  , const LAS int* SAL  , ...
;     ...
;         for (int st = 0; st < 16; ++st) {
;             const int p = st >> 2, q = st & 3;
;             if (st < 14) VDMA(st + 2, (st + 2) % 3);
;             if (st < 14) asm volatile("s_waitcnt vmcnt(8)" ::: "memory");
;             else if (st == 14) asm volatile("s_waitcnt vmcnt(4)" ::: "memory");
;             else asm volatile("s_waitcnt vmcnt(0)" ::: "memory");
;             if (q == 0) {
; #pragma unroll
;                 for (int r = 0; r < 4; ++r) { accH[r] = 0; accL[r] = 0; } }
; #pragma unroll
;             for (int tp = 0; tp < 2; ++tp) {
;                 const v2i ao = TR4(ATL + (2 * q + tp) * 128 + 8 * s16), ah = TR4(ATL + 1024 + (2 * q + tp) * 128 + 8 * s16);
; #pragma unroll
;                 for (int r = 0; r < 4; ++r) {
;                     const v2i d = TR4(ldsb + BUF[st % 3] + 2048 * tp + roff[r]);
;                     accH[r] = __builtin_amdgcn_sdot8(d.x, ah.x, accH[r], false); accH[r] = __builtin_amdgcn_sdot8(d.y, ah.y, accH[r], false);
;                     accL[r] = __builtin_amdgcn_sdot8(d.x, ao.x, accL[r], false); accL[r] = __builtin_amdgcn_sdot8(d.y, ao.y, accL[r], false);
;                 }
;             }
	v_add_u32_e32 v54, s79, v59
	v_add_u32_e32 v55, s79, v60
	v_add_u32_e32 v56, s79, v61
	v_add_u32_e32 v57, s79, v62
	ds_read_b64_tr_b4 v[50:51], v160 offset:384
	ds_read_b64_tr_b4 v[52:53], v160 offset:1408
	ds_read_b64_tr_b4 v[130:131], v54
	ds_read_b64_tr_b4 v[132:133], v55
	ds_read_b64_tr_b4 v[134:135], v56
	ds_read_b64_tr_b4 v[136:137], v57
	s_waitcnt lgkmcnt(15)
	v_dot8c_i32_i4_e32 v38, v122, v48
	v_dot8c_i32_i4_e32 v39, v122, v46
	v_dot8c_i32_i4_e32 v40, v124, v48
	v_dot8c_i32_i4_e32 v41, v124, v46
	v_dot8c_i32_i4_e32 v42, v126, v48
	v_dot8c_i32_i4_e32 v43, v126, v46
	v_dot8c_i32_i4_e32 v44, v128, v48
	v_dot8c_i32_i4_e32 v45, v128, v46
	v_dot8c_i32_i4_e32 v38, v123, v49
	v_dot8c_i32_i4_e32 v39, v123, v47
	v_dot8c_i32_i4_e32 v40, v125, v49
	v_dot8c_i32_i4_e32 v41, v125, v47
	v_dot8c_i32_i4_e32 v42, v127, v49
	v_dot8c_i32_i4_e32 v43, v127, v47
	v_dot8c_i32_i4_e32 v44, v129, v49
	v_dot8c_i32_i4_e32 v45, v129, v47
	s_waitcnt lgkmcnt(15)
	v_and_b32_e32 v78, 0xffff, v18
	v_lshrrev_b32_e32 v79, 16, v18
	v_lshl_add_u32 v78, v78, 7, v150
	v_lshl_add_u32 v79, v79, 7, v151
	s_mov_b32 m0, s78
	s_add_i32 s43, s78, 0x400
	global_load_lds_dwordx4 v78, s[50:51]
	s_mov_b32 m0, s43
	s_nop 0
	global_load_lds_dwordx4 v79, s[50:51]
	s_waitcnt vmcnt(9)
	v_add_u32_e32 v54, s98, v59
	v_add_u32_e32 v55, s98, v60
	v_add_u32_e32 v56, s98, v61
	v_add_u32_e32 v57, s98, v62
	ds_read_b64_tr_b4 v[46:47], v160 offset:512
	ds_read_b64_tr_b4 v[48:49], v160 offset:1536
	ds_read_b64_tr_b4 v[122:123], v54
	ds_read_b64_tr_b4 v[124:125], v55
	ds_read_b64_tr_b4 v[126:127], v56
	ds_read_b64_tr_b4 v[128:129], v57
	s_waitcnt lgkmcnt(6)
	v_dot8c_i32_i4_e32 v38, v130, v52
	v_dot8c_i32_i4_e32 v39, v130, v50
	v_dot8c_i32_i4_e32 v40, v132, v52
	v_dot8c_i32_i4_e32 v41, v132, v50
	v_dot8c_i32_i4_e32 v42, v134, v52
	v_dot8c_i32_i4_e32 v43, v134, v50
	v_dot8c_i32_i4_e32 v44, v136, v52
	v_dot8c_i32_i4_e32 v45, v136, v50
	v_dot8c_i32_i4_e32 v38, v131, v53
	v_dot8c_i32_i4_e32 v39, v131, v51
	v_dot8c_i32_i4_e32 v40, v133, v53
	v_dot8c_i32_i4_e32 v41, v133, v51
	v_dot8c_i32_i4_e32 v42, v135, v53
	v_dot8c_i32_i4_e32 v43, v135, v51
	v_dot8c_i32_i4_e32 v44, v137, v53
	v_dot8c_i32_i4_e32 v45, v137, v51
	v_and_b32_e32 v78, 0xffff, v19
	v_lshrrev_b32_e32 v79, 16, v19
	v_lshl_add_u32 v78, v78, 7, v150
	v_lshl_add_u32 v79, v79, 7, v151
	s_mov_b32 m0, s79
	s_add_i32 s43, s79, 0x400
	global_load_lds_dwordx4 v78, s[50:51]
	s_mov_b32 m0, s43
	s_nop 0
	global_load_lds_dwordx4 v79, s[50:51]
	s_waitcnt vmcnt(8)
	v_add_u32_e32 v54, s99, v59
	v_add_u32_e32 v55, s99, v60
	v_add_u32_e32 v56, s99, v61
	v_add_u32_e32 v57, s99, v62
	ds_read_b64_tr_b4 v[50:51], v160 offset:640
	ds_read_b64_tr_b4 v[52:53], v160 offset:1664
	ds_read_b64_tr_b4 v[130:131], v54
	ds_read_b64_tr_b4 v[132:133], v55
	ds_read_b64_tr_b4 v[134:135], v56
	ds_read_b64_tr_b4 v[136:137], v57
	s_waitcnt lgkmcnt(6)
	v_dot8c_i32_i4_e32 v38, v122, v48
	v_dot8c_i32_i4_e32 v39, v122, v46
	v_dot8c_i32_i4_e32 v40, v124, v48
	v_dot8c_i32_i4_e32 v41, v124, v46
	v_dot8c_i32_i4_e32 v42, v126, v48
	v_dot8c_i32_i4_e32 v43, v126, v46
	v_dot8c_i32_i4_e32 v44, v128, v48
	v_dot8c_i32_i4_e32 v45, v128, v46
	v_dot8c_i32_i4_e32 v38, v123, v49
	v_dot8c_i32_i4_e32 v39, v123, v47
	v_dot8c_i32_i4_e32 v40, v125, v49
	v_dot8c_i32_i4_e32 v41, v125, v47
	v_dot8c_i32_i4_e32 v42, v127, v49
	v_dot8c_i32_i4_e32 v43, v127, v47
	v_dot8c_i32_i4_e32 v44, v129, v49
	v_dot8c_i32_i4_e32 v45, v129, v47
	s_waitcnt lgkmcnt(15)
	v_add_u32_e32 v143, 8, v139
	v_and_b32_e32 v142, 15, v143
	v_xor_b32_e32 v142, 8, v142
	v_bfe_u32 v144, v143, 4, 4
	v_mul_lo_u32 v142, v142, s92
	v_mul_lo_u32 v144, v144, s92
	v_mov_b32_e32 v143, v142
	v_mov_b32_e32 v145, v144
	ds_write2st64_b64 v159, v[142:143], v[144:145] offset1:2
	v_and_b32_e32 v78, 0xffff, v20
	v_lshrrev_b32_e32 v79, 16, v20
	v_lshl_add_u32 v78, v78, 7, v150
	v_lshl_add_u32 v79, v79, 7, v151
	s_mov_b32 m0, s98
	s_add_i32 s43, s98, 0x400
	global_load_lds_dwordx4 v78, s[50:51]
	s_mov_b32 m0, s43
	s_nop 0
	global_load_lds_dwordx4 v79, s[50:51]
	s_waitcnt vmcnt(8)
	v_add_u32_e32 v54, s76, v59
	v_add_u32_e32 v55, s76, v60
	v_add_u32_e32 v56, s76, v61
	v_add_u32_e32 v57, s76, v62
	ds_read_b64_tr_b4 v[46:47], v160 offset:768
	ds_read_b64_tr_b4 v[48:49], v160 offset:1792
	ds_read_b64_tr_b4 v[122:123], v54
	ds_read_b64_tr_b4 v[124:125], v55
	ds_read_b64_tr_b4 v[126:127], v56
	ds_read_b64_tr_b4 v[128:129], v57
	s_waitcnt lgkmcnt(7)
	v_dot8c_i32_i4_e32 v38, v130, v52
	v_dot8c_i32_i4_e32 v39, v130, v50
	v_dot8c_i32_i4_e32 v40, v132, v52
	v_dot8c_i32_i4_e32 v41, v132, v50
	v_dot8c_i32_i4_e32 v42, v134, v52
	v_dot8c_i32_i4_e32 v43, v134, v50
	v_dot8c_i32_i4_e32 v44, v136, v52
	v_dot8c_i32_i4_e32 v45, v136, v50
	v_dot8c_i32_i4_e32 v38, v131, v53
	v_dot8c_i32_i4_e32 v39, v131, v51
	v_dot8c_i32_i4_e32 v40, v133, v53
	v_dot8c_i32_i4_e32 v41, v133, v51
	v_dot8c_i32_i4_e32 v42, v135, v53
	v_dot8c_i32_i4_e32 v43, v135, v51
	v_dot8c_i32_i4_e32 v44, v137, v53
	v_dot8c_i32_i4_e32 v45, v137, v51
	v_and_b32_e32 v78, 0xffff, v21
	v_lshrrev_b32_e32 v79, 16, v21
	v_lshl_add_u32 v78, v78, 7, v150
	v_lshl_add_u32 v79, v79, 7, v151
	s_mov_b32 m0, s99
	s_add_i32 s43, s99, 0x400
	global_load_lds_dwordx4 v78, s[50:51]
	s_mov_b32 m0, s43
	s_nop 0
	global_load_lds_dwordx4 v79, s[50:51]
	s_waitcnt vmcnt(8)
	v_add_u32_e32 v54, s77, v59
	v_add_u32_e32 v55, s77, v60
	v_add_u32_e32 v56, s77, v61
	v_add_u32_e32 v57, s77, v62
	ds_read_b64_tr_b4 v[50:51], v160 offset:896
	ds_read_b64_tr_b4 v[52:53], v160 offset:1920
	ds_read_b64_tr_b4 v[130:131], v54
	ds_read_b64_tr_b4 v[132:133], v55
	ds_read_b64_tr_b4 v[134:135], v56
	ds_read_b64_tr_b4 v[136:137], v57
	s_waitcnt lgkmcnt(6)
; __device__ __forceinline__ void peer_v_tokens(int j, const LAS unsigned short* EL, const LAS unsigned char* AL  , const LAS float* ASC  , const LAS int* SAL  , ...
;     ...
;         { const LAS v4u* ep = (const LAS v4u*)(EL + tl * 128 + 16 * g); const v4u e0 = ep[0], e1 = ep[1];
;           E[0] = e0.x; E[1] = e0.y; E[2] = e0.z; E[3] = e0.w; E[4] = e1.x; E[5] = e1.y; E[6] = e1.z; E[7] = e1.w; }
;         uint2 hv[4]; float4 gv[4];
;         { unsigned ho = (unsigned)t * (D / 4) + (unsigned)lane; asm volatile("" : "+v"(ho)); const uint2* hp = (const uint2*)HB + ho; const float4* gp = (const float4*)fng + lane;
; #pragma unroll
;           for (int jq = 0; jq < 4; ++jq) { hv[jq] = hp[64 * jq]; gv[jq] = gp[64 * jq]; } }
;         VDMA(0, 0); VDMA(1, 1);
; #pragma unroll
;         for (int m = 0; m < 2; ++m) {
;             const int idx = lane + 64 * m, tau = idx >> 4, sr = idx & 15, k = 16 * (sr & 7) + 2 * tau + (sr >> 3);
;     ...
;         for (int st = 0; st < 16; ++st) {
;             const int p = st >> 2, q = st & 3;
;             if (st < 14) VDMA(st + 2, (st + 2) % 3);
;             if (st < 14) asm volatile("s_waitcnt vmcnt(8)" ::: "memory");
;             else if (st == 14) asm volatile("s_waitcnt vmcnt(4)" ::: "memory");
;             else asm volatile("s_waitcnt vmcnt(0)" ::: "memory");
;             if (q == 0) {
; #pragma unroll
;                 for (int r = 0; r < 4; ++r) { accH[r] = 0; accL[r] = 0; } }
; #pragma unroll
;             for (int tp = 0; tp < 2; ++tp) {
;                 const v2i ao = TR4(ATL + (2 * q + tp) * 128 + 8 * s16), ah = TR4(ATL + 1024 + (2 * q + tp) * 128 + 8 * s16);
; #pragma unroll
;                 for (int r = 0; r < 4; ++r) {
;                     const v2i d = TR4(ldsb + BUF[st % 3] + 2048 * tp + roff[r]);
;                     accH[r] = __builtin_amdgcn_sdot8(d.x, ah.x, accH[r], false); accH[r] = __builtin_amdgcn_sdot8(d.y, ah.y, accH[r], false);
;                     accL[r] = __builtin_amdgcn_sdot8(d.x, ao.x, accL[r], false); accL[r] = __builtin_amdgcn_sdot8(d.y, ao.y, accL[r], false);
;                 }
;             }
;             asm volatile("s_waitcnt lgkmcnt(0)" ::: "memory");
;             if (q == 3) {
; #pragma unroll
;                 for (int r = 0; r < 4; ++r) STASH[256 * p + 16 * (grp + 4 * r) + pc] = f2bf(asc * (float)(2 * ((accH[r] << 4) + accL[r]) + sa));
;             }
	v_dot8c_i32_i4_e32 v38, v122, v48
	v_dot8c_i32_i4_e32 v39, v122, v46
	v_dot8c_i32_i4_e32 v40, v124, v48
	v_dot8c_i32_i4_e32 v41, v124, v46
	v_dot8c_i32_i4_e32 v42, v126, v48
	v_dot8c_i32_i4_e32 v43, v126, v46
	v_dot8c_i32_i4_e32 v44, v128, v48
	v_dot8c_i32_i4_e32 v45, v128, v46
	v_dot8c_i32_i4_e32 v38, v123, v49
	v_dot8c_i32_i4_e32 v39, v123, v47
	v_dot8c_i32_i4_e32 v40, v125, v49
	v_dot8c_i32_i4_e32 v41, v125, v47
	v_dot8c_i32_i4_e32 v42, v127, v49
	v_dot8c_i32_i4_e32 v43, v127, v47
	v_dot8c_i32_i4_e32 v44, v129, v49
	v_dot8c_i32_i4_e32 v45, v129, v47
	v_and_b32_e32 v78, 0xffff, v22
	v_lshrrev_b32_e32 v79, 16, v22
	v_lshl_add_u32 v78, v78, 7, v150
	v_lshl_add_u32 v79, v79, 7, v151
	s_mov_b32 m0, s76
	s_add_i32 s43, s76, 0x400
	global_load_lds_dwordx4 v78, s[50:51]
	s_mov_b32 m0, s43
	s_nop 0
	global_load_lds_dwordx4 v79, s[50:51]
	s_waitcnt vmcnt(8)
	v_add_u32_e32 v54, s78, v59
	v_add_u32_e32 v55, s78, v60
	v_add_u32_e32 v56, s78, v61
	v_add_u32_e32 v57, s78, v62
	ds_read_b64_tr_b4 v[46:47], v160
	ds_read_b64_tr_b4 v[48:49], v160 offset:1024
	ds_read_b64_tr_b4 v[122:123], v54
	ds_read_b64_tr_b4 v[124:125], v55
	ds_read_b64_tr_b4 v[126:127], v56
	ds_read_b64_tr_b4 v[128:129], v57
	s_waitcnt lgkmcnt(6)
	v_dot8c_i32_i4_e32 v38, v130, v52
	v_dot8c_i32_i4_e32 v39, v130, v50
	v_dot8c_i32_i4_e32 v40, v132, v52
	v_dot8c_i32_i4_e32 v41, v132, v50
	v_dot8c_i32_i4_e32 v42, v134, v52
	v_dot8c_i32_i4_e32 v43, v134, v50
	v_dot8c_i32_i4_e32 v44, v136, v52
	v_dot8c_i32_i4_e32 v45, v136, v50
	v_dot8c_i32_i4_e32 v38, v131, v53
	v_dot8c_i32_i4_e32 v39, v131, v51
	v_dot8c_i32_i4_e32 v40, v133, v53
	v_dot8c_i32_i4_e32 v41, v133, v51
	v_dot8c_i32_i4_e32 v42, v135, v53
	v_dot8c_i32_i4_e32 v43, v135, v51
	v_dot8c_i32_i4_e32 v44, v137, v53
	v_dot8c_i32_i4_e32 v45, v137, v51
	s_nop 3
	s_waitcnt lgkmcnt(15)
	v_lshlrev_b32_e32 v38, 5, v38
	v_lshlrev_b32_e32 v39, 1, v39
	v_add3_u32 v38, v39, v229, v38
	v_cvt_f32_i32_e32 v38, v38
	v_mul_f32_e32 v38, v228, v38
	v_lshlrev_b32_e32 v40, 5, v40
	v_lshlrev_b32_e32 v41, 1, v41
	v_add3_u32 v40, v41, v229, v40
	v_cvt_f32_i32_e32 v40, v40
	v_mul_f32_e32 v40, v228, v40
	v_lshlrev_b32_e32 v42, 5, v42
	v_lshlrev_b32_e32 v43, 1, v43
	v_add3_u32 v42, v43, v229, v42
	v_cvt_f32_i32_e32 v42, v42
	v_mul_f32_e32 v42, v228, v42
	v_lshlrev_b32_e32 v44, 5, v44
	v_lshlrev_b32_e32 v45, 1, v45
	v_add3_u32 v44, v45, v229, v44
	v_cvt_f32_i32_e32 v44, v44
	v_mul_f32_e32 v44, v228, v44
	v_cvt_pk_bf16_f32 v188, v38, v40
	v_cvt_pk_bf16_f32 v189, v42, v44
	ds_read_b128 v[252:255], v156
	s_add_i32 s44, s40, 32
	s_ashr_i32 s45, s44, 31
	s_lshl_b64 s[44:45], s[44:45], 12
	v_lshl_add_u64 v[80:81], v[36:37], 0, s[44:45]
	s_waitcnt lgkmcnt(0)
	v_mul_f32_e32 v218, v218, v252
	v_mul_f32_e32 v219, v219, v253
	v_mul_f32_e32 v220, v220, v254
	v_mul_f32_e32 v221, v221, v255
	global_store_dwordx4 v[80:81], v[218:221], off offset:2048 nt
	v_add_u32_e32 v147, 8, v140
	v_and_b32_e32 v146, 15, v147
	v_xor_b32_e32 v146, 8, v146
	v_bfe_u32 v148, v147, 4, 4
	v_mul_lo_u32 v146, v146, s92
	v_mul_lo_u32 v148, v148, s92
	v_mov_b32_e32 v147, v146
	v_mov_b32_e32 v149, v148
	ds_write2st64_b64 v77, v[146:147], v[148:149] offset1:2
	v_add_u32_e32 v138, 0x1c00, v74
	ds_read_u8 v139, v138
	v_add_u32_e32 v141, 0x1c00, v73
	ds_read_u8 v140, v141
	s_add_i32 s43, s67, 192
	v_mov_b32_e32 v138, s43
	ds_read2st64_b32 v[228:229], v138 offset1:1
	ds_read_b128 v[26:29], v227 offset:14336
	ds_read_b128 v[30:33], v227 offset:14352
	v_mov_b32_e32 v38, 0
	v_mov_b32_e32 v39, 0
	v_mov_b32_e32 v40, 0
	v_mov_b32_e32 v41, 0
	v_mov_b32_e32 v42, 0
	v_mov_b32_e32 v43, 0
	v_mov_b32_e32 v44, 0
	v_mov_b32_e32 v45, 0
	v_and_b32_e32 v78, 0xffff, v23
	v_lshrrev_b32_e32 v79, 16, v23
	v_lshl_add_u32 v78, v78, 7, v150
	v_lshl_add_u32 v79, v79, 7, v151
	s_mov_b32 m0, s77
	s_add_i32 s43, s77, 0x400
	global_load_lds_dwordx4 v78, s[50:51]
	s_mov_b32 m0, s43
	s_nop 0
	global_load_lds_dwordx4 v79, s[50:51]
	s_waitcnt vmcnt(9)
	v_add_u32_e32 v54, s79, v59
	v_add_u32_e32 v55, s79, v60
	v_add_u32_e32 v56, s79, v61
	v_add_u32_e32 v57, s79, v62
	ds_read_b64_tr_b4 v[50:51], v160 offset:128
	ds_read_b64_tr_b4 v[52:53], v160 offset:1152
	ds_read_b64_tr_b4 v[130:131], v54
	ds_read_b64_tr_b4 v[132:133], v55
	ds_read_b64_tr_b4 v[134:135], v56
	ds_read_b64_tr_b4 v[136:137], v57
	s_waitcnt lgkmcnt(13)
	s_waitcnt vmcnt(36) lgkmcnt(15)
; #define LAS __attribute__((address_space(3)))
; #define WS_DPP_(x, ctrl) __builtin_bit_cast(float, __builtin_amdgcn_update_dpp(0, __builtin_bit_cast(int, x), ctrl, 0xf, 0xf, false))
; __device__ __forceinline__ float wave_sum(float v) {
;     ...
;     v += WS_DPP_(v, 0xB1); v += WS_DPP_(v, 0x4E); v += WS_DPP_(v, 0x141); v += WS_DPP_(v, 0x140);
;     ...
;     const int vi = __builtin_bit_cast(int, v);
;     return (__builtin_bit_cast(float, __builtin_amdgcn_readlane(vi, 0)) + __builtin_bit_cast(float, __builtin_amdgcn_readlane(vi, 16))) +
;            (__builtin_bit_cast(float, __builtin_amdgcn_readlane(vi, 32)) + __builtin_bit_cast(float, __builtin_amdgcn_readlane(vi, 48)));
; }
; __device__ __forceinline__ void peer_v_tokens(int j, const LAS unsigned short* EL, const LAS unsigned char* AL  , const LAS float* ASC  , const LAS int* SAL  , ...
;     ...
;         {
;             float4 v[4]; float ss = 0.f;
; #pragma unroll
;             for (int jq = 0; jq < 4; ++jq) { typedef unsigned u2v __attribute__((ext_vector_type(2))); const u2v pw = *(const LAS u2v*)(STASH + 4 * lane + 256 * jq); const uint2 hw = hv[jq];
;                 v[jq] = make_float4(__uint_as_float(hw.x << 16) + __uint_as_float(pw.x << 16), __uint_as_float(hw.x & 0xffff0000u) + __uint_as_float(pw.x & 0xffff0000u),
;                                     __uint_as_float(hw.y << 16) + __uint_as_float(pw.y << 16), __uint_as_float(hw.y & 0xffff0000u) + __uint_as_float(pw.y & 0xffff0000u));
;                 ss += v[jq].x * v[jq].x + v[jq].y * v[jq].y + v[jq].z * v[jq].z + v[jq].w * v[jq].w; }
;             ss = wave_sum(ss);
;             const float r3 = rsqrtf(ss * (1.f / D) + EPS);
;             float4* op = (float4*)(outp + (size_t)t * D) + lane;
; #pragma unroll
;             for (int jq = 0; jq < 4; ++jq) { typedef float f4v __attribute__((ext_vector_type(4))); f4v o4; o4.x = v[jq].x * r3 * gv[jq].x; o4.y = v[jq].y * r3 * gv[jq].y; o4.z = v[jq].z * r3 * gv[jq].z; o4.w = v[jq].w * r3 * gv[jq].w;
	v_lshlrev_b32_e32 v236, 16, v194
	v_and_b32_e32 v237, 0xffff0000, v194
	v_lshlrev_b32_e32 v142, 16, v202
	v_and_b32_e32 v143, 0xffff0000, v202
	v_add_f32_e32 v236, v236, v142
	v_add_f32_e32 v237, v237, v143
	v_lshlrev_b32_e32 v238, 16, v195
	v_and_b32_e32 v239, 0xffff0000, v195
	v_lshlrev_b32_e32 v142, 16, v203
	v_and_b32_e32 v143, 0xffff0000, v203
	v_add_f32_e32 v238, v238, v142
	v_add_f32_e32 v239, v239, v143
	v_lshlrev_b32_e32 v240, 16, v196
	v_and_b32_e32 v241, 0xffff0000, v196
	v_lshlrev_b32_e32 v142, 16, v204
	v_and_b32_e32 v143, 0xffff0000, v204
	v_add_f32_e32 v240, v240, v142
	v_add_f32_e32 v241, v241, v143
	v_lshlrev_b32_e32 v242, 16, v197
	v_and_b32_e32 v243, 0xffff0000, v197
	v_lshlrev_b32_e32 v142, 16, v205
	v_and_b32_e32 v143, 0xffff0000, v205
	v_add_f32_e32 v242, v242, v142
	v_add_f32_e32 v243, v243, v143
	v_lshlrev_b32_e32 v244, 16, v198
	v_and_b32_e32 v245, 0xffff0000, v198
	v_lshlrev_b32_e32 v142, 16, v206
	v_and_b32_e32 v143, 0xffff0000, v206
	v_add_f32_e32 v244, v244, v142
	v_add_f32_e32 v245, v245, v143
	v_lshlrev_b32_e32 v246, 16, v199
	v_and_b32_e32 v247, 0xffff0000, v199
	v_lshlrev_b32_e32 v142, 16, v207
	v_and_b32_e32 v143, 0xffff0000, v207
	v_add_f32_e32 v246, v246, v142
	v_add_f32_e32 v247, v247, v143
	v_lshlrev_b32_e32 v248, 16, v200
	v_and_b32_e32 v249, 0xffff0000, v200
	v_lshlrev_b32_e32 v142, 16, v208
	v_and_b32_e32 v143, 0xffff0000, v208
	v_add_f32_e32 v248, v248, v142
	v_add_f32_e32 v249, v249, v143
	v_lshlrev_b32_e32 v250, 16, v201
	v_and_b32_e32 v251, 0xffff0000, v201
	v_lshlrev_b32_e32 v142, 16, v209
	v_and_b32_e32 v143, 0xffff0000, v209
	v_add_f32_e32 v250, v250, v142
	v_add_f32_e32 v251, v251, v143
	v_mov_b32_e32 v144, 0
	v_mul_f32_e32 v145, v236, v236
	v_fmac_f32_e32 v145, v237, v237
	v_fmac_f32_e32 v145, v238, v238
	v_fmac_f32_e32 v145, v239, v239
	v_add_f32_e32 v144, v144, v145
	v_mul_f32_e32 v145, v240, v240
	v_fmac_f32_e32 v145, v241, v241
	v_fmac_f32_e32 v145, v242, v242
	v_fmac_f32_e32 v145, v243, v243
	v_add_f32_e32 v144, v144, v145
	v_mul_f32_e32 v145, v244, v244
	v_fmac_f32_e32 v145, v245, v245
	v_fmac_f32_e32 v145, v246, v246
	v_fmac_f32_e32 v145, v247, v247
	v_add_f32_e32 v144, v144, v145
	v_mul_f32_e32 v145, v248, v248
	v_fmac_f32_e32 v145, v249, v249
	v_fmac_f32_e32 v145, v250, v250
	v_fmac_f32_e32 v145, v251, v251
	v_add_f32_e32 v144, v144, v145
	s_nop 1
	v_add_f32_dpp v144, v144, v144 quad_perm:[1,0,3,2] row_mask:0xf bank_mask:0xf bound_ctrl:1
	s_nop 1
	v_add_f32_dpp v144, v144, v144 quad_perm:[2,3,0,1] row_mask:0xf bank_mask:0xf bound_ctrl:1
	s_nop 1
	v_add_f32_dpp v144, v144, v144 row_half_mirror row_mask:0xf bank_mask:0xf bound_ctrl:1
	s_nop 1
	v_add_f32_dpp v144, v144, v144 row_mirror row_mask:0xf bank_mask:0xf bound_ctrl:1
	s_nop 1
	v_readlane_b32 s10, v144, 0
	v_readlane_b32 s11, v144, 16
	v_readlane_b32 s14, v144, 32
	v_readlane_b32 s15, v144, 48
	s_nop 3
	v_mov_b32_e32 v144, s11
	v_mov_b32_e32 v145, s15
	v_add_f32_e32 v144, s10, v144
	v_add_f32_e32 v145, s14, v145
	v_add_f32_e32 v144, v144, v145
	v_fmamk_f32 v144, v144, 0x3a800000, v111
	v_rsq_f32_e32 v144, v144
	s_nop 0
	v_mul_f32_e32 v236, v236, v144
	v_mul_f32_e32 v237, v237, v144
	v_mul_f32_e32 v238, v238, v144
	v_mul_f32_e32 v239, v239, v144
	v_mul_f32_e32 v240, v240, v144
	v_mul_f32_e32 v241, v241, v144
	v_mul_f32_e32 v242, v242, v144
	v_mul_f32_e32 v243, v243, v144
	v_mul_f32_e32 v244, v244, v144
	v_mul_f32_e32 v245, v245, v144
	v_mul_f32_e32 v246, v246, v144
	v_mul_f32_e32 v247, v247, v144
	v_mul_f32_e32 v248, v248, v144
	v_mul_f32_e32 v249, v249, v144
	v_mul_f32_e32 v250, v250, v144
	v_mul_f32_e32 v251, v251, v144
	v_dot8c_i32_i4_e32 v38, v122, v48
	v_dot8c_i32_i4_e32 v39, v122, v46
	v_dot8c_i32_i4_e32 v40, v124, v48
	v_dot8c_i32_i4_e32 v41, v124, v46
	v_dot8c_i32_i4_e32 v42, v126, v48
	v_dot8c_i32_i4_e32 v43, v126, v46
	v_dot8c_i32_i4_e32 v44, v128, v48
	v_dot8c_i32_i4_e32 v45, v128, v46
	v_dot8c_i32_i4_e32 v38, v123, v49
	v_dot8c_i32_i4_e32 v39, v123, v47
	v_dot8c_i32_i4_e32 v40, v125, v49
	v_dot8c_i32_i4_e32 v41, v125, v47
	v_dot8c_i32_i4_e32 v42, v127, v49
	v_dot8c_i32_i4_e32 v43, v127, v47
	v_dot8c_i32_i4_e32 v44, v129, v49
	v_dot8c_i32_i4_e32 v45, v129, v47
	v_and_b32_e32 v78, 0xffff, v24
	v_lshrrev_b32_e32 v79, 16, v24
	v_lshl_add_u32 v78, v78, 7, v150
	v_lshl_add_u32 v79, v79, 7, v151
	s_mov_b32 m0, s78
	s_add_i32 s43, s78, 0x400
	global_load_lds_dwordx4 v78, s[50:51]
	s_mov_b32 m0, s43
	s_nop 0
	global_load_lds_dwordx4 v79, s[50:51]
	s_waitcnt vmcnt(9)
	v_add_u32_e32 v54, s98, v59
	v_add_u32_e32 v55, s98, v60
	v_add_u32_e32 v56, s98, v61
	v_add_u32_e32 v57, s98, v62
	ds_read_b64_tr_b4 v[46:47], v160 offset:256
	ds_read_b64_tr_b4 v[48:49], v160 offset:1280
	ds_read_b64_tr_b4 v[122:123], v54
	ds_read_b64_tr_b4 v[124:125], v55
	ds_read_b64_tr_b4 v[126:127], v56
	ds_read_b64_tr_b4 v[128:129], v57
	s_waitcnt lgkmcnt(6)
	v_dot8c_i32_i4_e32 v38, v130, v52
	v_dot8c_i32_i4_e32 v39, v130, v50
	v_dot8c_i32_i4_e32 v40, v132, v52
	v_dot8c_i32_i4_e32 v41, v132, v50
	v_dot8c_i32_i4_e32 v42, v134, v52
	v_dot8c_i32_i4_e32 v43, v134, v50
	v_dot8c_i32_i4_e32 v44, v136, v52
	v_dot8c_i32_i4_e32 v45, v136, v50
	v_dot8c_i32_i4_e32 v38, v131, v53
	v_dot8c_i32_i4_e32 v39, v131, v51
	v_dot8c_i32_i4_e32 v40, v133, v53
	v_dot8c_i32_i4_e32 v41, v133, v51
	v_dot8c_i32_i4_e32 v42, v135, v53
	v_dot8c_i32_i4_e32 v43, v135, v51
	v_dot8c_i32_i4_e32 v44, v137, v53
	v_dot8c_i32_i4_e32 v45, v137, v51
	v_and_b32_e32 v78, 0xffff, v25
	v_lshrrev_b32_e32 v79, 16, v25
	v_lshl_add_u32 v78, v78, 7, v150
	v_lshl_add_u32 v79, v79, 7, v151
	s_mov_b32 m0, s79
	s_add_i32 s43, s79, 0x400
	global_load_lds_dwordx4 v78, s[50:51]
	s_mov_b32 m0, s43
	s_nop 0
	global_load_lds_dwordx4 v79, s[50:51]
	s_waitcnt vmcnt(9)
; #define TR4(p_) __builtin_amdgcn_ds_read_tr4_b64_v2i32((LAS v2i*)(p_))
; #define VDMA(st_, k_) do { _Pragma("unroll") for (int i_ = 0; i_ < 4; ++i_) { \
;         const unsigned off_ = (unsigned)((st_) >> 2) * (16384u * 128u) + (PE_ID(E, 4 * ((st_) & 3) + i_) << 7) + ((i_ & 1) ? cx1 : cx0); \
;         __builtin_amdgcn_global_load_lds((const unsigned*)(V4 + off_), (LAS unsigned*)(ldsb + BUF[k_] + 1024 * i_), 16, 0, 0); } } while (0)
; __device__ __forceinline__ void peer_v_tokens(int j, const LAS unsigned short* EL, const LAS unsigned char* AL  , const LAS float* ASC  , const LAS int* SAL  , ...
;     ...
;         for (int st = 0; st < 16; ++st) {
;             const int p = st >> 2, q = st & 3;
;             if (st < 14) VDMA(st + 2, (st + 2) % 3);
;             if (st < 14) asm volatile("s_waitcnt vmcnt(8)" ::: "memory");
;             else if (st == 14) asm volatile("s_waitcnt vmcnt(4)" ::: "memory");
;             else asm volatile("s_waitcnt vmcnt(0)" ::: "memory");
;             if (q == 0) {
; #pragma unroll
;                 for (int r = 0; r < 4; ++r) { accH[r] = 0; accL[r] = 0; } }
; #pragma unroll
;             for (int tp = 0; tp < 2; ++tp) {
;                 const v2i ao = TR4(ATL + (2 * q + tp) * 128 + 8 * s16), ah = TR4(ATL + 1024 + (2 * q + tp) * 128 + 8 * s16);
; #pragma unroll
;                 for (int r = 0; r < 4; ++r) {
;                     const v2i d = TR4(ldsb + BUF[st % 3] + 2048 * tp + roff[r]);
;                     accH[r] = __builtin_amdgcn_sdot8(d.x, ah.x, accH[r], false); accH[r] = __builtin_amdgcn_sdot8(d.y, ah.y, accH[r], false);
;                     accL[r] = __builtin_amdgcn_sdot8(d.x, ao.x, accL[r], false); accL[r] = __builtin_amdgcn_sdot8(d.y, ao.y, accL[r], false);
;                 }
;             }
	v_add_u32_e32 v54, s99, v59
	v_add_u32_e32 v55, s99, v60
	v_add_u32_e32 v56, s99, v61
	v_add_u32_e32 v57, s99, v62
	ds_read_b64_tr_b4 v[50:51], v160 offset:384
	ds_read_b64_tr_b4 v[52:53], v160 offset:1408
	ds_read_b64_tr_b4 v[130:131], v54
	ds_read_b64_tr_b4 v[132:133], v55
	ds_read_b64_tr_b4 v[134:135], v56
	ds_read_b64_tr_b4 v[136:137], v57
	s_waitcnt lgkmcnt(6)
	v_dot8c_i32_i4_e32 v38, v122, v48
	v_dot8c_i32_i4_e32 v39, v122, v46
	v_dot8c_i32_i4_e32 v40, v124, v48
	v_dot8c_i32_i4_e32 v41, v124, v46
	v_dot8c_i32_i4_e32 v42, v126, v48
	v_dot8c_i32_i4_e32 v43, v126, v46
	v_dot8c_i32_i4_e32 v44, v128, v48
	v_dot8c_i32_i4_e32 v45, v128, v46
	v_dot8c_i32_i4_e32 v38, v123, v49
	v_dot8c_i32_i4_e32 v39, v123, v47
	v_dot8c_i32_i4_e32 v40, v125, v49
	v_dot8c_i32_i4_e32 v41, v125, v47
	v_dot8c_i32_i4_e32 v42, v127, v49
	v_dot8c_i32_i4_e32 v43, v127, v47
	v_dot8c_i32_i4_e32 v44, v129, v49
	v_dot8c_i32_i4_e32 v45, v129, v47
	s_waitcnt lgkmcnt(15)
	v_and_b32_e32 v78, 0xffff, v26
	v_lshrrev_b32_e32 v79, 16, v26
	v_lshl_add_u32 v78, v78, 7, v150
	v_lshl_add_u32 v79, v79, 7, v151
	s_mov_b32 m0, s98
	s_add_i32 s43, s98, 0x400
	global_load_lds_dwordx4 v78, s[50:51]
	s_mov_b32 m0, s43
	s_nop 0
	global_load_lds_dwordx4 v79, s[50:51]
	s_waitcnt vmcnt(9)
	v_add_u32_e32 v54, s76, v59
	v_add_u32_e32 v55, s76, v60
	v_add_u32_e32 v56, s76, v61
	v_add_u32_e32 v57, s76, v62
	ds_read_b64_tr_b4 v[46:47], v160 offset:512
	ds_read_b64_tr_b4 v[48:49], v160 offset:1536
	ds_read_b64_tr_b4 v[122:123], v54
	ds_read_b64_tr_b4 v[124:125], v55
	ds_read_b64_tr_b4 v[126:127], v56
	ds_read_b64_tr_b4 v[128:129], v57
	s_waitcnt lgkmcnt(6)
	v_dot8c_i32_i4_e32 v38, v130, v52
	v_dot8c_i32_i4_e32 v39, v130, v50
	v_dot8c_i32_i4_e32 v40, v132, v52
	v_dot8c_i32_i4_e32 v41, v132, v50
	v_dot8c_i32_i4_e32 v42, v134, v52
	v_dot8c_i32_i4_e32 v43, v134, v50
	v_dot8c_i32_i4_e32 v44, v136, v52
	v_dot8c_i32_i4_e32 v45, v136, v50
	v_dot8c_i32_i4_e32 v38, v131, v53
	v_dot8c_i32_i4_e32 v39, v131, v51
	v_dot8c_i32_i4_e32 v40, v133, v53
	v_dot8c_i32_i4_e32 v41, v133, v51
	v_dot8c_i32_i4_e32 v42, v135, v53
	v_dot8c_i32_i4_e32 v43, v135, v51
	v_dot8c_i32_i4_e32 v44, v137, v53
	v_dot8c_i32_i4_e32 v45, v137, v51
	v_and_b32_e32 v78, 0xffff, v27
	v_lshrrev_b32_e32 v79, 16, v27
	v_lshl_add_u32 v78, v78, 7, v150
	v_lshl_add_u32 v79, v79, 7, v151
	s_mov_b32 m0, s99
	s_add_i32 s43, s99, 0x400
	global_load_lds_dwordx4 v78, s[50:51]
	s_mov_b32 m0, s43
	s_nop 0
	global_load_lds_dwordx4 v79, s[50:51]
	s_waitcnt vmcnt(8)
	v_add_u32_e32 v54, s77, v59
	v_add_u32_e32 v55, s77, v60
	v_add_u32_e32 v56, s77, v61
	v_add_u32_e32 v57, s77, v62
	ds_read_b64_tr_b4 v[50:51], v160 offset:640
	ds_read_b64_tr_b4 v[52:53], v160 offset:1664
	ds_read_b64_tr_b4 v[130:131], v54
	ds_read_b64_tr_b4 v[132:133], v55
	ds_read_b64_tr_b4 v[134:135], v56
	ds_read_b64_tr_b4 v[136:137], v57
	s_waitcnt lgkmcnt(6)
	v_dot8c_i32_i4_e32 v38, v122, v48
	v_dot8c_i32_i4_e32 v39, v122, v46
	v_dot8c_i32_i4_e32 v40, v124, v48
	v_dot8c_i32_i4_e32 v41, v124, v46
	v_dot8c_i32_i4_e32 v42, v126, v48
	v_dot8c_i32_i4_e32 v43, v126, v46
	v_dot8c_i32_i4_e32 v44, v128, v48
	v_dot8c_i32_i4_e32 v45, v128, v46
	v_dot8c_i32_i4_e32 v38, v123, v49
	v_dot8c_i32_i4_e32 v39, v123, v47
	v_dot8c_i32_i4_e32 v40, v125, v49
	v_dot8c_i32_i4_e32 v41, v125, v47
	v_dot8c_i32_i4_e32 v42, v127, v49
	v_dot8c_i32_i4_e32 v43, v127, v47
	v_dot8c_i32_i4_e32 v44, v129, v49
	v_dot8c_i32_i4_e32 v45, v129, v47
	s_waitcnt lgkmcnt(15)
	v_add_u32_e32 v143, 8, v139
	v_and_b32_e32 v142, 15, v143
	v_xor_b32_e32 v142, 8, v142
	v_bfe_u32 v144, v143, 4, 4
	v_mul_lo_u32 v142, v142, s92
	v_mul_lo_u32 v144, v144, s92
	v_mov_b32_e32 v143, v142
	v_mov_b32_e32 v145, v144
	ds_write2st64_b64 v159, v[142:143], v[144:145] offset1:2
	v_and_b32_e32 v78, 0xffff, v28
	v_lshrrev_b32_e32 v79, 16, v28
	v_lshl_add_u32 v78, v78, 7, v150
	v_lshl_add_u32 v79, v79, 7, v151
	s_mov_b32 m0, s76
	s_add_i32 s43, s76, 0x400
	global_load_lds_dwordx4 v78, s[50:51]
	s_mov_b32 m0, s43
	s_nop 0
	global_load_lds_dwordx4 v79, s[50:51]
	s_waitcnt vmcnt(8)
	v_add_u32_e32 v54, s78, v59
	v_add_u32_e32 v55, s78, v60
	v_add_u32_e32 v56, s78, v61
	v_add_u32_e32 v57, s78, v62
	ds_read_b64_tr_b4 v[46:47], v160 offset:768
	ds_read_b64_tr_b4 v[48:49], v160 offset:1792
	ds_read_b64_tr_b4 v[122:123], v54
	ds_read_b64_tr_b4 v[124:125], v55
	ds_read_b64_tr_b4 v[126:127], v56
	ds_read_b64_tr_b4 v[128:129], v57
	s_waitcnt lgkmcnt(7)
	v_dot8c_i32_i4_e32 v38, v130, v52
	v_dot8c_i32_i4_e32 v39, v130, v50
	v_dot8c_i32_i4_e32 v40, v132, v52
	v_dot8c_i32_i4_e32 v41, v132, v50
	v_dot8c_i32_i4_e32 v42, v134, v52
	v_dot8c_i32_i4_e32 v43, v134, v50
	v_dot8c_i32_i4_e32 v44, v136, v52
	v_dot8c_i32_i4_e32 v45, v136, v50
	v_dot8c_i32_i4_e32 v38, v131, v53
	v_dot8c_i32_i4_e32 v39, v131, v51
	v_dot8c_i32_i4_e32 v40, v133, v53
	v_dot8c_i32_i4_e32 v41, v133, v51
	v_dot8c_i32_i4_e32 v42, v135, v53
	v_dot8c_i32_i4_e32 v43, v135, v51
	v_dot8c_i32_i4_e32 v44, v137, v53
	v_dot8c_i32_i4_e32 v45, v137, v51
	v_and_b32_e32 v78, 0xffff, v29
	v_lshrrev_b32_e32 v79, 16, v29
	v_lshl_add_u32 v78, v78, 7, v150
	v_lshl_add_u32 v79, v79, 7, v151
	s_mov_b32 m0, s77
	s_add_i32 s43, s77, 0x400
	global_load_lds_dwordx4 v78, s[50:51]
	s_mov_b32 m0, s43
	s_nop 0
	global_load_lds_dwordx4 v79, s[50:51]
	s_waitcnt vmcnt(8)
	v_add_u32_e32 v54, s79, v59
	v_add_u32_e32 v55, s79, v60
	v_add_u32_e32 v56, s79, v61
	v_add_u32_e32 v57, s79, v62
	ds_read_b64_tr_b4 v[50:51], v160 offset:896
	ds_read_b64_tr_b4 v[52:53], v160 offset:1920
	ds_read_b64_tr_b4 v[130:131], v54
	ds_read_b64_tr_b4 v[132:133], v55
	ds_read_b64_tr_b4 v[134:135], v56
	ds_read_b64_tr_b4 v[136:137], v57
	s_waitcnt lgkmcnt(6)
; __device__ __forceinline__ bf16 f2bf(float f) { return (bf16)f2bfu(f); }
; #define TR4(p_) __builtin_amdgcn_ds_read_tr4_b64_v2i32((LAS v2i*)(p_))
; __device__ __forceinline__ void peer_v_tokens(int j, const LAS unsigned short* EL, const LAS unsigned char* AL  , const LAS float* ASC  , const LAS int* SAL  , ...
;     ...
;         for (int st = 0; st < 16; ++st) {
;             const int p = st >> 2, q = st & 3;
;             if (st < 14) VDMA(st + 2, (st + 2) % 3);
;             if (st < 14) asm volatile("s_waitcnt vmcnt(8)" ::: "memory");
;             else if (st == 14) asm volatile("s_waitcnt vmcnt(4)" ::: "memory");
;             else asm volatile("s_waitcnt vmcnt(0)" ::: "memory");
;             if (q == 0) {
; #pragma unroll
;                 for (int r = 0; r < 4; ++r) { accH[r] = 0; accL[r] = 0; } }
; #pragma unroll
;             for (int tp = 0; tp < 2; ++tp) {
;                 const v2i ao = TR4(ATL + (2 * q + tp) * 128 + 8 * s16), ah = TR4(ATL + 1024 + (2 * q + tp) * 128 + 8 * s16);
; #pragma unroll
;                 for (int r = 0; r < 4; ++r) {
;                     const v2i d = TR4(ldsb + BUF[st % 3] + 2048 * tp + roff[r]);
;                     accH[r] = __builtin_amdgcn_sdot8(d.x, ah.x, accH[r], false); accH[r] = __builtin_amdgcn_sdot8(d.y, ah.y, accH[r], false);
;                     accL[r] = __builtin_amdgcn_sdot8(d.x, ao.x, accL[r], false); accL[r] = __builtin_amdgcn_sdot8(d.y, ao.y, accL[r], false);
;                 }
;             }
;             asm volatile("s_waitcnt lgkmcnt(0)" ::: "memory");
;             if (q == 3) {
; #pragma unroll
;                 for (int r = 0; r < 4; ++r) STASH[256 * p + 16 * (grp + 4 * r) + pc] = f2bf(asc * (float)(2 * ((accH[r] << 4) + accL[r]) + sa));
;             }
;     ...
;             float4* op = (float4*)(outp + (size_t)t * D) + lane;
; #pragma unroll
;             for (int jq = 0; jq < 4; ++jq) { typedef float f4v __attribute__((ext_vector_type(4))); f4v o4; o4.x = v[jq].x * r3 * gv[jq].x; o4.y = v[jq].y * r3 * gv[jq].y; o4.z = v[jq].z * r3 * gv[jq].z; o4.w = v[jq].w * r3 * gv[jq].w;
;                 __builtin_nontemporal_store(o4, (f4v*)op + 64 * jq); }
	v_dot8c_i32_i4_e32 v38, v122, v48
	v_dot8c_i32_i4_e32 v39, v122, v46
	v_dot8c_i32_i4_e32 v40, v124, v48
	v_dot8c_i32_i4_e32 v41, v124, v46
	v_dot8c_i32_i4_e32 v42, v126, v48
	v_dot8c_i32_i4_e32 v43, v126, v46
	v_dot8c_i32_i4_e32 v44, v128, v48
	v_dot8c_i32_i4_e32 v45, v128, v46
	v_dot8c_i32_i4_e32 v38, v123, v49
	v_dot8c_i32_i4_e32 v39, v123, v47
	v_dot8c_i32_i4_e32 v40, v125, v49
	v_dot8c_i32_i4_e32 v41, v125, v47
	v_dot8c_i32_i4_e32 v42, v127, v49
	v_dot8c_i32_i4_e32 v43, v127, v47
	v_dot8c_i32_i4_e32 v44, v129, v49
	v_dot8c_i32_i4_e32 v45, v129, v47
	v_and_b32_e32 v78, 0xffff, v30
	v_lshrrev_b32_e32 v79, 16, v30
	v_lshl_add_u32 v78, v78, 7, v150
	v_lshl_add_u32 v79, v79, 7, v151
	s_mov_b32 m0, s78
	s_add_i32 s43, s78, 0x400
	global_load_lds_dwordx4 v78, s[50:51]
	s_mov_b32 m0, s43
	s_nop 0
	global_load_lds_dwordx4 v79, s[50:51]
	s_waitcnt vmcnt(8)
	v_add_u32_e32 v54, s98, v59
	v_add_u32_e32 v55, s98, v60
	v_add_u32_e32 v56, s98, v61
	v_add_u32_e32 v57, s98, v62
	ds_read_b64_tr_b4 v[46:47], v160
	ds_read_b64_tr_b4 v[48:49], v160 offset:1024
	ds_read_b64_tr_b4 v[122:123], v54
	ds_read_b64_tr_b4 v[124:125], v55
	ds_read_b64_tr_b4 v[126:127], v56
	ds_read_b64_tr_b4 v[128:129], v57
	s_waitcnt lgkmcnt(6)
	v_dot8c_i32_i4_e32 v38, v130, v52
	v_dot8c_i32_i4_e32 v39, v130, v50
	v_dot8c_i32_i4_e32 v40, v132, v52
	v_dot8c_i32_i4_e32 v41, v132, v50
	v_dot8c_i32_i4_e32 v42, v134, v52
	v_dot8c_i32_i4_e32 v43, v134, v50
	v_dot8c_i32_i4_e32 v44, v136, v52
	v_dot8c_i32_i4_e32 v45, v136, v50
	v_dot8c_i32_i4_e32 v38, v131, v53
	v_dot8c_i32_i4_e32 v39, v131, v51
	v_dot8c_i32_i4_e32 v40, v133, v53
	v_dot8c_i32_i4_e32 v41, v133, v51
	v_dot8c_i32_i4_e32 v42, v135, v53
	v_dot8c_i32_i4_e32 v43, v135, v51
	v_dot8c_i32_i4_e32 v44, v137, v53
	v_dot8c_i32_i4_e32 v45, v137, v51
	s_nop 3
	s_waitcnt lgkmcnt(15)
	v_lshlrev_b32_e32 v38, 5, v38
	v_lshlrev_b32_e32 v39, 1, v39
	v_add3_u32 v38, v39, v229, v38
	v_cvt_f32_i32_e32 v38, v38
	v_mul_f32_e32 v38, v228, v38
	v_lshlrev_b32_e32 v40, 5, v40
	v_lshlrev_b32_e32 v41, 1, v41
	v_add3_u32 v40, v41, v229, v40
	v_cvt_f32_i32_e32 v40, v40
	v_mul_f32_e32 v40, v228, v40
	v_lshlrev_b32_e32 v42, 5, v42
	v_lshlrev_b32_e32 v43, 1, v43
	v_add3_u32 v42, v43, v229, v42
	v_cvt_f32_i32_e32 v42, v42
	v_mul_f32_e32 v42, v228, v42
	v_lshlrev_b32_e32 v44, 5, v44
	v_lshlrev_b32_e32 v45, 1, v45
	v_add3_u32 v44, v45, v229, v44
	v_cvt_f32_i32_e32 v44, v44
	v_mul_f32_e32 v44, v228, v44
	v_cvt_pk_bf16_f32 v182, v38, v40
	v_cvt_pk_bf16_f32 v183, v42, v44
	ds_read_b128 v[252:255], v156 offset:1024
	s_add_i32 s44, s40, 32
	s_ashr_i32 s45, s44, 31
	s_lshl_b64 s[44:45], s[44:45], 12
	v_lshl_add_u64 v[80:81], v[36:37], 0, s[44:45]
	s_waitcnt lgkmcnt(0)
	v_mul_f32_e32 v222, v222, v252
	v_mul_f32_e32 v223, v223, v253
	v_mul_f32_e32 v224, v224, v254
	v_mul_f32_e32 v225, v225, v255
	global_store_dwordx4 v[80:81], v[222:225], off offset:3072 nt
	ds_read_b128 v[252:255], v155
	s_add_i32 s44, s40, 40
	s_ashr_i32 s45, s44, 31
	s_lshl_b64 s[44:45], s[44:45], 12
	v_lshl_add_u64 v[80:81], v[36:37], 0, s[44:45]
	s_waitcnt lgkmcnt(0)
	v_mul_f32_e32 v236, v236, v252
	v_mul_f32_e32 v237, v237, v253
	v_mul_f32_e32 v238, v238, v254
	v_mul_f32_e32 v239, v239, v255
	global_store_dwordx4 v[80:81], v[236:239], off nt
	v_add_u32_e32 v147, 8, v140
	v_and_b32_e32 v146, 15, v147
	v_xor_b32_e32 v146, 8, v146
	v_bfe_u32 v148, v147, 4, 4
	v_mul_lo_u32 v146, v146, s92
	v_mul_lo_u32 v148, v148, s92
	v_mov_b32_e32 v147, v146
	v_mov_b32_e32 v149, v148
	ds_write2st64_b64 v77, v[146:147], v[148:149] offset1:2
	v_add_u32_e32 v138, 0x1800, v74
	ds_read_u8 v139, v138
	v_add_u32_e32 v141, 0x1800, v73
	ds_read_u8 v140, v141
	s_add_i32 s43, s67, 224
	v_mov_b32_e32 v138, s43
	ds_read2st64_b32 v[228:229], v138 offset1:1
	ds_read_b128 v[18:21], v227 offset:12288
	ds_read_b128 v[22:25], v227 offset:12304
	v_add_u32_e32 v152, 0x600000, v63
	v_add_u32_e32 v153, 0x600000, v64
	v_mov_b32_e32 v38, 0
	v_mov_b32_e32 v39, 0
	v_mov_b32_e32 v40, 0
	v_mov_b32_e32 v41, 0
	v_mov_b32_e32 v42, 0
	v_mov_b32_e32 v43, 0
	v_mov_b32_e32 v44, 0
	v_mov_b32_e32 v45, 0
	v_and_b32_e32 v78, 0xffff, v31
	v_lshrrev_b32_e32 v79, 16, v31
	v_lshl_add_u32 v78, v78, 7, v150
	v_lshl_add_u32 v79, v79, 7, v151
	s_mov_b32 m0, s79
	s_add_i32 s43, s79, 0x400
	global_load_lds_dwordx4 v78, s[50:51]
	s_mov_b32 m0, s43
	s_nop 0
	global_load_lds_dwordx4 v79, s[50:51]
	s_waitcnt vmcnt(10)
	v_add_u32_e32 v54, s99, v59
	v_add_u32_e32 v55, s99, v60
	v_add_u32_e32 v56, s99, v61
	v_add_u32_e32 v57, s99, v62
	ds_read_b64_tr_b4 v[50:51], v160 offset:128
	ds_read_b64_tr_b4 v[52:53], v160 offset:1152
	ds_read_b64_tr_b4 v[130:131], v54
	ds_read_b64_tr_b4 v[132:133], v55
	ds_read_b64_tr_b4 v[134:135], v56
	ds_read_b64_tr_b4 v[136:137], v57
	s_waitcnt lgkmcnt(14)
	v_dot8c_i32_i4_e32 v38, v122, v48
	v_dot8c_i32_i4_e32 v39, v122, v46
	v_dot8c_i32_i4_e32 v40, v124, v48
	v_dot8c_i32_i4_e32 v41, v124, v46
	v_dot8c_i32_i4_e32 v42, v126, v48
	v_dot8c_i32_i4_e32 v43, v126, v46
	v_dot8c_i32_i4_e32 v44, v128, v48
	v_dot8c_i32_i4_e32 v45, v128, v46
	v_dot8c_i32_i4_e32 v38, v123, v49
	v_dot8c_i32_i4_e32 v39, v123, v47
	v_dot8c_i32_i4_e32 v40, v125, v49
	v_dot8c_i32_i4_e32 v41, v125, v47
	v_dot8c_i32_i4_e32 v42, v127, v49
	v_dot8c_i32_i4_e32 v43, v127, v47
	v_dot8c_i32_i4_e32 v44, v129, v49
	v_dot8c_i32_i4_e32 v45, v129, v47
	v_and_b32_e32 v78, 0xffff, v32
	v_lshrrev_b32_e32 v79, 16, v32
	v_lshl_add_u32 v78, v78, 7, v150
	v_lshl_add_u32 v79, v79, 7, v151
	s_mov_b32 m0, s98
	s_add_i32 s43, s98, 0x400
	global_load_lds_dwordx4 v78, s[50:51]
	s_mov_b32 m0, s43
	s_nop 0
	global_load_lds_dwordx4 v79, s[50:51]
	s_waitcnt vmcnt(10)
; #define TR4(p_) __builtin_amdgcn_ds_read_tr4_b64_v2i32((LAS v2i*)(p_))
; #define VDMA(st_, k_) do { _Pragma("unroll") for (int i_ = 0; i_ < 4; ++i_) { \
;         const unsigned off_ = (unsigned)((st_) >> 2) * (16384u * 128u) + (PE_ID(E, 4 * ((st_) & 3) + i_) << 7) + ((i_ & 1) ? cx1 : cx0); \
;         __builtin_amdgcn_global_load_lds((const unsigned*)(V4 + off_), (LAS unsigned*)(ldsb + BUF[k_] + 1024 * i_), 16, 0, 0); } } while (0)
; __device__ __forceinline__ void peer_v_tokens(int j, const LAS unsigned short* EL, const LAS unsigned char* AL  , const LAS float* ASC  , const LAS int* SAL  , ...
;     ...
;         for (int st = 0; st < 16; ++st) {
;             const int p = st >> 2, q = st & 3;
;             if (st < 14) VDMA(st + 2, (st + 2) % 3);
;             if (st < 14) asm volatile("s_waitcnt vmcnt(8)" ::: "memory");
;             else if (st == 14) asm volatile("s_waitcnt vmcnt(4)" ::: "memory");
;             else asm volatile("s_waitcnt vmcnt(0)" ::: "memory");
;             if (q == 0) {
; #pragma unroll
;                 for (int r = 0; r < 4; ++r) { accH[r] = 0; accL[r] = 0; } }
; #pragma unroll
;             for (int tp = 0; tp < 2; ++tp) {
;                 const v2i ao = TR4(ATL + (2 * q + tp) * 128 + 8 * s16), ah = TR4(ATL + 1024 + (2 * q + tp) * 128 + 8 * s16);
; #pragma unroll
;                 for (int r = 0; r < 4; ++r) {
;                     const v2i d = TR4(ldsb + BUF[st % 3] + 2048 * tp + roff[r]);
;                     accH[r] = __builtin_amdgcn_sdot8(d.x, ah.x, accH[r], false); accH[r] = __builtin_amdgcn_sdot8(d.y, ah.y, accH[r], false);
;                     accL[r] = __builtin_amdgcn_sdot8(d.x, ao.x, accL[r], false); accL[r] = __builtin_amdgcn_sdot8(d.y, ao.y, accL[r], false);
;                 }
;             }
	v_add_u32_e32 v54, s76, v59
	v_add_u32_e32 v55, s76, v60
	v_add_u32_e32 v56, s76, v61
	v_add_u32_e32 v57, s76, v62
	ds_read_b64_tr_b4 v[46:47], v160 offset:256
	ds_read_b64_tr_b4 v[48:49], v160 offset:1280
	ds_read_b64_tr_b4 v[122:123], v54
	ds_read_b64_tr_b4 v[124:125], v55
	ds_read_b64_tr_b4 v[126:127], v56
	ds_read_b64_tr_b4 v[128:129], v57
	s_waitcnt lgkmcnt(6)
	v_dot8c_i32_i4_e32 v38, v130, v52
	v_dot8c_i32_i4_e32 v39, v130, v50
	v_dot8c_i32_i4_e32 v40, v132, v52
	v_dot8c_i32_i4_e32 v41, v132, v50
	v_dot8c_i32_i4_e32 v42, v134, v52
	v_dot8c_i32_i4_e32 v43, v134, v50
	v_dot8c_i32_i4_e32 v44, v136, v52
	v_dot8c_i32_i4_e32 v45, v136, v50
	v_dot8c_i32_i4_e32 v38, v131, v53
	v_dot8c_i32_i4_e32 v39, v131, v51
	v_dot8c_i32_i4_e32 v40, v133, v53
	v_dot8c_i32_i4_e32 v41, v133, v51
	v_dot8c_i32_i4_e32 v42, v135, v53
	v_dot8c_i32_i4_e32 v43, v135, v51
	v_dot8c_i32_i4_e32 v44, v137, v53
	v_dot8c_i32_i4_e32 v45, v137, v51
	v_and_b32_e32 v78, 0xffff, v33
	v_lshrrev_b32_e32 v79, 16, v33
	v_lshl_add_u32 v78, v78, 7, v150
	v_lshl_add_u32 v79, v79, 7, v151
	s_mov_b32 m0, s99
	s_add_i32 s43, s99, 0x400
	global_load_lds_dwordx4 v78, s[50:51]
	s_mov_b32 m0, s43
	s_nop 0
	global_load_lds_dwordx4 v79, s[50:51]
	s_waitcnt vmcnt(10)
	v_add_u32_e32 v54, s77, v59
	v_add_u32_e32 v55, s77, v60
	v_add_u32_e32 v56, s77, v61
	v_add_u32_e32 v57, s77, v62
	ds_read_b64_tr_b4 v[50:51], v160 offset:384
	ds_read_b64_tr_b4 v[52:53], v160 offset:1408
	ds_read_b64_tr_b4 v[130:131], v54
	ds_read_b64_tr_b4 v[132:133], v55
	ds_read_b64_tr_b4 v[134:135], v56
	ds_read_b64_tr_b4 v[136:137], v57
	s_waitcnt lgkmcnt(6)
	v_dot8c_i32_i4_e32 v38, v122, v48
	v_dot8c_i32_i4_e32 v39, v122, v46
	v_dot8c_i32_i4_e32 v40, v124, v48
	v_dot8c_i32_i4_e32 v41, v124, v46
	v_dot8c_i32_i4_e32 v42, v126, v48
	v_dot8c_i32_i4_e32 v43, v126, v46
	v_dot8c_i32_i4_e32 v44, v128, v48
	v_dot8c_i32_i4_e32 v45, v128, v46
	v_dot8c_i32_i4_e32 v38, v123, v49
	v_dot8c_i32_i4_e32 v39, v123, v47
	v_dot8c_i32_i4_e32 v40, v125, v49
	v_dot8c_i32_i4_e32 v41, v125, v47
	v_dot8c_i32_i4_e32 v42, v127, v49
	v_dot8c_i32_i4_e32 v43, v127, v47
	v_dot8c_i32_i4_e32 v44, v129, v49
	v_dot8c_i32_i4_e32 v45, v129, v47
	s_waitcnt lgkmcnt(15)
	v_and_b32_e32 v78, 0xffff, v18
	v_lshrrev_b32_e32 v79, 16, v18
	v_lshl_add_u32 v78, v78, 7, v152
	v_lshl_add_u32 v79, v79, 7, v153
	s_mov_b32 m0, s76
	s_add_i32 s43, s76, 0x400
	global_load_lds_dwordx4 v78, s[50:51]
	s_mov_b32 m0, s43
	s_nop 0
	global_load_lds_dwordx4 v79, s[50:51]
	s_waitcnt vmcnt(10)
	v_add_u32_e32 v54, s78, v59
	v_add_u32_e32 v55, s78, v60
	v_add_u32_e32 v56, s78, v61
	v_add_u32_e32 v57, s78, v62
	ds_read_b64_tr_b4 v[46:47], v160 offset:512
	ds_read_b64_tr_b4 v[48:49], v160 offset:1536
	ds_read_b64_tr_b4 v[122:123], v54
	ds_read_b64_tr_b4 v[124:125], v55
	ds_read_b64_tr_b4 v[126:127], v56
	ds_read_b64_tr_b4 v[128:129], v57
	s_waitcnt lgkmcnt(6)
	v_dot8c_i32_i4_e32 v38, v130, v52
	v_dot8c_i32_i4_e32 v39, v130, v50
	v_dot8c_i32_i4_e32 v40, v132, v52
	v_dot8c_i32_i4_e32 v41, v132, v50
	v_dot8c_i32_i4_e32 v42, v134, v52
	v_dot8c_i32_i4_e32 v43, v134, v50
	v_dot8c_i32_i4_e32 v44, v136, v52
	v_dot8c_i32_i4_e32 v45, v136, v50
	v_dot8c_i32_i4_e32 v38, v131, v53
	v_dot8c_i32_i4_e32 v39, v131, v51
	v_dot8c_i32_i4_e32 v40, v133, v53
	v_dot8c_i32_i4_e32 v41, v133, v51
	v_dot8c_i32_i4_e32 v42, v135, v53
	v_dot8c_i32_i4_e32 v43, v135, v51
	v_dot8c_i32_i4_e32 v44, v137, v53
	v_dot8c_i32_i4_e32 v45, v137, v51
	v_and_b32_e32 v78, 0xffff, v19
	v_lshrrev_b32_e32 v79, 16, v19
	v_lshl_add_u32 v78, v78, 7, v152
	v_lshl_add_u32 v79, v79, 7, v153
	s_mov_b32 m0, s77
	s_add_i32 s43, s77, 0x400
	global_load_lds_dwordx4 v78, s[50:51]
	s_mov_b32 m0, s43
	s_nop 0
	global_load_lds_dwordx4 v79, s[50:51]
	s_waitcnt vmcnt(8)
	v_add_u32_e32 v54, s79, v59
	v_add_u32_e32 v55, s79, v60
	v_add_u32_e32 v56, s79, v61
	v_add_u32_e32 v57, s79, v62
	ds_read_b64_tr_b4 v[50:51], v160 offset:640
	ds_read_b64_tr_b4 v[52:53], v160 offset:1664
	ds_read_b64_tr_b4 v[130:131], v54
	ds_read_b64_tr_b4 v[132:133], v55
	ds_read_b64_tr_b4 v[134:135], v56
	ds_read_b64_tr_b4 v[136:137], v57
	s_waitcnt lgkmcnt(6)
	v_dot8c_i32_i4_e32 v38, v122, v48
	v_dot8c_i32_i4_e32 v39, v122, v46
	v_dot8c_i32_i4_e32 v40, v124, v48
	v_dot8c_i32_i4_e32 v41, v124, v46
	v_dot8c_i32_i4_e32 v42, v126, v48
	v_dot8c_i32_i4_e32 v43, v126, v46
	v_dot8c_i32_i4_e32 v44, v128, v48
	v_dot8c_i32_i4_e32 v45, v128, v46
	v_dot8c_i32_i4_e32 v38, v123, v49
	v_dot8c_i32_i4_e32 v39, v123, v47
	v_dot8c_i32_i4_e32 v40, v125, v49
	v_dot8c_i32_i4_e32 v41, v125, v47
	v_dot8c_i32_i4_e32 v42, v127, v49
	v_dot8c_i32_i4_e32 v43, v127, v47
	v_dot8c_i32_i4_e32 v44, v129, v49
	v_dot8c_i32_i4_e32 v45, v129, v47
	s_waitcnt lgkmcnt(15)
	v_add_u32_e32 v143, 8, v139
	v_and_b32_e32 v142, 15, v143
	v_xor_b32_e32 v142, 8, v142
	v_bfe_u32 v144, v143, 4, 4
	v_mul_lo_u32 v142, v142, s92
	v_mul_lo_u32 v144, v144, s92
	v_mov_b32_e32 v143, v142
	v_mov_b32_e32 v145, v144
	ds_write2st64_b64 v159, v[142:143], v[144:145] offset1:2
	v_and_b32_e32 v78, 0xffff, v20
	v_lshrrev_b32_e32 v79, 16, v20
	v_lshl_add_u32 v78, v78, 7, v152
	v_lshl_add_u32 v79, v79, 7, v153
	s_mov_b32 m0, s78
	s_add_i32 s43, s78, 0x400
	global_load_lds_dwordx4 v78, s[50:51]
	s_mov_b32 m0, s43
	s_nop 0
	global_load_lds_dwordx4 v79, s[50:51]
	s_waitcnt vmcnt(8)
	v_add_u32_e32 v54, s98, v59
	v_add_u32_e32 v55, s98, v60
	v_add_u32_e32 v56, s98, v61
	v_add_u32_e32 v57, s98, v62
	ds_read_b64_tr_b4 v[46:47], v160 offset:768
	ds_read_b64_tr_b4 v[48:49], v160 offset:1792
	ds_read_b64_tr_b4 v[122:123], v54
	ds_read_b64_tr_b4 v[124:125], v55
	ds_read_b64_tr_b4 v[126:127], v56
	ds_read_b64_tr_b4 v[128:129], v57
	s_waitcnt lgkmcnt(7)
; __device__ __forceinline__ void peer_v_tokens(int j, const LAS unsigned short* EL, const LAS unsigned char* AL  , const LAS float* ASC  , const LAS int* SAL  , ...
;     ...
;         { const LAS v4u* ep = (const LAS v4u*)(EL + tl * 128 + 16 * g); const v4u e0 = ep[0], e1 = ep[1];
;           E[0] = e0.x; E[1] = e0.y; E[2] = e0.z; E[3] = e0.w; E[4] = e1.x; E[5] = e1.y; E[6] = e1.z; E[7] = e1.w; }
;         uint2 hv[4]; float4 gv[4];
;         { unsigned ho = (unsigned)t * (D / 4) + (unsigned)lane; asm volatile("" : "+v"(ho)); const uint2* hp = (const uint2*)HB + ho; const float4* gp = (const float4*)fng + lane;
; #pragma unroll
;           for (int jq = 0; jq < 4; ++jq) { hv[jq] = hp[64 * jq]; gv[jq] = gp[64 * jq]; } }
;         VDMA(0, 0); VDMA(1, 1);
; #pragma unroll
;         for (int m = 0; m < 2; ++m) {
;             const int idx = lane + 64 * m, tau = idx >> 4, sr = idx & 15, k = 16 * (sr & 7) + 2 * tau + (sr >> 3);
;     ...
;         for (int st = 0; st < 16; ++st) {
;             const int p = st >> 2, q = st & 3;
;             if (st < 14) VDMA(st + 2, (st + 2) % 3);
;             if (st < 14) asm volatile("s_waitcnt vmcnt(8)" ::: "memory");
;             else if (st == 14) asm volatile("s_waitcnt vmcnt(4)" ::: "memory");
;             else asm volatile("s_waitcnt vmcnt(0)" ::: "memory");
;             if (q == 0) {
; #pragma unroll
;                 for (int r = 0; r < 4; ++r) { accH[r] = 0; accL[r] = 0; } }
; #pragma unroll
;             for (int tp = 0; tp < 2; ++tp) {
;                 const v2i ao = TR4(ATL + (2 * q + tp) * 128 + 8 * s16), ah = TR4(ATL + 1024 + (2 * q + tp) * 128 + 8 * s16);
; #pragma unroll
;                 for (int r = 0; r < 4; ++r) {
;                     const v2i d = TR4(ldsb + BUF[st % 3] + 2048 * tp + roff[r]);
;                     accH[r] = __builtin_amdgcn_sdot8(d.x, ah.x, accH[r], false); accH[r] = __builtin_amdgcn_sdot8(d.y, ah.y, accH[r], false);
;                     accL[r] = __builtin_amdgcn_sdot8(d.x, ao.x, accL[r], false); accL[r] = __builtin_amdgcn_sdot8(d.y, ao.y, accL[r], false);
;                 }
;             }
;             asm volatile("s_waitcnt lgkmcnt(0)" ::: "memory");
;             if (q == 3) {
; #pragma unroll
;                 for (int r = 0; r < 4; ++r) STASH[256 * p + 16 * (grp + 4 * r) + pc] = f2bf(asc * (float)(2 * ((accH[r] << 4) + accL[r]) + sa));
;             }
	v_dot8c_i32_i4_e32 v38, v130, v52
	v_dot8c_i32_i4_e32 v39, v130, v50
	v_dot8c_i32_i4_e32 v40, v132, v52
	v_dot8c_i32_i4_e32 v41, v132, v50
	v_dot8c_i32_i4_e32 v42, v134, v52
	v_dot8c_i32_i4_e32 v43, v134, v50
	v_dot8c_i32_i4_e32 v44, v136, v52
	v_dot8c_i32_i4_e32 v45, v136, v50
	v_dot8c_i32_i4_e32 v38, v131, v53
	v_dot8c_i32_i4_e32 v39, v131, v51
	v_dot8c_i32_i4_e32 v40, v133, v53
	v_dot8c_i32_i4_e32 v41, v133, v51
	v_dot8c_i32_i4_e32 v42, v135, v53
	v_dot8c_i32_i4_e32 v43, v135, v51
	v_dot8c_i32_i4_e32 v44, v137, v53
	v_dot8c_i32_i4_e32 v45, v137, v51
	v_and_b32_e32 v78, 0xffff, v21
	v_lshrrev_b32_e32 v79, 16, v21
	v_lshl_add_u32 v78, v78, 7, v152
	v_lshl_add_u32 v79, v79, 7, v153
	s_mov_b32 m0, s79
	s_add_i32 s43, s79, 0x400
	global_load_lds_dwordx4 v78, s[50:51]
	s_mov_b32 m0, s43
	s_nop 0
	global_load_lds_dwordx4 v79, s[50:51]
	s_waitcnt vmcnt(8)
	v_add_u32_e32 v54, s99, v59
	v_add_u32_e32 v55, s99, v60
	v_add_u32_e32 v56, s99, v61
	v_add_u32_e32 v57, s99, v62
	ds_read_b64_tr_b4 v[50:51], v160 offset:896
	ds_read_b64_tr_b4 v[52:53], v160 offset:1920
	ds_read_b64_tr_b4 v[130:131], v54
	ds_read_b64_tr_b4 v[132:133], v55
	ds_read_b64_tr_b4 v[134:135], v56
	ds_read_b64_tr_b4 v[136:137], v57
	s_waitcnt lgkmcnt(6)
	v_dot8c_i32_i4_e32 v38, v122, v48
	v_dot8c_i32_i4_e32 v39, v122, v46
	v_dot8c_i32_i4_e32 v40, v124, v48
	v_dot8c_i32_i4_e32 v41, v124, v46
	v_dot8c_i32_i4_e32 v42, v126, v48
	v_dot8c_i32_i4_e32 v43, v126, v46
	v_dot8c_i32_i4_e32 v44, v128, v48
	v_dot8c_i32_i4_e32 v45, v128, v46
	v_dot8c_i32_i4_e32 v38, v123, v49
	v_dot8c_i32_i4_e32 v39, v123, v47
	v_dot8c_i32_i4_e32 v40, v125, v49
	v_dot8c_i32_i4_e32 v41, v125, v47
	v_dot8c_i32_i4_e32 v42, v127, v49
	v_dot8c_i32_i4_e32 v43, v127, v47
	v_dot8c_i32_i4_e32 v44, v129, v49
	v_dot8c_i32_i4_e32 v45, v129, v47
	v_and_b32_e32 v78, 0xffff, v22
	v_lshrrev_b32_e32 v79, 16, v22
	v_lshl_add_u32 v78, v78, 7, v152
	v_lshl_add_u32 v79, v79, 7, v153
	s_mov_b32 m0, s98
	s_add_i32 s43, s98, 0x400
	global_load_lds_dwordx4 v78, s[50:51]
	s_mov_b32 m0, s43
	s_nop 0
	global_load_lds_dwordx4 v79, s[50:51]
	s_waitcnt vmcnt(8)
	v_add_u32_e32 v54, s76, v59
	v_add_u32_e32 v55, s76, v60
	v_add_u32_e32 v56, s76, v61
	v_add_u32_e32 v57, s76, v62
	ds_read_b64_tr_b4 v[46:47], v160
	ds_read_b64_tr_b4 v[48:49], v160 offset:1024
	ds_read_b64_tr_b4 v[122:123], v54
	ds_read_b64_tr_b4 v[124:125], v55
	ds_read_b64_tr_b4 v[126:127], v56
	ds_read_b64_tr_b4 v[128:129], v57
	s_waitcnt lgkmcnt(6)
	v_dot8c_i32_i4_e32 v38, v130, v52
	v_dot8c_i32_i4_e32 v39, v130, v50
	v_dot8c_i32_i4_e32 v40, v132, v52
	v_dot8c_i32_i4_e32 v41, v132, v50
	v_dot8c_i32_i4_e32 v42, v134, v52
	v_dot8c_i32_i4_e32 v43, v134, v50
	v_dot8c_i32_i4_e32 v44, v136, v52
	v_dot8c_i32_i4_e32 v45, v136, v50
	v_dot8c_i32_i4_e32 v38, v131, v53
	v_dot8c_i32_i4_e32 v39, v131, v51
	v_dot8c_i32_i4_e32 v40, v133, v53
	v_dot8c_i32_i4_e32 v41, v133, v51
	v_dot8c_i32_i4_e32 v42, v135, v53
	v_dot8c_i32_i4_e32 v43, v135, v51
	v_dot8c_i32_i4_e32 v44, v137, v53
	v_dot8c_i32_i4_e32 v45, v137, v51
	s_nop 3
	s_waitcnt lgkmcnt(15)
	v_lshlrev_b32_e32 v38, 5, v38
	v_lshlrev_b32_e32 v39, 1, v39
	v_add3_u32 v38, v39, v229, v38
	v_cvt_f32_i32_e32 v38, v38
	v_mul_f32_e32 v38, v228, v38
	v_lshlrev_b32_e32 v40, 5, v40
	v_lshlrev_b32_e32 v41, 1, v41
	v_add3_u32 v40, v41, v229, v40
	v_cvt_f32_i32_e32 v40, v40
	v_mul_f32_e32 v40, v228, v40
	v_lshlrev_b32_e32 v42, 5, v42
	v_lshlrev_b32_e32 v43, 1, v43
	v_add3_u32 v42, v43, v229, v42
	v_cvt_f32_i32_e32 v42, v42
	v_mul_f32_e32 v42, v228, v42
	v_lshlrev_b32_e32 v44, 5, v44
	v_lshlrev_b32_e32 v45, 1, v45
	v_add3_u32 v44, v45, v229, v44
	v_cvt_f32_i32_e32 v44, v44
	v_mul_f32_e32 v44, v228, v44
	v_cvt_pk_bf16_f32 v190, v38, v40
	v_cvt_pk_bf16_f32 v191, v42, v44
	ds_read_b128 v[252:255], v155 offset:1024
	s_add_i32 s44, s40, 40
	s_ashr_i32 s45, s44, 31
	s_lshl_b64 s[44:45], s[44:45], 12
	v_lshl_add_u64 v[80:81], v[36:37], 0, s[44:45]
	s_waitcnt lgkmcnt(0)
	v_mul_f32_e32 v240, v240, v252
	v_mul_f32_e32 v241, v241, v253
	v_mul_f32_e32 v242, v242, v254
	v_mul_f32_e32 v243, v243, v255
	global_store_dwordx4 v[80:81], v[240:243], off offset:1024 nt
	v_add_u32_e32 v147, 8, v140
	v_and_b32_e32 v146, 15, v147
	v_xor_b32_e32 v146, 8, v146
	v_bfe_u32 v148, v147, 4, 4
	v_mul_lo_u32 v146, v146, s92
	v_mul_lo_u32 v148, v148, s92
	v_mov_b32_e32 v147, v146
	v_mov_b32_e32 v149, v148
	ds_write2st64_b64 v77, v[146:147], v[148:149] offset1:2
	v_add_u32_e32 v138, 0x1c00, v74
	ds_read_u8 v139, v138
	v_add_u32_e32 v141, 0x1c00, v73
	ds_read_u8 v140, v141
	s_add_i32 s43, s67, 192
	v_mov_b32_e32 v138, s43
	ds_read2st64_b32 v[228:229], v138 offset1:1
	ds_read_b128 v[26:29], v227 offset:14336
	ds_read_b128 v[30:33], v227 offset:14352
	v_mov_b32_e32 v38, 0
	v_mov_b32_e32 v39, 0
	v_mov_b32_e32 v40, 0
	v_mov_b32_e32 v41, 0
	v_mov_b32_e32 v42, 0
	v_mov_b32_e32 v43, 0
	v_mov_b32_e32 v44, 0
	v_mov_b32_e32 v45, 0
	v_and_b32_e32 v78, 0xffff, v23
	v_lshrrev_b32_e32 v79, 16, v23
	v_lshl_add_u32 v78, v78, 7, v152
	v_lshl_add_u32 v79, v79, 7, v153
	s_mov_b32 m0, s99
	s_add_i32 s43, s99, 0x400
	global_load_lds_dwordx4 v78, s[50:51]
	s_mov_b32 m0, s43
	s_nop 0
	global_load_lds_dwordx4 v79, s[50:51]
	s_waitcnt vmcnt(9)
	v_add_u32_e32 v54, s77, v59
	v_add_u32_e32 v55, s77, v60
	v_add_u32_e32 v56, s77, v61
	v_add_u32_e32 v57, s77, v62
	ds_read_b64_tr_b4 v[50:51], v160 offset:128
	ds_read_b64_tr_b4 v[52:53], v160 offset:1152
	ds_read_b64_tr_b4 v[130:131], v54
	ds_read_b64_tr_b4 v[132:133], v55
	ds_read_b64_tr_b4 v[134:135], v56
	ds_read_b64_tr_b4 v[136:137], v57
	s_waitcnt lgkmcnt(13)
; #define TR4(p_) __builtin_amdgcn_ds_read_tr4_b64_v2i32((LAS v2i*)(p_))
; #define VDMA(st_, k_) do { _Pragma("unroll") for (int i_ = 0; i_ < 4; ++i_) { \
;         const unsigned off_ = (unsigned)((st_) >> 2) * (16384u * 128u) + (PE_ID(E, 4 * ((st_) & 3) + i_) << 7) + ((i_ & 1) ? cx1 : cx0); \
;         __builtin_amdgcn_global_load_lds((const unsigned*)(V4 + off_), (LAS unsigned*)(ldsb + BUF[k_] + 1024 * i_), 16, 0, 0); } } while (0)
; __device__ __forceinline__ void peer_v_tokens(int j, const LAS unsigned short* EL, const LAS unsigned char* AL  , const LAS float* ASC  , const LAS int* SAL  , ...
;     ...
;         for (int st = 0; st < 16; ++st) {
;             const int p = st >> 2, q = st & 3;
;             if (st < 14) VDMA(st + 2, (st + 2) % 3);
;             if (st < 14) asm volatile("s_waitcnt vmcnt(8)" ::: "memory");
;             else if (st == 14) asm volatile("s_waitcnt vmcnt(4)" ::: "memory");
;             else asm volatile("s_waitcnt vmcnt(0)" ::: "memory");
;             if (q == 0) {
; #pragma unroll
;                 for (int r = 0; r < 4; ++r) { accH[r] = 0; accL[r] = 0; } }
; #pragma unroll
;             for (int tp = 0; tp < 2; ++tp) {
;                 const v2i ao = TR4(ATL + (2 * q + tp) * 128 + 8 * s16), ah = TR4(ATL + 1024 + (2 * q + tp) * 128 + 8 * s16);
; #pragma unroll
;                 for (int r = 0; r < 4; ++r) {
;                     const v2i d = TR4(ldsb + BUF[st % 3] + 2048 * tp + roff[r]);
;                     accH[r] = __builtin_amdgcn_sdot8(d.x, ah.x, accH[r], false); accH[r] = __builtin_amdgcn_sdot8(d.y, ah.y, accH[r], false);
;                     accL[r] = __builtin_amdgcn_sdot8(d.x, ao.x, accL[r], false); accL[r] = __builtin_amdgcn_sdot8(d.y, ao.y, accL[r], false);
;                 }
;             }
	v_dot8c_i32_i4_e32 v38, v122, v48
	v_dot8c_i32_i4_e32 v39, v122, v46
	v_dot8c_i32_i4_e32 v40, v124, v48
	v_dot8c_i32_i4_e32 v41, v124, v46
	v_dot8c_i32_i4_e32 v42, v126, v48
	v_dot8c_i32_i4_e32 v43, v126, v46
	v_dot8c_i32_i4_e32 v44, v128, v48
	v_dot8c_i32_i4_e32 v45, v128, v46
	v_dot8c_i32_i4_e32 v38, v123, v49
	v_dot8c_i32_i4_e32 v39, v123, v47
	v_dot8c_i32_i4_e32 v40, v125, v49
	v_dot8c_i32_i4_e32 v41, v125, v47
	v_dot8c_i32_i4_e32 v42, v127, v49
	v_dot8c_i32_i4_e32 v43, v127, v47
	v_dot8c_i32_i4_e32 v44, v129, v49
	v_dot8c_i32_i4_e32 v45, v129, v47
	v_and_b32_e32 v78, 0xffff, v24
	v_lshrrev_b32_e32 v79, 16, v24
	v_lshl_add_u32 v78, v78, 7, v152
	v_lshl_add_u32 v79, v79, 7, v153
	s_mov_b32 m0, s76
	s_add_i32 s43, s76, 0x400
	global_load_lds_dwordx4 v78, s[50:51]
	s_mov_b32 m0, s43
	s_nop 0
	global_load_lds_dwordx4 v79, s[50:51]
	s_waitcnt vmcnt(9)
	v_add_u32_e32 v54, s78, v59
	v_add_u32_e32 v55, s78, v60
	v_add_u32_e32 v56, s78, v61
	v_add_u32_e32 v57, s78, v62
	ds_read_b64_tr_b4 v[46:47], v160 offset:256
	ds_read_b64_tr_b4 v[48:49], v160 offset:1280
	ds_read_b64_tr_b4 v[122:123], v54
	ds_read_b64_tr_b4 v[124:125], v55
	ds_read_b64_tr_b4 v[126:127], v56
	ds_read_b64_tr_b4 v[128:129], v57
	s_waitcnt lgkmcnt(6)
	v_dot8c_i32_i4_e32 v38, v130, v52
	v_dot8c_i32_i4_e32 v39, v130, v50
	v_dot8c_i32_i4_e32 v40, v132, v52
	v_dot8c_i32_i4_e32 v41, v132, v50
	v_dot8c_i32_i4_e32 v42, v134, v52
	v_dot8c_i32_i4_e32 v43, v134, v50
	v_dot8c_i32_i4_e32 v44, v136, v52
	v_dot8c_i32_i4_e32 v45, v136, v50
	v_dot8c_i32_i4_e32 v38, v131, v53
	v_dot8c_i32_i4_e32 v39, v131, v51
	v_dot8c_i32_i4_e32 v40, v133, v53
	v_dot8c_i32_i4_e32 v41, v133, v51
	v_dot8c_i32_i4_e32 v42, v135, v53
	v_dot8c_i32_i4_e32 v43, v135, v51
	v_dot8c_i32_i4_e32 v44, v137, v53
	v_dot8c_i32_i4_e32 v45, v137, v51
	v_and_b32_e32 v78, 0xffff, v25
	v_lshrrev_b32_e32 v79, 16, v25
	v_lshl_add_u32 v78, v78, 7, v152
	v_lshl_add_u32 v79, v79, 7, v153
	s_mov_b32 m0, s77
	s_add_i32 s43, s77, 0x400
	global_load_lds_dwordx4 v78, s[50:51]
	s_mov_b32 m0, s43
	s_nop 0
	global_load_lds_dwordx4 v79, s[50:51]
	s_waitcnt vmcnt(9)
	v_add_u32_e32 v54, s79, v59
	v_add_u32_e32 v55, s79, v60
	v_add_u32_e32 v56, s79, v61
	v_add_u32_e32 v57, s79, v62
	ds_read_b64_tr_b4 v[50:51], v160 offset:384
	ds_read_b64_tr_b4 v[52:53], v160 offset:1408
	ds_read_b64_tr_b4 v[130:131], v54
	ds_read_b64_tr_b4 v[132:133], v55
	ds_read_b64_tr_b4 v[134:135], v56
	ds_read_b64_tr_b4 v[136:137], v57
	s_waitcnt lgkmcnt(6)
	v_dot8c_i32_i4_e32 v38, v122, v48
	v_dot8c_i32_i4_e32 v39, v122, v46
	v_dot8c_i32_i4_e32 v40, v124, v48
	v_dot8c_i32_i4_e32 v41, v124, v46
	v_dot8c_i32_i4_e32 v42, v126, v48
	v_dot8c_i32_i4_e32 v43, v126, v46
	v_dot8c_i32_i4_e32 v44, v128, v48
	v_dot8c_i32_i4_e32 v45, v128, v46
	v_dot8c_i32_i4_e32 v38, v123, v49
	v_dot8c_i32_i4_e32 v39, v123, v47
	v_dot8c_i32_i4_e32 v40, v125, v49
	v_dot8c_i32_i4_e32 v41, v125, v47
	v_dot8c_i32_i4_e32 v42, v127, v49
	v_dot8c_i32_i4_e32 v43, v127, v47
	v_dot8c_i32_i4_e32 v44, v129, v49
	v_dot8c_i32_i4_e32 v45, v129, v47
	s_waitcnt lgkmcnt(15)
	v_and_b32_e32 v78, 0xffff, v26
	v_lshrrev_b32_e32 v79, 16, v26
	v_lshl_add_u32 v78, v78, 7, v152
	v_lshl_add_u32 v79, v79, 7, v153
	s_mov_b32 m0, s78
	s_add_i32 s43, s78, 0x400
	global_load_lds_dwordx4 v78, s[50:51]
	s_mov_b32 m0, s43
	s_nop 0
	global_load_lds_dwordx4 v79, s[50:51]
	s_waitcnt vmcnt(9)
	v_add_u32_e32 v54, s98, v59
	v_add_u32_e32 v55, s98, v60
	v_add_u32_e32 v56, s98, v61
	v_add_u32_e32 v57, s98, v62
	ds_read_b64_tr_b4 v[46:47], v160 offset:512
	ds_read_b64_tr_b4 v[48:49], v160 offset:1536
	ds_read_b64_tr_b4 v[122:123], v54
	ds_read_b64_tr_b4 v[124:125], v55
	ds_read_b64_tr_b4 v[126:127], v56
	ds_read_b64_tr_b4 v[128:129], v57
	s_waitcnt lgkmcnt(6)
	v_dot8c_i32_i4_e32 v38, v130, v52
	v_dot8c_i32_i4_e32 v39, v130, v50
	v_dot8c_i32_i4_e32 v40, v132, v52
	v_dot8c_i32_i4_e32 v41, v132, v50
	v_dot8c_i32_i4_e32 v42, v134, v52
	v_dot8c_i32_i4_e32 v43, v134, v50
	v_dot8c_i32_i4_e32 v44, v136, v52
	v_dot8c_i32_i4_e32 v45, v136, v50
	v_dot8c_i32_i4_e32 v38, v131, v53
	v_dot8c_i32_i4_e32 v39, v131, v51
	v_dot8c_i32_i4_e32 v40, v133, v53
	v_dot8c_i32_i4_e32 v41, v133, v51
	v_dot8c_i32_i4_e32 v42, v135, v53
	v_dot8c_i32_i4_e32 v43, v135, v51
	v_dot8c_i32_i4_e32 v44, v137, v53
	v_dot8c_i32_i4_e32 v45, v137, v51
	v_and_b32_e32 v78, 0xffff, v27
	v_lshrrev_b32_e32 v79, 16, v27
	v_lshl_add_u32 v78, v78, 7, v152
	v_lshl_add_u32 v79, v79, 7, v153
	s_mov_b32 m0, s79
	s_add_i32 s43, s79, 0x400
	global_load_lds_dwordx4 v78, s[50:51]
	s_mov_b32 m0, s43
	s_nop 0
	global_load_lds_dwordx4 v79, s[50:51]
	s_waitcnt vmcnt(8)
	v_add_u32_e32 v54, s99, v59
	v_add_u32_e32 v55, s99, v60
	v_add_u32_e32 v56, s99, v61
	v_add_u32_e32 v57, s99, v62
	ds_read_b64_tr_b4 v[50:51], v160 offset:640
	ds_read_b64_tr_b4 v[52:53], v160 offset:1664
	ds_read_b64_tr_b4 v[130:131], v54
	ds_read_b64_tr_b4 v[132:133], v55
	ds_read_b64_tr_b4 v[134:135], v56
	ds_read_b64_tr_b4 v[136:137], v57
	s_waitcnt lgkmcnt(6)
	v_dot8c_i32_i4_e32 v38, v122, v48
	v_dot8c_i32_i4_e32 v39, v122, v46
	v_dot8c_i32_i4_e32 v40, v124, v48
	v_dot8c_i32_i4_e32 v41, v124, v46
	v_dot8c_i32_i4_e32 v42, v126, v48
	v_dot8c_i32_i4_e32 v43, v126, v46
	v_dot8c_i32_i4_e32 v44, v128, v48
	v_dot8c_i32_i4_e32 v45, v128, v46
	v_dot8c_i32_i4_e32 v38, v123, v49
	v_dot8c_i32_i4_e32 v39, v123, v47
	v_dot8c_i32_i4_e32 v40, v125, v49
	v_dot8c_i32_i4_e32 v41, v125, v47
	v_dot8c_i32_i4_e32 v42, v127, v49
	v_dot8c_i32_i4_e32 v43, v127, v47
	v_dot8c_i32_i4_e32 v44, v129, v49
	v_dot8c_i32_i4_e32 v45, v129, v47
	s_waitcnt lgkmcnt(15)
; __device__ __forceinline__ void peer_v_tokens(int j, const LAS unsigned short* EL, const LAS unsigned char* AL  , const LAS float* ASC  , const LAS int* SAL  , ...
;     ...
;             const int idx = lane + 64 * m, tau = idx >> 4, sr = idx & 15, k = 16 * (sr & 7) + 2 * tau + (sr >> 3);
;             const int aq = (int)*(const LAS signed char*)(AL + tl * 128 + k); const int tq = aq + 8;
;             const unsigned lo = (((unsigned)tq & 15u) ^ 8u) * 0x11111111u, hi = ((unsigned)(tq >> 4) & 15u) * 0x11111111u;
;             typedef unsigned u2v __attribute__((ext_vector_type(2)));
;             u2v l2; l2.x = lo; l2.y = lo; u2v h2; h2.x = hi; h2.y = hi;
;             *(LAS u2v*)(ATL + 8 * idx) = l2; *(LAS u2v*)(ATL + 1024 + 8 * idx) = h2;
;         }
;         const float asc = ASC[tl]; const int sa = SAL[tl];
;         CFENCE();
;         int accH[4], accL[4];
; #pragma unroll
;         for (int st = 0; st < 16; ++st) {
;             const int p = st >> 2, q = st & 3;
;             if (st < 14) VDMA(st + 2, (st + 2) % 3);
;             if (st < 14) asm volatile("s_waitcnt vmcnt(8)" ::: "memory");
;             else if (st == 14) asm volatile("s_waitcnt vmcnt(4)" ::: "memory");
;             else asm volatile("s_waitcnt vmcnt(0)" ::: "memory");
;             if (q == 0) {
; #pragma unroll
;                 for (int r = 0; r < 4; ++r) { accH[r] = 0; accL[r] = 0; } }
; #pragma unroll
;             for (int tp = 0; tp < 2; ++tp) {
;                 const v2i ao = TR4(ATL + (2 * q + tp) * 128 + 8 * s16), ah = TR4(ATL + 1024 + (2 * q + tp) * 128 + 8 * s16);
; #pragma unroll
;                 for (int r = 0; r < 4; ++r) {
;                     const v2i d = TR4(ldsb + BUF[st % 3] + 2048 * tp + roff[r]);
;                     accH[r] = __builtin_amdgcn_sdot8(d.x, ah.x, accH[r], false); accH[r] = __builtin_amdgcn_sdot8(d.y, ah.y, accH[r], false);
;                     accL[r] = __builtin_amdgcn_sdot8(d.x, ao.x, accL[r], false); accL[r] = __builtin_amdgcn_sdot8(d.y, ao.y, accL[r], false);
;                 }
;             }
;             asm volatile("s_waitcnt lgkmcnt(0)" ::: "memory");
;             if (q == 3) {
; #pragma unroll
;                 for (int r = 0; r < 4; ++r) STASH[256 * p + 16 * (grp + 4 * r) + pc] = f2bf(asc * (float)(2 * ((accH[r] << 4) + accL[r]) + sa));
;             }
;         }
;         CFENCE();
;         {
	v_add_u32_e32 v143, 8, v139
	v_and_b32_e32 v142, 15, v143
	v_xor_b32_e32 v142, 8, v142
	v_bfe_u32 v144, v143, 4, 4
	v_mul_lo_u32 v142, v142, s92
	v_mul_lo_u32 v144, v144, s92
	v_mov_b32_e32 v143, v142
	v_mov_b32_e32 v145, v144
	ds_write2st64_b64 v159, v[142:143], v[144:145] offset1:2
	v_and_b32_e32 v78, 0xffff, v28
	v_lshrrev_b32_e32 v79, 16, v28
	v_lshl_add_u32 v78, v78, 7, v152
	v_lshl_add_u32 v79, v79, 7, v153
	s_mov_b32 m0, s98
	s_add_i32 s43, s98, 0x400
	global_load_lds_dwordx4 v78, s[50:51]
	s_mov_b32 m0, s43
	s_nop 0
	global_load_lds_dwordx4 v79, s[50:51]
	s_waitcnt vmcnt(8)
	v_add_u32_e32 v54, s76, v59
	v_add_u32_e32 v55, s76, v60
	v_add_u32_e32 v56, s76, v61
	v_add_u32_e32 v57, s76, v62
	ds_read_b64_tr_b4 v[46:47], v160 offset:768
	ds_read_b64_tr_b4 v[48:49], v160 offset:1792
	ds_read_b64_tr_b4 v[122:123], v54
	ds_read_b64_tr_b4 v[124:125], v55
	ds_read_b64_tr_b4 v[126:127], v56
	ds_read_b64_tr_b4 v[128:129], v57
	s_waitcnt lgkmcnt(7)
	v_dot8c_i32_i4_e32 v38, v130, v52
	v_dot8c_i32_i4_e32 v39, v130, v50
	v_dot8c_i32_i4_e32 v40, v132, v52
	v_dot8c_i32_i4_e32 v41, v132, v50
	v_dot8c_i32_i4_e32 v42, v134, v52
	v_dot8c_i32_i4_e32 v43, v134, v50
	v_dot8c_i32_i4_e32 v44, v136, v52
	v_dot8c_i32_i4_e32 v45, v136, v50
	v_dot8c_i32_i4_e32 v38, v131, v53
	v_dot8c_i32_i4_e32 v39, v131, v51
	v_dot8c_i32_i4_e32 v40, v133, v53
	v_dot8c_i32_i4_e32 v41, v133, v51
	v_dot8c_i32_i4_e32 v42, v135, v53
	v_dot8c_i32_i4_e32 v43, v135, v51
	v_dot8c_i32_i4_e32 v44, v137, v53
	v_dot8c_i32_i4_e32 v45, v137, v51
	v_and_b32_e32 v78, 0xffff, v29
	v_lshrrev_b32_e32 v79, 16, v29
	v_lshl_add_u32 v78, v78, 7, v152
	v_lshl_add_u32 v79, v79, 7, v153
	s_mov_b32 m0, s99
	s_add_i32 s43, s99, 0x400
	global_load_lds_dwordx4 v78, s[50:51]
	s_mov_b32 m0, s43
	s_nop 0
	global_load_lds_dwordx4 v79, s[50:51]
	s_waitcnt vmcnt(8)
	v_add_u32_e32 v54, s77, v59
	v_add_u32_e32 v55, s77, v60
	v_add_u32_e32 v56, s77, v61
	v_add_u32_e32 v57, s77, v62
	ds_read_b64_tr_b4 v[50:51], v160 offset:896
	ds_read_b64_tr_b4 v[52:53], v160 offset:1920
	ds_read_b64_tr_b4 v[130:131], v54
	ds_read_b64_tr_b4 v[132:133], v55
	ds_read_b64_tr_b4 v[134:135], v56
	ds_read_b64_tr_b4 v[136:137], v57
	s_waitcnt lgkmcnt(6)
	v_dot8c_i32_i4_e32 v38, v122, v48
	v_dot8c_i32_i4_e32 v39, v122, v46
	v_dot8c_i32_i4_e32 v40, v124, v48
	v_dot8c_i32_i4_e32 v41, v124, v46
	v_dot8c_i32_i4_e32 v42, v126, v48
	v_dot8c_i32_i4_e32 v43, v126, v46
	v_dot8c_i32_i4_e32 v44, v128, v48
	v_dot8c_i32_i4_e32 v45, v128, v46
	v_dot8c_i32_i4_e32 v38, v123, v49
	v_dot8c_i32_i4_e32 v39, v123, v47
	v_dot8c_i32_i4_e32 v40, v125, v49
	v_dot8c_i32_i4_e32 v41, v125, v47
	v_dot8c_i32_i4_e32 v42, v127, v49
	v_dot8c_i32_i4_e32 v43, v127, v47
	v_dot8c_i32_i4_e32 v44, v129, v49
	v_dot8c_i32_i4_e32 v45, v129, v47
	v_and_b32_e32 v78, 0xffff, v30
	v_lshrrev_b32_e32 v79, 16, v30
	v_lshl_add_u32 v78, v78, 7, v152
	v_lshl_add_u32 v79, v79, 7, v153
	s_mov_b32 m0, s76
	s_add_i32 s43, s76, 0x400
	global_load_lds_dwordx4 v78, s[50:51]
	s_mov_b32 m0, s43
	s_nop 0
	global_load_lds_dwordx4 v79, s[50:51]
	s_waitcnt vmcnt(8)
	v_add_u32_e32 v54, s78, v59
	v_add_u32_e32 v55, s78, v60
	v_add_u32_e32 v56, s78, v61
	v_add_u32_e32 v57, s78, v62
	ds_read_b64_tr_b4 v[46:47], v160
	ds_read_b64_tr_b4 v[48:49], v160 offset:1024
	ds_read_b64_tr_b4 v[122:123], v54
	ds_read_b64_tr_b4 v[124:125], v55
	ds_read_b64_tr_b4 v[126:127], v56
	ds_read_b64_tr_b4 v[128:129], v57
	s_waitcnt lgkmcnt(6)
	v_dot8c_i32_i4_e32 v38, v130, v52
	v_dot8c_i32_i4_e32 v39, v130, v50
	v_dot8c_i32_i4_e32 v40, v132, v52
	v_dot8c_i32_i4_e32 v41, v132, v50
	v_dot8c_i32_i4_e32 v42, v134, v52
	v_dot8c_i32_i4_e32 v43, v134, v50
	v_dot8c_i32_i4_e32 v44, v136, v52
	v_dot8c_i32_i4_e32 v45, v136, v50
	v_dot8c_i32_i4_e32 v38, v131, v53
	v_dot8c_i32_i4_e32 v39, v131, v51
	v_dot8c_i32_i4_e32 v40, v133, v53
	v_dot8c_i32_i4_e32 v41, v133, v51
	v_dot8c_i32_i4_e32 v42, v135, v53
	v_dot8c_i32_i4_e32 v43, v135, v51
	v_dot8c_i32_i4_e32 v44, v137, v53
	v_dot8c_i32_i4_e32 v45, v137, v51
	s_nop 3
	s_waitcnt lgkmcnt(15)
	v_lshlrev_b32_e32 v38, 5, v38
	v_lshlrev_b32_e32 v39, 1, v39
	v_add3_u32 v38, v39, v229, v38
	v_cvt_f32_i32_e32 v38, v38
	v_mul_f32_e32 v38, v228, v38
	v_lshlrev_b32_e32 v40, 5, v40
	v_lshlrev_b32_e32 v41, 1, v41
	v_add3_u32 v40, v41, v229, v40
	v_cvt_f32_i32_e32 v40, v40
	v_mul_f32_e32 v40, v228, v40
	v_lshlrev_b32_e32 v42, 5, v42
	v_lshlrev_b32_e32 v43, 1, v43
	v_add3_u32 v42, v43, v229, v42
	v_cvt_f32_i32_e32 v42, v42
	v_mul_f32_e32 v42, v228, v42
	v_lshlrev_b32_e32 v44, 5, v44
	v_lshlrev_b32_e32 v45, 1, v45
	v_add3_u32 v44, v45, v229, v44
	v_cvt_f32_i32_e32 v44, v44
	v_mul_f32_e32 v44, v228, v44
	v_cvt_pk_bf16_f32 v184, v38, v40
	v_cvt_pk_bf16_f32 v185, v42, v44
	ds_read_b128 v[252:255], v156
	s_add_i32 s44, s40, 40
	s_ashr_i32 s45, s44, 31
	s_lshl_b64 s[44:45], s[44:45], 12
	v_lshl_add_u64 v[80:81], v[36:37], 0, s[44:45]
	s_waitcnt lgkmcnt(0)
; #define LAS __attribute__((address_space(3)))
; #define TR4(p_) __builtin_amdgcn_ds_read_tr4_b64_v2i32((LAS v2i*)(p_))
; #define CFENCE() asm volatile("" ::: "memory")
; __device__ __forceinline__ void peer_v_tokens(int j, const LAS unsigned short* EL, const LAS unsigned char* AL  , const LAS float* ASC  , const LAS int* SAL  , ...
;     ...
;           for (int jq = 0; jq < 4; ++jq) { hv[jq] = hp[64 * jq]; gv[jq] = gp[64 * jq]; } }
;         VDMA(0, 0); VDMA(1, 1);
; #pragma unroll
;         for (int m = 0; m < 2; ++m) {
;             const int idx = lane + 64 * m, tau = idx >> 4, sr = idx & 15, k = 16 * (sr & 7) + 2 * tau + (sr >> 3);
;             const int aq = (int)*(const LAS signed char*)(AL + tl * 128 + k); const int tq = aq + 8;
;             const unsigned lo = (((unsigned)tq & 15u) ^ 8u) * 0x11111111u, hi = ((unsigned)(tq >> 4) & 15u) * 0x11111111u;
;             typedef unsigned u2v __attribute__((ext_vector_type(2)));
;             u2v l2; l2.x = lo; l2.y = lo; u2v h2; h2.x = hi; h2.y = hi;
;             *(LAS u2v*)(ATL + 8 * idx) = l2; *(LAS u2v*)(ATL + 1024 + 8 * idx) = h2;
;         }
;         const float asc = ASC[tl]; const int sa = SAL[tl];
;         CFENCE();
;         int accH[4], accL[4];
; #pragma unroll
;         for (int st = 0; st < 16; ++st) {
;             const int p = st >> 2, q = st & 3;
;             if (st < 14) VDMA(st + 2, (st + 2) % 3);
;             if (st < 14) asm volatile("s_waitcnt vmcnt(8)" ::: "memory");
;             else if (st == 14) asm volatile("s_waitcnt vmcnt(4)" ::: "memory");
;             else asm volatile("s_waitcnt vmcnt(0)" ::: "memory");
;             if (q == 0) {
; #pragma unroll
;                 for (int r = 0; r < 4; ++r) { accH[r] = 0; accL[r] = 0; } }
; #pragma unroll
;             for (int tp = 0; tp < 2; ++tp) {
;                 const v2i ao = TR4(ATL + (2 * q + tp) * 128 + 8 * s16), ah = TR4(ATL + 1024 + (2 * q + tp) * 128 + 8 * s16);
; #pragma unroll
;                 for (int r = 0; r < 4; ++r) {
;                     const v2i d = TR4(ldsb + BUF[st % 3] + 2048 * tp + roff[r]);
;                     accH[r] = __builtin_amdgcn_sdot8(d.x, ah.x, accH[r], false); accH[r] = __builtin_amdgcn_sdot8(d.y, ah.y, accH[r], false);
;                     accL[r] = __builtin_amdgcn_sdot8(d.x, ao.x, accL[r], false); accL[r] = __builtin_amdgcn_sdot8(d.y, ao.y, accL[r], false);
;                 }
	v_mul_f32_e32 v244, v244, v252
	v_mul_f32_e32 v245, v245, v253
	v_mul_f32_e32 v246, v246, v254
	v_mul_f32_e32 v247, v247, v255
	global_store_dwordx4 v[80:81], v[244:247], off offset:2048 nt
	s_add_i32 s43, s40, 48
	s_lshl_b32 s43, s43, 11
	v_add_u32_e32 v138, s43, v66
	global_load_dwordx2 v[194:195], v138, s[70:71]
	global_load_dwordx2 v[196:197], v138, s[70:71] offset:512
	global_load_dwordx2 v[198:199], v138, s[70:71] offset:1024
	global_load_dwordx2 v[200:201], v138, s[70:71] offset:1536
	s_add_i32 s43, s40, 56
	s_lshl_b32 s43, s43, 11
	v_add_u32_e32 v138, s43, v66
	global_load_dwordx2 v[18:19], v138, s[70:71]
	global_load_dwordx2 v[20:21], v138, s[70:71] offset:512
	global_load_dwordx2 v[22:23], v138, s[70:71] offset:1024
	global_load_dwordx2 v[24:25], v138, s[70:71] offset:1536
	v_add_u32_e32 v147, 8, v140
	v_and_b32_e32 v146, 15, v147
	v_xor_b32_e32 v146, 8, v146
	v_bfe_u32 v148, v147, 4, 4
	v_mul_lo_u32 v146, v146, s92
	v_mul_lo_u32 v148, v148, s92
	v_mov_b32_e32 v147, v146
	v_mov_b32_e32 v149, v148
	ds_write2st64_b64 v77, v[146:147], v[148:149] offset1:2
	s_add_i32 s43, s67, 224
	v_mov_b32_e32 v138, s43
	ds_read2st64_b32 v[228:229], v138 offset1:1
	v_mov_b32_e32 v38, 0
	v_mov_b32_e32 v39, 0
	v_mov_b32_e32 v40, 0
	v_mov_b32_e32 v41, 0
	v_mov_b32_e32 v42, 0
	v_mov_b32_e32 v43, 0
	v_mov_b32_e32 v44, 0
	v_mov_b32_e32 v45, 0
	v_and_b32_e32 v78, 0xffff, v31
	v_lshrrev_b32_e32 v79, 16, v31
	v_lshl_add_u32 v78, v78, 7, v152
	v_lshl_add_u32 v79, v79, 7, v153
	s_mov_b32 m0, s77
	s_add_i32 s43, s77, 0x400
	global_load_lds_dwordx4 v78, s[50:51]
	s_mov_b32 m0, s43
	s_nop 0
	global_load_lds_dwordx4 v79, s[50:51]
	s_waitcnt vmcnt(17)
	v_add_u32_e32 v54, s79, v59
	v_add_u32_e32 v55, s79, v60
	v_add_u32_e32 v56, s79, v61
	v_add_u32_e32 v57, s79, v62
	ds_read_b64_tr_b4 v[50:51], v160 offset:128
	ds_read_b64_tr_b4 v[52:53], v160 offset:1152
	ds_read_b64_tr_b4 v[130:131], v54
	ds_read_b64_tr_b4 v[132:133], v55
	ds_read_b64_tr_b4 v[134:135], v56
	ds_read_b64_tr_b4 v[136:137], v57
	s_waitcnt lgkmcnt(9)
	v_dot8c_i32_i4_e32 v38, v122, v48
	v_dot8c_i32_i4_e32 v39, v122, v46
	v_dot8c_i32_i4_e32 v40, v124, v48
	v_dot8c_i32_i4_e32 v41, v124, v46
	v_dot8c_i32_i4_e32 v42, v126, v48
	v_dot8c_i32_i4_e32 v43, v126, v46
	v_dot8c_i32_i4_e32 v44, v128, v48
	v_dot8c_i32_i4_e32 v45, v128, v46
	v_dot8c_i32_i4_e32 v38, v123, v49
	v_dot8c_i32_i4_e32 v39, v123, v47
	v_dot8c_i32_i4_e32 v40, v125, v49
	v_dot8c_i32_i4_e32 v41, v125, v47
	v_dot8c_i32_i4_e32 v42, v127, v49
	v_dot8c_i32_i4_e32 v43, v127, v47
	v_dot8c_i32_i4_e32 v44, v129, v49
	v_dot8c_i32_i4_e32 v45, v129, v47
	v_and_b32_e32 v78, 0xffff, v32
	v_lshrrev_b32_e32 v79, 16, v32
	v_lshl_add_u32 v78, v78, 7, v152
	v_lshl_add_u32 v79, v79, 7, v153
	s_mov_b32 m0, s78
	s_add_i32 s43, s78, 0x400
	global_load_lds_dwordx4 v78, s[50:51]
	s_mov_b32 m0, s43
	s_nop 0
	global_load_lds_dwordx4 v79, s[50:51]
	s_waitcnt vmcnt(17)
	v_add_u32_e32 v54, s98, v59
	v_add_u32_e32 v55, s98, v60
	v_add_u32_e32 v56, s98, v61
	v_add_u32_e32 v57, s98, v62
	ds_read_b64_tr_b4 v[46:47], v160 offset:256
	ds_read_b64_tr_b4 v[48:49], v160 offset:1280
	ds_read_b64_tr_b4 v[122:123], v54
	ds_read_b64_tr_b4 v[124:125], v55
	ds_read_b64_tr_b4 v[126:127], v56
	ds_read_b64_tr_b4 v[128:129], v57
	s_waitcnt lgkmcnt(6)
	v_dot8c_i32_i4_e32 v38, v130, v52
	v_dot8c_i32_i4_e32 v39, v130, v50
	v_dot8c_i32_i4_e32 v40, v132, v52
	v_dot8c_i32_i4_e32 v41, v132, v50
	v_dot8c_i32_i4_e32 v42, v134, v52
	v_dot8c_i32_i4_e32 v43, v134, v50
	v_dot8c_i32_i4_e32 v44, v136, v52
	v_dot8c_i32_i4_e32 v45, v136, v50
	v_dot8c_i32_i4_e32 v38, v131, v53
	v_dot8c_i32_i4_e32 v39, v131, v51
	v_dot8c_i32_i4_e32 v40, v133, v53
	v_dot8c_i32_i4_e32 v41, v133, v51
	v_dot8c_i32_i4_e32 v42, v135, v53
	v_dot8c_i32_i4_e32 v43, v135, v51
	v_dot8c_i32_i4_e32 v44, v137, v53
	v_dot8c_i32_i4_e32 v45, v137, v51
	v_and_b32_e32 v78, 0xffff, v33
	v_lshrrev_b32_e32 v79, 16, v33
	v_lshl_add_u32 v78, v78, 7, v152
	v_lshl_add_u32 v79, v79, 7, v153
	s_mov_b32 m0, s79
	s_add_i32 s43, s79, 0x400
	global_load_lds_dwordx4 v78, s[50:51]
	s_mov_b32 m0, s43
	s_nop 0
	global_load_lds_dwordx4 v79, s[50:51]
	s_waitcnt vmcnt(17)
	v_add_u32_e32 v54, s99, v59
	v_add_u32_e32 v55, s99, v60
	v_add_u32_e32 v56, s99, v61
	v_add_u32_e32 v57, s99, v62
	ds_read_b64_tr_b4 v[50:51], v160 offset:384
	ds_read_b64_tr_b4 v[52:53], v160 offset:1408
	ds_read_b64_tr_b4 v[130:131], v54
	ds_read_b64_tr_b4 v[132:133], v55
	ds_read_b64_tr_b4 v[134:135], v56
	ds_read_b64_tr_b4 v[136:137], v57
	s_waitcnt lgkmcnt(6)
	v_dot8c_i32_i4_e32 v38, v122, v48
	v_dot8c_i32_i4_e32 v39, v122, v46
	v_dot8c_i32_i4_e32 v40, v124, v48
	v_dot8c_i32_i4_e32 v41, v124, v46
	v_dot8c_i32_i4_e32 v42, v126, v48
	v_dot8c_i32_i4_e32 v43, v126, v46
	v_dot8c_i32_i4_e32 v44, v128, v48
	v_dot8c_i32_i4_e32 v45, v128, v46
	v_dot8c_i32_i4_e32 v38, v123, v49
	v_dot8c_i32_i4_e32 v39, v123, v47
	v_dot8c_i32_i4_e32 v40, v125, v49
	v_dot8c_i32_i4_e32 v41, v125, v47
	v_dot8c_i32_i4_e32 v42, v127, v49
	v_dot8c_i32_i4_e32 v43, v127, v47
	v_dot8c_i32_i4_e32 v44, v129, v49
	v_dot8c_i32_i4_e32 v45, v129, v47
	s_waitcnt vmcnt(15)
	v_add_u32_e32 v54, s76, v59
	v_add_u32_e32 v55, s76, v60
	v_add_u32_e32 v56, s76, v61
	v_add_u32_e32 v57, s76, v62
	ds_read_b64_tr_b4 v[46:47], v160 offset:512
	ds_read_b64_tr_b4 v[48:49], v160 offset:1536
	ds_read_b64_tr_b4 v[122:123], v54
	ds_read_b64_tr_b4 v[124:125], v55
	ds_read_b64_tr_b4 v[126:127], v56
	ds_read_b64_tr_b4 v[128:129], v57
	s_waitcnt lgkmcnt(6)
; #define LAS __attribute__((address_space(3)))
; __device__ __forceinline__ bf16 f2bf(float f) { return (bf16)f2bfu(f); }
; #define TR4(p_) __builtin_amdgcn_ds_read_tr4_b64_v2i32((LAS v2i*)(p_))
; #define CFENCE() asm volatile("" ::: "memory")
; __device__ __forceinline__ void peer_v_tokens(int j, const LAS unsigned short* EL, const LAS unsigned char* AL  , const LAS float* ASC  , const LAS int* SAL  , ...
;     ...
;         for (int st = 0; st < 16; ++st) {
;             const int p = st >> 2, q = st & 3;
;             if (st < 14) VDMA(st + 2, (st + 2) % 3);
;             if (st < 14) asm volatile("s_waitcnt vmcnt(8)" ::: "memory");
;             else if (st == 14) asm volatile("s_waitcnt vmcnt(4)" ::: "memory");
;             else asm volatile("s_waitcnt vmcnt(0)" ::: "memory");
;             if (q == 0) {
; #pragma unroll
;                 for (int r = 0; r < 4; ++r) { accH[r] = 0; accL[r] = 0; } }
; #pragma unroll
;             for (int tp = 0; tp < 2; ++tp) {
;                 const v2i ao = TR4(ATL + (2 * q + tp) * 128 + 8 * s16), ah = TR4(ATL + 1024 + (2 * q + tp) * 128 + 8 * s16);
; #pragma unroll
;                 for (int r = 0; r < 4; ++r) {
;                     const v2i d = TR4(ldsb + BUF[st % 3] + 2048 * tp + roff[r]);
;                     accH[r] = __builtin_amdgcn_sdot8(d.x, ah.x, accH[r], false); accH[r] = __builtin_amdgcn_sdot8(d.y, ah.y, accH[r], false);
;                     accL[r] = __builtin_amdgcn_sdot8(d.x, ao.x, accL[r], false); accL[r] = __builtin_amdgcn_sdot8(d.y, ao.y, accL[r], false);
;                 }
;             }
;             asm volatile("s_waitcnt lgkmcnt(0)" ::: "memory");
;             if (q == 3) {
; #pragma unroll
;                 for (int r = 0; r < 4; ++r) STASH[256 * p + 16 * (grp + 4 * r) + pc] = f2bf(asc * (float)(2 * ((accH[r] << 4) + accL[r]) + sa));
;             }
;         }
;         CFENCE();
;         {
;             float4 v[4]; float ss = 0.f;
; #pragma unroll
;             for (int jq = 0; jq < 4; ++jq) { typedef unsigned u2v __attribute__((ext_vector_type(2))); const u2v pw = *(const LAS u2v*)(STASH + 4 * lane + 256 * jq); const uint2 hw = hv[jq];
	v_dot8c_i32_i4_e32 v38, v130, v52
	v_dot8c_i32_i4_e32 v39, v130, v50
	v_dot8c_i32_i4_e32 v40, v132, v52
	v_dot8c_i32_i4_e32 v41, v132, v50
	v_dot8c_i32_i4_e32 v42, v134, v52
	v_dot8c_i32_i4_e32 v43, v134, v50
	v_dot8c_i32_i4_e32 v44, v136, v52
	v_dot8c_i32_i4_e32 v45, v136, v50
	v_dot8c_i32_i4_e32 v38, v131, v53
	v_dot8c_i32_i4_e32 v39, v131, v51
	v_dot8c_i32_i4_e32 v40, v133, v53
	v_dot8c_i32_i4_e32 v41, v133, v51
	v_dot8c_i32_i4_e32 v42, v135, v53
	v_dot8c_i32_i4_e32 v43, v135, v51
	v_dot8c_i32_i4_e32 v44, v137, v53
	v_dot8c_i32_i4_e32 v45, v137, v51
	s_waitcnt vmcnt(4)
	v_add_u32_e32 v54, s77, v59
	v_add_u32_e32 v55, s77, v60
	v_add_u32_e32 v56, s77, v61
	v_add_u32_e32 v57, s77, v62
	ds_read_b64_tr_b4 v[50:51], v160 offset:640
	ds_read_b64_tr_b4 v[52:53], v160 offset:1664
	ds_read_b64_tr_b4 v[130:131], v54
	ds_read_b64_tr_b4 v[132:133], v55
	ds_read_b64_tr_b4 v[134:135], v56
	ds_read_b64_tr_b4 v[136:137], v57
	s_waitcnt lgkmcnt(6)
	v_dot8c_i32_i4_e32 v38, v122, v48
	v_dot8c_i32_i4_e32 v39, v122, v46
	v_dot8c_i32_i4_e32 v40, v124, v48
	v_dot8c_i32_i4_e32 v41, v124, v46
	v_dot8c_i32_i4_e32 v42, v126, v48
	v_dot8c_i32_i4_e32 v43, v126, v46
	v_dot8c_i32_i4_e32 v44, v128, v48
	v_dot8c_i32_i4_e32 v45, v128, v46
	v_dot8c_i32_i4_e32 v38, v123, v49
	v_dot8c_i32_i4_e32 v39, v123, v47
	v_dot8c_i32_i4_e32 v40, v125, v49
	v_dot8c_i32_i4_e32 v41, v125, v47
	v_dot8c_i32_i4_e32 v42, v127, v49
	v_dot8c_i32_i4_e32 v43, v127, v47
	v_dot8c_i32_i4_e32 v44, v129, v49
	v_dot8c_i32_i4_e32 v45, v129, v47
	s_waitcnt vmcnt(2)
	v_add_u32_e32 v54, s78, v59
	v_add_u32_e32 v55, s78, v60
	v_add_u32_e32 v56, s78, v61
	v_add_u32_e32 v57, s78, v62
	ds_read_b64_tr_b4 v[46:47], v160 offset:768
	ds_read_b64_tr_b4 v[48:49], v160 offset:1792
	ds_read_b64_tr_b4 v[122:123], v54
	ds_read_b64_tr_b4 v[124:125], v55
	ds_read_b64_tr_b4 v[126:127], v56
	ds_read_b64_tr_b4 v[128:129], v57
	s_waitcnt lgkmcnt(6)
	v_dot8c_i32_i4_e32 v38, v130, v52
	v_dot8c_i32_i4_e32 v39, v130, v50
	v_dot8c_i32_i4_e32 v40, v132, v52
	v_dot8c_i32_i4_e32 v41, v132, v50
	v_dot8c_i32_i4_e32 v42, v134, v52
	v_dot8c_i32_i4_e32 v43, v134, v50
	v_dot8c_i32_i4_e32 v44, v136, v52
	v_dot8c_i32_i4_e32 v45, v136, v50
	v_dot8c_i32_i4_e32 v38, v131, v53
	v_dot8c_i32_i4_e32 v39, v131, v51
	v_dot8c_i32_i4_e32 v40, v133, v53
	v_dot8c_i32_i4_e32 v41, v133, v51
	v_dot8c_i32_i4_e32 v42, v135, v53
	v_dot8c_i32_i4_e32 v43, v135, v51
	v_dot8c_i32_i4_e32 v44, v137, v53
	v_dot8c_i32_i4_e32 v45, v137, v51
	s_waitcnt vmcnt(0)
	v_add_u32_e32 v54, s79, v59
	v_add_u32_e32 v55, s79, v60
	v_add_u32_e32 v56, s79, v61
	v_add_u32_e32 v57, s79, v62
	ds_read_b64_tr_b4 v[50:51], v160 offset:896
	ds_read_b64_tr_b4 v[52:53], v160 offset:1920
	ds_read_b64_tr_b4 v[130:131], v54
	ds_read_b64_tr_b4 v[132:133], v55
	ds_read_b64_tr_b4 v[134:135], v56
	ds_read_b64_tr_b4 v[136:137], v57
	s_waitcnt lgkmcnt(6)
	v_dot8c_i32_i4_e32 v38, v122, v48
	v_dot8c_i32_i4_e32 v39, v122, v46
	v_dot8c_i32_i4_e32 v40, v124, v48
	v_dot8c_i32_i4_e32 v41, v124, v46
	v_dot8c_i32_i4_e32 v42, v126, v48
	v_dot8c_i32_i4_e32 v43, v126, v46
	v_dot8c_i32_i4_e32 v44, v128, v48
	v_dot8c_i32_i4_e32 v45, v128, v46
	v_dot8c_i32_i4_e32 v38, v123, v49
	v_dot8c_i32_i4_e32 v39, v123, v47
	v_dot8c_i32_i4_e32 v40, v125, v49
	v_dot8c_i32_i4_e32 v41, v125, v47
	v_dot8c_i32_i4_e32 v42, v127, v49
	v_dot8c_i32_i4_e32 v43, v127, v47
	v_dot8c_i32_i4_e32 v44, v129, v49
	v_dot8c_i32_i4_e32 v45, v129, v47
	s_waitcnt lgkmcnt(0)
	v_dot8c_i32_i4_e32 v38, v130, v52
	v_dot8c_i32_i4_e32 v39, v130, v50
	v_dot8c_i32_i4_e32 v40, v132, v52
	v_dot8c_i32_i4_e32 v41, v132, v50
	v_dot8c_i32_i4_e32 v42, v134, v52
	v_dot8c_i32_i4_e32 v43, v134, v50
	v_dot8c_i32_i4_e32 v44, v136, v52
	v_dot8c_i32_i4_e32 v45, v136, v50
	v_dot8c_i32_i4_e32 v38, v131, v53
	v_dot8c_i32_i4_e32 v39, v131, v51
	v_dot8c_i32_i4_e32 v40, v133, v53
	v_dot8c_i32_i4_e32 v41, v133, v51
	v_dot8c_i32_i4_e32 v42, v135, v53
	v_dot8c_i32_i4_e32 v43, v135, v51
	v_dot8c_i32_i4_e32 v44, v137, v53
	v_dot8c_i32_i4_e32 v45, v137, v51
	s_nop 3
	s_waitcnt lgkmcnt(15)
	v_lshlrev_b32_e32 v38, 5, v38
	v_lshlrev_b32_e32 v39, 1, v39
	v_add3_u32 v38, v39, v229, v38
	v_cvt_f32_i32_e32 v38, v38
	v_mul_f32_e32 v38, v228, v38
	v_lshlrev_b32_e32 v40, 5, v40
	v_lshlrev_b32_e32 v41, 1, v41
	v_add3_u32 v40, v41, v229, v40
	v_cvt_f32_i32_e32 v40, v40
	v_mul_f32_e32 v40, v228, v40
	v_lshlrev_b32_e32 v42, 5, v42
	v_lshlrev_b32_e32 v43, 1, v43
	v_add3_u32 v42, v43, v229, v42
	v_cvt_f32_i32_e32 v42, v42
	v_mul_f32_e32 v42, v228, v42
	v_lshlrev_b32_e32 v44, 5, v44
	v_lshlrev_b32_e32 v45, 1, v45
	v_add3_u32 v44, v45, v229, v44
	v_cvt_f32_i32_e32 v44, v44
	v_mul_f32_e32 v44, v228, v44
	v_cvt_pk_bf16_f32 v192, v38, v40
	v_cvt_pk_bf16_f32 v193, v42, v44
	ds_read_b128 v[252:255], v156 offset:1024
	s_add_i32 s44, s40, 40
	s_ashr_i32 s45, s44, 31
	s_lshl_b64 s[44:45], s[44:45], 12
	v_lshl_add_u64 v[80:81], v[36:37], 0, s[44:45]
	s_waitcnt lgkmcnt(0)
	v_mul_f32_e32 v248, v248, v252
	v_mul_f32_e32 v249, v249, v253
	v_mul_f32_e32 v250, v250, v254
	v_mul_f32_e32 v251, v251, v255
	global_store_dwordx4 v[80:81], v[248:251], off offset:3072 nt
	ds_write_b16 v65, v178
	ds_write_b16_d16_hi v65, v178 offset:128
	ds_write_b16 v65, v179 offset:256
	ds_write_b16_d16_hi v65, v179 offset:384
	ds_write_b16 v65, v180 offset:512
	ds_write_b16_d16_hi v65, v180 offset:640
	ds_write_b16 v65, v181 offset:768
	ds_write_b16_d16_hi v65, v181 offset:896
	ds_write_b16 v65, v182 offset:1024
	ds_write_b16_d16_hi v65, v182 offset:1152
	ds_write_b16 v65, v183 offset:1280
	ds_write_b16_d16_hi v65, v183 offset:1408
	ds_write_b16 v65, v184 offset:1536
	ds_write_b16_d16_hi v65, v184 offset:1664
	ds_write_b16 v65, v185 offset:1792
	ds_write_b16_d16_hi v65, v185 offset:1920
	ds_read_b64 v[202:203], v154
	ds_read_b64 v[204:205], v154 offset:512
	ds_read_b64 v[206:207], v154 offset:1024
	ds_read_b64 v[208:209], v154 offset:1536
	s_waitcnt vmcnt(11) lgkmcnt(0)
; #define LAS __attribute__((address_space(3)))
; __device__ __forceinline__ void peer_v_tokens(int j, const LAS unsigned short* EL, const LAS unsigned char* AL  , const LAS float* ASC  , const LAS int* SAL  , ...
;     ...
;             float4 v[4]; float ss = 0.f;
; #pragma unroll
;             for (int jq = 0; jq < 4; ++jq) { typedef unsigned u2v __attribute__((ext_vector_type(2))); const u2v pw = *(const LAS u2v*)(STASH + 4 * lane + 256 * jq); const uint2 hw = hv[jq];
;                 v[jq] = make_float4(__uint_as_float(hw.x << 16) + __uint_as_float(pw.x << 16), __uint_as_float(hw.x & 0xffff0000u) + __uint_as_float(pw.x & 0xffff0000u),
;                                     __uint_as_float(hw.y << 16) + __uint_as_float(pw.y << 16), __uint_as_float(hw.y & 0xffff0000u) + __uint_as_float(pw.y & 0xffff0000u));
;                 ss += v[jq].x * v[jq].x + v[jq].y * v[jq].y + v[jq].z * v[jq].z + v[jq].w * v[jq].w; }
;             ss = wave_sum(ss);
;             const float r3 = rsqrtf(ss * (1.f / D) + EPS);
;             float4* op = (float4*)(outp + (size_t)t * D) + lane;
; #pragma unroll
;             for (int jq = 0; jq < 4; ++jq) { typedef float f4v __attribute__((ext_vector_type(4))); f4v o4; o4.x = v[jq].x * r3 * gv[jq].x; o4.y = v[jq].y * r3 * gv[jq].y; o4.z = v[jq].z * r3 * gv[jq].z; o4.w = v[jq].w * r3 * gv[jq].w;
;                 __builtin_nontemporal_store(o4, (f4v*)op + 64 * jq); }
	v_lshlrev_b32_e32 v210, 16, v194
	v_and_b32_e32 v211, 0xffff0000, v194
	v_lshlrev_b32_e32 v142, 16, v202
	v_and_b32_e32 v143, 0xffff0000, v202
	v_add_f32_e32 v210, v210, v142
	v_add_f32_e32 v211, v211, v143
	v_lshlrev_b32_e32 v212, 16, v195
	v_and_b32_e32 v213, 0xffff0000, v195
	v_lshlrev_b32_e32 v142, 16, v203
	v_and_b32_e32 v143, 0xffff0000, v203
	v_add_f32_e32 v212, v212, v142
	v_add_f32_e32 v213, v213, v143
	v_lshlrev_b32_e32 v214, 16, v196
	v_and_b32_e32 v215, 0xffff0000, v196
	v_lshlrev_b32_e32 v142, 16, v204
	v_and_b32_e32 v143, 0xffff0000, v204
	v_add_f32_e32 v214, v214, v142
	v_add_f32_e32 v215, v215, v143
	v_lshlrev_b32_e32 v216, 16, v197
	v_and_b32_e32 v217, 0xffff0000, v197
	v_lshlrev_b32_e32 v142, 16, v205
	v_and_b32_e32 v143, 0xffff0000, v205
	v_add_f32_e32 v216, v216, v142
	v_add_f32_e32 v217, v217, v143
	v_lshlrev_b32_e32 v218, 16, v198
	v_and_b32_e32 v219, 0xffff0000, v198
	v_lshlrev_b32_e32 v142, 16, v206
	v_and_b32_e32 v143, 0xffff0000, v206
	v_add_f32_e32 v218, v218, v142
	v_add_f32_e32 v219, v219, v143
	v_lshlrev_b32_e32 v220, 16, v199
	v_and_b32_e32 v221, 0xffff0000, v199
	v_lshlrev_b32_e32 v142, 16, v207
	v_and_b32_e32 v143, 0xffff0000, v207
	v_add_f32_e32 v220, v220, v142
	v_add_f32_e32 v221, v221, v143
	v_lshlrev_b32_e32 v222, 16, v200
	v_and_b32_e32 v223, 0xffff0000, v200
	v_lshlrev_b32_e32 v142, 16, v208
	v_and_b32_e32 v143, 0xffff0000, v208
	v_add_f32_e32 v222, v222, v142
	v_add_f32_e32 v223, v223, v143
	v_lshlrev_b32_e32 v224, 16, v201
	v_and_b32_e32 v225, 0xffff0000, v201
	v_lshlrev_b32_e32 v142, 16, v209
	v_and_b32_e32 v143, 0xffff0000, v209
	v_add_f32_e32 v224, v224, v142
	v_add_f32_e32 v225, v225, v143
	v_mov_b32_e32 v144, 0
	v_mul_f32_e32 v145, v210, v210
	v_fmac_f32_e32 v145, v211, v211
	v_fmac_f32_e32 v145, v212, v212
	v_fmac_f32_e32 v145, v213, v213
	v_add_f32_e32 v144, v144, v145
	v_mul_f32_e32 v145, v214, v214
	v_fmac_f32_e32 v145, v215, v215
	v_fmac_f32_e32 v145, v216, v216
	v_fmac_f32_e32 v145, v217, v217
	v_add_f32_e32 v144, v144, v145
	v_mul_f32_e32 v145, v218, v218
	v_fmac_f32_e32 v145, v219, v219
	v_fmac_f32_e32 v145, v220, v220
	v_fmac_f32_e32 v145, v221, v221
	v_add_f32_e32 v144, v144, v145
	v_mul_f32_e32 v145, v222, v222
	v_fmac_f32_e32 v145, v223, v223
	v_fmac_f32_e32 v145, v224, v224
	v_fmac_f32_e32 v145, v225, v225
	v_add_f32_e32 v144, v144, v145
	s_nop 1
	v_add_f32_dpp v144, v144, v144 quad_perm:[1,0,3,2] row_mask:0xf bank_mask:0xf bound_ctrl:1
	s_nop 1
	v_add_f32_dpp v144, v144, v144 quad_perm:[2,3,0,1] row_mask:0xf bank_mask:0xf bound_ctrl:1
	s_nop 1
	v_add_f32_dpp v144, v144, v144 row_half_mirror row_mask:0xf bank_mask:0xf bound_ctrl:1
	s_nop 1
	v_add_f32_dpp v144, v144, v144 row_mirror row_mask:0xf bank_mask:0xf bound_ctrl:1
	s_nop 1
	v_readlane_b32 s10, v144, 0
	v_readlane_b32 s11, v144, 16
	v_readlane_b32 s14, v144, 32
	v_readlane_b32 s15, v144, 48
	s_nop 3
	v_mov_b32_e32 v144, s11
	v_mov_b32_e32 v145, s15
	v_add_f32_e32 v144, s10, v144
	v_add_f32_e32 v145, s14, v145
	v_add_f32_e32 v144, v144, v145
	v_fmamk_f32 v144, v144, 0x3a800000, v111
	v_rsq_f32_e32 v144, v144
	s_nop 0
	v_mul_f32_e32 v210, v210, v144
	v_mul_f32_e32 v211, v211, v144
	v_mul_f32_e32 v212, v212, v144
	v_mul_f32_e32 v213, v213, v144
	v_mul_f32_e32 v214, v214, v144
	v_mul_f32_e32 v215, v215, v144
	v_mul_f32_e32 v216, v216, v144
	v_mul_f32_e32 v217, v217, v144
	v_mul_f32_e32 v218, v218, v144
	v_mul_f32_e32 v219, v219, v144
	v_mul_f32_e32 v220, v220, v144
	v_mul_f32_e32 v221, v221, v144
	v_mul_f32_e32 v222, v222, v144
	v_mul_f32_e32 v223, v223, v144
	v_mul_f32_e32 v224, v224, v144
	v_mul_f32_e32 v225, v225, v144
	ds_read_b128 v[252:255], v155
	s_add_i32 s44, s40, 48
	s_ashr_i32 s45, s44, 31
	s_lshl_b64 s[44:45], s[44:45], 12
	v_lshl_add_u64 v[80:81], v[36:37], 0, s[44:45]
	s_waitcnt lgkmcnt(0)
	v_mul_f32_e32 v210, v210, v252
	v_mul_f32_e32 v211, v211, v253
	v_mul_f32_e32 v212, v212, v254
	v_mul_f32_e32 v213, v213, v255
	global_store_dwordx4 v[80:81], v[210:213], off nt
	ds_read_b128 v[252:255], v155 offset:1024
	s_add_i32 s44, s40, 48
	s_ashr_i32 s45, s44, 31
	s_lshl_b64 s[44:45], s[44:45], 12
	v_lshl_add_u64 v[80:81], v[36:37], 0, s[44:45]
	s_waitcnt lgkmcnt(0)
	v_mul_f32_e32 v214, v214, v252
	v_mul_f32_e32 v215, v215, v253
	v_mul_f32_e32 v216, v216, v254
	v_mul_f32_e32 v217, v217, v255
	global_store_dwordx4 v[80:81], v[214:217], off offset:1024 nt
	ds_read_b128 v[252:255], v156
	s_add_i32 s44, s40, 48
	s_ashr_i32 s45, s44, 31
	s_lshl_b64 s[44:45], s[44:45], 12
	v_lshl_add_u64 v[80:81], v[36:37], 0, s[44:45]
	s_waitcnt lgkmcnt(0)
	v_mul_f32_e32 v218, v218, v252
	v_mul_f32_e32 v219, v219, v253
	v_mul_f32_e32 v220, v220, v254
	v_mul_f32_e32 v221, v221, v255
	global_store_dwordx4 v[80:81], v[218:221], off offset:2048 nt
	ds_read_b128 v[252:255], v156 offset:1024
	s_add_i32 s44, s40, 48
	s_ashr_i32 s45, s44, 31
	s_lshl_b64 s[44:45], s[44:45], 12
	v_lshl_add_u64 v[80:81], v[36:37], 0, s[44:45]
	s_waitcnt lgkmcnt(0)
	v_mul_f32_e32 v222, v222, v252
	v_mul_f32_e32 v223, v223, v253
	v_mul_f32_e32 v224, v224, v254
	v_mul_f32_e32 v225, v225, v255
	global_store_dwordx4 v[80:81], v[222:225], off offset:3072 nt
	ds_write_b16 v65, v186
	ds_write_b16_d16_hi v65, v186 offset:128
	ds_write_b16 v65, v187 offset:256
	ds_write_b16_d16_hi v65, v187 offset:384
	ds_write_b16 v65, v188 offset:512
	ds_write_b16_d16_hi v65, v188 offset:640
	ds_write_b16 v65, v189 offset:768
	ds_write_b16_d16_hi v65, v189 offset:896
	ds_write_b16 v65, v190 offset:1024
	ds_write_b16_d16_hi v65, v190 offset:1152
	ds_write_b16 v65, v191 offset:1280
	ds_write_b16_d16_hi v65, v191 offset:1408
	ds_write_b16 v65, v192 offset:1536
	ds_write_b16_d16_hi v65, v192 offset:1664
	ds_write_b16 v65, v193 offset:1792
	ds_write_b16_d16_hi v65, v193 offset:1920
	ds_read_b64 v[202:203], v154
	ds_read_b64 v[204:205], v154 offset:512
	ds_read_b64 v[206:207], v154 offset:1024
	ds_read_b64 v[208:209], v154 offset:1536
	s_waitcnt vmcnt(11) lgkmcnt(0)
; #define LAS __attribute__((address_space(3)))
; __device__ __forceinline__ void peer_v_tokens(int j, const LAS unsigned short* EL, const LAS unsigned char* AL  , const LAS float* ASC  , const LAS int* SAL  , ...
;     ...
;             float4 v[4]; float ss = 0.f;
; #pragma unroll
;             for (int jq = 0; jq < 4; ++jq) { typedef unsigned u2v __attribute__((ext_vector_type(2))); const u2v pw = *(const LAS u2v*)(STASH + 4 * lane + 256 * jq); const uint2 hw = hv[jq];
;                 v[jq] = make_float4(__uint_as_float(hw.x << 16) + __uint_as_float(pw.x << 16), __uint_as_float(hw.x & 0xffff0000u) + __uint_as_float(pw.x & 0xffff0000u),
;                                     __uint_as_float(hw.y << 16) + __uint_as_float(pw.y << 16), __uint_as_float(hw.y & 0xffff0000u) + __uint_as_float(pw.y & 0xffff0000u));
;                 ss += v[jq].x * v[jq].x + v[jq].y * v[jq].y + v[jq].z * v[jq].z + v[jq].w * v[jq].w; }
;             ss = wave_sum(ss);
;             const float r3 = rsqrtf(ss * (1.f / D) + EPS);
;             float4* op = (float4*)(outp + (size_t)t * D) + lane;
; #pragma unroll
;             for (int jq = 0; jq < 4; ++jq) { typedef float f4v __attribute__((ext_vector_type(4))); f4v o4; o4.x = v[jq].x * r3 * gv[jq].x; o4.y = v[jq].y * r3 * gv[jq].y; o4.z = v[jq].z * r3 * gv[jq].z; o4.w = v[jq].w * r3 * gv[jq].w;
;                 __builtin_nontemporal_store(o4, (f4v*)op + 64 * jq); }
	v_lshlrev_b32_e32 v236, 16, v18
	v_and_b32_e32 v237, 0xffff0000, v18
	v_lshlrev_b32_e32 v142, 16, v202
	v_and_b32_e32 v143, 0xffff0000, v202
	v_add_f32_e32 v236, v236, v142
	v_add_f32_e32 v237, v237, v143
	v_lshlrev_b32_e32 v238, 16, v19
	v_and_b32_e32 v239, 0xffff0000, v19
	v_lshlrev_b32_e32 v142, 16, v203
	v_and_b32_e32 v143, 0xffff0000, v203
	v_add_f32_e32 v238, v238, v142
	v_add_f32_e32 v239, v239, v143
	v_lshlrev_b32_e32 v240, 16, v20
	v_and_b32_e32 v241, 0xffff0000, v20
	v_lshlrev_b32_e32 v142, 16, v204
	v_and_b32_e32 v143, 0xffff0000, v204
	v_add_f32_e32 v240, v240, v142
	v_add_f32_e32 v241, v241, v143
	v_lshlrev_b32_e32 v242, 16, v21
	v_and_b32_e32 v243, 0xffff0000, v21
	v_lshlrev_b32_e32 v142, 16, v205
	v_and_b32_e32 v143, 0xffff0000, v205
	v_add_f32_e32 v242, v242, v142
	v_add_f32_e32 v243, v243, v143
	v_lshlrev_b32_e32 v244, 16, v22
	v_and_b32_e32 v245, 0xffff0000, v22
	v_lshlrev_b32_e32 v142, 16, v206
	v_and_b32_e32 v143, 0xffff0000, v206
	v_add_f32_e32 v244, v244, v142
	v_add_f32_e32 v245, v245, v143
	v_lshlrev_b32_e32 v246, 16, v23
	v_and_b32_e32 v247, 0xffff0000, v23
	v_lshlrev_b32_e32 v142, 16, v207
	v_and_b32_e32 v143, 0xffff0000, v207
	v_add_f32_e32 v246, v246, v142
	v_add_f32_e32 v247, v247, v143
	v_lshlrev_b32_e32 v248, 16, v24
	v_and_b32_e32 v249, 0xffff0000, v24
	v_lshlrev_b32_e32 v142, 16, v208
	v_and_b32_e32 v143, 0xffff0000, v208
	v_add_f32_e32 v248, v248, v142
	v_add_f32_e32 v249, v249, v143
	v_lshlrev_b32_e32 v250, 16, v25
	v_and_b32_e32 v251, 0xffff0000, v25
	v_lshlrev_b32_e32 v142, 16, v209
	v_and_b32_e32 v143, 0xffff0000, v209
	v_add_f32_e32 v250, v250, v142
	v_add_f32_e32 v251, v251, v143
	v_mov_b32_e32 v144, 0
	v_mul_f32_e32 v145, v236, v236
	v_fmac_f32_e32 v145, v237, v237
	v_fmac_f32_e32 v145, v238, v238
	v_fmac_f32_e32 v145, v239, v239
	v_add_f32_e32 v144, v144, v145
	v_mul_f32_e32 v145, v240, v240
	v_fmac_f32_e32 v145, v241, v241
	v_fmac_f32_e32 v145, v242, v242
	v_fmac_f32_e32 v145, v243, v243
	v_add_f32_e32 v144, v144, v145
	v_mul_f32_e32 v145, v244, v244
	v_fmac_f32_e32 v145, v245, v245
	v_fmac_f32_e32 v145, v246, v246
	v_fmac_f32_e32 v145, v247, v247
	v_add_f32_e32 v144, v144, v145
	v_mul_f32_e32 v145, v248, v248
	v_fmac_f32_e32 v145, v249, v249
	v_fmac_f32_e32 v145, v250, v250
	v_fmac_f32_e32 v145, v251, v251
	v_add_f32_e32 v144, v144, v145
	s_nop 1
	v_add_f32_dpp v144, v144, v144 quad_perm:[1,0,3,2] row_mask:0xf bank_mask:0xf bound_ctrl:1
	s_nop 1
	v_add_f32_dpp v144, v144, v144 quad_perm:[2,3,0,1] row_mask:0xf bank_mask:0xf bound_ctrl:1
	s_nop 1
	v_add_f32_dpp v144, v144, v144 row_half_mirror row_mask:0xf bank_mask:0xf bound_ctrl:1
	s_nop 1
	v_add_f32_dpp v144, v144, v144 row_mirror row_mask:0xf bank_mask:0xf bound_ctrl:1
	s_nop 1
	v_readlane_b32 s10, v144, 0
	v_readlane_b32 s11, v144, 16
	v_readlane_b32 s14, v144, 32
	v_readlane_b32 s15, v144, 48
	s_nop 3
	v_mov_b32_e32 v144, s11
	v_mov_b32_e32 v145, s15
	v_add_f32_e32 v144, s10, v144
	v_add_f32_e32 v145, s14, v145
	v_add_f32_e32 v144, v144, v145
	v_fmamk_f32 v144, v144, 0x3a800000, v111
	v_rsq_f32_e32 v144, v144
	s_nop 0
	v_mul_f32_e32 v236, v236, v144
	v_mul_f32_e32 v237, v237, v144
	v_mul_f32_e32 v238, v238, v144
	v_mul_f32_e32 v239, v239, v144
	v_mul_f32_e32 v240, v240, v144
	v_mul_f32_e32 v241, v241, v144
	v_mul_f32_e32 v242, v242, v144
	v_mul_f32_e32 v243, v243, v144
	v_mul_f32_e32 v244, v244, v144
	v_mul_f32_e32 v245, v245, v144
	v_mul_f32_e32 v246, v246, v144
	v_mul_f32_e32 v247, v247, v144
	v_mul_f32_e32 v248, v248, v144
	v_mul_f32_e32 v249, v249, v144
	v_mul_f32_e32 v250, v250, v144
	v_mul_f32_e32 v251, v251, v144
	ds_read_b128 v[252:255], v155
	s_add_i32 s44, s40, 56
	s_ashr_i32 s45, s44, 31
	s_lshl_b64 s[44:45], s[44:45], 12
	v_lshl_add_u64 v[80:81], v[36:37], 0, s[44:45]
	s_waitcnt lgkmcnt(0)
	v_mul_f32_e32 v236, v236, v252
	v_mul_f32_e32 v237, v237, v253
	v_mul_f32_e32 v238, v238, v254
	v_mul_f32_e32 v239, v239, v255
	global_store_dwordx4 v[80:81], v[236:239], off nt
	ds_read_b128 v[252:255], v155 offset:1024
	s_add_i32 s44, s40, 56
	s_ashr_i32 s45, s44, 31
	s_lshl_b64 s[44:45], s[44:45], 12
	v_lshl_add_u64 v[80:81], v[36:37], 0, s[44:45]
	s_waitcnt lgkmcnt(0)
	v_mul_f32_e32 v240, v240, v252
	v_mul_f32_e32 v241, v241, v253
	v_mul_f32_e32 v242, v242, v254
	v_mul_f32_e32 v243, v243, v255
	global_store_dwordx4 v[80:81], v[240:243], off offset:1024 nt
	ds_read_b128 v[252:255], v156
	s_add_i32 s44, s40, 56
	s_ashr_i32 s45, s44, 31
	s_lshl_b64 s[44:45], s[44:45], 12
	v_lshl_add_u64 v[80:81], v[36:37], 0, s[44:45]
	s_waitcnt lgkmcnt(0)
	v_mul_f32_e32 v244, v244, v252
	v_mul_f32_e32 v245, v245, v253
	v_mul_f32_e32 v246, v246, v254
	v_mul_f32_e32 v247, v247, v255
	global_store_dwordx4 v[80:81], v[244:247], off offset:2048 nt
	ds_read_b128 v[252:255], v156 offset:1024
	s_add_i32 s44, s40, 56
	s_ashr_i32 s45, s44, 31
	s_lshl_b64 s[44:45], s[44:45], 12
	v_lshl_add_u64 v[80:81], v[36:37], 0, s[44:45]
	s_waitcnt lgkmcnt(0)
	v_mul_f32_e32 v248, v248, v252
	v_mul_f32_e32 v249, v249, v253
	v_mul_f32_e32 v250, v250, v254
	v_mul_f32_e32 v251, v251, v255
	global_store_dwordx4 v[80:81], v[248:251], off offset:3072 nt
	s_add_i32 s2, s2, s33
	s_add_i32 s40, s40, s63
	s_add_i32 s73, s73, s74
	s_cmpk_lt_i32 s2, 0x100
	s_cbranch_scc1 .LBB0_648
